# all phases: flat_load replaced by global_load (every such address is global memory)
# speedup vs baseline: 1.0047x; 1.0003x over previous
.LBB0_30:
	ds_read_b128 v[136:139], v149
	ds_read_b128 v[140:143], v149 offset:16
	ds_read_b128 v[132:135], v149 offset:32
	ds_read_b128 v[128:131], v149 offset:48
	ds_read_b128 v[144:147], v149 offset:4096
	ds_read_b128 v[160:163], v149 offset:8192
	ds_read_b128 v[164:167], v149 offset:4112
	ds_read_b128 v[168:171], v149 offset:12288
	ds_read_b128 v[176:179], v149 offset:8208
	ds_read_b128 v[180:183], v149 offset:16384
	ds_read_b128 v[184:187], v149 offset:12304
	s_waitcnt vmcnt(0) lgkmcnt(0)
	v_pk_fma_f32 v[172:173], v[0:1], v[136:137], 0 op_sel_hi:[1,0,0]
	v_pk_fma_f32 v[192:193], v[2:3], v[136:137], 0 op_sel_hi:[1,0,0]
	s_waitcnt lgkmcnt(6)
	v_pk_fma_f32 v[194:195], v[0:1], v[144:145], 0 op_sel_hi:[1,0,0]
	v_pk_fma_f32 v[196:197], v[2:3], v[144:145], 0 op_sel_hi:[1,0,0]
	s_waitcnt vmcnt(30)
	v_pk_fma_f32 v[192:193], v[6:7], v[136:137], v[192:193] op_sel:[0,1,0]
	v_pk_fma_f32 v[136:137], v[4:5], v[136:137], v[172:173] op_sel:[0,1,0]
	s_waitcnt lgkmcnt(5)
	v_pk_fma_f32 v[198:199], v[0:1], v[160:161], 0 op_sel_hi:[1,0,0]
	v_pk_fma_f32 v[200:201], v[2:3], v[160:161], 0 op_sel_hi:[1,0,0]
	s_waitcnt lgkmcnt(3)
	v_pk_fma_f32 v[202:203], v[0:1], v[168:169], 0 op_sel_hi:[1,0,0]
	v_pk_fma_f32 v[204:205], v[2:3], v[168:169], 0 op_sel_hi:[1,0,0]
	ds_read_b128 v[188:191], v149 offset:16400
	v_pk_fma_f32 v[172:173], v[6:7], v[144:145], v[196:197] op_sel:[0,1,0]
	v_pk_fma_f32 v[144:145], v[4:5], v[144:145], v[194:195] op_sel:[0,1,0]
	s_waitcnt vmcnt(29)
	v_pk_fma_f32 v[136:137], v[8:9], v[138:139], v[136:137] op_sel_hi:[1,0,1]
	v_pk_fma_f32 v[192:193], v[10:11], v[138:139], v[192:193] op_sel_hi:[1,0,1]
	v_mov_b32_e32 v138, v139
	s_waitcnt lgkmcnt(2)
	v_pk_fma_f32 v[206:207], v[0:1], v[180:181], 0 op_sel_hi:[1,0,0]
	v_pk_fma_f32 v[208:209], v[2:3], v[180:181], 0 op_sel_hi:[1,0,0]
	v_pk_fma_f32 v[194:195], v[6:7], v[160:161], v[200:201] op_sel:[0,1,0]
	v_pk_fma_f32 v[160:161], v[4:5], v[160:161], v[198:199] op_sel:[0,1,0]
	v_pk_fma_f32 v[196:197], v[6:7], v[168:169], v[204:205] op_sel:[0,1,0]
	v_pk_fma_f32 v[168:169], v[4:5], v[168:169], v[202:203] op_sel:[0,1,0]
	v_pk_fma_f32 v[144:145], v[8:9], v[146:147], v[144:145] op_sel_hi:[1,0,1]
	v_pk_fma_f32 v[172:173], v[10:11], v[146:147], v[172:173] op_sel_hi:[1,0,1]
	s_waitcnt vmcnt(28)
	v_pk_fma_f32 v[192:193], v[14:15], v[138:139], v[192:193] op_sel_hi:[1,0,1]
	v_pk_fma_f32 v[136:137], v[12:13], v[138:139], v[136:137] op_sel_hi:[1,0,1]
	v_mov_b32_e32 v138, v147
	v_pk_fma_f32 v[198:199], v[6:7], v[180:181], v[208:209] op_sel:[0,1,0]
	v_pk_fma_f32 v[180:181], v[4:5], v[180:181], v[206:207] op_sel:[0,1,0]
	v_pk_fma_f32 v[160:161], v[8:9], v[162:163], v[160:161] op_sel_hi:[1,0,1]
	v_pk_fma_f32 v[194:195], v[10:11], v[162:163], v[194:195] op_sel_hi:[1,0,1]
	v_pk_fma_f32 v[168:169], v[8:9], v[170:171], v[168:169] op_sel_hi:[1,0,1]
	v_pk_fma_f32 v[196:197], v[10:11], v[170:171], v[196:197] op_sel_hi:[1,0,1]
	v_pk_fma_f32 v[146:147], v[14:15], v[138:139], v[172:173] op_sel_hi:[1,0,1]
	v_pk_fma_f32 v[138:139], v[12:13], v[138:139], v[144:145] op_sel_hi:[1,0,1]
	v_mov_b32_e32 v144, v163
	v_mov_b32_e32 v156, v171
	v_pk_fma_f32 v[180:181], v[8:9], v[182:183], v[180:181] op_sel_hi:[1,0,1]
	v_pk_fma_f32 v[198:199], v[10:11], v[182:183], v[198:199] op_sel_hi:[1,0,1]
	v_pk_fma_f32 v[162:163], v[14:15], v[144:145], v[194:195] op_sel_hi:[1,0,1]
	v_pk_fma_f32 v[144:145], v[12:13], v[144:145], v[160:161] op_sel_hi:[1,0,1]
	v_pk_fma_f32 v[160:161], v[14:15], v[156:157], v[196:197] op_sel_hi:[1,0,1]
	v_pk_fma_f32 v[168:169], v[12:13], v[156:157], v[168:169] op_sel_hi:[1,0,1]
	v_mov_b32_e32 v156, v183
	v_pk_fma_f32 v[170:171], v[14:15], v[156:157], v[198:199] op_sel_hi:[1,0,1]
	v_pk_fma_f32 v[172:173], v[12:13], v[156:157], v[180:181] op_sel_hi:[1,0,1]
	s_waitcnt vmcnt(27)
	v_pk_fma_f32 v[136:137], v[16:17], v[140:141], v[136:137] op_sel_hi:[1,0,1]
	v_pk_fma_f32 v[180:181], v[18:19], v[140:141], v[192:193] op_sel_hi:[1,0,1]
	v_pk_fma_f32 v[138:139], v[16:17], v[164:165], v[138:139] op_sel_hi:[1,0,1]
	v_pk_fma_f32 v[146:147], v[18:19], v[164:165], v[146:147] op_sel_hi:[1,0,1]
	s_waitcnt lgkmcnt(0)
	v_pk_fma_f32 v[170:171], v[18:19], v[188:189], v[170:171] op_sel_hi:[1,0,1]
	s_waitcnt vmcnt(26)
	v_pk_fma_f32 v[180:181], v[22:23], v[140:141], v[180:181] op_sel:[0,1,0]
	v_pk_fma_f32 v[136:137], v[20:21], v[140:141], v[136:137] op_sel:[0,1,0]
	v_pk_fma_f32 v[144:145], v[16:17], v[176:177], v[144:145] op_sel_hi:[1,0,1]
	v_pk_fma_f32 v[162:163], v[18:19], v[176:177], v[162:163] op_sel_hi:[1,0,1]
	v_pk_fma_f32 v[140:141], v[22:23], v[164:165], v[146:147] op_sel:[0,1,0]
	v_pk_fma_f32 v[138:139], v[20:21], v[164:165], v[138:139] op_sel:[0,1,0]
	v_pk_fma_f32 v[164:165], v[22:23], v[188:189], v[170:171] op_sel:[0,1,0]
	s_waitcnt vmcnt(25)
	v_pk_fma_f32 v[136:137], v[24:25], v[142:143], v[136:137] op_sel_hi:[1,0,1]
	v_pk_fma_f32 v[170:171], v[26:27], v[142:143], v[180:181] op_sel_hi:[1,0,1]
	v_mov_b32_e32 v142, v143
	v_pk_fma_f32 v[168:169], v[16:17], v[184:185], v[168:169] op_sel_hi:[1,0,1]
	v_pk_fma_f32 v[160:161], v[18:19], v[184:185], v[160:161] op_sel_hi:[1,0,1]
	v_pk_fma_f32 v[172:173], v[16:17], v[188:189], v[172:173] op_sel_hi:[1,0,1]
	v_pk_fma_f32 v[146:147], v[22:23], v[176:177], v[162:163] op_sel:[0,1,0]
	v_pk_fma_f32 v[144:145], v[20:21], v[176:177], v[144:145] op_sel:[0,1,0]
	v_pk_fma_f32 v[138:139], v[24:25], v[166:167], v[138:139] op_sel_hi:[1,0,1]
	v_pk_fma_f32 v[140:141], v[26:27], v[166:167], v[140:141] op_sel_hi:[1,0,1]
	s_waitcnt vmcnt(24)
	v_pk_fma_f32 v[170:171], v[30:31], v[142:143], v[170:171] op_sel_hi:[1,0,1]
	v_pk_fma_f32 v[142:143], v[28:29], v[142:143], v[136:137] op_sel_hi:[1,0,1]
	v_mov_b32_e32 v136, v167
	v_pk_fma_f32 v[160:161], v[22:23], v[184:185], v[160:161] op_sel:[0,1,0]
	v_pk_fma_f32 v[162:163], v[20:21], v[184:185], v[168:169] op_sel:[0,1,0]
	v_pk_fma_f32 v[168:169], v[20:21], v[188:189], v[172:173] op_sel:[0,1,0]
	v_pk_fma_f32 v[144:145], v[24:25], v[178:179], v[144:145] op_sel_hi:[1,0,1]
	v_pk_fma_f32 v[146:147], v[26:27], v[178:179], v[146:147] op_sel_hi:[1,0,1]
	v_pk_fma_f32 v[166:167], v[30:31], v[136:137], v[140:141] op_sel_hi:[1,0,1]
	v_pk_fma_f32 v[172:173], v[28:29], v[136:137], v[138:139] op_sel_hi:[1,0,1]
	v_mov_b32_e32 v136, v179
	v_pk_fma_f32 v[162:163], v[24:25], v[186:187], v[162:163] op_sel_hi:[1,0,1]
	v_pk_fma_f32 v[160:161], v[26:27], v[186:187], v[160:161] op_sel_hi:[1,0,1]
	v_pk_fma_f32 v[176:177], v[30:31], v[136:137], v[146:147] op_sel_hi:[1,0,1]
	v_pk_fma_f32 v[178:179], v[28:29], v[136:137], v[144:145] op_sel_hi:[1,0,1]
	v_mov_b32_e32 v136, v187
	v_pk_fma_f32 v[168:169], v[24:25], v[190:191], v[168:169] op_sel_hi:[1,0,1]
	v_pk_fma_f32 v[164:165], v[26:27], v[190:191], v[164:165] op_sel_hi:[1,0,1]
	v_pk_fma_f32 v[180:181], v[30:31], v[136:137], v[160:161] op_sel_hi:[1,0,1]
	v_pk_fma_f32 v[182:183], v[28:29], v[136:137], v[162:163] op_sel_hi:[1,0,1]
	v_mov_b32_e32 v136, v191
	v_pk_fma_f32 v[184:185], v[30:31], v[136:137], v[164:165] op_sel_hi:[1,0,1]
	v_pk_fma_f32 v[186:187], v[28:29], v[136:137], v[168:169] op_sel_hi:[1,0,1]
	ds_read_b128 v[136:139], v149 offset:4128
	s_waitcnt vmcnt(23)
	v_pk_fma_f32 v[188:189], v[32:33], v[132:133], v[142:143] op_sel_hi:[1,0,1]
	ds_read_b128 v[140:143], v149 offset:8224
	ds_read_b128 v[144:147], v149 offset:4144
	v_pk_fma_f32 v[190:191], v[34:35], v[132:133], v[170:171] op_sel_hi:[1,0,1]
	s_add_i32 s48, s48, 1
	s_waitcnt lgkmcnt(2)
	v_pk_fma_f32 v[192:193], v[34:35], v[136:137], v[166:167] op_sel_hi:[1,0,1]
	ds_read_b128 v[160:163], v149 offset:12320
	ds_read_b128 v[164:167], v149 offset:8240
	s_waitcnt lgkmcnt(3)
	v_pk_fma_f32 v[194:195], v[32:33], v[140:141], v[178:179] op_sel_hi:[1,0,1]
	v_pk_fma_f32 v[196:197], v[34:35], v[140:141], v[176:177] op_sel_hi:[1,0,1]
	ds_read_b128 v[168:171], v149 offset:16416
	ds_read_b128 v[176:179], v149 offset:12336
	v_pk_fma_f32 v[172:173], v[32:33], v[136:137], v[172:173] op_sel_hi:[1,0,1]
	s_waitcnt vmcnt(22)
	v_pk_fma_f32 v[190:191], v[38:39], v[132:133], v[190:191] op_sel:[0,1,0]
	v_pk_fma_f32 v[132:133], v[36:37], v[132:133], v[188:189] op_sel:[0,1,0]
	s_waitcnt lgkmcnt(1)
	v_pk_fma_f32 v[186:187], v[32:33], v[168:169], v[186:187] op_sel_hi:[1,0,1]
	v_pk_fma_f32 v[184:185], v[34:35], v[168:169], v[184:185] op_sel_hi:[1,0,1]
	v_pk_fma_f32 v[188:189], v[38:39], v[136:137], v[192:193] op_sel:[0,1,0]
	v_pk_fma_f32 v[136:137], v[36:37], v[136:137], v[172:173] op_sel:[0,1,0]
	v_pk_fma_f32 v[184:185], v[38:39], v[168:169], v[184:185] op_sel:[0,1,0]
	v_pk_fma_f32 v[168:169], v[36:37], v[168:169], v[186:187] op_sel:[0,1,0]
	s_waitcnt vmcnt(21)
	v_pk_fma_f32 v[132:133], v[40:41], v[134:135], v[132:133] op_sel_hi:[1,0,1]
	v_pk_fma_f32 v[186:187], v[42:43], v[134:135], v[190:191] op_sel_hi:[1,0,1]
	v_mov_b32_e32 v134, v135
	v_pk_fma_f32 v[200:201], v[34:35], v[160:161], v[180:181] op_sel_hi:[1,0,1]
	v_pk_fma_f32 v[172:173], v[38:39], v[140:141], v[196:197] op_sel:[0,1,0]
	v_pk_fma_f32 v[140:141], v[36:37], v[140:141], v[194:195] op_sel:[0,1,0]
	v_pk_fma_f32 v[136:137], v[40:41], v[138:139], v[136:137] op_sel_hi:[1,0,1]
	v_pk_fma_f32 v[188:189], v[42:43], v[138:139], v[188:189] op_sel_hi:[1,0,1]
	s_waitcnt vmcnt(20)
	v_pk_fma_f32 v[186:187], v[46:47], v[134:135], v[186:187] op_sel_hi:[1,0,1]
	v_pk_fma_f32 v[132:133], v[44:45], v[134:135], v[132:133] op_sel_hi:[1,0,1]
	v_mov_b32_e32 v134, v139
	v_pk_fma_f32 v[198:199], v[32:33], v[160:161], v[182:183] op_sel_hi:[1,0,1]
	ds_read_b128 v[180:183], v149 offset:16432
	v_pk_fma_f32 v[192:193], v[38:39], v[160:161], v[200:201] op_sel:[0,1,0]
	v_pk_fma_f32 v[140:141], v[40:41], v[142:143], v[140:141] op_sel_hi:[1,0,1]
	v_pk_fma_f32 v[172:173], v[42:43], v[142:143], v[172:173] op_sel_hi:[1,0,1]
	v_pk_fma_f32 v[138:139], v[46:47], v[134:135], v[188:189] op_sel_hi:[1,0,1]
	v_pk_fma_f32 v[134:135], v[44:45], v[134:135], v[136:137] op_sel_hi:[1,0,1]
	v_mov_b32_e32 v136, v143
	v_pk_fma_f32 v[160:161], v[36:37], v[160:161], v[198:199] op_sel:[0,1,0]
	v_pk_fma_f32 v[190:191], v[42:43], v[162:163], v[192:193] op_sel_hi:[1,0,1]
	v_pk_fma_f32 v[142:143], v[46:47], v[136:137], v[172:173] op_sel_hi:[1,0,1]
	v_pk_fma_f32 v[136:137], v[44:45], v[136:137], v[140:141] op_sel_hi:[1,0,1]
	v_mov_b32_e32 v140, v163
	v_pk_fma_f32 v[160:161], v[40:41], v[162:163], v[160:161] op_sel_hi:[1,0,1]
	v_pk_fma_f32 v[168:169], v[40:41], v[170:171], v[168:169] op_sel_hi:[1,0,1]
	v_pk_fma_f32 v[184:185], v[42:43], v[170:171], v[184:185] op_sel_hi:[1,0,1]
	v_pk_fma_f32 v[162:163], v[46:47], v[140:141], v[190:191] op_sel_hi:[1,0,1]
	v_mov_b32_e32 v156, v171
	s_waitcnt vmcnt(19)
	v_pk_fma_f32 v[132:133], v[48:49], v[128:129], v[132:133] op_sel_hi:[1,0,1]
	v_pk_fma_f32 v[170:171], v[50:51], v[128:129], v[186:187] op_sel_hi:[1,0,1]
	v_pk_fma_f32 v[134:135], v[48:49], v[144:145], v[134:135] op_sel_hi:[1,0,1]
	v_pk_fma_f32 v[138:139], v[50:51], v[144:145], v[138:139] op_sel_hi:[1,0,1]
	v_pk_fma_f32 v[142:143], v[50:51], v[164:165], v[142:143] op_sel_hi:[1,0,1]
	s_waitcnt lgkmcnt(1)
	v_pk_fma_f32 v[162:163], v[50:51], v[176:177], v[162:163] op_sel_hi:[1,0,1]
	s_waitcnt vmcnt(18)
	v_pk_fma_f32 v[170:171], v[54:55], v[128:129], v[170:171] op_sel:[0,1,0]
	v_pk_fma_f32 v[128:129], v[52:53], v[128:129], v[132:133] op_sel:[0,1,0]
	v_pk_fma_f32 v[140:141], v[44:45], v[140:141], v[160:161] op_sel_hi:[1,0,1]
	v_pk_fma_f32 v[160:161], v[46:47], v[156:157], v[184:185] op_sel_hi:[1,0,1]
	v_pk_fma_f32 v[168:169], v[44:45], v[156:157], v[168:169] op_sel_hi:[1,0,1]
	v_pk_fma_f32 v[136:137], v[48:49], v[164:165], v[136:137] op_sel_hi:[1,0,1]
	v_pk_fma_f32 v[132:133], v[54:55], v[144:145], v[138:139] op_sel:[0,1,0]
	v_pk_fma_f32 v[134:135], v[52:53], v[144:145], v[134:135] op_sel:[0,1,0]
	v_pk_fma_f32 v[138:139], v[54:55], v[164:165], v[142:143] op_sel:[0,1,0]
	v_pk_fma_f32 v[142:143], v[54:55], v[176:177], v[162:163] op_sel:[0,1,0]
	s_waitcnt vmcnt(17)
	v_pk_fma_f32 v[128:129], v[56:57], v[130:131], v[128:129] op_sel_hi:[1,0,1]
	v_pk_fma_f32 v[162:163], v[58:59], v[130:131], v[170:171] op_sel_hi:[1,0,1]
	v_mov_b32_e32 v130, v131
	v_pk_fma_f32 v[140:141], v[48:49], v[176:177], v[140:141] op_sel_hi:[1,0,1]
	s_waitcnt lgkmcnt(0)
	v_pk_fma_f32 v[168:169], v[48:49], v[180:181], v[168:169] op_sel_hi:[1,0,1]
	v_pk_fma_f32 v[160:161], v[50:51], v[180:181], v[160:161] op_sel_hi:[1,0,1]
	v_pk_fma_f32 v[136:137], v[52:53], v[164:165], v[136:137] op_sel:[0,1,0]
	v_pk_fma_f32 v[134:135], v[56:57], v[146:147], v[134:135] op_sel_hi:[1,0,1]
	v_pk_fma_f32 v[132:133], v[58:59], v[146:147], v[132:133] op_sel_hi:[1,0,1]
	s_waitcnt vmcnt(16)
	v_pk_fma_f32 v[164:165], v[60:61], v[130:131], v[128:129] op_sel_hi:[1,0,1]
	v_mov_b32_e32 v128, v147
	v_pk_fma_f32 v[140:141], v[52:53], v[176:177], v[140:141] op_sel:[0,1,0]
	v_pk_fma_f32 v[144:145], v[54:55], v[180:181], v[160:161] op_sel:[0,1,0]
	v_pk_fma_f32 v[160:161], v[52:53], v[180:181], v[168:169] op_sel:[0,1,0]
	v_pk_fma_f32 v[136:137], v[56:57], v[166:167], v[136:137] op_sel_hi:[1,0,1]
	v_pk_fma_f32 v[138:139], v[58:59], v[166:167], v[138:139] op_sel_hi:[1,0,1]
	v_pk_fma_f32 v[168:169], v[62:63], v[128:129], v[132:133] op_sel_hi:[1,0,1]
	v_pk_fma_f32 v[170:171], v[60:61], v[128:129], v[134:135] op_sel_hi:[1,0,1]
	v_mov_b32_e32 v128, v167
	v_pk_fma_f32 v[140:141], v[56:57], v[178:179], v[140:141] op_sel_hi:[1,0,1]
	v_pk_fma_f32 v[142:143], v[58:59], v[178:179], v[142:143] op_sel_hi:[1,0,1]
	v_pk_fma_f32 v[172:173], v[62:63], v[128:129], v[138:139] op_sel_hi:[1,0,1]
	v_pk_fma_f32 v[176:177], v[60:61], v[128:129], v[136:137] op_sel_hi:[1,0,1]
	v_mov_b32_e32 v128, v179
	v_pk_fma_f32 v[160:161], v[56:57], v[182:183], v[160:161] op_sel_hi:[1,0,1]
	v_pk_fma_f32 v[144:145], v[58:59], v[182:183], v[144:145] op_sel_hi:[1,0,1]
	v_pk_fma_f32 v[162:163], v[62:63], v[130:131], v[162:163] op_sel_hi:[1,0,1]
	v_pk_fma_f32 v[180:181], v[62:63], v[128:129], v[142:143] op_sel_hi:[1,0,1]
	v_pk_fma_f32 v[184:185], v[60:61], v[128:129], v[140:141] op_sel_hi:[1,0,1]
	v_mov_b32_e32 v132, v183
	ds_read_b128 v[128:131], v149 offset:64
	v_pk_fma_f32 v[186:187], v[62:63], v[132:133], v[144:145] op_sel_hi:[1,0,1]
	v_pk_fma_f32 v[188:189], v[60:61], v[132:133], v[160:161] op_sel_hi:[1,0,1]
	ds_read_b128 v[132:135], v149 offset:4160
	ds_read_b128 v[136:139], v149 offset:80
	ds_read_b128 v[140:143], v149 offset:8256
	ds_read_b128 v[144:147], v149 offset:4176
	s_waitcnt vmcnt(15) lgkmcnt(4)
	v_pk_fma_f32 v[190:191], v[64:65], v[128:129], v[164:165] op_sel_hi:[1,0,1]
	v_pk_fma_f32 v[192:193], v[66:67], v[128:129], v[162:163] op_sel_hi:[1,0,1]
	s_waitcnt lgkmcnt(3)
	v_pk_fma_f32 v[194:195], v[64:65], v[132:133], v[170:171] op_sel_hi:[1,0,1]
	v_pk_fma_f32 v[196:197], v[66:67], v[132:133], v[168:169] op_sel_hi:[1,0,1]
	ds_read_b128 v[160:163], v149 offset:12352
	ds_read_b128 v[164:167], v149 offset:8272
	s_waitcnt lgkmcnt(3)
	v_pk_fma_f32 v[198:199], v[64:65], v[140:141], v[176:177] op_sel_hi:[1,0,1]
	ds_read_b128 v[168:171], v149 offset:16448
	ds_read_b128 v[176:179], v149 offset:12368
	s_waitcnt vmcnt(14)
	v_pk_fma_f32 v[192:193], v[70:71], v[128:129], v[192:193] op_sel:[0,1,0]
	s_waitcnt lgkmcnt(3)
	v_pk_fma_f32 v[184:185], v[64:65], v[160:161], v[184:185] op_sel_hi:[1,0,1]
	v_pk_fma_f32 v[200:201], v[66:67], v[160:161], v[180:181] op_sel_hi:[1,0,1]
	s_waitcnt lgkmcnt(1)
	v_pk_fma_f32 v[186:187], v[66:67], v[168:169], v[186:187] op_sel_hi:[1,0,1]
	v_pk_fma_f32 v[128:129], v[68:69], v[128:129], v[190:191] op_sel:[0,1,0]
	v_pk_fma_f32 v[172:173], v[66:67], v[140:141], v[172:173] op_sel_hi:[1,0,1]
	v_pk_fma_f32 v[188:189], v[64:65], v[168:169], v[188:189] op_sel_hi:[1,0,1]
	v_pk_fma_f32 v[190:191], v[70:71], v[132:133], v[196:197] op_sel:[0,1,0]
	v_pk_fma_f32 v[132:133], v[68:69], v[132:133], v[194:195] op_sel:[0,1,0]
	v_pk_fma_f32 v[194:195], v[70:71], v[160:161], v[200:201] op_sel:[0,1,0]
	v_pk_fma_f32 v[160:161], v[68:69], v[160:161], v[184:185] op_sel:[0,1,0]
	v_pk_fma_f32 v[184:185], v[70:71], v[168:169], v[186:187] op_sel:[0,1,0]
	s_waitcnt vmcnt(13)
	v_pk_fma_f32 v[128:129], v[72:73], v[130:131], v[128:129] op_sel_hi:[1,0,1]
	v_pk_fma_f32 v[186:187], v[74:75], v[130:131], v[192:193] op_sel_hi:[1,0,1]
	v_mov_b32_e32 v130, v131
	v_pk_fma_f32 v[172:173], v[70:71], v[140:141], v[172:173] op_sel:[0,1,0]
	v_pk_fma_f32 v[140:141], v[68:69], v[140:141], v[198:199] op_sel:[0,1,0]
	v_pk_fma_f32 v[168:169], v[68:69], v[168:169], v[188:189] op_sel:[0,1,0]
	v_pk_fma_f32 v[132:133], v[72:73], v[134:135], v[132:133] op_sel_hi:[1,0,1]
	v_pk_fma_f32 v[188:189], v[74:75], v[134:135], v[190:191] op_sel_hi:[1,0,1]
	s_waitcnt vmcnt(12)
	v_pk_fma_f32 v[186:187], v[78:79], v[130:131], v[186:187] op_sel_hi:[1,0,1]
	v_pk_fma_f32 v[128:129], v[76:77], v[130:131], v[128:129] op_sel_hi:[1,0,1]
	v_mov_b32_e32 v130, v135
	ds_read_b128 v[180:183], v149 offset:16464
	v_pk_fma_f32 v[140:141], v[72:73], v[142:143], v[140:141] op_sel_hi:[1,0,1]
	v_pk_fma_f32 v[172:173], v[74:75], v[142:143], v[172:173] op_sel_hi:[1,0,1]
	v_pk_fma_f32 v[134:135], v[78:79], v[130:131], v[188:189] op_sel_hi:[1,0,1]
	v_pk_fma_f32 v[130:131], v[76:77], v[130:131], v[132:133] op_sel_hi:[1,0,1]
	v_mov_b32_e32 v132, v143
	v_pk_fma_f32 v[190:191], v[74:75], v[162:163], v[194:195] op_sel_hi:[1,0,1]
	v_pk_fma_f32 v[142:143], v[78:79], v[132:133], v[172:173] op_sel_hi:[1,0,1]
	v_pk_fma_f32 v[132:133], v[76:77], v[132:133], v[140:141] op_sel_hi:[1,0,1]
	v_mov_b32_e32 v140, v163
	v_pk_fma_f32 v[160:161], v[72:73], v[162:163], v[160:161] op_sel_hi:[1,0,1]
	v_pk_fma_f32 v[168:169], v[72:73], v[170:171], v[168:169] op_sel_hi:[1,0,1]
	v_pk_fma_f32 v[184:185], v[74:75], v[170:171], v[184:185] op_sel_hi:[1,0,1]
	v_pk_fma_f32 v[162:163], v[78:79], v[140:141], v[190:191] op_sel_hi:[1,0,1]
	v_mov_b32_e32 v156, v171
	s_waitcnt vmcnt(11)
	v_pk_fma_f32 v[128:129], v[80:81], v[136:137], v[128:129] op_sel_hi:[1,0,1]
	v_pk_fma_f32 v[170:171], v[82:83], v[136:137], v[186:187] op_sel_hi:[1,0,1]
	v_pk_fma_f32 v[130:131], v[80:81], v[144:145], v[130:131] op_sel_hi:[1,0,1]
	v_pk_fma_f32 v[134:135], v[82:83], v[144:145], v[134:135] op_sel_hi:[1,0,1]
	v_pk_fma_f32 v[142:143], v[82:83], v[164:165], v[142:143] op_sel_hi:[1,0,1]
	s_waitcnt lgkmcnt(1)
	v_pk_fma_f32 v[162:163], v[82:83], v[176:177], v[162:163] op_sel_hi:[1,0,1]
	s_waitcnt vmcnt(10)
	v_pk_fma_f32 v[170:171], v[86:87], v[136:137], v[170:171] op_sel:[0,1,0]
	v_pk_fma_f32 v[128:129], v[84:85], v[136:137], v[128:129] op_sel:[0,1,0]
	v_pk_fma_f32 v[140:141], v[76:77], v[140:141], v[160:161] op_sel_hi:[1,0,1]
	v_pk_fma_f32 v[160:161], v[78:79], v[156:157], v[184:185] op_sel_hi:[1,0,1]
	v_pk_fma_f32 v[168:169], v[76:77], v[156:157], v[168:169] op_sel_hi:[1,0,1]
	v_pk_fma_f32 v[132:133], v[80:81], v[164:165], v[132:133] op_sel_hi:[1,0,1]
	v_pk_fma_f32 v[134:135], v[86:87], v[144:145], v[134:135] op_sel:[0,1,0]
	v_pk_fma_f32 v[130:131], v[84:85], v[144:145], v[130:131] op_sel:[0,1,0]
	v_pk_fma_f32 v[136:137], v[86:87], v[164:165], v[142:143] op_sel:[0,1,0]
	v_pk_fma_f32 v[142:143], v[86:87], v[176:177], v[162:163] op_sel:[0,1,0]
	s_waitcnt vmcnt(9)
	v_pk_fma_f32 v[128:129], v[88:89], v[138:139], v[128:129] op_sel_hi:[1,0,1]
	v_pk_fma_f32 v[162:163], v[90:91], v[138:139], v[170:171] op_sel_hi:[1,0,1]
	v_mov_b32_e32 v138, v139
	v_pk_fma_f32 v[140:141], v[80:81], v[176:177], v[140:141] op_sel_hi:[1,0,1]
	s_waitcnt lgkmcnt(0)
	v_pk_fma_f32 v[168:169], v[80:81], v[180:181], v[168:169] op_sel_hi:[1,0,1]
	v_pk_fma_f32 v[160:161], v[82:83], v[180:181], v[160:161] op_sel_hi:[1,0,1]
	v_pk_fma_f32 v[132:133], v[84:85], v[164:165], v[132:133] op_sel:[0,1,0]
	v_pk_fma_f32 v[130:131], v[88:89], v[146:147], v[130:131] op_sel_hi:[1,0,1]
	v_pk_fma_f32 v[134:135], v[90:91], v[146:147], v[134:135] op_sel_hi:[1,0,1]
	s_waitcnt vmcnt(8)
	v_pk_fma_f32 v[164:165], v[92:93], v[138:139], v[128:129] op_sel_hi:[1,0,1]
	v_mov_b32_e32 v128, v147
	v_pk_fma_f32 v[140:141], v[84:85], v[176:177], v[140:141] op_sel:[0,1,0]
	v_pk_fma_f32 v[144:145], v[86:87], v[180:181], v[160:161] op_sel:[0,1,0]
	v_pk_fma_f32 v[160:161], v[84:85], v[180:181], v[168:169] op_sel:[0,1,0]
	v_pk_fma_f32 v[132:133], v[88:89], v[166:167], v[132:133] op_sel_hi:[1,0,1]
	v_pk_fma_f32 v[136:137], v[90:91], v[166:167], v[136:137] op_sel_hi:[1,0,1]
	v_pk_fma_f32 v[168:169], v[94:95], v[128:129], v[134:135] op_sel_hi:[1,0,1]
	v_pk_fma_f32 v[170:171], v[92:93], v[128:129], v[130:131] op_sel_hi:[1,0,1]
	v_mov_b32_e32 v128, v167
	v_pk_fma_f32 v[140:141], v[88:89], v[178:179], v[140:141] op_sel_hi:[1,0,1]
	v_pk_fma_f32 v[142:143], v[90:91], v[178:179], v[142:143] op_sel_hi:[1,0,1]
	v_pk_fma_f32 v[172:173], v[94:95], v[128:129], v[136:137] op_sel_hi:[1,0,1]
	v_pk_fma_f32 v[176:177], v[92:93], v[128:129], v[132:133] op_sel_hi:[1,0,1]
	v_mov_b32_e32 v128, v179
	v_pk_fma_f32 v[160:161], v[88:89], v[182:183], v[160:161] op_sel_hi:[1,0,1]
	v_pk_fma_f32 v[144:145], v[90:91], v[182:183], v[144:145] op_sel_hi:[1,0,1]
	v_pk_fma_f32 v[180:181], v[94:95], v[128:129], v[142:143] op_sel_hi:[1,0,1]
	v_pk_fma_f32 v[184:185], v[92:93], v[128:129], v[140:141] op_sel_hi:[1,0,1]
	v_mov_b32_e32 v132, v183
	ds_read_b128 v[128:131], v149 offset:96
	v_pk_fma_f32 v[162:163], v[94:95], v[138:139], v[162:163] op_sel_hi:[1,0,1]
	v_pk_fma_f32 v[186:187], v[94:95], v[132:133], v[144:145] op_sel_hi:[1,0,1]
	v_pk_fma_f32 v[188:189], v[92:93], v[132:133], v[160:161] op_sel_hi:[1,0,1]
	ds_read_b128 v[132:135], v149 offset:4192
	ds_read_b128 v[136:139], v149 offset:112
	ds_read_b128 v[140:143], v149 offset:8288
	ds_read_b128 v[144:147], v149 offset:4208
	s_waitcnt vmcnt(7) lgkmcnt(4)
	v_pk_fma_f32 v[190:191], v[96:97], v[128:129], v[164:165] op_sel_hi:[1,0,1]
	v_pk_fma_f32 v[192:193], v[98:99], v[128:129], v[162:163] op_sel_hi:[1,0,1]
	s_waitcnt lgkmcnt(3)
	v_pk_fma_f32 v[194:195], v[96:97], v[132:133], v[170:171] op_sel_hi:[1,0,1]
	v_pk_fma_f32 v[196:197], v[98:99], v[132:133], v[168:169] op_sel_hi:[1,0,1]
	ds_read_b128 v[160:163], v149 offset:12384
	ds_read_b128 v[164:167], v149 offset:8304
	s_waitcnt lgkmcnt(3)
	v_pk_fma_f32 v[198:199], v[96:97], v[140:141], v[176:177] op_sel_hi:[1,0,1]
	ds_read_b128 v[168:171], v149 offset:16480
	ds_read_b128 v[176:179], v149 offset:12400
	s_waitcnt vmcnt(6)
	v_pk_fma_f32 v[192:193], v[102:103], v[128:129], v[192:193] op_sel:[0,1,0]
	s_waitcnt lgkmcnt(3)
	v_pk_fma_f32 v[184:185], v[96:97], v[160:161], v[184:185] op_sel_hi:[1,0,1]
	v_pk_fma_f32 v[200:201], v[98:99], v[160:161], v[180:181] op_sel_hi:[1,0,1]
	s_waitcnt lgkmcnt(1)
	v_pk_fma_f32 v[186:187], v[98:99], v[168:169], v[186:187] op_sel_hi:[1,0,1]
	v_pk_fma_f32 v[128:129], v[100:101], v[128:129], v[190:191] op_sel:[0,1,0]
	v_pk_fma_f32 v[172:173], v[98:99], v[140:141], v[172:173] op_sel_hi:[1,0,1]
	ds_read_b128 v[180:183], v149 offset:16496
	v_pk_fma_f32 v[188:189], v[96:97], v[168:169], v[188:189] op_sel_hi:[1,0,1]
	v_pk_fma_f32 v[190:191], v[102:103], v[132:133], v[196:197] op_sel:[0,1,0]
	v_pk_fma_f32 v[132:133], v[100:101], v[132:133], v[194:195] op_sel:[0,1,0]
	v_pk_fma_f32 v[194:195], v[102:103], v[160:161], v[200:201] op_sel:[0,1,0]
	v_pk_fma_f32 v[160:161], v[100:101], v[160:161], v[184:185] op_sel:[0,1,0]
	v_pk_fma_f32 v[184:185], v[102:103], v[168:169], v[186:187] op_sel:[0,1,0]
	s_waitcnt vmcnt(5)
	v_pk_fma_f32 v[128:129], v[104:105], v[130:131], v[128:129] op_sel_hi:[1,0,1]
	v_pk_fma_f32 v[186:187], v[106:107], v[130:131], v[192:193] op_sel_hi:[1,0,1]
	v_mov_b32_e32 v130, v131
	v_pk_fma_f32 v[172:173], v[102:103], v[140:141], v[172:173] op_sel:[0,1,0]
	v_pk_fma_f32 v[140:141], v[100:101], v[140:141], v[198:199] op_sel:[0,1,0]
	v_pk_fma_f32 v[168:169], v[100:101], v[168:169], v[188:189] op_sel:[0,1,0]
	v_pk_fma_f32 v[132:133], v[104:105], v[134:135], v[132:133] op_sel_hi:[1,0,1]
	v_pk_fma_f32 v[188:189], v[106:107], v[134:135], v[190:191] op_sel_hi:[1,0,1]
	s_waitcnt vmcnt(4)
	v_pk_fma_f32 v[186:187], v[110:111], v[130:131], v[186:187] op_sel_hi:[1,0,1]
	v_pk_fma_f32 v[128:129], v[108:109], v[130:131], v[128:129] op_sel_hi:[1,0,1]
	v_mov_b32_e32 v130, v135
	v_pk_fma_f32 v[140:141], v[104:105], v[142:143], v[140:141] op_sel_hi:[1,0,1]
	v_pk_fma_f32 v[172:173], v[106:107], v[142:143], v[172:173] op_sel_hi:[1,0,1]
	v_pk_fma_f32 v[134:135], v[110:111], v[130:131], v[188:189] op_sel_hi:[1,0,1]
	v_pk_fma_f32 v[130:131], v[108:109], v[130:131], v[132:133] op_sel_hi:[1,0,1]
	v_mov_b32_e32 v132, v143
	v_pk_fma_f32 v[160:161], v[104:105], v[162:163], v[160:161] op_sel_hi:[1,0,1]
	v_pk_fma_f32 v[190:191], v[106:107], v[162:163], v[194:195] op_sel_hi:[1,0,1]
	v_pk_fma_f32 v[168:169], v[104:105], v[170:171], v[168:169] op_sel_hi:[1,0,1]
	v_pk_fma_f32 v[184:185], v[106:107], v[170:171], v[184:185] op_sel_hi:[1,0,1]
	v_pk_fma_f32 v[142:143], v[110:111], v[132:133], v[172:173] op_sel_hi:[1,0,1]
	v_pk_fma_f32 v[132:133], v[108:109], v[132:133], v[140:141] op_sel_hi:[1,0,1]
	v_mov_b32_e32 v140, v163
	v_mov_b32_e32 v156, v171
	v_pk_fma_f32 v[162:163], v[110:111], v[140:141], v[190:191] op_sel_hi:[1,0,1]
	v_pk_fma_f32 v[140:141], v[108:109], v[140:141], v[160:161] op_sel_hi:[1,0,1]
	v_pk_fma_f32 v[160:161], v[110:111], v[156:157], v[184:185] op_sel_hi:[1,0,1]
	v_pk_fma_f32 v[168:169], v[108:109], v[156:157], v[168:169] op_sel_hi:[1,0,1]
	s_waitcnt vmcnt(3)
	v_pk_fma_f32 v[128:129], v[112:113], v[136:137], v[128:129] op_sel_hi:[1,0,1]
	v_pk_fma_f32 v[170:171], v[114:115], v[136:137], v[186:187] op_sel_hi:[1,0,1]
	v_pk_fma_f32 v[130:131], v[112:113], v[144:145], v[130:131] op_sel_hi:[1,0,1]
	v_pk_fma_f32 v[134:135], v[114:115], v[144:145], v[134:135] op_sel_hi:[1,0,1]
	v_pk_fma_f32 v[132:133], v[112:113], v[164:165], v[132:133] op_sel_hi:[1,0,1]
	v_pk_fma_f32 v[142:143], v[114:115], v[164:165], v[142:143] op_sel_hi:[1,0,1]
	s_waitcnt lgkmcnt(1)
	v_pk_fma_f32 v[140:141], v[112:113], v[176:177], v[140:141] op_sel_hi:[1,0,1]
	v_pk_fma_f32 v[162:163], v[114:115], v[176:177], v[162:163] op_sel_hi:[1,0,1]
	s_waitcnt lgkmcnt(0)
	v_pk_fma_f32 v[168:169], v[112:113], v[180:181], v[168:169] op_sel_hi:[1,0,1]
	v_pk_fma_f32 v[160:161], v[114:115], v[180:181], v[160:161] op_sel_hi:[1,0,1]
	s_waitcnt vmcnt(2)
	v_pk_fma_f32 v[170:171], v[118:119], v[136:137], v[170:171] op_sel:[0,1,0]
	v_pk_fma_f32 v[128:129], v[116:117], v[136:137], v[128:129] op_sel:[0,1,0]
	v_pk_fma_f32 v[134:135], v[118:119], v[144:145], v[134:135] op_sel:[0,1,0]
	v_pk_fma_f32 v[130:131], v[116:117], v[144:145], v[130:131] op_sel:[0,1,0]
	v_pk_fma_f32 v[136:137], v[118:119], v[164:165], v[142:143] op_sel:[0,1,0]
	v_pk_fma_f32 v[132:133], v[116:117], v[164:165], v[132:133] op_sel:[0,1,0]
	v_pk_fma_f32 v[142:143], v[118:119], v[176:177], v[162:163] op_sel:[0,1,0]
	v_pk_fma_f32 v[140:141], v[116:117], v[176:177], v[140:141] op_sel:[0,1,0]
	v_pk_fma_f32 v[144:145], v[118:119], v[180:181], v[160:161] op_sel:[0,1,0]
	v_pk_fma_f32 v[160:161], v[116:117], v[180:181], v[168:169] op_sel:[0,1,0]
	s_waitcnt vmcnt(1)
	v_pk_fma_f32 v[128:129], v[120:121], v[138:139], v[128:129] op_sel_hi:[1,0,1]
	v_pk_fma_f32 v[162:163], v[122:123], v[138:139], v[170:171] op_sel_hi:[1,0,1]
	v_pk_fma_f32 v[164:165], v[120:121], v[146:147], v[130:131] op_sel_hi:[1,0,1]
	v_pk_fma_f32 v[134:135], v[122:123], v[146:147], v[134:135] op_sel_hi:[1,0,1]
	v_pk_fma_f32 v[168:169], v[120:121], v[166:167], v[132:133] op_sel_hi:[1,0,1]
	v_pk_fma_f32 v[136:137], v[122:123], v[166:167], v[136:137] op_sel_hi:[1,0,1]
	v_mov_b32_e32 v132, v139
	v_mov_b32_e32 v146, v167
	v_pk_fma_f32 v[140:141], v[120:121], v[178:179], v[140:141] op_sel_hi:[1,0,1]
	v_pk_fma_f32 v[142:143], v[122:123], v[178:179], v[142:143] op_sel_hi:[1,0,1]
	v_pk_fma_f32 v[160:161], v[120:121], v[182:183], v[160:161] op_sel_hi:[1,0,1]
	v_pk_fma_f32 v[144:145], v[122:123], v[182:183], v[144:145] op_sel_hi:[1,0,1]
	s_waitcnt vmcnt(0)
	v_pk_fma_f32 v[130:131], v[126:127], v[132:133], v[162:163] op_sel_hi:[1,0,1]
	v_pk_fma_f32 v[128:129], v[124:125], v[132:133], v[128:129] op_sel_hi:[1,0,1]
	v_mov_b32_e32 v132, v147
	v_pk_fma_f32 v[138:139], v[126:127], v[146:147], v[136:137] op_sel_hi:[1,0,1]
	v_pk_fma_f32 v[136:137], v[124:125], v[146:147], v[168:169] op_sel_hi:[1,0,1]
	v_mov_b32_e32 v146, v179
	v_mov_b32_e32 v156, v183
	v_pk_fma_f32 v[134:135], v[126:127], v[132:133], v[134:135] op_sel_hi:[1,0,1]
	v_pk_fma_f32 v[132:133], v[124:125], v[132:133], v[164:165] op_sel_hi:[1,0,1]
	v_pk_fma_f32 v[142:143], v[126:127], v[146:147], v[142:143] op_sel_hi:[1,0,1]
	v_pk_fma_f32 v[140:141], v[124:125], v[146:147], v[140:141] op_sel_hi:[1,0,1]
	v_pk_fma_f32 v[146:147], v[126:127], v[156:157], v[144:145] op_sel_hi:[1,0,1]
	s_cmp_ge_u32 s48, s18
	v_pk_fma_f32 v[144:145], v[124:125], v[156:157], v[160:161] op_sel_hi:[1,0,1]
	s_cbranch_scc1 .LBB0_32
	s_add_i32 s10, s2, 0x70
	s_mul_hi_u32 s16, s10, 0xaaaaaaab
	s_lshr_b32 s49, s16, 6
	v_mad_u64_u32 v[0:1], s[16:17], s49, v158, v[150:151]
	s_mulk_i32 s49, 0x60
	s_sub_i32 s10, s10, s49
	s_lshl_b32 s10, s10, 6
	v_lshl_add_u64 v[120:121], s[10:11], 2, v[0:1]
	s_nop 0
	v_add_co_u32_e32 v4, vcc, s19, v120
	s_nop 1
	v_addc_co_u32_e32 v5, vcc, 0, v121, vcc
	v_add_co_u32_e32 v8, vcc, s20, v120
	global_load_dwordx4 v[0:3], v[120:121], off
	s_nop 0
	global_load_dwordx4 v[4:7], v[4:5], off
	v_addc_co_u32_e32 v9, vcc, 0, v121, vcc
	v_add_co_u32_e32 v12, vcc, s22, v120
	s_nop 1
	v_addc_co_u32_e32 v13, vcc, 0, v121, vcc
	v_add_co_u32_e32 v16, vcc, s23, v120
	global_load_dwordx4 v[8:11], v[8:9], off
	s_nop 0
	global_load_dwordx4 v[12:15], v[12:13], off
	v_addc_co_u32_e32 v17, vcc, 0, v121, vcc
	v_add_co_u32_e32 v20, vcc, s24, v120
	s_nop 1
	v_addc_co_u32_e32 v21, vcc, 0, v121, vcc
	v_add_co_u32_e32 v24, vcc, s25, v120
	global_load_dwordx4 v[16:19], v[16:17], off
	s_nop 0
	global_load_dwordx4 v[20:23], v[20:21], off
	v_addc_co_u32_e32 v25, vcc, 0, v121, vcc
	v_add_co_u32_e32 v28, vcc, s26, v120
	s_nop 1
	v_addc_co_u32_e32 v29, vcc, 0, v121, vcc
	v_add_co_u32_e32 v32, vcc, s27, v120
	global_load_dwordx4 v[24:27], v[24:25], off
	s_nop 0
	global_load_dwordx4 v[28:31], v[28:29], off
	v_addc_co_u32_e32 v33, vcc, 0, v121, vcc
	v_add_co_u32_e32 v36, vcc, s28, v120
	s_nop 1
	v_addc_co_u32_e32 v37, vcc, 0, v121, vcc
	v_add_co_u32_e32 v40, vcc, s29, v120
	global_load_dwordx4 v[32:35], v[32:33], off
	s_nop 0
	global_load_dwordx4 v[36:39], v[36:37], off
	v_addc_co_u32_e32 v41, vcc, 0, v121, vcc
	v_add_co_u32_e32 v44, vcc, s30, v120
	s_nop 1
	v_addc_co_u32_e32 v45, vcc, 0, v121, vcc
	v_add_co_u32_e32 v48, vcc, s31, v120
	global_load_dwordx4 v[40:43], v[40:41], off
	s_nop 0
	global_load_dwordx4 v[44:47], v[44:45], off
	v_addc_co_u32_e32 v49, vcc, 0, v121, vcc
	v_add_co_u32_e32 v52, vcc, s33, v120
	s_nop 1
	v_addc_co_u32_e32 v53, vcc, 0, v121, vcc
	v_add_co_u32_e32 v56, vcc, s34, v120
	global_load_dwordx4 v[48:51], v[48:49], off
	s_nop 0
	global_load_dwordx4 v[52:55], v[52:53], off
	v_addc_co_u32_e32 v57, vcc, 0, v121, vcc
	v_add_co_u32_e32 v60, vcc, s35, v120
	s_nop 1
	v_addc_co_u32_e32 v61, vcc, 0, v121, vcc
	v_add_co_u32_e32 v64, vcc, s36, v120
	global_load_dwordx4 v[56:59], v[56:57], off
	s_nop 0
	global_load_dwordx4 v[60:63], v[60:61], off
	v_addc_co_u32_e32 v65, vcc, 0, v121, vcc
	v_add_co_u32_e32 v68, vcc, s37, v120
	s_nop 1
	v_addc_co_u32_e32 v69, vcc, 0, v121, vcc
	v_add_co_u32_e32 v72, vcc, s38, v120
	global_load_dwordx4 v[64:67], v[64:65], off
	s_nop 0
	global_load_dwordx4 v[68:71], v[68:69], off
	v_addc_co_u32_e32 v73, vcc, 0, v121, vcc
	v_add_co_u32_e32 v76, vcc, s39, v120
	s_nop 1
	v_addc_co_u32_e32 v77, vcc, 0, v121, vcc
	v_add_co_u32_e32 v80, vcc, s40, v120
	global_load_dwordx4 v[72:75], v[72:73], off
	s_nop 0
	global_load_dwordx4 v[76:79], v[76:77], off
	v_addc_co_u32_e32 v81, vcc, 0, v121, vcc
	v_add_co_u32_e32 v84, vcc, s41, v120
	s_nop 1
	v_addc_co_u32_e32 v85, vcc, 0, v121, vcc
	v_add_co_u32_e32 v88, vcc, s42, v120
	global_load_dwordx4 v[80:83], v[80:81], off
	s_nop 0
	global_load_dwordx4 v[84:87], v[84:85], off
	v_addc_co_u32_e32 v89, vcc, 0, v121, vcc
	v_add_co_u32_e32 v92, vcc, s43, v120
	s_nop 1
	v_addc_co_u32_e32 v93, vcc, 0, v121, vcc
	v_add_co_u32_e32 v96, vcc, s44, v120
	global_load_dwordx4 v[88:91], v[88:89], off
	s_nop 0
	global_load_dwordx4 v[92:95], v[92:93], off
	v_addc_co_u32_e32 v97, vcc, 0, v121, vcc
	v_add_co_u32_e32 v100, vcc, s45, v120
	s_nop 1
	v_addc_co_u32_e32 v101, vcc, 0, v121, vcc
	v_add_co_u32_e32 v104, vcc, s46, v120
	global_load_dwordx4 v[96:99], v[96:97], off
	s_nop 0
	global_load_dwordx4 v[100:103], v[100:101], off
	v_addc_co_u32_e32 v105, vcc, 0, v121, vcc
	v_add_co_u32_e32 v108, vcc, s47, v120
	s_nop 1
	v_addc_co_u32_e32 v109, vcc, 0, v121, vcc
	v_add_co_u32_e32 v112, vcc, 0xa8000, v120
	global_load_dwordx4 v[104:107], v[104:105], off
	s_nop 0
	global_load_dwordx4 v[108:111], v[108:109], off
	v_addc_co_u32_e32 v113, vcc, 0, v121, vcc
	v_add_co_u32_e32 v116, vcc, 0xae000, v120
	s_nop 1
	v_addc_co_u32_e32 v117, vcc, 0, v121, vcc
	v_add_co_u32_e32 v122, vcc, 0xb4000, v120
	global_load_dwordx4 v[112:115], v[112:113], off
	s_nop 0
	global_load_dwordx4 v[116:119], v[116:117], off
	v_addc_co_u32_e32 v123, vcc, 0, v121, vcc
	v_add_co_u32_e32 v124, vcc, 0xba000, v120
	s_nop 1
	v_addc_co_u32_e32 v125, vcc, 0, v121, vcc
	global_load_dwordx4 v[120:123], v[122:123], off
	s_nop 0
	global_load_dwordx4 v[124:127], v[124:125], off

.LBB0_161:
	v_lshlrev_b64 v[0:1], 12, v[106:107]
	v_lshl_add_u64 v[4:5], v[104:105], 0, v[0:1]
	global_load_dwordx4 v[0:3], v[4:5], off offset:2048
	s_nop 0
	global_load_dwordx4 v[4:7], v[4:5], off offset:3072
	s_waitcnt vmcnt(0) lgkmcnt(0)
	v_lshlrev_b32_e32 v16, 16, v0
	v_and_b32_e32 v17, 0xffff0000, v0
	v_lshlrev_b32_e32 v18, 16, v1
	v_and_b32_e32 v19, 0xffff0000, v1
	v_lshlrev_b32_e32 v20, 16, v2
	v_and_b32_e32 v21, 0xffff0000, v2
	v_lshlrev_b32_e32 v22, 16, v3
	v_and_b32_e32 v23, 0xffff0000, v3
	v_lshlrev_b32_e32 v24, 16, v4
	v_and_b32_e32 v25, 0xffff0000, v4
	v_lshlrev_b32_e32 v26, 16, v5
	v_and_b32_e32 v27, 0xffff0000, v5
	v_lshlrev_b32_e32 v28, 16, v6
	v_and_b32_e32 v29, 0xffff0000, v6
	v_lshlrev_b32_e32 v30, 16, v7
	v_and_b32_e32 v31, 0xffff0000, v7

.LBB0_164:
	v_lshlrev_b64 v[0:1], 12, v[32:33]
	v_lshl_add_u64 v[4:5], v[104:105], 0, v[0:1]
	global_load_dwordx4 v[0:3], v[4:5], off offset:2048
	s_nop 0
	global_load_dwordx4 v[4:7], v[4:5], off offset:3072
	s_waitcnt vmcnt(0) lgkmcnt(0)
	v_lshlrev_b32_e32 v48, 16, v0
	v_and_b32_e32 v49, 0xffff0000, v0
	v_lshlrev_b32_e32 v50, 16, v1
	v_and_b32_e32 v51, 0xffff0000, v1
	v_lshlrev_b32_e32 v52, 16, v2
	v_and_b32_e32 v53, 0xffff0000, v2
	v_lshlrev_b32_e32 v54, 16, v3
	v_and_b32_e32 v55, 0xffff0000, v3
	v_lshlrev_b32_e32 v56, 16, v4
	v_and_b32_e32 v57, 0xffff0000, v4
	v_lshlrev_b32_e32 v58, 16, v5
	v_and_b32_e32 v59, 0xffff0000, v5
	v_lshlrev_b32_e32 v60, 16, v6
	v_and_b32_e32 v61, 0xffff0000, v6
	v_lshlrev_b32_e32 v62, 16, v7
	v_and_b32_e32 v63, 0xffff0000, v7

.LBB0_167:
	v_lshlrev_b64 v[0:1], 12, v[114:115]
	v_lshl_add_u64 v[4:5], v[104:105], 0, v[0:1]
	global_load_dwordx4 v[0:3], v[4:5], off offset:2048
	s_nop 0
	global_load_dwordx4 v[4:7], v[4:5], off offset:3072
	s_waitcnt vmcnt(0) lgkmcnt(0)
	v_lshlrev_b32_e32 v64, 16, v0
	v_and_b32_e32 v65, 0xffff0000, v0
	v_lshlrev_b32_e32 v66, 16, v1
	v_and_b32_e32 v67, 0xffff0000, v1
	v_lshlrev_b32_e32 v68, 16, v2
	v_and_b32_e32 v69, 0xffff0000, v2
	v_lshlrev_b32_e32 v70, 16, v3
	v_and_b32_e32 v71, 0xffff0000, v3
	v_lshlrev_b32_e32 v72, 16, v4
	v_and_b32_e32 v73, 0xffff0000, v4
	v_lshlrev_b32_e32 v74, 16, v5
	v_and_b32_e32 v75, 0xffff0000, v5
	v_lshlrev_b32_e32 v76, 16, v6
	v_and_b32_e32 v77, 0xffff0000, v6
	v_lshlrev_b32_e32 v78, 16, v7
	v_and_b32_e32 v79, 0xffff0000, v7

.LBB0_170:
	v_lshlrev_b64 v[0:1], 12, v[116:117]
	v_lshl_add_u64 v[4:5], v[104:105], 0, v[0:1]
	global_load_dwordx4 v[0:3], v[4:5], off offset:2048
	s_nop 0
	global_load_dwordx4 v[4:7], v[4:5], off offset:3072
	s_waitcnt vmcnt(0) lgkmcnt(0)
	v_lshlrev_b32_e32 v80, 16, v0
	v_and_b32_e32 v81, 0xffff0000, v0
	v_lshlrev_b32_e32 v82, 16, v1
	v_and_b32_e32 v83, 0xffff0000, v1
	v_lshlrev_b32_e32 v84, 16, v2
	v_and_b32_e32 v85, 0xffff0000, v2
	v_lshlrev_b32_e32 v86, 16, v3
	v_and_b32_e32 v87, 0xffff0000, v3
	v_lshlrev_b32_e32 v88, 16, v4
	v_and_b32_e32 v89, 0xffff0000, v4
	v_lshlrev_b32_e32 v90, 16, v5
	v_and_b32_e32 v91, 0xffff0000, v5
	v_lshlrev_b32_e32 v92, 16, v6
	v_and_b32_e32 v93, 0xffff0000, v6
	v_lshlrev_b32_e32 v94, 16, v7
	v_and_b32_e32 v95, 0xffff0000, v7

.LBB0_183:
	s_and_b64 vcc, exec, s[8:9]
	s_cbranch_vccnz .LBB0_158
	v_lshrrev_b32_e32 v64, 11, v109
	v_add_u32_e32 v64, 1, v64
	v_cmp_lt_i32_e32 vcc, s38, v106
	v_mov_b32_e32 v109, v97
	v_mov_b32_e32 v111, v97
	v_cndmask_b32_e32 v66, 0, v64, vcc
	v_mov_b64_e32 v[64:65], s[26:27]
	v_mad_u64_u32 v[64:65], s[8:9], v66, s39, v[64:65]
	v_lshl_add_u64 v[66:67], v[64:65], 0, s[30:31]
	v_lshl_add_u64 v[68:69], v[66:67], 0, v[96:97]
	global_load_dwordx4 v[80:83], v[68:69], off
	v_lshl_add_u64 v[68:69], v[66:67], 0, v[108:109]
	v_mov_b32_e32 v113, v97
	global_load_dwordx4 v[84:87], v[68:69], off
	v_lshl_add_u64 v[68:69], v[66:67], 0, v[110:111]
	v_lshl_add_u64 v[66:67], v[66:67], 0, v[112:113]
	global_load_dwordx4 v[88:91], v[68:69], off
	global_load_dwordx4 v[92:95], v[66:67], off
	global_load_dwordx4 v[114:117], v[100:101], off
	global_load_dwordx4 v[120:123], v[100:101], off offset:16
	global_load_dwordx4 v[124:127], v[100:101], off offset:2048
	global_load_dwordx4 v[128:131], v[100:101], off offset:2064
	v_lshl_add_u64 v[64:65], v[64:65], 0, v[96:97]
	global_load_dwordx4 v[76:79], v[64:65], off
	global_load_dwordx4 v[72:75], v[64:65], off offset:16
	global_load_dwordx4 v[68:71], v[64:65], off offset:2048
	v_mul_f32_e32 v107, v1, v1
	global_load_dwordx4 v[64:67], v[64:65], off offset:2064
	v_mul_f32_e32 v109, v5, v5
	v_mul_f32_e32 v119, v33, v33
	v_mul_f32_e32 v132, v37, v37
	v_mul_f32_e32 v111, v9, v9
	v_mul_f32_e32 v133, v41, v41
	v_fmac_f32_e32 v107, v0, v0
	v_fmac_f32_e32 v109, v4, v4
	v_fmac_f32_e32 v119, v32, v32
	v_fmac_f32_e32 v132, v36, v36
	v_mul_f32_e32 v113, v13, v13
	v_mul_f32_e32 v134, v45, v45
	v_fmac_f32_e32 v111, v8, v8
	v_fmac_f32_e32 v133, v40, v40
	v_fmac_f32_e32 v107, v2, v2
	v_fmac_f32_e32 v109, v6, v6
	v_fmac_f32_e32 v119, v34, v34
	v_fmac_f32_e32 v132, v38, v38
	v_fmac_f32_e32 v113, v12, v12
	v_fmac_f32_e32 v111, v10, v10
	v_fmac_f32_e32 v133, v42, v42
	v_fmac_f32_e32 v107, v3, v3
	v_fmac_f32_e32 v109, v7, v7
	v_fmac_f32_e32 v119, v35, v35
	v_fmac_f32_e32 v132, v39, v39
	v_fmac_f32_e32 v134, v44, v44
	v_fmac_f32_e32 v113, v14, v14
	v_fmac_f32_e32 v111, v11, v11
	v_fmac_f32_e32 v133, v43, v43
	v_add_f32_e32 v107, v109, v107
	v_add_f32_e32 v109, v119, v132
	v_fmac_f32_e32 v134, v46, v46
	v_fmac_f32_e32 v113, v15, v15
	v_add_f32_e32 v107, v111, v107
	v_add_f32_e32 v109, v109, v133
	v_fmac_f32_e32 v134, v47, v47
	v_add_f32_e32 v107, v113, v107
	s_waitcnt vmcnt(0) lgkmcnt(0)
	v_pk_add_f32 v[80:81], v[80:81], 1.0 op_sel_hi:[1,0]
	v_add_f32_dpp v107, v107, v107 quad_perm:[1,0,3,2] row_mask:0xf bank_mask:0xf bound_ctrl:1
	v_pk_add_f32 v[82:83], v[82:83], 1.0 op_sel_hi:[1,0]
	v_pk_add_f32 v[94:95], v[94:95], 1.0 op_sel_hi:[1,0]
	v_add_f32_dpp v107, v107, v107 quad_perm:[2,3,0,1] row_mask:0xf bank_mask:0xf bound_ctrl:1
	v_pk_add_f32 v[84:85], v[84:85], 1.0 op_sel_hi:[1,0]
	v_pk_add_f32 v[136:137], v[90:91], 1.0 op_sel_hi:[1,0]
	v_pk_mul_f32 v[90:91], v[114:115], v[80:81]
	v_pk_mul_f32 v[80:81], v[130:131], v[94:95]
	v_add_f32_e32 v94, v109, v134
	v_add_f32_dpp v107, v107, v107 row_half_mirror row_mask:0xf bank_mask:0xf bound_ctrl:1
	v_mov_b64_e32 v[114:115], s[36:37]
	v_add_f32_dpp v94, v94, v94 quad_perm:[1,0,3,2] row_mask:0xf bank_mask:0xf bound_ctrl:1
	v_add_f32_dpp v107, v107, v107 row_mirror row_mask:0xf bank_mask:0xf bound_ctrl:1
	v_mov_b32_e32 v111, v107
	v_add_f32_dpp v94, v94, v94 quad_perm:[2,3,0,1] row_mask:0xf bank_mask:0xf bound_ctrl:1
	s_nop 0
	v_permlane16_swap_b32_e32 v107, v111
	v_add_f32_dpp v94, v94, v94 row_half_mirror row_mask:0xf bank_mask:0xf bound_ctrl:1
	v_add_f32_e32 v133, v107, v111
	v_mov_b32_e32 v135, v133
	v_add_f32_dpp v94, v94, v94 row_mirror row_mask:0xf bank_mask:0xf bound_ctrl:1
	v_mov_b32_e32 v95, v94
	s_nop 1
	v_permlane16_swap_b32_e32 v94, v95
	v_add_f32_e32 v132, v94, v95
	v_mov_b32_e32 v134, v132
	v_permlane32_swap_b32_e32 v133, v135
	s_nop 0
	v_permlane32_swap_b32_e32 v132, v134
	v_pk_add_f32 v[94:95], v[132:133], v[134:135]
	v_pk_add_f32 v[138:139], v[88:89], 1.0 op_sel_hi:[1,0]
	v_pk_mul_f32 v[88:89], v[116:117], v[82:83]
	v_pk_fma_f32 v[116:117], v[94:95], s[34:35], v[114:115] op_sel_hi:[1,0,0]
	v_pk_add_f32 v[86:87], v[86:87], 1.0 op_sel_hi:[1,0]
	v_mul_f32_e32 v94, 0x4b800000, v117
	v_cmp_gt_f32_e32 vcc, s42, v117
	v_pk_add_f32 v[140:141], v[92:93], 1.0 op_sel_hi:[1,0]
	v_pk_mul_f32 v[92:93], v[120:121], v[84:85]
	v_cndmask_b32_e32 v94, v117, v94, vcc
	v_rsq_f32_e32 v107, v94
	v_pk_mul_f32 v[86:87], v[122:123], v[86:87]
	v_add_u32_e32 v109, 0xffffe400, v99
	v_pk_mul_f32 v[82:83], v[126:127], v[136:137]
	v_mul_f32_e32 v113, 0x45800000, v107
	v_cndmask_b32_e32 v120, v107, v113, vcc
	v_pk_mul_f32 v[0:1], v[0:1], v[120:121] op_sel_hi:[1,0]
	v_pk_mul_f32 v[4:5], v[4:5], v[120:121] op_sel_hi:[1,0]
	v_pk_mul_f32 v[2:3], v[2:3], v[120:121] op_sel_hi:[1,0]
	v_pk_mul_f32 v[6:7], v[6:7], v[120:121] op_sel_hi:[1,0]
	v_pk_fma_f32 v[0:1], v[90:91], v[0:1], v[76:77]
	v_pk_fma_f32 v[4:5], v[92:93], v[4:5], v[72:73]
	v_pk_fma_f32 v[2:3], v[88:89], v[2:3], v[78:79]
	v_pk_fma_f32 v[6:7], v[86:87], v[6:7], v[74:75]
	v_cvt_pk_bf16_f32 v0, v0, v1
	v_cvt_pk_bf16_f32 v1, v2, v3
	v_cvt_pk_bf16_f32 v2, v4, v5
	v_cvt_pk_bf16_f32 v3, v6, v7
	v_pk_mul_f32 v[84:85], v[124:125], v[138:139]
	buffer_store_dwordx4 v[0:3], v109, s[16:19], 0 offen sc1
	v_pk_mul_f32 v[4:5], v[10:11], v[120:121] op_sel_hi:[1,0]
	v_cmp_gt_f32_e32 vcc, s42, v116
	v_pk_mul_f32 v[0:1], v[8:9], v[120:121] op_sel_hi:[1,0]
	v_pk_fma_f32 v[4:5], v[82:83], v[4:5], v[70:71]
	v_pk_fma_f32 v[0:1], v[84:85], v[0:1], v[68:69]
	v_pk_mul_f32 v[94:95], v[128:129], v[140:141]
	v_cvt_pk_bf16_f32 v0, v0, v1
	v_cvt_pk_bf16_f32 v1, v4, v5
	v_mul_f32_e32 v4, 0x4b800000, v116
	v_cndmask_b32_e32 v4, v116, v4, vcc
	v_rsq_f32_e32 v4, v4
	v_pk_mul_f32 v[2:3], v[12:13], v[120:121] op_sel_hi:[1,0]
	v_pk_mul_f32 v[6:7], v[14:15], v[120:121] op_sel_hi:[1,0]
	v_pk_fma_f32 v[2:3], v[94:95], v[2:3], v[64:65]
	v_pk_fma_f32 v[6:7], v[80:81], v[6:7], v[66:67]
	v_add_u32_e32 v111, 0xffffe800, v99
	v_cvt_pk_bf16_f32 v2, v2, v3
	v_cvt_pk_bf16_f32 v3, v6, v7
	buffer_store_dwordx4 v[0:3], v111, s[16:19], 0 offen sc1
	v_add_u32_e32 v12, 0xfffff800, v99
	s_nop 0
	v_mul_f32_e32 v0, 0x45800000, v4
	v_cndmask_b32_e32 v4, v4, v0, vcc
	v_pk_mul_f32 v[0:1], v[32:33], v[4:5] op_sel_hi:[1,0]
	v_pk_mul_f32 v[2:3], v[36:37], v[4:5] op_sel_hi:[1,0]
	v_pk_mul_f32 v[6:7], v[34:35], v[4:5] op_sel_hi:[1,0]
	v_pk_mul_f32 v[8:9], v[38:39], v[4:5] op_sel_hi:[1,0]
	v_pk_fma_f32 v[0:1], v[90:91], v[0:1], v[76:77]
	v_pk_fma_f32 v[2:3], v[92:93], v[2:3], v[72:73]
	v_pk_fma_f32 v[6:7], v[88:89], v[6:7], v[78:79]
	v_pk_fma_f32 v[8:9], v[86:87], v[8:9], v[74:75]
	v_cvt_pk_bf16_f32 v0, v0, v1
	v_cvt_pk_bf16_f32 v1, v6, v7
	v_cvt_pk_bf16_f32 v2, v2, v3
	v_cvt_pk_bf16_f32 v3, v8, v9
	v_add_u32_e32 v5, 0xffffec00, v99
	buffer_store_dwordx4 v[0:3], v5, s[16:19], 0 offen sc1
	v_pk_mul_f32 v[6:7], v[42:43], v[4:5] op_sel_hi:[1,0]
	v_add_u32_e32 v8, 0xfffff000, v99
	v_pk_mul_f32 v[0:1], v[40:41], v[4:5] op_sel_hi:[1,0]
	v_pk_mul_f32 v[2:3], v[44:45], v[4:5] op_sel_hi:[1,0]
	v_pk_mul_f32 v[4:5], v[46:47], v[4:5] op_sel_hi:[1,0]
	v_pk_fma_f32 v[2:3], v[94:95], v[2:3], v[64:65]
	v_pk_fma_f32 v[4:5], v[80:81], v[4:5], v[66:67]
	v_cvt_pk_bf16_f32 v2, v2, v3
	v_cvt_pk_bf16_f32 v3, v4, v5
	v_mul_f32_e32 v4, v17, v17
	v_mul_f32_e32 v5, v21, v21
	v_fmac_f32_e32 v4, v16, v16
	v_fmac_f32_e32 v5, v20, v20
	v_fmac_f32_e32 v4, v18, v18
	v_fmac_f32_e32 v5, v22, v22
	v_fmac_f32_e32 v4, v19, v19
	v_fmac_f32_e32 v5, v23, v23
	v_add_f32_e32 v4, v4, v5
	v_mul_f32_e32 v5, v25, v25
	v_fmac_f32_e32 v5, v24, v24
	v_fmac_f32_e32 v5, v26, v26
	v_fmac_f32_e32 v5, v27, v27
	v_add_f32_e32 v4, v4, v5
	v_mul_f32_e32 v5, v29, v29
	v_fmac_f32_e32 v5, v28, v28
	v_fmac_f32_e32 v5, v30, v30
	v_fmac_f32_e32 v5, v31, v31
	v_add_f32_e32 v4, v4, v5
	v_pk_fma_f32 v[0:1], v[84:85], v[0:1], v[68:69]
	v_pk_fma_f32 v[6:7], v[82:83], v[6:7], v[70:71]
	v_add_f32_dpp v4, v4, v4 quad_perm:[1,0,3,2] row_mask:0xf bank_mask:0xf bound_ctrl:1
	v_cvt_pk_bf16_f32 v0, v0, v1
	v_cvt_pk_bf16_f32 v1, v6, v7
	v_add_f32_dpp v4, v4, v4 quad_perm:[2,3,0,1] row_mask:0xf bank_mask:0xf bound_ctrl:1
	v_mul_f32_e32 v6, v53, v53
	v_fmac_f32_e32 v6, v52, v52
	v_add_f32_dpp v4, v4, v4 row_half_mirror row_mask:0xf bank_mask:0xf bound_ctrl:1
	v_fmac_f32_e32 v6, v54, v54
	v_fmac_f32_e32 v6, v55, v55
	v_add_f32_dpp v4, v4, v4 row_mirror row_mask:0xf bank_mask:0xf bound_ctrl:1
	v_mov_b32_e32 v5, v4
	s_nop 1
	v_permlane16_swap_b32_e32 v4, v5
	v_add_f32_e32 v5, v4, v5
	v_mul_f32_e32 v4, v49, v49
	v_fmac_f32_e32 v4, v48, v48
	v_fmac_f32_e32 v4, v50, v50
	v_fmac_f32_e32 v4, v51, v51
	v_add_f32_e32 v4, v4, v6
	v_mul_f32_e32 v6, v57, v57
	v_fmac_f32_e32 v6, v56, v56
	v_fmac_f32_e32 v6, v58, v58
	v_fmac_f32_e32 v6, v59, v59
	v_add_f32_e32 v4, v4, v6
	v_mul_f32_e32 v6, v61, v61
	v_fmac_f32_e32 v6, v60, v60
	v_fmac_f32_e32 v6, v62, v62
	v_fmac_f32_e32 v6, v63, v63
	v_add_f32_e32 v4, v4, v6
	v_mov_b32_e32 v7, v5
	s_nop 1
	v_permlane32_swap_b32_e32 v5, v7
	v_add_f32_dpp v4, v4, v4 quad_perm:[1,0,3,2] row_mask:0xf bank_mask:0xf bound_ctrl:1
	buffer_store_dwordx4 v[0:3], v8, s[16:19], 0 offen sc1
	s_nop 0
	v_add_f32_dpp v4, v4, v4 quad_perm:[2,3,0,1] row_mask:0xf bank_mask:0xf bound_ctrl:1
	s_nop 1
	v_add_f32_dpp v4, v4, v4 row_half_mirror row_mask:0xf bank_mask:0xf bound_ctrl:1
	s_nop 1
	v_add_f32_dpp v4, v4, v4 row_mirror row_mask:0xf bank_mask:0xf bound_ctrl:1
	v_mov_b32_e32 v6, v4
	s_nop 1
	v_permlane16_swap_b32_e32 v4, v6
	v_add_f32_e32 v4, v4, v6
	v_mov_b32_e32 v6, v4
	s_nop 1
	v_permlane32_swap_b32_e32 v4, v6
	v_pk_add_f32 v[4:5], v[4:5], v[6:7]
	v_add_u32_e32 v7, 0xfffff400, v99
	v_pk_fma_f32 v[4:5], v[4:5], s[34:35], v[114:115] op_sel_hi:[1,0,0]
	s_nop 0
	v_mul_f32_e32 v6, 0x4b800000, v5
	v_cmp_gt_f32_e32 vcc, s42, v5
	s_nop 1
	v_cndmask_b32_e32 v5, v5, v6, vcc
	v_rsq_f32_e32 v5, v5
	s_nop 0
	v_mul_f32_e32 v0, 0x45800000, v5
	v_cndmask_b32_e32 v6, v5, v0, vcc
	v_pk_mul_f32 v[0:1], v[16:17], v[6:7] op_sel_hi:[1,0]
	v_pk_mul_f32 v[2:3], v[20:21], v[6:7] op_sel_hi:[1,0]
	v_pk_mul_f32 v[8:9], v[18:19], v[6:7] op_sel_hi:[1,0]
	v_pk_mul_f32 v[10:11], v[22:23], v[6:7] op_sel_hi:[1,0]
	v_mul_f32_e32 v5, 0x4b800000, v4
	v_cmp_gt_f32_e32 vcc, s42, v4
	v_pk_fma_f32 v[0:1], v[90:91], v[0:1], v[76:77]
	v_pk_fma_f32 v[2:3], v[92:93], v[2:3], v[72:73]
	v_pk_fma_f32 v[8:9], v[88:89], v[8:9], v[78:79]
	v_pk_fma_f32 v[10:11], v[86:87], v[10:11], v[74:75]
	v_cndmask_b32_e32 v4, v4, v5, vcc
	v_cvt_pk_bf16_f32 v0, v0, v1
	v_cvt_pk_bf16_f32 v1, v8, v9
	v_cvt_pk_bf16_f32 v2, v2, v3
	v_cvt_pk_bf16_f32 v3, v10, v11
	v_rsq_f32_e32 v4, v4
	buffer_store_dwordx4 v[0:3], v7, s[16:19], 0 offen sc1
	v_pk_mul_f32 v[8:9], v[26:27], v[6:7] op_sel_hi:[1,0]
	s_nop 0
	v_pk_mul_f32 v[0:1], v[24:25], v[6:7] op_sel_hi:[1,0]
	v_pk_mul_f32 v[2:3], v[28:29], v[6:7] op_sel_hi:[1,0]
	v_pk_mul_f32 v[6:7], v[30:31], v[6:7] op_sel_hi:[1,0]
	v_pk_fma_f32 v[0:1], v[84:85], v[0:1], v[68:69]
	v_pk_fma_f32 v[2:3], v[94:95], v[2:3], v[64:65]
	v_pk_fma_f32 v[8:9], v[82:83], v[8:9], v[70:71]
	v_pk_fma_f32 v[6:7], v[80:81], v[6:7], v[66:67]
	v_cvt_pk_bf16_f32 v0, v0, v1
	v_cvt_pk_bf16_f32 v1, v8, v9
	v_cvt_pk_bf16_f32 v2, v2, v3
	v_cvt_pk_bf16_f32 v3, v6, v7
	buffer_store_dwordx4 v[0:3], v12, s[16:19], 0 offen sc1
	s_nop 1
	v_mul_f32_e32 v0, 0x45800000, v4
	v_cndmask_b32_e32 v4, v4, v0, vcc
	v_pk_mul_f32 v[0:1], v[48:49], v[4:5] op_sel_hi:[1,0]
	v_pk_mul_f32 v[2:3], v[52:53], v[4:5] op_sel_hi:[1,0]
	v_pk_mul_f32 v[6:7], v[50:51], v[4:5] op_sel_hi:[1,0]
	v_pk_mul_f32 v[8:9], v[54:55], v[4:5] op_sel_hi:[1,0]
	v_pk_fma_f32 v[0:1], v[90:91], v[0:1], v[76:77]
	v_pk_fma_f32 v[2:3], v[92:93], v[2:3], v[72:73]
	v_pk_fma_f32 v[6:7], v[88:89], v[6:7], v[78:79]
	v_pk_fma_f32 v[8:9], v[86:87], v[8:9], v[74:75]
	v_cvt_pk_bf16_f32 v0, v0, v1
	v_cvt_pk_bf16_f32 v1, v6, v7
	v_cvt_pk_bf16_f32 v2, v2, v3
	v_cvt_pk_bf16_f32 v3, v8, v9
	v_add_u32_e32 v5, 0xfffffc00, v99
	buffer_store_dwordx4 v[0:3], v5, s[16:19], 0 offen sc1
	v_pk_mul_f32 v[6:7], v[58:59], v[4:5] op_sel_hi:[1,0]
	s_nop 0
	v_pk_mul_f32 v[0:1], v[56:57], v[4:5] op_sel_hi:[1,0]
	v_pk_mul_f32 v[2:3], v[60:61], v[4:5] op_sel_hi:[1,0]
	v_pk_mul_f32 v[4:5], v[62:63], v[4:5] op_sel_hi:[1,0]
	v_pk_fma_f32 v[0:1], v[84:85], v[0:1], v[68:69]
	v_pk_fma_f32 v[2:3], v[94:95], v[2:3], v[64:65]
	v_pk_fma_f32 v[6:7], v[82:83], v[6:7], v[70:71]
	v_pk_fma_f32 v[4:5], v[80:81], v[4:5], v[66:67]
	v_cvt_pk_bf16_f32 v0, v0, v1
	v_cvt_pk_bf16_f32 v1, v6, v7
	v_cvt_pk_bf16_f32 v2, v2, v3
	v_cvt_pk_bf16_f32 v3, v4, v5
	buffer_store_dwordx4 v[0:3], v99, s[16:19], 0 offen sc1
	s_waitcnt vmcnt(0)
	s_and_saveexec_b64 s[8:9], s[4:5]
	s_cbranch_execz .LBB0_157
	v_ashrrev_i32_e32 v0, 2, v106
	v_and_b32_e32 v0, 0xffffffc0, v0
	v_ashrrev_i32_e32 v1, 31, v0
	v_lshl_add_u64 v[0:1], v[0:1], 2, s[24:25]
	flat_atomic_add v[0:1], v118
	s_branch .LBB0_157

.LBB0_465:
	v_add_u32_e32 v24, s25, v45
	v_mul_hi_i32 v0, v24, s27
	v_lshrrev_b32_e32 v1, 31, v0
	v_ashrrev_i32_e32 v0, 4, v0
	v_add_u32_e32 v32, v0, v1
	v_mul_lo_u32 v2, v32, s30
	v_add3_u32 v38, s26, v44, v2
	v_mad_i64_i32 v[0:1], s[4:5], v32, s29, v[28:29]
	v_ashrrev_i32_e32 v39, 31, v38
	v_lshl_add_u64 v[0:1], v[38:39], 1, v[0:1]
	global_load_dwordx4 v[16:19], v[0:1], off offset:2112
	v_cmp_lt_i32_e32 vcc, s28, v24
	v_lshl_add_u64 v[0:1], v[0:1], 0, s[16:17]
	v_mov_b32_e32 v14, 0
	v_cndmask_b32_e32 v2, v27, v35, vcc
	v_and_b32_e32 v3, v2, v32
	v_cmp_ne_u32_e32 vcc, 0, v3
	v_mov_b32_e32 v22, 0
	v_mov_b32_e32 v23, 0
	v_mov_b32_e32 v20, 0
	v_mov_b32_e32 v21, 0
	s_and_saveexec_b64 s[4:5], vcc
	s_cbranch_execz .LBB0_467
	v_add_co_u32_e32 v4, vcc, 0xffffe9a0, v0
	s_nop 1
	v_addc_co_u32_e32 v5, vcc, -1, v1, vcc
	global_load_dwordx4 v[20:23], v[4:5], off
.LBB0_467:
	s_or_b64 exec, exec, s[4:5]
	v_cmp_ne_u32_e32 vcc, v3, v2
	v_mov_b32_e32 v15, 0
	v_mov_b32_e32 v12, 0
	v_mov_b32_e32 v13, 0
	s_and_saveexec_b64 s[4:5], vcc
	s_cbranch_execz .LBB0_469
	v_add_co_u32_e32 v0, vcc, 0x1000, v0
	s_nop 1
	v_addc_co_u32_e32 v1, vcc, 0, v1, vcc
	global_load_dwordx4 v[12:15], v[0:1], off offset:1632
.LBB0_469:
	s_or_b64 exec, exec, s[4:5]
	v_add_u32_e32 v34, s21, v45
	v_mul_hi_i32 v0, v34, s27
	v_lshrrev_b32_e32 v1, 31, v0
	v_ashrrev_i32_e32 v0, 4, v0
	v_add_u32_e32 v30, v0, v1
	v_mul_lo_u32 v2, v30, s30
	v_add3_u32 v36, s23, v44, v2
	v_mad_i64_i32 v[0:1], s[4:5], v30, s29, v[28:29]
	v_ashrrev_i32_e32 v37, 31, v36
	v_lshl_add_u64 v[2:3], v[36:37], 1, v[0:1]
	global_load_dwordx4 v[4:7], v[2:3], off offset:2112
	v_cmp_lt_i32_e32 vcc, s28, v34
	v_lshl_add_u64 v[40:41], v[2:3], 0, s[16:17]
	v_mov_b32_e32 v2, 0
	v_cndmask_b32_e32 v0, v27, v35, vcc
	v_and_b32_e32 v1, v0, v30
	v_cmp_ne_u32_e32 vcc, 0, v1
	v_mov_b32_e32 v10, 0
	v_mov_b32_e32 v11, 0
	v_mov_b32_e32 v8, 0
	v_mov_b32_e32 v9, 0
	s_and_saveexec_b64 s[4:5], vcc
	s_cbranch_execz .LBB0_471
	v_add_co_u32_e32 v8, vcc, 0xffffe9a0, v40
	s_nop 1
	v_addc_co_u32_e32 v9, vcc, -1, v41, vcc
	global_load_dwordx4 v[8:11], v[8:9], off
.LBB0_471:
	s_or_b64 exec, exec, s[4:5]
	v_cmp_ne_u32_e32 vcc, v1, v0
	v_mov_b32_e32 v3, 0
	v_mov_b32_e32 v0, 0
	v_mov_b32_e32 v1, 0
	s_and_saveexec_b64 s[4:5], vcc
	s_cbranch_execz .LBB0_473
	v_add_co_u32_e32 v0, vcc, 0x1000, v40
	s_nop 1
	v_addc_co_u32_e32 v1, vcc, 0, v41, vcc
	global_load_dwordx4 v[0:3], v[0:1], off offset:1632

.LBB0_480:
	s_nop 0
	v_mul_hi_i32 v0, v14, s22
	v_lshrrev_b32_e32 v1, 31, v0
	v_ashrrev_i32_e32 v0, 4, v0
	v_add_u32_e32 v22, v0, v1
	v_mad_u64_u32 v[24:25], s[4:5], v22, s25, v[16:17]
	v_mad_i64_i32 v[0:1], s[4:5], v22, s24, v[18:19]
	v_ashrrev_i32_e32 v25, 31, v24
	v_lshl_add_u64 v[2:3], v[24:25], 1, v[0:1]
	global_load_dwordx4 v[4:7], v[2:3], off offset:2112
	v_cmp_lt_i32_e32 vcc, s23, v14
	v_lshl_add_u64 v[26:27], v[2:3], 0, s[16:17]
	v_mov_b32_e32 v10, 0
	v_cndmask_b32_e32 v0, v15, v17, vcc
	v_and_b32_e32 v1, v0, v22
	v_cmp_ne_u32_e32 vcc, 0, v1
	v_mov_b32_e32 v11, 0
	v_mov_b32_e32 v8, 0
	v_mov_b32_e32 v9, 0
	s_and_saveexec_b64 s[4:5], vcc
	s_cbranch_execz .LBB0_482
	v_add_co_u32_e32 v2, vcc, 0xffffe9a0, v26
	s_nop 1
	v_addc_co_u32_e32 v3, vcc, -1, v27, vcc
	global_load_dwordx4 v[8:11], v[2:3], off
.LBB0_482:
	s_or_b64 exec, exec, s[4:5]
	v_cmp_ne_u32_e32 vcc, v1, v0
	v_mov_b32_e32 v2, 0
	v_mov_b32_e32 v3, 0
	v_mov_b32_e32 v0, 0
	v_mov_b32_e32 v1, 0
	s_and_saveexec_b64 s[4:5], vcc
	s_cbranch_execz .LBB0_484
	v_add_co_u32_e32 v0, vcc, 0x1000, v26
	s_nop 1
	v_addc_co_u32_e32 v1, vcc, 0, v27, vcc
	global_load_dwordx4 v[0:3], v[0:1], off offset:1632

.LBB0_489:
	v_add_u32_e32 v20, s13, v50
	v_ashrrev_i32_e32 v36, 4, v20
	v_mad_i64_i32 v[0:1], s[4:5], v36, s17, v[26:27]
	global_load_dwordx4 v[12:15], v[0:1], off offset:768
	v_add_u32_e32 v33, s13, v39
	v_add_u32_e32 v31, s13, v40
	v_add_u32_e32 v43, s13, v38
	v_ashrrev_i32_e32 v34, 4, v33
	global_load_dwordx4 v[44:47], v[24:25], off offset:16
	global_load_dwordx4 v[16:19], v[24:25], off
	v_ashrrev_i32_e32 v32, 4, v31
	v_ashrrev_i32_e32 v30, 4, v43
	v_mad_i64_i32 v[48:49], s[4:5], v34, s17, v[26:27]
	v_mad_i64_i32 v[52:53], s[4:5], v32, s17, v[26:27]
	v_mad_i64_i32 v[54:55], s[4:5], v30, s17, v[26:27]
	global_load_dwordx4 v[8:11], v[48:49], off offset:768
	global_load_dwordx4 v[4:7], v[52:53], off offset:768
	global_load_dwordx4 v[0:3], v[54:55], off offset:768
	v_ashrrev_i32_e32 v37, 31, v36
	v_cmp_gt_i32_e64 s[4:5], s18, v36
	s_waitcnt vmcnt(0) lgkmcnt(0)
	v_lshlrev_b32_e32 v48, 16, v12
	v_and_b32_e32 v49, 0xffff0000, v12
	v_lshlrev_b32_e32 v12, 16, v13
	v_and_b32_e32 v13, 0xffff0000, v13
	v_pk_mul_f32 v[60:61], v[48:49], v[48:49]
	v_pk_mul_f32 v[58:59], v[12:13], v[12:13]
	v_add_f32_e32 v29, v60, v61
	v_lshlrev_b32_e32 v52, 16, v14
	v_and_b32_e32 v53, 0xffff0000, v14
	v_add_f32_e32 v29, v29, v58
	v_pk_mul_f32 v[56:57], v[52:53], v[52:53]
	v_add_f32_e32 v29, v59, v29
	v_lshlrev_b32_e32 v14, 16, v15
	v_and_b32_e32 v15, 0xffff0000, v15
	v_add_f32_e32 v29, v56, v29
	v_pk_mul_f32 v[54:55], v[14:15], v[14:15]
	v_add_f32_e32 v29, v57, v29
	v_add_f32_e32 v29, v54, v29
	v_add_f32_e32 v29, v55, v29
	v_lshlrev_b64 v[54:55], 8, v[36:37]
	s_nop 0
	v_add_f32_dpp v29, v29, v29 quad_perm:[1,0,3,2] row_mask:0xf bank_mask:0xf bound_ctrl:1
	s_nop 1
	v_add_f32_dpp v29, v29, v29 quad_perm:[2,3,0,1] row_mask:0xf bank_mask:0xf bound_ctrl:1
	s_nop 1
	v_add_f32_dpp v29, v29, v29 row_half_mirror row_mask:0xf bank_mask:0xf bound_ctrl:1
	s_nop 1
	v_add_f32_dpp v29, v29, v29 row_mirror row_mask:0xf bank_mask:0xf bound_ctrl:1
	v_fmamk_f32 v29, v29, 0x3c000000, v41
	v_mul_f32_e32 v35, 0x4b800000, v29
	v_cmp_gt_f32_e32 vcc, s19, v29
	s_nop 1
	v_cndmask_b32_e32 v29, v29, v35, vcc
	v_rsq_f32_e32 v29, v29
	s_nop 0
	v_mul_f32_e32 v35, 0x45800000, v29
	v_cndmask_b32_e32 v56, v29, v35, vcc
	v_pk_mul_f32 v[48:49], v[56:57], v[48:49] op_sel_hi:[0,1]
	v_pk_mul_f32 v[12:13], v[56:57], v[12:13] op_sel_hi:[0,1]
	v_pk_mul_f32 v[52:53], v[56:57], v[52:53] op_sel_hi:[0,1]
	v_pk_mul_f32 v[14:15], v[56:57], v[14:15] op_sel_hi:[0,1]
	v_pk_mul_f32 v[16:17], v[16:17], v[48:49]
	v_pk_mul_f32 v[18:19], v[18:19], v[12:13]
	v_pk_mul_f32 v[12:13], v[44:45], v[52:53]
	v_pk_mul_f32 v[14:15], v[46:47], v[14:15]
	v_cvt_pk_bf16_f32 v44, v16, v17
	v_cvt_pk_bf16_f32 v45, v18, v19
	v_cvt_pk_bf16_f32 v46, v12, v13
	v_cvt_pk_bf16_f32 v47, v14, v15
	v_lshl_add_u64 v[48:49], v[22:23], 0, v[54:55]
	flat_store_dwordx4 v[48:49], v[44:47]
	s_and_saveexec_b64 s[10:11], s[4:5]
	s_cbranch_execz .LBB0_491
	v_ashrrev_i32_e32 v20, 11, v20
	v_and_b32_e32 v44, -2, v20
	v_ashrrev_i32_e32 v45, 31, v44
	v_lshlrev_b64 v[44:45], 17, v[44:45]
	v_lshlrev_b32_e32 v20, 9, v36
	v_lshl_add_u64 v[44:45], s[8:9], 0, v[44:45]
	v_and_b32_e32 v20, 0x1fe00, v20
	v_lshl_add_u64 v[36:37], v[44:45], 0, v[20:21]
	v_mov_b32_e32 v29, v21
	v_lshl_add_u64 v[36:37], v[36:37], 0, v[28:29]
	flat_store_dwordx4 v[36:37], v[16:19]
	flat_store_dwordx4 v[36:37], v[12:15] offset:16

.LBB0_501:
	v_ashrrev_i32_e32 v24, 4, v26
	v_mad_i64_i32 v[0:1], s[10:11], v24, s16, v[18:19]
	global_load_dwordx4 v[4:7], v[0:1], off offset:768
	global_load_dwordx4 v[8:11], v[16:17], off
	global_load_dwordx4 v[30:33], v[16:17], off offset:16
	v_lshl_add_u32 v28, s4, 9, v50
	v_ashrrev_i32_e32 v22, 4, v28
	v_mad_i64_i32 v[0:1], s[4:5], v22, s16, v[18:19]
	global_load_dwordx4 v[0:3], v[0:1], off offset:768
	v_ashrrev_i32_e32 v25, 31, v24
	v_cmp_gt_i32_e64 s[4:5], s17, v24
	s_waitcnt vmcnt(0) lgkmcnt(0)
	v_lshlrev_b32_e32 v34, 16, v4
	v_and_b32_e32 v35, 0xffff0000, v4
	v_lshlrev_b32_e32 v4, 16, v5
	v_and_b32_e32 v5, 0xffff0000, v5
	v_pk_mul_f32 v[46:47], v[34:35], v[34:35]
	v_pk_mul_f32 v[44:45], v[4:5], v[4:5]
	v_add_f32_e32 v12, v46, v47
	v_lshlrev_b32_e32 v36, 16, v6
	v_and_b32_e32 v37, 0xffff0000, v6
	v_add_f32_e32 v12, v12, v44
	v_pk_mul_f32 v[40:41], v[36:37], v[36:37]
	v_add_f32_e32 v12, v45, v12
	v_lshlrev_b32_e32 v6, 16, v7
	v_and_b32_e32 v7, 0xffff0000, v7
	v_add_f32_e32 v12, v40, v12
	v_pk_mul_f32 v[38:39], v[6:7], v[6:7]
	v_add_f32_e32 v12, v41, v12
	v_add_f32_e32 v12, v38, v12
	v_add_f32_e32 v12, v39, v12
	v_lshlrev_b64 v[38:39], 8, v[24:25]
	s_nop 0
	v_add_f32_dpp v12, v12, v12 quad_perm:[1,0,3,2] row_mask:0xf bank_mask:0xf bound_ctrl:1
	s_nop 1
	v_add_f32_dpp v12, v12, v12 quad_perm:[2,3,0,1] row_mask:0xf bank_mask:0xf bound_ctrl:1
	s_nop 1
	v_add_f32_dpp v12, v12, v12 row_half_mirror row_mask:0xf bank_mask:0xf bound_ctrl:1
	s_nop 1
	v_add_f32_dpp v12, v12, v12 row_mirror row_mask:0xf bank_mask:0xf bound_ctrl:1
	v_fmamk_f32 v12, v12, 0x3c000000, v27
	v_mul_f32_e32 v21, 0x4b800000, v12
	v_cmp_gt_f32_e32 vcc, s18, v12
	s_nop 1
	v_cndmask_b32_e32 v12, v12, v21, vcc
	v_rsq_f32_e32 v12, v12
	s_nop 0
	v_mul_f32_e32 v21, 0x45800000, v12
	v_cndmask_b32_e32 v12, v12, v21, vcc
	v_pk_mul_f32 v[34:35], v[12:13], v[34:35] op_sel_hi:[0,1]
	v_pk_mul_f32 v[4:5], v[12:13], v[4:5] op_sel_hi:[0,1]
	v_pk_mul_f32 v[36:37], v[12:13], v[36:37] op_sel_hi:[0,1]
	v_pk_mul_f32 v[6:7], v[12:13], v[6:7] op_sel_hi:[0,1]
	v_pk_mul_f32 v[8:9], v[8:9], v[34:35]
	v_pk_mul_f32 v[10:11], v[10:11], v[4:5]
	v_pk_mul_f32 v[4:5], v[30:31], v[36:37]
	v_pk_mul_f32 v[6:7], v[32:33], v[6:7]
	v_cvt_pk_bf16_f32 v30, v8, v9
	v_cvt_pk_bf16_f32 v31, v10, v11
	v_cvt_pk_bf16_f32 v32, v4, v5
	v_cvt_pk_bf16_f32 v33, v6, v7
	v_lshl_add_u64 v[34:35], v[14:15], 0, v[38:39]
	flat_store_dwordx4 v[34:35], v[30:33]
	s_and_saveexec_b64 s[10:11], s[4:5]
	s_cbranch_execz .LBB0_503
	v_ashrrev_i32_e32 v12, 11, v26
	v_and_b32_e32 v30, -2, v12
	v_ashrrev_i32_e32 v31, 31, v30
	v_lshlrev_b64 v[30:31], 17, v[30:31]
	v_lshlrev_b32_e32 v12, 9, v24
	v_lshl_add_u64 v[30:31], s[8:9], 0, v[30:31]
	v_and_b32_e32 v12, 0x1fe00, v12
	v_lshl_add_u64 v[24:25], v[30:31], 0, v[12:13]
	v_mov_b32_e32 v21, v13
	v_lshl_add_u64 v[24:25], v[24:25], 0, v[20:21]
	flat_store_dwordx4 v[24:25], v[8:11]
	flat_store_dwordx4 v[24:25], v[4:7] offset:16

.LBB0_508:
	v_ashrrev_i32_e32 v18, 4, v20
	v_mad_i64_i32 v[26:27], s[4:5], v18, s11, v[14:15]
	global_load_dwordx4 v[0:3], v[26:27], off offset:768
	global_load_dwordx4 v[4:7], v[12:13], off
	global_load_dwordx4 v[22:25], v[12:13], off offset:16
	v_ashrrev_i32_e32 v19, 31, v18
	v_cmp_gt_i32_e64 s[4:5], s12, v18
	s_waitcnt vmcnt(0) lgkmcnt(0)
	v_lshlrev_b32_e32 v26, 16, v0
	v_and_b32_e32 v27, 0xffff0000, v0
	v_lshlrev_b32_e32 v0, 16, v1
	v_and_b32_e32 v1, 0xffff0000, v1
	v_pk_mul_f32 v[36:37], v[26:27], v[26:27]
	v_pk_mul_f32 v[34:35], v[0:1], v[0:1]
	v_add_f32_e32 v8, v36, v37
	v_lshlrev_b32_e32 v28, 16, v2
	v_and_b32_e32 v29, 0xffff0000, v2
	v_add_f32_e32 v8, v8, v34
	v_pk_mul_f32 v[32:33], v[28:29], v[28:29]
	v_add_f32_e32 v8, v35, v8
	v_lshlrev_b32_e32 v2, 16, v3
	v_and_b32_e32 v3, 0xffff0000, v3
	v_add_f32_e32 v8, v32, v8
	v_pk_mul_f32 v[30:31], v[2:3], v[2:3]
	v_add_f32_e32 v8, v33, v8
	v_add_f32_e32 v8, v30, v8
	v_add_f32_e32 v8, v31, v8
	v_lshlrev_b64 v[30:31], 8, v[18:19]
	s_nop 0
	v_add_f32_dpp v8, v8, v8 quad_perm:[1,0,3,2] row_mask:0xf bank_mask:0xf bound_ctrl:1
	s_nop 1
	v_add_f32_dpp v8, v8, v8 quad_perm:[2,3,0,1] row_mask:0xf bank_mask:0xf bound_ctrl:1
	s_nop 1
	v_add_f32_dpp v8, v8, v8 row_half_mirror row_mask:0xf bank_mask:0xf bound_ctrl:1
	s_nop 1
	v_add_f32_dpp v8, v8, v8 row_mirror row_mask:0xf bank_mask:0xf bound_ctrl:1
	v_fmamk_f32 v8, v8, 0x3c000000, v21
	v_mul_f32_e32 v17, 0x4b800000, v8
	v_cmp_gt_f32_e32 vcc, s13, v8
	s_nop 1
	v_cndmask_b32_e32 v8, v8, v17, vcc
	v_rsq_f32_e32 v8, v8
	s_nop 0
	v_mul_f32_e32 v17, 0x45800000, v8
	v_cndmask_b32_e32 v8, v8, v17, vcc
	v_pk_mul_f32 v[26:27], v[8:9], v[26:27] op_sel_hi:[0,1]
	v_pk_mul_f32 v[0:1], v[8:9], v[0:1] op_sel_hi:[0,1]
	v_pk_mul_f32 v[28:29], v[8:9], v[28:29] op_sel_hi:[0,1]
	v_pk_mul_f32 v[2:3], v[8:9], v[2:3] op_sel_hi:[0,1]
	v_pk_mul_f32 v[4:5], v[4:5], v[26:27]
	v_pk_mul_f32 v[6:7], v[6:7], v[0:1]
	v_pk_mul_f32 v[0:1], v[22:23], v[28:29]
	v_pk_mul_f32 v[2:3], v[24:25], v[2:3]
	v_cvt_pk_bf16_f32 v22, v4, v5
	v_cvt_pk_bf16_f32 v23, v6, v7
	v_cvt_pk_bf16_f32 v24, v0, v1
	v_cvt_pk_bf16_f32 v25, v2, v3
	v_lshl_add_u64 v[26:27], v[10:11], 0, v[30:31]
	flat_store_dwordx4 v[26:27], v[22:25]
	s_and_saveexec_b64 s[8:9], s[4:5]
	s_cbranch_execz .LBB0_507
	v_ashrrev_i32_e32 v8, 11, v20
	v_and_b32_e32 v22, -2, v8
	v_ashrrev_i32_e32 v23, 31, v22
	v_lshlrev_b64 v[22:23], 17, v[22:23]
	v_lshlrev_b32_e32 v8, 9, v18
	v_lshl_add_u64 v[22:23], s[6:7], 0, v[22:23]
	v_and_b32_e32 v8, 0x1fe00, v8
	v_lshl_add_u64 v[18:19], v[22:23], 0, v[8:9]
	v_mov_b32_e32 v17, v9
	v_lshl_add_u64 v[18:19], v[18:19], 0, v[16:17]
	flat_store_dwordx4 v[18:19], v[4:7]
	flat_store_dwordx4 v[18:19], v[0:3] offset:16
	s_branch .LBB0_507

.LBB0_532:
	s_andn2_saveexec_b64 s[4:5], s[4:5]
	v_lshl_add_u32 v0, v1, 3, v41
	s_or_b64 exec, exec, s[4:5]
	v_mad_i64_i32 v[4:5], s[4:5], v26, s70, v[16:17]
	v_ashrrev_i32_e32 v1, 31, v0
	v_lshl_add_u64 v[0:1], v[0:1], 1, v[4:5]
	global_load_dwordx4 v[12:15], v[0:1], off
	v_add_u32_e32 v48, s54, v44
	v_mul_hi_i32 v0, v48, s58
	v_add_u32_e32 v0, v0, v48
	v_lshrrev_b32_e32 v1, 31, v0
	v_ashrrev_i32_e32 v0, 7, v0
	v_add_u32_e32 v24, v0, v1
	s_add_i32 s4, s3, s76
	v_mul_lo_u32 v0, v24, s59
	s_lshl_b32 s4, s4, 9
	v_add_u32_e32 v23, v48, v0
	v_add3_u32 v1, s4, v50, v0
	v_cmp_lt_i32_e64 s[6:7], 3, v23
	s_and_saveexec_b64 s[4:5], s[6:7]
	s_xor_b64 s[4:5], exec, s[4:5]
	s_cbranch_execz .LBB0_552
	v_cmp_lt_u32_e32 vcc, 51, v23
	s_waitcnt lgkmcnt(0)
	s_and_saveexec_b64 s[10:11], vcc
	s_xor_b64 s[10:11], exec, s[10:11]
	s_cbranch_execz .LBB0_549
	v_cmp_lt_u32_e32 vcc, s60, v23
	s_and_saveexec_b64 s[12:13], vcc
	s_xor_b64 s[12:13], exec, s[12:13]
	s_cbranch_execz .LBB0_546
	v_cmp_lt_u32_e32 vcc, s61, v23
	s_and_saveexec_b64 s[42:43], vcc
	s_xor_b64 s[42:43], exec, s[42:43]
	s_cbranch_execz .LBB0_543
	v_cmp_lt_u32_e32 vcc, s62, v23
	s_and_saveexec_b64 s[44:45], vcc
	s_xor_b64 s[44:45], exec, s[44:45]
	v_lshl_add_u32 v0, v1, 3, v38
	s_andn2_saveexec_b64 s[44:45], s[44:45]
	v_mul_lo_u32 v0, v24, s63
	v_add_u32_e32 v1, s55, v42
	v_add3_u32 v0, v1, v0, s64
	s_or_b64 exec, exec, s[44:45]

.LBB0_552:
	s_andn2_saveexec_b64 s[4:5], s[4:5]
	v_lshl_add_u32 v0, v1, 3, v41
	s_or_b64 exec, exec, s[4:5]
	v_mad_i64_i32 v[4:5], s[4:5], v24, s70, v[16:17]
	v_ashrrev_i32_e32 v1, 31, v0
	v_lshl_add_u64 v[0:1], v[0:1], 1, v[4:5]
	global_load_dwordx4 v[8:11], v[0:1], off
	v_add_u32_e32 v47, s56, v44
	v_mul_hi_i32 v0, v47, s58
	v_add_u32_e32 v0, v0, v47
	v_lshrrev_b32_e32 v1, 31, v0
	v_ashrrev_i32_e32 v0, 7, v0
	v_add_u32_e32 v22, v0, v1
	v_mul_lo_u32 v0, v22, s59
	v_add_u32_e32 v21, v47, v0
	v_add3_u32 v1, v2, s38, v0
	v_cmp_lt_i32_e64 s[4:5], 3, v21
	s_waitcnt lgkmcnt(0)
	s_and_saveexec_b64 s[10:11], s[4:5]
	s_xor_b64 s[10:11], exec, s[10:11]
	s_cbranch_execz .LBB0_572
	v_cmp_lt_u32_e32 vcc, 51, v21
	s_and_saveexec_b64 s[12:13], vcc
	s_xor_b64 s[12:13], exec, s[12:13]
	s_cbranch_execz .LBB0_569
	v_cmp_lt_u32_e32 vcc, s60, v21
	s_and_saveexec_b64 s[42:43], vcc
	s_xor_b64 s[42:43], exec, s[42:43]
	s_cbranch_execz .LBB0_566
	v_cmp_lt_u32_e32 vcc, s61, v21
	s_and_saveexec_b64 s[44:45], vcc
	s_xor_b64 s[44:45], exec, s[44:45]
	s_cbranch_execz .LBB0_563
	v_cmp_lt_u32_e32 vcc, s62, v21
	s_and_saveexec_b64 s[46:47], vcc
	s_xor_b64 s[46:47], exec, s[46:47]
	v_lshl_add_u32 v0, v1, 3, v38
	s_andn2_saveexec_b64 s[46:47], s[46:47]
	v_mul_lo_u32 v0, v22, s63
	v_add_u32_e32 v1, s57, v42
	v_add3_u32 v0, v1, v0, s64
	s_or_b64 exec, exec, s[46:47]
	s_load_dwordx2 s[86:87], s[92:93], 0x140

.LBB0_572:
	s_andn2_saveexec_b64 s[10:11], s[10:11]
	v_lshl_add_u32 v0, v1, 3, v41
	s_or_b64 exec, exec, s[10:11]
	v_mad_i64_i32 v[2:3], s[10:11], v22, s70, v[16:17]
	v_ashrrev_i32_e32 v1, 31, v0
	v_lshl_add_u64 v[0:1], v[0:1], 1, v[2:3]
	global_load_dwordx4 v[4:7], v[0:1], off
	v_add_u32_e32 v46, s49, v44
	v_mul_hi_i32 v0, v46, s58
	v_add_u32_e32 v0, v0, v46
	v_lshrrev_b32_e32 v1, 31, v0
	v_ashrrev_i32_e32 v0, 7, v0
	v_add_u32_e32 v20, v0, v1
	v_mul_lo_u32 v0, v20, s59
	s_lshl_b32 s10, s84, 9
	v_add_u32_e32 v45, v46, v0
	v_add3_u32 v1, s10, v50, v0
	v_cmp_lt_i32_e32 vcc, 3, v45
	s_and_saveexec_b64 s[10:11], vcc
	s_xor_b64 s[12:13], exec, s[10:11]
	s_cbranch_execz .LBB0_592
	v_cmp_lt_u32_e64 s[10:11], 51, v45
	s_and_saveexec_b64 s[42:43], s[10:11]
	s_xor_b64 s[42:43], exec, s[42:43]
	s_cbranch_execz .LBB0_589
	v_cmp_lt_u32_e64 s[10:11], s60, v45
	s_and_saveexec_b64 s[44:45], s[10:11]
	s_xor_b64 s[44:45], exec, s[44:45]
	s_cbranch_execz .LBB0_586
	v_cmp_lt_u32_e64 s[10:11], s61, v45
	s_and_saveexec_b64 s[46:47], s[10:11]
	s_xor_b64 s[46:47], exec, s[46:47]
	s_cbranch_execz .LBB0_583
	v_cmp_lt_u32_e64 s[10:11], s62, v45
	s_and_saveexec_b64 s[84:85], s[10:11]
	s_xor_b64 s[10:11], exec, s[84:85]
	v_lshl_add_u32 v0, v1, 3, v38
	s_andn2_saveexec_b64 s[10:11], s[10:11]
	v_mul_lo_u32 v0, v20, s63
	v_add_u32_e32 v1, s52, v42
	v_add3_u32 v0, v1, v0, s64
	s_or_b64 exec, exec, s[10:11]
	s_waitcnt lgkmcnt(0)
	s_load_dwordx2 s[86:87], s[92:93], 0x140

.LBB0_592:
	s_andn2_saveexec_b64 s[10:11], s[12:13]
	v_lshl_add_u32 v0, v1, 3, v41
	s_or_b64 exec, exec, s[10:11]
	v_mad_i64_i32 v[2:3], s[10:11], v20, s70, v[16:17]
	v_ashrrev_i32_e32 v1, 31, v0
	v_lshl_add_u64 v[0:1], v[0:1], 1, v[2:3]
	global_load_dwordx4 v[0:3], v[0:1], off
	v_add_u32_e32 v28, 0xfffff000, v26
	v_lshrrev_b32_e32 v28, 11, v28
	v_ashrrev_i32_e32 v29, 8, v26
	v_cmp_lt_i32_e64 s[12:13], s72, v18
	v_cmp_gt_i32_e64 s[10:11], s71, v18
	v_ashrrev_i32_e32 v27, 31, v26
	v_cndmask_b32_e64 v28, v29, v28, s[12:13]
	v_lshlrev_b32_e32 v28, 1, v28
	v_cndmask_b32_e64 v18, v36, v37, s[12:13]
	v_ashrrev_i32_e32 v29, 31, v28
	v_and_b32_e32 v18, v18, v26
	v_lshlrev_b64 v[28:29], 8, v[28:29]
	v_lshl_add_u64 v[34:35], v[28:29], 0, v[18:19]
	s_and_saveexec_b64 s[12:13], s[8:9]
	s_xor_b64 s[12:13], exec, s[12:13]
	s_cbranch_execnz .LBB0_598
	s_andn2_saveexec_b64 s[8:9], s[12:13]
	s_cbranch_execnz .LBB0_615

.LBB0_619:
	v_cmp_ne_u64_e64 s[8:9], 0, v[32:33]
	s_and_saveexec_b64 s[12:13], s[8:9]
	s_cbranch_execz .LBB0_621
	global_load_dwordx4 v[52:55], v[32:33], off
	s_nop 0
	global_load_dwordx4 v[30:33], v[32:33], off offset:16
	s_waitcnt vmcnt(0)
	v_lshlrev_b32_e32 v18, 16, v12
	v_and_b32_e32 v12, 0xffff0000, v12
	v_and_b32_e32 v34, 0xffff0000, v13
	v_lshlrev_b32_e32 v56, 16, v14
	v_and_b32_e32 v14, 0xffff0000, v14
	v_and_b32_e32 v60, 0xffff0000, v15
	v_lshlrev_b32_e32 v26, 16, v13
	v_lshlrev_b32_e32 v58, 16, v15
	s_waitcnt lgkmcnt(0)
	v_pk_mul_f32 v[12:13], v[52:53], v[12:13] op_sel:[1,0] op_sel_hi:[0,0]
	v_pk_mul_f32 v[34:35], v[54:55], v[34:35] op_sel:[1,0] op_sel_hi:[0,0]
	v_pk_mul_f32 v[14:15], v[30:31], v[14:15] op_sel:[1,0] op_sel_hi:[0,0]
	v_pk_mul_f32 v[60:61], v[32:33], v[60:61] op_sel:[1,0] op_sel_hi:[0,0]
	v_pk_fma_f32 v[62:63], v[52:53], v[18:19], v[12:13] neg_lo:[0,0,1] neg_hi:[0,0,1]
	v_pk_fma_f32 v[12:13], v[52:53], v[18:19], v[12:13] op_sel_hi:[1,0,1]
	v_pk_fma_f32 v[52:53], v[54:55], v[26:27], v[34:35] neg_lo:[0,0,1] neg_hi:[0,0,1]
	v_pk_fma_f32 v[26:27], v[54:55], v[26:27], v[34:35] op_sel_hi:[1,0,1]
	v_pk_fma_f32 v[34:35], v[30:31], v[56:57], v[14:15] neg_lo:[0,0,1] neg_hi:[0,0,1]
	v_pk_fma_f32 v[14:15], v[30:31], v[56:57], v[14:15] op_sel_hi:[1,0,1]
	v_pk_fma_f32 v[30:31], v[32:33], v[58:59], v[60:61] neg_lo:[0,0,1] neg_hi:[0,0,1]
	v_pk_fma_f32 v[32:33], v[32:33], v[58:59], v[60:61] op_sel_hi:[1,0,1]
	v_cvt_pk_bf16_f32 v12, v62, v13
	v_cvt_pk_bf16_f32 v13, v52, v27
	v_cvt_pk_bf16_f32 v14, v34, v15
	v_cvt_pk_bf16_f32 v15, v30, v33

.LBB0_647:
	v_cmp_ne_u64_e64 s[6:7], 0, v[26:27]
	s_and_saveexec_b64 s[10:11], s[6:7]
	s_cbranch_execz .LBB0_649
	global_load_dwordx4 v[28:31], v[26:27], off
	s_nop 0
	global_load_dwordx4 v[24:27], v[26:27], off offset:16
	v_lshlrev_b32_e32 v14, 16, v8
	v_and_b32_e32 v8, 0xffff0000, v8
	v_and_b32_e32 v32, 0xffff0000, v9
	v_lshlrev_b32_e32 v34, 16, v10
	v_and_b32_e32 v10, 0xffff0000, v10
	v_and_b32_e32 v52, 0xffff0000, v11
	v_lshlrev_b32_e32 v18, 16, v9
	v_lshlrev_b32_e32 v48, 16, v11
	s_waitcnt vmcnt(0) lgkmcnt(0)
	v_pk_mul_f32 v[8:9], v[28:29], v[8:9] op_sel:[1,0] op_sel_hi:[0,0]
	v_pk_mul_f32 v[32:33], v[30:31], v[32:33] op_sel:[1,0] op_sel_hi:[0,0]
	v_pk_mul_f32 v[10:11], v[24:25], v[10:11] op_sel:[1,0] op_sel_hi:[0,0]
	v_pk_mul_f32 v[52:53], v[26:27], v[52:53] op_sel:[1,0] op_sel_hi:[0,0]
	v_pk_fma_f32 v[54:55], v[28:29], v[14:15], v[8:9] neg_lo:[0,0,1] neg_hi:[0,0,1]
	v_pk_fma_f32 v[8:9], v[28:29], v[14:15], v[8:9] op_sel_hi:[1,0,1]
	v_pk_fma_f32 v[14:15], v[30:31], v[18:19], v[32:33] neg_lo:[0,0,1] neg_hi:[0,0,1]
	v_pk_fma_f32 v[28:29], v[30:31], v[18:19], v[32:33] op_sel_hi:[1,0,1]
	v_pk_fma_f32 v[30:31], v[24:25], v[34:35], v[10:11] neg_lo:[0,0,1] neg_hi:[0,0,1]
	v_pk_fma_f32 v[10:11], v[24:25], v[34:35], v[10:11] op_sel_hi:[1,0,1]
	v_pk_fma_f32 v[24:25], v[26:27], v[48:49], v[52:53] neg_lo:[0,0,1] neg_hi:[0,0,1]
	v_pk_fma_f32 v[26:27], v[26:27], v[48:49], v[52:53] op_sel_hi:[1,0,1]
	v_cvt_pk_bf16_f32 v8, v54, v9
	v_cvt_pk_bf16_f32 v9, v14, v29
	v_cvt_pk_bf16_f32 v10, v30, v11
	v_cvt_pk_bf16_f32 v11, v24, v27

.LBB0_675:
	v_cmp_ne_u64_e64 s[4:5], 0, v[12:13]
	s_and_saveexec_b64 s[8:9], s[4:5]
	s_cbranch_execz .LBB0_677
	global_load_dwordx4 v[22:25], v[12:13], off
	s_nop 0
	global_load_dwordx4 v[10:13], v[12:13], off offset:16
	s_waitcnt lgkmcnt(0)
	v_lshlrev_b32_e32 v14, 16, v4
	v_and_b32_e32 v4, 0xffff0000, v4
	v_and_b32_e32 v26, 0xffff0000, v5
	v_lshlrev_b32_e32 v28, 16, v6
	v_and_b32_e32 v6, 0xffff0000, v6
	v_and_b32_e32 v32, 0xffff0000, v7
	v_lshlrev_b32_e32 v18, 16, v5
	v_lshlrev_b32_e32 v30, 16, v7
	s_waitcnt vmcnt(0)
	v_pk_mul_f32 v[4:5], v[22:23], v[4:5] op_sel:[1,0] op_sel_hi:[0,0]
	v_pk_mul_f32 v[26:27], v[24:25], v[26:27] op_sel:[1,0] op_sel_hi:[0,0]
	v_pk_mul_f32 v[6:7], v[10:11], v[6:7] op_sel:[1,0] op_sel_hi:[0,0]
	v_pk_mul_f32 v[32:33], v[12:13], v[32:33] op_sel:[1,0] op_sel_hi:[0,0]
	v_pk_fma_f32 v[34:35], v[22:23], v[14:15], v[4:5] neg_lo:[0,0,1] neg_hi:[0,0,1]
	v_pk_fma_f32 v[4:5], v[22:23], v[14:15], v[4:5] op_sel_hi:[1,0,1]
	v_pk_fma_f32 v[14:15], v[24:25], v[18:19], v[26:27] neg_lo:[0,0,1] neg_hi:[0,0,1]
	v_pk_fma_f32 v[22:23], v[24:25], v[18:19], v[26:27] op_sel_hi:[1,0,1]
	v_pk_fma_f32 v[24:25], v[10:11], v[28:29], v[6:7] neg_lo:[0,0,1] neg_hi:[0,0,1]
	v_pk_fma_f32 v[6:7], v[10:11], v[28:29], v[6:7] op_sel_hi:[1,0,1]
	v_pk_fma_f32 v[10:11], v[12:13], v[30:31], v[32:33] neg_lo:[0,0,1] neg_hi:[0,0,1]
	v_pk_fma_f32 v[12:13], v[12:13], v[30:31], v[32:33] op_sel_hi:[1,0,1]
	v_cvt_pk_bf16_f32 v4, v34, v5
	v_cvt_pk_bf16_f32 v5, v14, v23
	v_cvt_pk_bf16_f32 v6, v24, v7
	v_cvt_pk_bf16_f32 v7, v10, v13

.LBB0_703:
	v_cmp_ne_u64_e32 vcc, 0, v[8:9]
	s_and_saveexec_b64 s[6:7], vcc
	s_cbranch_execz .LBB0_512
	global_load_dwordx4 v[10:13], v[8:9], off
	s_nop 0
	global_load_dwordx4 v[6:9], v[8:9], off offset:16
	v_lshlrev_b32_e32 v14, 16, v0
	v_and_b32_e32 v0, 0xffff0000, v0
	v_and_b32_e32 v20, 0xffff0000, v1
	v_lshlrev_b32_e32 v22, 16, v2
	v_and_b32_e32 v2, 0xffff0000, v2
	v_and_b32_e32 v26, 0xffff0000, v3
	v_lshlrev_b32_e32 v18, 16, v1
	v_lshlrev_b32_e32 v24, 16, v3
	s_waitcnt vmcnt(0) lgkmcnt(0)
	v_pk_mul_f32 v[0:1], v[10:11], v[0:1] op_sel:[1,0] op_sel_hi:[0,0]
	v_pk_mul_f32 v[20:21], v[12:13], v[20:21] op_sel:[1,0] op_sel_hi:[0,0]
	v_pk_mul_f32 v[2:3], v[6:7], v[2:3] op_sel:[1,0] op_sel_hi:[0,0]
	v_pk_mul_f32 v[26:27], v[8:9], v[26:27] op_sel:[1,0] op_sel_hi:[0,0]
	v_pk_fma_f32 v[28:29], v[10:11], v[14:15], v[0:1] neg_lo:[0,0,1] neg_hi:[0,0,1]
	v_pk_fma_f32 v[0:1], v[10:11], v[14:15], v[0:1] op_sel_hi:[1,0,1]
	v_pk_fma_f32 v[10:11], v[12:13], v[18:19], v[20:21] neg_lo:[0,0,1] neg_hi:[0,0,1]
	v_pk_fma_f32 v[12:13], v[12:13], v[18:19], v[20:21] op_sel_hi:[1,0,1]
	v_pk_fma_f32 v[14:15], v[6:7], v[22:23], v[2:3] neg_lo:[0,0,1] neg_hi:[0,0,1]
	v_pk_fma_f32 v[2:3], v[6:7], v[22:23], v[2:3] op_sel_hi:[1,0,1]
	v_pk_fma_f32 v[6:7], v[8:9], v[24:25], v[26:27] neg_lo:[0,0,1] neg_hi:[0,0,1]
	v_pk_fma_f32 v[8:9], v[8:9], v[24:25], v[26:27] op_sel_hi:[1,0,1]
	v_cvt_pk_bf16_f32 v0, v28, v1
	v_cvt_pk_bf16_f32 v1, v10, v13
	v_cvt_pk_bf16_f32 v2, v14, v3
	v_cvt_pk_bf16_f32 v3, v6, v9
	s_branch .LBB0_512

.LBB0_728:
	s_andn2_saveexec_b64 s[4:5], s[4:5]
	v_lshl_add_u32 v0, v1, 3, v35
	s_or_b64 exec, exec, s[4:5]
	v_mad_i64_i32 v[2:3], s[4:5], v20, s54, v[10:11]
	v_ashrrev_i32_e32 v1, 31, v0
	v_lshl_add_u64 v[0:1], v[0:1], 1, v[2:3]
	global_load_dwordx4 v[4:7], v[0:1], off
	v_lshl_add_u32 v18, s62, 9, v50
	v_mul_hi_i32 v0, v18, s44
	v_add_u32_e32 v0, v0, v18
	v_lshrrev_b32_e32 v1, 31, v0
	v_ashrrev_i32_e32 v0, 7, v0
	v_add_u32_e32 v14, v0, v1
	v_mad_u64_u32 v[16:17], s[4:5], v14, s45, v[18:19]
	v_cmp_lt_i32_e32 vcc, 3, v16
	s_and_saveexec_b64 s[4:5], vcc
	s_xor_b64 s[8:9], exec, s[4:5]
	s_cbranch_execz .LBB0_748
	v_cmp_lt_u32_e64 s[4:5], 51, v16
	s_and_saveexec_b64 s[36:37], s[4:5]
	s_xor_b64 s[36:37], exec, s[36:37]
	s_cbranch_execz .LBB0_745
	v_cmp_lt_u32_e64 s[4:5], s46, v16
	s_and_saveexec_b64 s[40:41], s[4:5]
	s_xor_b64 s[40:41], exec, s[40:41]
	s_cbranch_execz .LBB0_742
	v_cmp_lt_u32_e64 s[4:5], s47, v16
	s_and_saveexec_b64 s[42:43], s[4:5]
	s_xor_b64 s[42:43], exec, s[42:43]
	s_cbranch_execz .LBB0_739
	v_cmp_lt_u32_e64 s[4:5], s48, v16
	v_lshlrev_b32_e32 v1, 3, v16
	s_and_saveexec_b64 s[62:63], s[4:5]
	s_xor_b64 s[4:5], exec, s[62:63]
	v_add_u32_e32 v0, 0x380, v1
	s_andn2_saveexec_b64 s[4:5], s[4:5]
	v_add_u32_e32 v0, 0x80, v1
	s_or_b64 exec, exec, s[4:5]

.LBB0_748:
	s_andn2_saveexec_b64 s[4:5], s[8:9]
	v_lshl_add_u32 v0, v16, 3, v35
	s_or_b64 exec, exec, s[4:5]
	v_mad_i64_i32 v[2:3], s[4:5], v14, s54, v[10:11]
	v_ashrrev_i32_e32 v1, 31, v0
	v_lshl_add_u64 v[0:1], v[0:1], 1, v[2:3]
	global_load_dwordx4 v[0:3], v[0:1], off
	v_add_u32_e32 v12, 0xfffff000, v20
	v_lshrrev_b32_e32 v12, 11, v12
	v_ashrrev_i32_e32 v17, 8, v20
	v_cmp_lt_i32_e64 s[8:9], s56, v9
	v_ashrrev_i32_e32 v21, 31, v20
	v_cmp_gt_i32_e64 s[4:5], s55, v9
	v_cndmask_b32_e64 v17, v17, v12, s[8:9]
	v_lshlrev_b32_e32 v22, 1, v17
	v_cndmask_b32_e64 v19, v30, v31, s[8:9]
	v_ashrrev_i32_e32 v23, 31, v22
	v_and_b32_e32 v12, v19, v20
	v_lshlrev_b64 v[22:23], 8, v[22:23]
	v_lshl_add_u64 v[28:29], v[22:23], 0, v[12:13]
	s_and_saveexec_b64 s[8:9], s[6:7]
	s_xor_b64 s[8:9], exec, s[8:9]
	s_cbranch_execnz .LBB0_754
	s_andn2_saveexec_b64 s[6:7], s[8:9]
	s_cbranch_execnz .LBB0_771

.LBB0_775:
	v_cmp_ne_u64_e64 s[4:5], 0, v[26:27]
	s_and_saveexec_b64 s[8:9], s[4:5]
	s_cbranch_execz .LBB0_777
	global_load_dwordx4 v[44:47], v[26:27], off
	s_nop 0
	global_load_dwordx4 v[24:27], v[26:27], off offset:16
	s_waitcnt vmcnt(0) lgkmcnt(0)
	v_lshlrev_b32_e32 v12, 16, v4
	v_and_b32_e32 v4, 0xffff0000, v4
	v_and_b32_e32 v28, 0xffff0000, v5
	v_lshlrev_b32_e32 v40, 16, v6
	v_and_b32_e32 v6, 0xffff0000, v6
	v_and_b32_e32 v52, 0xffff0000, v7
	v_lshlrev_b32_e32 v20, 16, v5
	v_lshlrev_b32_e32 v48, 16, v7
	v_pk_mul_f32 v[4:5], v[44:45], v[4:5] op_sel:[1,0] op_sel_hi:[0,0]
	v_pk_mul_f32 v[28:29], v[46:47], v[28:29] op_sel:[1,0] op_sel_hi:[0,0]
	v_pk_mul_f32 v[6:7], v[24:25], v[6:7] op_sel:[1,0] op_sel_hi:[0,0]
	v_pk_mul_f32 v[52:53], v[26:27], v[52:53] op_sel:[1,0] op_sel_hi:[0,0]
	v_pk_fma_f32 v[54:55], v[44:45], v[12:13], v[4:5] neg_lo:[0,0,1] neg_hi:[0,0,1]
	v_pk_fma_f32 v[4:5], v[44:45], v[12:13], v[4:5] op_sel_hi:[1,0,1]
	v_pk_fma_f32 v[44:45], v[46:47], v[20:21], v[28:29] neg_lo:[0,0,1] neg_hi:[0,0,1]
	v_pk_fma_f32 v[20:21], v[46:47], v[20:21], v[28:29] op_sel_hi:[1,0,1]
	v_pk_fma_f32 v[28:29], v[24:25], v[40:41], v[6:7] neg_lo:[0,0,1] neg_hi:[0,0,1]
	v_pk_fma_f32 v[6:7], v[24:25], v[40:41], v[6:7] op_sel_hi:[1,0,1]
	v_pk_fma_f32 v[24:25], v[26:27], v[48:49], v[52:53] neg_lo:[0,0,1] neg_hi:[0,0,1]
	v_pk_fma_f32 v[26:27], v[26:27], v[48:49], v[52:53] op_sel_hi:[1,0,1]
	v_cvt_pk_bf16_f32 v4, v54, v5
	v_cvt_pk_bf16_f32 v5, v44, v21
	v_cvt_pk_bf16_f32 v6, v28, v7
	v_cvt_pk_bf16_f32 v7, v24, v27

.LBB0_803:
	v_cmp_ne_u64_e32 vcc, 0, v[18:19]
	s_and_saveexec_b64 s[6:7], vcc
	s_cbranch_execz .LBB0_708
	global_load_dwordx4 v[14:17], v[18:19], off
	s_nop 0
	global_load_dwordx4 v[18:21], v[18:19], off offset:16
	v_lshlrev_b32_e32 v6, 16, v0
	v_and_b32_e32 v0, 0xffff0000, v0
	v_and_b32_e32 v22, 0xffff0000, v1
	v_lshlrev_b32_e32 v24, 16, v2
	v_and_b32_e32 v2, 0xffff0000, v2
	v_and_b32_e32 v28, 0xffff0000, v3
	v_lshlrev_b32_e32 v12, 16, v1
	v_lshlrev_b32_e32 v26, 16, v3
	s_waitcnt vmcnt(0) lgkmcnt(0)
	v_pk_mul_f32 v[0:1], v[14:15], v[0:1] op_sel:[1,0] op_sel_hi:[0,0]
	v_pk_mul_f32 v[22:23], v[16:17], v[22:23] op_sel:[1,0] op_sel_hi:[0,0]
	v_pk_mul_f32 v[2:3], v[18:19], v[2:3] op_sel:[1,0] op_sel_hi:[0,0]
	v_pk_mul_f32 v[28:29], v[20:21], v[28:29] op_sel:[1,0] op_sel_hi:[0,0]
	v_pk_fma_f32 v[40:41], v[14:15], v[6:7], v[0:1] neg_lo:[0,0,1] neg_hi:[0,0,1]
	v_pk_fma_f32 v[0:1], v[14:15], v[6:7], v[0:1] op_sel_hi:[1,0,1]
	v_pk_fma_f32 v[6:7], v[16:17], v[12:13], v[22:23] neg_lo:[0,0,1] neg_hi:[0,0,1]
	v_pk_fma_f32 v[14:15], v[16:17], v[12:13], v[22:23] op_sel_hi:[1,0,1]
	v_pk_fma_f32 v[16:17], v[18:19], v[24:25], v[2:3] neg_lo:[0,0,1] neg_hi:[0,0,1]
	v_pk_fma_f32 v[2:3], v[18:19], v[24:25], v[2:3] op_sel_hi:[1,0,1]
	v_pk_fma_f32 v[18:19], v[20:21], v[26:27], v[28:29] neg_lo:[0,0,1] neg_hi:[0,0,1]
	v_pk_fma_f32 v[20:21], v[20:21], v[26:27], v[28:29] op_sel_hi:[1,0,1]
	v_cvt_pk_bf16_f32 v0, v40, v1
	v_cvt_pk_bf16_f32 v1, v6, v15
	v_cvt_pk_bf16_f32 v2, v16, v3
	v_cvt_pk_bf16_f32 v3, v18, v21
	s_branch .LBB0_708

.LBB0_827:
	s_andn2_saveexec_b64 s[6:7], s[6:7]
	v_lshl_add_u32 v0, v1, 3, v25
	s_or_b64 exec, exec, s[6:7]
	v_mad_i64_i32 v[2:3], s[6:7], v12, s51, v[6:7]
	v_ashrrev_i32_e32 v1, 31, v0
	v_lshl_add_u64 v[0:1], v[0:1], 1, v[2:3]
	global_load_dwordx4 v[0:3], v[0:1], off
	v_add_u32_e32 v8, 0xfffff000, v12
	v_lshrrev_b32_e32 v8, 11, v8
	v_ashrrev_i32_e32 v10, 8, v12
	v_cmp_lt_i32_e64 s[6:7], s53, v5
	v_ashrrev_i32_e32 v13, 31, v12
	v_cmp_gt_i32_e32 vcc, s52, v5
	v_cndmask_b32_e64 v10, v10, v8, s[6:7]
	v_cndmask_b32_e64 v11, v20, v21, s[6:7]
	v_lshlrev_b32_e32 v10, 1, v10
	v_and_b32_e32 v8, v11, v12
	v_ashrrev_i32_e32 v11, 31, v10
	v_lshlrev_b64 v[10:11], 8, v[10:11]
	v_lshl_add_u64 v[18:19], v[10:11], 0, v[8:9]
	s_and_saveexec_b64 s[6:7], s[4:5]
	s_xor_b64 s[6:7], exec, s[6:7]
	s_cbranch_execnz .LBB0_833
	s_andn2_saveexec_b64 s[4:5], s[6:7]
	s_cbranch_execnz .LBB0_850

.LBB0_854:
	v_cmp_ne_u64_e32 vcc, 0, v[16:17]
	s_and_saveexec_b64 s[6:7], vcc
	s_cbranch_execz .LBB0_807
	global_load_dwordx4 v[12:15], v[16:17], off
	s_nop 0
	global_load_dwordx4 v[16:19], v[16:17], off offset:16
	s_waitcnt vmcnt(0) lgkmcnt(0)
	v_lshlrev_b32_e32 v8, 16, v0
	v_and_b32_e32 v0, 0xffff0000, v0
	v_and_b32_e32 v30, 0xffff0000, v1
	v_lshlrev_b32_e32 v32, 16, v2
	v_and_b32_e32 v2, 0xffff0000, v2
	v_and_b32_e32 v36, 0xffff0000, v3
	v_lshlrev_b32_e32 v28, 16, v1
	v_lshlrev_b32_e32 v34, 16, v3
	v_pk_mul_f32 v[0:1], v[12:13], v[0:1] op_sel:[1,0] op_sel_hi:[0,0]
	v_pk_mul_f32 v[30:31], v[14:15], v[30:31] op_sel:[1,0] op_sel_hi:[0,0]
	v_pk_mul_f32 v[2:3], v[16:17], v[2:3] op_sel:[1,0] op_sel_hi:[0,0]
	v_pk_mul_f32 v[36:37], v[18:19], v[36:37] op_sel:[1,0] op_sel_hi:[0,0]
	v_pk_fma_f32 v[38:39], v[12:13], v[8:9], v[0:1] neg_lo:[0,0,1] neg_hi:[0,0,1]
	v_pk_fma_f32 v[0:1], v[12:13], v[8:9], v[0:1] op_sel_hi:[1,0,1]
	v_pk_fma_f32 v[12:13], v[14:15], v[28:29], v[30:31] neg_lo:[0,0,1] neg_hi:[0,0,1]
	v_pk_fma_f32 v[14:15], v[14:15], v[28:29], v[30:31] op_sel_hi:[1,0,1]
	v_pk_fma_f32 v[28:29], v[16:17], v[32:33], v[2:3] neg_lo:[0,0,1] neg_hi:[0,0,1]
	v_pk_fma_f32 v[2:3], v[16:17], v[32:33], v[2:3] op_sel_hi:[1,0,1]
	v_pk_fma_f32 v[16:17], v[18:19], v[34:35], v[36:37] neg_lo:[0,0,1] neg_hi:[0,0,1]
	v_pk_fma_f32 v[18:19], v[18:19], v[34:35], v[36:37] op_sel_hi:[1,0,1]
	v_cvt_pk_bf16_f32 v0, v38, v1
	v_cvt_pk_bf16_f32 v1, v12, v15
	v_cvt_pk_bf16_f32 v2, v28, v3
	v_cvt_pk_bf16_f32 v3, v16, v19
	s_branch .LBB0_807

.LBB0_858:
	v_add_u32_e32 v18, s39, v53
	v_mad_i64_i32 v[22:23], s[4:5], v18, s54, v[16:17]
	s_waitcnt lgkmcnt(0)
	global_load_dwordx4 v[8:11], v51, s[56:57] offset:16
	global_load_dwordx4 v[0:3], v51, s[58:59] offset:16
	global_load_dwordx4 v[12:15], v51, s[56:57]
	global_load_dwordx4 v[4:7], v51, s[58:59]
	v_add_co_u32_e32 v36, vcc, 0x1000, v22
	v_add_u32_e32 v20, s2, v53
	s_nop 0
	v_addc_co_u32_e32 v37, vcc, 0, v23, vcc
	v_mad_i64_i32 v[34:35], s[4:5], v20, s54, v[16:17]
	global_load_dwordx4 v[26:29], v[36:37], off offset:64
	global_load_dwordx4 v[30:33], v[36:37], off offset:80
	v_add_co_u32_e32 v42, vcc, s55, v34
	s_add_i32 s3, s3, s33
	s_nop 0
	v_addc_co_u32_e32 v43, vcc, 0, v35, vcc
	global_load_dwordx4 v[34:37], v[42:43], off offset:64
	global_load_dwordx4 v[38:41], v[42:43], off offset:80
	s_add_i32 s4, s76, s3
	s_cmp_gt_i32 s4, 23
	v_ashrrev_i32_e32 v19, 31, v18
	v_lshlrev_b64 v[18:19], 5, v[18:19]
	v_lshl_add_u64 v[24:25], s[70:71], 0, v[18:19]
	v_lshl_add_u64 v[22:23], s[72:73], 0, v[18:19]
	v_ashrrev_i32_e32 v21, 31, v20
	v_lshlrev_b64 v[20:21], 5, v[20:21]
	v_lshl_add_u64 v[18:19], s[70:71], 0, v[20:21]
	v_lshl_add_u64 v[20:21], s[72:73], 0, v[20:21]
	v_add_u32_e32 v53, s38, v53
	s_waitcnt vmcnt(0)
	v_mul_f32_e32 v8, 0x3fb8aa3b, v8
	v_mul_f32_e32 v9, 0x3fb8aa3b, v9
	v_mul_f32_e32 v12, 0x3fb8aa3b, v12
	v_mul_f32_e32 v14, 0x3fb8aa3b, v14
	v_mul_f32_e32 v13, 0x3fb8aa3b, v13
	v_mul_f32_e32 v15, 0x3fb8aa3b, v15
	v_mul_f32_e32 v10, 0x3fb8aa3b, v10
	v_mul_f32_e32 v11, 0x3fb8aa3b, v11
	v_exp_f32_e32 v42, v12
	v_exp_f32_e32 v44, v14
	v_exp_f32_e32 v43, v13
	v_exp_f32_e32 v45, v15
	v_exp_f32_e32 v46, v8
	v_exp_f32_e32 v47, v9
	v_exp_f32_e32 v48, v10
	v_exp_f32_e32 v49, v11
	s_waitcnt lgkmcnt(0)
	v_lshlrev_b32_e32 v8, 16, v26
	v_and_b32_e32 v9, 0xffff0000, v26
	v_lshlrev_b32_e32 v10, 16, v27
	v_and_b32_e32 v11, 0xffff0000, v27
	v_lshlrev_b32_e32 v14, 16, v30
	v_and_b32_e32 v26, 0xffff0000, v30
	v_lshlrev_b32_e32 v27, 16, v31
	v_lshlrev_b32_e32 v12, 16, v28
	v_and_b32_e32 v13, 0xffff0000, v28
	v_lshlrev_b32_e32 v28, 16, v29
	v_and_b32_e32 v29, 0xffff0000, v29
	v_and_b32_e32 v30, 0xffff0000, v31
	v_lshlrev_b32_e32 v31, 16, v32
	v_and_b32_e32 v32, 0xffff0000, v32
	v_mul_f32_e32 v56, 0xbfb8aa3b, v14
	v_pk_add_f32 v[14:15], v[4:5], v[8:9]
	v_mul_f32_e32 v57, 0xbfb8aa3b, v26
	v_mul_f32_e32 v58, 0xbfb8aa3b, v27
	v_pk_add_f32 v[26:27], v[6:7], v[10:11]
	v_lshlrev_b32_e32 v54, 16, v33
	v_and_b32_e32 v55, 0xffff0000, v33
	v_xor_b32_e32 v8, 0x80000000, v42
	v_xor_b32_e32 v10, 0x80000000, v44
	v_mul_f32_e32 v42, 0xbfb8aa3b, v30
	v_mul_f32_e32 v44, 0xbfb8aa3b, v32
	v_pk_add_f32 v[32:33], v[2:3], v[28:29]
	v_lshlrev_b32_e32 v2, 16, v36
	v_and_b32_e32 v3, 0xffff0000, v36
	v_mul_f32_e32 v62, 0x3fb8aa3b, v15
	v_exp_f32_e32 v36, v58
	v_mul_f32_e32 v58, 0x3fb8aa3b, v27
	v_xor_b32_e32 v9, 0x80000000, v43
	v_xor_b32_e32 v11, 0x80000000, v45
	v_mul_f32_e32 v43, 0xbfb8aa3b, v31
	v_pk_add_f32 v[30:31], v[0:1], v[12:13]
	v_mul_f32_e32 v45, 0xbfb8aa3b, v54
	v_xor_b32_e32 v13, 0x80000000, v47
	v_xor_b32_e32 v12, 0x80000000, v46
	v_xor_b32_e32 v29, 0x80000000, v49
	v_xor_b32_e32 v28, 0x80000000, v48
	v_mul_f32_e32 v46, 0xbfb8aa3b, v55
	v_lshlrev_b32_e32 v6, 16, v34
	v_and_b32_e32 v7, 0xffff0000, v34
	v_lshlrev_b32_e32 v4, 16, v35
	v_and_b32_e32 v5, 0xffff0000, v35
	v_lshlrev_b32_e32 v0, 16, v37
	v_and_b32_e32 v1, 0xffff0000, v37
	v_lshlrev_b32_e32 v47, 16, v38
	v_and_b32_e32 v48, 0xffff0000, v38
	v_lshlrev_b32_e32 v49, 16, v39
	v_and_b32_e32 v54, 0xffff0000, v39
	v_lshlrev_b32_e32 v55, 16, v40
	v_and_b32_e32 v59, 0xffff0000, v40
	v_lshlrev_b32_e32 v60, 16, v41
	v_and_b32_e32 v61, 0xffff0000, v41
	v_exp_f32_e32 v34, v56
	v_mul_f32_e32 v56, 0x3fb8aa3b, v14
	v_exp_f32_e32 v35, v57
	v_mul_f32_e32 v57, 0x3fb8aa3b, v26
	v_exp_f32_e32 v37, v42
	v_exp_f32_e32 v62, v62
	v_exp_f32_e32 v58, v58
	v_exp_f32_e32 v38, v43
	v_mul_f32_e32 v42, 0x3fb8aa3b, v30
	v_mul_f32_e32 v43, 0x3fb8aa3b, v31
	v_exp_f32_e32 v40, v45
	v_exp_f32_e32 v41, v46
	v_mul_f32_e32 v46, 0xbfb8aa3b, v47
	v_mul_f32_e32 v47, 0xbfb8aa3b, v48
	v_mul_f32_e32 v48, 0xbfb8aa3b, v49
	v_mul_f32_e32 v49, 0xbfb8aa3b, v54
	v_mul_f32_e32 v54, 0xbfb8aa3b, v55
	v_mul_f32_e32 v55, 0xbfb8aa3b, v59
	v_mul_f32_e32 v59, 0xbfb8aa3b, v60
	v_mul_f32_e32 v60, 0xbfb8aa3b, v61
	v_exp_f32_e32 v61, v56
	v_exp_f32_e32 v63, v57
	v_exp_f32_e32 v39, v44
	v_mul_f32_e32 v44, 0x3fb8aa3b, v32
	v_mul_f32_e32 v45, 0x3fb8aa3b, v33
	v_exp_f32_e32 v64, v42
	v_exp_f32_e32 v65, v43
	v_exp_f32_e32 v42, v46
	v_exp_f32_e32 v43, v47
	v_exp_f32_e32 v46, v48
	v_exp_f32_e32 v47, v49
	v_exp_f32_e32 v54, v54
	v_exp_f32_e32 v55, v55
	v_exp_f32_e32 v56, v59
	v_exp_f32_e32 v57, v60
	v_exp_f32_e32 v66, v44
	v_exp_f32_e32 v67, v45
	v_pk_add_f32 v[48:49], v[36:37], 1.0 op_sel_hi:[1,0]
	v_add_f32_e32 v60, 1.0, v62
	v_add_f32_e32 v58, 1.0, v58
	v_pk_add_f32 v[44:45], v[34:35], 1.0 op_sel_hi:[1,0]
	v_pk_add_f32 v[40:41], v[40:41], 1.0 op_sel_hi:[1,0]
	v_add_f32_e32 v59, 1.0, v61
	v_add_f32_e32 v61, 1.0, v63
	v_div_scale_f32 v62, s[4:5], v49, v49, 1.0
	v_cmp_gt_f32_e64 s[40:41], s60, v60
	v_cmp_gt_f32_e64 s[44:45], s60, v58
	v_pk_add_f32 v[36:37], v[38:39], 1.0 op_sel_hi:[1,0]
	v_div_scale_f32 v68, s[4:5], v48, v48, 1.0
	v_div_scale_f32 v72, s[4:5], v44, v44, 1.0
	v_div_scale_f32 v74, s[4:5], v41, v41, 1.0
	v_pk_add_f32 v[42:43], v[42:43], 1.0 op_sel_hi:[1,0]
	v_pk_add_f32 v[46:47], v[46:47], 1.0 op_sel_hi:[1,0]
	v_pk_add_f32 v[34:35], v[54:55], 1.0 op_sel_hi:[1,0]
	v_pk_add_f32 v[38:39], v[56:57], 1.0 op_sel_hi:[1,0]
	v_cndmask_b32_e64 v55, 0, 32, s[40:41]
	v_cmp_gt_f32_e64 s[42:43], s60, v61
	v_cndmask_b32_e64 v57, 0, 32, s[44:45]
	v_rcp_f32_e32 v82, v62
	v_div_scale_f32 v70, s[4:5], v45, v45, 1.0
	v_add_f32_e32 v64, 1.0, v64
	v_add_f32_e32 v65, 1.0, v65
	v_add_f32_e32 v66, 1.0, v66
	v_add_f32_e32 v67, 1.0, v67
	v_div_scale_f32 v76, s[4:5], v40, v40, 1.0
	v_cmp_gt_f32_e64 s[36:37], s60, v59
	v_cndmask_b32_e64 v56, 0, 32, s[42:43]
	v_rcp_f32_e32 v83, v68
	v_rcp_f32_e32 v85, v72
	v_rcp_f32_e32 v90, v74
	v_div_scale_f32 v96, s[16:17], v46, v46, 1.0
	v_div_scale_f32 v100, s[16:17], v42, v42, 1.0
	v_div_scale_f32 v102, s[16:17], v39, v39, 1.0
	v_ldexp_f32 v55, v60, v55
	v_ldexp_f32 v57, v58, v57
	v_cndmask_b32_e64 v54, 0, 32, s[36:37]
	v_rcp_f32_e32 v84, v70
	v_cmp_gt_f32_e64 s[46:47], s60, v64
	v_cmp_gt_f32_e64 s[48:49], s60, v65
	v_cmp_gt_f32_e64 s[50:51], s60, v66
	v_cmp_gt_f32_e64 s[52:53], s60, v67
	v_rcp_f32_e32 v91, v76
	v_div_scale_f32 v98, s[16:17], v43, v43, 1.0
	v_div_scale_f32 v104, s[16:17], v38, v38, 1.0
	v_ldexp_f32 v56, v61, v56
	v_rcp_f32_e32 v111, v96
	v_rcp_f32_e32 v113, v100
	v_rcp_f32_e32 v114, v102
	v_log_f32_e32 v55, v55
	v_log_f32_e32 v57, v57
	v_div_scale_f32 v78, s[4:5], v37, v37, 1.0
	v_cndmask_b32_e64 v86, 0, 32, s[46:47]
	v_cndmask_b32_e64 v87, 0, 32, s[48:49]
	v_cndmask_b32_e64 v88, 0, 32, s[50:51]
	v_cndmask_b32_e64 v89, 0, 32, s[52:53]
	v_div_scale_f32 v94, s[16:17], v47, v47, 1.0
	v_ldexp_f32 v54, v59, v54
	v_rcp_f32_e32 v112, v98
	v_rcp_f32_e32 v115, v104
	v_log_f32_e32 v56, v56
	v_div_scale_f32 v80, s[4:5], v36, v36, 1.0
	v_rcp_f32_e32 v92, v78
	v_div_scale_f32 v106, s[16:17], v35, v35, 1.0
	v_ldexp_f32 v64, v64, v86
	v_ldexp_f32 v65, v65, v87
	v_ldexp_f32 v66, v66, v88
	v_ldexp_f32 v67, v67, v89
	v_rcp_f32_e32 v110, v94
	v_log_f32_e32 v54, v54
	v_fma_f32 v118, -v62, v82, 1.0
	v_div_scale_f32 v63, vcc, 1.0, v49, 1.0
	v_rcp_f32_e32 v93, v80
	v_div_scale_f32 v108, s[16:17], v34, v34, 1.0
	v_rcp_f32_e32 v116, v106
	v_log_f32_e32 v64, v64
	v_log_f32_e32 v65, v65
	v_log_f32_e32 v66, v66
	v_log_f32_e32 v67, v67
	v_fma_f32 v119, -v68, v83, 1.0
	v_fma_f32 v121, -v72, v85, 1.0
	v_fma_f32 v122, -v74, v90, 1.0
	v_fmac_f32_e32 v82, v118, v82
	v_div_scale_f32 v69, s[30:31], 1.0, v48, 1.0
	v_rcp_f32_e32 v117, v108
	v_fma_f32 v120, -v70, v84, 1.0
	v_fma_f32 v123, -v76, v91, 1.0
	v_fmac_f32_e32 v83, v119, v83
	v_fmac_f32_e32 v85, v121, v85
	v_fmac_f32_e32 v90, v122, v90
	v_fma_f32 v119, -v96, v111, 1.0
	v_fma_f32 v121, -v100, v113, 1.0
	v_fma_f32 v122, -v102, v114, 1.0
	v_mul_f32_e32 v127, 0x3f317217, v55
	v_mul_f32_e32 v129, 0x3f317217, v57
	v_mul_f32_e32 v130, v63, v82
	v_fmac_f32_e32 v84, v120, v84
	v_fmac_f32_e32 v91, v123, v91
	v_fma_f32 v120, -v98, v112, 1.0
	v_fma_f32 v123, -v104, v115, 1.0
	v_mul_f32_e32 v128, 0x3f317217, v56
	v_mul_f32_e32 v131, v69, v83
	v_fmac_f32_e32 v111, v119, v111
	v_fmac_f32_e32 v113, v121, v113
	v_fmac_f32_e32 v114, v122, v114
	v_fma_f32 v119, v55, s61, -v127
	v_fma_f32 v121, v57, s61, -v129
	v_fma_f32 v122, -v62, v130, v63
	v_div_scale_f32 v71, s[14:15], 1.0, v45, 1.0
	v_fma_f32 v124, -v78, v92, 1.0
	v_fma_f32 v118, -v94, v110, 1.0
	v_mul_f32_e32 v126, 0x3f317217, v54
	v_fmac_f32_e32 v112, v120, v112
	v_fmac_f32_e32 v115, v123, v115
	v_fma_f32 v120, v56, s61, -v128
	v_fma_f32 v123, -v68, v131, v69
	v_fmac_f32_e32 v119, 0x3377d1cf, v55
	v_fmac_f32_e32 v121, 0x3377d1cf, v57
	v_fmac_f32_e32 v130, v122, v82
	v_div_scale_f32 v73, s[10:11], 1.0, v44, 1.0
	v_cndmask_b32_e64 v59, 0, v52, s[36:37]
	v_cndmask_b32_e64 v61, 0, v52, s[42:43]
	v_fma_f32 v125, -v80, v93, 1.0
	v_fmac_f32_e32 v92, v124, v92
	v_fma_f32 v124, -v106, v116, 1.0
	v_mul_f32_e32 v132, v71, v84
	v_mul_f32_e32 v134, 0x3f317217, v64
	v_mul_f32_e32 v135, 0x3f317217, v65
	v_mul_f32_e32 v136, 0x3f317217, v66
	v_mul_f32_e32 v137, 0x3f317217, v67
	v_fmac_f32_e32 v110, v118, v110
	v_fma_f32 v118, v54, s61, -v126
	v_fmac_f32_e32 v120, 0x3377d1cf, v56
	v_fmac_f32_e32 v131, v123, v83
	v_fmac_f32_e32 v119, 0x3f317217, v55
	v_cmp_lt_f32_e64 s[36:37], |v55|, s62
	v_fmac_f32_e32 v121, 0x3f317217, v57
	v_cmp_lt_f32_e64 s[42:43], |v57|, s62
	v_fma_f32 v62, -v62, v130, v63
	v_div_scale_f32 v75, s[12:13], 1.0, v41, 1.0
	v_cndmask_b32_e64 v60, 0, v52, s[40:41]
	v_cndmask_b32_e64 v58, 0, v52, s[44:45]
	v_fmac_f32_e32 v93, v125, v93
	v_fma_f32 v125, -v108, v117, 1.0
	v_mul_f32_e32 v133, v73, v85
	v_fmac_f32_e32 v116, v124, v116
	v_fma_f32 v124, -v70, v132, v71
	v_fma_f32 v126, v64, s61, -v134
	v_fma_f32 v127, v65, s61, -v135
	v_fma_f32 v128, v66, s61, -v136
	v_fma_f32 v129, v67, s61, -v137
	v_fmac_f32_e32 v118, 0x3377d1cf, v54
	v_fmac_f32_e32 v120, 0x3f317217, v56
	v_cmp_lt_f32_e64 s[40:41], |v56|, s62
	v_fma_f32 v63, -v68, v131, v69
	v_cndmask_b32_e64 v55, v55, v119, s[36:37]
	v_cndmask_b32_e64 v57, v57, v121, s[42:43]
	v_div_fmas_f32 v62, v62, v82, v130
	s_mov_b64 vcc, s[30:31]
	v_div_scale_f32 v77, s[8:9], 1.0, v40, 1.0
	v_cndmask_b32_e64 v89, 0, v52, s[52:53]
	v_mul_f32_e32 v138, v75, v90
	v_fmac_f32_e32 v117, v125, v117
	v_fma_f32 v125, -v72, v133, v73
	v_fmac_f32_e32 v132, v124, v84
	v_fmac_f32_e32 v126, 0x3377d1cf, v64
	v_fmac_f32_e32 v127, 0x3377d1cf, v65
	v_fmac_f32_e32 v128, 0x3377d1cf, v66
	v_fmac_f32_e32 v129, 0x3377d1cf, v67
	v_fmac_f32_e32 v118, 0x3f317217, v54
	v_cmp_lt_f32_e64 s[52:53], |v54|, s62
	v_cndmask_b32_e64 v56, v56, v120, s[40:41]
	v_sub_f32_e32 v55, v55, v60
	v_sub_f32_e32 v58, v57, v58
	v_div_fixup_f32 v57, v62, v49, 1.0
	v_div_fmas_f32 v49, v63, v83, v131
	v_cmp_lt_f32_e32 vcc, s63, v15
	v_div_scale_f32 v79, s[6:7], 1.0, v37, 1.0
	v_cndmask_b32_e64 v86, 0, v52, s[46:47]
	v_cndmask_b32_e64 v87, 0, v52, s[48:49]
	v_cndmask_b32_e64 v88, 0, v52, s[50:51]
	v_mul_f32_e32 v139, v77, v91
	v_fma_f32 v134, -v74, v138, v75
	v_fmac_f32_e32 v133, v125, v85
	v_fma_f32 v68, -v70, v132, v71
	v_fmac_f32_e32 v126, 0x3f317217, v64
	v_cmp_lt_f32_e64 s[44:45], |v64|, s62
	v_fmac_f32_e32 v127, 0x3f317217, v65
	v_cmp_lt_f32_e64 s[46:47], |v65|, s62
	v_fmac_f32_e32 v128, 0x3f317217, v66
	v_cmp_lt_f32_e64 s[48:49], |v66|, s62
	v_fmac_f32_e32 v129, 0x3f317217, v67
	v_cmp_lt_f32_e64 s[50:51], |v67|, s62
	v_cndmask_b32_e64 v54, v54, v118, s[52:53]
	v_sub_f32_e32 v56, v56, v61
	v_cmp_lt_f32_e64 s[36:37], s63, v26
	v_cmp_lt_f32_e64 s[40:41], s63, v27
	v_cndmask_b32_e32 v15, v55, v15, vcc
	s_mov_b64 vcc, s[14:15]
	v_div_scale_f32 v81, s[4:5], 1.0, v36, 1.0
	v_mul_f32_e32 v140, v79, v92
	v_fma_f32 v135, -v76, v139, v77
	v_fmac_f32_e32 v138, v134, v90
	v_fma_f32 v69, -v72, v133, v73
	v_cndmask_b32_e64 v64, v64, v126, s[44:45]
	v_cndmask_b32_e64 v65, v65, v127, s[46:47]
	v_cndmask_b32_e64 v66, v66, v128, s[48:49]
	v_cndmask_b32_e64 v67, v67, v129, s[50:51]
	v_sub_f32_e32 v54, v54, v59
	v_cmp_lt_f32_e64 s[42:43], s63, v14
	v_cndmask_b32_e64 v27, v58, v27, s[40:41]
	v_cndmask_b32_e64 v26, v56, v26, s[36:37]
	v_div_fixup_f32 v56, v49, v48, 1.0
	v_div_fmas_f32 v48, v68, v84, v132
	s_mov_b64 vcc, s[10:11]
	v_mul_f32_e32 v141, v81, v93
	v_fma_f32 v136, -v78, v140, v79
	v_fmac_f32_e32 v139, v135, v91
	v_fma_f32 v70, -v74, v138, v75
	v_sub_f32_e32 v59, v64, v86
	v_sub_f32_e32 v60, v65, v87
	v_sub_f32_e32 v61, v66, v88
	v_sub_f32_e32 v62, v67, v89
	v_cmp_lt_f32_e64 s[30:31], s63, v32
	v_cmp_lt_f32_e64 s[44:45], s63, v33
	v_cmp_lt_f32_e64 s[46:47], s63, v30
	v_cmp_lt_f32_e64 s[48:49], s63, v31
	v_cndmask_b32_e64 v14, v54, v14, s[42:43]
	v_pk_mul_f32 v[10:11], v[26:27], v[10:11]
	v_div_fmas_f32 v26, v69, v85, v133
	s_mov_b64 vcc, s[12:13]
	v_div_scale_f32 v95, s[34:35], 1.0, v47, 1.0
	v_fma_f32 v137, -v80, v141, v81
	v_fmac_f32_e32 v140, v136, v92
	v_fma_f32 v71, -v76, v139, v77
	v_cndmask_b32_e64 v31, v60, v31, s[48:49]
	v_cndmask_b32_e64 v30, v59, v30, s[46:47]
	v_cndmask_b32_e64 v33, v62, v33, s[44:45]
	v_cndmask_b32_e64 v32, v61, v32, s[30:31]
	v_pk_mul_f32 v[8:9], v[14:15], v[8:9]
	v_div_fixup_f32 v54, v26, v44, 1.0
	v_div_fmas_f32 v26, v70, v90, v138
	s_mov_b64 vcc, s[8:9]
	v_mul_f32_e32 v142, v95, v110
	v_fmac_f32_e32 v141, v137, v93
	v_fma_f32 v72, -v78, v140, v79
	v_pk_mul_f32 v[14:15], v[32:33], v[28:29]
	v_pk_mul_f32 v[12:13], v[30:31], v[12:13]
	flat_store_dwordx4 v[24:25], v[8:11]
	flat_store_dwordx4 v[24:25], v[12:15] offset:16
	v_fma_f32 v122, -v94, v142, v95
	v_div_fmas_f32 v8, v71, v91, v139
	s_mov_b64 vcc, s[6:7]
	v_fma_f32 v73, -v80, v141, v81
	v_div_fixup_f32 v10, v8, v40, 1.0
	v_div_fmas_f32 v8, v72, v92, v140
	s_mov_b64 vcc, s[4:5]
	v_fmac_f32_e32 v142, v122, v110
	v_div_fixup_f32 v9, v8, v37, 1.0
	v_div_fmas_f32 v8, v73, v93, v141
	v_fma_f32 v74, -v94, v142, v95
	v_div_fixup_f32 v55, v48, v45, 1.0
	v_div_fixup_f32 v11, v26, v41, 1.0
	v_div_fixup_f32 v8, v8, v36, 1.0
	s_mov_b64 vcc, s[34:35]
	flat_store_dwordx4 v[22:23], v[54:57]
	v_div_fmas_f32 v12, v74, v110, v142
	flat_store_dwordx4 v[22:23], v[8:11] offset:16
	v_div_scale_f32 v97, s[28:29], 1.0, v46, 1.0
	s_nop 0
	v_div_fixup_f32 v11, v12, v47, 1.0
	global_load_dwordx4 v[12:15], v51, s[56:57]
	global_load_dwordx4 v[22:25], v51, s[58:59]
	global_load_dwordx4 v[26:29], v51, s[56:57] offset:16
	global_load_dwordx4 v[30:33], v51, s[58:59] offset:16
	v_div_scale_f32 v99, s[26:27], 1.0, v43, 1.0
	v_mul_f32_e32 v143, v97, v111
	v_div_scale_f32 v101, s[24:25], 1.0, v42, 1.0
	v_mul_f32_e32 v144, v99, v112
	v_fma_f32 v123, -v96, v143, v97
	v_div_scale_f32 v103, s[22:23], 1.0, v39, 1.0
	v_mul_f32_e32 v145, v101, v113
	v_fma_f32 v124, -v98, v144, v99
	v_fmac_f32_e32 v143, v123, v111
	v_div_scale_f32 v105, s[20:21], 1.0, v38, 1.0
	v_mul_f32_e32 v146, v103, v114
	v_fma_f32 v125, -v100, v145, v101
	v_fmac_f32_e32 v144, v124, v112
	v_fma_f32 v75, -v96, v143, v97
	s_mov_b64 vcc, s[28:29]
	v_div_scale_f32 v107, s[18:19], 1.0, v35, 1.0
	v_mul_f32_e32 v147, v105, v115
	v_fma_f32 v134, -v102, v146, v103
	v_fmac_f32_e32 v145, v125, v113
	v_fma_f32 v76, -v98, v144, v99
	v_div_fmas_f32 v8, v75, v111, v143
	s_mov_b64 vcc, s[26:27]
	v_div_scale_f32 v109, s[16:17], 1.0, v34, 1.0
	v_mul_f32_e32 v148, v107, v116
	v_fma_f32 v135, -v104, v147, v105
	v_fmac_f32_e32 v146, v134, v114
	v_fma_f32 v77, -v100, v145, v101
	v_div_fixup_f32 v10, v8, v46, 1.0
	v_div_fmas_f32 v8, v76, v112, v144
	s_mov_b64 vcc, s[24:25]
	v_mul_f32_e32 v149, v109, v117
	v_fma_f32 v136, -v106, v148, v107
	v_fmac_f32_e32 v147, v135, v115
	v_fma_f32 v78, -v102, v146, v103
	v_div_fixup_f32 v9, v8, v43, 1.0
	v_div_fmas_f32 v8, v77, v113, v145
	s_mov_b64 vcc, s[22:23]
	v_fma_f32 v137, -v108, v149, v109
	v_fmac_f32_e32 v148, v136, v116
	v_fma_f32 v79, -v104, v147, v105
	v_div_fmas_f32 v36, v78, v114, v146
	s_mov_b64 vcc, s[20:21]
	v_fmac_f32_e32 v149, v137, v117
	v_fma_f32 v80, -v106, v148, v107
	v_div_fixup_f32 v8, v8, v42, 1.0
	v_div_fixup_f32 v37, v36, v39, 1.0
	v_div_fmas_f32 v36, v79, v115, v147
	s_mov_b64 vcc, s[18:19]
	v_fma_f32 v81, -v108, v149, v109
	flat_store_dwordx4 v[20:21], v[8:11]
	v_div_fixup_f32 v36, v36, v38, 1.0
	s_waitcnt vmcnt(0)
	v_pk_add_f32 v[6:7], v[22:23], v[6:7]
	v_div_fmas_f32 v8, v80, v116, v148
	s_mov_b64 vcc, s[16:17]
	v_div_fixup_f32 v35, v8, v35, 1.0
	v_div_fmas_f32 v8, v81, v117, v149
	v_div_fixup_f32 v34, v8, v34, 1.0
	v_mul_f32_e32 v8, 0x3fb8aa3b, v12
	v_mul_f32_e32 v9, 0x3fb8aa3b, v13
	v_pk_add_f32 v[4:5], v[24:25], v[4:5]
	flat_store_dwordx4 v[20:21], v[34:37] offset:16
	v_mul_f32_e32 v10, 0x3fb8aa3b, v14
	v_mul_f32_e32 v11, 0x3fb8aa3b, v15
	v_mul_f32_e32 v12, 0x3fb8aa3b, v26
	v_mul_f32_e32 v13, 0x3fb8aa3b, v27
	v_pk_add_f32 v[2:3], v[30:31], v[2:3]
	v_pk_add_f32 v[0:1], v[32:33], v[0:1]
	v_exp_f32_e32 v20, v8
	v_exp_f32_e32 v21, v9
	v_mul_f32_e32 v8, 0x3fb8aa3b, v6
	v_mul_f32_e32 v9, 0x3fb8aa3b, v7
	v_mul_f32_e32 v22, 0x3fb8aa3b, v4
	v_mul_f32_e32 v23, 0x3fb8aa3b, v5
	v_mul_f32_e32 v14, 0x3fb8aa3b, v28
	v_mul_f32_e32 v15, 0x3fb8aa3b, v29
	v_exp_f32_e32 v10, v10
	v_exp_f32_e32 v11, v11
	v_exp_f32_e32 v24, v12
	v_exp_f32_e32 v25, v13
	v_mul_f32_e32 v12, 0x3fb8aa3b, v2
	v_mul_f32_e32 v13, 0x3fb8aa3b, v3
	v_mul_f32_e32 v26, 0x3fb8aa3b, v0
	v_mul_f32_e32 v27, 0x3fb8aa3b, v1
	v_exp_f32_e32 v28, v8
	v_exp_f32_e32 v29, v9
	v_exp_f32_e32 v22, v22
	v_exp_f32_e32 v23, v23
	v_exp_f32_e32 v14, v14
	v_exp_f32_e32 v15, v15
	v_exp_f32_e32 v30, v12
	v_exp_f32_e32 v31, v13
	v_exp_f32_e32 v26, v26
	v_exp_f32_e32 v27, v27
	v_xor_b32_e32 v9, 0x80000000, v11
	v_xor_b32_e32 v8, 0x80000000, v10
	v_xor_b32_e32 v11, 0x80000000, v21
	v_xor_b32_e32 v10, 0x80000000, v20
	v_add_f32_e32 v20, 1.0, v28
	v_add_f32_e32 v21, 1.0, v29
	v_add_f32_e32 v22, 1.0, v22
	v_add_f32_e32 v23, 1.0, v23
	v_xor_b32_e32 v13, 0x80000000, v15
	v_xor_b32_e32 v12, 0x80000000, v14
	v_xor_b32_e32 v15, 0x80000000, v25
	v_xor_b32_e32 v14, 0x80000000, v24
	v_add_f32_e32 v24, 1.0, v30
	v_add_f32_e32 v25, 1.0, v31
	v_add_f32_e32 v26, 1.0, v26
	v_add_f32_e32 v27, 1.0, v27
	v_cmp_gt_f32_e32 vcc, s60, v20
	v_cmp_gt_f32_e64 s[4:5], s60, v21
	v_cmp_gt_f32_e64 s[6:7], s60, v22
	v_cmp_gt_f32_e64 s[8:9], s60, v23
	v_cndmask_b32_e64 v28, 0, 32, vcc
	v_cndmask_b32_e64 v29, 0, 32, s[4:5]
	v_cndmask_b32_e64 v30, 0, 32, s[6:7]
	v_cndmask_b32_e64 v31, 0, 32, s[8:9]
	v_cmp_gt_f32_e64 s[10:11], s60, v24
	v_cmp_gt_f32_e64 s[12:13], s60, v25
	v_cmp_gt_f32_e64 s[14:15], s60, v26
	v_cmp_gt_f32_e64 s[16:17], s60, v27
	v_cndmask_b32_e64 v32, 0, 32, s[10:11]
	v_cndmask_b32_e64 v33, 0, 32, s[12:13]
	v_cndmask_b32_e64 v34, 0, 32, s[14:15]
	v_cndmask_b32_e64 v35, 0, 32, s[16:17]
	v_ldexp_f32 v20, v20, v28
	v_ldexp_f32 v21, v21, v29
	v_ldexp_f32 v22, v22, v30
	v_ldexp_f32 v23, v23, v31
	v_ldexp_f32 v24, v24, v32
	v_ldexp_f32 v25, v25, v33
	v_ldexp_f32 v26, v26, v34
	v_ldexp_f32 v27, v27, v35
	v_log_f32_e32 v20, v20
	v_log_f32_e32 v21, v21
	v_log_f32_e32 v22, v22
	v_log_f32_e32 v23, v23
	v_log_f32_e32 v24, v24
	v_log_f32_e32 v25, v25
	v_log_f32_e32 v26, v26
	v_log_f32_e32 v27, v27
	v_mul_f32_e32 v36, 0x3f317217, v20
	v_mul_f32_e32 v37, 0x3f317217, v21
	v_mul_f32_e32 v38, 0x3f317217, v22
	v_mul_f32_e32 v39, 0x3f317217, v23
	v_mul_f32_e32 v40, 0x3f317217, v24
	v_mul_f32_e32 v41, 0x3f317217, v25
	v_mul_f32_e32 v42, 0x3f317217, v26
	v_mul_f32_e32 v43, 0x3f317217, v27
	v_fma_f32 v36, v20, s61, -v36
	v_fma_f32 v37, v21, s61, -v37
	v_fma_f32 v38, v22, s61, -v38
	v_fma_f32 v39, v23, s61, -v39
	v_fma_f32 v40, v24, s61, -v40
	v_fma_f32 v41, v25, s61, -v41
	v_fma_f32 v42, v26, s61, -v42
	v_fma_f32 v43, v27, s61, -v43
	v_fmac_f32_e32 v36, 0x3377d1cf, v20
	v_fmac_f32_e32 v37, 0x3377d1cf, v21
	v_fmac_f32_e32 v38, 0x3377d1cf, v22
	v_fmac_f32_e32 v39, 0x3377d1cf, v23
	v_cndmask_b32_e32 v28, 0, v52, vcc
	v_cndmask_b32_e64 v29, 0, v52, s[4:5]
	v_cndmask_b32_e64 v30, 0, v52, s[6:7]
	v_cndmask_b32_e64 v35, 0, v52, s[16:17]
	v_fmac_f32_e32 v40, 0x3377d1cf, v24
	v_fmac_f32_e32 v41, 0x3377d1cf, v25
	v_fmac_f32_e32 v42, 0x3377d1cf, v26
	v_fmac_f32_e32 v43, 0x3377d1cf, v27
	v_fmac_f32_e32 v36, 0x3f317217, v20
	v_fmac_f32_e32 v37, 0x3f317217, v21
	v_cmp_lt_f32_e64 vcc, |v21|, s62
	v_fmac_f32_e32 v38, 0x3f317217, v22
	v_cmp_lt_f32_e64 s[4:5], |v22|, s62
	v_fmac_f32_e32 v39, 0x3f317217, v23
	v_cmp_lt_f32_e64 s[6:7], |v23|, s62
	v_cmp_lt_f32_e64 s[16:17], |v20|, s62
	v_cndmask_b32_e64 v31, 0, v52, s[8:9]
	v_cndmask_b32_e64 v32, 0, v52, s[10:11]
	v_cndmask_b32_e64 v33, 0, v52, s[12:13]
	v_cndmask_b32_e64 v34, 0, v52, s[14:15]
	v_fmac_f32_e32 v40, 0x3f317217, v24
	v_cmp_lt_f32_e64 s[8:9], |v24|, s62
	v_fmac_f32_e32 v41, 0x3f317217, v25
	v_cmp_lt_f32_e64 s[10:11], |v25|, s62
	v_fmac_f32_e32 v42, 0x3f317217, v26
	v_cmp_lt_f32_e64 s[12:13], |v26|, s62
	v_fmac_f32_e32 v43, 0x3f317217, v27
	v_cmp_lt_f32_e64 s[14:15], |v27|, s62
	v_cndmask_b32_e64 v20, v20, v36, s[16:17]
	v_cndmask_b32_e32 v21, v21, v37, vcc
	v_cndmask_b32_e64 v22, v22, v38, s[4:5]
	v_cndmask_b32_e64 v23, v23, v39, s[6:7]
	v_cndmask_b32_e64 v24, v24, v40, s[8:9]
	v_cndmask_b32_e64 v25, v25, v41, s[10:11]
	v_cndmask_b32_e64 v26, v26, v42, s[12:13]
	v_cndmask_b32_e64 v27, v27, v43, s[14:15]
	v_sub_f32_e32 v20, v20, v28
	v_sub_f32_e32 v21, v21, v29
	v_sub_f32_e32 v22, v22, v30
	v_sub_f32_e32 v23, v23, v31
	v_cmp_lt_f32_e32 vcc, s63, v6
	v_cmp_lt_f32_e64 s[4:5], s63, v7
	v_cmp_lt_f32_e64 s[6:7], s63, v4
	v_cmp_lt_f32_e64 s[16:17], s63, v5
	v_sub_f32_e32 v24, v24, v32
	v_sub_f32_e32 v25, v25, v33
	v_sub_f32_e32 v26, v26, v34
	v_sub_f32_e32 v27, v27, v35
	v_cmp_lt_f32_e64 s[8:9], s63, v2
	v_cmp_lt_f32_e64 s[10:11], s63, v3
	v_cmp_lt_f32_e64 s[12:13], s63, v0
	v_cmp_lt_f32_e64 s[14:15], s63, v1
	v_cndmask_b32_e64 v5, v23, v5, s[16:17]
	v_cndmask_b32_e64 v4, v22, v4, s[6:7]
	v_cndmask_b32_e64 v7, v21, v7, s[4:5]
	v_cndmask_b32_e32 v6, v20, v6, vcc
	v_cndmask_b32_e64 v21, v27, v1, s[14:15]
	v_cndmask_b32_e64 v20, v26, v0, s[12:13]
	v_cndmask_b32_e64 v23, v25, v3, s[10:11]
	v_cndmask_b32_e64 v22, v24, v2, s[8:9]
	v_pk_mul_f32 v[0:1], v[6:7], v[10:11]
	v_pk_mul_f32 v[2:3], v[4:5], v[8:9]
	v_pk_mul_f32 v[4:5], v[22:23], v[14:15]
	v_pk_mul_f32 v[6:7], v[20:21], v[12:13]
	flat_store_dwordx4 v[18:19], v[0:3]
	flat_store_dwordx4 v[18:19], v[4:7] offset:16
	s_cbranch_scc0 .LBB0_858

.LBB0_861:
	v_mad_i64_i32 v[0:1], s[4:5], v16, s10, v[18:19]
	global_load_dwordx4 v[8:11], v22, s[12:13]
	v_add_co_u32_e32 v0, vcc, 0x1000, v0
	v_ashrrev_i32_e32 v17, 31, v16
	s_nop 0
	v_addc_co_u32_e32 v1, vcc, 0, v1, vcc
	global_load_dwordx4 v[12:15], v[0:1], off offset:64
	global_load_dwordx4 v[24:27], v[0:1], off offset:80
	global_load_dwordx4 v[28:31], v22, s[14:15]
	s_nop 0
	global_load_dwordx4 v[0:3], v22, s[12:13] offset:16
	global_load_dwordx4 v[4:7], v22, s[14:15] offset:16
	s_add_i32 s3, s3, s76
	s_cmp_lt_i32 s3, 24
	s_waitcnt vmcnt(0)
	v_mul_f32_e32 v8, 0x3fb8aa3b, v8
	v_mul_f32_e32 v9, 0x3fb8aa3b, v9
	v_exp_f32_e32 v34, v8
	v_exp_f32_e32 v35, v9
	s_waitcnt lgkmcnt(0)
	v_lshlrev_b32_e32 v8, 16, v12
	v_and_b32_e32 v9, 0xffff0000, v12
	v_mul_f32_e32 v10, 0x3fb8aa3b, v10
	v_mul_f32_e32 v11, 0x3fb8aa3b, v11
	v_pk_add_f32 v[8:9], v[28:29], v[8:9]
	v_exp_f32_e32 v36, v10
	v_exp_f32_e32 v37, v11
	v_lshlrev_b32_e32 v10, 16, v13
	v_and_b32_e32 v11, 0xffff0000, v13
	v_lshlrev_b32_e32 v12, 16, v24
	v_and_b32_e32 v13, 0xffff0000, v24
	v_mul_f32_e32 v24, 0x3fb8aa3b, v8
	v_lshlrev_b32_e32 v32, 16, v14
	v_and_b32_e32 v33, 0xffff0000, v14
	v_lshlrev_b32_e32 v20, 16, v15
	v_and_b32_e32 v21, 0xffff0000, v15
	v_lshlrev_b32_e32 v14, 16, v25
	v_and_b32_e32 v15, 0xffff0000, v25
	v_pk_add_f32 v[10:11], v[30:31], v[10:11]
	v_mul_f32_e32 v25, 0x3fb8aa3b, v9
	v_exp_f32_e32 v24, v24
	v_lshlrev_b32_e32 v38, 16, v26
	v_and_b32_e32 v39, 0xffff0000, v26
	v_mul_f32_e32 v26, 0x3fb8aa3b, v10
	v_exp_f32_e32 v25, v25
	v_lshlrev_b32_e32 v40, 16, v27
	v_and_b32_e32 v41, 0xffff0000, v27
	v_mul_f32_e32 v27, 0x3fb8aa3b, v11
	v_exp_f32_e32 v26, v26
	v_exp_f32_e32 v27, v27
	v_add_f32_e32 v24, 1.0, v24
	v_add_f32_e32 v25, 1.0, v25
	v_cmp_gt_f32_e32 vcc, s11, v24
	v_add_f32_e32 v26, 1.0, v26
	v_cmp_gt_f32_e64 s[4:5], s11, v25
	v_cndmask_b32_e64 v28, 0, 32, vcc
	v_add_f32_e32 v27, 1.0, v27
	v_cndmask_b32_e64 v29, 0, 32, s[4:5]
	v_cmp_gt_f32_e64 s[6:7], s11, v26
	v_ldexp_f32 v24, v24, v28
	v_cmp_gt_f32_e64 s[8:9], s11, v27
	v_cndmask_b32_e64 v30, 0, 32, s[6:7]
	v_ldexp_f32 v25, v25, v29
	v_log_f32_e32 v24, v24
	v_cndmask_b32_e64 v31, 0, 32, s[8:9]
	v_ldexp_f32 v26, v26, v30
	v_log_f32_e32 v25, v25
	v_ldexp_f32 v27, v27, v31
	v_log_f32_e32 v26, v26
	v_log_f32_e32 v27, v27
	v_mul_f32_e32 v31, 0x3f317217, v24
	v_mul_f32_e32 v42, 0x3f317217, v25
	v_fma_f32 v31, v24, s16, -v31
	v_mul_f32_e32 v14, 0xbfb8aa3b, v14
	v_mul_f32_e32 v43, 0x3f317217, v26
	v_fma_f32 v42, v25, s16, -v42
	v_fmac_f32_e32 v31, 0x3377d1cf, v24
	v_mul_f32_e32 v15, 0xbfb8aa3b, v15
	v_exp_f32_e32 v14, v14
	v_cndmask_b32_e32 v28, 0, v23, vcc
	v_mul_f32_e32 v44, 0x3f317217, v27
	v_fma_f32 v43, v26, s16, -v43
	v_fmac_f32_e32 v42, 0x3377d1cf, v25
	v_fmac_f32_e32 v31, 0x3f317217, v24
	v_cmp_lt_f32_e64 vcc, |v24|, s17
	v_exp_f32_e32 v15, v15
	v_fma_f32 v44, v27, s16, -v44
	v_fmac_f32_e32 v43, 0x3377d1cf, v26
	v_fmac_f32_e32 v42, 0x3f317217, v25
	v_cndmask_b32_e32 v24, v24, v31, vcc
	v_cmp_lt_f32_e64 vcc, |v25|, s17
	v_fmac_f32_e32 v44, 0x3377d1cf, v27
	v_fmac_f32_e32 v43, 0x3f317217, v26
	v_cndmask_b32_e32 v25, v25, v42, vcc
	v_cmp_lt_f32_e64 vcc, |v26|, s17
	v_fmac_f32_e32 v44, 0x3f317217, v27
	v_sub_f32_e32 v24, v24, v28
	v_cndmask_b32_e32 v26, v26, v43, vcc
	v_cmp_lt_f32_e64 vcc, |v27|, s17
	v_cndmask_b32_e64 v28, 0, v23, s[8:9]
	v_pk_add_f32 v[14:15], v[14:15], 1.0 op_sel_hi:[1,0]
	v_cndmask_b32_e32 v27, v27, v44, vcc
	v_cndmask_b32_e64 v29, 0, v23, s[4:5]
	v_sub_f32_e32 v27, v27, v28
	v_div_scale_f32 v28, s[4:5], v15, v15, 1.0
	v_sub_f32_e32 v25, v25, v29
	v_rcp_f32_e32 v29, v28
	v_cmp_lt_f32_e32 vcc, s18, v9
	v_cndmask_b32_e64 v30, 0, v23, s[6:7]
	v_sub_f32_e32 v26, v26, v30
	v_cndmask_b32_e32 v9, v25, v9, vcc
	v_cmp_lt_f32_e32 vcc, s18, v8
	v_xor_b32_e32 v25, 0x80000000, v35
	v_mul_f32_e32 v12, 0xbfb8aa3b, v12
	v_cndmask_b32_e32 v8, v24, v8, vcc
	v_cmp_lt_f32_e32 vcc, s18, v11
	v_xor_b32_e32 v24, 0x80000000, v34
	v_pk_mul_f32 v[8:9], v[8:9], v[24:25]
	v_cndmask_b32_e32 v11, v27, v11, vcc
	v_cmp_lt_f32_e32 vcc, s18, v10
	v_fma_f32 v24, -v28, v29, 1.0
	v_fmac_f32_e32 v29, v24, v29
	v_cndmask_b32_e32 v10, v26, v10, vcc
	v_div_scale_f32 v24, vcc, 1.0, v15, 1.0
	v_xor_b32_e32 v27, 0x80000000, v37
	v_xor_b32_e32 v26, 0x80000000, v36
	v_mul_f32_e32 v25, v24, v29
	v_pk_mul_f32 v[10:11], v[10:11], v[26:27]
	v_fma_f32 v26, -v28, v25, v24
	v_fmac_f32_e32 v25, v26, v29
	v_div_scale_f32 v26, s[4:5], v14, v14, 1.0
	v_rcp_f32_e32 v27, v26
	v_fma_f32 v24, -v28, v25, v24
	v_mul_f32_e32 v13, 0xbfb8aa3b, v13
	v_div_fmas_f32 v24, v24, v29, v25
	v_exp_f32_e32 v12, v12
	v_exp_f32_e32 v13, v13
	v_div_fixup_f32 v15, v24, v15, 1.0
	v_fma_f32 v24, -v26, v27, 1.0
	v_fmac_f32_e32 v27, v24, v27
	v_div_scale_f32 v24, vcc, 1.0, v14, 1.0
	v_mul_f32_e32 v25, v24, v27
	v_fma_f32 v28, -v26, v25, v24
	v_pk_add_f32 v[12:13], v[12:13], 1.0 op_sel_hi:[1,0]
	v_fmac_f32_e32 v25, v28, v27
	v_fma_f32 v24, -v26, v25, v24
	v_div_scale_f32 v26, s[4:5], v13, v13, 1.0
	v_rcp_f32_e32 v28, v26
	v_div_fmas_f32 v24, v24, v27, v25
	v_div_fixup_f32 v14, v24, v14, 1.0
	v_pk_add_f32 v[4:5], v[4:5], v[32:33]
	v_fma_f32 v24, -v26, v28, 1.0
	v_fmac_f32_e32 v28, v24, v28
	v_div_scale_f32 v24, vcc, 1.0, v13, 1.0
	v_mul_f32_e32 v25, v24, v28
	v_fma_f32 v27, -v26, v25, v24
	v_fmac_f32_e32 v25, v27, v28
	v_fma_f32 v24, -v26, v25, v24
	v_div_scale_f32 v26, s[4:5], v12, v12, 1.0
	v_rcp_f32_e32 v27, v26
	v_div_fmas_f32 v24, v24, v28, v25
	v_div_fixup_f32 v13, v24, v13, 1.0
	v_mul_f32_e32 v0, 0x3fb8aa3b, v0
	v_fma_f32 v24, -v26, v27, 1.0
	v_fmac_f32_e32 v27, v24, v27
	v_div_scale_f32 v24, vcc, 1.0, v12, 1.0
	v_mul_f32_e32 v25, v24, v27
	v_fma_f32 v28, -v26, v25, v24
	v_fmac_f32_e32 v25, v28, v27
	v_fma_f32 v24, -v26, v25, v24
	v_div_fmas_f32 v24, v24, v27, v25
	v_div_fixup_f32 v12, v24, v12, 1.0
	v_mul_f32_e32 v24, 0x3fb8aa3b, v4
	v_exp_f32_e32 v24, v24
	v_exp_f32_e32 v26, v0
	v_mul_f32_e32 v0, 0xbfb8aa3b, v38
	v_mul_f32_e32 v3, 0x3fb8aa3b, v3
	v_add_f32_e32 v24, 1.0, v24
	v_cmp_gt_f32_e32 vcc, s11, v24
	v_mul_f32_e32 v2, 0x3fb8aa3b, v2
	s_nop 0
	v_cndmask_b32_e64 v25, 0, 32, vcc
	v_ldexp_f32 v24, v24, v25
	v_log_f32_e32 v25, v24
	v_exp_f32_e32 v24, v0
	v_mul_f32_e32 v0, 0x3fb8aa3b, v1
	v_mul_f32_e32 v1, 0x3fb8aa3b, v5
	v_exp_f32_e32 v1, v1
	v_exp_f32_e32 v27, v0
	v_mul_f32_e32 v0, 0x3f317217, v25
	v_fma_f32 v0, v25, s16, -v0
	v_add_f32_e32 v1, 1.0, v1
	v_cmp_gt_f32_e64 s[4:5], s11, v1
	v_fmac_f32_e32 v0, 0x3377d1cf, v25
	v_fmac_f32_e32 v0, 0x3f317217, v25
	v_cndmask_b32_e64 v28, 0, 32, s[4:5]
	v_ldexp_f32 v1, v1, v28
	v_log_f32_e32 v1, v1
	v_cmp_lt_f32_e64 s[6:7], |v25|, s17
	s_nop 1
	v_cndmask_b32_e64 v0, v25, v0, s[6:7]
	v_cndmask_b32_e32 v25, 0, v23, vcc
	v_sub_f32_e32 v28, v0, v25
	v_mul_f32_e32 v0, 0x3f317217, v1
	v_fma_f32 v0, v1, s16, -v0
	v_fmac_f32_e32 v0, 0x3377d1cf, v1
	v_fmac_f32_e32 v0, 0x3f317217, v1
	v_cmp_lt_f32_e64 vcc, |v1|, s17
	s_nop 1
	v_cndmask_b32_e32 v0, v1, v0, vcc
	v_cndmask_b32_e64 v1, 0, v23, s[4:5]
	v_sub_f32_e32 v29, v0, v1
	v_mul_f32_e32 v0, 0xbfb8aa3b, v39
	v_exp_f32_e32 v25, v0
	v_pk_add_f32 v[0:1], v[6:7], v[20:21]
	v_exp_f32_e32 v21, v3
	v_mul_f32_e32 v6, 0x3fb8aa3b, v0
	v_exp_f32_e32 v6, v6
	v_exp_f32_e32 v20, v2
	v_mul_f32_e32 v2, 0xbfb8aa3b, v40
	v_exp_f32_e32 v2, v2
	v_add_f32_e32 v6, 1.0, v6
	v_cmp_gt_f32_e32 vcc, s11, v6
	v_xor_b32_e32 v21, 0x80000000, v21
	v_xor_b32_e32 v20, 0x80000000, v20
	v_cndmask_b32_e64 v7, 0, 32, vcc
	v_ldexp_f32 v6, v6, v7
	v_mul_f32_e32 v7, 0x3fb8aa3b, v1
	v_exp_f32_e32 v7, v7
	v_log_f32_e32 v6, v6
	v_add_f32_e32 v7, 1.0, v7
	v_cmp_gt_f32_e64 s[4:5], s11, v7
	v_mul_f32_e32 v3, 0x3f317217, v6
	v_fma_f32 v3, v6, s16, -v3
	v_cndmask_b32_e64 v30, 0, 32, s[4:5]
	v_ldexp_f32 v7, v7, v30
	v_log_f32_e32 v7, v7
	v_fmac_f32_e32 v3, 0x3377d1cf, v6
	v_fmac_f32_e32 v3, 0x3f317217, v6
	v_cmp_lt_f32_e64 s[6:7], |v6|, s17
	s_nop 1
	v_cndmask_b32_e64 v3, v6, v3, s[6:7]
	v_cndmask_b32_e32 v6, 0, v23, vcc
	v_sub_f32_e32 v3, v3, v6
	v_mul_f32_e32 v6, 0x3f317217, v7
	v_fma_f32 v6, v7, s16, -v6
	v_fmac_f32_e32 v6, 0x3377d1cf, v7
	v_fmac_f32_e32 v6, 0x3f317217, v7
	v_cmp_lt_f32_e64 vcc, |v7|, s17
	s_nop 1
	v_cndmask_b32_e32 v6, v7, v6, vcc
	v_cmp_lt_f32_e32 vcc, s18, v5
	v_cndmask_b32_e64 v7, 0, v23, s[4:5]
	v_sub_f32_e32 v6, v6, v7
	v_cndmask_b32_e32 v5, v29, v5, vcc
	v_cmp_lt_f32_e32 vcc, s18, v4
	v_xor_b32_e32 v7, 0x80000000, v27
	s_nop 0
	v_cndmask_b32_e32 v4, v28, v4, vcc
	v_cmp_lt_f32_e32 vcc, s18, v1
	s_nop 1
	v_cndmask_b32_e32 v1, v6, v1, vcc
	v_cmp_lt_f32_e32 vcc, s18, v0
	v_xor_b32_e32 v6, 0x80000000, v26
	s_nop 0
	v_cndmask_b32_e32 v0, v3, v0, vcc
	v_mul_f32_e32 v3, 0xbfb8aa3b, v41
	v_exp_f32_e32 v3, v3
	s_nop 0
	v_pk_add_f32 v[26:27], v[2:3], 1.0 op_sel_hi:[1,0]
	s_nop 0
	v_div_scale_f32 v28, s[4:5], v27, v27, 1.0
	v_rcp_f32_e32 v29, v28
	v_pk_mul_f32 v[2:3], v[0:1], v[20:21]
	v_pk_mul_f32 v[0:1], v[4:5], v[6:7]
	v_pk_add_f32 v[4:5], v[24:25], 1.0 op_sel_hi:[1,0]
	v_fma_f32 v6, -v28, v29, 1.0
	v_fmac_f32_e32 v29, v6, v29
	v_div_scale_f32 v6, vcc, 1.0, v27, 1.0
	v_mul_f32_e32 v7, v6, v29
	v_fma_f32 v20, -v28, v7, v6
	v_fmac_f32_e32 v7, v20, v29
	v_div_scale_f32 v20, s[4:5], v26, v26, 1.0
	v_rcp_f32_e32 v21, v20
	v_fma_f32 v6, -v28, v7, v6
	v_div_fmas_f32 v6, v6, v29, v7
	v_div_fixup_f32 v7, v6, v27, 1.0
	v_fma_f32 v6, -v20, v21, 1.0
	v_fmac_f32_e32 v21, v6, v21
	v_div_scale_f32 v6, vcc, 1.0, v26, 1.0
	v_mul_f32_e32 v24, v6, v21
	v_fma_f32 v25, -v20, v24, v6
	v_fmac_f32_e32 v24, v25, v21
	v_fma_f32 v6, -v20, v24, v6
	v_div_scale_f32 v20, s[4:5], v5, v5, 1.0
	v_rcp_f32_e32 v25, v20
	v_div_fmas_f32 v6, v6, v21, v24
	v_div_fixup_f32 v6, v6, v26, 1.0
	v_fma_f32 v21, -v20, v25, 1.0
	v_fmac_f32_e32 v25, v21, v25
	v_div_scale_f32 v21, vcc, 1.0, v5, 1.0
	v_mul_f32_e32 v24, v21, v25
	v_fma_f32 v26, -v20, v24, v21
	v_fmac_f32_e32 v24, v26, v25
	v_fma_f32 v20, -v20, v24, v21
	v_div_scale_f32 v21, s[4:5], v4, v4, 1.0
	v_rcp_f32_e32 v26, v21
	v_div_fmas_f32 v20, v20, v25, v24
	v_div_fixup_f32 v5, v20, v5, 1.0
	v_fma_f32 v20, -v21, v26, 1.0
	v_fmac_f32_e32 v26, v20, v26
	v_div_scale_f32 v20, vcc, 1.0, v4, 1.0
	v_mul_f32_e32 v24, v20, v26
	v_fma_f32 v25, -v21, v24, v20
	v_fmac_f32_e32 v24, v25, v26
	v_fma_f32 v20, -v21, v24, v20
	v_div_fmas_f32 v20, v20, v26, v24
	v_div_fixup_f32 v4, v20, v4, 1.0
	v_lshlrev_b64 v[20:21], 5, v[16:17]
	v_lshl_add_u64 v[24:25], s[70:71], 0, v[20:21]
	flat_store_dwordx4 v[24:25], v[8:11]
	flat_store_dwordx4 v[24:25], v[0:3] offset:16
	v_add_u32_e32 v16, s2, v16
	s_nop 0
	v_lshl_add_u64 v[0:1], s[72:73], 0, v[20:21]
	flat_store_dwordx4 v[0:1], v[12:15]
	flat_store_dwordx4 v[0:1], v[4:7] offset:16
	s_cbranch_scc1 .LBB0_861

.LBB0_866:
	s_and_saveexec_b64 s[16:17], s[4:5]
	s_cbranch_execz .LBB0_865
	s_cmpk_gt_i32 s75, 0x7f
	s_cselect_b32 s6, s20, 0xe0
	s_cselect_b32 s13, s3, 0x100
	s_waitcnt lgkmcnt(0)
	s_and_b32 s10, s6, s12
	v_add_u32_e32 v0, s12, v52
	v_mad_i64_i32 v[24:25], s[6:7], v0, s21, v[56:57]
	v_add_u32_e32 v9, s10, v52
	s_add_u32 s8, s92, s74
	v_cmp_lt_i32_e32 vcc, 0, v9
	v_cmp_ge_i32_e64 s[6:7], s13, v9
	s_addc_u32 s9, s93, s77
	v_mov_b32_e32 v0, 0
	s_and_b64 s[10:11], vcc, s[6:7]
	v_mov_b32_e32 v4, 0
	v_mov_b32_e32 v5, 0
	v_mov_b32_e32 v6, 0
	v_mov_b32_e32 v7, 0
	s_and_saveexec_b64 s[6:7], s[10:11]
	s_cbranch_execz .LBB0_869
	v_add_co_u32_e32 v2, vcc, 0xfffffa00, v24
	s_nop 1
	v_addc_co_u32_e32 v3, vcc, -1, v25, vcc
	global_load_dwordx4 v[4:7], v[2:3], off
.LBB0_869:
	s_or_b64 exec, exec, s[6:7]
	s_load_dwordx2 s[18:19], s[8:9], 0xc0
	v_cmp_gt_u32_e64 s[6:7], s13, v9
	v_mov_b32_e32 v1, 0
	v_mov_b32_e32 v2, 0
	v_mov_b32_e32 v3, 0
	s_and_saveexec_b64 s[8:9], s[6:7]
	s_cbranch_execz .LBB0_871
	v_add_co_u32_e32 v0, vcc, 0x1000, v24
	s_nop 1
	v_addc_co_u32_e32 v1, vcc, 0, v25, vcc
	global_load_dwordx4 v[0:3], v[0:1], off offset:96
.LBB0_871:
	s_or_b64 exec, exec, s[8:9]
	v_mov_b32_e32 v20, 0
	v_mov_b32_e32 v16, 0
	v_mov_b32_e32 v17, 0
	v_mov_b32_e32 v18, 0
	v_mov_b32_e32 v19, 0
	s_and_saveexec_b64 s[8:9], s[6:7]
	s_cbranch_execz .LBB0_873
	v_add_co_u32_e32 v10, vcc, 0x2000, v24
	s_nop 1
	v_addc_co_u32_e32 v11, vcc, 0, v25, vcc
	global_load_dwordx4 v[16:19], v[10:11], off offset:1728
.LBB0_873:
	s_or_b64 exec, exec, s[8:9]
	v_or_b32_e32 v8, 3, v9
	v_cmp_lt_i32_e32 vcc, -1, v9
	v_cmp_ge_i32_e64 s[10:11], s13, v8
	v_cmp_gt_i32_e64 s[8:9], 0, v9
	s_and_b64 s[24:25], vcc, s[10:11]
	v_mov_b32_e32 v21, 0
	v_mov_b32_e32 v22, 0
	v_mov_b32_e32 v23, 0
	s_and_saveexec_b64 s[10:11], s[24:25]
	s_cbranch_execz .LBB0_875
	v_add_co_u32_e32 v10, vcc, 0x3000, v24
	s_nop 1
	v_addc_co_u32_e32 v11, vcc, 0, v25, vcc
	global_load_dwordx4 v[20:23], v[10:11], off offset:3360
.LBB0_875:
	s_or_b64 exec, exec, s[10:11]
	v_mov_b32_e32 v36, 0
	v_mov_b32_e32 v32, 0
	v_mov_b32_e32 v33, 0
	v_mov_b32_e32 v34, 0
	v_mov_b32_e32 v35, 0
	s_and_saveexec_b64 s[10:11], s[6:7]
	s_cbranch_execz .LBB0_877
	v_add_co_u32_e32 v10, vcc, 0x5000, v24
	s_nop 1
	v_addc_co_u32_e32 v11, vcc, 0, v25, vcc
	global_load_dwordx4 v[32:35], v[10:11], off offset:896
.LBB0_877:
	s_or_b64 exec, exec, s[10:11]
	v_or_b32_e32 v8, 5, v9
	v_cmp_ge_i32_e32 vcc, s13, v8
	s_xor_b64 s[6:7], s[8:9], -1
	s_and_b64 s[10:11], s[6:7], vcc
	v_mov_b32_e32 v37, 0
	v_mov_b32_e32 v38, 0
	v_mov_b32_e32 v39, 0
	s_and_saveexec_b64 s[8:9], s[10:11]
	s_cbranch_execz .LBB0_879
	v_add_co_u32_e32 v10, vcc, 0x6000, v24
	s_nop 1
	v_addc_co_u32_e32 v11, vcc, 0, v25, vcc
	global_load_dwordx4 v[36:39], v[10:11], off offset:2528
.LBB0_879:
	s_or_b64 exec, exec, s[8:9]
	v_or_b32_e32 v8, 6, v9
	v_cmp_ge_i32_e32 vcc, s13, v8
	s_and_b64 s[10:11], s[6:7], vcc
	v_mov_b32_e32 v44, 0
	v_mov_b32_e32 v48, 0
	v_mov_b32_e32 v49, 0
	v_mov_b32_e32 v50, 0
	v_mov_b32_e32 v51, 0
	s_and_saveexec_b64 s[8:9], s[10:11]
	s_cbranch_execz .LBB0_881
	v_add_co_u32_e32 v10, vcc, 0x8000, v24
	s_nop 1
	v_addc_co_u32_e32 v11, vcc, 0, v25, vcc
	global_load_dwordx4 v[48:51], v[10:11], off offset:64
.LBB0_881:
	s_or_b64 exec, exec, s[8:9]
	v_or_b32_e32 v8, 7, v9
	v_cmp_ge_i32_e32 vcc, s13, v8
	s_and_b64 s[8:9], s[6:7], vcc
	v_mov_b32_e32 v45, 0
	v_mov_b32_e32 v46, 0
	v_mov_b32_e32 v47, 0
	s_and_saveexec_b64 s[6:7], s[8:9]
	s_cbranch_execz .LBB0_883
	v_add_co_u32_e32 v10, vcc, 0x9000, v24
	s_nop 1
	v_addc_co_u32_e32 v11, vcc, 0, v25, vcc
	global_load_dwordx4 v[44:47], v[10:11], off offset:1696
.LBB0_883:
	s_or_b64 exec, exec, s[6:7]
	v_cmp_lt_i32_e32 vcc, -8, v9
	v_cmp_gt_i32_e64 s[6:7], s13, v9
	s_and_b64 s[8:9], vcc, s[6:7]
	v_mov_b32_e32 v8, 0
	v_mov_b32_e32 v12, 0
	v_mov_b32_e32 v13, 0
	v_mov_b32_e32 v14, 0
	v_mov_b32_e32 v15, 0
	s_and_saveexec_b64 s[6:7], s[8:9]
	s_cbranch_execz .LBB0_885
	v_add_co_u32_e32 v10, vcc, 0xa000, v24
	s_nop 1
	v_addc_co_u32_e32 v11, vcc, 0, v25, vcc
	global_load_dwordx4 v[12:15], v[10:11], off offset:3328
.LBB0_885:
	s_or_b64 exec, exec, s[6:7]
	v_add_u32_e32 v10, 9, v9
	v_cmp_lt_i32_e32 vcc, -9, v9
	v_cmp_ge_i32_e64 s[6:7], s13, v10
	s_and_b64 s[8:9], vcc, s[6:7]
	v_mov_b32_e32 v9, 0
	v_mov_b32_e32 v10, 0
	v_mov_b32_e32 v11, 0
	s_and_saveexec_b64 s[6:7], s[8:9]
	s_cbranch_execz .LBB0_864
	v_add_co_u32_e32 v8, vcc, 0xc000, v24
	s_nop 1
	v_addc_co_u32_e32 v9, vcc, 0, v25, vcc
	global_load_dwordx4 v[8:11], v[8:9], off offset:864
	s_branch .LBB0_864

.LBB0_941:
	s_add_i32 s4, s72, 0xffffff80
	s_lshr_b32 s4, s4, 3
	s_addk_i32 s4, 0x80
	s_and_b32 s5, s39, 28
	s_cmpk_lt_i32 s72, 0x80
	s_cselect_b32 s73, s72, s4
	s_cselect_b32 s77, 0, s5
	s_add_i32 s6, s73, 0xffffff80
	s_cmpk_gt_i32 s73, 0x7f
	s_cselect_b64 s[4:5], -1, 0
	s_and_b64 s[4:5], s[4:5], exec
	s_cselect_b32 s74, s6, s73
	s_cselect_b32 s75, s41, 0x100
	s_ashr_i32 s4, s74, 3
	s_lshl_b32 s5, s4, 11
	s_add_i32 s6, s5, 0x1000
	s_lshl_b32 s7, s4, 8
	s_cmpk_gt_i32 s73, 0x7f
	s_cselect_b64 s[28:29], -1, 0
	v_mov_b32_e32 v99, v96
	s_and_b64 s[4:5], s[28:29], exec
	v_and_b32_e32 v76, 64, v99
	s_cselect_b32 s30, s6, s7
	v_cmp_eq_u32_e64 s[6:7], 0, v76
	v_cmp_ne_u32_e64 s[4:5], 0, v76
	s_and_saveexec_b64 s[34:35], s[4:5]
	s_xor_b64 s[34:35], exec, s[34:35]
	s_ashr_i32 s31, s30, 31
	s_or_saveexec_b64 s[34:35], s[34:35]
	v_ashrrev_i32_e32 v140, 7, v99
	v_add_u32_e32 v77, s77, v140
	v_and_b32_e32 v98, 63, v99
	s_and_b32 s10, s74, 3
	s_bfe_u32 s76, s74, 0x10002
	v_lshlrev_b32_e32 v151, 6, v77
	v_mov_b32_e32 v127, 0
	v_mov_b64_e32 v[68:69], s[30:31]
	v_mov_b32_e32 v152, 0
	s_xor_b64 exec, exec, s[34:35]
	s_cbranch_execz .LBB0_945
	v_or_b32_e32 v4, v151, v98
	s_cmp_eq_u32 s76, 0
	v_xad_u32 v5, v4, -1, s75
	s_cselect_b64 vcc, -1, 0
	v_cndmask_b32_e32 v4, v5, v4, vcc
	s_ashr_i32 s31, s30, 31
	v_ashrrev_i32_e32 v5, 31, v4
	v_lshl_add_u64 v[4:5], v[4:5], 0, s[30:31]
	v_lshlrev_b64 v[4:5], 3, v[4:5]
	v_lshl_or_b32 v4, s76, 2, v4
	v_or_b32_e32 v4, s10, v4
	v_lshlrev_b64 v[4:5], 2, v[4:5]
	v_lshl_add_u64 v[6:7], s[14:15], 0, v[4:5]
	v_lshl_add_u64 v[4:5], s[12:13], 0, v[4:5]
	global_load_dword v152, v[6:7], off
	global_load_dword v127, v[4:5], off
	v_mov_b64_e32 v[68:69], s[30:31]
.LBB0_945:
	s_or_b64 exec, exec, s[34:35]
	v_and_b32_e32 v126, 15, v99
	v_or_b32_e32 v12, v151, v126
	s_cmp_eq_u32 s76, 0
	v_xad_u32 v6, v12, -1, s75
	s_cselect_b64 vcc, -1, 0
	s_lshl_b32 s34, s10, 7
	v_cndmask_b32_e32 v6, v6, v12, vcc
	s_add_u32 s30, s37, s34
	v_ashrrev_i32_e32 v7, 31, v6
	s_addc_u32 s31, s38, 0
	v_and_b32_e32 v72, 48, v98
	v_lshl_add_u64 v[6:7], v[68:69], 0, v[6:7]
	v_lshl_add_u64 v[4:5], s[30:31], 0, v[72:73]
	v_lshlrev_b64 v[6:7], 9, v[6:7]
	v_lshl_add_u64 v[10:11], v[4:5], 0, v[6:7]
	global_load_dwordx4 v[36:39], v[10:11], off
	s_add_u32 s34, s33, s34
	s_addc_u32 s35, s36, 0
	v_lshl_add_u64 v[8:9], s[34:35], 0, v[72:73]
	v_lshl_add_u64 v[6:7], v[8:9], 0, v[6:7]
	s_waitcnt vmcnt(0) lgkmcnt(0)
	v_mov_b64_e32 v[62:63], v[38:39]
	v_mov_b64_e32 v[60:61], v[36:37]
	s_and_saveexec_b64 s[34:35], s[4:5]
	s_cbranch_execz .LBB0_947
	global_load_dwordx4 v[60:63], v[6:7], off
.LBB0_947:
	s_or_b64 exec, exec, s[34:35]
	global_load_dwordx4 v[40:43], v[10:11], off offset:64
	s_waitcnt vmcnt(0) lgkmcnt(0)
	v_mov_b64_e32 v[66:67], v[42:43]
	v_mov_b64_e32 v[64:65], v[40:41]
	s_and_saveexec_b64 s[34:35], s[4:5]
	s_cbranch_execz .LBB0_949
	global_load_dwordx4 v[64:67], v[6:7], off offset:64
.LBB0_949:
	s_or_b64 exec, exec, s[34:35]
	v_xor_b32_e32 v7, 0xffffffef, v12
	v_or_b32_e32 v6, 16, v12
	v_add_u32_e32 v7, s75, v7
	v_cndmask_b32_e32 v6, v7, v6, vcc
	v_ashrrev_i32_e32 v7, 31, v6
	v_lshl_add_u64 v[6:7], v[68:69], 0, v[6:7]
	v_lshlrev_b64 v[6:7], 9, v[6:7]
	v_lshl_add_u64 v[10:11], v[4:5], 0, v[6:7]
	global_load_dwordx4 v[28:31], v[10:11], off
	v_lshl_add_u64 v[6:7], v[8:9], 0, v[6:7]
	s_waitcnt vmcnt(0) lgkmcnt(0)
	v_mov_b64_e32 v[54:55], v[30:31]
	v_mov_b64_e32 v[52:53], v[28:29]
	s_and_saveexec_b64 s[34:35], s[4:5]
	s_cbranch_execz .LBB0_951
	global_load_dwordx4 v[52:55], v[6:7], off
.LBB0_951:
	s_or_b64 exec, exec, s[34:35]
	global_load_dwordx4 v[32:35], v[10:11], off offset:64
	s_waitcnt vmcnt(0) lgkmcnt(0)
	v_mov_b64_e32 v[58:59], v[34:35]
	v_mov_b64_e32 v[56:57], v[32:33]
	s_and_saveexec_b64 s[34:35], s[4:5]
	s_cbranch_execz .LBB0_953
	global_load_dwordx4 v[56:59], v[6:7], off offset:64
.LBB0_953:
	s_or_b64 exec, exec, s[34:35]
	v_xor_b32_e32 v7, 0xffffffdf, v12
	v_or_b32_e32 v6, 32, v12
	v_add_u32_e32 v7, s75, v7
	v_cndmask_b32_e32 v6, v7, v6, vcc
	v_ashrrev_i32_e32 v7, 31, v6
	v_lshl_add_u64 v[6:7], v[68:69], 0, v[6:7]
	v_lshlrev_b64 v[6:7], 9, v[6:7]
	v_lshl_add_u64 v[10:11], v[4:5], 0, v[6:7]
	global_load_dwordx4 v[20:23], v[10:11], off
	v_lshl_add_u64 v[6:7], v[8:9], 0, v[6:7]
	s_waitcnt vmcnt(0) lgkmcnt(0)
	v_mov_b64_e32 v[46:47], v[22:23]
	v_mov_b64_e32 v[44:45], v[20:21]
	s_and_saveexec_b64 s[34:35], s[4:5]
	s_cbranch_execz .LBB0_955
	global_load_dwordx4 v[44:47], v[6:7], off
.LBB0_955:
	s_or_b64 exec, exec, s[34:35]
	global_load_dwordx4 v[24:27], v[10:11], off offset:64
	s_waitcnt vmcnt(0) lgkmcnt(0)
	v_mov_b64_e32 v[50:51], v[26:27]
	v_mov_b64_e32 v[48:49], v[24:25]
	s_and_saveexec_b64 s[34:35], s[4:5]
	s_cbranch_execz .LBB0_957
	global_load_dwordx4 v[48:51], v[6:7], off offset:64
.LBB0_957:
	s_or_b64 exec, exec, s[34:35]
	v_xor_b32_e32 v7, 0xffffffcf, v12
	v_or_b32_e32 v6, 48, v12
	v_add_u32_e32 v7, s75, v7
	v_cndmask_b32_e32 v6, v7, v6, vcc
	v_ashrrev_i32_e32 v7, 31, v6
	v_lshl_add_u64 v[6:7], v[68:69], 0, v[6:7]
	v_lshlrev_b64 v[10:11], 9, v[6:7]
	v_lshl_add_u64 v[12:13], v[4:5], 0, v[10:11]
	global_load_dwordx4 v[4:7], v[12:13], off
	v_lshl_add_u64 v[70:71], v[8:9], 0, v[10:11]
	s_waitcnt vmcnt(0) lgkmcnt(0)
	v_mov_b64_e32 v[10:11], v[6:7]
	v_mov_b64_e32 v[8:9], v[4:5]
	s_and_saveexec_b64 s[34:35], s[4:5]
	s_cbranch_execz .LBB0_959
	global_load_dwordx4 v[8:11], v[70:71], off
.LBB0_959:
	s_or_b64 exec, exec, s[34:35]
	global_load_dwordx4 v[12:15], v[12:13], off offset:64
	s_lshl_b32 s10, s10, 6
	v_mov_b64_e32 v[74:75], 0xc532000
	s_waitcnt vmcnt(0) lgkmcnt(0)
	v_mov_b64_e32 v[18:19], v[14:15]
	v_mov_b64_e32 v[16:17], v[12:13]
	s_and_saveexec_b64 s[34:35], s[4:5]
	s_cbranch_execz .LBB0_961
	global_load_dwordx4 v[16:19], v[70:71], off offset:64
	v_mov_b64_e32 v[74:75], 0xbf32000
.LBB0_961:
	s_or_b64 exec, exec, s[34:35]
	v_lshrrev_b32_e32 v101, 4, v98
	v_lshl_add_u64 v[70:71], s[8:9], 0, v[74:75]
	v_lshlrev_b32_e32 v100, 2, v101
	s_lshl_b32 s10, s10, 1
	v_or_b32_e32 v90, v151, v100
	v_lshl_add_u64 v[70:71], v[70:71], 0, s[10:11]
	v_lshlrev_b32_e32 v72, 1, v126
	v_lshl_add_u64 v[70:71], v[70:71], 0, v[72:73]
	v_xad_u32 v72, v90, -1, s75
	v_cndmask_b32_e32 v74, v72, v90, vcc
	v_or_b32_e32 v72, 1, v90
	v_xad_u32 v78, v90, -2, s75
	v_ashrrev_i32_e32 v75, 31, v74
	v_cndmask_b32_e32 v78, v78, v72, vcc
	v_lshl_add_u64 v[74:75], v[68:69], 0, v[74:75]
	v_ashrrev_i32_e32 v79, 31, v78
	v_lshlrev_b64 v[74:75], 9, v[74:75]
	v_lshl_add_u64 v[78:79], v[68:69], 0, v[78:79]
	v_lshl_add_u64 v[74:75], v[70:71], 0, v[74:75]
	v_lshlrev_b64 v[78:79], 9, v[78:79]
	v_lshl_add_u64 v[80:81], v[70:71], 0, v[78:79]
	global_load_ushort v86, v[74:75], off
	global_load_ushort v87, v[74:75], off offset:32
	global_load_ushort v94, v[74:75], off offset:64
	global_load_ushort v95, v[74:75], off offset:96
	global_load_ushort v84, v[80:81], off
	global_load_ushort v85, v[80:81], off offset:32
	global_load_ushort v78, v[80:81], off offset:64
	global_load_ushort v79, v[80:81], off offset:96
	v_or_b32_e32 v72, 2, v90
	v_xad_u32 v74, v90, -3, s75
	v_cndmask_b32_e32 v74, v74, v72, vcc
	v_or_b32_e32 v72, 3, v90
	v_xad_u32 v80, v90, -4, s75
	v_ashrrev_i32_e32 v75, 31, v74
	v_cndmask_b32_e32 v80, v80, v72, vcc
	v_lshl_add_u64 v[74:75], v[68:69], 0, v[74:75]
	v_ashrrev_i32_e32 v81, 31, v80
	v_lshlrev_b64 v[74:75], 9, v[74:75]
	v_lshl_add_u64 v[80:81], v[68:69], 0, v[80:81]
	v_lshl_add_u64 v[74:75], v[70:71], 0, v[74:75]
	v_lshlrev_b64 v[80:81], 9, v[80:81]
	v_lshl_add_u64 v[80:81], v[70:71], 0, v[80:81]
	global_load_ushort v106, v[74:75], off
	global_load_ushort v107, v[74:75], off offset:32
	global_load_ushort v108, v[74:75], off offset:64
	global_load_ushort v109, v[74:75], off offset:96
	global_load_ushort v102, v[80:81], off
	global_load_ushort v103, v[80:81], off offset:32
	global_load_ushort v104, v[80:81], off offset:64
	global_load_ushort v105, v[80:81], off offset:96
	v_bitop3_b32 v74, v151, s43, v100 bitop3:0x36
	v_or_b32_e32 v72, 16, v90
	v_add_u32_e32 v74, s75, v74
	v_bitop3_b32 v80, v151, s47, v100 bitop3:0x36
	v_cndmask_b32_e32 v74, v74, v72, vcc
	v_or_b32_e32 v72, 17, v90
	v_add_u32_e32 v80, s75, v80
	v_ashrrev_i32_e32 v75, 31, v74
	v_cndmask_b32_e32 v80, v80, v72, vcc
	v_lshl_add_u64 v[74:75], v[68:69], 0, v[74:75]
	v_ashrrev_i32_e32 v81, 31, v80
	v_lshlrev_b64 v[74:75], 9, v[74:75]
	v_lshl_add_u64 v[80:81], v[68:69], 0, v[80:81]
	v_lshl_add_u64 v[74:75], v[70:71], 0, v[74:75]
	v_lshlrev_b64 v[80:81], 9, v[80:81]
	v_lshl_add_u64 v[80:81], v[70:71], 0, v[80:81]
	global_load_ushort v114, v[74:75], off
	global_load_ushort v115, v[74:75], off offset:32
	global_load_ushort v116, v[74:75], off offset:64
	global_load_ushort v117, v[74:75], off offset:96
	global_load_ushort v110, v[80:81], off
	global_load_ushort v111, v[80:81], off offset:32
	global_load_ushort v112, v[80:81], off offset:64
	global_load_ushort v113, v[80:81], off offset:96
	v_bitop3_b32 v74, v151, s48, v100 bitop3:0x36
	v_or_b32_e32 v72, 18, v90
	v_add_u32_e32 v74, s75, v74
	v_bitop3_b32 v80, v151, s49, v100 bitop3:0x36
	v_cndmask_b32_e32 v74, v74, v72, vcc
	v_or_b32_e32 v72, 19, v90
	v_add_u32_e32 v80, s75, v80
	v_ashrrev_i32_e32 v75, 31, v74
	v_cndmask_b32_e32 v80, v80, v72, vcc
	v_lshl_add_u64 v[74:75], v[68:69], 0, v[74:75]
	v_ashrrev_i32_e32 v81, 31, v80
	v_lshlrev_b64 v[74:75], 9, v[74:75]
	v_lshl_add_u64 v[80:81], v[68:69], 0, v[80:81]
	v_lshl_add_u64 v[74:75], v[70:71], 0, v[74:75]
	v_lshlrev_b64 v[80:81], 9, v[80:81]
	v_lshl_add_u64 v[80:81], v[70:71], 0, v[80:81]
	global_load_ushort v122, v[74:75], off
	global_load_ushort v123, v[74:75], off offset:32
	global_load_ushort v124, v[74:75], off offset:64
	global_load_ushort v125, v[74:75], off offset:96
	global_load_ushort v118, v[80:81], off
	global_load_ushort v119, v[80:81], off offset:32
	global_load_ushort v120, v[80:81], off offset:64
	global_load_ushort v121, v[80:81], off offset:96
	v_bitop3_b32 v74, v151, s44, v100 bitop3:0x36
	v_or_b32_e32 v72, 32, v90
	v_add_u32_e32 v74, s75, v74
	v_bitop3_b32 v80, v151, s50, v100 bitop3:0x36
	v_cndmask_b32_e32 v74, v74, v72, vcc
	v_or_b32_e32 v72, 33, v90
	v_add_u32_e32 v80, s75, v80
	v_ashrrev_i32_e32 v75, 31, v74
	v_cndmask_b32_e32 v80, v80, v72, vcc
	v_lshl_add_u64 v[74:75], v[68:69], 0, v[74:75]
	v_ashrrev_i32_e32 v81, 31, v80
	v_lshlrev_b64 v[74:75], 9, v[74:75]
	v_lshl_add_u64 v[80:81], v[68:69], 0, v[80:81]
	v_lshl_add_u64 v[74:75], v[70:71], 0, v[74:75]
	v_lshlrev_b64 v[80:81], 9, v[80:81]
	v_lshl_add_u64 v[80:81], v[70:71], 0, v[80:81]
	global_load_ushort v132, v[74:75], off
	global_load_ushort v133, v[74:75], off offset:32
	global_load_ushort v134, v[74:75], off offset:64
	global_load_ushort v135, v[74:75], off offset:96
	global_load_ushort v128, v[80:81], off
	global_load_ushort v129, v[80:81], off offset:32
	global_load_ushort v130, v[80:81], off offset:64
	global_load_ushort v131, v[80:81], off offset:96
	v_bitop3_b32 v74, v151, s51, v100 bitop3:0x36
	v_or_b32_e32 v72, 34, v90
	v_add_u32_e32 v74, s75, v74
	v_bitop3_b32 v80, v151, s52, v100 bitop3:0x36
	v_cndmask_b32_e32 v74, v74, v72, vcc
	v_or_b32_e32 v72, 35, v90
	v_add_u32_e32 v80, s75, v80
	v_ashrrev_i32_e32 v75, 31, v74
	v_cndmask_b32_e32 v80, v80, v72, vcc
	v_lshl_add_u64 v[74:75], v[68:69], 0, v[74:75]
	v_ashrrev_i32_e32 v81, 31, v80
	v_lshlrev_b64 v[74:75], 9, v[74:75]
	v_lshl_add_u64 v[80:81], v[68:69], 0, v[80:81]
	v_lshl_add_u64 v[74:75], v[70:71], 0, v[74:75]
	v_lshlrev_b64 v[80:81], 9, v[80:81]
	v_lshl_add_u64 v[88:89], v[70:71], 0, v[80:81]
	global_load_ushort v136, v[74:75], off
	global_load_ushort v137, v[74:75], off offset:32
	global_load_ushort v138, v[74:75], off offset:64
	global_load_ushort v139, v[74:75], off offset:96
	global_load_ushort v82, v[88:89], off
	global_load_ushort v83, v[88:89], off offset:32
	global_load_ushort v80, v[88:89], off offset:64
	global_load_ushort v81, v[88:89], off offset:96
	v_bitop3_b32 v74, v151, s45, v100 bitop3:0x36
	v_or_b32_e32 v72, 48, v90
	v_add_u32_e32 v74, s75, v74
	v_bitop3_b32 v88, v151, s53, v100 bitop3:0x36
	v_cndmask_b32_e32 v74, v74, v72, vcc
	v_or_b32_e32 v72, 49, v90
	v_add_u32_e32 v88, s75, v88
	v_ashrrev_i32_e32 v75, 31, v74
	v_cndmask_b32_e32 v88, v88, v72, vcc
	v_lshl_add_u64 v[74:75], v[68:69], 0, v[74:75]
	v_ashrrev_i32_e32 v89, 31, v88
	v_lshlrev_b64 v[74:75], 9, v[74:75]
	v_lshl_add_u64 v[88:89], v[68:69], 0, v[88:89]
	v_lshl_add_u64 v[74:75], v[70:71], 0, v[74:75]
	v_lshlrev_b64 v[88:89], 9, v[88:89]
	v_lshl_add_u64 v[88:89], v[70:71], 0, v[88:89]
	global_load_ushort v145, v[74:75], off
	global_load_ushort v146, v[74:75], off offset:32
	global_load_ushort v147, v[74:75], off offset:64
	global_load_ushort v148, v[74:75], off offset:96
	global_load_ushort v141, v[88:89], off
	global_load_ushort v142, v[88:89], off offset:32
	global_load_ushort v143, v[88:89], off offset:64
	global_load_ushort v144, v[88:89], off offset:96
	v_bitop3_b32 v74, v151, s54, v100 bitop3:0x36
	v_or_b32_e32 v72, 50, v90
	v_add_u32_e32 v74, s75, v74
	v_bitop3_b32 v88, v151, s55, v100 bitop3:0x36
	v_cndmask_b32_e32 v74, v74, v72, vcc
	v_or_b32_e32 v72, 51, v90
	v_add_u32_e32 v88, s75, v88
	v_cndmask_b32_e32 v88, v88, v72, vcc
	v_ashrrev_i32_e32 v75, 31, v74
	v_ashrrev_i32_e32 v89, 31, v88
	v_lshl_add_u64 v[74:75], v[68:69], 0, v[74:75]
	v_lshl_add_u64 v[88:89], v[68:69], 0, v[88:89]
	v_lshlrev_b64 v[74:75], 9, v[74:75]
	v_lshlrev_b64 v[88:89], 9, v[88:89]
	v_lshl_add_u64 v[74:75], v[70:71], 0, v[74:75]
	v_lshl_add_u64 v[70:71], v[70:71], 0, v[88:89]
	global_load_ushort v149, v[74:75], off
	global_load_ushort v150, v[74:75], off offset:32
	global_load_ushort v93, v[74:75], off offset:64
	global_load_ushort v92, v[74:75], off offset:96
	global_load_ushort v91, v[70:71], off
	global_load_ushort v90, v[70:71], off offset:32
	global_load_ushort v89, v[70:71], off offset:64
	global_load_ushort v88, v[70:71], off offset:96
	v_lshrrev_b32_e32 v70, 1, v99
	v_and_b32_e32 v162, 32, v70
	v_or_b32_e32 v153, v151, v162
	v_lshlrev_b32_e32 v72, 1, v98
	v_lshl_add_u64 v[70:71], s[30:31], 0, v[72:73]
	v_xad_u32 v72, v153, -1, s75
	v_cndmask_b32_e32 v74, v72, v153, vcc
	v_or_b32_e32 v72, 1, v153
	v_xad_u32 v154, v153, -2, s75
	v_cndmask_b32_e32 v154, v154, v72, vcc
	v_or_b32_e32 v72, 2, v153
	v_xad_u32 v156, v153, -3, s75
	v_cndmask_b32_e32 v156, v156, v72, vcc
	v_or_b32_e32 v72, 3, v153
	v_xad_u32 v158, v153, -4, s75
	v_cndmask_b32_e32 v158, v158, v72, vcc
	v_or_b32_e32 v72, 4, v153
	v_xad_u32 v160, v153, -5, s75
	v_cndmask_b32_e32 v160, v160, v72, vcc
	v_or_b32_e32 v72, 5, v153
	v_xad_u32 v163, v153, -6, s75
	v_cndmask_b32_e32 v164, v163, v72, vcc
	v_ashrrev_i32_e32 v165, 31, v164
	v_lshl_add_u64 v[164:165], v[68:69], 0, v[164:165]
	v_lshlrev_b64 v[164:165], 9, v[164:165]
	v_or_b32_e32 v72, 6, v153
	v_xad_u32 v163, v153, -7, s75
	v_lshl_add_u64 v[166:167], v[70:71], 0, v[164:165]
	v_cndmask_b32_e32 v164, v163, v72, vcc
	v_ashrrev_i32_e32 v165, 31, v164
	v_lshl_add_u64 v[164:165], v[68:69], 0, v[164:165]
	v_lshlrev_b64 v[164:165], 9, v[164:165]
	v_or_b32_e32 v72, 7, v153
	v_xad_u32 v163, v153, -8, s75
	v_ashrrev_i32_e32 v75, 31, v74
	v_lshl_add_u64 v[178:179], v[70:71], 0, v[164:165]
	v_cndmask_b32_e32 v164, v163, v72, vcc
	v_lshl_add_u64 v[74:75], v[68:69], 0, v[74:75]
	v_ashrrev_i32_e32 v155, 31, v154
	v_ashrrev_i32_e32 v157, 31, v156
	v_ashrrev_i32_e32 v159, 31, v158
	v_ashrrev_i32_e32 v161, 31, v160
	v_ashrrev_i32_e32 v165, 31, v164
	v_lshlrev_b64 v[74:75], 9, v[74:75]
	v_lshl_add_u64 v[154:155], v[68:69], 0, v[154:155]
	v_lshl_add_u64 v[156:157], v[68:69], 0, v[156:157]
	v_lshl_add_u64 v[158:159], v[68:69], 0, v[158:159]
	v_lshl_add_u64 v[160:161], v[68:69], 0, v[160:161]
	v_lshl_add_u64 v[164:165], v[68:69], 0, v[164:165]
	v_lshl_add_u64 v[74:75], v[70:71], 0, v[74:75]
	v_lshlrev_b64 v[154:155], 9, v[154:155]
	v_lshlrev_b64 v[156:157], 9, v[156:157]
	v_lshlrev_b64 v[158:159], 9, v[158:159]
	v_lshlrev_b64 v[160:161], 9, v[160:161]
	v_lshlrev_b64 v[164:165], 9, v[164:165]
	v_lshl_add_u64 v[154:155], v[70:71], 0, v[154:155]
	v_lshl_add_u64 v[156:157], v[70:71], 0, v[156:157]
	v_lshl_add_u64 v[158:159], v[70:71], 0, v[158:159]
	v_lshl_add_u64 v[160:161], v[70:71], 0, v[160:161]
	v_lshl_add_u64 v[180:181], v[70:71], 0, v[164:165]
	global_load_ushort v173, v[74:75], off
	global_load_ushort v176, v[154:155], off
	global_load_ushort v169, v[156:157], off
	global_load_ushort v170, v[158:159], off
	global_load_ushort v165, v[160:161], off
	s_nop 0
	global_load_ushort v166, v[166:167], off
	s_nop 0
	global_load_ushort v163, v[178:179], off
	global_load_ushort v164, v[180:181], off
	v_or_b32_e32 v72, 8, v153
	v_xad_u32 v74, v153, -9, s75
	v_cndmask_b32_e32 v74, v74, v72, vcc
	v_or_b32_e32 v72, 9, v153
	v_xad_u32 v154, v153, -10, s75
	v_cndmask_b32_e32 v154, v154, v72, vcc
	v_or_b32_e32 v72, 10, v153
	v_xad_u32 v156, v153, -11, s75
	v_cndmask_b32_e32 v156, v156, v72, vcc
	v_or_b32_e32 v72, 11, v153
	v_xad_u32 v158, v153, -12, s75
	v_cndmask_b32_e32 v158, v158, v72, vcc
	v_or_b32_e32 v72, 12, v153
	v_xad_u32 v160, v153, -13, s75
	v_cndmask_b32_e32 v160, v160, v72, vcc
	v_or_b32_e32 v72, 13, v153
	v_xad_u32 v167, v153, -14, s75
	v_cndmask_b32_e32 v178, v167, v72, vcc
	v_ashrrev_i32_e32 v179, 31, v178
	v_lshl_add_u64 v[178:179], v[68:69], 0, v[178:179]
	v_lshlrev_b64 v[178:179], 9, v[178:179]
	v_or_b32_e32 v72, 14, v153
	v_xad_u32 v167, v153, -15, s75
	v_lshl_add_u64 v[184:185], v[70:71], 0, v[178:179]
	v_cndmask_b32_e32 v178, v167, v72, vcc
	v_ashrrev_i32_e32 v179, 31, v178
	v_lshl_add_u64 v[178:179], v[68:69], 0, v[178:179]
	v_lshlrev_b64 v[178:179], 9, v[178:179]
	v_or_b32_e32 v72, 15, v153
	v_xad_u32 v167, v153, -16, s75
	v_ashrrev_i32_e32 v75, 31, v74
	v_lshl_add_u64 v[186:187], v[70:71], 0, v[178:179]
	v_cndmask_b32_e32 v178, v167, v72, vcc
	v_lshl_add_u64 v[74:75], v[68:69], 0, v[74:75]
	v_ashrrev_i32_e32 v155, 31, v154
	v_ashrrev_i32_e32 v157, 31, v156
	v_ashrrev_i32_e32 v159, 31, v158
	v_ashrrev_i32_e32 v161, 31, v160
	v_ashrrev_i32_e32 v179, 31, v178
	v_lshlrev_b64 v[74:75], 9, v[74:75]
	v_lshl_add_u64 v[154:155], v[68:69], 0, v[154:155]
	v_lshl_add_u64 v[156:157], v[68:69], 0, v[156:157]
	v_lshl_add_u64 v[158:159], v[68:69], 0, v[158:159]
	v_lshl_add_u64 v[160:161], v[68:69], 0, v[160:161]
	v_lshl_add_u64 v[178:179], v[68:69], 0, v[178:179]
	v_lshl_add_u64 v[74:75], v[70:71], 0, v[74:75]
	v_lshlrev_b64 v[154:155], 9, v[154:155]
	v_lshlrev_b64 v[156:157], 9, v[156:157]
	v_lshlrev_b64 v[158:159], 9, v[158:159]
	v_lshlrev_b64 v[160:161], 9, v[160:161]
	v_lshlrev_b64 v[178:179], 9, v[178:179]
	v_lshl_add_u64 v[154:155], v[70:71], 0, v[154:155]
	v_lshl_add_u64 v[156:157], v[70:71], 0, v[156:157]
	v_lshl_add_u64 v[158:159], v[70:71], 0, v[158:159]
	v_lshl_add_u64 v[160:161], v[70:71], 0, v[160:161]
	v_lshl_add_u64 v[188:189], v[70:71], 0, v[178:179]
	global_load_ushort v181, v[74:75], off
	global_load_ushort v182, v[154:155], off
	global_load_ushort v177, v[156:157], off
	global_load_ushort v178, v[158:159], off
	global_load_ushort v171, v[160:161], off
	global_load_ushort v172, v[184:185], off
	global_load_ushort v167, v[186:187], off
	global_load_ushort v168, v[188:189], off
	v_bitop3_b32 v74, v151, s43, v162 bitop3:0x36
	v_or_b32_e32 v72, 16, v153
	v_add_u32_e32 v74, s75, v74
	v_bitop3_b32 v154, v151, s47, v162 bitop3:0x36
	v_cndmask_b32_e32 v74, v74, v72, vcc
	v_or_b32_e32 v72, 17, v153
	v_add_u32_e32 v154, s75, v154
	v_bitop3_b32 v156, v151, s48, v162 bitop3:0x36
	v_cndmask_b32_e32 v154, v154, v72, vcc
	v_or_b32_e32 v72, 18, v153
	v_add_u32_e32 v156, s75, v156
	v_bitop3_b32 v158, v151, s49, v162 bitop3:0x36
	v_cndmask_b32_e32 v156, v156, v72, vcc
	v_or_b32_e32 v72, 19, v153
	v_add_u32_e32 v158, s75, v158
	v_bitop3_b32 v160, v151, s56, v162 bitop3:0x36
	v_cndmask_b32_e32 v158, v158, v72, vcc
	v_or_b32_e32 v72, 20, v153
	v_add_u32_e32 v160, s75, v160
	v_bitop3_b32 v179, v151, s57, v162 bitop3:0x36
	v_cndmask_b32_e32 v160, v160, v72, vcc
	v_or_b32_e32 v72, 21, v153
	v_add_u32_e32 v179, s75, v179
	v_cndmask_b32_e32 v184, v179, v72, vcc
	v_ashrrev_i32_e32 v185, 31, v184
	v_lshl_add_u64 v[184:185], v[68:69], 0, v[184:185]
	v_bitop3_b32 v179, v151, s58, v162 bitop3:0x36
	v_lshlrev_b64 v[184:185], 9, v[184:185]
	v_or_b32_e32 v72, 22, v153
	v_add_u32_e32 v179, s75, v179
	v_lshl_add_u64 v[192:193], v[70:71], 0, v[184:185]
	v_cndmask_b32_e32 v184, v179, v72, vcc
	v_ashrrev_i32_e32 v185, 31, v184
	v_lshl_add_u64 v[184:185], v[68:69], 0, v[184:185]
	v_bitop3_b32 v179, v151, s59, v162 bitop3:0x36
	v_lshlrev_b64 v[184:185], 9, v[184:185]
	v_or_b32_e32 v72, 23, v153
	v_add_u32_e32 v179, s75, v179
	v_ashrrev_i32_e32 v75, 31, v74
	v_lshl_add_u64 v[194:195], v[70:71], 0, v[184:185]
	v_cndmask_b32_e32 v184, v179, v72, vcc
	v_lshl_add_u64 v[74:75], v[68:69], 0, v[74:75]
	v_ashrrev_i32_e32 v155, 31, v154
	v_ashrrev_i32_e32 v157, 31, v156
	v_ashrrev_i32_e32 v159, 31, v158
	v_ashrrev_i32_e32 v161, 31, v160
	v_ashrrev_i32_e32 v185, 31, v184
	v_lshlrev_b64 v[74:75], 9, v[74:75]
	v_lshl_add_u64 v[154:155], v[68:69], 0, v[154:155]
	v_lshl_add_u64 v[156:157], v[68:69], 0, v[156:157]
	v_lshl_add_u64 v[158:159], v[68:69], 0, v[158:159]
	v_lshl_add_u64 v[160:161], v[68:69], 0, v[160:161]
	v_lshl_add_u64 v[184:185], v[68:69], 0, v[184:185]
	v_lshl_add_u64 v[74:75], v[70:71], 0, v[74:75]
	v_lshlrev_b64 v[154:155], 9, v[154:155]
	v_lshlrev_b64 v[156:157], 9, v[156:157]
	v_lshlrev_b64 v[158:159], 9, v[158:159]
	v_lshlrev_b64 v[160:161], 9, v[160:161]
	v_lshlrev_b64 v[184:185], 9, v[184:185]
	v_lshl_add_u64 v[154:155], v[70:71], 0, v[154:155]
	v_lshl_add_u64 v[156:157], v[70:71], 0, v[156:157]
	v_lshl_add_u64 v[158:159], v[70:71], 0, v[158:159]
	v_lshl_add_u64 v[160:161], v[70:71], 0, v[160:161]
	v_lshl_add_u64 v[196:197], v[70:71], 0, v[184:185]
	global_load_ushort v189, v[74:75], off
	global_load_ushort v191, v[154:155], off
	global_load_ushort v185, v[156:157], off
	global_load_ushort v187, v[158:159], off
	global_load_ushort v183, v[160:161], off
	global_load_ushort v184, v[192:193], off
	global_load_ushort v179, v[194:195], off
	global_load_ushort v180, v[196:197], off
	v_bitop3_b32 v74, v151, s60, v162 bitop3:0x36
	v_or_b32_e32 v72, 24, v153
	v_add_u32_e32 v74, s75, v74
	v_bitop3_b32 v154, v151, s61, v162 bitop3:0x36
	v_cndmask_b32_e32 v74, v74, v72, vcc
	v_or_b32_e32 v72, 25, v153
	v_add_u32_e32 v154, s75, v154
	v_bitop3_b32 v156, v151, s62, v162 bitop3:0x36
	v_cndmask_b32_e32 v154, v154, v72, vcc
	v_or_b32_e32 v72, 26, v153
	v_add_u32_e32 v156, s75, v156
	v_bitop3_b32 v158, v151, s63, v162 bitop3:0x36
	v_cndmask_b32_e32 v156, v156, v72, vcc
	v_or_b32_e32 v72, 27, v153
	v_add_u32_e32 v158, s75, v158
	v_bitop3_b32 v160, v151, s64, v162 bitop3:0x36
	v_cndmask_b32_e32 v158, v158, v72, vcc
	v_or_b32_e32 v72, 28, v153
	v_add_u32_e32 v160, s75, v160
	v_bitop3_b32 v186, v151, s65, v162 bitop3:0x36
	v_cndmask_b32_e32 v160, v160, v72, vcc
	v_or_b32_e32 v72, 29, v153
	v_add_u32_e32 v186, s75, v186
	v_cndmask_b32_e32 v192, v186, v72, vcc
	v_bitop3_b32 v186, v151, s66, v162 bitop3:0x36
	v_or_b32_e32 v72, 30, v153
	v_add_u32_e32 v186, s75, v186
	v_cndmask_b32_e32 v194, v186, v72, vcc
	v_ashrrev_i32_e32 v195, 31, v194
	v_lshl_add_u64 v[194:195], v[68:69], 0, v[194:195]
	v_bitop3_b32 v151, v151, s67, v162 bitop3:0x36
	v_lshlrev_b64 v[194:195], 9, v[194:195]
	v_or_b32_e32 v72, 31, v153
	v_add_u32_e32 v151, s75, v151
	v_ashrrev_i32_e32 v75, 31, v74
	v_ashrrev_i32_e32 v193, 31, v192
	v_lshl_add_u64 v[198:199], v[70:71], 0, v[194:195]
	v_cndmask_b32_e32 v194, v151, v72, vcc
	v_lshl_add_u64 v[74:75], v[68:69], 0, v[74:75]
	v_ashrrev_i32_e32 v155, 31, v154
	v_ashrrev_i32_e32 v157, 31, v156
	v_ashrrev_i32_e32 v159, 31, v158
	v_ashrrev_i32_e32 v161, 31, v160
	v_lshl_add_u64 v[192:193], v[68:69], 0, v[192:193]
	v_ashrrev_i32_e32 v195, 31, v194
	v_lshlrev_b64 v[74:75], 9, v[74:75]
	v_lshl_add_u64 v[154:155], v[68:69], 0, v[154:155]
	v_lshl_add_u64 v[156:157], v[68:69], 0, v[156:157]
	v_lshl_add_u64 v[158:159], v[68:69], 0, v[158:159]
	v_lshl_add_u64 v[160:161], v[68:69], 0, v[160:161]
	v_lshlrev_b64 v[192:193], 9, v[192:193]
	v_lshl_add_u64 v[68:69], v[68:69], 0, v[194:195]
	v_lshl_add_u64 v[74:75], v[70:71], 0, v[74:75]
	v_lshlrev_b64 v[154:155], 9, v[154:155]
	v_lshlrev_b64 v[156:157], 9, v[156:157]
	v_lshlrev_b64 v[158:159], 9, v[158:159]
	v_lshlrev_b64 v[160:161], 9, v[160:161]
	v_lshl_add_u64 v[192:193], v[70:71], 0, v[192:193]
	v_lshlrev_b64 v[68:69], 9, v[68:69]
	v_lshl_add_u64 v[154:155], v[70:71], 0, v[154:155]
	v_lshl_add_u64 v[156:157], v[70:71], 0, v[156:157]
	v_lshl_add_u64 v[158:159], v[70:71], 0, v[158:159]
	v_lshl_add_u64 v[160:161], v[70:71], 0, v[160:161]
	v_lshl_add_u64 v[68:69], v[70:71], 0, v[68:69]
	global_load_ushort v196, v[74:75], off
	global_load_ushort v197, v[154:155], off
	global_load_ushort v194, v[156:157], off
	global_load_ushort v195, v[158:159], off
	global_load_ushort v190, v[160:161], off
	s_nop 0
	global_load_ushort v192, v[192:193], off
	s_nop 0
	global_load_ushort v186, v[198:199], off
	global_load_ushort v188, v[68:69], off
	v_mul_lo_u32 v151, v140, s46
	s_waitcnt lgkmcnt(0)
	s_barrier
	s_and_saveexec_b64 s[30:31], s[6:7]
	s_cbranch_execz .LBB0_963
	v_and_b32_e32 v68, 64, v97
	v_add_u32_e32 v69, -1, v97
	v_cmp_lt_i32_e32 vcc, v69, v68
	v_add_u32_e32 v70, -2, v97
	s_nop 0
	v_cndmask_b32_e32 v69, v69, v97, vcc
	v_lshlrev_b32_e32 v69, 2, v69
	ds_bpermute_b32 v69, v69, v152
	v_cmp_eq_u32_e32 vcc, 0, v98
	s_waitcnt lgkmcnt(0)
	v_add_f32_e32 v69, v152, v69
	v_cndmask_b32_e32 v69, v69, v152, vcc
	v_cmp_lt_i32_e32 vcc, v70, v68
	s_nop 1
	v_cndmask_b32_e32 v70, v70, v97, vcc
	v_lshlrev_b32_e32 v70, 2, v70
	ds_bpermute_b32 v70, v70, v69
	v_cmp_gt_u32_e32 vcc, 2, v98
	s_waitcnt lgkmcnt(0)
	v_add_f32_e32 v70, v69, v70
	v_cndmask_b32_e32 v69, v70, v69, vcc
	v_add_u32_e32 v70, -4, v97
	v_cmp_lt_i32_e32 vcc, v70, v68
	s_nop 1
	v_cndmask_b32_e32 v70, v70, v97, vcc
	v_lshlrev_b32_e32 v70, 2, v70
	ds_bpermute_b32 v70, v70, v69
	v_cmp_gt_u32_e32 vcc, 4, v98
	s_waitcnt lgkmcnt(0)
	v_add_f32_e32 v70, v69, v70
	v_cndmask_b32_e32 v69, v70, v69, vcc
	v_add_u32_e32 v70, -8, v97
	v_cmp_lt_i32_e32 vcc, v70, v68
	s_nop 1
	v_cndmask_b32_e32 v70, v70, v97, vcc
	v_lshlrev_b32_e32 v70, 2, v70
	ds_bpermute_b32 v70, v70, v69
	v_cmp_gt_u32_e32 vcc, 8, v98
	s_waitcnt lgkmcnt(0)
	v_add_f32_e32 v70, v69, v70
	v_cndmask_b32_e32 v69, v70, v69, vcc
	v_add_u32_e32 v70, -16, v97
	v_cmp_lt_i32_e32 vcc, v70, v68
	s_nop 1
	v_cndmask_b32_e32 v70, v70, v97, vcc
	v_lshlrev_b32_e32 v70, 2, v70
	ds_bpermute_b32 v70, v70, v69
	v_cmp_gt_u32_e32 vcc, 16, v98
	s_waitcnt lgkmcnt(0)
	v_add_f32_e32 v70, v69, v70
	v_cndmask_b32_e32 v69, v70, v69, vcc
	v_subrev_u32_e32 v70, 32, v97
	v_cmp_lt_i32_e32 vcc, v70, v68
	s_nop 1
	v_cndmask_b32_e32 v68, v70, v97, vcc
	v_lshlrev_b32_e32 v68, 2, v68
	ds_bpermute_b32 v68, v68, v69
	v_cmp_gt_u32_e32 vcc, 32, v98
	s_waitcnt lgkmcnt(0)
	v_add_f32_e32 v68, v69, v68
	v_cndmask_b32_e32 v68, v68, v69, vcc
	v_lshl_add_u32 v69, v98, 2, v151
	ds_write2st64_b32 v69, v68, v127 offset0:68 offset1:69

.LBB0_1131:
	s_and_b64 s[10:11], s[10:11], exec
	v_ashrrev_i32_e32 v29, 3, v3
	s_cselect_b32 s10, s18, 0x3040000
	v_add_u32_e32 v4, s24, v29
	s_add_u32 s10, s8, s10
	v_ashrrev_i32_e32 v5, 31, v4
	s_addc_u32 s11, s9, 0
	v_lshlrev_b64 v[4:5], 8, v[4:5]
	v_lshlrev_b32_e32 v0, 4, v3
	v_lshl_add_u64 v[4:5], s[10:11], 0, v[4:5]
	v_and_b32_e32 v0, 0x70, v0
	v_lshl_add_u64 v[106:107], v[4:5], 0, v[0:1]
	v_add_co_u32_e32 v110, vcc, s19, v106
	v_add_u32_e32 v4, s25, v29
	s_nop 0
	v_addc_co_u32_e32 v111, vcc, 0, v107, vcc
	v_ashrrev_i32_e32 v5, 31, v4
	v_add_co_u32_e32 v112, vcc, s20, v106
	v_lshlrev_b64 v[4:5], 8, v[4:5]
	s_nop 0
	v_addc_co_u32_e32 v113, vcc, 0, v107, vcc
	v_lshl_add_u64 v[4:5], s[4:5], 0, v[4:5]
	v_add_co_u32_e32 v114, vcc, s21, v106
	v_lshl_add_u64 v[108:109], v[4:5], 0, v[0:1]
	s_nop 0
	v_addc_co_u32_e32 v115, vcc, 0, v107, vcc
	v_add_co_u32_e32 v116, vcc, s19, v108
	global_load_dwordx4 v[4:7], v[110:111], off
	global_load_dwordx4 v[8:11], v[112:113], off
	global_load_dwordx4 v[12:15], v[106:107], off
	global_load_dwordx4 v[16:19], v[108:109], off
	v_addc_co_u32_e32 v117, vcc, 0, v109, vcc
	global_load_dwordx4 v[20:23], v[114:115], off
	global_load_dwordx4 v[24:27], v[116:117], off
	v_bfe_u32 v122, v3, 4, 2
	v_ashrrev_i32_e32 v28, 1, v3
	v_and_b32_e32 v30, 0x4f, v3
	v_and_b32_e32 v123, 0xffffffc0, v28
	v_lshlrev_b32_e32 v28, 4, v122
	v_mad_u64_u32 v[118:119], s[10:11], v29, s22, v[0:1]
	v_mad_u32_u24 v0, v30, s22, v28
	s_waitcnt lgkmcnt(0)
	s_barrier
	v_and_b32_e32 v97, 15, v3
	s_add_u32 s6, s8, s6
	s_addc_u32 s7, s9, s7
	s_add_i32 s15, s15, s14
	s_add_i32 s2, s2, s3
	s_add_i32 s16, s16, s17
	s_cmpk_lt_u32 s15, 0xe0
	s_waitcnt vmcnt(0)
	ds_write_b128 v118, v[12:15]
	ds_write_b128 v118, v[16:19] offset:36864
	ds_write_b128 v118, v[4:7] offset:9216
	ds_write_b128 v118, v[8:11] offset:18432
	ds_write_b128 v118, v[20:23] offset:27648
	ds_write_b128 v118, v[24:27] offset:46080
	s_waitcnt lgkmcnt(0)
	s_barrier
	ds_read_b128 v[4:7], v0 offset:36864
	v_or_b32_e32 v8, v123, v97
	v_mad_u64_u32 v[120:121], s[10:11], v8, s22, v[28:29]
	ds_read_b128 v[8:11], v120
	ds_read_b128 v[12:15], v120 offset:64
	ds_read_b128 v[16:19], v0 offset:36928
	ds_read_b128 v[24:27], v0 offset:39168
	ds_read_b128 v[28:31], v0 offset:39232
	ds_read_b128 v[36:39], v0 offset:41472
	ds_read_b128 v[40:43], v0 offset:41536
	ds_read_b128 v[48:51], v0 offset:43776
	ds_read_b128 v[52:55], v0 offset:43840
	ds_read_b128 v[56:59], v120 offset:2304
	ds_read_b128 v[60:63], v120 offset:2368
	ds_read_b128 v[76:79], v120 offset:4608
	ds_read_b128 v[80:83], v120 offset:4672
	s_waitcnt lgkmcnt(12)
	v_mfma_f32_16x16x32_bf16 v[20:23], v[4:7], v[8:11], 0
	ds_read_b128 v[98:101], v120 offset:6912
	ds_read_b128 v[102:105], v120 offset:6976
	s_waitcnt lgkmcnt(11)
	v_mfma_f32_16x16x32_bf16 v[32:35], v[24:27], v[8:11], 0
	s_waitcnt lgkmcnt(9)
	v_mfma_f32_16x16x32_bf16 v[44:47], v[36:39], v[8:11], 0
	s_waitcnt lgkmcnt(7)
	v_mfma_f32_16x16x32_bf16 v[8:11], v[48:51], v[8:11], 0
	s_waitcnt lgkmcnt(5)
	v_mfma_f32_16x16x32_bf16 v[64:67], v[4:7], v[56:59], 0
	v_mfma_f32_16x16x32_bf16 v[68:71], v[24:27], v[56:59], 0
	v_mfma_f32_16x16x32_bf16 v[72:75], v[36:39], v[56:59], 0
	v_mfma_f32_16x16x32_bf16 v[56:59], v[48:51], v[56:59], 0
	s_waitcnt lgkmcnt(3)
	v_mfma_f32_16x16x32_bf16 v[84:87], v[4:7], v[76:79], 0
	v_mfma_f32_16x16x32_bf16 v[88:91], v[24:27], v[76:79], 0
	v_mfma_f32_16x16x32_bf16 v[92:95], v[36:39], v[76:79], 0
	v_mfma_f32_16x16x32_bf16 v[76:79], v[48:51], v[76:79], 0
	s_waitcnt lgkmcnt(1)
	v_mfma_f32_16x16x32_bf16 v[4:7], v[4:7], v[98:101], 0
	v_mfma_f32_16x16x32_bf16 v[24:27], v[24:27], v[98:101], 0
	v_mfma_f32_16x16x32_bf16 v[36:39], v[36:39], v[98:101], 0
	v_mfma_f32_16x16x32_bf16 v[48:51], v[48:51], v[98:101], 0
	v_mfma_f32_16x16x32_bf16 v[20:23], v[16:19], v[12:15], v[20:23]
	v_mfma_f32_16x16x32_bf16 v[32:35], v[28:31], v[12:15], v[32:35]
	v_mfma_f32_16x16x32_bf16 v[44:47], v[40:43], v[12:15], v[44:47]
	v_mfma_f32_16x16x32_bf16 v[8:11], v[52:55], v[12:15], v[8:11]
	v_mfma_f32_16x16x32_bf16 v[12:15], v[16:19], v[60:63], v[64:67]
	v_mfma_f32_16x16x32_bf16 v[64:67], v[28:31], v[60:63], v[68:71]
	v_mfma_f32_16x16x32_bf16 v[68:71], v[40:43], v[60:63], v[72:75]
	v_mfma_f32_16x16x32_bf16 v[56:59], v[52:55], v[60:63], v[56:59]
	v_mfma_f32_16x16x32_bf16 v[60:63], v[16:19], v[80:83], v[84:87]
	v_mfma_f32_16x16x32_bf16 v[72:75], v[28:31], v[80:83], v[88:91]
	v_mfma_f32_16x16x32_bf16 v[84:87], v[40:43], v[80:83], v[92:95]
	s_nop 1
	global_load_dwordx4 v[88:91], v[108:109], off offset:128
	global_load_dwordx4 v[92:95], v[106:107], off offset:128
	v_mfma_f32_16x16x32_bf16 v[76:79], v[52:55], v[80:83], v[76:79]
	global_load_dwordx4 v[80:83], v[110:111], off offset:128
	global_load_dwordx4 v[98:101], v[112:113], off offset:128
	global_load_dwordx4 v[106:109], v[114:115], off offset:128
	s_waitcnt lgkmcnt(0)
	v_mfma_f32_16x16x32_bf16 v[4:7], v[16:19], v[102:105], v[4:7]
	global_load_dwordx4 v[16:19], v[116:117], off offset:128
	s_waitcnt lgkmcnt(0)
	s_barrier
	s_waitcnt vmcnt(0)
	ds_write_b128 v118, v[92:95]
	ds_write_b128 v118, v[80:83] offset:9216
	ds_write_b128 v118, v[98:101] offset:18432
	ds_write_b128 v118, v[106:109] offset:27648
	ds_write_b128 v118, v[88:91] offset:36864
	ds_write_b128 v118, v[16:19] offset:46080
	s_waitcnt lgkmcnt(0)
	s_barrier
	ds_read_b128 v[16:19], v0 offset:36864
	v_mfma_f32_16x16x32_bf16 v[24:27], v[28:31], v[102:105], v[24:27]
	v_mfma_f32_16x16x32_bf16 v[28:31], v[40:43], v[102:105], v[36:39]
	v_mfma_f32_16x16x32_bf16 v[36:39], v[52:55], v[102:105], v[48:51]
	ds_read_b128 v[40:43], v120
	s_nop 1
	ds_read_b128 v[48:51], v120 offset:64
	ds_read_b128 v[52:55], v0 offset:36928
	ds_read_b128 v[80:83], v0 offset:39168
	ds_read_b128 v[88:91], v0 offset:39232
	ds_read_b128 v[92:95], v0 offset:41472
	ds_read_b128 v[98:101], v0 offset:41536
	ds_read_b128 v[102:105], v0 offset:43776
	ds_read_b128 v[106:109], v0 offset:43840
	s_waitcnt lgkmcnt(8)
	v_mfma_f32_16x16x32_bf16 v[20:23], v[16:19], v[40:43], v[20:23]
	v_and_b32_e32 v0, 64, v3
	v_or_b32_e32 v3, s24, v97
	v_lshlrev_b32_e32 v97, 2, v122
	s_waitcnt lgkmcnt(5)
	v_mfma_f32_16x16x32_bf16 v[32:35], v[80:83], v[40:43], v[32:35]
	v_add_u32_e32 v122, v3, v123
	v_ashrrev_i32_e32 v123, 31, v122
	v_lshlrev_b64 v[118:119], 10, v[122:123]
	s_waitcnt lgkmcnt(3)
	v_mfma_f32_16x16x32_bf16 v[44:47], v[92:95], v[40:43], v[44:47]
	v_or3_b32 v0, v97, v0, s25
	v_lshlrev_b64 v[124:125], 1, v[0:1]
	s_waitcnt lgkmcnt(1)
	v_mfma_f32_16x16x32_bf16 v[8:11], v[102:105], v[40:43], v[8:11]
	ds_read_b128 v[40:43], v120 offset:2304
	ds_read_b128 v[110:113], v120 offset:2368
	s_waitcnt lgkmcnt(1)
	v_mfma_f32_16x16x32_bf16 v[12:15], v[16:19], v[40:43], v[12:15]
	v_mfma_f32_16x16x32_bf16 v[64:67], v[80:83], v[40:43], v[64:67]
	v_mfma_f32_16x16x32_bf16 v[68:71], v[92:95], v[40:43], v[68:71]
	v_mfma_f32_16x16x32_bf16 v[40:43], v[102:105], v[40:43], v[56:59]
	s_nop 2
	ds_read_b128 v[56:59], v120 offset:4608
	ds_read_b128 v[114:117], v120 offset:4672
	v_mfma_f32_16x16x32_bf16 v[20:23], v[52:55], v[48:51], v[20:23]
	s_waitcnt lgkmcnt(1)
	v_mfma_f32_16x16x32_bf16 v[60:63], v[16:19], v[56:59], v[60:63]
	v_mfma_f32_16x16x32_bf16 v[72:75], v[80:83], v[56:59], v[72:75]
	s_nop 4
	v_and_b32_sdwa v3, v20, v2 dst_sel:DWORD dst_unused:UNUSED_PAD src0_sel:WORD_1 src1_sel:DWORD
	v_and_b32_sdwa v97, v23, v2 dst_sel:DWORD dst_unused:UNUSED_PAD src0_sel:WORD_1 src1_sel:DWORD
	v_and_b32_sdwa v123, v21, v2 dst_sel:DWORD dst_unused:UNUSED_PAD src0_sel:WORD_1 src1_sel:DWORD
	v_mfma_f32_16x16x32_bf16 v[84:87], v[92:95], v[56:59], v[84:87]
	v_and_b32_sdwa v0, v22, v2 dst_sel:DWORD dst_unused:UNUSED_PAD src0_sel:WORD_1 src1_sel:DWORD
	v_add3_u32 v3, v20, v3, s23
	v_add3_u32 v20, v23, v97, s23
	v_mfma_f32_16x16x32_bf16 v[56:59], v[102:105], v[56:59], v[76:79]
	v_add3_u32 v21, v21, v123, s23
	v_add3_u32 v0, v22, v0, s23
	v_and_b32_e32 v20, 0xffff0000, v20
	v_lshl_add_u64 v[76:77], s[6:7], 0, v[118:119]
	v_lshl_add_u64 v[126:127], v[76:77], 0, v[124:125]
	ds_read_b128 v[76:79], v120 offset:6912
	ds_read_b128 v[118:121], v120 offset:6976
	v_mfma_f32_16x16x32_bf16 v[32:35], v[88:91], v[48:51], v[32:35]
	v_and_b32_e32 v21, 0xffff0000, v21
	s_waitcnt lgkmcnt(1)
	v_mfma_f32_16x16x32_bf16 v[4:7], v[16:19], v[76:79], v[4:7]
	v_or_b32_sdwa v17, v20, v0 dst_sel:DWORD dst_unused:UNUSED_PAD src0_sel:DWORD src1_sel:WORD_1
	v_or_b32_sdwa v16, v21, v3 dst_sel:DWORD dst_unused:UNUSED_PAD src0_sel:DWORD src1_sel:WORD_1
	flat_store_dwordx2 v[126:127], v[16:17]
	v_mfma_f32_16x16x32_bf16 v[16:19], v[80:83], v[76:79], v[24:27]
	s_nop 0
	v_and_b32_sdwa v0, v35, v2 dst_sel:DWORD dst_unused:UNUSED_PAD src0_sel:WORD_1 src1_sel:DWORD
	v_and_b32_sdwa v3, v33, v2 dst_sel:DWORD dst_unused:UNUSED_PAD src0_sel:WORD_1 src1_sel:DWORD
	v_and_b32_sdwa v128, v34, v2 dst_sel:DWORD dst_unused:UNUSED_PAD src0_sel:WORD_1 src1_sel:DWORD
	v_mfma_f32_16x16x32_bf16 v[24:27], v[98:101], v[48:51], v[44:47]
	v_and_b32_sdwa v129, v32, v2 dst_sel:DWORD dst_unused:UNUSED_PAD src0_sel:WORD_1 src1_sel:DWORD
	v_add3_u32 v0, v35, v0, s23
	v_add3_u32 v3, v33, v3, s23
	v_add3_u32 v32, v32, v129, s23
	v_add3_u32 v34, v34, v128, s23
	v_and_b32_e32 v0, 0xffff0000, v0
	v_and_b32_e32 v3, 0xffff0000, v3
	v_mfma_f32_16x16x32_bf16 v[20:23], v[92:95], v[76:79], v[28:31]
	s_nop 2
	v_or_b32_sdwa v29, v0, v34 dst_sel:DWORD dst_unused:UNUSED_PAD src0_sel:DWORD src1_sel:WORD_1
	v_or_b32_sdwa v28, v3, v32 dst_sel:DWORD dst_unused:UNUSED_PAD src0_sel:DWORD src1_sel:WORD_1
	v_and_b32_sdwa v0, v26, v2 dst_sel:DWORD dst_unused:UNUSED_PAD src0_sel:WORD_1 src1_sel:DWORD
	v_and_b32_sdwa v3, v24, v2 dst_sel:DWORD dst_unused:UNUSED_PAD src0_sel:WORD_1 src1_sel:DWORD
	v_mfma_f32_16x16x32_bf16 v[8:11], v[106:109], v[48:51], v[8:11]
	v_add3_u32 v3, v24, v3, s23
	v_add3_u32 v0, v26, v0, s23
	v_and_b32_sdwa v24, v27, v2 dst_sel:DWORD dst_unused:UNUSED_PAD src0_sel:WORD_1 src1_sel:DWORD
	v_and_b32_sdwa v26, v25, v2 dst_sel:DWORD dst_unused:UNUSED_PAD src0_sel:WORD_1 src1_sel:DWORD
	v_add3_u32 v24, v27, v24, s23
	v_add3_u32 v25, v25, v26, s23
	v_and_b32_e32 v32, 0xffff0000, v24
	v_and_b32_e32 v34, 0xffff0000, v25
	v_mfma_f32_16x16x32_bf16 v[12:15], v[52:55], v[110:113], v[12:15]
	v_or_b32_sdwa v33, v32, v0 dst_sel:DWORD dst_unused:UNUSED_PAD src0_sel:DWORD src1_sel:WORD_1
	v_or_b32_sdwa v32, v34, v3 dst_sel:DWORD dst_unused:UNUSED_PAD src0_sel:DWORD src1_sel:WORD_1
	v_and_b32_sdwa v0, v10, v2 dst_sel:DWORD dst_unused:UNUSED_PAD src0_sel:WORD_1 src1_sel:DWORD
	v_and_b32_sdwa v3, v8, v2 dst_sel:DWORD dst_unused:UNUSED_PAD src0_sel:WORD_1 src1_sel:DWORD
	v_add3_u32 v3, v8, v3, s23
	v_add3_u32 v0, v10, v0, s23
	v_and_b32_sdwa v8, v11, v2 dst_sel:DWORD dst_unused:UNUSED_PAD src0_sel:WORD_1 src1_sel:DWORD
	v_and_b32_sdwa v10, v9, v2 dst_sel:DWORD dst_unused:UNUSED_PAD src0_sel:WORD_1 src1_sel:DWORD
	v_add3_u32 v8, v11, v8, s23
	v_add3_u32 v44, v9, v10, s23
	flat_store_dwordx2 v[126:127], v[28:29] offset:32
	v_mfma_f32_16x16x32_bf16 v[28:31], v[102:105], v[76:79], v[36:39]
	v_and_b32_e32 v45, 0xffff0000, v8
	v_and_b32_e32 v44, 0xffff0000, v44
	v_or_b32_sdwa v49, v45, v0 dst_sel:DWORD dst_unused:UNUSED_PAD src0_sel:DWORD src1_sel:WORD_1
	v_mfma_f32_16x16x32_bf16 v[24:27], v[88:91], v[110:113], v[64:67]
	v_or_b32_sdwa v48, v44, v3 dst_sel:DWORD dst_unused:UNUSED_PAD src0_sel:DWORD src1_sel:WORD_1
	v_and_b32_sdwa v0, v14, v2 dst_sel:DWORD dst_unused:UNUSED_PAD src0_sel:WORD_1 src1_sel:DWORD
	v_and_b32_sdwa v3, v12, v2 dst_sel:DWORD dst_unused:UNUSED_PAD src0_sel:WORD_1 src1_sel:DWORD
	v_add3_u32 v3, v12, v3, s23
	v_add3_u32 v0, v14, v0, s23
	v_and_b32_sdwa v12, v15, v2 dst_sel:DWORD dst_unused:UNUSED_PAD src0_sel:WORD_1 src1_sel:DWORD
	v_and_b32_sdwa v14, v13, v2 dst_sel:DWORD dst_unused:UNUSED_PAD src0_sel:WORD_1 src1_sel:DWORD
	v_mfma_f32_16x16x32_bf16 v[36:39], v[106:109], v[110:113], v[40:43]
	v_add3_u32 v12, v15, v12, s23
	flat_store_dwordx2 v[126:127], v[32:33] offset:64
	flat_store_dwordx2 v[126:127], v[48:49] offset:96
	v_mfma_f32_16x16x32_bf16 v[40:43], v[52:55], v[114:117], v[60:63]
	s_waitcnt lgkmcnt(0)
	v_mfma_f32_16x16x32_bf16 v[4:7], v[52:55], v[118:121], v[4:7]
	v_add3_u32 v52, v13, v14, s23
	v_and_b32_e32 v53, 0xffff0000, v12
	v_or_b32_e32 v60, 16, v122
	v_mfma_f32_16x16x32_bf16 v[12:15], v[106:109], v[118:121], v[28:31]
	v_ashrrev_i32_e32 v61, 31, v60
	s_nop 1
	v_and_b32_e32 v28, 0xffff0000, v52
	v_or_b32_sdwa v29, v53, v0 dst_sel:DWORD dst_unused:UNUSED_PAD src0_sel:DWORD src1_sel:WORD_1
	v_or_b32_sdwa v28, v28, v3 dst_sel:DWORD dst_unused:UNUSED_PAD src0_sel:DWORD src1_sel:WORD_1
	v_and_b32_sdwa v0, v26, v2 dst_sel:DWORD dst_unused:UNUSED_PAD src0_sel:WORD_1 src1_sel:DWORD
	v_and_b32_sdwa v3, v24, v2 dst_sel:DWORD dst_unused:UNUSED_PAD src0_sel:WORD_1 src1_sel:DWORD
	v_mfma_f32_16x16x32_bf16 v[32:35], v[98:101], v[110:113], v[68:71]
	v_add3_u32 v3, v24, v3, s23
	v_add3_u32 v0, v26, v0, s23
	v_and_b32_sdwa v24, v27, v2 dst_sel:DWORD dst_unused:UNUSED_PAD src0_sel:WORD_1 src1_sel:DWORD
	v_and_b32_sdwa v26, v25, v2 dst_sel:DWORD dst_unused:UNUSED_PAD src0_sel:WORD_1 src1_sel:DWORD
	v_mfma_f32_16x16x32_bf16 v[48:51], v[106:109], v[114:117], v[56:59]
	v_add3_u32 v24, v27, v24, s23
	v_add3_u32 v25, v25, v26, s23
	v_and_b32_e32 v24, 0xffff0000, v24
	v_lshlrev_b64 v[56:57], 10, v[60:61]
	v_lshl_add_u64 v[56:57], s[6:7], 0, v[56:57]
	v_and_b32_e32 v26, 0xffff0000, v25
	v_lshl_add_u64 v[56:57], v[56:57], 0, v[124:125]
	v_or_b32_sdwa v25, v24, v0 dst_sel:DWORD dst_unused:UNUSED_PAD src0_sel:DWORD src1_sel:WORD_1
	v_or_b32_sdwa v24, v26, v3 dst_sel:DWORD dst_unused:UNUSED_PAD src0_sel:DWORD src1_sel:WORD_1
	flat_store_dwordx2 v[56:57], v[24:25] offset:32
	v_and_b32_sdwa v24, v35, v2 dst_sel:DWORD dst_unused:UNUSED_PAD src0_sel:WORD_1 src1_sel:DWORD
	v_and_b32_sdwa v25, v33, v2 dst_sel:DWORD dst_unused:UNUSED_PAD src0_sel:WORD_1 src1_sel:DWORD
	v_and_b32_sdwa v0, v34, v2 dst_sel:DWORD dst_unused:UNUSED_PAD src0_sel:WORD_1 src1_sel:DWORD
	v_and_b32_sdwa v3, v32, v2 dst_sel:DWORD dst_unused:UNUSED_PAD src0_sel:WORD_1 src1_sel:DWORD
	v_add3_u32 v24, v35, v24, s23
	v_add3_u32 v25, v33, v25, s23
	v_add3_u32 v3, v32, v3, s23
	v_add3_u32 v0, v34, v0, s23
	v_and_b32_e32 v24, 0xffff0000, v24
	v_and_b32_e32 v26, 0xffff0000, v25
	v_or_b32_sdwa v25, v24, v0 dst_sel:DWORD dst_unused:UNUSED_PAD src0_sel:DWORD src1_sel:WORD_1
	v_or_b32_sdwa v24, v26, v3 dst_sel:DWORD dst_unused:UNUSED_PAD src0_sel:DWORD src1_sel:WORD_1
	flat_store_dwordx2 v[56:57], v[24:25] offset:64
	v_and_b32_sdwa v24, v39, v2 dst_sel:DWORD dst_unused:UNUSED_PAD src0_sel:WORD_1 src1_sel:DWORD
	v_and_b32_sdwa v25, v37, v2 dst_sel:DWORD dst_unused:UNUSED_PAD src0_sel:WORD_1 src1_sel:DWORD
	v_and_b32_sdwa v0, v38, v2 dst_sel:DWORD dst_unused:UNUSED_PAD src0_sel:WORD_1 src1_sel:DWORD
	v_and_b32_sdwa v3, v36, v2 dst_sel:DWORD dst_unused:UNUSED_PAD src0_sel:WORD_1 src1_sel:DWORD
	v_add3_u32 v24, v39, v24, s23
	v_add3_u32 v25, v37, v25, s23
	v_mfma_f32_16x16x32_bf16 v[8:11], v[88:91], v[114:117], v[72:75]
	v_add3_u32 v3, v36, v3, s23
	v_add3_u32 v0, v38, v0, s23
	v_and_b32_e32 v24, 0xffff0000, v24
	v_and_b32_e32 v26, 0xffff0000, v25
	v_or_b32_sdwa v25, v24, v0 dst_sel:DWORD dst_unused:UNUSED_PAD src0_sel:DWORD src1_sel:WORD_1
	v_or_b32_sdwa v24, v26, v3 dst_sel:DWORD dst_unused:UNUSED_PAD src0_sel:DWORD src1_sel:WORD_1
	v_and_b32_sdwa v26, v43, v2 dst_sel:DWORD dst_unused:UNUSED_PAD src0_sel:WORD_1 src1_sel:DWORD
	v_and_b32_sdwa v27, v41, v2 dst_sel:DWORD dst_unused:UNUSED_PAD src0_sel:WORD_1 src1_sel:DWORD
	v_and_b32_sdwa v0, v42, v2 dst_sel:DWORD dst_unused:UNUSED_PAD src0_sel:WORD_1 src1_sel:DWORD
	v_and_b32_sdwa v3, v40, v2 dst_sel:DWORD dst_unused:UNUSED_PAD src0_sel:WORD_1 src1_sel:DWORD
	v_add3_u32 v26, v43, v26, s23
	v_add3_u32 v27, v41, v27, s23
	flat_store_dwordx2 v[56:57], v[28:29]
	v_add3_u32 v3, v40, v3, s23
	v_add3_u32 v0, v42, v0, s23
	v_and_b32_e32 v26, 0xffff0000, v26
	v_and_b32_e32 v28, 0xffff0000, v27
	flat_store_dwordx2 v[56:57], v[24:25] offset:96
	v_or_b32_e32 v24, 32, v122
	v_or_b32_sdwa v27, v26, v0 dst_sel:DWORD dst_unused:UNUSED_PAD src0_sel:DWORD src1_sel:WORD_1
	v_or_b32_sdwa v26, v28, v3 dst_sel:DWORD dst_unused:UNUSED_PAD src0_sel:DWORD src1_sel:WORD_1
	v_and_b32_sdwa v0, v10, v2 dst_sel:DWORD dst_unused:UNUSED_PAD src0_sel:WORD_1 src1_sel:DWORD
	v_and_b32_sdwa v3, v8, v2 dst_sel:DWORD dst_unused:UNUSED_PAD src0_sel:WORD_1 src1_sel:DWORD
	v_mfma_f32_16x16x32_bf16 v[44:47], v[98:101], v[114:117], v[84:87]
	v_ashrrev_i32_e32 v25, 31, v24
	v_add3_u32 v3, v8, v3, s23
	v_add3_u32 v0, v10, v0, s23
	v_and_b32_sdwa v8, v11, v2 dst_sel:DWORD dst_unused:UNUSED_PAD src0_sel:WORD_1 src1_sel:DWORD
	v_and_b32_sdwa v10, v9, v2 dst_sel:DWORD dst_unused:UNUSED_PAD src0_sel:WORD_1 src1_sel:DWORD
	v_lshlrev_b64 v[24:25], 10, v[24:25]
	v_add3_u32 v8, v11, v8, s23
	v_add3_u32 v9, v9, v10, s23
	v_lshl_add_u64 v[24:25], s[6:7], 0, v[24:25]
	v_and_b32_e32 v8, 0xffff0000, v8
	v_and_b32_e32 v10, 0xffff0000, v9
	v_lshl_add_u64 v[24:25], v[24:25], 0, v[124:125]
	v_or_b32_sdwa v9, v8, v0 dst_sel:DWORD dst_unused:UNUSED_PAD src0_sel:DWORD src1_sel:WORD_1
	v_or_b32_sdwa v8, v10, v3 dst_sel:DWORD dst_unused:UNUSED_PAD src0_sel:DWORD src1_sel:WORD_1
	flat_store_dwordx2 v[24:25], v[8:9] offset:32
	v_and_b32_sdwa v8, v47, v2 dst_sel:DWORD dst_unused:UNUSED_PAD src0_sel:WORD_1 src1_sel:DWORD
	v_and_b32_sdwa v9, v45, v2 dst_sel:DWORD dst_unused:UNUSED_PAD src0_sel:WORD_1 src1_sel:DWORD
	v_and_b32_sdwa v0, v46, v2 dst_sel:DWORD dst_unused:UNUSED_PAD src0_sel:WORD_1 src1_sel:DWORD
	v_and_b32_sdwa v3, v44, v2 dst_sel:DWORD dst_unused:UNUSED_PAD src0_sel:WORD_1 src1_sel:DWORD
	v_add3_u32 v8, v47, v8, s23
	v_add3_u32 v9, v45, v9, s23
	v_add3_u32 v3, v44, v3, s23
	v_add3_u32 v0, v46, v0, s23
	v_and_b32_e32 v8, 0xffff0000, v8
	v_and_b32_e32 v10, 0xffff0000, v9
	v_or_b32_sdwa v9, v8, v0 dst_sel:DWORD dst_unused:UNUSED_PAD src0_sel:DWORD src1_sel:WORD_1
	v_or_b32_sdwa v8, v10, v3 dst_sel:DWORD dst_unused:UNUSED_PAD src0_sel:DWORD src1_sel:WORD_1
	flat_store_dwordx2 v[24:25], v[8:9] offset:64
	v_and_b32_sdwa v8, v51, v2 dst_sel:DWORD dst_unused:UNUSED_PAD src0_sel:WORD_1 src1_sel:DWORD
	v_and_b32_sdwa v9, v49, v2 dst_sel:DWORD dst_unused:UNUSED_PAD src0_sel:WORD_1 src1_sel:DWORD
	v_and_b32_sdwa v0, v50, v2 dst_sel:DWORD dst_unused:UNUSED_PAD src0_sel:WORD_1 src1_sel:DWORD
	v_and_b32_sdwa v3, v48, v2 dst_sel:DWORD dst_unused:UNUSED_PAD src0_sel:WORD_1 src1_sel:DWORD
	v_add3_u32 v8, v51, v8, s23
	v_add3_u32 v9, v49, v9, s23
	v_add3_u32 v3, v48, v3, s23
	v_add3_u32 v0, v50, v0, s23
	v_and_b32_e32 v8, 0xffff0000, v8
	v_and_b32_e32 v10, 0xffff0000, v9
	v_or_b32_sdwa v9, v8, v0 dst_sel:DWORD dst_unused:UNUSED_PAD src0_sel:DWORD src1_sel:WORD_1
	v_or_b32_sdwa v8, v10, v3 dst_sel:DWORD dst_unused:UNUSED_PAD src0_sel:DWORD src1_sel:WORD_1
	flat_store_dwordx2 v[24:25], v[8:9] offset:96
	v_or_b32_e32 v8, 48, v122
	v_and_b32_sdwa v0, v6, v2 dst_sel:DWORD dst_unused:UNUSED_PAD src0_sel:WORD_1 src1_sel:DWORD
	v_and_b32_sdwa v3, v4, v2 dst_sel:DWORD dst_unused:UNUSED_PAD src0_sel:WORD_1 src1_sel:DWORD
	v_mfma_f32_16x16x32_bf16 v[16:19], v[88:91], v[118:121], v[16:19]
	v_ashrrev_i32_e32 v9, 31, v8
	v_add3_u32 v3, v4, v3, s23
	v_add3_u32 v0, v6, v0, s23
	v_and_b32_sdwa v4, v7, v2 dst_sel:DWORD dst_unused:UNUSED_PAD src0_sel:WORD_1 src1_sel:DWORD
	v_and_b32_sdwa v6, v5, v2 dst_sel:DWORD dst_unused:UNUSED_PAD src0_sel:WORD_1 src1_sel:DWORD
	v_lshlrev_b64 v[8:9], 10, v[8:9]
	v_add3_u32 v4, v7, v4, s23
	v_add3_u32 v5, v5, v6, s23
	v_lshl_add_u64 v[8:9], s[6:7], 0, v[8:9]
	v_and_b32_e32 v4, 0xffff0000, v4
	v_and_b32_e32 v6, 0xffff0000, v5
	v_lshl_add_u64 v[8:9], v[8:9], 0, v[124:125]
	v_or_b32_sdwa v5, v4, v0 dst_sel:DWORD dst_unused:UNUSED_PAD src0_sel:DWORD src1_sel:WORD_1
	v_or_b32_sdwa v4, v6, v3 dst_sel:DWORD dst_unused:UNUSED_PAD src0_sel:DWORD src1_sel:WORD_1
	v_mfma_f32_16x16x32_bf16 v[20:23], v[98:101], v[118:121], v[20:23]
	flat_store_dwordx2 v[8:9], v[4:5]
	v_and_b32_sdwa v4, v19, v2 dst_sel:DWORD dst_unused:UNUSED_PAD src0_sel:WORD_1 src1_sel:DWORD
	v_and_b32_sdwa v5, v17, v2 dst_sel:DWORD dst_unused:UNUSED_PAD src0_sel:WORD_1 src1_sel:DWORD
	v_and_b32_sdwa v0, v18, v2 dst_sel:DWORD dst_unused:UNUSED_PAD src0_sel:WORD_1 src1_sel:DWORD
	v_and_b32_sdwa v3, v16, v2 dst_sel:DWORD dst_unused:UNUSED_PAD src0_sel:WORD_1 src1_sel:DWORD
	v_add3_u32 v4, v19, v4, s23
	v_add3_u32 v5, v17, v5, s23
	v_add3_u32 v3, v16, v3, s23
	v_add3_u32 v0, v18, v0, s23
	v_and_b32_e32 v4, 0xffff0000, v4
	v_and_b32_e32 v6, 0xffff0000, v5
	v_or_b32_sdwa v5, v4, v0 dst_sel:DWORD dst_unused:UNUSED_PAD src0_sel:DWORD src1_sel:WORD_1
	v_or_b32_sdwa v4, v6, v3 dst_sel:DWORD dst_unused:UNUSED_PAD src0_sel:DWORD src1_sel:WORD_1
	flat_store_dwordx2 v[8:9], v[4:5] offset:32
	v_and_b32_sdwa v4, v23, v2 dst_sel:DWORD dst_unused:UNUSED_PAD src0_sel:WORD_1 src1_sel:DWORD
	v_and_b32_sdwa v5, v21, v2 dst_sel:DWORD dst_unused:UNUSED_PAD src0_sel:WORD_1 src1_sel:DWORD
	v_and_b32_sdwa v0, v22, v2 dst_sel:DWORD dst_unused:UNUSED_PAD src0_sel:WORD_1 src1_sel:DWORD
	v_and_b32_sdwa v3, v20, v2 dst_sel:DWORD dst_unused:UNUSED_PAD src0_sel:WORD_1 src1_sel:DWORD
	v_add3_u32 v4, v23, v4, s23
	v_add3_u32 v5, v21, v5, s23
	v_add3_u32 v3, v20, v3, s23
	v_add3_u32 v0, v22, v0, s23
	v_and_b32_e32 v4, 0xffff0000, v4
	v_and_b32_e32 v6, 0xffff0000, v5
	v_or_b32_sdwa v5, v4, v0 dst_sel:DWORD dst_unused:UNUSED_PAD src0_sel:DWORD src1_sel:WORD_1
	v_or_b32_sdwa v4, v6, v3 dst_sel:DWORD dst_unused:UNUSED_PAD src0_sel:DWORD src1_sel:WORD_1
	flat_store_dwordx2 v[8:9], v[4:5] offset:64
	v_and_b32_sdwa v4, v15, v2 dst_sel:DWORD dst_unused:UNUSED_PAD src0_sel:WORD_1 src1_sel:DWORD
	v_and_b32_sdwa v5, v13, v2 dst_sel:DWORD dst_unused:UNUSED_PAD src0_sel:WORD_1 src1_sel:DWORD
	v_and_b32_sdwa v0, v14, v2 dst_sel:DWORD dst_unused:UNUSED_PAD src0_sel:WORD_1 src1_sel:DWORD
	v_and_b32_sdwa v3, v12, v2 dst_sel:DWORD dst_unused:UNUSED_PAD src0_sel:WORD_1 src1_sel:DWORD
	v_add3_u32 v4, v15, v4, s23
	v_add3_u32 v5, v13, v5, s23
	v_add3_u32 v3, v12, v3, s23
	v_add3_u32 v0, v14, v0, s23
	v_and_b32_e32 v4, 0xffff0000, v4
	v_and_b32_e32 v6, 0xffff0000, v5
	v_or_b32_sdwa v5, v4, v0 dst_sel:DWORD dst_unused:UNUSED_PAD src0_sel:DWORD src1_sel:WORD_1
	v_or_b32_sdwa v4, v6, v3 dst_sel:DWORD dst_unused:UNUSED_PAD src0_sel:DWORD src1_sel:WORD_1
	flat_store_dwordx2 v[24:25], v[26:27]
	flat_store_dwordx2 v[8:9], v[4:5] offset:96
	s_waitcnt lgkmcnt(0)
	s_barrier
	s_cbranch_scc0 .LBB0_1140

.LBB0_1402:
	s_cmpk_gt_i32 s31, 0xbf
	s_cbranch_scc0 .LBB0_1406
	v_lshl_add_u64 v[20:21], s[20:21], 0, v[0:1]
	v_lshlrev_b64 v[22:23], 9, v[20:21]
	v_lshl_add_u64 v[40:41], v[4:5], 0, v[22:23]
	v_lshl_add_u64 v[42:43], v[6:7], 0, v[22:23]
	v_lshl_add_u64 v[22:23], v[8:9], 0, v[22:23]
	global_load_dwordx2 v[44:45], v[40:41], off
	global_load_dwordx2 v[46:47], v[42:43], off
	s_add_u32 s6, s90, s70
	global_load_dwordx2 v[22:23], v[22:23], off
	s_addc_u32 s7, s91, s24
	s_load_dwordx2 s[6:7], s[6:7], 0xb8
	v_lshlrev_b64 v[40:41], 11, v[20:21]
	v_lshl_add_u64 v[48:49], s[16:17], 0, v[40:41]
	s_waitcnt lgkmcnt(0)
	global_load_dwordx4 v[40:43], v29, s[6:7]
	s_waitcnt vmcnt(0)
	v_lshlrev_b32_e32 v50, 16, v44
	v_lshlrev_b32_e32 v52, 16, v46
	v_and_b32_e32 v51, 0xffff0000, v44
	v_and_b32_e32 v53, 0xffff0000, v46
	v_lshlrev_b32_e32 v44, 16, v45
	v_lshlrev_b32_e32 v46, 16, v47
	v_and_b32_e32 v45, 0xffff0000, v45
	v_and_b32_e32 v47, 0xffff0000, v47
	v_lshlrev_b32_e32 v56, 16, v22
	v_and_b32_e32 v57, 0xffff0000, v22
	v_lshlrev_b32_e32 v58, 16, v23
	v_and_b32_e32 v59, 0xffff0000, v23
	v_pk_add_f32 v[22:23], v[44:45], v[46:47]
	v_pk_add_f32 v[44:45], v[50:51], v[52:53]
	v_mul_f32_e32 v52, 0xbfb8aa3b, v56
	v_mul_f32_e32 v53, 0xbfb8aa3b, v57
	v_mul_f32_e32 v54, 0xbfb8aa3b, v58
	v_mul_f32_e32 v55, 0xbfb8aa3b, v59
	v_exp_f32_e32 v52, v52
	v_exp_f32_e32 v53, v53
	v_pk_mul_f32 v[50:51], v[44:45], v[44:45]
	v_exp_f32_e32 v54, v54
	v_exp_f32_e32 v55, v55
	v_pk_mul_f32 v[46:47], v[22:23], v[22:23]
	v_add_f32_e32 v50, v50, v51
	v_add_f32_e32 v46, v46, v50
	v_add_f32_e32 v50, v47, v46
	v_pk_add_f32 v[46:47], v[52:53], 1.0 op_sel_hi:[1,0]
	s_nop 0
	v_add_f32_dpp v52, v50, v50 quad_perm:[1,0,3,2] row_mask:0xf bank_mask:0xf bound_ctrl:1
	v_pk_add_f32 v[50:51], v[54:55], 1.0 op_sel_hi:[1,0]
	v_div_scale_f32 v53, s[6:7], v47, v47, v57
	v_div_scale_f32 v55, s[6:7], v46, v46, v56
	v_add_f32_dpp v52, v52, v52 quad_perm:[2,3,0,1] row_mask:0xf bank_mask:0xf bound_ctrl:1
	v_div_scale_f32 v61, s[8:9], v51, v51, v59
	v_rcp_f32_e32 v64, v53
	v_rcp_f32_e32 v65, v55
	v_add_f32_dpp v52, v52, v52 row_half_mirror row_mask:0xf bank_mask:0xf bound_ctrl:1
	v_rcp_f32_e32 v66, v61
	v_div_scale_f32 v63, s[10:11], v50, v50, v58
	v_add_f32_dpp v52, v52, v52 row_mirror row_mask:0xf bank_mask:0xf bound_ctrl:1
	v_fmamk_f32 v52, v52, 0x3c800000, v30
	v_mul_f32_e32 v68, 0x4b800000, v52
	v_fma_f32 v69, -v53, v64, 1.0
	v_cmp_gt_f32_e64 s[10:11], s30, v52
	v_div_scale_f32 v54, vcc, v57, v47, v57
	v_fma_f32 v70, -v55, v65, 1.0
	v_cndmask_b32_e64 v52, v52, v68, s[10:11]
	v_fma_f32 v68, -v61, v66, 1.0
	v_fmac_f32_e32 v64, v69, v64
	v_div_scale_f32 v60, s[6:7], v56, v46, v56
	v_fmac_f32_e32 v65, v70, v65
	v_rsq_f32_e32 v52, v52
	v_fmac_f32_e32 v66, v68, v66
	v_mul_f32_e32 v68, v54, v64
	v_mul_f32_e32 v69, v60, v65
	v_fma_f32 v72, -v53, v68, v54
	v_div_scale_f32 v62, s[8:9], v59, v51, v59
	v_fma_f32 v73, -v55, v69, v60
	v_fmac_f32_e32 v68, v72, v64
	v_rcp_f32_e32 v67, v63
	v_mul_f32_e32 v70, v62, v66
	v_fmac_f32_e32 v69, v73, v65
	v_fma_f32 v53, -v53, v68, v54
	v_fma_f32 v74, -v61, v70, v62
	v_fma_f32 v54, -v55, v69, v60
	v_mul_f32_e32 v55, 0x45800000, v52
	v_div_fmas_f32 v53, v53, v64, v68
	s_mov_b64 vcc, s[6:7]
	v_fmac_f32_e32 v70, v74, v66
	v_cndmask_b32_e64 v52, v52, v55, s[10:11]
	v_div_fixup_f32 v47, v53, v47, v57
	v_div_fmas_f32 v53, v54, v65, v69
	v_fma_f32 v60, -v61, v70, v62
	v_pk_mul_f32 v[22:23], v[22:23], v[52:53] op_sel_hi:[1,0]
	s_mov_b64 vcc, s[8:9]
	v_fma_f32 v71, -v63, v67, 1.0
	v_pk_mul_f32 v[22:23], v[42:43], v[22:23]
	v_div_fmas_f32 v42, v60, v66, v70
	v_pk_mul_f32 v[44:45], v[44:45], v[52:53] op_sel_hi:[1,0]
	v_div_fixup_f32 v43, v42, v51, v59
	v_fmac_f32_e32 v67, v71, v67
	v_div_scale_f32 v42, vcc, v58, v50, v58
	v_pk_mul_f32 v[40:41], v[40:41], v[44:45]
	v_mul_f32_e32 v44, v42, v67
	v_fma_f32 v45, -v63, v44, v42
	v_fmac_f32_e32 v44, v45, v67
	v_fma_f32 v42, -v63, v44, v42
	v_div_fmas_f32 v42, v42, v67, v44
	v_div_fixup_f32 v46, v53, v46, v56
	v_div_fixup_f32 v42, v42, v50, v58
	v_pk_mul_f32 v[40:41], v[46:47], v[40:41]
	v_pk_mul_f32 v[22:23], v[42:43], v[22:23]
	v_lshl_add_u64 v[42:43], v[48:49], 0, v[2:3]
	v_cvt_pk_bf16_f32 v40, v40, v41
	v_cvt_pk_bf16_f32 v41, v22, v23
	v_add_co_u32_e32 v22, vcc, 0x4552000, v42
	s_mov_b64 s[8:9], 0
	s_nop 0
	v_addc_co_u32_e32 v23, vcc, 0, v43, vcc
	flat_store_dwordx2 v[22:23], v[40:41] offset:1024 sc1
	s_waitcnt vmcnt(0)
	s_mov_b64 s[6:7], 0
	s_and_saveexec_b64 s[10:11], s[4:5]
	s_xor_b64 s[10:11], exec, s[10:11]
	v_ashrrev_i64 v[22:23], 2, v[20:21]
	s_mov_b64 s[6:7], exec
	v_and_b32_e32 v22, 0xffffffc0, v22
	s_or_b64 exec, exec, s[10:11]
	s_and_b64 vcc, exec, s[8:9]
	s_cbranch_vccnz .LBB0_1407
	s_branch .LBB0_1410

.LBB0_1407:
	s_ashr_i32 s23, s22, 31
	v_lshl_add_u64 v[40:41], s[22:23], 1, v[10:11]
	v_lshl_add_u64 v[20:21], v[40:41], 0, v[12:13]
	s_waitcnt lgkmcnt(0)
	s_barrier
	global_load_dwordx4 v[20:23], v[20:21], off
	v_lshl_add_u64 v[42:43], v[40:41], 0, v[14:15]
	v_add_u32_e32 v52, v28, v25
	v_add_u32_e32 v53, v27, v25
	v_add_u32_e32 v54, v26, v25
	v_add_u32_e32 v55, v24, v25
	s_waitcnt vmcnt(0) lgkmcnt(0)
	ds_write_b16 v31, v20
	ds_write_b16_d16_hi v31, v20 offset:528
	ds_write_b16 v31, v21 offset:1056
	ds_write_b16_d16_hi v31, v21 offset:1584
	ds_write_b16 v31, v22 offset:2112
	ds_write_b16_d16_hi v31, v22 offset:2640
	ds_write_b16 v31, v23 offset:3168
	ds_write_b16_d16_hi v31, v23 offset:3696
	global_load_dwordx4 v[20:23], v[42:43], off
	v_lshl_add_u64 v[42:43], v[40:41], 0, v[16:17]
	v_lshl_add_u64 v[40:41], v[40:41], 0, v[18:19]
	s_waitcnt vmcnt(0) lgkmcnt(0)
	ds_write_b16 v32, v20
	ds_write_b16_d16_hi v32, v20 offset:528
	ds_write_b16 v32, v21 offset:1056
	ds_write_b16_d16_hi v32, v21 offset:1584
	ds_write_b16 v32, v22 offset:2112
	ds_write_b16_d16_hi v32, v22 offset:2640
	ds_write_b16 v32, v23 offset:3168
	ds_write_b16_d16_hi v32, v23 offset:3696
	global_load_dwordx4 v[20:23], v[42:43], off
	s_waitcnt vmcnt(0) lgkmcnt(0)
	ds_write_b16 v33, v20
	ds_write_b16_d16_hi v33, v20 offset:528
	ds_write_b16 v33, v21 offset:1056
	ds_write_b16_d16_hi v33, v21 offset:1584
	ds_write_b16 v33, v22 offset:2112
	ds_write_b16_d16_hi v33, v22 offset:2640
	ds_write_b16 v33, v23 offset:3168
	ds_write_b16_d16_hi v33, v23 offset:3696
	global_load_dwordx4 v[20:23], v[40:41], off
	s_waitcnt vmcnt(0) lgkmcnt(0)
	ds_write_b16 v34, v20
	ds_write_b16_d16_hi v34, v20 offset:528
	ds_write_b16 v34, v21 offset:1056
	ds_write_b16_d16_hi v34, v21 offset:1584
	ds_write_b16 v34, v22 offset:2112
	ds_write_b16_d16_hi v34, v22 offset:2640
	ds_write_b16 v34, v23 offset:3168
	ds_write_b16_d16_hi v34, v23 offset:3696
	s_waitcnt lgkmcnt(0)
	s_barrier
	ds_read_b128 v[20:23], v35
	ds_read_b128 v[40:43], v36
	ds_read_b128 v[44:47], v37
	ds_read_b128 v[48:51], v38
	s_waitcnt lgkmcnt(3)
	buffer_store_dwordx4 v[20:23], v52, s[12:15], 0 offen sc1
	s_waitcnt lgkmcnt(2)
	buffer_store_dwordx4 v[40:43], v53, s[12:15], 0 offen sc1
	s_waitcnt lgkmcnt(1)
	buffer_store_dwordx4 v[44:47], v54, s[12:15], 0 offen sc1
	s_waitcnt lgkmcnt(0)
	buffer_store_dwordx4 v[48:51], v55, s[12:15], 0 offen sc1
	s_waitcnt vmcnt(0)
	s_and_saveexec_b64 s[10:11], s[4:5]
	s_and_b32 s8, s28, 0xffffffc0
	s_ashr_i32 s9, s8, 31
	s_or_b64 s[6:7], s[6:7], exec
	s_or_b64 exec, exec, s[10:11]
	v_mov_b64_e32 v[22:23], s[8:9]

.LBB0_1413:
	s_andn2_b64 vcc, exec, s[4:5]
	s_cbranch_vccnz .LBB0_1431
	s_cmpk_gt_i32 s3, 0xbf
	v_ashrrev_i32_e32 v4, 6, v150
	v_and_b32_e32 v74, 63, v150
	s_cbranch_scc0 .LBB0_1420
	s_mul_i32 s4, s3, 0x48
	s_addk_i32 s4, 0xe800
	s_mov_b32 s5, 0
	v_ashrrev_i32_e32 v5, 31, v4
	v_lshlrev_b32_e32 v8, 3, v74
	v_mov_b32_e32 v9, 0
	v_lshl_add_u64 v[6:7], s[4:5], 0, v[4:5]
	v_lshl_add_u64 v[0:1], s[16:17], 0, v[8:9]
	s_mov_b64 s[4:5], 0x6952000
	s_waitcnt vmcnt(0)
	v_lshl_add_u64 v[26:27], v[0:1], 0, s[4:5]
	s_mov_b64 s[4:5], 0x6f52000
	v_lshl_add_u64 v[28:29], v[0:1], 0, s[4:5]
	s_mov_b64 s[4:5], 0xcb32000
	v_lshlrev_b64 v[2:3], 9, v[6:7]
	v_lshl_add_u64 v[30:31], v[0:1], 0, s[4:5]
	v_lshl_add_u64 v[10:11], v[26:27], 0, v[2:3]
	v_lshl_add_u64 v[0:1], v[30:31], 0, v[2:3]
	v_lshl_add_u64 v[12:13], v[28:29], 0, v[2:3]
	global_load_dwordx2 v[76:77], v[10:11], off
	global_load_dwordx2 v[78:79], v[12:13], off
	global_load_dwordx2 v[80:81], v[0:1], off
	v_lshl_add_u64 v[10:11], v[6:7], 0, 8
	v_lshlrev_b64 v[0:1], 9, v[10:11]
	v_lshl_add_u64 v[2:3], v[26:27], 0, v[0:1]
	v_lshl_add_u64 v[12:13], v[6:7], 0, 16
	global_load_dwordx2 v[70:71], v[2:3], off
	v_lshl_add_u64 v[2:3], v[28:29], 0, v[0:1]
	v_lshl_add_u64 v[0:1], v[30:31], 0, v[0:1]
	v_lshlrev_b64 v[14:15], 9, v[12:13]
	v_lshl_add_u64 v[16:17], v[26:27], 0, v[14:15]
	v_lshl_add_u64 v[18:19], v[28:29], 0, v[14:15]
	global_load_dwordx2 v[72:73], v[2:3], off
	global_load_dwordx2 v[68:69], v[0:1], off
	global_load_dwordx2 v[64:65], v[16:17], off
	global_load_dwordx2 v[66:67], v[18:19], off
	v_lshl_add_u64 v[0:1], v[30:31], 0, v[14:15]
	v_lshl_add_u64 v[14:15], v[6:7], 0, 24
	v_lshlrev_b64 v[2:3], 9, v[14:15]
	v_lshl_add_u64 v[16:17], v[26:27], 0, v[2:3]
	v_lshl_add_u64 v[18:19], v[28:29], 0, v[2:3]
	v_lshl_add_u64 v[2:3], v[30:31], 0, v[2:3]
	global_load_dwordx2 v[44:45], v[0:1], off
	global_load_dwordx2 v[60:61], v[16:17], off
	global_load_dwordx2 v[62:63], v[18:19], off
	global_load_dwordx2 v[58:59], v[2:3], off
	v_lshl_add_u64 v[16:17], v[6:7], 0, 32
	v_lshlrev_b64 v[0:1], 9, v[16:17]
	v_lshl_add_u64 v[18:19], v[6:7], 0, 40
	v_lshl_add_u64 v[2:3], v[26:27], 0, v[0:1]
	v_lshl_add_u64 v[20:21], v[28:29], 0, v[0:1]
	v_lshlrev_b64 v[22:23], 9, v[18:19]
	s_ashr_i32 s5, s70, 31
	v_lshl_add_u64 v[0:1], v[30:31], 0, v[0:1]
	v_lshl_add_u64 v[24:25], v[26:27], 0, v[22:23]
	global_load_dwordx2 v[54:55], v[2:3], off
	global_load_dwordx2 v[56:57], v[20:21], off
	global_load_dwordx2 v[52:53], v[0:1], off
	global_load_dwordx2 v[48:49], v[24:25], off
	v_lshl_add_u64 v[20:21], v[6:7], 0, 48
	s_add_u32 s4, s90, s70
	v_lshl_add_u64 v[0:1], v[28:29], 0, v[22:23]
	v_lshl_add_u64 v[2:3], v[30:31], 0, v[22:23]
	v_lshlrev_b64 v[22:23], 9, v[20:21]
	s_addc_u32 s5, s91, s5
	v_lshl_add_u64 v[24:25], v[26:27], 0, v[22:23]
	v_lshl_add_u64 v[32:33], v[28:29], 0, v[22:23]
	global_load_dwordx2 v[50:51], v[0:1], off
	global_load_dwordx2 v[46:47], v[2:3], off
	global_load_dwordx2 v[38:39], v[24:25], off
	global_load_dwordx2 v[40:41], v[32:33], off
	s_load_dwordx2 s[4:5], s[4:5], 0xb8
	v_lshl_add_u64 v[0:1], v[30:31], 0, v[22:23]
	v_lshl_add_u64 v[22:23], v[6:7], 0, 56
	v_lshlrev_b64 v[2:3], 9, v[22:23]
	v_lshl_add_u64 v[24:25], v[26:27], 0, v[2:3]
	v_lshl_add_u64 v[82:83], v[28:29], 0, v[2:3]
	v_lshl_add_u64 v[2:3], v[30:31], 0, v[2:3]
	global_load_dwordx2 v[42:43], v[0:1], off
	global_load_dwordx2 v[34:35], v[24:25], off
	global_load_dwordx2 v[36:37], v[82:83], off
	global_load_dwordx2 v[32:33], v[2:3], off
	v_lshlrev_b32_e32 v0, 4, v150
	v_and_b32_e32 v0, 0xf0, v0
	s_waitcnt lgkmcnt(0)
	global_load_dwordx4 v[0:3], v0, s[4:5]
	v_lshl_add_u64 v[24:25], v[6:7], 0, 64
	v_lshlrev_b64 v[82:83], 9, v[24:25]
	v_lshl_add_u64 v[84:85], v[26:27], 0, v[82:83]
	v_lshl_add_u64 v[86:87], v[28:29], 0, v[82:83]
	v_lshl_add_u64 v[82:83], v[30:31], 0, v[82:83]
	global_load_dwordx2 v[28:29], v[84:85], off
	global_load_dwordx2 v[30:31], v[86:87], off
	global_load_dwordx2 v[26:27], v[82:83], off
	s_mov_b32 s7, 0x800000
	s_mov_b32 s8, 0x4552000
	s_mov_b32 s6, 0x3c800000
	s_mov_b64 s[10:11], 0
	s_waitcnt vmcnt(0)
	v_lshlrev_b32_e32 v82, 16, v76
	v_lshlrev_b32_e32 v84, 16, v78
	v_lshlrev_b32_e32 v5, 16, v80
	v_and_b32_e32 v75, 0xffff0000, v80
	v_mul_f32_e32 v80, 0xbfb8aa3b, v5
	v_exp_f32_e32 v86, v80
	v_mul_f32_e32 v80, 0xbfb8aa3b, v75
	v_exp_f32_e32 v87, v80
	v_and_b32_e32 v83, 0xffff0000, v76
	v_and_b32_e32 v85, 0xffff0000, v78
	v_lshlrev_b32_e32 v76, 16, v77
	v_lshlrev_b32_e32 v78, 16, v79
	v_and_b32_e32 v77, 0xffff0000, v77
	v_and_b32_e32 v79, 0xffff0000, v79
	v_pk_add_f32 v[76:77], v[76:77], v[78:79]
	v_pk_add_f32 v[78:79], v[86:87], 1.0 op_sel_hi:[1,0]
	v_pk_add_f32 v[82:83], v[82:83], v[84:85]
	v_div_scale_f32 v86, s[4:5], v79, v79, v75
	v_rcp_f32_e32 v87, v86
	v_pk_mul_f32 v[84:85], v[82:83], v[82:83]
	v_lshlrev_b32_e32 v88, 16, v81
	v_and_b32_e32 v89, 0xffff0000, v81
	v_fma_f32 v90, -v86, v87, 1.0
	v_fmac_f32_e32 v87, v90, v87
	v_div_scale_f32 v90, vcc, v75, v79, v75
	v_mul_f32_e32 v91, v90, v87
	v_fma_f32 v92, -v86, v91, v90
	v_fmac_f32_e32 v91, v92, v87
	v_fma_f32 v86, -v86, v91, v90
	v_div_scale_f32 v90, s[4:5], v78, v78, v5
	v_rcp_f32_e32 v92, v90
	v_pk_mul_f32 v[80:81], v[76:77], v[76:77]
	v_add_f32_e32 v84, v84, v85
	v_div_fmas_f32 v86, v86, v87, v91
	v_add_f32_e32 v80, v84, v80
	v_div_fixup_f32 v79, v86, v79, v75
	v_fma_f32 v75, -v90, v92, 1.0
	v_add_f32_e32 v80, v81, v80
	v_fmac_f32_e32 v92, v75, v92
	v_div_scale_f32 v75, vcc, v5, v78, v5
	v_add_f32_dpp v80, v80, v80 quad_perm:[1,0,3,2] row_mask:0xf bank_mask:0xf bound_ctrl:1
	v_mul_f32_e32 v86, v75, v92
	v_fma_f32 v87, -v90, v86, v75
	v_add_f32_dpp v80, v80, v80 quad_perm:[2,3,0,1] row_mask:0xf bank_mask:0xf bound_ctrl:1
	v_fmac_f32_e32 v86, v87, v92
	v_mov_b32_e32 v81, 0x358637bd
	v_add_f32_dpp v80, v80, v80 row_half_mirror row_mask:0xf bank_mask:0xf bound_ctrl:1
	v_fma_f32 v75, -v90, v86, v75
	v_div_fmas_f32 v75, v75, v92, v86
	v_add_f32_dpp v80, v80, v80 row_mirror row_mask:0xf bank_mask:0xf bound_ctrl:1
	v_fmac_f32_e32 v81, 0x3c800000, v80
	v_mul_f32_e32 v80, 0x4b800000, v81
	v_cmp_gt_f32_e64 s[4:5], s7, v81
	v_div_fixup_f32 v78, v75, v78, v5
	v_mul_f32_e32 v75, 0xbfb8aa3b, v88
	v_cndmask_b32_e64 v80, v81, v80, s[4:5]
	v_rsq_f32_e32 v84, v80
	v_exp_f32_e32 v80, v75
	v_mul_f32_e32 v75, 0xbfb8aa3b, v89
	v_exp_f32_e32 v81, v75
	v_mul_f32_e32 v5, 0x45800000, v84
	v_cndmask_b32_e64 v84, v84, v5, s[4:5]
	v_pk_mul_f32 v[82:83], v[82:83], v[84:85] op_sel_hi:[1,0]
	v_pk_add_f32 v[80:81], v[80:81], 1.0 op_sel_hi:[1,0]
	v_pk_mul_f32 v[82:83], v[0:1], v[82:83]
	v_div_scale_f32 v5, s[4:5], v81, v81, v89
	v_rcp_f32_e32 v75, v5
	v_pk_mul_f32 v[78:79], v[78:79], v[82:83]
	v_pk_mul_f32 v[76:77], v[76:77], v[84:85] op_sel_hi:[1,0]
	v_cvt_pk_bf16_f32 v78, v78, v79
	v_fma_f32 v82, -v5, v75, 1.0
	v_fmac_f32_e32 v75, v82, v75
	v_div_scale_f32 v82, vcc, v89, v81, v89
	v_mul_f32_e32 v83, v82, v75
	v_fma_f32 v84, -v5, v83, v82
	v_fmac_f32_e32 v83, v84, v75
	v_fma_f32 v5, -v5, v83, v82
	v_div_scale_f32 v82, s[4:5], v80, v80, v88
	v_rcp_f32_e32 v84, v82
	v_div_fmas_f32 v5, v5, v75, v83
	v_div_fixup_f32 v81, v5, v81, v89
	v_pk_mul_f32 v[76:77], v[2:3], v[76:77]
	v_fma_f32 v5, -v82, v84, 1.0
	v_fmac_f32_e32 v84, v5, v84
	v_div_scale_f32 v5, vcc, v88, v80, v88
	v_mul_f32_e32 v75, v5, v84
	v_fma_f32 v83, -v82, v75, v5
	v_fmac_f32_e32 v75, v83, v84
	v_fma_f32 v5, -v82, v75, v5
	v_div_fmas_f32 v5, v5, v84, v75
	v_div_fixup_f32 v80, v5, v80, v88
	v_pk_mul_f32 v[76:77], v[80:81], v[76:77]
	v_lshlrev_b32_e32 v5, 16, v68
	v_cvt_pk_bf16_f32 v79, v76, v77
	v_lshlrev_b64 v[76:77], 11, v[6:7]
	v_and_b32_e32 v75, 0xffff0000, v68
	v_mul_f32_e32 v68, 0xbfb8aa3b, v5
	v_lshl_add_u64 v[76:77], s[16:17], 0, v[76:77]
	v_exp_f32_e32 v80, v68
	v_mul_f32_e32 v68, 0xbfb8aa3b, v75
	v_lshl_add_u64 v[76:77], v[76:77], 0, v[8:9]
	v_exp_f32_e32 v81, v68
	v_add_co_u32_e32 v76, vcc, s8, v76
	v_lshlrev_b32_e32 v82, 16, v69
	s_nop 0
	v_addc_co_u32_e32 v77, vcc, 0, v77, vcc
	flat_store_dwordx2 v[76:77], v[78:79] offset:1024 sc1
	v_lshlrev_b32_e32 v76, 16, v70
	v_lshlrev_b32_e32 v78, 16, v72
	v_and_b32_e32 v77, 0xffff0000, v70
	v_and_b32_e32 v79, 0xffff0000, v72
	v_lshlrev_b32_e32 v70, 16, v71
	v_lshlrev_b32_e32 v72, 16, v73
	v_and_b32_e32 v71, 0xffff0000, v71
	v_and_b32_e32 v73, 0xffff0000, v73
	v_and_b32_e32 v83, 0xffff0000, v69
	v_pk_add_f32 v[68:69], v[70:71], v[72:73]
	v_pk_add_f32 v[70:71], v[80:81], 1.0 op_sel_hi:[1,0]
	v_pk_add_f32 v[76:77], v[76:77], v[78:79]
	v_div_scale_f32 v80, s[4:5], v71, v71, v75
	v_rcp_f32_e32 v81, v80
	v_pk_mul_f32 v[78:79], v[76:77], v[76:77]
	v_pk_mul_f32 v[72:73], v[68:69], v[68:69]
	v_lshlrev_b32_e32 v90, 16, v45
	v_fma_f32 v84, -v80, v81, 1.0
	v_fmac_f32_e32 v81, v84, v81
	v_div_scale_f32 v84, vcc, v75, v71, v75
	v_mul_f32_e32 v85, v84, v81
	v_fma_f32 v86, -v80, v85, v84
	v_fmac_f32_e32 v85, v86, v81
	v_fma_f32 v80, -v80, v85, v84
	v_div_scale_f32 v84, s[4:5], v70, v70, v5
	v_rcp_f32_e32 v86, v84
	v_div_fmas_f32 v80, v80, v81, v85
	v_div_fixup_f32 v71, v80, v71, v75
	v_mul_f32_e32 v80, 0xbfb8aa3b, v82
	v_mul_f32_e32 v81, 0xbfb8aa3b, v83
	v_fma_f32 v75, -v84, v86, 1.0
	v_exp_f32_e32 v80, v80
	v_exp_f32_e32 v81, v81
	v_fmac_f32_e32 v86, v75, v86
	v_div_scale_f32 v75, vcc, v5, v70, v5
	v_mul_f32_e32 v85, v75, v86
	v_fma_f32 v87, -v84, v85, v75
	v_fmac_f32_e32 v85, v87, v86
	v_pk_add_f32 v[80:81], v[80:81], 1.0 op_sel_hi:[1,0]
	v_fma_f32 v75, -v84, v85, v75
	v_div_scale_f32 v84, s[4:5], v81, v81, v83
	v_rcp_f32_e32 v87, v84
	v_div_fmas_f32 v75, v75, v86, v85
	v_div_fixup_f32 v70, v75, v70, v5
	v_lshlrev_b32_e32 v86, 16, v66
	v_fma_f32 v5, -v84, v87, 1.0
	v_fmac_f32_e32 v87, v5, v87
	v_div_scale_f32 v5, vcc, v83, v81, v83
	v_mul_f32_e32 v75, v5, v87
	v_fma_f32 v85, -v84, v75, v5
	v_fmac_f32_e32 v75, v85, v87
	v_fma_f32 v5, -v84, v75, v5
	v_div_scale_f32 v84, s[4:5], v80, v80, v82
	v_rcp_f32_e32 v85, v84
	v_div_fmas_f32 v5, v5, v87, v75
	v_div_fixup_f32 v81, v5, v81, v83
	v_and_b32_e32 v87, 0xffff0000, v66
	v_fma_f32 v5, -v84, v85, 1.0
	v_fmac_f32_e32 v85, v5, v85
	v_div_scale_f32 v5, vcc, v82, v80, v82
	v_mul_f32_e32 v75, v5, v85
	v_fma_f32 v83, -v84, v75, v5
	v_fmac_f32_e32 v75, v83, v85
	v_fma_f32 v5, -v84, v75, v5
	v_div_fmas_f32 v5, v5, v85, v75
	v_div_fixup_f32 v80, v5, v80, v82
	v_lshlrev_b32_e32 v5, 16, v44
	v_and_b32_e32 v75, 0xffff0000, v44
	v_mul_f32_e32 v44, 0xbfb8aa3b, v5
	v_exp_f32_e32 v88, v44
	v_mul_f32_e32 v44, 0xbfb8aa3b, v75
	v_exp_f32_e32 v89, v44
	v_lshlrev_b32_e32 v84, 16, v64
	v_and_b32_e32 v85, 0xffff0000, v64
	v_lshlrev_b32_e32 v64, 16, v65
	v_lshlrev_b32_e32 v66, 16, v67
	v_and_b32_e32 v65, 0xffff0000, v65
	v_and_b32_e32 v67, 0xffff0000, v67
	v_pk_add_f32 v[64:65], v[64:65], v[66:67]
	v_pk_add_f32 v[66:67], v[88:89], 1.0 op_sel_hi:[1,0]
	v_pk_add_f32 v[84:85], v[84:85], v[86:87]
	v_div_scale_f32 v88, s[4:5], v67, v67, v75
	v_rcp_f32_e32 v89, v88
	v_pk_mul_f32 v[86:87], v[84:85], v[84:85]
	v_and_b32_e32 v91, 0xffff0000, v45
	v_pk_mul_f32 v[44:45], v[64:65], v[64:65]
	v_fma_f32 v92, -v88, v89, 1.0
	v_fmac_f32_e32 v89, v92, v89
	v_div_scale_f32 v92, vcc, v75, v67, v75
	v_mul_f32_e32 v93, v92, v89
	v_fma_f32 v94, -v88, v93, v92
	v_fmac_f32_e32 v93, v94, v89
	v_fma_f32 v88, -v88, v93, v92
	v_div_scale_f32 v92, s[4:5], v66, v66, v5
	v_rcp_f32_e32 v94, v92
	v_div_fmas_f32 v88, v88, v89, v93
	v_div_fixup_f32 v67, v88, v67, v75
	v_mov_b32_e32 v89, v78
	v_fma_f32 v75, -v92, v94, 1.0
	v_fmac_f32_e32 v94, v75, v94
	v_div_scale_f32 v75, vcc, v5, v66, v5
	v_mul_f32_e32 v93, v75, v94
	v_fma_f32 v88, -v92, v93, v75
	v_fmac_f32_e32 v93, v88, v94
	v_mov_b32_e32 v88, v86
	v_mov_b32_e32 v78, v87
	v_pk_add_f32 v[78:79], v[88:89], v[78:79]
	v_mov_b32_e32 v86, v44
	v_mov_b32_e32 v87, v72
	v_pk_add_f32 v[78:79], v[78:79], v[86:87]
	v_mov_b32_e32 v72, v45
	v_pk_add_f32 v[44:45], v[72:73], v[78:79]
	s_mov_b32 s4, 0x358637bd
	v_fma_f32 v75, -v92, v93, v75
	v_mov_b32_dpp v73, v45 quad_perm:[1,0,3,2] row_mask:0xf bank_mask:0xf bound_ctrl:1
	v_mov_b32_dpp v72, v44 quad_perm:[1,0,3,2] row_mask:0xf bank_mask:0xf bound_ctrl:1
	v_pk_add_f32 v[44:45], v[44:45], v[72:73]
	v_div_fmas_f32 v75, v75, v94, v93
	v_div_fixup_f32 v66, v75, v66, v5
	v_mov_b32_dpp v73, v45 quad_perm:[2,3,0,1] row_mask:0xf bank_mask:0xf bound_ctrl:1
	v_mov_b32_dpp v72, v44 quad_perm:[2,3,0,1] row_mask:0xf bank_mask:0xf bound_ctrl:1
	v_pk_add_f32 v[44:45], v[44:45], v[72:73]
	v_lshlrev_b64 v[82:83], 11, v[10:11]
	v_lshl_add_u64 v[82:83], s[16:17], 0, v[82:83]
	v_mov_b32_dpp v73, v45 row_half_mirror row_mask:0xf bank_mask:0xf bound_ctrl:1
	v_mov_b32_dpp v72, v44 row_half_mirror row_mask:0xf bank_mask:0xf bound_ctrl:1
	v_pk_add_f32 v[44:45], v[44:45], v[72:73]
	v_lshl_add_u64 v[82:83], v[82:83], 0, v[8:9]
	s_nop 0
	v_mov_b32_dpp v73, v45 row_mirror row_mask:0xf bank_mask:0xf bound_ctrl:1
	v_mov_b32_dpp v72, v44 row_mirror row_mask:0xf bank_mask:0xf bound_ctrl:1
	v_pk_add_f32 v[72:73], v[44:45], v[72:73]
	v_mov_b64_e32 v[44:45], s[4:5]
	v_pk_fma_f32 v[72:73], v[72:73], s[6:7], v[44:45] op_sel_hi:[1,0,0]
	s_nop 0
	v_mul_f32_e32 v78, 0x4b800000, v73
	v_cmp_gt_f32_e64 s[4:5], s7, v73
	v_cmp_gt_f32_e32 vcc, s7, v72
	s_nop 0
	v_cndmask_b32_e64 v73, v73, v78, s[4:5]
	v_rsq_f32_e32 v73, v73
	s_nop 0
	v_mul_f32_e32 v5, 0x45800000, v73
	v_cndmask_b32_e64 v78, v73, v5, s[4:5]
	v_pk_mul_f32 v[76:77], v[76:77], v[78:79] op_sel_hi:[1,0]
	v_pk_mul_f32 v[68:69], v[68:69], v[78:79] op_sel_hi:[1,0]
	v_pk_mul_f32 v[76:77], v[0:1], v[76:77]
	v_pk_mul_f32 v[68:69], v[2:3], v[68:69]
	v_pk_mul_f32 v[70:71], v[70:71], v[76:77]
	v_pk_mul_f32 v[68:69], v[80:81], v[68:69]
	v_cvt_pk_bf16_f32 v70, v70, v71
	v_cvt_pk_bf16_f32 v71, v68, v69
	v_add_co_u32_e64 v68, s[4:5], s8, v82
	v_mul_f32_e32 v5, 0x4b800000, v72
	s_nop 0
	v_addc_co_u32_e64 v69, s[4:5], 0, v83, s[4:5]
	v_cndmask_b32_e32 v5, v72, v5, vcc
	flat_store_dwordx2 v[68:69], v[70:71] offset:1024 sc1
	v_mul_f32_e32 v68, 0xbfb8aa3b, v90
	v_mul_f32_e32 v69, 0xbfb8aa3b, v91
	v_rsq_f32_e32 v5, v5
	v_exp_f32_e32 v68, v68
	v_exp_f32_e32 v69, v69
	v_lshlrev_b32_e32 v80, 16, v53
	v_mul_f32_e32 v70, 0x45800000, v5
	v_cndmask_b32_e32 v70, v5, v70, vcc
	v_pk_add_f32 v[68:69], v[68:69], 1.0 op_sel_hi:[1,0]
	v_pk_mul_f32 v[72:73], v[84:85], v[70:71] op_sel_hi:[1,0]
	v_div_scale_f32 v5, s[4:5], v69, v69, v91
	v_rcp_f32_e32 v71, v5
	v_pk_mul_f32 v[72:73], v[0:1], v[72:73]
	v_and_b32_e32 v81, 0xffff0000, v53
	v_pk_mul_f32 v[66:67], v[66:67], v[72:73]
	v_pk_mul_f32 v[64:65], v[64:65], v[70:71] op_sel_hi:[1,0]
	v_fma_f32 v70, -v5, v71, 1.0
	v_fmac_f32_e32 v71, v70, v71
	v_div_scale_f32 v70, vcc, v91, v69, v91
	v_mul_f32_e32 v72, v70, v71
	v_fma_f32 v73, -v5, v72, v70
	v_fmac_f32_e32 v72, v73, v71
	v_fma_f32 v5, -v5, v72, v70
	v_div_scale_f32 v70, s[4:5], v68, v68, v90
	v_rcp_f32_e32 v73, v70
	v_div_fmas_f32 v5, v5, v71, v72
	v_div_fixup_f32 v69, v5, v69, v91
	v_pk_mul_f32 v[64:65], v[2:3], v[64:65]
	v_fma_f32 v5, -v70, v73, 1.0
	v_fmac_f32_e32 v73, v5, v73
	v_div_scale_f32 v5, vcc, v90, v68, v90
	v_mul_f32_e32 v71, v5, v73
	v_fma_f32 v72, -v70, v71, v5
	v_fmac_f32_e32 v71, v72, v73
	v_fma_f32 v5, -v70, v71, v5
	v_div_fmas_f32 v5, v5, v73, v71
	v_div_fixup_f32 v68, v5, v68, v90
	v_pk_mul_f32 v[64:65], v[68:69], v[64:65]
	v_lshlrev_b32_e32 v5, 16, v58
	v_cvt_pk_bf16_f32 v66, v66, v67
	v_cvt_pk_bf16_f32 v67, v64, v65
	v_lshlrev_b64 v[64:65], 11, v[12:13]
	v_and_b32_e32 v70, 0xffff0000, v58
	v_mul_f32_e32 v58, 0xbfb8aa3b, v5
	v_lshl_add_u64 v[64:65], s[16:17], 0, v[64:65]
	v_exp_f32_e32 v68, v58
	v_mul_f32_e32 v58, 0xbfb8aa3b, v70
	v_lshl_add_u64 v[64:65], v[64:65], 0, v[8:9]
	v_exp_f32_e32 v69, v58
	v_add_co_u32_e32 v64, vcc, s8, v64
	v_lshlrev_b32_e32 v71, 16, v59
	s_nop 0
	v_addc_co_u32_e32 v65, vcc, 0, v65, vcc
	flat_store_dwordx2 v[64:65], v[66:67] offset:1024 sc1
	v_lshlrev_b32_e32 v64, 16, v60
	v_lshlrev_b32_e32 v66, 16, v62
	v_and_b32_e32 v65, 0xffff0000, v60
	v_and_b32_e32 v67, 0xffff0000, v62
	v_lshlrev_b32_e32 v60, 16, v61
	v_lshlrev_b32_e32 v62, 16, v63
	v_and_b32_e32 v61, 0xffff0000, v61
	v_and_b32_e32 v63, 0xffff0000, v63
	v_and_b32_e32 v72, 0xffff0000, v59
	v_pk_add_f32 v[58:59], v[60:61], v[62:63]
	v_pk_add_f32 v[60:61], v[68:69], 1.0 op_sel_hi:[1,0]
	v_pk_add_f32 v[64:65], v[64:65], v[66:67]
	v_div_scale_f32 v68, s[4:5], v61, v61, v70
	v_rcp_f32_e32 v69, v68
	v_pk_mul_f32 v[66:67], v[64:65], v[64:65]
	v_pk_mul_f32 v[62:63], v[58:59], v[58:59]
	v_fma_f32 v73, -v68, v69, 1.0
	v_fmac_f32_e32 v69, v73, v69
	v_div_scale_f32 v73, vcc, v70, v61, v70
	v_mul_f32_e32 v75, v73, v69
	v_fma_f32 v76, -v68, v75, v73
	v_fmac_f32_e32 v75, v76, v69
	v_fma_f32 v68, -v68, v75, v73
	v_div_scale_f32 v73, s[4:5], v60, v60, v5
	v_rcp_f32_e32 v76, v73
	v_div_fmas_f32 v68, v68, v69, v75
	v_div_fixup_f32 v61, v68, v61, v70
	v_mul_f32_e32 v69, 0xbfb8aa3b, v72
	v_fma_f32 v68, -v73, v76, 1.0
	v_fmac_f32_e32 v76, v68, v76
	v_mul_f32_e32 v68, 0xbfb8aa3b, v71
	v_exp_f32_e32 v68, v68
	v_exp_f32_e32 v69, v69
	v_div_scale_f32 v70, vcc, v5, v60, v5
	v_mul_f32_e32 v75, v70, v76
	v_fma_f32 v77, -v73, v75, v70
	v_fmac_f32_e32 v75, v77, v76
	v_pk_add_f32 v[68:69], v[68:69], 1.0 op_sel_hi:[1,0]
	v_fma_f32 v70, -v73, v75, v70
	v_div_scale_f32 v73, s[4:5], v69, v69, v72
	v_rcp_f32_e32 v77, v73
	v_div_fmas_f32 v70, v70, v76, v75
	v_div_fixup_f32 v60, v70, v60, v5
	v_lshlrev_b32_e32 v76, 16, v56
	v_fma_f32 v5, -v73, v77, 1.0
	v_fmac_f32_e32 v77, v5, v77
	v_div_scale_f32 v5, vcc, v72, v69, v72
	v_mul_f32_e32 v70, v5, v77
	v_fma_f32 v75, -v73, v70, v5
	v_fmac_f32_e32 v70, v75, v77
	v_fma_f32 v5, -v73, v70, v5
	v_div_scale_f32 v73, s[4:5], v68, v68, v71
	v_rcp_f32_e32 v75, v73
	v_div_fmas_f32 v5, v5, v77, v70
	v_div_fixup_f32 v69, v5, v69, v72
	v_and_b32_e32 v77, 0xffff0000, v56
	v_fma_f32 v5, -v73, v75, 1.0
	v_fmac_f32_e32 v75, v5, v75
	v_div_scale_f32 v5, vcc, v71, v68, v71
	v_mul_f32_e32 v70, v5, v75
	v_fma_f32 v72, -v73, v70, v5
	v_fmac_f32_e32 v70, v72, v75
	v_fma_f32 v5, -v73, v70, v5
	v_div_fmas_f32 v5, v5, v75, v70
	v_div_fixup_f32 v68, v5, v68, v71
	v_lshlrev_b32_e32 v5, 16, v52
	v_and_b32_e32 v75, 0xffff0000, v52
	v_mul_f32_e32 v52, 0xbfb8aa3b, v5
	v_exp_f32_e32 v78, v52
	v_mul_f32_e32 v52, 0xbfb8aa3b, v75
	v_exp_f32_e32 v79, v52
	v_lshlrev_b32_e32 v72, 16, v54
	v_and_b32_e32 v73, 0xffff0000, v54
	v_lshlrev_b32_e32 v54, 16, v55
	v_lshlrev_b32_e32 v56, 16, v57
	v_and_b32_e32 v55, 0xffff0000, v55
	v_and_b32_e32 v57, 0xffff0000, v57
	v_pk_add_f32 v[52:53], v[54:55], v[56:57]
	v_pk_add_f32 v[54:55], v[78:79], 1.0 op_sel_hi:[1,0]
	v_pk_add_f32 v[72:73], v[72:73], v[76:77]
	v_div_scale_f32 v78, s[4:5], v55, v55, v75
	v_rcp_f32_e32 v79, v78
	v_pk_mul_f32 v[76:77], v[72:73], v[72:73]
	v_pk_mul_f32 v[56:57], v[52:53], v[52:53]
	v_lshlrev_b64 v[70:71], 11, v[14:15]
	v_fma_f32 v82, -v78, v79, 1.0
	v_fmac_f32_e32 v79, v82, v79
	v_div_scale_f32 v82, vcc, v75, v55, v75
	v_mul_f32_e32 v83, v82, v79
	v_fma_f32 v84, -v78, v83, v82
	v_fmac_f32_e32 v83, v84, v79
	v_fma_f32 v78, -v78, v83, v82
	v_div_scale_f32 v82, s[4:5], v54, v54, v5
	v_rcp_f32_e32 v84, v82
	v_div_fmas_f32 v78, v78, v79, v83
	v_div_fixup_f32 v55, v78, v55, v75
	v_mov_b32_e32 v79, v66
	v_fma_f32 v75, -v82, v84, 1.0
	v_fmac_f32_e32 v84, v75, v84
	v_div_scale_f32 v75, vcc, v5, v54, v5
	v_mul_f32_e32 v83, v75, v84
	v_fma_f32 v78, -v82, v83, v75
	v_fmac_f32_e32 v83, v78, v84
	v_mov_b32_e32 v78, v76
	v_mov_b32_e32 v66, v77
	v_pk_add_f32 v[66:67], v[78:79], v[66:67]
	v_mov_b32_e32 v76, v56
	v_mov_b32_e32 v77, v62
	v_pk_add_f32 v[66:67], v[66:67], v[76:77]
	v_mov_b32_e32 v62, v57
	v_pk_add_f32 v[56:57], v[62:63], v[66:67]
	v_fma_f32 v75, -v82, v83, v75
	v_lshl_add_u64 v[70:71], s[16:17], 0, v[70:71]
	v_mov_b32_dpp v63, v57 quad_perm:[1,0,3,2] row_mask:0xf bank_mask:0xf bound_ctrl:1
	v_mov_b32_dpp v62, v56 quad_perm:[1,0,3,2] row_mask:0xf bank_mask:0xf bound_ctrl:1
	v_pk_add_f32 v[56:57], v[56:57], v[62:63]
	v_lshl_add_u64 v[70:71], v[70:71], 0, v[8:9]
	v_and_b32_e32 v66, 0xffff0000, v42
	v_mov_b32_dpp v63, v57 quad_perm:[2,3,0,1] row_mask:0xf bank_mask:0xf bound_ctrl:1
	v_mov_b32_dpp v62, v56 quad_perm:[2,3,0,1] row_mask:0xf bank_mask:0xf bound_ctrl:1
	v_pk_add_f32 v[56:57], v[56:57], v[62:63]
	v_lshlrev_b32_e32 v67, 16, v43
	s_nop 0
	v_mov_b32_dpp v63, v57 row_half_mirror row_mask:0xf bank_mask:0xf bound_ctrl:1
	v_mov_b32_dpp v62, v56 row_half_mirror row_mask:0xf bank_mask:0xf bound_ctrl:1
	v_pk_add_f32 v[56:57], v[56:57], v[62:63]
	s_nop 1
	v_mov_b32_dpp v63, v57 row_mirror row_mask:0xf bank_mask:0xf bound_ctrl:1
	v_mov_b32_dpp v62, v56 row_mirror row_mask:0xf bank_mask:0xf bound_ctrl:1
	v_pk_add_f32 v[56:57], v[56:57], v[62:63]
	s_nop 0
	v_pk_fma_f32 v[56:57], v[56:57], s[6:7], v[44:45] op_sel_hi:[1,0,0]
	s_nop 0
	v_mul_f32_e32 v62, 0x4b800000, v57
	v_cmp_gt_f32_e64 s[4:5], s7, v57
	s_nop 1
	v_cndmask_b32_e64 v57, v57, v62, s[4:5]
	v_rsq_f32_e32 v57, v57
	v_div_fmas_f32 v62, v75, v84, v83
	v_div_fixup_f32 v54, v62, v54, v5
	v_cmp_gt_f32_e32 vcc, s7, v56
	v_mul_f32_e32 v5, 0x45800000, v57
	v_cndmask_b32_e64 v62, v57, v5, s[4:5]
	v_pk_mul_f32 v[64:65], v[64:65], v[62:63] op_sel_hi:[1,0]
	v_pk_mul_f32 v[58:59], v[58:59], v[62:63] op_sel_hi:[1,0]
	v_pk_mul_f32 v[64:65], v[0:1], v[64:65]
	v_pk_mul_f32 v[58:59], v[2:3], v[58:59]
	v_mul_f32_e32 v5, 0x4b800000, v56
	v_pk_mul_f32 v[60:61], v[60:61], v[64:65]
	v_pk_mul_f32 v[58:59], v[68:69], v[58:59]
	v_cndmask_b32_e32 v5, v56, v5, vcc
	v_add_co_u32_e64 v56, s[4:5], s8, v70
	v_cvt_pk_bf16_f32 v60, v60, v61
	v_cvt_pk_bf16_f32 v61, v58, v59
	v_addc_co_u32_e64 v57, s[4:5], 0, v71, s[4:5]
	flat_store_dwordx2 v[56:57], v[60:61] offset:1024 sc1
	v_mul_f32_e32 v56, 0xbfb8aa3b, v80
	v_mul_f32_e32 v57, 0xbfb8aa3b, v81
	v_rsq_f32_e32 v5, v5
	v_exp_f32_e32 v56, v56
	v_exp_f32_e32 v57, v57
	v_and_b32_e32 v68, 0xffff0000, v43
	v_mul_f32_e32 v58, 0x45800000, v5
	v_cndmask_b32_e32 v58, v5, v58, vcc
	v_pk_add_f32 v[56:57], v[56:57], 1.0 op_sel_hi:[1,0]
	v_pk_mul_f32 v[60:61], v[72:73], v[58:59] op_sel_hi:[1,0]
	v_div_scale_f32 v5, s[4:5], v57, v57, v81
	v_rcp_f32_e32 v59, v5
	v_pk_mul_f32 v[60:61], v[0:1], v[60:61]
	v_pk_mul_f32 v[52:53], v[52:53], v[58:59] op_sel_hi:[1,0]
	v_fma_f32 v58, -v5, v59, 1.0
	v_fmac_f32_e32 v59, v58, v59
	v_div_scale_f32 v58, vcc, v81, v57, v81
	v_pk_mul_f32 v[54:55], v[54:55], v[60:61]
	v_mul_f32_e32 v60, v58, v59
	v_fma_f32 v61, -v5, v60, v58
	v_fmac_f32_e32 v60, v61, v59
	v_fma_f32 v5, -v5, v60, v58
	v_div_scale_f32 v58, s[4:5], v56, v56, v80
	v_rcp_f32_e32 v61, v58
	v_div_fmas_f32 v5, v5, v59, v60
	v_div_fixup_f32 v57, v5, v57, v81
	v_pk_mul_f32 v[52:53], v[2:3], v[52:53]
	v_fma_f32 v5, -v58, v61, 1.0
	v_fmac_f32_e32 v61, v5, v61
	v_div_scale_f32 v5, vcc, v80, v56, v80
	v_mul_f32_e32 v59, v5, v61
	v_fma_f32 v60, -v58, v59, v5
	v_fmac_f32_e32 v59, v60, v61
	v_fma_f32 v5, -v58, v59, v5
	v_div_fmas_f32 v5, v5, v61, v59
	v_div_fixup_f32 v56, v5, v56, v80
	v_pk_mul_f32 v[52:53], v[56:57], v[52:53]
	v_lshlrev_b32_e32 v5, 16, v46
	v_cvt_pk_bf16_f32 v54, v54, v55
	v_cvt_pk_bf16_f32 v55, v52, v53
	v_lshlrev_b64 v[52:53], 11, v[16:17]
	v_and_b32_e32 v58, 0xffff0000, v46
	v_mul_f32_e32 v46, 0xbfb8aa3b, v5
	v_lshl_add_u64 v[52:53], s[16:17], 0, v[52:53]
	v_exp_f32_e32 v56, v46
	v_mul_f32_e32 v46, 0xbfb8aa3b, v58
	v_lshl_add_u64 v[52:53], v[52:53], 0, v[8:9]
	v_exp_f32_e32 v57, v46
	v_add_co_u32_e32 v52, vcc, s8, v52
	v_lshlrev_b32_e32 v59, 16, v47
	s_nop 0
	v_addc_co_u32_e32 v53, vcc, 0, v53, vcc
	flat_store_dwordx2 v[52:53], v[54:55] offset:1024 sc1
	v_lshlrev_b32_e32 v52, 16, v48
	v_lshlrev_b32_e32 v54, 16, v50
	v_and_b32_e32 v53, 0xffff0000, v48
	v_and_b32_e32 v55, 0xffff0000, v50
	v_lshlrev_b32_e32 v48, 16, v49
	v_lshlrev_b32_e32 v50, 16, v51
	v_and_b32_e32 v49, 0xffff0000, v49
	v_and_b32_e32 v51, 0xffff0000, v51
	v_and_b32_e32 v60, 0xffff0000, v47
	v_pk_add_f32 v[46:47], v[48:49], v[50:51]
	v_pk_add_f32 v[48:49], v[56:57], 1.0 op_sel_hi:[1,0]
	v_pk_add_f32 v[52:53], v[52:53], v[54:55]
	v_div_scale_f32 v56, s[4:5], v49, v49, v58
	v_rcp_f32_e32 v57, v56
	v_pk_mul_f32 v[54:55], v[52:53], v[52:53]
	v_pk_mul_f32 v[50:51], v[46:47], v[46:47]
	v_fma_f32 v61, -v56, v57, 1.0
	v_fmac_f32_e32 v57, v61, v57
	v_div_scale_f32 v61, vcc, v58, v49, v58
	v_mul_f32_e32 v62, v61, v57
	v_fma_f32 v63, -v56, v62, v61
	v_fmac_f32_e32 v62, v63, v57
	v_fma_f32 v56, -v56, v62, v61
	v_div_scale_f32 v61, s[4:5], v48, v48, v5
	v_rcp_f32_e32 v63, v61
	v_div_fmas_f32 v56, v56, v57, v62
	v_div_fixup_f32 v49, v56, v49, v58
	v_mul_f32_e32 v57, 0xbfb8aa3b, v60
	v_fma_f32 v56, -v61, v63, 1.0
	v_fmac_f32_e32 v63, v56, v63
	v_mul_f32_e32 v56, 0xbfb8aa3b, v59
	v_exp_f32_e32 v56, v56
	v_exp_f32_e32 v57, v57
	v_div_scale_f32 v58, vcc, v5, v48, v5
	v_mul_f32_e32 v62, v58, v63
	v_fma_f32 v64, -v61, v62, v58
	v_fmac_f32_e32 v62, v64, v63
	v_pk_add_f32 v[56:57], v[56:57], 1.0 op_sel_hi:[1,0]
	v_fma_f32 v58, -v61, v62, v58
	v_div_scale_f32 v61, s[4:5], v57, v57, v60
	v_rcp_f32_e32 v64, v61
	v_div_fmas_f32 v58, v58, v63, v62
	v_div_fixup_f32 v48, v58, v48, v5
	v_and_b32_e32 v63, 0xffff0000, v40
	v_fma_f32 v5, -v61, v64, 1.0
	v_fmac_f32_e32 v64, v5, v64
	v_div_scale_f32 v5, vcc, v60, v57, v60
	v_mul_f32_e32 v58, v5, v64
	v_fma_f32 v62, -v61, v58, v5
	v_fmac_f32_e32 v58, v62, v64
	v_fma_f32 v5, -v61, v58, v5
	v_div_scale_f32 v61, s[4:5], v56, v56, v59
	v_rcp_f32_e32 v62, v61
	v_div_fmas_f32 v5, v5, v64, v58
	v_div_fixup_f32 v57, v5, v57, v60
	v_fma_f32 v5, -v61, v62, 1.0
	v_fmac_f32_e32 v62, v5, v62
	v_div_scale_f32 v5, vcc, v59, v56, v59
	v_mul_f32_e32 v58, v5, v62
	v_fma_f32 v60, -v61, v58, v5
	v_fmac_f32_e32 v58, v60, v62
	v_fma_f32 v5, -v61, v58, v5
	v_div_fmas_f32 v5, v5, v62, v58
	v_div_fixup_f32 v56, v5, v56, v59
	v_lshlrev_b32_e32 v5, 16, v42
	v_mul_f32_e32 v42, 0xbfb8aa3b, v5
	v_exp_f32_e32 v64, v42
	v_mul_f32_e32 v42, 0xbfb8aa3b, v66
	v_exp_f32_e32 v65, v42
	v_lshlrev_b32_e32 v60, 16, v38
	v_lshlrev_b32_e32 v62, 16, v40
	v_and_b32_e32 v61, 0xffff0000, v38
	v_lshlrev_b32_e32 v38, 16, v39
	v_lshlrev_b32_e32 v40, 16, v41
	v_and_b32_e32 v39, 0xffff0000, v39
	v_and_b32_e32 v41, 0xffff0000, v41
	v_pk_add_f32 v[38:39], v[38:39], v[40:41]
	v_pk_add_f32 v[40:41], v[64:65], 1.0 op_sel_hi:[1,0]
	v_pk_add_f32 v[60:61], v[60:61], v[62:63]
	v_div_scale_f32 v64, s[4:5], v41, v41, v66
	v_rcp_f32_e32 v65, v64
	v_pk_mul_f32 v[62:63], v[60:61], v[60:61]
	v_pk_mul_f32 v[42:43], v[38:39], v[38:39]
	v_lshlrev_b64 v[58:59], 11, v[18:19]
	v_fma_f32 v69, -v64, v65, 1.0
	v_fmac_f32_e32 v65, v69, v65
	v_div_scale_f32 v69, vcc, v66, v41, v66
	v_mul_f32_e32 v70, v69, v65
	v_fma_f32 v71, -v64, v70, v69
	v_fmac_f32_e32 v70, v71, v65
	v_fma_f32 v64, -v64, v70, v69
	v_div_scale_f32 v69, s[4:5], v40, v40, v5
	v_rcp_f32_e32 v71, v69
	v_div_fmas_f32 v64, v64, v65, v70
	v_div_fixup_f32 v41, v64, v41, v66
	v_lshl_add_u64 v[58:59], s[16:17], 0, v[58:59]
	v_fma_f32 v64, -v69, v71, 1.0
	v_fmac_f32_e32 v71, v64, v71
	v_div_scale_f32 v64, vcc, v5, v40, v5
	v_mul_f32_e32 v66, v64, v71
	v_fma_f32 v65, -v69, v66, v64
	v_fmac_f32_e32 v66, v65, v71
	v_fma_f32 v69, -v69, v66, v64
	v_mov_b32_e32 v64, v62
	v_mov_b32_e32 v65, v54
	v_mov_b32_e32 v54, v63
	v_pk_add_f32 v[54:55], v[64:65], v[54:55]
	v_mov_b32_e32 v62, v42
	v_mov_b32_e32 v63, v50
	v_pk_add_f32 v[54:55], v[54:55], v[62:63]
	v_mov_b32_e32 v50, v43
	v_pk_add_f32 v[42:43], v[50:51], v[54:55]
	v_lshl_add_u64 v[58:59], v[58:59], 0, v[8:9]
	s_waitcnt lgkmcnt(0)
	v_and_b32_e32 v54, 0xffff0000, v26
	v_mov_b32_dpp v51, v43 quad_perm:[1,0,3,2] row_mask:0xf bank_mask:0xf bound_ctrl:1
	v_mov_b32_dpp v50, v42 quad_perm:[1,0,3,2] row_mask:0xf bank_mask:0xf bound_ctrl:1
	v_pk_add_f32 v[42:43], v[42:43], v[50:51]
	v_lshlrev_b32_e32 v55, 16, v27
	s_nop 0
	v_mov_b32_dpp v51, v43 quad_perm:[2,3,0,1] row_mask:0xf bank_mask:0xf bound_ctrl:1
	v_mov_b32_dpp v50, v42 quad_perm:[2,3,0,1] row_mask:0xf bank_mask:0xf bound_ctrl:1
	v_pk_add_f32 v[42:43], v[42:43], v[50:51]
	s_nop 1
	v_mov_b32_dpp v51, v43 row_half_mirror row_mask:0xf bank_mask:0xf bound_ctrl:1
	v_mov_b32_dpp v50, v42 row_half_mirror row_mask:0xf bank_mask:0xf bound_ctrl:1
	v_pk_add_f32 v[42:43], v[42:43], v[50:51]
	s_nop 1
	v_mov_b32_dpp v51, v43 row_mirror row_mask:0xf bank_mask:0xf bound_ctrl:1
	v_mov_b32_dpp v50, v42 row_mirror row_mask:0xf bank_mask:0xf bound_ctrl:1
	v_pk_add_f32 v[42:43], v[42:43], v[50:51]
	s_nop 0
	v_pk_fma_f32 v[42:43], v[42:43], s[6:7], v[44:45] op_sel_hi:[1,0,0]
	s_nop 0
	v_mul_f32_e32 v50, 0x4b800000, v43
	v_cmp_gt_f32_e64 s[4:5], s7, v43
	s_nop 1
	v_cndmask_b32_e64 v43, v43, v50, s[4:5]
	v_rsq_f32_e32 v43, v43
	v_div_fmas_f32 v50, v69, v71, v66
	v_div_fixup_f32 v40, v50, v40, v5
	v_cmp_gt_f32_e32 vcc, s7, v42
	v_mul_f32_e32 v5, 0x45800000, v43
	v_cndmask_b32_e64 v50, v43, v5, s[4:5]
	v_pk_mul_f32 v[52:53], v[52:53], v[50:51] op_sel_hi:[1,0]
	v_pk_mul_f32 v[46:47], v[46:47], v[50:51] op_sel_hi:[1,0]
	v_pk_mul_f32 v[52:53], v[0:1], v[52:53]
	v_pk_mul_f32 v[46:47], v[2:3], v[46:47]
	v_mul_f32_e32 v5, 0x4b800000, v42
	v_pk_mul_f32 v[48:49], v[48:49], v[52:53]
	v_pk_mul_f32 v[46:47], v[56:57], v[46:47]
	v_cndmask_b32_e32 v5, v42, v5, vcc
	v_add_co_u32_e64 v42, s[4:5], s8, v58
	v_cvt_pk_bf16_f32 v48, v48, v49
	v_cvt_pk_bf16_f32 v49, v46, v47
	v_addc_co_u32_e64 v43, s[4:5], 0, v59, s[4:5]
	flat_store_dwordx2 v[42:43], v[48:49] offset:1024 sc1
	v_mul_f32_e32 v42, 0xbfb8aa3b, v67
	v_mul_f32_e32 v43, 0xbfb8aa3b, v68
	v_rsq_f32_e32 v5, v5
	v_exp_f32_e32 v42, v42
	v_exp_f32_e32 v43, v43
	v_and_b32_e32 v56, 0xffff0000, v27
	v_mul_f32_e32 v46, 0x45800000, v5
	v_cndmask_b32_e32 v46, v5, v46, vcc
	v_pk_add_f32 v[42:43], v[42:43], 1.0 op_sel_hi:[1,0]
	v_pk_mul_f32 v[48:49], v[60:61], v[46:47] op_sel_hi:[1,0]
	v_div_scale_f32 v5, s[4:5], v43, v43, v68
	v_rcp_f32_e32 v47, v5
	v_pk_mul_f32 v[48:49], v[0:1], v[48:49]
	v_pk_mul_f32 v[38:39], v[38:39], v[46:47] op_sel_hi:[1,0]
	v_fma_f32 v46, -v5, v47, 1.0
	v_fmac_f32_e32 v47, v46, v47
	v_div_scale_f32 v46, vcc, v68, v43, v68
	v_pk_mul_f32 v[40:41], v[40:41], v[48:49]
	v_mul_f32_e32 v48, v46, v47
	v_fma_f32 v49, -v5, v48, v46
	v_fmac_f32_e32 v48, v49, v47
	v_fma_f32 v5, -v5, v48, v46
	v_div_scale_f32 v46, s[4:5], v42, v42, v67
	v_rcp_f32_e32 v49, v46
	v_div_fmas_f32 v5, v5, v47, v48
	v_div_fixup_f32 v43, v5, v43, v68
	v_pk_mul_f32 v[38:39], v[2:3], v[38:39]
	v_fma_f32 v5, -v46, v49, 1.0
	v_fmac_f32_e32 v49, v5, v49
	v_div_scale_f32 v5, vcc, v67, v42, v67
	v_mul_f32_e32 v47, v5, v49
	v_fma_f32 v48, -v46, v47, v5
	v_fmac_f32_e32 v47, v48, v49
	v_fma_f32 v5, -v46, v47, v5
	v_div_fmas_f32 v5, v5, v49, v47
	v_div_fixup_f32 v42, v5, v42, v67
	v_pk_mul_f32 v[38:39], v[42:43], v[38:39]
	v_lshlrev_b32_e32 v5, 16, v32
	v_cvt_pk_bf16_f32 v40, v40, v41
	v_cvt_pk_bf16_f32 v41, v38, v39
	v_lshlrev_b64 v[38:39], 11, v[20:21]
	v_and_b32_e32 v46, 0xffff0000, v32
	v_mul_f32_e32 v32, 0xbfb8aa3b, v5
	v_lshl_add_u64 v[38:39], s[16:17], 0, v[38:39]
	v_exp_f32_e32 v42, v32
	v_mul_f32_e32 v32, 0xbfb8aa3b, v46
	v_lshl_add_u64 v[38:39], v[38:39], 0, v[8:9]
	v_exp_f32_e32 v43, v32
	v_add_co_u32_e32 v38, vcc, s8, v38
	v_lshlrev_b32_e32 v47, 16, v33
	s_nop 0
	v_addc_co_u32_e32 v39, vcc, 0, v39, vcc
	flat_store_dwordx2 v[38:39], v[40:41] offset:1024 sc1
	v_lshlrev_b32_e32 v38, 16, v34
	v_lshlrev_b32_e32 v40, 16, v36
	v_and_b32_e32 v39, 0xffff0000, v34
	v_and_b32_e32 v41, 0xffff0000, v36
	v_lshlrev_b32_e32 v34, 16, v35
	v_lshlrev_b32_e32 v36, 16, v37
	v_and_b32_e32 v35, 0xffff0000, v35
	v_and_b32_e32 v37, 0xffff0000, v37
	v_and_b32_e32 v48, 0xffff0000, v33
	v_pk_add_f32 v[32:33], v[34:35], v[36:37]
	v_pk_add_f32 v[34:35], v[42:43], 1.0 op_sel_hi:[1,0]
	v_pk_add_f32 v[38:39], v[38:39], v[40:41]
	v_div_scale_f32 v42, s[4:5], v35, v35, v46
	v_rcp_f32_e32 v43, v42
	v_pk_mul_f32 v[40:41], v[38:39], v[38:39]
	v_pk_mul_f32 v[36:37], v[32:33], v[32:33]
	v_fma_f32 v49, -v42, v43, 1.0
	v_fmac_f32_e32 v43, v49, v43
	v_div_scale_f32 v49, vcc, v46, v35, v46
	v_mul_f32_e32 v50, v49, v43
	v_fma_f32 v51, -v42, v50, v49
	v_fmac_f32_e32 v50, v51, v43
	v_fma_f32 v42, -v42, v50, v49
	v_div_scale_f32 v49, s[4:5], v34, v34, v5
	v_rcp_f32_e32 v51, v49
	v_div_fmas_f32 v42, v42, v43, v50
	v_div_fixup_f32 v35, v42, v35, v46
	v_mul_f32_e32 v43, 0xbfb8aa3b, v48
	v_fma_f32 v42, -v49, v51, 1.0
	v_fmac_f32_e32 v51, v42, v51
	v_mul_f32_e32 v42, 0xbfb8aa3b, v47
	v_exp_f32_e32 v42, v42
	v_exp_f32_e32 v43, v43
	v_div_scale_f32 v46, vcc, v5, v34, v5
	v_mul_f32_e32 v50, v46, v51
	v_fma_f32 v52, -v49, v50, v46
	v_fmac_f32_e32 v50, v52, v51
	v_pk_add_f32 v[42:43], v[42:43], 1.0 op_sel_hi:[1,0]
	v_fma_f32 v46, -v49, v50, v46
	v_div_scale_f32 v49, s[4:5], v43, v43, v48
	v_rcp_f32_e32 v52, v49
	v_div_fmas_f32 v46, v46, v51, v50
	v_div_fixup_f32 v34, v46, v34, v5
	v_and_b32_e32 v51, 0xffff0000, v30
	v_fma_f32 v5, -v49, v52, 1.0
	v_fmac_f32_e32 v52, v5, v52
	v_div_scale_f32 v5, vcc, v48, v43, v48
	v_mul_f32_e32 v46, v5, v52
	v_fma_f32 v50, -v49, v46, v5
	v_fmac_f32_e32 v46, v50, v52
	v_fma_f32 v5, -v49, v46, v5
	v_div_scale_f32 v49, s[4:5], v42, v42, v47
	v_rcp_f32_e32 v50, v49
	v_div_fmas_f32 v5, v5, v52, v46
	v_div_fixup_f32 v43, v5, v43, v48
	v_fma_f32 v5, -v49, v50, 1.0
	v_fmac_f32_e32 v50, v5, v50
	v_div_scale_f32 v5, vcc, v47, v42, v47
	v_mul_f32_e32 v46, v5, v50
	v_fma_f32 v48, -v49, v46, v5
	v_fmac_f32_e32 v46, v48, v50
	v_fma_f32 v5, -v49, v46, v5
	v_div_fmas_f32 v5, v5, v50, v46
	v_div_fixup_f32 v42, v5, v42, v47
	v_lshlrev_b32_e32 v5, 16, v26
	v_mul_f32_e32 v26, 0xbfb8aa3b, v5
	v_exp_f32_e32 v52, v26
	v_mul_f32_e32 v26, 0xbfb8aa3b, v54
	v_exp_f32_e32 v53, v26
	v_lshlrev_b32_e32 v48, 16, v28
	v_lshlrev_b32_e32 v50, 16, v30
	v_and_b32_e32 v49, 0xffff0000, v28
	v_lshlrev_b32_e32 v28, 16, v29
	v_lshlrev_b32_e32 v30, 16, v31
	v_and_b32_e32 v29, 0xffff0000, v29
	v_and_b32_e32 v31, 0xffff0000, v31
	v_pk_add_f32 v[26:27], v[28:29], v[30:31]
	v_pk_add_f32 v[28:29], v[52:53], 1.0 op_sel_hi:[1,0]
	v_pk_add_f32 v[48:49], v[48:49], v[50:51]
	v_div_scale_f32 v52, s[4:5], v29, v29, v54
	v_rcp_f32_e32 v53, v52
	v_pk_mul_f32 v[50:51], v[48:49], v[48:49]
	v_pk_mul_f32 v[30:31], v[26:27], v[26:27]
	v_lshlrev_b64 v[46:47], 11, v[22:23]
	v_fma_f32 v57, -v52, v53, 1.0
	v_fmac_f32_e32 v53, v57, v53
	v_div_scale_f32 v57, vcc, v54, v29, v54
	v_mul_f32_e32 v58, v57, v53
	v_fma_f32 v59, -v52, v58, v57
	v_fmac_f32_e32 v58, v59, v53
	v_fma_f32 v52, -v52, v58, v57
	v_div_scale_f32 v57, s[4:5], v28, v28, v5
	v_rcp_f32_e32 v59, v57
	v_div_fmas_f32 v52, v52, v53, v58
	v_div_fixup_f32 v29, v52, v29, v54
	v_lshl_add_u64 v[46:47], s[16:17], 0, v[46:47]
	v_fma_f32 v52, -v57, v59, 1.0
	v_fmac_f32_e32 v59, v52, v59
	v_div_scale_f32 v52, vcc, v5, v28, v5
	v_mul_f32_e32 v54, v52, v59
	v_fma_f32 v53, -v57, v54, v52
	v_fmac_f32_e32 v54, v53, v59
	v_fma_f32 v57, -v57, v54, v52
	v_mov_b32_e32 v52, v50
	v_mov_b32_e32 v53, v40
	v_mov_b32_e32 v40, v51
	v_pk_add_f32 v[40:41], v[52:53], v[40:41]
	v_mov_b32_e32 v50, v30
	v_mov_b32_e32 v51, v36
	v_pk_add_f32 v[40:41], v[40:41], v[50:51]
	v_mov_b32_e32 v36, v31
	v_pk_add_f32 v[30:31], v[36:37], v[40:41]
	v_lshl_add_u64 v[46:47], v[46:47], 0, v[8:9]
	s_nop 0
	v_mov_b32_dpp v37, v31 quad_perm:[1,0,3,2] row_mask:0xf bank_mask:0xf bound_ctrl:1
	v_mov_b32_dpp v36, v30 quad_perm:[1,0,3,2] row_mask:0xf bank_mask:0xf bound_ctrl:1
	v_pk_add_f32 v[30:31], v[30:31], v[36:37]
	s_nop 1
	v_mov_b32_dpp v37, v31 quad_perm:[2,3,0,1] row_mask:0xf bank_mask:0xf bound_ctrl:1
	v_mov_b32_dpp v36, v30 quad_perm:[2,3,0,1] row_mask:0xf bank_mask:0xf bound_ctrl:1
	v_pk_add_f32 v[30:31], v[30:31], v[36:37]
	s_nop 1
	v_mov_b32_dpp v37, v31 row_half_mirror row_mask:0xf bank_mask:0xf bound_ctrl:1
	v_mov_b32_dpp v36, v30 row_half_mirror row_mask:0xf bank_mask:0xf bound_ctrl:1
	v_pk_add_f32 v[30:31], v[30:31], v[36:37]
	s_nop 1
	v_mov_b32_dpp v37, v31 row_mirror row_mask:0xf bank_mask:0xf bound_ctrl:1
	v_mov_b32_dpp v36, v30 row_mirror row_mask:0xf bank_mask:0xf bound_ctrl:1
	v_pk_add_f32 v[30:31], v[30:31], v[36:37]
	s_nop 0
	v_pk_fma_f32 v[30:31], v[30:31], s[6:7], v[44:45] op_sel_hi:[1,0,0]
	s_nop 0
	v_mul_f32_e32 v36, 0x4b800000, v31
	v_cmp_gt_f32_e64 s[4:5], s7, v31
	s_nop 1
	v_cndmask_b32_e64 v31, v31, v36, s[4:5]
	v_rsq_f32_e32 v31, v31
	v_div_fmas_f32 v36, v57, v59, v54
	v_div_fixup_f32 v28, v36, v28, v5
	v_cmp_gt_f32_e32 vcc, s7, v30
	v_mul_f32_e32 v5, 0x45800000, v31
	v_cndmask_b32_e64 v36, v31, v5, s[4:5]
	v_pk_mul_f32 v[38:39], v[38:39], v[36:37] op_sel_hi:[1,0]
	v_pk_mul_f32 v[32:33], v[32:33], v[36:37] op_sel_hi:[1,0]
	v_pk_mul_f32 v[38:39], v[0:1], v[38:39]
	v_pk_mul_f32 v[32:33], v[2:3], v[32:33]
	v_mul_f32_e32 v5, 0x4b800000, v30
	v_pk_mul_f32 v[34:35], v[34:35], v[38:39]
	v_pk_mul_f32 v[32:33], v[42:43], v[32:33]
	v_cndmask_b32_e32 v5, v30, v5, vcc
	v_add_co_u32_e64 v30, s[4:5], s8, v46
	v_cvt_pk_bf16_f32 v34, v34, v35
	v_cvt_pk_bf16_f32 v35, v32, v33
	v_addc_co_u32_e64 v31, s[4:5], 0, v47, s[4:5]
	flat_store_dwordx2 v[30:31], v[34:35] offset:1024 sc1
	v_mul_f32_e32 v30, 0xbfb8aa3b, v55
	v_mul_f32_e32 v31, 0xbfb8aa3b, v56
	v_rsq_f32_e32 v5, v5
	v_exp_f32_e32 v30, v30
	v_exp_f32_e32 v31, v31
	v_mul_f32_e32 v32, 0x45800000, v5
	v_cndmask_b32_e32 v32, v5, v32, vcc
	v_pk_add_f32 v[30:31], v[30:31], 1.0 op_sel_hi:[1,0]
	v_pk_mul_f32 v[34:35], v[48:49], v[32:33] op_sel_hi:[1,0]
	v_div_scale_f32 v5, s[4:5], v31, v31, v56
	v_rcp_f32_e32 v33, v5
	v_pk_mul_f32 v[0:1], v[0:1], v[34:35]
	v_pk_mul_f32 v[26:27], v[26:27], v[32:33] op_sel_hi:[1,0]
	s_nop 0
	v_pk_mul_f32 v[2:3], v[2:3], v[26:27]
	v_fma_f32 v26, -v5, v33, 1.0
	v_fmac_f32_e32 v33, v26, v33
	v_div_scale_f32 v26, vcc, v56, v31, v56
	v_mul_f32_e32 v27, v26, v33
	v_pk_mul_f32 v[0:1], v[28:29], v[0:1]
	v_fma_f32 v28, -v5, v27, v26
	v_fmac_f32_e32 v27, v28, v33
	v_fma_f32 v5, -v5, v27, v26
	v_div_scale_f32 v26, s[4:5], v30, v30, v55
	v_rcp_f32_e32 v28, v26
	v_div_fmas_f32 v5, v5, v33, v27
	v_div_fixup_f32 v27, v5, v31, v56
	v_cvt_pk_bf16_f32 v0, v0, v1
	v_fma_f32 v5, -v26, v28, 1.0
	v_fmac_f32_e32 v28, v5, v28
	v_div_scale_f32 v5, vcc, v55, v30, v55
	v_mul_f32_e32 v29, v5, v28
	v_fma_f32 v31, -v26, v29, v5
	v_fmac_f32_e32 v29, v31, v28
	v_fma_f32 v5, -v26, v29, v5
	v_div_fmas_f32 v5, v5, v28, v29
	v_div_fixup_f32 v26, v5, v30, v55
	v_pk_mul_f32 v[2:3], v[26:27], v[2:3]
	s_mov_b64 s[4:5], 0
	v_cvt_pk_bf16_f32 v1, v2, v3
	v_lshlrev_b64 v[2:3], 11, v[24:25]
	v_lshl_add_u64 v[2:3], s[16:17], 0, v[2:3]
	v_lshl_add_u64 v[2:3], v[2:3], 0, v[8:9]
	v_add_co_u32_e32 v2, vcc, 0x4552000, v2
	s_nop 1
	v_addc_co_u32_e32 v3, vcc, 0, v3, vcc
	flat_store_dwordx2 v[2:3], v[0:1] offset:1024 sc1
	s_waitcnt vmcnt(0)
	v_cmp_eq_u32_e32 vcc, 0, v74
	s_and_saveexec_b64 s[6:7], vcc
	s_cbranch_execz .LBB0_1419
	v_alignbit_b32 v0, v11, v10, 8
	v_alignbit_b32 v1, v7, v6, 8
	v_cmp_eq_u32_e32 vcc, v0, v1
	v_alignbit_b32 v2, v13, v12, 8
	v_alignbit_b32 v3, v17, v16, 8
	v_cndmask_b32_e64 v0, 1, 2, vcc
	v_cmp_eq_u32_e32 vcc, v2, v1
	v_alignbit_b32 v2, v15, v14, 8
	s_mov_b64 s[8:9], 0
	v_addc_co_u32_e32 v0, vcc, 0, v0, vcc
	v_cmp_eq_u32_e32 vcc, v2, v1
	s_nop 1
	v_cndmask_b32_e64 v2, 0, 1, vcc
	v_cmp_eq_u32_e32 vcc, v3, v1
	v_alignbit_b32 v3, v21, v20, 8
	s_nop 0
	v_addc_co_u32_e32 v0, vcc, v0, v2, vcc
	v_alignbit_b32 v2, v19, v18, 8
	v_cmp_eq_u32_e32 vcc, v2, v1
	s_nop 1
	v_cndmask_b32_e64 v2, 0, 1, vcc
	v_cmp_eq_u32_e32 vcc, v3, v1
	v_alignbit_b32 v3, v25, v24, 8
	s_nop 0
	v_addc_co_u32_e32 v0, vcc, v0, v2, vcc
	v_alignbit_b32 v2, v23, v22, 8
	v_cmp_eq_u32_e32 vcc, v2, v1
	s_nop 1
	v_cndmask_b32_e64 v2, 0, 1, vcc
	v_cmp_eq_u32_e32 vcc, v3, v1
	s_nop 1
	v_addc_co_u32_e32 v2, vcc, v0, v2, vcc
	v_lshlrev_b32_e32 v0, 6, v1
	v_ashrrev_i32_e32 v1, 31, v0
	v_lshl_add_u64 v[6:7], v[0:1], 2, s[18:19]
	flat_atomic_add v[6:7], v2
	v_cmp_gt_u32_e32 vcc, 9, v2
	s_and_saveexec_b64 s[10:11], vcc
	s_xor_b64 s[10:11], exec, s[10:11]
	s_mov_b64 s[8:9], exec
	v_sub_u32_e32 v1, 9, v2
	s_or_b64 exec, exec, s[10:11]
	s_and_b64 s[10:11], s[8:9], exec

.LBB0_1421:
	s_lshl_b32 s4, s3, 6
	s_ashr_i32 s5, s4, 31
	s_lshl_b64 s[6:7], s[4:5], 1
	v_lshlrev_b32_e32 v0, 3, v150
	s_add_u32 s6, s16, s6
	v_and_b32_e32 v5, 56, v0
	s_addc_u32 s7, s17, s7
	v_lshlrev_b32_e32 v6, 1, v5
	v_mov_b32_e32 v7, 0
	v_lshl_add_u64 v[0:1], s[6:7], 0, v[6:7]
	s_mov_b64 s[6:7], 0x7552000
	v_lshl_add_u64 v[8:9], v[0:1], 0, s[6:7]
	v_ashrrev_i32_e32 v6, 3, v150
	s_movk_i32 s5, 0x6000
	v_mad_i64_i32 v[0:1], s[6:7], v6, s5, v[8:9]
	s_waitcnt lgkmcnt(0)
	s_barrier
	global_load_dwordx4 v[0:3], v[0:1], off
	v_add_u32_e32 v12, 0x200, v150
	v_mul_u32_u24_e32 v5, 0x210, v5
	v_ashrrev_i32_e32 v13, 3, v12
	v_lshl_add_u32 v6, v6, 1, v5
	v_mad_i64_i32 v[10:11], s[6:7], v13, s5, v[8:9]
	v_lshl_add_u32 v13, v13, 1, v5
	s_waitcnt vmcnt(0) lgkmcnt(0)
	ds_write_b16 v6, v0
	ds_write_b16_d16_hi v6, v0 offset:528
	ds_write_b16 v6, v1 offset:1056
	ds_write_b16_d16_hi v6, v1 offset:1584
	ds_write_b16 v6, v2 offset:2112
	ds_write_b16_d16_hi v6, v2 offset:2640
	ds_write_b16 v6, v3 offset:3168
	ds_write_b16_d16_hi v6, v3 offset:3696
	global_load_dwordx4 v[0:3], v[10:11], off
	v_add_u32_e32 v6, 0x400, v150
	v_ashrrev_i32_e32 v14, 3, v6
	v_mad_i64_i32 v[10:11], s[6:7], v14, s5, v[8:9]
	v_ashrrev_i32_e32 v6, 5, v6
	s_waitcnt vmcnt(0) lgkmcnt(0)
	ds_write_b16 v13, v0
	ds_write_b16_d16_hi v13, v0 offset:528
	ds_write_b16 v13, v1 offset:1056
	ds_write_b16_d16_hi v13, v1 offset:1584
	ds_write_b16 v13, v2 offset:2112
	ds_write_b16_d16_hi v13, v2 offset:2640
	ds_write_b16 v13, v3 offset:3168
	ds_write_b16_d16_hi v13, v3 offset:3696
	global_load_dwordx4 v[0:3], v[10:11], off
	v_add_u32_e32 v13, 0x600, v150
	v_ashrrev_i32_e32 v18, 3, v13
	v_lshl_add_u32 v10, v14, 1, v5
	v_mad_i64_i32 v[8:9], s[6:7], v18, s5, v[8:9]
	s_movk_i32 s5, 0x210
	v_ashrrev_i32_e32 v20, 5, v13
	s_mov_b32 s7, 0x20000
	s_brev_b32 s6, -2
	s_waitcnt vmcnt(0) lgkmcnt(0)
	ds_write_b16 v10, v0
	ds_write_b16_d16_hi v10, v0 offset:528
	ds_write_b16 v10, v1 offset:1056
	ds_write_b16_d16_hi v10, v1 offset:1584
	ds_write_b16 v10, v2 offset:2112
	ds_write_b16_d16_hi v10, v2 offset:2640
	ds_write_b16 v10, v3 offset:3168
	ds_write_b16_d16_hi v10, v3 offset:3696
	global_load_dwordx4 v[8:11], v[8:9], off
	v_lshlrev_b32_e32 v0, 4, v150
	v_ashrrev_i32_e32 v1, 5, v150
	v_and_b32_e32 v2, 0x1f0, v0
	v_ashrrev_i32_e32 v3, 5, v12
	v_mad_u64_u32 v[12:13], s[8:9], v1, s5, v[2:3]
	v_add_u32_e32 v19, s4, v1
	v_or_b32_e32 v21, 0x600, v2
	v_add_u32_e32 v1, s4, v3
	v_mad_u64_u32 v[14:15], s[8:9], v3, s5, v[2:3]
	v_add_u32_e32 v13, s4, v6
	v_mad_u64_u32 v[16:17], s[8:9], v6, s5, v[2:3]
	v_add_u32_e32 v6, s4, v20
	v_mad_u64_u32 v[2:3], s[4:5], v20, s5, v[2:3]
	v_lshl_add_u32 v3, v18, 1, v5
	v_lshl_or_b32 v5, v19, 11, v21
	v_lshl_or_b32 v1, v1, 11, v21
	v_lshl_or_b32 v24, v13, 11, v21
	v_lshl_or_b32 v6, v6, 11, v21
	s_add_u32 s4, s16, 0x4552000
	s_addc_u32 s5, s17, 0
	s_and_b32 s5, s5, 0xffff
	s_waitcnt vmcnt(0) lgkmcnt(0)
	ds_write_b16 v3, v8
	ds_write_b16_d16_hi v3, v8 offset:528
	ds_write_b16 v3, v9 offset:1056
	ds_write_b16_d16_hi v3, v9 offset:1584
	ds_write_b16 v3, v10 offset:2112
	ds_write_b16_d16_hi v3, v10 offset:2640
	ds_write_b16 v3, v11 offset:3168
	ds_write_b16_d16_hi v3, v11 offset:3696
	s_waitcnt lgkmcnt(0)
	s_barrier
	ds_read_b128 v[8:11], v12
	ds_read_b128 v[12:15], v14
	ds_read_b128 v[16:19], v16
	ds_read_b128 v[20:23], v2
	s_waitcnt lgkmcnt(3)
	buffer_store_dwordx4 v[8:11], v5, s[4:7], 0 offen sc1
	s_waitcnt lgkmcnt(2)
	buffer_store_dwordx4 v[12:15], v1, s[4:7], 0 offen sc1
	s_waitcnt lgkmcnt(1)
	buffer_store_dwordx4 v[16:19], v24, s[4:7], 0 offen sc1
	s_waitcnt lgkmcnt(0)
	buffer_store_dwordx4 v[20:23], v6, s[4:7], 0 offen sc1
	s_waitcnt vmcnt(0)
	v_cmp_eq_u32_e64 s[4:5], 0, v74
	s_and_saveexec_b64 s[6:7], s[4:5]
	s_cbranch_execz .LBB0_1423
	s_lshl_b32 s8, s3, 4
	s_andn2_b32 s8, s8, 63
	s_ashr_i32 s9, s8, 31
	s_lshl_b64 s[8:9], s[8:9], 2
	s_add_u32 s8, s18, s8
	s_addc_u32 s9, s19, s9
	v_mov_b32_e32 v1, 1
	v_mov_b64_e32 v[2:3], s[8:9]
	flat_atomic_add v[2:3], v1
.LBB0_1423:
	s_or_b64 exec, exec, s[6:7]
	s_mul_i32 s6, s3, 40
	s_ashr_i32 s7, s6, 31
	v_ashrrev_i32_e32 v5, 31, v4
	v_lshlrev_b32_e32 v6, 3, v74
	v_lshl_add_u64 v[4:5], s[6:7], 0, v[4:5]
	v_lshl_add_u64 v[2:3], s[16:17], 0, v[6:7]
	s_mov_b64 s[6:7], 0x6952000
	v_lshl_add_u64 v[16:17], v[2:3], 0, s[6:7]
	s_mov_b64 s[6:7], 0x6f52000
	v_lshl_add_u64 v[18:19], v[2:3], 0, s[6:7]
	s_mov_b64 s[6:7], 0xcb32000
	v_lshlrev_b64 v[8:9], 9, v[4:5]
	v_lshl_add_u64 v[2:3], v[2:3], 0, s[6:7]
	v_lshl_add_u64 v[10:11], v[16:17], 0, v[8:9]
	v_lshl_add_u64 v[12:13], v[18:19], 0, v[8:9]
	v_lshl_add_u64 v[8:9], v[2:3], 0, v[8:9]
	global_load_dwordx2 v[34:35], v[10:11], off
	global_load_dwordx2 v[36:37], v[12:13], off
	global_load_dwordx2 v[38:39], v[8:9], off
	s_ashr_i32 s7, s70, 31
	s_add_u32 s6, s90, s70
	s_addc_u32 s7, s91, s7
	s_load_dwordx2 s[6:7], s[6:7], 0xb8
	v_lshl_add_u64 v[14:15], v[4:5], 0, 8
	v_and_b32_e32 v70, 0xf0, v0
	v_lshl_add_u64 v[12:13], v[4:5], 0, 16
	v_lshl_add_u64 v[10:11], v[4:5], 0, 24
	v_lshl_add_u64 v[8:9], v[4:5], 0, 32
	v_lshlrev_b64 v[0:1], 9, v[14:15]
	v_lshlrev_b64 v[20:21], 9, v[12:13]
	v_lshlrev_b64 v[22:23], 9, v[10:11]
	v_lshlrev_b64 v[24:25], 9, v[8:9]
	v_lshl_add_u64 v[40:41], v[16:17], 0, v[0:1]
	v_lshl_add_u64 v[42:43], v[18:19], 0, v[0:1]
	v_lshl_add_u64 v[44:45], v[2:3], 0, v[0:1]
	v_lshl_add_u64 v[46:47], v[16:17], 0, v[20:21]
	v_lshl_add_u64 v[48:49], v[18:19], 0, v[20:21]
	v_lshl_add_u64 v[50:51], v[2:3], 0, v[20:21]
	v_lshl_add_u64 v[52:53], v[16:17], 0, v[22:23]
	v_lshl_add_u64 v[54:55], v[18:19], 0, v[22:23]
	v_lshl_add_u64 v[56:57], v[2:3], 0, v[22:23]
	v_lshl_add_u64 v[58:59], v[16:17], 0, v[24:25]
	v_lshl_add_u64 v[60:61], v[18:19], 0, v[24:25]
	v_lshl_add_u64 v[62:63], v[2:3], 0, v[24:25]
	global_load_dwordx2 v[64:65], v[40:41], off
	s_waitcnt lgkmcnt(0)
	global_load_dwordx4 v[0:3], v70, s[6:7]
	global_load_dwordx2 v[66:67], v[42:43], off
	global_load_dwordx2 v[68:69], v[44:45], off
	global_load_dwordx2 v[30:31], v[46:47], off
	global_load_dwordx2 v[32:33], v[48:49], off
	global_load_dwordx2 v[28:29], v[50:51], off
	global_load_dwordx2 v[24:25], v[52:53], off
	global_load_dwordx2 v[26:27], v[54:55], off
	global_load_dwordx2 v[22:23], v[56:57], off
	global_load_dwordx2 v[18:19], v[58:59], off
	global_load_dwordx2 v[20:21], v[60:61], off
	global_load_dwordx2 v[16:17], v[62:63], off
	s_mov_b32 s13, 0x800000
	s_mov_b32 s12, 0x3c800000
	s_waitcnt vmcnt(0)
	v_lshlrev_b32_e32 v40, 16, v34
	v_lshlrev_b32_e32 v42, 16, v36
	v_and_b32_e32 v41, 0xffff0000, v34
	v_and_b32_e32 v43, 0xffff0000, v36
	v_lshlrev_b32_e32 v34, 16, v35
	v_lshlrev_b32_e32 v36, 16, v37
	v_and_b32_e32 v35, 0xffff0000, v35
	v_and_b32_e32 v37, 0xffff0000, v37
	v_lshlrev_b32_e32 v44, 16, v38
	v_and_b32_e32 v45, 0xffff0000, v38
	v_pk_add_f32 v[34:35], v[34:35], v[36:37]
	v_mul_f32_e32 v36, 0xbfb8aa3b, v44
	v_mul_f32_e32 v37, 0xbfb8aa3b, v45
	v_exp_f32_e32 v36, v36
	v_exp_f32_e32 v37, v37
	v_lshlrev_b32_e32 v46, 16, v39
	v_and_b32_e32 v47, 0xffff0000, v39
	v_pk_add_f32 v[38:39], v[40:41], v[42:43]
	v_pk_add_f32 v[36:37], v[36:37], 1.0 op_sel_hi:[1,0]
	v_pk_mul_f32 v[42:43], v[38:39], v[38:39]
	v_div_scale_f32 v48, s[6:7], v37, v37, v45
	v_rcp_f32_e32 v51, v48
	v_div_scale_f32 v50, s[6:7], v36, v36, v44
	v_pk_mul_f32 v[40:41], v[34:35], v[34:35]
	v_rcp_f32_e32 v52, v50
	v_add_f32_e32 v42, v42, v43
	v_add_f32_e32 v40, v42, v40
	v_fma_f32 v54, -v48, v51, 1.0
	v_add_f32_e32 v40, v41, v40
	v_div_scale_f32 v49, vcc, v45, v37, v45
	v_fmac_f32_e32 v51, v54, v51
	v_add_f32_dpp v40, v40, v40 quad_perm:[1,0,3,2] row_mask:0xf bank_mask:0xf bound_ctrl:1
	v_fma_f32 v55, -v50, v52, 1.0
	v_mul_f32_e32 v54, v49, v51
	v_add_f32_dpp v40, v40, v40 quad_perm:[2,3,0,1] row_mask:0xf bank_mask:0xf bound_ctrl:1
	v_div_scale_f32 v53, s[6:7], v44, v36, v44
	v_fmac_f32_e32 v52, v55, v52
	v_fma_f32 v56, -v48, v54, v49
	v_add_f32_dpp v40, v40, v40 row_half_mirror row_mask:0xf bank_mask:0xf bound_ctrl:1
	v_mul_f32_e32 v55, v53, v52
	v_fmac_f32_e32 v54, v56, v51
	v_add_f32_dpp v40, v40, v40 row_mirror row_mask:0xf bank_mask:0xf bound_ctrl:1
	v_mov_b32_e32 v41, 0x358637bd
	v_fma_f32 v57, -v50, v55, v53
	v_fma_f32 v48, -v48, v54, v49
	v_fmac_f32_e32 v41, 0x3c800000, v40
	v_fmac_f32_e32 v55, v57, v52
	v_div_fmas_f32 v48, v48, v51, v54
	v_mul_f32_e32 v40, 0x4b800000, v41
	v_cmp_gt_f32_e64 s[8:9], s13, v41
	v_div_fixup_f32 v37, v48, v37, v45
	v_fma_f32 v45, -v50, v55, v53
	v_cndmask_b32_e64 v40, v41, v40, s[8:9]
	s_mov_b64 vcc, s[6:7]
	v_rsq_f32_e32 v42, v40
	v_div_fmas_f32 v40, v45, v52, v55
	v_div_fixup_f32 v36, v40, v36, v44
	v_mul_f32_e32 v40, 0xbfb8aa3b, v46
	v_mul_f32_e32 v41, 0xbfb8aa3b, v47
	v_exp_f32_e32 v40, v40
	v_exp_f32_e32 v41, v41
	v_mul_f32_e32 v43, 0x45800000, v42
	v_cndmask_b32_e64 v42, v42, v43, s[8:9]
	v_pk_mul_f32 v[38:39], v[38:39], v[42:43] op_sel_hi:[1,0]
	v_pk_add_f32 v[40:41], v[40:41], 1.0 op_sel_hi:[1,0]
	v_pk_mul_f32 v[38:39], v[0:1], v[38:39]
	v_div_scale_f32 v43, s[6:7], v41, v41, v47
	v_rcp_f32_e32 v44, v43
	v_pk_mul_f32 v[36:37], v[36:37], v[38:39]
	v_pk_mul_f32 v[34:35], v[34:35], v[42:43] op_sel_hi:[1,0]
	v_cvt_pk_bf16_f32 v36, v36, v37
	v_fma_f32 v38, -v43, v44, 1.0
	v_fmac_f32_e32 v44, v38, v44
	v_div_scale_f32 v38, vcc, v47, v41, v47
	v_mul_f32_e32 v39, v38, v44
	v_fma_f32 v42, -v43, v39, v38
	v_fmac_f32_e32 v39, v42, v44
	v_div_scale_f32 v42, s[6:7], v40, v40, v46
	v_fma_f32 v38, -v43, v39, v38
	v_rcp_f32_e32 v43, v42
	v_div_fmas_f32 v38, v38, v44, v39
	v_div_fixup_f32 v39, v38, v41, v47
	v_pk_mul_f32 v[34:35], v[2:3], v[34:35]
	v_fma_f32 v38, -v42, v43, 1.0
	v_fmac_f32_e32 v43, v38, v43
	v_div_scale_f32 v38, vcc, v46, v40, v46
	v_mul_f32_e32 v41, v38, v43
	v_fma_f32 v44, -v42, v41, v38
	v_fmac_f32_e32 v41, v44, v43
	v_fma_f32 v38, -v42, v41, v38
	v_div_fmas_f32 v38, v38, v43, v41
	v_div_fixup_f32 v38, v38, v40, v46
	s_waitcnt lgkmcnt(0)
	v_lshlrev_b32_e32 v46, 16, v68
	v_and_b32_e32 v44, 0xffff0000, v68
	v_mul_f32_e32 v42, 0xbfb8aa3b, v46
	v_mul_f32_e32 v43, 0xbfb8aa3b, v44
	v_exp_f32_e32 v42, v42
	v_exp_f32_e32 v43, v43
	v_pk_mul_f32 v[34:35], v[38:39], v[34:35]
	v_lshlrev_b32_e32 v38, 16, v65
	v_lshlrev_b32_e32 v40, 16, v67
	v_and_b32_e32 v39, 0xffff0000, v65
	v_and_b32_e32 v41, 0xffff0000, v67
	v_pk_add_f32 v[38:39], v[38:39], v[40:41]
	v_pk_add_f32 v[40:41], v[42:43], 1.0 op_sel_hi:[1,0]
	v_cvt_pk_bf16_f32 v37, v34, v35
	v_div_scale_f32 v45, s[6:7], v41, v41, v44
	v_lshlrev_b64 v[34:35], 11, v[4:5]
	v_rcp_f32_e32 v49, v45
	v_lshl_add_u64 v[34:35], s[16:17], 0, v[34:35]
	v_lshl_add_u64 v[34:35], v[34:35], 0, v[6:7]
	s_mov_b32 s8, 0x4552000
	v_add_co_u32_e32 v34, vcc, s8, v34
	v_fma_f32 v50, -v45, v49, 1.0
	s_nop 0
	v_addc_co_u32_e32 v35, vcc, 0, v35, vcc
	v_fmac_f32_e32 v49, v50, v49
	v_div_scale_f32 v50, vcc, v44, v41, v44
	v_mul_f32_e32 v51, v50, v49
	v_fma_f32 v52, -v45, v51, v50
	v_fmac_f32_e32 v51, v52, v49
	v_fma_f32 v45, -v45, v51, v50
	v_div_scale_f32 v50, s[6:7], v40, v40, v46
	v_rcp_f32_e32 v52, v50
	v_div_fmas_f32 v45, v45, v49, v51
	v_lshlrev_b32_e32 v47, 16, v69
	v_and_b32_e32 v48, 0xffff0000, v69
	v_div_fixup_f32 v41, v45, v41, v44
	v_fma_f32 v44, -v50, v52, 1.0
	v_fmac_f32_e32 v52, v44, v52
	v_mul_f32_e32 v44, 0xbfb8aa3b, v47
	v_mul_f32_e32 v45, 0xbfb8aa3b, v48
	v_exp_f32_e32 v44, v44
	v_exp_f32_e32 v45, v45
	v_div_scale_f32 v49, vcc, v46, v40, v46
	v_mul_f32_e32 v51, v49, v52
	v_fma_f32 v53, -v50, v51, v49
	v_fmac_f32_e32 v51, v53, v52
	v_pk_add_f32 v[44:45], v[44:45], 1.0 op_sel_hi:[1,0]
	v_fma_f32 v49, -v50, v51, v49
	v_div_scale_f32 v50, s[6:7], v45, v45, v48
	v_rcp_f32_e32 v53, v50
	v_div_fmas_f32 v49, v49, v52, v51
	v_div_fixup_f32 v40, v49, v40, v46
	v_lshlrev_b32_e32 v54, 16, v28
	v_fma_f32 v46, -v50, v53, 1.0
	v_fmac_f32_e32 v53, v46, v53
	v_div_scale_f32 v46, vcc, v48, v45, v48
	v_mul_f32_e32 v49, v46, v53
	v_fma_f32 v51, -v50, v49, v46
	v_fmac_f32_e32 v49, v51, v53
	v_fma_f32 v46, -v50, v49, v46
	v_div_scale_f32 v50, s[6:7], v44, v44, v47
	v_rcp_f32_e32 v51, v50
	v_div_fmas_f32 v46, v46, v53, v49
	v_div_fixup_f32 v45, v46, v45, v48
	v_and_b32_e32 v55, 0xffff0000, v28
	v_fma_f32 v46, -v50, v51, 1.0
	v_fmac_f32_e32 v51, v46, v51
	v_div_scale_f32 v46, vcc, v47, v44, v47
	v_mul_f32_e32 v28, 0xbfb8aa3b, v54
	v_mul_f32_e32 v48, v46, v51
	v_exp_f32_e32 v52, v28
	v_mul_f32_e32 v28, 0xbfb8aa3b, v55
	v_fma_f32 v49, -v50, v48, v46
	v_exp_f32_e32 v53, v28
	v_fmac_f32_e32 v48, v49, v51
	v_fma_f32 v46, -v50, v48, v46
	v_div_fmas_f32 v46, v46, v51, v48
	v_lshlrev_b32_e32 v48, 16, v30
	v_lshlrev_b32_e32 v50, 16, v32
	v_and_b32_e32 v49, 0xffff0000, v30
	v_and_b32_e32 v51, 0xffff0000, v32
	v_lshlrev_b32_e32 v30, 16, v31
	v_lshlrev_b32_e32 v32, 16, v33
	v_and_b32_e32 v31, 0xffff0000, v31
	v_and_b32_e32 v33, 0xffff0000, v33
	v_pk_add_f32 v[30:31], v[30:31], v[32:33]
	v_pk_add_f32 v[32:33], v[52:53], 1.0 op_sel_hi:[1,0]
	flat_store_dwordx2 v[34:35], v[36:37] offset:1024 sc1
	v_div_scale_f32 v52, s[6:7], v33, v33, v55
	v_rcp_f32_e32 v53, v52
	v_lshlrev_b32_e32 v34, 16, v64
	v_lshlrev_b32_e32 v36, 16, v66
	v_and_b32_e32 v35, 0xffff0000, v64
	v_fma_f32 v58, -v52, v53, 1.0
	v_fmac_f32_e32 v53, v58, v53
	v_div_scale_f32 v58, vcc, v55, v33, v55
	v_mul_f32_e32 v59, v58, v53
	v_fma_f32 v60, -v52, v59, v58
	v_fmac_f32_e32 v59, v60, v53
	v_fma_f32 v52, -v52, v59, v58
	v_div_scale_f32 v58, s[6:7], v32, v32, v54
	v_rcp_f32_e32 v60, v58
	v_div_fmas_f32 v52, v52, v53, v59
	v_div_fixup_f32 v33, v52, v33, v55
	v_and_b32_e32 v37, 0xffff0000, v66
	v_fma_f32 v52, -v58, v60, 1.0
	v_fmac_f32_e32 v60, v52, v60
	v_div_scale_f32 v52, vcc, v54, v32, v54
	v_mul_f32_e32 v55, v52, v60
	v_pk_add_f32 v[34:35], v[34:35], v[36:37]
	v_pk_add_f32 v[48:49], v[48:49], v[50:51]
	v_fma_f32 v53, -v58, v55, v52
	v_pk_mul_f32 v[36:37], v[34:35], v[34:35]
	v_pk_mul_f32 v[50:51], v[48:49], v[48:49]
	v_fmac_f32_e32 v55, v53, v60
	v_pk_mul_f32 v[42:43], v[38:39], v[38:39]
	v_lshlrev_b32_e32 v56, 16, v29
	v_and_b32_e32 v57, 0xffff0000, v29
	v_pk_mul_f32 v[28:29], v[30:31], v[30:31]
	v_fma_f32 v58, -v58, v55, v52
	v_mov_b32_e32 v52, v50
	v_mov_b32_e32 v53, v36
	v_mov_b32_e32 v36, v51
	v_pk_add_f32 v[36:37], v[52:53], v[36:37]
	v_mov_b32_e32 v50, v28
	v_mov_b32_e32 v51, v42
	v_pk_add_f32 v[36:37], v[36:37], v[50:51]
	v_mov_b32_e32 v42, v29
	v_pk_add_f32 v[28:29], v[42:43], v[36:37]
	s_mov_b32 s6, 0x358637bd
	v_div_fixup_f32 v44, v46, v44, v47
	v_mov_b32_dpp v37, v29 quad_perm:[1,0,3,2] row_mask:0xf bank_mask:0xf bound_ctrl:1
	v_mov_b32_dpp v36, v28 quad_perm:[1,0,3,2] row_mask:0xf bank_mask:0xf bound_ctrl:1
	v_pk_add_f32 v[28:29], v[28:29], v[36:37]
	v_lshlrev_b64 v[46:47], 11, v[14:15]
	v_lshl_add_u64 v[46:47], s[16:17], 0, v[46:47]
	v_mov_b32_dpp v37, v29 quad_perm:[2,3,0,1] row_mask:0xf bank_mask:0xf bound_ctrl:1
	v_mov_b32_dpp v36, v28 quad_perm:[2,3,0,1] row_mask:0xf bank_mask:0xf bound_ctrl:1
	v_pk_add_f32 v[28:29], v[28:29], v[36:37]
	v_lshl_add_u64 v[46:47], v[46:47], 0, v[6:7]
	s_nop 0
	v_mov_b32_dpp v37, v29 row_half_mirror row_mask:0xf bank_mask:0xf bound_ctrl:1
	v_mov_b32_dpp v36, v28 row_half_mirror row_mask:0xf bank_mask:0xf bound_ctrl:1
	v_pk_add_f32 v[28:29], v[28:29], v[36:37]
	s_nop 1
	v_mov_b32_dpp v37, v29 row_mirror row_mask:0xf bank_mask:0xf bound_ctrl:1
	v_mov_b32_dpp v36, v28 row_mirror row_mask:0xf bank_mask:0xf bound_ctrl:1
	v_pk_add_f32 v[36:37], v[28:29], v[36:37]
	v_mov_b64_e32 v[28:29], s[6:7]
	v_pk_fma_f32 v[36:37], v[36:37], s[12:13], v[28:29] op_sel_hi:[1,0,0]
	s_nop 0
	v_mul_f32_e32 v42, 0x4b800000, v37
	v_cmp_gt_f32_e64 s[6:7], s13, v37
	s_nop 1
	v_cndmask_b32_e64 v37, v37, v42, s[6:7]
	v_rsq_f32_e32 v37, v37
	v_div_fmas_f32 v42, v58, v60, v55
	v_div_fixup_f32 v32, v42, v32, v54
	v_cmp_gt_f32_e32 vcc, s13, v36
	v_mul_f32_e32 v42, 0x45800000, v37
	v_cndmask_b32_e64 v42, v37, v42, s[6:7]
	v_pk_mul_f32 v[34:35], v[34:35], v[42:43] op_sel_hi:[1,0]
	v_pk_mul_f32 v[38:39], v[38:39], v[42:43] op_sel_hi:[1,0]
	v_pk_mul_f32 v[34:35], v[0:1], v[34:35]
	v_pk_mul_f32 v[38:39], v[2:3], v[38:39]
	v_mul_f32_e32 v37, 0x4b800000, v36
	v_pk_mul_f32 v[34:35], v[40:41], v[34:35]
	v_pk_mul_f32 v[38:39], v[44:45], v[38:39]
	v_cndmask_b32_e32 v36, v36, v37, vcc
	v_cvt_pk_bf16_f32 v34, v34, v35
	v_cvt_pk_bf16_f32 v35, v38, v39
	v_rsq_f32_e32 v38, v36
	v_add_co_u32_e64 v36, s[6:7], s8, v46
	v_lshlrev_b32_e32 v44, 16, v16
	s_nop 0
	v_addc_co_u32_e64 v37, s[6:7], 0, v47, s[6:7]
	flat_store_dwordx2 v[36:37], v[34:35] offset:1024 sc1
	v_mul_f32_e32 v34, 0xbfb8aa3b, v56
	v_mul_f32_e32 v35, 0xbfb8aa3b, v57
	v_exp_f32_e32 v34, v34
	v_exp_f32_e32 v35, v35
	v_mul_f32_e32 v36, 0x45800000, v38
	v_cndmask_b32_e32 v36, v38, v36, vcc
	v_pk_mul_f32 v[38:39], v[48:49], v[36:37] op_sel_hi:[1,0]
	v_pk_add_f32 v[34:35], v[34:35], 1.0 op_sel_hi:[1,0]
	v_pk_mul_f32 v[38:39], v[0:1], v[38:39]
	v_div_scale_f32 v37, s[6:7], v35, v35, v57
	v_rcp_f32_e32 v40, v37
	v_pk_mul_f32 v[30:31], v[30:31], v[36:37] op_sel_hi:[1,0]
	v_pk_mul_f32 v[32:33], v[32:33], v[38:39]
	v_pk_mul_f32 v[30:31], v[2:3], v[30:31]
	v_fma_f32 v36, -v37, v40, 1.0
	v_fmac_f32_e32 v40, v36, v40
	v_div_scale_f32 v36, vcc, v57, v35, v57
	v_mul_f32_e32 v38, v36, v40
	v_fma_f32 v39, -v37, v38, v36
	v_fmac_f32_e32 v38, v39, v40
	v_fma_f32 v36, -v37, v38, v36
	v_div_scale_f32 v37, s[6:7], v34, v34, v56
	v_rcp_f32_e32 v39, v37
	v_div_fmas_f32 v36, v36, v40, v38
	v_div_fixup_f32 v35, v36, v35, v57
	v_cvt_pk_bf16_f32 v32, v32, v33
	v_fma_f32 v36, -v37, v39, 1.0
	v_fmac_f32_e32 v39, v36, v39
	v_div_scale_f32 v36, vcc, v56, v34, v56
	v_mul_f32_e32 v38, v36, v39
	v_fma_f32 v40, -v37, v38, v36
	v_fmac_f32_e32 v38, v40, v39
	v_fma_f32 v36, -v37, v38, v36
	v_div_fmas_f32 v36, v36, v39, v38
	v_div_fixup_f32 v34, v36, v34, v56
	v_pk_mul_f32 v[30:31], v[34:35], v[30:31]
	v_lshlrev_b32_e32 v36, 16, v22
	v_cvt_pk_bf16_f32 v33, v30, v31
	v_lshlrev_b64 v[30:31], 11, v[12:13]
	v_and_b32_e32 v37, 0xffff0000, v22
	v_mul_f32_e32 v22, 0xbfb8aa3b, v36
	v_lshl_add_u64 v[30:31], s[16:17], 0, v[30:31]
	v_exp_f32_e32 v34, v22
	v_mul_f32_e32 v22, 0xbfb8aa3b, v37
	v_lshl_add_u64 v[30:31], v[30:31], 0, v[6:7]
	v_exp_f32_e32 v35, v22
	v_add_co_u32_e32 v30, vcc, s8, v30
	v_lshlrev_b32_e32 v38, 16, v23
	s_nop 0
	v_addc_co_u32_e32 v31, vcc, 0, v31, vcc
	flat_store_dwordx2 v[30:31], v[32:33] offset:1024 sc1
	v_lshlrev_b32_e32 v30, 16, v24
	v_lshlrev_b32_e32 v32, 16, v26
	v_and_b32_e32 v31, 0xffff0000, v24
	v_and_b32_e32 v33, 0xffff0000, v26
	v_lshlrev_b32_e32 v24, 16, v25
	v_lshlrev_b32_e32 v26, 16, v27
	v_and_b32_e32 v25, 0xffff0000, v25
	v_and_b32_e32 v27, 0xffff0000, v27
	v_and_b32_e32 v39, 0xffff0000, v23
	v_pk_add_f32 v[22:23], v[24:25], v[26:27]
	v_pk_add_f32 v[24:25], v[34:35], 1.0 op_sel_hi:[1,0]
	v_and_b32_e32 v45, 0xffff0000, v16
	v_div_scale_f32 v34, s[6:7], v25, v25, v37
	v_rcp_f32_e32 v35, v34
	v_mul_f32_e32 v16, 0xbfb8aa3b, v44
	v_lshlrev_b32_e32 v46, 16, v17
	v_and_b32_e32 v47, 0xffff0000, v17
	v_fma_f32 v40, -v34, v35, 1.0
	v_fmac_f32_e32 v35, v40, v35
	v_div_scale_f32 v40, vcc, v37, v25, v37
	v_mul_f32_e32 v41, v40, v35
	v_fma_f32 v42, -v34, v41, v40
	v_fmac_f32_e32 v41, v42, v35
	v_fma_f32 v34, -v34, v41, v40
	v_div_scale_f32 v40, s[6:7], v24, v24, v36
	v_rcp_f32_e32 v42, v40
	v_div_fmas_f32 v34, v34, v35, v41
	v_div_fixup_f32 v25, v34, v25, v37
	v_mul_f32_e32 v35, 0xbfb8aa3b, v39
	v_fma_f32 v34, -v40, v42, 1.0
	v_fmac_f32_e32 v42, v34, v42
	v_mul_f32_e32 v34, 0xbfb8aa3b, v38
	v_exp_f32_e32 v34, v34
	v_exp_f32_e32 v35, v35
	v_div_scale_f32 v37, vcc, v36, v24, v36
	v_mul_f32_e32 v41, v37, v42
	v_fma_f32 v43, -v40, v41, v37
	v_fmac_f32_e32 v41, v43, v42
	v_pk_add_f32 v[34:35], v[34:35], 1.0 op_sel_hi:[1,0]
	v_fma_f32 v37, -v40, v41, v37
	v_div_scale_f32 v40, s[6:7], v35, v35, v39
	v_rcp_f32_e32 v43, v40
	v_div_fmas_f32 v37, v37, v42, v41
	v_div_fixup_f32 v24, v37, v24, v36
	v_exp_f32_e32 v42, v16
	v_fma_f32 v36, -v40, v43, 1.0
	v_fmac_f32_e32 v43, v36, v43
	v_div_scale_f32 v36, vcc, v39, v35, v39
	v_mul_f32_e32 v37, v36, v43
	v_fma_f32 v41, -v40, v37, v36
	v_fmac_f32_e32 v37, v41, v43
	v_fma_f32 v36, -v40, v37, v36
	v_div_scale_f32 v40, s[6:7], v34, v34, v38
	v_rcp_f32_e32 v41, v40
	v_div_fmas_f32 v36, v36, v43, v37
	v_div_fixup_f32 v35, v36, v35, v39
	v_mul_f32_e32 v16, 0xbfb8aa3b, v45
	v_fma_f32 v36, -v40, v41, 1.0
	v_fmac_f32_e32 v41, v36, v41
	v_div_scale_f32 v36, vcc, v38, v34, v38
	v_mul_f32_e32 v37, v36, v41
	v_fma_f32 v39, -v40, v37, v36
	v_fmac_f32_e32 v37, v39, v41
	v_exp_f32_e32 v43, v16
	v_fma_f32 v36, -v40, v37, v36
	v_div_fmas_f32 v36, v36, v41, v37
	v_div_fixup_f32 v34, v36, v34, v38
	v_lshlrev_b32_e32 v38, 16, v18
	v_lshlrev_b32_e32 v40, 16, v20
	v_and_b32_e32 v39, 0xffff0000, v18
	v_and_b32_e32 v41, 0xffff0000, v20
	v_lshlrev_b32_e32 v18, 16, v19
	v_lshlrev_b32_e32 v20, 16, v21
	v_and_b32_e32 v19, 0xffff0000, v19
	v_and_b32_e32 v21, 0xffff0000, v21
	v_pk_add_f32 v[16:17], v[18:19], v[20:21]
	v_pk_add_f32 v[18:19], v[42:43], 1.0 op_sel_hi:[1,0]
	v_pk_add_f32 v[30:31], v[30:31], v[32:33]
	v_div_scale_f32 v42, s[6:7], v19, v19, v45
	v_rcp_f32_e32 v43, v42
	v_pk_add_f32 v[38:39], v[38:39], v[40:41]
	v_pk_mul_f32 v[32:33], v[30:31], v[30:31]
	v_pk_mul_f32 v[40:41], v[38:39], v[38:39]
	v_fma_f32 v48, -v42, v43, 1.0
	v_fmac_f32_e32 v43, v48, v43
	v_div_scale_f32 v48, vcc, v45, v19, v45
	v_mul_f32_e32 v49, v48, v43
	v_fma_f32 v50, -v42, v49, v48
	v_fmac_f32_e32 v49, v50, v43
	v_fma_f32 v42, -v42, v49, v48
	v_div_scale_f32 v48, s[6:7], v18, v18, v44
	v_rcp_f32_e32 v50, v48
	v_div_fmas_f32 v42, v42, v43, v49
	v_div_fixup_f32 v19, v42, v19, v45
	v_pk_mul_f32 v[26:27], v[22:23], v[22:23]
	v_fma_f32 v42, -v48, v50, 1.0
	v_fmac_f32_e32 v50, v42, v50
	v_div_scale_f32 v42, vcc, v44, v18, v44
	v_mul_f32_e32 v45, v42, v50
	v_fma_f32 v43, -v48, v45, v42
	v_fmac_f32_e32 v45, v43, v50
	v_pk_mul_f32 v[20:21], v[16:17], v[16:17]
	v_fma_f32 v48, -v48, v45, v42
	v_mov_b32_e32 v42, v40
	v_mov_b32_e32 v43, v32
	v_mov_b32_e32 v32, v41
	v_pk_add_f32 v[32:33], v[42:43], v[32:33]
	v_mov_b32_e32 v40, v20
	v_mov_b32_e32 v41, v26
	v_pk_add_f32 v[32:33], v[32:33], v[40:41]
	v_mov_b32_e32 v26, v21
	v_pk_add_f32 v[20:21], v[26:27], v[32:33]
	v_lshlrev_b64 v[36:37], 11, v[10:11]
	v_lshl_add_u64 v[36:37], s[16:17], 0, v[36:37]
	v_mov_b32_dpp v27, v21 quad_perm:[1,0,3,2] row_mask:0xf bank_mask:0xf bound_ctrl:1
	v_mov_b32_dpp v26, v20 quad_perm:[1,0,3,2] row_mask:0xf bank_mask:0xf bound_ctrl:1
	v_pk_add_f32 v[20:21], v[20:21], v[26:27]
	v_lshl_add_u64 v[36:37], v[36:37], 0, v[6:7]
	s_nop 0
	v_mov_b32_dpp v27, v21 quad_perm:[2,3,0,1] row_mask:0xf bank_mask:0xf bound_ctrl:1
	v_mov_b32_dpp v26, v20 quad_perm:[2,3,0,1] row_mask:0xf bank_mask:0xf bound_ctrl:1
	v_pk_add_f32 v[20:21], v[20:21], v[26:27]
	s_nop 1
	v_mov_b32_dpp v27, v21 row_half_mirror row_mask:0xf bank_mask:0xf bound_ctrl:1
	v_mov_b32_dpp v26, v20 row_half_mirror row_mask:0xf bank_mask:0xf bound_ctrl:1
	v_pk_add_f32 v[20:21], v[20:21], v[26:27]
	s_nop 1
	v_mov_b32_dpp v27, v21 row_mirror row_mask:0xf bank_mask:0xf bound_ctrl:1
	v_mov_b32_dpp v26, v20 row_mirror row_mask:0xf bank_mask:0xf bound_ctrl:1
	v_pk_add_f32 v[20:21], v[20:21], v[26:27]
	s_nop 0
	v_pk_fma_f32 v[20:21], v[20:21], s[12:13], v[28:29] op_sel_hi:[1,0,0]
	s_nop 0
	v_mul_f32_e32 v26, 0x4b800000, v21
	v_cmp_gt_f32_e64 s[6:7], s13, v21
	s_nop 1
	v_cndmask_b32_e64 v21, v21, v26, s[6:7]
	v_rsq_f32_e32 v21, v21
	v_div_fmas_f32 v26, v48, v50, v45
	v_div_fixup_f32 v18, v26, v18, v44
	v_cmp_gt_f32_e32 vcc, s13, v20
	v_mul_f32_e32 v26, 0x45800000, v21
	v_cndmask_b32_e64 v26, v21, v26, s[6:7]
	v_pk_mul_f32 v[28:29], v[30:31], v[26:27] op_sel_hi:[1,0]
	v_pk_mul_f32 v[22:23], v[22:23], v[26:27] op_sel_hi:[1,0]
	v_pk_mul_f32 v[28:29], v[0:1], v[28:29]
	v_pk_mul_f32 v[22:23], v[2:3], v[22:23]
	v_mul_f32_e32 v21, 0x4b800000, v20
	v_pk_mul_f32 v[24:25], v[24:25], v[28:29]
	v_pk_mul_f32 v[22:23], v[34:35], v[22:23]
	v_cndmask_b32_e32 v20, v20, v21, vcc
	v_cvt_pk_bf16_f32 v24, v24, v25
	v_cvt_pk_bf16_f32 v25, v22, v23
	v_rsq_f32_e32 v22, v20
	v_add_co_u32_e64 v20, s[6:7], s8, v36
	v_mul_f32_e32 v23, 0x45800000, v22
	s_nop 0
	v_addc_co_u32_e64 v21, s[6:7], 0, v37, s[6:7]
	flat_store_dwordx2 v[20:21], v[24:25] offset:1024 sc1
	v_mul_f32_e32 v20, 0xbfb8aa3b, v46
	v_mul_f32_e32 v21, 0xbfb8aa3b, v47
	v_exp_f32_e32 v20, v20
	v_exp_f32_e32 v21, v21
	v_cndmask_b32_e32 v22, v22, v23, vcc
	v_pk_mul_f32 v[24:25], v[38:39], v[22:23] op_sel_hi:[1,0]
	v_pk_add_f32 v[20:21], v[20:21], 1.0 op_sel_hi:[1,0]
	s_nop 0
	v_div_scale_f32 v23, s[6:7], v21, v21, v47
	v_pk_mul_f32 v[0:1], v[0:1], v[24:25]
	v_rcp_f32_e32 v24, v23
	v_pk_mul_f32 v[16:17], v[16:17], v[22:23] op_sel_hi:[1,0]
	v_pk_mul_f32 v[0:1], v[18:19], v[0:1]
	v_pk_mul_f32 v[2:3], v[2:3], v[16:17]
	v_fma_f32 v16, -v23, v24, 1.0
	v_fmac_f32_e32 v24, v16, v24
	v_div_scale_f32 v16, vcc, v47, v21, v47
	v_mul_f32_e32 v17, v16, v24
	v_fma_f32 v18, -v23, v17, v16
	v_fmac_f32_e32 v17, v18, v24
	v_div_scale_f32 v18, s[6:7], v20, v20, v46
	v_rcp_f32_e32 v19, v18
	v_fma_f32 v16, -v23, v17, v16
	v_div_fmas_f32 v16, v16, v24, v17
	v_div_fixup_f32 v17, v16, v21, v47
	v_fma_f32 v16, -v18, v19, 1.0
	v_fmac_f32_e32 v19, v16, v19
	v_div_scale_f32 v16, vcc, v46, v20, v46
	v_mul_f32_e32 v21, v16, v19
	v_fma_f32 v22, -v18, v21, v16
	v_fmac_f32_e32 v21, v22, v19
	v_fma_f32 v16, -v18, v21, v16
	v_div_fmas_f32 v16, v16, v19, v21
	v_div_fixup_f32 v16, v16, v20, v46
	v_pk_mul_f32 v[2:3], v[16:17], v[2:3]
	v_cvt_pk_bf16_f32 v0, v0, v1
	v_cvt_pk_bf16_f32 v1, v2, v3
	v_lshlrev_b64 v[2:3], 11, v[8:9]
	v_lshl_add_u64 v[2:3], s[16:17], 0, v[2:3]
	v_lshl_add_u64 v[2:3], v[2:3], 0, v[6:7]
	v_add_co_u32_e32 v2, vcc, 0x4552000, v2
	s_nop 1
	v_addc_co_u32_e32 v3, vcc, 0, v3, vcc
	flat_store_dwordx2 v[2:3], v[0:1] offset:1024 sc1
	s_waitcnt vmcnt(0)
	s_and_saveexec_b64 s[6:7], s[4:5]
	s_cbranch_execz .LBB0_1427
	v_alignbit_b32 v0, v15, v14, 8
	v_alignbit_b32 v1, v5, v4, 8
	v_cmp_eq_u32_e32 vcc, v0, v1
	v_alignbit_b32 v2, v13, v12, 8
	v_alignbit_b32 v3, v9, v8, 8
	v_cndmask_b32_e64 v0, 1, 2, vcc
	v_cmp_eq_u32_e32 vcc, v2, v1
	v_alignbit_b32 v2, v11, v10, 8
	s_mov_b64 s[4:5], s[10:11]
	v_addc_co_u32_e32 v0, vcc, 0, v0, vcc
	v_cmp_eq_u32_e32 vcc, v2, v1
	s_nop 1
	v_cndmask_b32_e64 v2, 0, 1, vcc
	v_cmp_eq_u32_e32 vcc, v3, v1
	s_nop 1
	v_addc_co_u32_e32 v2, vcc, v0, v2, vcc
	v_lshlrev_b32_e32 v0, 6, v1
	v_ashrrev_i32_e32 v1, 31, v0
	v_lshl_add_u64 v[4:5], v[0:1], 2, s[18:19]
	flat_atomic_add v[4:5], v2
	v_cmp_gt_u32_e32 vcc, 5, v2
	s_and_saveexec_b64 s[8:9], vcc
	v_sub_u32_e32 v1, 5, v2
	s_or_b64 s[4:5], s[10:11], exec
	s_or_b64 exec, exec, s[8:9]
	s_andn2_b64 s[8:9], s[10:11], exec
	s_and_b64 s[4:5], s[4:5], exec
	s_or_b64 s[10:11], s[8:9], s[4:5]

.LBB0_1683:
	v_ashrrev_i32_e32 v75, 31, v74
	v_lshlrev_b64 v[0:1], 12, v[74:75]
	v_lshl_add_u64 v[102:103], s[18:19], 0, v[0:1]
	v_add_u32_e32 v0, 0xfffff000, v74
	v_lshrrev_b32_e32 v0, 11, v0
	v_add_u32_e32 v0, 1, v0
	v_cmp_lt_i32_e32 vcc, s33, v74
	v_lshl_add_u64 v[8:9], v[102:103], 0, v[76:77]
	global_load_dwordx4 v[10:13], v[8:9], off offset:2048
	global_load_dwordx4 v[40:43], v[8:9], off offset:3072
	v_cndmask_b32_e32 v83, 0, v0, vcc
	v_mad_u64_u32 v[0:1], s[6:7], v83, s36, v[66:67]
	global_load_dwordx4 v[44:47], v[0:1], off
	global_load_dwordx4 v[48:51], v[64:65], off
	global_load_dwordx4 v[52:55], v[64:65], off offset:16
	global_load_dwordx4 v[90:93], v[0:1], off offset:16
	global_load_dwordx4 v[94:97], v[0:1], off offset:2048
	global_load_dwordx4 v[98:101], v[64:65], off offset:2048
	global_load_dwordx4 v[104:107], v[64:65], off offset:2064
	global_load_dwordx4 v[118:121], v[0:1], off offset:2064
	v_lshlrev_b64 v[0:1], 11, v[74:75]
	v_lshl_add_u64 v[0:1], v[62:63], 0, v[0:1]
	global_load_dwordx4 v[122:125], v[0:1], off
	global_load_dwordx4 v[126:129], v[0:1], off offset:1024
	v_add_u32_e32 v0, 1, v74
	v_ashrrev_i32_e32 v1, 31, v0
	v_lshlrev_b64 v[6:7], 12, v[0:1]
	v_lshlrev_b64 v[0:1], 11, v[0:1]
	v_lshl_add_u64 v[0:1], v[62:63], 0, v[0:1]
	global_load_dwordx4 v[130:133], v[0:1], off
	global_load_dwordx4 v[134:137], v[0:1], off offset:1024
	v_add_u32_e32 v2, 2, v74
	v_add_u32_e32 v4, 3, v74
	v_ashrrev_i32_e32 v3, 31, v2
	v_ashrrev_i32_e32 v5, 31, v4
	v_lshlrev_b64 v[14:15], 12, v[2:3]
	v_lshlrev_b64 v[2:3], 11, v[2:3]
	v_lshlrev_b64 v[16:17], 12, v[4:5]
	v_lshlrev_b64 v[4:5], 11, v[4:5]
	v_lshl_add_u64 v[112:113], s[18:19], 0, v[6:7]
	v_lshl_add_u64 v[110:111], s[18:19], 0, v[14:15]
	v_lshl_add_u64 v[2:3], v[62:63], 0, v[2:3]
	v_lshl_add_u64 v[88:89], v[72:73], 0, v[16:17]
	v_lshl_add_u64 v[14:15], v[62:63], 0, v[4:5]
	v_lshl_add_u64 v[114:115], v[112:113], 0, v[76:77]
	v_lshl_add_u64 v[116:117], v[110:111], 0, v[76:77]
	global_load_dwordx4 v[142:145], v[2:3], off
	global_load_dwordx4 v[150:153], v[2:3], off offset:1024
	global_load_dwordx4 v[20:23], v[88:89], off offset:2048
	global_load_dwordx4 v[16:19], v[88:89], off offset:3072
	global_load_dwordx4 v[4:7], v[14:15], off
	s_nop 0
	global_load_dwordx4 v[0:3], v[14:15], off offset:1024
	global_load_dwordx4 v[36:39], v[114:115], off offset:2048
	global_load_dwordx4 v[32:35], v[114:115], off offset:3072
	global_load_dwordx4 v[28:31], v[116:117], off offset:2048
	global_load_dwordx4 v[24:27], v[116:117], off offset:3072
	s_waitcnt vmcnt(0) lgkmcnt(0)
	v_lshlrev_b32_e32 v14, 16, v10
	v_lshlrev_b32_e32 v140, 16, v40
	v_and_b32_e32 v141, 0xffff0000, v40
	v_lshlrev_b32_e32 v146, 16, v41
	v_and_b32_e32 v147, 0xffff0000, v41
	v_pk_mul_f32 v[40:41], v[50:51], v[46:47]
	v_lshlrev_b32_e32 v148, 16, v42
	v_and_b32_e32 v149, 0xffff0000, v42
	v_lshlrev_b32_e32 v154, 16, v43
	v_and_b32_e32 v155, 0xffff0000, v43
	v_pk_mul_f32 v[42:43], v[48:49], v[44:45]
	v_pk_mul_f32 v[48:49], v[100:101], v[96:97]
	v_pk_mul_f32 v[96:97], v[78:79], v[40:41]
	v_lshlrev_b32_e32 v40, 16, v122
	v_and_b32_e32 v41, 0xffff0000, v122
	v_pk_mul_f32 v[44:45], v[54:55], v[92:93]
	v_pk_mul_f32 v[46:47], v[52:53], v[90:91]
	v_pk_mul_f32 v[100:101], v[70:71], v[42:43]
	v_lshlrev_b32_e32 v42, 16, v123
	v_and_b32_e32 v43, 0xffff0000, v123
	v_pk_mul_f32 v[156:157], v[40:41], v[40:41]
	v_pk_mul_f32 v[50:51], v[98:99], v[94:95]
	v_pk_mul_f32 v[54:55], v[104:105], v[118:119]
	v_pk_mul_f32 v[92:93], v[78:79], v[44:45]
	v_pk_mul_f32 v[98:99], v[70:71], v[46:47]
	v_lshlrev_b32_e32 v44, 16, v124
	v_and_b32_e32 v45, 0xffff0000, v124
	v_lshlrev_b32_e32 v46, 16, v125
	v_and_b32_e32 v47, 0xffff0000, v125
	v_lshlrev_b32_e32 v118, 16, v128
	v_and_b32_e32 v119, 0xffff0000, v128
	v_lshlrev_b32_e32 v124, 16, v129
	v_and_b32_e32 v125, 0xffff0000, v129
	v_pk_mul_f32 v[128:129], v[42:43], v[42:43]
	v_add_f32_e32 v56, v156, v157
	v_add_f32_e32 v56, v128, v56
	v_pk_mul_f32 v[90:91], v[78:79], v[48:49]
	v_pk_mul_f32 v[94:95], v[70:71], v[50:51]
	v_lshlrev_b32_e32 v48, 16, v126
	v_and_b32_e32 v49, 0xffff0000, v126
	v_lshlrev_b32_e32 v50, 16, v127
	v_and_b32_e32 v51, 0xffff0000, v127
	v_pk_mul_f32 v[126:127], v[44:45], v[44:45]
	v_add_f32_e32 v56, v129, v56
	v_add_f32_e32 v56, v126, v56
	v_pk_mul_f32 v[122:123], v[46:47], v[46:47]
	v_add_f32_e32 v56, v127, v56
	v_add_f32_e32 v56, v122, v56
	v_pk_mul_f32 v[52:53], v[106:107], v[120:121]
	v_pk_mul_f32 v[120:121], v[48:49], v[48:49]
	v_add_f32_e32 v56, v123, v56
	v_add_f32_e32 v56, v120, v56
	v_pk_mul_f32 v[108:109], v[50:51], v[50:51]
	v_add_f32_e32 v56, v121, v56
	v_add_f32_e32 v56, v108, v56
	v_pk_mul_f32 v[106:107], v[118:119], v[118:119]
	v_add_f32_e32 v56, v109, v56
	v_add_f32_e32 v56, v106, v56
	v_pk_mul_f32 v[104:105], v[124:125], v[124:125]
	v_add_f32_e32 v56, v107, v56
	v_add_f32_e32 v56, v104, v56
	v_add_f32_e32 v56, v105, v56
	v_lshlrev_b32_e32 v104, 16, v130
	v_and_b32_e32 v105, 0xffff0000, v130
	v_add_f32_dpp v56, v56, v56 quad_perm:[1,0,3,2] row_mask:0xf bank_mask:0xf bound_ctrl:1
	v_lshlrev_b32_e32 v106, 16, v131
	v_and_b32_e32 v107, 0xffff0000, v131
	v_add_f32_dpp v56, v56, v56 quad_perm:[2,3,0,1] row_mask:0xf bank_mask:0xf bound_ctrl:1
	v_pk_mul_f32 v[168:169], v[104:105], v[104:105]
	v_pk_mul_f32 v[156:157], v[106:107], v[106:107]
	v_add_f32_dpp v56, v56, v56 row_half_mirror row_mask:0xf bank_mask:0xf bound_ctrl:1
	v_lshlrev_b32_e32 v108, 16, v132
	v_and_b32_e32 v109, 0xffff0000, v132
	v_add_f32_dpp v56, v56, v56 row_mirror row_mask:0xf bank_mask:0xf bound_ctrl:1
	v_mov_b32_e32 v75, v56
	s_nop 1
	v_permlane16_swap_b32_e32 v56, v75
	v_add_f32_e32 v121, v56, v75
	v_add_f32_e32 v56, v168, v169
	v_add_f32_e32 v56, v156, v56
	v_lshlrev_b32_e32 v164, 16, v136
	v_and_b32_e32 v165, 0xffff0000, v136
	v_lshlrev_b32_e32 v166, 16, v137
	v_and_b32_e32 v167, 0xffff0000, v137
	v_pk_mul_f32 v[136:137], v[108:109], v[108:109]
	v_add_f32_e32 v56, v157, v56
	v_lshlrev_b32_e32 v158, 16, v133
	v_and_b32_e32 v159, 0xffff0000, v133
	v_add_f32_e32 v56, v136, v56
	v_lshlrev_b32_e32 v160, 16, v134
	v_and_b32_e32 v161, 0xffff0000, v134
	v_lshlrev_b32_e32 v162, 16, v135
	v_and_b32_e32 v163, 0xffff0000, v135
	v_pk_mul_f32 v[134:135], v[158:159], v[158:159]
	v_add_f32_e32 v56, v137, v56
	v_add_f32_e32 v56, v134, v56
	v_pk_mul_f32 v[132:133], v[160:161], v[160:161]
	v_add_f32_e32 v56, v135, v56
	v_add_f32_e32 v56, v132, v56
	v_pk_mul_f32 v[130:131], v[162:163], v[162:163]
	v_add_f32_e32 v56, v133, v56
	v_add_f32_e32 v56, v130, v56
	v_pk_mul_f32 v[128:129], v[164:165], v[164:165]
	v_add_f32_e32 v56, v131, v56
	v_add_f32_e32 v56, v128, v56
	v_pk_mul_f32 v[126:127], v[166:167], v[166:167]
	v_add_f32_e32 v56, v129, v56
	v_add_f32_e32 v56, v126, v56
	v_add_f32_e32 v56, v127, v56
	v_mov_b32_e32 v123, v121
	s_nop 1
	v_permlane32_swap_b32_e32 v121, v123
	v_add_f32_dpp v56, v56, v56 quad_perm:[1,0,3,2] row_mask:0xf bank_mask:0xf bound_ctrl:1
	v_and_b32_e32 v15, 0xffff0000, v10
	v_lshlrev_b32_e32 v10, 16, v11
	v_add_f32_dpp v56, v56, v56 quad_perm:[2,3,0,1] row_mask:0xf bank_mask:0xf bound_ctrl:1
	v_and_b32_e32 v11, 0xffff0000, v11
	v_lshlrev_b32_e32 v138, 16, v12
	v_add_f32_dpp v56, v56, v56 row_half_mirror row_mask:0xf bank_mask:0xf bound_ctrl:1
	v_and_b32_e32 v139, 0xffff0000, v12
	v_lshlrev_b32_e32 v12, 16, v13
	v_add_f32_dpp v56, v56, v56 row_mirror row_mask:0xf bank_mask:0xf bound_ctrl:1
	v_mov_b32_e32 v75, v56
	s_nop 1
	v_permlane16_swap_b32_e32 v56, v75
	v_add_f32_e32 v120, v56, v75
	v_mov_b32_e32 v122, v120
	s_nop 1
	v_permlane32_swap_b32_e32 v120, v122
	v_pk_add_f32 v[120:121], v[120:121], v[122:123]
	v_pk_mul_f32 v[122:123], v[70:71], v[54:55]
	v_pk_fma_f32 v[168:169], v[120:121], s[24:25], v[80:81] op_sel_hi:[1,0,0]
	v_pk_mul_f32 v[120:121], v[78:79], v[52:53]
	v_mul_f32_e32 v56, 0x4b800000, v169
	v_cmp_gt_f32_e32 vcc, s37, v169
	v_and_b32_e32 v13, 0xffff0000, v13
	v_lshlrev_b32_e32 v134, 16, v1
	v_cndmask_b32_e32 v56, v169, v56, vcc
	v_rsq_f32_e32 v56, v56
	v_and_b32_e32 v135, 0xffff0000, v1
	v_lshlrev_b32_e32 v136, 16, v2
	v_and_b32_e32 v137, 0xffff0000, v2
	v_mul_f32_e32 v52, 0x45800000, v56
	v_cndmask_b32_e32 v54, v56, v52, vcc
	v_pk_mul_f32 v[40:41], v[54:55], v[40:41] op_sel_hi:[0,1]
	v_pk_fma_f32 v[40:41], v[100:101], v[40:41], v[14:15]
	v_pk_mul_f32 v[14:15], v[54:55], v[42:43] op_sel_hi:[0,1]
	v_pk_fma_f32 v[42:43], v[96:97], v[14:15], v[10:11]
	v_pk_mul_f32 v[10:11], v[54:55], v[44:45] op_sel_hi:[0,1]
	v_pk_fma_f32 v[44:45], v[98:99], v[10:11], v[138:139]
	v_pk_mul_f32 v[10:11], v[54:55], v[46:47] op_sel_hi:[0,1]
	v_pk_fma_f32 v[46:47], v[92:93], v[10:11], v[12:13]
	v_pk_mul_f32 v[10:11], v[54:55], v[48:49] op_sel_hi:[0,1]
	v_pk_fma_f32 v[48:49], v[94:95], v[10:11], v[140:141]
	v_pk_mul_f32 v[10:11], v[54:55], v[50:51] op_sel_hi:[0,1]
	v_pk_fma_f32 v[50:51], v[90:91], v[10:11], v[146:147]
	v_pk_mul_f32 v[10:11], v[54:55], v[118:119] op_sel_hi:[0,1]
	v_lshlrev_b32_e32 v118, 16, v142
	v_and_b32_e32 v119, 0xffff0000, v142
	v_lshlrev_b32_e32 v140, 16, v143
	v_and_b32_e32 v141, 0xffff0000, v143
	v_pk_mul_f32 v[132:133], v[118:119], v[118:119]
	v_pk_mul_f32 v[130:131], v[140:141], v[140:141]
	v_add_f32_e32 v56, v132, v133
	v_lshlrev_b32_e32 v142, 16, v144
	v_and_b32_e32 v143, 0xffff0000, v144
	v_add_f32_e32 v56, v130, v56
	v_pk_mul_f32 v[128:129], v[142:143], v[142:143]
	v_add_f32_e32 v56, v131, v56
	v_lshlrev_b32_e32 v144, 16, v145
	v_and_b32_e32 v145, 0xffff0000, v145
	v_add_f32_e32 v56, v128, v56
	v_pk_mul_f32 v[126:127], v[144:145], v[144:145]
	v_add_f32_e32 v56, v129, v56
	v_lshlrev_b32_e32 v146, 16, v150
	v_and_b32_e32 v147, 0xffff0000, v150
	v_add_f32_e32 v56, v126, v56
	v_pk_fma_f32 v[52:53], v[122:123], v[10:11], v[148:149]
	v_pk_mul_f32 v[10:11], v[54:55], v[124:125] op_sel_hi:[0,1]
	v_pk_mul_f32 v[124:125], v[146:147], v[146:147]
	v_add_f32_e32 v56, v127, v56
	v_lshlrev_b32_e32 v148, 16, v151
	v_and_b32_e32 v149, 0xffff0000, v151
	v_add_f32_e32 v56, v124, v56
	v_pk_mul_f32 v[14:15], v[148:149], v[148:149]
	v_add_f32_e32 v56, v125, v56
	v_lshlrev_b32_e32 v150, 16, v152
	v_and_b32_e32 v151, 0xffff0000, v152
	v_add_f32_e32 v14, v14, v56
	v_pk_mul_f32 v[12:13], v[150:151], v[150:151]
	v_add_f32_e32 v14, v15, v14
	v_lshlrev_b32_e32 v152, 16, v153
	v_and_b32_e32 v153, 0xffff0000, v153
	v_add_f32_e32 v12, v12, v14
	v_pk_fma_f32 v[54:55], v[120:121], v[10:11], v[154:155]
	v_pk_mul_f32 v[10:11], v[152:153], v[152:153]
	v_add_f32_e32 v12, v13, v12
	v_add_f32_e32 v10, v10, v12
	v_add_f32_e32 v10, v11, v10
	v_lshlrev_b32_e32 v124, 16, v4
	v_and_b32_e32 v125, 0xffff0000, v4
	v_add_f32_dpp v10, v10, v10 quad_perm:[1,0,3,2] row_mask:0xf bank_mask:0xf bound_ctrl:1
	v_lshlrev_b32_e32 v126, 16, v5
	v_and_b32_e32 v127, 0xffff0000, v5
	v_add_f32_dpp v10, v10, v10 quad_perm:[2,3,0,1] row_mask:0xf bank_mask:0xf bound_ctrl:1
	v_pk_mul_f32 v[172:173], v[124:125], v[124:125]
	v_pk_mul_f32 v[14:15], v[126:127], v[126:127]
	v_add_f32_dpp v10, v10, v10 row_half_mirror row_mask:0xf bank_mask:0xf bound_ctrl:1
	v_add_f32_e32 v56, v172, v173
	v_lshlrev_b32_e32 v128, 16, v6
	v_add_f32_dpp v10, v10, v10 row_mirror row_mask:0xf bank_mask:0xf bound_ctrl:1
	v_and_b32_e32 v129, 0xffff0000, v6
	v_add_f32_e32 v14, v14, v56
	v_mov_b32_e32 v11, v10
	v_pk_mul_f32 v[12:13], v[128:129], v[128:129]
	v_add_f32_e32 v14, v15, v14
	v_permlane16_swap_b32_e32 v10, v11
	v_lshlrev_b32_e32 v130, 16, v7
	v_and_b32_e32 v131, 0xffff0000, v7
	v_add_f32_e32 v12, v12, v14
	v_add_f32_e32 v155, v10, v11
	v_pk_mul_f32 v[10:11], v[130:131], v[130:131]
	v_add_f32_e32 v12, v13, v12
	v_lshlrev_b32_e32 v132, 16, v0
	v_and_b32_e32 v133, 0xffff0000, v0
	v_add_f32_e32 v10, v10, v12
	v_pk_mul_f32 v[6:7], v[132:133], v[132:133]
	v_add_f32_e32 v10, v11, v10
	v_add_f32_e32 v6, v6, v10
	v_pk_mul_f32 v[4:5], v[134:135], v[134:135]
	v_add_f32_e32 v6, v7, v6
	v_add_f32_e32 v4, v4, v6
	v_lshlrev_b32_e32 v138, 16, v3
	v_and_b32_e32 v139, 0xffff0000, v3
	v_pk_mul_f32 v[2:3], v[136:137], v[136:137]
	v_add_f32_e32 v4, v5, v4
	v_add_f32_e32 v2, v2, v4
	v_pk_mul_f32 v[0:1], v[138:139], v[138:139]
	v_add_f32_e32 v2, v3, v2
	v_add_f32_e32 v0, v0, v2
	v_add_f32_e32 v0, v1, v0
	v_mov_b32_e32 v157, v155
	v_cmp_gt_f32_e64 s[6:7], s37, v168
	v_add_f32_dpp v0, v0, v0 quad_perm:[1,0,3,2] row_mask:0xf bank_mask:0xf bound_ctrl:1
	v_permlane32_swap_b32_e32 v155, v157
	s_nop 0
	v_add_f32_dpp v0, v0, v0 quad_perm:[2,3,0,1] row_mask:0xf bank_mask:0xf bound_ctrl:1
	s_and_b64 vcc, exec, s[22:23]
	s_nop 0
	v_add_f32_dpp v0, v0, v0 row_half_mirror row_mask:0xf bank_mask:0xf bound_ctrl:1
	s_nop 1
	v_add_f32_dpp v0, v0, v0 row_mirror row_mask:0xf bank_mask:0xf bound_ctrl:1
	v_mov_b32_e32 v1, v0
	s_nop 1
	v_permlane16_swap_b32_e32 v0, v1
	v_add_f32_e32 v154, v0, v1
	v_mov_b32_e32 v156, v154
	s_nop 1
	v_permlane32_swap_b32_e32 v154, v156
	s_cbranch_vccz .LBB0_1698
	v_cvt_pk_bf16_f32 v0, v40, v41
	v_cvt_pk_bf16_f32 v1, v42, v43
	v_cvt_pk_bf16_f32 v2, v44, v45
	v_cvt_pk_bf16_f32 v3, v46, v47
	v_cvt_pk_bf16_f32 v176, v48, v49
	v_cvt_pk_bf16_f32 v177, v50, v51
	v_cvt_pk_bf16_f32 v178, v52, v53
	v_cvt_pk_bf16_f32 v179, v54, v55
	flat_store_dwordx4 v[8:9], v[0:3] offset:2048
	v_lshlrev_b32_e32 v4, 16, v0
	v_and_b32_e32 v5, 0xffff0000, v0
	v_lshlrev_b32_e32 v6, 16, v1
	v_and_b32_e32 v7, 0xffff0000, v1
	v_lshlrev_b32_e32 v12, 16, v2
	v_and_b32_e32 v13, 0xffff0000, v2
	v_lshlrev_b32_e32 v14, 16, v3
	v_and_b32_e32 v15, 0xffff0000, v3
	flat_store_dwordx4 v[8:9], v[176:179] offset:3072
	v_lshlrev_b32_e32 v0, 16, v176
	v_and_b32_e32 v1, 0xffff0000, v176
	v_lshlrev_b32_e32 v2, 16, v177
	v_and_b32_e32 v3, 0xffff0000, v177
	v_lshlrev_b32_e32 v8, 16, v178
	v_and_b32_e32 v9, 0xffff0000, v178
	v_lshlrev_b32_e32 v10, 16, v179
	v_and_b32_e32 v11, 0xffff0000, v179
	v_lshlrev_b32_e32 v56, 2, v58
	s_cbranch_execnz .LBB0_1686

.LBB0_1695:
	s_and_b64 vcc, exec, s[6:7]
	s_cbranch_vccnz .LBB0_1682
	v_mul_hi_u32_u24_e32 v17, 0x6000, v83
	v_mul_u32_u24_e32 v16, 0x6000, v83
	v_lshl_add_u64 v[16:17], s[20:21], 0, v[16:17]
	v_lshl_add_u64 v[18:19], v[16:17], 0, s[28:29]
	v_lshl_add_u64 v[20:21], v[18:19], 0, v[56:57]
	v_mov_b32_e32 v83, v57
	global_load_dwordx4 v[98:101], v[20:21], off
	v_lshl_add_u64 v[20:21], v[18:19], 0, v[82:83]
	v_mov_b32_e32 v85, v57
	global_load_dwordx4 v[120:123], v[20:21], off
	v_lshl_add_u64 v[20:21], v[18:19], 0, v[84:85]
	v_mov_b32_e32 v87, v57
	global_load_dwordx4 v[124:127], v[20:21], off
	v_lshl_add_u64 v[18:19], v[18:19], 0, v[86:87]
	global_load_dwordx4 v[128:131], v[18:19], off
	global_load_dwordx4 v[132:135], v[68:69], off
	global_load_dwordx4 v[136:139], v[68:69], off offset:16
	global_load_dwordx4 v[140:143], v[68:69], off offset:2048
	global_load_dwordx4 v[144:147], v[68:69], off offset:2064
	v_lshl_add_u64 v[16:17], v[16:17], 0, s[30:31]
	v_lshl_add_u64 v[18:19], v[16:17], 0, v[56:57]
	global_load_dwordx4 v[28:31], v[18:19], off
	v_lshl_add_u64 v[18:19], v[16:17], 0, v[82:83]
	global_load_dwordx4 v[24:27], v[18:19], off
	v_lshl_add_u64 v[18:19], v[16:17], 0, v[84:85]
	global_load_dwordx4 v[20:23], v[18:19], off
	v_lshl_add_u64 v[16:17], v[16:17], 0, v[86:87]
	global_load_dwordx4 v[16:19], v[16:17], off
	v_mul_f32_e32 v75, v5, v5
	v_mul_f32_e32 v88, v13, v13
	v_mul_f32_e32 v89, v1, v1
	v_fmac_f32_e32 v75, v4, v4
	v_fmac_f32_e32 v88, v12, v12
	v_mul_f32_e32 v110, v9, v9
	v_fmac_f32_e32 v89, v0, v0
	v_fmac_f32_e32 v75, v6, v6
	v_fmac_f32_e32 v88, v14, v14
	v_fmac_f32_e32 v110, v8, v8
	v_fmac_f32_e32 v89, v2, v2
	v_fmac_f32_e32 v75, v7, v7
	v_fmac_f32_e32 v88, v15, v15
	v_fmac_f32_e32 v110, v10, v10
	v_fmac_f32_e32 v89, v3, v3
	v_add_f32_e32 v56, v88, v75
	v_fmac_f32_e32 v110, v11, v11
	v_add_f32_e32 v56, v89, v56
	v_add_f32_e32 v56, v110, v56
	v_mul_f32_e32 v111, v109, v109
	v_mul_f32_e32 v148, v107, v107
	v_add_f32_dpp v56, v56, v56 quad_perm:[1,0,3,2] row_mask:0xf bank_mask:0xf bound_ctrl:1
	v_mul_f32_e32 v150, v55, v55
	v_fmac_f32_e32 v111, v108, v108
	v_add_f32_dpp v56, v56, v56 quad_perm:[2,3,0,1] row_mask:0xf bank_mask:0xf bound_ctrl:1
	v_fmac_f32_e32 v148, v106, v106
	v_fmac_f32_e32 v150, v54, v54
	v_add_f32_dpp v56, v56, v56 row_half_mirror row_mask:0xf bank_mask:0xf bound_ctrl:1
	v_fmac_f32_e32 v111, v104, v104
	v_fmac_f32_e32 v148, v102, v102
	v_add_f32_dpp v56, v56, v56 row_mirror row_mask:0xf bank_mask:0xf bound_ctrl:1
	v_fmac_f32_e32 v150, v50, v50
	v_fmac_f32_e32 v111, v105, v105
	v_fmac_f32_e32 v148, v103, v103
	v_mov_b32_e32 v83, v56
	v_fmac_f32_e32 v150, v51, v51
	v_add_f32_e32 v75, v111, v148
	v_permlane16_swap_b32_e32 v56, v83
	v_add_f32_e32 v149, v56, v83
	v_add_f32_e32 v56, v75, v150
	v_mul_f32_e32 v75, v53, v53
	v_fmac_f32_e32 v75, v52, v52
	v_fmac_f32_e32 v75, v48, v48
	v_fmac_f32_e32 v75, v49, v49
	v_add_f32_e32 v56, v56, v75
	v_mov_b32_e32 v151, v149
	s_nop 1
	v_permlane32_swap_b32_e32 v149, v151
	v_add_f32_dpp v56, v56, v56 quad_perm:[1,0,3,2] row_mask:0xf bank_mask:0xf bound_ctrl:1
	v_add_u32_e32 v83, 0xffffe800, v81
	s_waitcnt vmcnt(0) lgkmcnt(0)
	v_pk_add_f32 v[88:89], v[100:101], 1.0 op_sel_hi:[1,0]
	v_add_f32_dpp v56, v56, v56 quad_perm:[2,3,0,1] row_mask:0xf bank_mask:0xf bound_ctrl:1
	v_pk_add_f32 v[98:99], v[98:99], 1.0 op_sel_hi:[1,0]
	v_pk_add_f32 v[130:131], v[130:131], 1.0 op_sel_hi:[1,0]
	v_add_f32_dpp v56, v56, v56 row_half_mirror row_mask:0xf bank_mask:0xf bound_ctrl:1
	v_pk_add_f32 v[100:101], v[122:123], 1.0 op_sel_hi:[1,0]
	v_pk_add_f32 v[126:127], v[126:127], 1.0 op_sel_hi:[1,0]
	v_add_f32_dpp v56, v56, v56 row_mirror row_mask:0xf bank_mask:0xf bound_ctrl:1
	v_mov_b32_e32 v75, v56
	s_nop 1
	v_permlane16_swap_b32_e32 v56, v75
	v_add_f32_e32 v148, v56, v75
	v_mov_b32_e32 v150, v148
	s_nop 1
	v_permlane32_swap_b32_e32 v148, v150
	v_pk_add_f32 v[122:123], v[120:121], 1.0 op_sel_hi:[1,0]
	v_pk_add_f32 v[152:153], v[124:125], 1.0 op_sel_hi:[1,0]
	v_pk_mul_f32 v[120:121], v[134:135], v[88:89]
	v_pk_mul_f32 v[124:125], v[132:133], v[98:99]
	v_pk_mul_f32 v[98:99], v[142:143], v[126:127]
	v_pk_mul_f32 v[88:89], v[146:147], v[130:131]
	v_pk_add_f32 v[126:127], v[148:149], v[150:151]
	v_mov_b64_e32 v[130:131], s[26:27]
	v_pk_fma_f32 v[132:133], v[126:127], s[24:25], v[130:131] op_sel_hi:[1,0,0]
	v_pk_mul_f32 v[110:111], v[138:139], v[100:101]
	v_mul_f32_e32 v56, 0x4b800000, v133
	v_cmp_gt_f32_e32 vcc, s37, v133
	v_pk_mul_f32 v[100:101], v[140:141], v[152:153]
	v_pk_mul_f32 v[122:123], v[136:137], v[122:123]
	v_cndmask_b32_e32 v56, v133, v56, vcc
	v_rsq_f32_e32 v56, v56
	v_add_u32_e32 v75, 0xffffe400, v81
	v_pk_add_f32 v[128:129], v[128:129], 1.0 op_sel_hi:[1,0]
	v_mul_f32_e32 v85, 0x45800000, v56
	v_cndmask_b32_e32 v56, v56, v85, vcc
	v_pk_mul_f32 v[0:1], v[0:1], v[56:57] op_sel_hi:[1,0]
	v_pk_mul_f32 v[2:3], v[2:3], v[56:57] op_sel_hi:[1,0]
	v_pk_mul_f32 v[4:5], v[4:5], v[56:57] op_sel_hi:[1,0]
	v_pk_mul_f32 v[12:13], v[12:13], v[56:57] op_sel_hi:[1,0]
	v_pk_mul_f32 v[6:7], v[6:7], v[56:57] op_sel_hi:[1,0]
	v_pk_mul_f32 v[14:15], v[14:15], v[56:57] op_sel_hi:[1,0]
	v_pk_fma_f32 v[0:1], v[100:101], v[0:1], v[20:21]
	v_pk_fma_f32 v[2:3], v[98:99], v[2:3], v[22:23]
	v_pk_fma_f32 v[4:5], v[124:125], v[4:5], v[28:29]
	v_pk_fma_f32 v[12:13], v[122:123], v[12:13], v[24:25]
	v_pk_fma_f32 v[6:7], v[120:121], v[6:7], v[30:31]
	v_pk_fma_f32 v[14:15], v[110:111], v[14:15], v[26:27]
	v_cvt_pk_bf16_f32 v0, v0, v1
	v_cvt_pk_bf16_f32 v1, v2, v3
	v_mul_f32_e32 v2, 0x4b800000, v132
	v_cmp_gt_f32_e32 vcc, s37, v132
	v_cvt_pk_bf16_f32 v4, v4, v5
	v_cvt_pk_bf16_f32 v5, v6, v7
	v_cvt_pk_bf16_f32 v6, v12, v13
	v_cvt_pk_bf16_f32 v7, v14, v15
	v_cndmask_b32_e32 v2, v132, v2, vcc
	buffer_store_dwordx4 v[4:7], v75, s[12:15], 0 offen sc1
	v_pk_mul_f32 v[126:127], v[144:145], v[128:129]
	v_add_u32_e32 v12, 0xfffff800, v81
	v_pk_mul_f32 v[4:5], v[8:9], v[56:57] op_sel_hi:[1,0]
	v_rsq_f32_e32 v8, v2
	v_pk_mul_f32 v[6:7], v[10:11], v[56:57] op_sel_hi:[1,0]
	v_pk_fma_f32 v[4:5], v[126:127], v[4:5], v[16:17]
	v_pk_fma_f32 v[6:7], v[88:89], v[6:7], v[18:19]
	v_cvt_pk_bf16_f32 v2, v4, v5
	v_cvt_pk_bf16_f32 v3, v6, v7
	buffer_store_dwordx4 v[0:3], v83, s[12:15], 0 offen sc1
	s_nop 1
	v_mul_f32_e32 v0, 0x45800000, v8
	v_cndmask_b32_e32 v4, v8, v0, vcc
	v_pk_mul_f32 v[0:1], v[108:109], v[4:5] op_sel_hi:[1,0]
	v_pk_mul_f32 v[2:3], v[106:107], v[4:5] op_sel_hi:[1,0]
	v_pk_mul_f32 v[6:7], v[104:105], v[4:5] op_sel_hi:[1,0]
	v_pk_mul_f32 v[8:9], v[102:103], v[4:5] op_sel_hi:[1,0]
	v_pk_fma_f32 v[0:1], v[124:125], v[0:1], v[28:29]
	v_pk_fma_f32 v[2:3], v[122:123], v[2:3], v[24:25]
	v_pk_fma_f32 v[6:7], v[120:121], v[6:7], v[30:31]
	v_pk_fma_f32 v[8:9], v[110:111], v[8:9], v[26:27]
	v_cvt_pk_bf16_f32 v0, v0, v1
	v_cvt_pk_bf16_f32 v1, v6, v7
	v_cvt_pk_bf16_f32 v2, v2, v3
	v_cvt_pk_bf16_f32 v3, v8, v9
	v_add_u32_e32 v5, 0xffffec00, v81
	buffer_store_dwordx4 v[0:3], v5, s[12:15], 0 offen sc1
	v_pk_mul_f32 v[6:7], v[50:51], v[4:5] op_sel_hi:[1,0]
	v_add_u32_e32 v8, 0xfffff000, v81
	v_pk_mul_f32 v[0:1], v[54:55], v[4:5] op_sel_hi:[1,0]
	v_pk_mul_f32 v[2:3], v[52:53], v[4:5] op_sel_hi:[1,0]
	v_pk_mul_f32 v[4:5], v[48:49], v[4:5] op_sel_hi:[1,0]
	v_pk_fma_f32 v[2:3], v[126:127], v[2:3], v[16:17]
	v_pk_fma_f32 v[4:5], v[88:89], v[4:5], v[18:19]
	v_cvt_pk_bf16_f32 v2, v2, v3
	v_cvt_pk_bf16_f32 v3, v4, v5
	v_mul_f32_e32 v4, v115, v115
	v_mul_f32_e32 v5, v119, v119
	v_fmac_f32_e32 v4, v114, v114
	v_fmac_f32_e32 v5, v118, v118
	v_fmac_f32_e32 v4, v42, v42
	v_fmac_f32_e32 v5, v112, v112
	v_fmac_f32_e32 v4, v43, v43
	v_fmac_f32_e32 v5, v113, v113
	v_add_f32_e32 v4, v4, v5
	v_mul_f32_e32 v5, v47, v47
	v_fmac_f32_e32 v5, v46, v46
	v_fmac_f32_e32 v5, v40, v40
	v_fmac_f32_e32 v5, v41, v41
	v_add_f32_e32 v4, v4, v5
	v_mul_f32_e32 v5, v117, v117
	v_fmac_f32_e32 v5, v116, v116
	v_fmac_f32_e32 v5, v44, v44
	v_fmac_f32_e32 v5, v45, v45
	v_add_f32_e32 v4, v4, v5
	v_pk_fma_f32 v[0:1], v[100:101], v[0:1], v[20:21]
	v_pk_fma_f32 v[6:7], v[98:99], v[6:7], v[22:23]
	v_add_f32_dpp v4, v4, v4 quad_perm:[1,0,3,2] row_mask:0xf bank_mask:0xf bound_ctrl:1
	v_cvt_pk_bf16_f32 v0, v0, v1
	v_cvt_pk_bf16_f32 v1, v6, v7
	v_add_f32_dpp v4, v4, v4 quad_perm:[2,3,0,1] row_mask:0xf bank_mask:0xf bound_ctrl:1
	v_mul_f32_e32 v6, v95, v95
	v_fmac_f32_e32 v6, v94, v94
	v_add_f32_dpp v4, v4, v4 row_half_mirror row_mask:0xf bank_mask:0xf bound_ctrl:1
	v_fmac_f32_e32 v6, v90, v90
	v_fmac_f32_e32 v6, v91, v91
	v_add_f32_dpp v4, v4, v4 row_mirror row_mask:0xf bank_mask:0xf bound_ctrl:1
	v_mov_b32_e32 v5, v4
	s_nop 1
	v_permlane16_swap_b32_e32 v4, v5
	v_add_f32_e32 v5, v4, v5
	v_mul_f32_e32 v4, v97, v97
	v_fmac_f32_e32 v4, v96, v96
	v_fmac_f32_e32 v4, v92, v92
	v_fmac_f32_e32 v4, v93, v93
	v_add_f32_e32 v4, v4, v6
	v_mul_f32_e32 v6, v39, v39
	v_fmac_f32_e32 v6, v38, v38
	v_fmac_f32_e32 v6, v34, v34
	v_fmac_f32_e32 v6, v35, v35
	v_add_f32_e32 v4, v4, v6
	v_mul_f32_e32 v6, v37, v37
	v_fmac_f32_e32 v6, v36, v36
	v_fmac_f32_e32 v6, v32, v32
	v_fmac_f32_e32 v6, v33, v33
	v_add_f32_e32 v4, v4, v6
	v_mov_b32_e32 v7, v5
	s_nop 1
	v_permlane32_swap_b32_e32 v5, v7
	v_add_f32_dpp v4, v4, v4 quad_perm:[1,0,3,2] row_mask:0xf bank_mask:0xf bound_ctrl:1
	buffer_store_dwordx4 v[0:3], v8, s[12:15], 0 offen sc1
	s_nop 0
	v_add_f32_dpp v4, v4, v4 quad_perm:[2,3,0,1] row_mask:0xf bank_mask:0xf bound_ctrl:1
	s_nop 1
	v_add_f32_dpp v4, v4, v4 row_half_mirror row_mask:0xf bank_mask:0xf bound_ctrl:1
	s_nop 1
	v_add_f32_dpp v4, v4, v4 row_mirror row_mask:0xf bank_mask:0xf bound_ctrl:1
	v_mov_b32_e32 v6, v4
	s_nop 1
	v_permlane16_swap_b32_e32 v4, v6
	v_add_f32_e32 v4, v4, v6
	v_mov_b32_e32 v6, v4
	s_nop 1
	v_permlane32_swap_b32_e32 v4, v6
	v_pk_add_f32 v[4:5], v[4:5], v[6:7]
	v_add_u32_e32 v7, 0xfffff400, v81
	v_pk_fma_f32 v[4:5], v[4:5], s[24:25], v[130:131] op_sel_hi:[1,0,0]
	s_nop 0
	v_mul_f32_e32 v6, 0x4b800000, v5
	v_cmp_gt_f32_e32 vcc, s37, v5
	s_nop 1
	v_cndmask_b32_e32 v5, v5, v6, vcc
	v_rsq_f32_e32 v5, v5
	s_nop 0
	v_mul_f32_e32 v0, 0x45800000, v5
	v_cndmask_b32_e32 v6, v5, v0, vcc
	v_pk_mul_f32 v[0:1], v[114:115], v[6:7] op_sel_hi:[1,0]
	v_pk_mul_f32 v[2:3], v[118:119], v[6:7] op_sel_hi:[1,0]
	v_pk_mul_f32 v[8:9], v[42:43], v[6:7] op_sel_hi:[1,0]
	v_pk_mul_f32 v[10:11], v[112:113], v[6:7] op_sel_hi:[1,0]
	v_mul_f32_e32 v5, 0x4b800000, v4
	v_cmp_gt_f32_e32 vcc, s37, v4
	v_pk_fma_f32 v[0:1], v[124:125], v[0:1], v[28:29]
	v_pk_fma_f32 v[2:3], v[122:123], v[2:3], v[24:25]
	v_pk_fma_f32 v[8:9], v[120:121], v[8:9], v[30:31]
	v_pk_fma_f32 v[10:11], v[110:111], v[10:11], v[26:27]
	v_cndmask_b32_e32 v4, v4, v5, vcc
	v_cvt_pk_bf16_f32 v0, v0, v1
	v_cvt_pk_bf16_f32 v1, v8, v9
	v_cvt_pk_bf16_f32 v2, v2, v3
	v_cvt_pk_bf16_f32 v3, v10, v11
	v_rsq_f32_e32 v4, v4
	buffer_store_dwordx4 v[0:3], v7, s[12:15], 0 offen sc1
	v_pk_mul_f32 v[8:9], v[40:41], v[6:7] op_sel_hi:[1,0]
	s_nop 0
	v_pk_mul_f32 v[0:1], v[46:47], v[6:7] op_sel_hi:[1,0]
	v_pk_mul_f32 v[2:3], v[116:117], v[6:7] op_sel_hi:[1,0]
	v_pk_mul_f32 v[6:7], v[44:45], v[6:7] op_sel_hi:[1,0]
	v_pk_fma_f32 v[0:1], v[100:101], v[0:1], v[20:21]
	v_pk_fma_f32 v[2:3], v[126:127], v[2:3], v[16:17]
	v_pk_fma_f32 v[8:9], v[98:99], v[8:9], v[22:23]
	v_pk_fma_f32 v[6:7], v[88:89], v[6:7], v[18:19]
	v_cvt_pk_bf16_f32 v0, v0, v1
	v_cvt_pk_bf16_f32 v1, v8, v9
	v_cvt_pk_bf16_f32 v2, v2, v3
	v_cvt_pk_bf16_f32 v3, v6, v7
	buffer_store_dwordx4 v[0:3], v12, s[12:15], 0 offen sc1
	s_nop 1
	v_mul_f32_e32 v0, 0x45800000, v4
	v_cndmask_b32_e32 v4, v4, v0, vcc
	v_pk_mul_f32 v[0:1], v[96:97], v[4:5] op_sel_hi:[1,0]
	v_pk_mul_f32 v[2:3], v[94:95], v[4:5] op_sel_hi:[1,0]
	v_pk_mul_f32 v[6:7], v[92:93], v[4:5] op_sel_hi:[1,0]
	v_pk_mul_f32 v[8:9], v[90:91], v[4:5] op_sel_hi:[1,0]
	v_pk_fma_f32 v[0:1], v[124:125], v[0:1], v[28:29]
	v_pk_fma_f32 v[2:3], v[122:123], v[2:3], v[24:25]
	v_pk_fma_f32 v[6:7], v[120:121], v[6:7], v[30:31]
	v_pk_fma_f32 v[8:9], v[110:111], v[8:9], v[26:27]
	v_cvt_pk_bf16_f32 v0, v0, v1
	v_cvt_pk_bf16_f32 v1, v6, v7
	v_cvt_pk_bf16_f32 v2, v2, v3
	v_cvt_pk_bf16_f32 v3, v8, v9
	v_add_u32_e32 v5, 0xfffffc00, v81
	buffer_store_dwordx4 v[0:3], v5, s[12:15], 0 offen sc1
	v_pk_mul_f32 v[6:7], v[34:35], v[4:5] op_sel_hi:[1,0]
	s_nop 0
	v_pk_mul_f32 v[0:1], v[38:39], v[4:5] op_sel_hi:[1,0]
	v_pk_mul_f32 v[2:3], v[36:37], v[4:5] op_sel_hi:[1,0]
	v_pk_mul_f32 v[4:5], v[32:33], v[4:5] op_sel_hi:[1,0]
	v_pk_fma_f32 v[0:1], v[100:101], v[0:1], v[20:21]
	v_pk_fma_f32 v[2:3], v[126:127], v[2:3], v[16:17]
	v_pk_fma_f32 v[6:7], v[98:99], v[6:7], v[22:23]
	v_pk_fma_f32 v[4:5], v[88:89], v[4:5], v[18:19]
	v_cvt_pk_bf16_f32 v0, v0, v1
	v_cvt_pk_bf16_f32 v1, v6, v7
	v_cvt_pk_bf16_f32 v2, v2, v3
	v_cvt_pk_bf16_f32 v3, v4, v5
	buffer_store_dwordx4 v[0:3], v81, s[12:15], 0 offen sc1
	s_waitcnt vmcnt(0)
	s_and_saveexec_b64 s[6:7], s[4:5]
	s_cbranch_execz .LBB0_1681
	v_ashrrev_i32_e32 v0, 2, v74
	v_and_b32_e32 v0, 0xffffffc0, v0
	v_ashrrev_i32_e32 v1, 31, v0
	v_lshl_add_u64 v[0:1], v[0:1], 2, s[16:17]
	flat_atomic_add v[0:1], v170
	s_branch .LBB0_1681

.LBB0_2073:
	v_ashrrev_i32_e32 v77, 31, v76
	v_lshlrev_b64 v[0:1], 12, v[76:77]
	v_lshl_add_u64 v[104:105], s[18:19], 0, v[0:1]
	v_add_u32_e32 v0, 0xfffff000, v76
	v_lshrrev_b32_e32 v0, 11, v0
	v_add_u32_e32 v0, 1, v0
	v_cmp_lt_i32_e32 vcc, s33, v76
	v_lshl_add_u64 v[8:9], v[104:105], 0, v[78:79]
	global_load_dwordx4 v[10:13], v[8:9], off offset:2048
	global_load_dwordx4 v[40:43], v[8:9], off offset:3072
	v_cndmask_b32_e32 v85, 0, v0, vcc
	v_mad_u64_u32 v[0:1], s[6:7], v85, s34, v[66:67]
	global_load_dwordx4 v[44:47], v[0:1], off
	global_load_dwordx4 v[48:51], v[64:65], off
	global_load_dwordx4 v[52:55], v[64:65], off offset:16
	global_load_dwordx4 v[92:95], v[0:1], off offset:16
	global_load_dwordx4 v[96:99], v[0:1], off offset:2048
	global_load_dwordx4 v[100:103], v[64:65], off offset:2048
	global_load_dwordx4 v[106:109], v[64:65], off offset:2064
	global_load_dwordx4 v[120:123], v[0:1], off offset:2064
	v_lshlrev_b64 v[0:1], 11, v[76:77]
	v_lshl_add_u64 v[0:1], v[62:63], 0, v[0:1]
	global_load_dwordx4 v[124:127], v[0:1], off
	global_load_dwordx4 v[128:131], v[0:1], off offset:1024
	v_add_u32_e32 v0, 1, v76
	v_ashrrev_i32_e32 v1, 31, v0
	v_lshlrev_b64 v[6:7], 12, v[0:1]
	v_lshlrev_b64 v[0:1], 11, v[0:1]
	v_lshl_add_u64 v[0:1], v[62:63], 0, v[0:1]
	global_load_dwordx4 v[132:135], v[0:1], off
	global_load_dwordx4 v[136:139], v[0:1], off offset:1024
	v_add_u32_e32 v2, 2, v76
	v_add_u32_e32 v4, 3, v76
	v_ashrrev_i32_e32 v3, 31, v2
	v_ashrrev_i32_e32 v5, 31, v4
	v_lshlrev_b64 v[14:15], 12, v[2:3]
	v_lshlrev_b64 v[2:3], 11, v[2:3]
	v_lshlrev_b64 v[16:17], 12, v[4:5]
	v_lshlrev_b64 v[4:5], 11, v[4:5]
	v_lshl_add_u64 v[114:115], s[18:19], 0, v[6:7]
	v_lshl_add_u64 v[112:113], s[18:19], 0, v[14:15]
	v_lshl_add_u64 v[2:3], v[62:63], 0, v[2:3]
	v_lshl_add_u64 v[90:91], v[74:75], 0, v[16:17]
	v_lshl_add_u64 v[14:15], v[62:63], 0, v[4:5]
	v_lshl_add_u64 v[116:117], v[114:115], 0, v[78:79]
	v_lshl_add_u64 v[118:119], v[112:113], 0, v[78:79]
	global_load_dwordx4 v[144:147], v[2:3], off
	global_load_dwordx4 v[152:155], v[2:3], off offset:1024
	global_load_dwordx4 v[20:23], v[90:91], off offset:2048
	global_load_dwordx4 v[16:19], v[90:91], off offset:3072
	global_load_dwordx4 v[4:7], v[14:15], off
	s_nop 0
	global_load_dwordx4 v[0:3], v[14:15], off offset:1024
	global_load_dwordx4 v[36:39], v[116:117], off offset:2048
	global_load_dwordx4 v[32:35], v[116:117], off offset:3072
	global_load_dwordx4 v[28:31], v[118:119], off offset:2048
	global_load_dwordx4 v[24:27], v[118:119], off offset:3072
	s_waitcnt vmcnt(0) lgkmcnt(0)
	v_lshlrev_b32_e32 v14, 16, v10
	v_lshlrev_b32_e32 v142, 16, v40
	v_and_b32_e32 v143, 0xffff0000, v40
	v_lshlrev_b32_e32 v148, 16, v41
	v_and_b32_e32 v149, 0xffff0000, v41
	v_pk_mul_f32 v[40:41], v[50:51], v[46:47]
	v_lshlrev_b32_e32 v150, 16, v42
	v_and_b32_e32 v151, 0xffff0000, v42
	v_lshlrev_b32_e32 v156, 16, v43
	v_and_b32_e32 v157, 0xffff0000, v43
	v_pk_mul_f32 v[42:43], v[48:49], v[44:45]
	v_pk_mul_f32 v[48:49], v[102:103], v[98:99]
	v_pk_mul_f32 v[98:99], v[80:81], v[40:41]
	v_lshlrev_b32_e32 v40, 16, v124
	v_and_b32_e32 v41, 0xffff0000, v124
	v_pk_mul_f32 v[44:45], v[54:55], v[94:95]
	v_pk_mul_f32 v[46:47], v[52:53], v[92:93]
	v_pk_mul_f32 v[102:103], v[72:73], v[42:43]
	v_lshlrev_b32_e32 v42, 16, v125
	v_and_b32_e32 v43, 0xffff0000, v125
	v_pk_mul_f32 v[158:159], v[40:41], v[40:41]
	v_pk_mul_f32 v[50:51], v[100:101], v[96:97]
	v_pk_mul_f32 v[54:55], v[106:107], v[120:121]
	v_pk_mul_f32 v[94:95], v[80:81], v[44:45]
	v_pk_mul_f32 v[100:101], v[72:73], v[46:47]
	v_lshlrev_b32_e32 v44, 16, v126
	v_and_b32_e32 v45, 0xffff0000, v126
	v_lshlrev_b32_e32 v46, 16, v127
	v_and_b32_e32 v47, 0xffff0000, v127
	v_lshlrev_b32_e32 v120, 16, v130
	v_and_b32_e32 v121, 0xffff0000, v130
	v_lshlrev_b32_e32 v126, 16, v131
	v_and_b32_e32 v127, 0xffff0000, v131
	v_pk_mul_f32 v[130:131], v[42:43], v[42:43]
	v_add_f32_e32 v56, v158, v159
	v_add_f32_e32 v56, v130, v56
	v_pk_mul_f32 v[92:93], v[80:81], v[48:49]
	v_pk_mul_f32 v[96:97], v[72:73], v[50:51]
	v_lshlrev_b32_e32 v48, 16, v128
	v_and_b32_e32 v49, 0xffff0000, v128
	v_lshlrev_b32_e32 v50, 16, v129
	v_and_b32_e32 v51, 0xffff0000, v129
	v_pk_mul_f32 v[128:129], v[44:45], v[44:45]
	v_add_f32_e32 v56, v131, v56
	v_add_f32_e32 v56, v128, v56
	v_pk_mul_f32 v[124:125], v[46:47], v[46:47]
	v_add_f32_e32 v56, v129, v56
	v_add_f32_e32 v56, v124, v56
	v_pk_mul_f32 v[52:53], v[108:109], v[122:123]
	v_pk_mul_f32 v[122:123], v[48:49], v[48:49]
	v_add_f32_e32 v56, v125, v56
	v_add_f32_e32 v56, v122, v56
	v_pk_mul_f32 v[110:111], v[50:51], v[50:51]
	v_add_f32_e32 v56, v123, v56
	v_add_f32_e32 v56, v110, v56
	v_pk_mul_f32 v[108:109], v[120:121], v[120:121]
	v_add_f32_e32 v56, v111, v56
	v_add_f32_e32 v56, v108, v56
	v_pk_mul_f32 v[106:107], v[126:127], v[126:127]
	v_add_f32_e32 v56, v109, v56
	v_add_f32_e32 v56, v106, v56
	v_add_f32_e32 v56, v107, v56
	v_lshlrev_b32_e32 v106, 16, v132
	v_and_b32_e32 v107, 0xffff0000, v132
	v_add_f32_dpp v56, v56, v56 quad_perm:[1,0,3,2] row_mask:0xf bank_mask:0xf bound_ctrl:1
	v_lshlrev_b32_e32 v108, 16, v133
	v_and_b32_e32 v109, 0xffff0000, v133
	v_add_f32_dpp v56, v56, v56 quad_perm:[2,3,0,1] row_mask:0xf bank_mask:0xf bound_ctrl:1
	v_pk_mul_f32 v[170:171], v[106:107], v[106:107]
	v_pk_mul_f32 v[158:159], v[108:109], v[108:109]
	v_add_f32_dpp v56, v56, v56 row_half_mirror row_mask:0xf bank_mask:0xf bound_ctrl:1
	v_lshlrev_b32_e32 v110, 16, v134
	v_and_b32_e32 v111, 0xffff0000, v134
	v_add_f32_dpp v56, v56, v56 row_mirror row_mask:0xf bank_mask:0xf bound_ctrl:1
	v_mov_b32_e32 v77, v56
	s_nop 1
	v_permlane16_swap_b32_e32 v56, v77
	v_add_f32_e32 v123, v56, v77
	v_add_f32_e32 v56, v170, v171
	v_add_f32_e32 v56, v158, v56
	v_lshlrev_b32_e32 v166, 16, v138
	v_and_b32_e32 v167, 0xffff0000, v138
	v_lshlrev_b32_e32 v168, 16, v139
	v_and_b32_e32 v169, 0xffff0000, v139
	v_pk_mul_f32 v[138:139], v[110:111], v[110:111]
	v_add_f32_e32 v56, v159, v56
	v_lshlrev_b32_e32 v160, 16, v135
	v_and_b32_e32 v161, 0xffff0000, v135
	v_add_f32_e32 v56, v138, v56
	v_lshlrev_b32_e32 v162, 16, v136
	v_and_b32_e32 v163, 0xffff0000, v136
	v_lshlrev_b32_e32 v164, 16, v137
	v_and_b32_e32 v165, 0xffff0000, v137
	v_pk_mul_f32 v[136:137], v[160:161], v[160:161]
	v_add_f32_e32 v56, v139, v56
	v_add_f32_e32 v56, v136, v56
	v_pk_mul_f32 v[134:135], v[162:163], v[162:163]
	v_add_f32_e32 v56, v137, v56
	v_add_f32_e32 v56, v134, v56
	v_pk_mul_f32 v[132:133], v[164:165], v[164:165]
	v_add_f32_e32 v56, v135, v56
	v_add_f32_e32 v56, v132, v56
	v_pk_mul_f32 v[130:131], v[166:167], v[166:167]
	v_add_f32_e32 v56, v133, v56
	v_add_f32_e32 v56, v130, v56
	v_pk_mul_f32 v[128:129], v[168:169], v[168:169]
	v_add_f32_e32 v56, v131, v56
	v_add_f32_e32 v56, v128, v56
	v_add_f32_e32 v56, v129, v56
	v_mov_b32_e32 v125, v123
	s_nop 1
	v_permlane32_swap_b32_e32 v123, v125
	v_add_f32_dpp v56, v56, v56 quad_perm:[1,0,3,2] row_mask:0xf bank_mask:0xf bound_ctrl:1
	v_and_b32_e32 v15, 0xffff0000, v10
	v_lshlrev_b32_e32 v10, 16, v11
	v_add_f32_dpp v56, v56, v56 quad_perm:[2,3,0,1] row_mask:0xf bank_mask:0xf bound_ctrl:1
	v_and_b32_e32 v11, 0xffff0000, v11
	v_lshlrev_b32_e32 v140, 16, v12
	v_add_f32_dpp v56, v56, v56 row_half_mirror row_mask:0xf bank_mask:0xf bound_ctrl:1
	v_and_b32_e32 v141, 0xffff0000, v12
	v_lshlrev_b32_e32 v12, 16, v13
	v_add_f32_dpp v56, v56, v56 row_mirror row_mask:0xf bank_mask:0xf bound_ctrl:1
	v_mov_b32_e32 v77, v56
	s_nop 1
	v_permlane16_swap_b32_e32 v56, v77
	v_add_f32_e32 v122, v56, v77
	v_mov_b32_e32 v124, v122
	s_nop 1
	v_permlane32_swap_b32_e32 v122, v124
	v_pk_add_f32 v[122:123], v[122:123], v[124:125]
	v_pk_mul_f32 v[124:125], v[72:73], v[54:55]
	v_pk_fma_f32 v[170:171], v[122:123], s[26:27], v[82:83] op_sel_hi:[1,0,0]
	v_pk_mul_f32 v[122:123], v[80:81], v[52:53]
	v_mul_f32_e32 v56, 0x4b800000, v171
	v_cmp_gt_f32_e32 vcc, s35, v171
	v_and_b32_e32 v13, 0xffff0000, v13
	v_lshlrev_b32_e32 v136, 16, v1
	v_cndmask_b32_e32 v56, v171, v56, vcc
	v_rsq_f32_e32 v56, v56
	v_and_b32_e32 v137, 0xffff0000, v1
	v_lshlrev_b32_e32 v138, 16, v2
	v_and_b32_e32 v139, 0xffff0000, v2
	v_mul_f32_e32 v52, 0x45800000, v56
	v_cndmask_b32_e32 v54, v56, v52, vcc
	v_pk_mul_f32 v[40:41], v[54:55], v[40:41] op_sel_hi:[0,1]
	v_pk_fma_f32 v[40:41], v[102:103], v[40:41], v[14:15]
	v_pk_mul_f32 v[14:15], v[54:55], v[42:43] op_sel_hi:[0,1]
	v_pk_fma_f32 v[42:43], v[98:99], v[14:15], v[10:11]
	v_pk_mul_f32 v[10:11], v[54:55], v[44:45] op_sel_hi:[0,1]
	v_pk_fma_f32 v[44:45], v[100:101], v[10:11], v[140:141]
	v_pk_mul_f32 v[10:11], v[54:55], v[46:47] op_sel_hi:[0,1]
	v_pk_fma_f32 v[46:47], v[94:95], v[10:11], v[12:13]
	v_pk_mul_f32 v[10:11], v[54:55], v[48:49] op_sel_hi:[0,1]
	v_pk_fma_f32 v[48:49], v[96:97], v[10:11], v[142:143]
	v_pk_mul_f32 v[10:11], v[54:55], v[50:51] op_sel_hi:[0,1]
	v_pk_fma_f32 v[50:51], v[92:93], v[10:11], v[148:149]
	v_pk_mul_f32 v[10:11], v[54:55], v[120:121] op_sel_hi:[0,1]
	v_lshlrev_b32_e32 v120, 16, v144
	v_and_b32_e32 v121, 0xffff0000, v144
	v_lshlrev_b32_e32 v142, 16, v145
	v_and_b32_e32 v143, 0xffff0000, v145
	v_pk_mul_f32 v[134:135], v[120:121], v[120:121]
	v_pk_mul_f32 v[132:133], v[142:143], v[142:143]
	v_add_f32_e32 v56, v134, v135
	v_lshlrev_b32_e32 v144, 16, v146
	v_and_b32_e32 v145, 0xffff0000, v146
	v_add_f32_e32 v56, v132, v56
	v_pk_mul_f32 v[130:131], v[144:145], v[144:145]
	v_add_f32_e32 v56, v133, v56
	v_lshlrev_b32_e32 v146, 16, v147
	v_and_b32_e32 v147, 0xffff0000, v147
	v_add_f32_e32 v56, v130, v56
	v_pk_mul_f32 v[128:129], v[146:147], v[146:147]
	v_add_f32_e32 v56, v131, v56
	v_lshlrev_b32_e32 v148, 16, v152
	v_and_b32_e32 v149, 0xffff0000, v152
	v_add_f32_e32 v56, v128, v56
	v_pk_fma_f32 v[52:53], v[124:125], v[10:11], v[150:151]
	v_pk_mul_f32 v[10:11], v[54:55], v[126:127] op_sel_hi:[0,1]
	v_pk_mul_f32 v[126:127], v[148:149], v[148:149]
	v_add_f32_e32 v56, v129, v56
	v_lshlrev_b32_e32 v150, 16, v153
	v_and_b32_e32 v151, 0xffff0000, v153
	v_add_f32_e32 v56, v126, v56
	v_pk_mul_f32 v[14:15], v[150:151], v[150:151]
	v_add_f32_e32 v56, v127, v56
	v_lshlrev_b32_e32 v152, 16, v154
	v_and_b32_e32 v153, 0xffff0000, v154
	v_add_f32_e32 v14, v14, v56
	v_pk_mul_f32 v[12:13], v[152:153], v[152:153]
	v_add_f32_e32 v14, v15, v14
	v_lshlrev_b32_e32 v154, 16, v155
	v_and_b32_e32 v155, 0xffff0000, v155
	v_add_f32_e32 v12, v12, v14
	v_pk_fma_f32 v[54:55], v[122:123], v[10:11], v[156:157]
	v_pk_mul_f32 v[10:11], v[154:155], v[154:155]
	v_add_f32_e32 v12, v13, v12
	v_add_f32_e32 v10, v10, v12
	v_add_f32_e32 v10, v11, v10
	v_lshlrev_b32_e32 v126, 16, v4
	v_and_b32_e32 v127, 0xffff0000, v4
	v_add_f32_dpp v10, v10, v10 quad_perm:[1,0,3,2] row_mask:0xf bank_mask:0xf bound_ctrl:1
	v_lshlrev_b32_e32 v128, 16, v5
	v_and_b32_e32 v129, 0xffff0000, v5
	v_add_f32_dpp v10, v10, v10 quad_perm:[2,3,0,1] row_mask:0xf bank_mask:0xf bound_ctrl:1
	v_pk_mul_f32 v[176:177], v[126:127], v[126:127]
	v_pk_mul_f32 v[14:15], v[128:129], v[128:129]
	v_add_f32_dpp v10, v10, v10 row_half_mirror row_mask:0xf bank_mask:0xf bound_ctrl:1
	v_add_f32_e32 v56, v176, v177
	v_lshlrev_b32_e32 v130, 16, v6
	v_add_f32_dpp v10, v10, v10 row_mirror row_mask:0xf bank_mask:0xf bound_ctrl:1
	v_and_b32_e32 v131, 0xffff0000, v6
	v_add_f32_e32 v14, v14, v56
	v_mov_b32_e32 v11, v10
	v_pk_mul_f32 v[12:13], v[130:131], v[130:131]
	v_add_f32_e32 v14, v15, v14
	v_permlane16_swap_b32_e32 v10, v11
	v_lshlrev_b32_e32 v132, 16, v7
	v_and_b32_e32 v133, 0xffff0000, v7
	v_add_f32_e32 v12, v12, v14
	v_add_f32_e32 v157, v10, v11
	v_pk_mul_f32 v[10:11], v[132:133], v[132:133]
	v_add_f32_e32 v12, v13, v12
	v_lshlrev_b32_e32 v134, 16, v0
	v_and_b32_e32 v135, 0xffff0000, v0
	v_add_f32_e32 v10, v10, v12
	v_pk_mul_f32 v[6:7], v[134:135], v[134:135]
	v_add_f32_e32 v10, v11, v10
	v_add_f32_e32 v6, v6, v10
	v_pk_mul_f32 v[4:5], v[136:137], v[136:137]
	v_add_f32_e32 v6, v7, v6
	v_add_f32_e32 v4, v4, v6
	v_lshlrev_b32_e32 v140, 16, v3
	v_and_b32_e32 v141, 0xffff0000, v3
	v_pk_mul_f32 v[2:3], v[138:139], v[138:139]
	v_add_f32_e32 v4, v5, v4
	v_add_f32_e32 v2, v2, v4
	v_pk_mul_f32 v[0:1], v[140:141], v[140:141]
	v_add_f32_e32 v2, v3, v2
	v_add_f32_e32 v0, v0, v2
	v_add_f32_e32 v0, v1, v0
	v_mov_b32_e32 v159, v157
	v_cmp_gt_f32_e64 s[6:7], s35, v170
	v_add_f32_dpp v0, v0, v0 quad_perm:[1,0,3,2] row_mask:0xf bank_mask:0xf bound_ctrl:1
	v_permlane32_swap_b32_e32 v157, v159
	s_nop 0
	v_add_f32_dpp v0, v0, v0 quad_perm:[2,3,0,1] row_mask:0xf bank_mask:0xf bound_ctrl:1
	s_and_b64 vcc, exec, s[22:23]
	s_nop 0
	v_add_f32_dpp v0, v0, v0 row_half_mirror row_mask:0xf bank_mask:0xf bound_ctrl:1
	s_nop 1
	v_add_f32_dpp v0, v0, v0 row_mirror row_mask:0xf bank_mask:0xf bound_ctrl:1
	v_mov_b32_e32 v1, v0
	s_nop 1
	v_permlane16_swap_b32_e32 v0, v1
	v_add_f32_e32 v156, v0, v1
	v_mov_b32_e32 v158, v156
	s_nop 1
	v_permlane32_swap_b32_e32 v156, v158
	s_cbranch_vccz .LBB0_2088
	v_cvt_pk_bf16_f32 v0, v40, v41
	v_cvt_pk_bf16_f32 v1, v42, v43
	v_cvt_pk_bf16_f32 v2, v44, v45
	v_cvt_pk_bf16_f32 v3, v46, v47
	v_cvt_pk_bf16_f32 v176, v48, v49
	v_cvt_pk_bf16_f32 v177, v50, v51
	v_cvt_pk_bf16_f32 v178, v52, v53
	v_cvt_pk_bf16_f32 v179, v54, v55
	flat_store_dwordx4 v[8:9], v[0:3] offset:2048
	v_lshlrev_b32_e32 v4, 16, v0
	v_and_b32_e32 v5, 0xffff0000, v0
	v_lshlrev_b32_e32 v6, 16, v1
	v_and_b32_e32 v7, 0xffff0000, v1
	v_lshlrev_b32_e32 v12, 16, v2
	v_and_b32_e32 v13, 0xffff0000, v2
	v_lshlrev_b32_e32 v14, 16, v3
	v_and_b32_e32 v15, 0xffff0000, v3
	flat_store_dwordx4 v[8:9], v[176:179] offset:3072
	v_lshlrev_b32_e32 v0, 16, v176
	v_and_b32_e32 v1, 0xffff0000, v176
	v_lshlrev_b32_e32 v2, 16, v177
	v_and_b32_e32 v3, 0xffff0000, v177
	v_lshlrev_b32_e32 v8, 16, v178
	v_and_b32_e32 v9, 0xffff0000, v178
	v_lshlrev_b32_e32 v10, 16, v179
	v_and_b32_e32 v11, 0xffff0000, v179
	v_lshlrev_b32_e32 v56, 2, v58
	s_cbranch_execnz .LBB0_2076

.LBB0_2085:
	s_and_b64 vcc, exec, s[6:7]
	s_cbranch_vccnz .LBB0_2072
	v_add_u32_e32 v18, 5, v85
	v_mov_b64_e32 v[16:17], s[20:21]
	v_mad_u64_u32 v[16:17], s[6:7], v18, s34, v[16:17]
	v_lshl_add_u64 v[18:19], v[16:17], 0, s[24:25]
	v_lshl_add_u64 v[20:21], v[18:19], 0, v[56:57]
	v_mov_b32_e32 v85, v57
	global_load_dwordx4 v[100:103], v[20:21], off
	v_lshl_add_u64 v[20:21], v[18:19], 0, v[84:85]
	v_mov_b32_e32 v87, v57
	global_load_dwordx4 v[122:125], v[20:21], off
	v_lshl_add_u64 v[20:21], v[18:19], 0, v[86:87]
	v_mov_b32_e32 v89, v57
	global_load_dwordx4 v[126:129], v[20:21], off
	v_lshl_add_u64 v[18:19], v[18:19], 0, v[88:89]
	global_load_dwordx4 v[130:133], v[18:19], off
	global_load_dwordx4 v[134:137], v[68:69], off
	global_load_dwordx4 v[138:141], v[68:69], off offset:16
	global_load_dwordx4 v[142:145], v[70:71], off
	global_load_dwordx4 v[146:149], v[70:71], off offset:16
	v_lshl_add_u64 v[16:17], v[16:17], 0, v[56:57]
	global_load_dwordx4 v[20:23], v[16:17], off offset:2048
	global_load_dwordx4 v[28:31], v[16:17], off
	global_load_dwordx4 v[24:27], v[16:17], off offset:16
	v_mul_f32_e32 v77, v5, v5
	global_load_dwordx4 v[16:19], v[16:17], off offset:2064
	v_mul_f32_e32 v85, v13, v13
	v_mul_f32_e32 v87, v1, v1
	v_fmac_f32_e32 v77, v4, v4
	v_fmac_f32_e32 v85, v12, v12
	v_mul_f32_e32 v89, v9, v9
	v_fmac_f32_e32 v87, v0, v0
	v_fmac_f32_e32 v77, v6, v6
	v_fmac_f32_e32 v85, v14, v14
	v_fmac_f32_e32 v89, v8, v8
	v_fmac_f32_e32 v87, v2, v2
	v_fmac_f32_e32 v77, v7, v7
	v_fmac_f32_e32 v85, v15, v15
	v_fmac_f32_e32 v89, v10, v10
	v_fmac_f32_e32 v87, v3, v3
	v_add_f32_e32 v56, v85, v77
	v_fmac_f32_e32 v89, v11, v11
	v_add_f32_e32 v56, v87, v56
	v_add_f32_e32 v56, v89, v56
	v_mul_f32_e32 v90, v111, v111
	v_mul_f32_e32 v91, v109, v109
	v_add_f32_dpp v56, v56, v56 quad_perm:[1,0,3,2] row_mask:0xf bank_mask:0xf bound_ctrl:1
	v_mul_f32_e32 v112, v55, v55
	v_fmac_f32_e32 v90, v110, v110
	v_fmac_f32_e32 v91, v108, v108
	v_add_f32_dpp v56, v56, v56 quad_perm:[2,3,0,1] row_mask:0xf bank_mask:0xf bound_ctrl:1
	v_mul_f32_e32 v150, v53, v53
	v_fmac_f32_e32 v112, v54, v54
	v_fmac_f32_e32 v90, v106, v106
	v_fmac_f32_e32 v91, v104, v104
	v_add_f32_dpp v56, v56, v56 row_half_mirror row_mask:0xf bank_mask:0xf bound_ctrl:1
	v_fmac_f32_e32 v150, v52, v52
	v_fmac_f32_e32 v112, v50, v50
	v_fmac_f32_e32 v90, v107, v107
	v_fmac_f32_e32 v91, v105, v105
	v_add_f32_dpp v56, v56, v56 row_mirror row_mask:0xf bank_mask:0xf bound_ctrl:1
	v_fmac_f32_e32 v112, v51, v51
	v_add_f32_e32 v77, v90, v91
	v_mov_b32_e32 v85, v56
	v_fmac_f32_e32 v150, v48, v48
	v_add_f32_e32 v77, v77, v112
	v_permlane16_swap_b32_e32 v56, v85
	v_fmac_f32_e32 v150, v49, v49
	v_add_f32_e32 v151, v56, v85
	v_add_f32_e32 v56, v77, v150
	v_mov_b32_e32 v153, v151
	s_nop 1
	v_permlane32_swap_b32_e32 v151, v153
	v_add_f32_dpp v56, v56, v56 quad_perm:[1,0,3,2] row_mask:0xf bank_mask:0xf bound_ctrl:1
	v_add_u32_e32 v85, 0xffffe800, v83
	s_waitcnt vmcnt(0) lgkmcnt(0)
	v_pk_add_f32 v[90:91], v[102:103], 1.0 op_sel_hi:[1,0]
	v_add_f32_dpp v56, v56, v56 quad_perm:[2,3,0,1] row_mask:0xf bank_mask:0xf bound_ctrl:1
	v_pk_add_f32 v[100:101], v[100:101], 1.0 op_sel_hi:[1,0]
	v_pk_add_f32 v[132:133], v[132:133], 1.0 op_sel_hi:[1,0]
	v_add_f32_dpp v56, v56, v56 row_half_mirror row_mask:0xf bank_mask:0xf bound_ctrl:1
	v_pk_add_f32 v[102:103], v[124:125], 1.0 op_sel_hi:[1,0]
	v_pk_add_f32 v[128:129], v[128:129], 1.0 op_sel_hi:[1,0]
	v_add_f32_dpp v56, v56, v56 row_mirror row_mask:0xf bank_mask:0xf bound_ctrl:1
	v_mov_b32_e32 v77, v56
	s_nop 1
	v_permlane16_swap_b32_e32 v56, v77
	v_add_f32_e32 v150, v56, v77
	v_mov_b32_e32 v152, v150
	s_nop 1
	v_permlane32_swap_b32_e32 v150, v152
	v_pk_add_f32 v[124:125], v[122:123], 1.0 op_sel_hi:[1,0]
	v_pk_add_f32 v[154:155], v[126:127], 1.0 op_sel_hi:[1,0]
	v_pk_mul_f32 v[122:123], v[136:137], v[90:91]
	v_pk_mul_f32 v[126:127], v[134:135], v[100:101]
	v_pk_mul_f32 v[100:101], v[144:145], v[128:129]
	v_pk_mul_f32 v[90:91], v[148:149], v[132:133]
	v_pk_add_f32 v[128:129], v[150:151], v[152:153]
	v_mov_b64_e32 v[132:133], s[28:29]
	v_pk_fma_f32 v[134:135], v[128:129], s[26:27], v[132:133] op_sel_hi:[1,0,0]
	v_pk_mul_f32 v[112:113], v[140:141], v[102:103]
	v_mul_f32_e32 v56, 0x4b800000, v135
	v_cmp_gt_f32_e32 vcc, s35, v135
	v_pk_mul_f32 v[102:103], v[142:143], v[154:155]
	v_pk_mul_f32 v[124:125], v[138:139], v[124:125]
	v_cndmask_b32_e32 v56, v135, v56, vcc
	v_rsq_f32_e32 v56, v56
	v_add_u32_e32 v77, 0xffffe400, v83
	v_pk_add_f32 v[130:131], v[130:131], 1.0 op_sel_hi:[1,0]
	v_mul_f32_e32 v87, 0x45800000, v56
	v_cndmask_b32_e32 v56, v56, v87, vcc
	v_pk_mul_f32 v[0:1], v[0:1], v[56:57] op_sel_hi:[1,0]
	v_pk_mul_f32 v[2:3], v[2:3], v[56:57] op_sel_hi:[1,0]
	v_pk_mul_f32 v[4:5], v[4:5], v[56:57] op_sel_hi:[1,0]
	v_pk_mul_f32 v[12:13], v[12:13], v[56:57] op_sel_hi:[1,0]
	v_pk_mul_f32 v[6:7], v[6:7], v[56:57] op_sel_hi:[1,0]
	v_pk_mul_f32 v[14:15], v[14:15], v[56:57] op_sel_hi:[1,0]
	v_pk_fma_f32 v[0:1], v[102:103], v[0:1], v[20:21]
	v_pk_fma_f32 v[2:3], v[100:101], v[2:3], v[22:23]
	v_pk_fma_f32 v[4:5], v[126:127], v[4:5], v[28:29]
	v_pk_fma_f32 v[12:13], v[124:125], v[12:13], v[24:25]
	v_pk_fma_f32 v[6:7], v[122:123], v[6:7], v[30:31]
	v_pk_fma_f32 v[14:15], v[112:113], v[14:15], v[26:27]
	v_cvt_pk_bf16_f32 v0, v0, v1
	v_cvt_pk_bf16_f32 v1, v2, v3
	v_mul_f32_e32 v2, 0x4b800000, v134
	v_cmp_gt_f32_e32 vcc, s35, v134
	v_cvt_pk_bf16_f32 v4, v4, v5
	v_cvt_pk_bf16_f32 v5, v6, v7
	v_cvt_pk_bf16_f32 v6, v12, v13
	v_cvt_pk_bf16_f32 v7, v14, v15
	v_cndmask_b32_e32 v2, v134, v2, vcc
	buffer_store_dwordx4 v[4:7], v77, s[12:15], 0 offen sc1
	v_pk_mul_f32 v[128:129], v[146:147], v[130:131]
	v_add_u32_e32 v12, 0xfffff800, v83
	v_pk_mul_f32 v[4:5], v[8:9], v[56:57] op_sel_hi:[1,0]
	v_rsq_f32_e32 v8, v2
	v_pk_mul_f32 v[6:7], v[10:11], v[56:57] op_sel_hi:[1,0]
	v_pk_fma_f32 v[4:5], v[128:129], v[4:5], v[16:17]
	v_pk_fma_f32 v[6:7], v[90:91], v[6:7], v[18:19]
	v_cvt_pk_bf16_f32 v2, v4, v5
	v_cvt_pk_bf16_f32 v3, v6, v7
	buffer_store_dwordx4 v[0:3], v85, s[12:15], 0 offen sc1
	s_nop 1
	v_mul_f32_e32 v0, 0x45800000, v8
	v_cndmask_b32_e32 v4, v8, v0, vcc
	v_pk_mul_f32 v[0:1], v[110:111], v[4:5] op_sel_hi:[1,0]
	v_pk_mul_f32 v[2:3], v[108:109], v[4:5] op_sel_hi:[1,0]
	v_pk_mul_f32 v[6:7], v[106:107], v[4:5] op_sel_hi:[1,0]
	v_pk_mul_f32 v[8:9], v[104:105], v[4:5] op_sel_hi:[1,0]
	v_pk_fma_f32 v[0:1], v[126:127], v[0:1], v[28:29]
	v_pk_fma_f32 v[2:3], v[124:125], v[2:3], v[24:25]
	v_pk_fma_f32 v[6:7], v[122:123], v[6:7], v[30:31]
	v_pk_fma_f32 v[8:9], v[112:113], v[8:9], v[26:27]
	v_cvt_pk_bf16_f32 v0, v0, v1
	v_cvt_pk_bf16_f32 v1, v6, v7
	v_cvt_pk_bf16_f32 v2, v2, v3
	v_cvt_pk_bf16_f32 v3, v8, v9
	v_add_u32_e32 v5, 0xffffec00, v83
	buffer_store_dwordx4 v[0:3], v5, s[12:15], 0 offen sc1
	v_pk_mul_f32 v[6:7], v[50:51], v[4:5] op_sel_hi:[1,0]
	v_add_u32_e32 v8, 0xfffff000, v83
	v_pk_mul_f32 v[0:1], v[54:55], v[4:5] op_sel_hi:[1,0]
	v_pk_mul_f32 v[2:3], v[52:53], v[4:5] op_sel_hi:[1,0]
	v_pk_mul_f32 v[4:5], v[48:49], v[4:5] op_sel_hi:[1,0]
	v_pk_fma_f32 v[2:3], v[128:129], v[2:3], v[16:17]
	v_pk_fma_f32 v[4:5], v[90:91], v[4:5], v[18:19]
	v_cvt_pk_bf16_f32 v2, v2, v3
	v_cvt_pk_bf16_f32 v3, v4, v5
	v_mul_f32_e32 v4, v117, v117
	v_mul_f32_e32 v5, v121, v121
	v_fmac_f32_e32 v4, v116, v116
	v_fmac_f32_e32 v5, v120, v120
	v_fmac_f32_e32 v4, v42, v42
	v_fmac_f32_e32 v5, v114, v114
	v_fmac_f32_e32 v4, v43, v43
	v_fmac_f32_e32 v5, v115, v115
	v_add_f32_e32 v4, v4, v5
	v_mul_f32_e32 v5, v47, v47
	v_fmac_f32_e32 v5, v46, v46
	v_fmac_f32_e32 v5, v40, v40
	v_fmac_f32_e32 v5, v41, v41
	v_add_f32_e32 v4, v4, v5
	v_mul_f32_e32 v5, v119, v119
	v_fmac_f32_e32 v5, v118, v118
	v_fmac_f32_e32 v5, v44, v44
	v_fmac_f32_e32 v5, v45, v45
	v_add_f32_e32 v4, v4, v5
	v_pk_fma_f32 v[0:1], v[102:103], v[0:1], v[20:21]
	v_pk_fma_f32 v[6:7], v[100:101], v[6:7], v[22:23]
	v_add_f32_dpp v4, v4, v4 quad_perm:[1,0,3,2] row_mask:0xf bank_mask:0xf bound_ctrl:1
	v_cvt_pk_bf16_f32 v0, v0, v1
	v_cvt_pk_bf16_f32 v1, v6, v7
	v_add_f32_dpp v4, v4, v4 quad_perm:[2,3,0,1] row_mask:0xf bank_mask:0xf bound_ctrl:1
	v_mul_f32_e32 v6, v97, v97
	v_fmac_f32_e32 v6, v96, v96
	v_add_f32_dpp v4, v4, v4 row_half_mirror row_mask:0xf bank_mask:0xf bound_ctrl:1
	v_fmac_f32_e32 v6, v92, v92
	v_fmac_f32_e32 v6, v93, v93
	v_add_f32_dpp v4, v4, v4 row_mirror row_mask:0xf bank_mask:0xf bound_ctrl:1
	v_mov_b32_e32 v5, v4
	s_nop 1
	v_permlane16_swap_b32_e32 v4, v5
	v_add_f32_e32 v5, v4, v5
	v_mul_f32_e32 v4, v99, v99
	v_fmac_f32_e32 v4, v98, v98
	v_fmac_f32_e32 v4, v94, v94
	v_fmac_f32_e32 v4, v95, v95
	v_add_f32_e32 v4, v4, v6
	v_mul_f32_e32 v6, v39, v39
	v_fmac_f32_e32 v6, v38, v38
	v_fmac_f32_e32 v6, v34, v34
	v_fmac_f32_e32 v6, v35, v35
	v_add_f32_e32 v4, v4, v6
	v_mul_f32_e32 v6, v37, v37
	v_fmac_f32_e32 v6, v36, v36
	v_fmac_f32_e32 v6, v32, v32
	v_fmac_f32_e32 v6, v33, v33
	v_add_f32_e32 v4, v4, v6
	v_mov_b32_e32 v7, v5
	s_nop 1
	v_permlane32_swap_b32_e32 v5, v7
	v_add_f32_dpp v4, v4, v4 quad_perm:[1,0,3,2] row_mask:0xf bank_mask:0xf bound_ctrl:1
	buffer_store_dwordx4 v[0:3], v8, s[12:15], 0 offen sc1
	s_nop 0
	v_add_f32_dpp v4, v4, v4 quad_perm:[2,3,0,1] row_mask:0xf bank_mask:0xf bound_ctrl:1
	s_nop 1
	v_add_f32_dpp v4, v4, v4 row_half_mirror row_mask:0xf bank_mask:0xf bound_ctrl:1
	s_nop 1
	v_add_f32_dpp v4, v4, v4 row_mirror row_mask:0xf bank_mask:0xf bound_ctrl:1
	v_mov_b32_e32 v6, v4
	s_nop 1
	v_permlane16_swap_b32_e32 v4, v6
	v_add_f32_e32 v4, v4, v6
	v_mov_b32_e32 v6, v4
	s_nop 1
	v_permlane32_swap_b32_e32 v4, v6
	v_pk_add_f32 v[4:5], v[4:5], v[6:7]
	v_add_u32_e32 v7, 0xfffff400, v83
	v_pk_fma_f32 v[4:5], v[4:5], s[26:27], v[132:133] op_sel_hi:[1,0,0]
	s_nop 0
	v_mul_f32_e32 v6, 0x4b800000, v5
	v_cmp_gt_f32_e32 vcc, s35, v5
	s_nop 1
	v_cndmask_b32_e32 v5, v5, v6, vcc
	v_rsq_f32_e32 v5, v5
	s_nop 0
	v_mul_f32_e32 v0, 0x45800000, v5
	v_cndmask_b32_e32 v6, v5, v0, vcc
	v_pk_mul_f32 v[0:1], v[116:117], v[6:7] op_sel_hi:[1,0]
	v_pk_mul_f32 v[2:3], v[120:121], v[6:7] op_sel_hi:[1,0]
	v_pk_mul_f32 v[8:9], v[42:43], v[6:7] op_sel_hi:[1,0]
	v_pk_mul_f32 v[10:11], v[114:115], v[6:7] op_sel_hi:[1,0]
	v_mul_f32_e32 v5, 0x4b800000, v4
	v_cmp_gt_f32_e32 vcc, s35, v4
	v_pk_fma_f32 v[0:1], v[126:127], v[0:1], v[28:29]
	v_pk_fma_f32 v[2:3], v[124:125], v[2:3], v[24:25]
	v_pk_fma_f32 v[8:9], v[122:123], v[8:9], v[30:31]
	v_pk_fma_f32 v[10:11], v[112:113], v[10:11], v[26:27]
	v_cndmask_b32_e32 v4, v4, v5, vcc
	v_cvt_pk_bf16_f32 v0, v0, v1
	v_cvt_pk_bf16_f32 v1, v8, v9
	v_cvt_pk_bf16_f32 v2, v2, v3
	v_cvt_pk_bf16_f32 v3, v10, v11
	v_rsq_f32_e32 v4, v4
	buffer_store_dwordx4 v[0:3], v7, s[12:15], 0 offen sc1
	v_pk_mul_f32 v[8:9], v[40:41], v[6:7] op_sel_hi:[1,0]
	s_nop 0
	v_pk_mul_f32 v[0:1], v[46:47], v[6:7] op_sel_hi:[1,0]
	v_pk_mul_f32 v[2:3], v[118:119], v[6:7] op_sel_hi:[1,0]
	v_pk_mul_f32 v[6:7], v[44:45], v[6:7] op_sel_hi:[1,0]
	v_pk_fma_f32 v[0:1], v[102:103], v[0:1], v[20:21]
	v_pk_fma_f32 v[2:3], v[128:129], v[2:3], v[16:17]
	v_pk_fma_f32 v[8:9], v[100:101], v[8:9], v[22:23]
	v_pk_fma_f32 v[6:7], v[90:91], v[6:7], v[18:19]
	v_cvt_pk_bf16_f32 v0, v0, v1
	v_cvt_pk_bf16_f32 v1, v8, v9
	v_cvt_pk_bf16_f32 v2, v2, v3
	v_cvt_pk_bf16_f32 v3, v6, v7
	buffer_store_dwordx4 v[0:3], v12, s[12:15], 0 offen sc1
	s_nop 1
	v_mul_f32_e32 v0, 0x45800000, v4
	v_cndmask_b32_e32 v4, v4, v0, vcc
	v_pk_mul_f32 v[0:1], v[98:99], v[4:5] op_sel_hi:[1,0]
	v_pk_mul_f32 v[2:3], v[96:97], v[4:5] op_sel_hi:[1,0]
	v_pk_mul_f32 v[6:7], v[94:95], v[4:5] op_sel_hi:[1,0]
	v_pk_mul_f32 v[8:9], v[92:93], v[4:5] op_sel_hi:[1,0]
	v_pk_fma_f32 v[0:1], v[126:127], v[0:1], v[28:29]
	v_pk_fma_f32 v[2:3], v[124:125], v[2:3], v[24:25]
	v_pk_fma_f32 v[6:7], v[122:123], v[6:7], v[30:31]
	v_pk_fma_f32 v[8:9], v[112:113], v[8:9], v[26:27]
	v_cvt_pk_bf16_f32 v0, v0, v1
	v_cvt_pk_bf16_f32 v1, v6, v7
	v_cvt_pk_bf16_f32 v2, v2, v3
	v_cvt_pk_bf16_f32 v3, v8, v9
	v_add_u32_e32 v5, 0xfffffc00, v83
	buffer_store_dwordx4 v[0:3], v5, s[12:15], 0 offen sc1
	v_pk_mul_f32 v[6:7], v[34:35], v[4:5] op_sel_hi:[1,0]
	s_nop 0
	v_pk_mul_f32 v[0:1], v[38:39], v[4:5] op_sel_hi:[1,0]
	v_pk_mul_f32 v[2:3], v[36:37], v[4:5] op_sel_hi:[1,0]
	v_pk_mul_f32 v[4:5], v[32:33], v[4:5] op_sel_hi:[1,0]
	v_pk_fma_f32 v[0:1], v[102:103], v[0:1], v[20:21]
	v_pk_fma_f32 v[2:3], v[128:129], v[2:3], v[16:17]
	v_pk_fma_f32 v[6:7], v[100:101], v[6:7], v[22:23]
	v_pk_fma_f32 v[4:5], v[90:91], v[4:5], v[18:19]
	v_cvt_pk_bf16_f32 v0, v0, v1
	v_cvt_pk_bf16_f32 v1, v6, v7
	v_cvt_pk_bf16_f32 v2, v2, v3
	v_cvt_pk_bf16_f32 v3, v4, v5
	buffer_store_dwordx4 v[0:3], v83, s[12:15], 0 offen sc1
	s_waitcnt vmcnt(0)
	s_and_saveexec_b64 s[6:7], s[4:5]
	s_cbranch_execz .LBB0_2071
	v_ashrrev_i32_e32 v0, 2, v76
	v_and_b32_e32 v0, 0xffffffc0, v0
	v_ashrrev_i32_e32 v1, 31, v0
	v_lshl_add_u64 v[0:1], v[0:1], 2, s[16:17]
	flat_atomic_add v[0:1], v172
	s_branch .LBB0_2071

.LBB0_2246:
	v_add_u32_e32 v20, s13, v50
	v_ashrrev_i32_e32 v36, 4, v20
	v_mad_i64_i32 v[0:1], s[4:5], v36, s17, v[26:27]
	global_load_dwordx4 v[12:15], v[0:1], off offset:768
	v_add_u32_e32 v33, s13, v39
	v_add_u32_e32 v31, s13, v40
	v_add_u32_e32 v43, s13, v38
	v_ashrrev_i32_e32 v34, 4, v33
	global_load_dwordx4 v[44:47], v[24:25], off offset:528
	global_load_dwordx4 v[16:19], v[24:25], off offset:512
	v_ashrrev_i32_e32 v32, 4, v31
	v_ashrrev_i32_e32 v30, 4, v43
	v_mad_i64_i32 v[48:49], s[4:5], v34, s17, v[26:27]
	v_mad_i64_i32 v[52:53], s[4:5], v32, s17, v[26:27]
	v_mad_i64_i32 v[54:55], s[4:5], v30, s17, v[26:27]
	global_load_dwordx4 v[8:11], v[48:49], off offset:768
	global_load_dwordx4 v[4:7], v[52:53], off offset:768
	global_load_dwordx4 v[0:3], v[54:55], off offset:768
	v_ashrrev_i32_e32 v37, 31, v36
	v_cmp_gt_i32_e64 s[4:5], s18, v36
	s_waitcnt vmcnt(0) lgkmcnt(0)
	v_lshlrev_b32_e32 v48, 16, v12
	v_and_b32_e32 v49, 0xffff0000, v12
	v_lshlrev_b32_e32 v12, 16, v13
	v_and_b32_e32 v13, 0xffff0000, v13
	v_pk_mul_f32 v[60:61], v[48:49], v[48:49]
	v_pk_mul_f32 v[58:59], v[12:13], v[12:13]
	v_add_f32_e32 v29, v60, v61
	v_lshlrev_b32_e32 v52, 16, v14
	v_and_b32_e32 v53, 0xffff0000, v14
	v_add_f32_e32 v29, v29, v58
	v_pk_mul_f32 v[56:57], v[52:53], v[52:53]
	v_add_f32_e32 v29, v59, v29
	v_lshlrev_b32_e32 v14, 16, v15
	v_and_b32_e32 v15, 0xffff0000, v15
	v_add_f32_e32 v29, v56, v29
	v_pk_mul_f32 v[54:55], v[14:15], v[14:15]
	v_add_f32_e32 v29, v57, v29
	v_add_f32_e32 v29, v54, v29
	v_add_f32_e32 v29, v55, v29
	v_lshlrev_b64 v[54:55], 8, v[36:37]
	s_nop 0
	v_add_f32_dpp v29, v29, v29 quad_perm:[1,0,3,2] row_mask:0xf bank_mask:0xf bound_ctrl:1
	s_nop 1
	v_add_f32_dpp v29, v29, v29 quad_perm:[2,3,0,1] row_mask:0xf bank_mask:0xf bound_ctrl:1
	s_nop 1
	v_add_f32_dpp v29, v29, v29 row_half_mirror row_mask:0xf bank_mask:0xf bound_ctrl:1
	s_nop 1
	v_add_f32_dpp v29, v29, v29 row_mirror row_mask:0xf bank_mask:0xf bound_ctrl:1
	v_fmamk_f32 v29, v29, 0x3c000000, v41
	v_mul_f32_e32 v35, 0x4b800000, v29
	v_cmp_gt_f32_e32 vcc, s19, v29
	s_nop 1
	v_cndmask_b32_e32 v29, v29, v35, vcc
	v_rsq_f32_e32 v29, v29
	s_nop 0
	v_mul_f32_e32 v35, 0x45800000, v29
	v_cndmask_b32_e32 v56, v29, v35, vcc
	v_pk_mul_f32 v[48:49], v[56:57], v[48:49] op_sel_hi:[0,1]
	v_pk_mul_f32 v[12:13], v[56:57], v[12:13] op_sel_hi:[0,1]
	v_pk_mul_f32 v[52:53], v[56:57], v[52:53] op_sel_hi:[0,1]
	v_pk_mul_f32 v[14:15], v[56:57], v[14:15] op_sel_hi:[0,1]
	v_pk_mul_f32 v[16:17], v[16:17], v[48:49]
	v_pk_mul_f32 v[18:19], v[18:19], v[12:13]
	v_pk_mul_f32 v[12:13], v[44:45], v[52:53]
	v_pk_mul_f32 v[14:15], v[46:47], v[14:15]
	v_cvt_pk_bf16_f32 v44, v16, v17
	v_cvt_pk_bf16_f32 v45, v18, v19
	v_cvt_pk_bf16_f32 v46, v12, v13
	v_cvt_pk_bf16_f32 v47, v14, v15
	v_lshl_add_u64 v[48:49], v[22:23], 0, v[54:55]
	flat_store_dwordx4 v[48:49], v[44:47]
	s_and_saveexec_b64 s[10:11], s[4:5]
	s_cbranch_execz .LBB0_2248
	v_ashrrev_i32_e32 v20, 11, v20
	v_or_b32_e32 v44, 1, v20
	v_ashrrev_i32_e32 v45, 31, v44
	v_lshlrev_b64 v[44:45], 17, v[44:45]
	v_lshlrev_b32_e32 v20, 9, v36
	v_lshl_add_u64 v[44:45], s[8:9], 0, v[44:45]
	v_and_b32_e32 v20, 0x1fe00, v20
	v_lshl_add_u64 v[36:37], v[44:45], 0, v[20:21]
	v_mov_b32_e32 v29, v21
	v_lshl_add_u64 v[36:37], v[36:37], 0, v[28:29]
	flat_store_dwordx4 v[36:37], v[16:19]
	flat_store_dwordx4 v[36:37], v[12:15] offset:16

.LBB0_2258:
	v_ashrrev_i32_e32 v24, 4, v26
	v_mad_i64_i32 v[0:1], s[10:11], v24, s16, v[18:19]
	global_load_dwordx4 v[4:7], v[0:1], off offset:768
	global_load_dwordx4 v[8:11], v[16:17], off offset:512
	global_load_dwordx4 v[30:33], v[16:17], off offset:528
	v_lshl_add_u32 v28, s4, 9, v50
	v_ashrrev_i32_e32 v22, 4, v28
	v_mad_i64_i32 v[0:1], s[4:5], v22, s16, v[18:19]
	global_load_dwordx4 v[0:3], v[0:1], off offset:768
	v_ashrrev_i32_e32 v25, 31, v24
	v_cmp_gt_i32_e64 s[4:5], s17, v24
	s_waitcnt vmcnt(0) lgkmcnt(0)
	v_lshlrev_b32_e32 v34, 16, v4
	v_and_b32_e32 v35, 0xffff0000, v4
	v_lshlrev_b32_e32 v4, 16, v5
	v_and_b32_e32 v5, 0xffff0000, v5
	v_pk_mul_f32 v[46:47], v[34:35], v[34:35]
	v_pk_mul_f32 v[44:45], v[4:5], v[4:5]
	v_add_f32_e32 v12, v46, v47
	v_lshlrev_b32_e32 v36, 16, v6
	v_and_b32_e32 v37, 0xffff0000, v6
	v_add_f32_e32 v12, v12, v44
	v_pk_mul_f32 v[40:41], v[36:37], v[36:37]
	v_add_f32_e32 v12, v45, v12
	v_lshlrev_b32_e32 v6, 16, v7
	v_and_b32_e32 v7, 0xffff0000, v7
	v_add_f32_e32 v12, v40, v12
	v_pk_mul_f32 v[38:39], v[6:7], v[6:7]
	v_add_f32_e32 v12, v41, v12
	v_add_f32_e32 v12, v38, v12
	v_add_f32_e32 v12, v39, v12
	v_lshlrev_b64 v[38:39], 8, v[24:25]
	s_nop 0
	v_add_f32_dpp v12, v12, v12 quad_perm:[1,0,3,2] row_mask:0xf bank_mask:0xf bound_ctrl:1
	s_nop 1
	v_add_f32_dpp v12, v12, v12 quad_perm:[2,3,0,1] row_mask:0xf bank_mask:0xf bound_ctrl:1
	s_nop 1
	v_add_f32_dpp v12, v12, v12 row_half_mirror row_mask:0xf bank_mask:0xf bound_ctrl:1
	s_nop 1
	v_add_f32_dpp v12, v12, v12 row_mirror row_mask:0xf bank_mask:0xf bound_ctrl:1
	v_fmamk_f32 v12, v12, 0x3c000000, v27
	v_mul_f32_e32 v21, 0x4b800000, v12
	v_cmp_gt_f32_e32 vcc, s18, v12
	s_nop 1
	v_cndmask_b32_e32 v12, v12, v21, vcc
	v_rsq_f32_e32 v12, v12
	s_nop 0
	v_mul_f32_e32 v21, 0x45800000, v12
	v_cndmask_b32_e32 v12, v12, v21, vcc
	v_pk_mul_f32 v[34:35], v[12:13], v[34:35] op_sel_hi:[0,1]
	v_pk_mul_f32 v[4:5], v[12:13], v[4:5] op_sel_hi:[0,1]
	v_pk_mul_f32 v[36:37], v[12:13], v[36:37] op_sel_hi:[0,1]
	v_pk_mul_f32 v[6:7], v[12:13], v[6:7] op_sel_hi:[0,1]
	v_pk_mul_f32 v[8:9], v[8:9], v[34:35]
	v_pk_mul_f32 v[10:11], v[10:11], v[4:5]
	v_pk_mul_f32 v[4:5], v[30:31], v[36:37]
	v_pk_mul_f32 v[6:7], v[32:33], v[6:7]
	v_cvt_pk_bf16_f32 v30, v8, v9
	v_cvt_pk_bf16_f32 v31, v10, v11
	v_cvt_pk_bf16_f32 v32, v4, v5
	v_cvt_pk_bf16_f32 v33, v6, v7
	v_lshl_add_u64 v[34:35], v[14:15], 0, v[38:39]
	flat_store_dwordx4 v[34:35], v[30:33]
	s_and_saveexec_b64 s[10:11], s[4:5]
	s_cbranch_execz .LBB0_2260
	v_ashrrev_i32_e32 v12, 11, v26
	v_or_b32_e32 v30, 1, v12
	v_ashrrev_i32_e32 v31, 31, v30
	v_lshlrev_b64 v[30:31], 17, v[30:31]
	v_lshlrev_b32_e32 v12, 9, v24
	v_lshl_add_u64 v[30:31], s[8:9], 0, v[30:31]
	v_and_b32_e32 v12, 0x1fe00, v12
	v_lshl_add_u64 v[24:25], v[30:31], 0, v[12:13]
	v_mov_b32_e32 v21, v13
	v_lshl_add_u64 v[24:25], v[24:25], 0, v[20:21]
	flat_store_dwordx4 v[24:25], v[8:11]
	flat_store_dwordx4 v[24:25], v[4:7] offset:16

.LBB0_2265:
	v_ashrrev_i32_e32 v18, 4, v20
	v_mad_i64_i32 v[26:27], s[4:5], v18, s11, v[14:15]
	global_load_dwordx4 v[0:3], v[26:27], off offset:768
	global_load_dwordx4 v[4:7], v[12:13], off offset:512
	global_load_dwordx4 v[22:25], v[12:13], off offset:528
	v_ashrrev_i32_e32 v19, 31, v18
	v_cmp_gt_i32_e64 s[4:5], s12, v18
	s_waitcnt vmcnt(0) lgkmcnt(0)
	v_lshlrev_b32_e32 v26, 16, v0
	v_and_b32_e32 v27, 0xffff0000, v0
	v_lshlrev_b32_e32 v0, 16, v1
	v_and_b32_e32 v1, 0xffff0000, v1
	v_pk_mul_f32 v[36:37], v[26:27], v[26:27]
	v_pk_mul_f32 v[34:35], v[0:1], v[0:1]
	v_add_f32_e32 v8, v36, v37
	v_lshlrev_b32_e32 v28, 16, v2
	v_and_b32_e32 v29, 0xffff0000, v2
	v_add_f32_e32 v8, v8, v34
	v_pk_mul_f32 v[32:33], v[28:29], v[28:29]
	v_add_f32_e32 v8, v35, v8
	v_lshlrev_b32_e32 v2, 16, v3
	v_and_b32_e32 v3, 0xffff0000, v3
	v_add_f32_e32 v8, v32, v8
	v_pk_mul_f32 v[30:31], v[2:3], v[2:3]
	v_add_f32_e32 v8, v33, v8
	v_add_f32_e32 v8, v30, v8
	v_add_f32_e32 v8, v31, v8
	v_lshlrev_b64 v[30:31], 8, v[18:19]
	s_nop 0
	v_add_f32_dpp v8, v8, v8 quad_perm:[1,0,3,2] row_mask:0xf bank_mask:0xf bound_ctrl:1
	s_nop 1
	v_add_f32_dpp v8, v8, v8 quad_perm:[2,3,0,1] row_mask:0xf bank_mask:0xf bound_ctrl:1
	s_nop 1
	v_add_f32_dpp v8, v8, v8 row_half_mirror row_mask:0xf bank_mask:0xf bound_ctrl:1
	s_nop 1
	v_add_f32_dpp v8, v8, v8 row_mirror row_mask:0xf bank_mask:0xf bound_ctrl:1
	v_fmamk_f32 v8, v8, 0x3c000000, v21
	v_mul_f32_e32 v17, 0x4b800000, v8
	v_cmp_gt_f32_e32 vcc, s13, v8
	s_nop 1
	v_cndmask_b32_e32 v8, v8, v17, vcc
	v_rsq_f32_e32 v8, v8
	s_nop 0
	v_mul_f32_e32 v17, 0x45800000, v8
	v_cndmask_b32_e32 v8, v8, v17, vcc
	v_pk_mul_f32 v[26:27], v[8:9], v[26:27] op_sel_hi:[0,1]
	v_pk_mul_f32 v[0:1], v[8:9], v[0:1] op_sel_hi:[0,1]
	v_pk_mul_f32 v[28:29], v[8:9], v[28:29] op_sel_hi:[0,1]
	v_pk_mul_f32 v[2:3], v[8:9], v[2:3] op_sel_hi:[0,1]
	v_pk_mul_f32 v[4:5], v[4:5], v[26:27]
	v_pk_mul_f32 v[6:7], v[6:7], v[0:1]
	v_pk_mul_f32 v[0:1], v[22:23], v[28:29]
	v_pk_mul_f32 v[2:3], v[24:25], v[2:3]
	v_cvt_pk_bf16_f32 v22, v4, v5
	v_cvt_pk_bf16_f32 v23, v6, v7
	v_cvt_pk_bf16_f32 v24, v0, v1
	v_cvt_pk_bf16_f32 v25, v2, v3
	v_lshl_add_u64 v[26:27], v[10:11], 0, v[30:31]
	flat_store_dwordx4 v[26:27], v[22:25]
	s_and_saveexec_b64 s[8:9], s[4:5]
	s_cbranch_execz .LBB0_2264
	v_ashrrev_i32_e32 v8, 11, v20
	v_or_b32_e32 v22, 1, v8
	v_ashrrev_i32_e32 v23, 31, v22
	v_lshlrev_b64 v[22:23], 17, v[22:23]
	v_lshlrev_b32_e32 v8, 9, v18
	v_lshl_add_u64 v[22:23], s[6:7], 0, v[22:23]
	v_and_b32_e32 v8, 0x1fe00, v8
	v_lshl_add_u64 v[18:19], v[22:23], 0, v[8:9]
	v_mov_b32_e32 v17, v9
	v_lshl_add_u64 v[18:19], v[18:19], 0, v[16:17]
	flat_store_dwordx4 v[18:19], v[4:7]
	flat_store_dwordx4 v[18:19], v[0:3] offset:16
	s_branch .LBB0_2264

.LBB0_2289:
	s_andn2_saveexec_b64 s[4:5], s[4:5]
	v_lshl_add_u32 v0, v1, 3, v41
	s_or_b64 exec, exec, s[4:5]
	v_mad_i64_i32 v[4:5], s[4:5], v26, s66, v[16:17]
	v_ashrrev_i32_e32 v1, 31, v0
	v_lshl_add_u64 v[0:1], v[0:1], 1, v[4:5]
	global_load_dwordx4 v[12:15], v[0:1], off
	v_add_u32_e32 v48, s54, v44
	v_mul_hi_i32 v0, v48, s58
	v_add_u32_e32 v0, v0, v48
	v_lshrrev_b32_e32 v1, 31, v0
	v_ashrrev_i32_e32 v0, 7, v0
	v_add_u32_e32 v24, v0, v1
	s_add_i32 s4, s3, s79
	v_mul_lo_u32 v0, v24, s59
	s_lshl_b32 s4, s4, 9
	v_add_u32_e32 v23, v48, v0
	v_add3_u32 v1, s4, v50, v0
	v_cmp_lt_i32_e64 s[6:7], 3, v23
	s_and_saveexec_b64 s[4:5], s[6:7]
	s_xor_b64 s[4:5], exec, s[4:5]
	s_cbranch_execz .LBB0_2309
	v_cmp_lt_u32_e32 vcc, 51, v23
	s_and_saveexec_b64 s[10:11], vcc
	s_xor_b64 s[10:11], exec, s[10:11]
	s_cbranch_execz .LBB0_2306
	v_cmp_lt_u32_e32 vcc, s60, v23
	s_and_saveexec_b64 s[12:13], vcc
	s_xor_b64 s[12:13], exec, s[12:13]
	s_cbranch_execz .LBB0_2303
	v_cmp_lt_u32_e32 vcc, s61, v23
	s_and_saveexec_b64 s[42:43], vcc
	s_xor_b64 s[42:43], exec, s[42:43]
	s_cbranch_execz .LBB0_2300
	v_cmp_lt_u32_e32 vcc, s62, v23
	s_and_saveexec_b64 s[44:45], vcc
	s_xor_b64 s[44:45], exec, s[44:45]
	v_lshl_add_u32 v0, v1, 3, v38
	s_andn2_saveexec_b64 s[44:45], s[44:45]
	v_mul_lo_u32 v0, v24, s63
	v_add_u32_e32 v1, s55, v42
	v_add3_u32 v0, v1, v0, s64
	s_or_b64 exec, exec, s[44:45]

.LBB0_2309:
	s_andn2_saveexec_b64 s[4:5], s[4:5]
	v_lshl_add_u32 v0, v1, 3, v41
	s_or_b64 exec, exec, s[4:5]
	v_mad_i64_i32 v[4:5], s[4:5], v24, s66, v[16:17]
	v_ashrrev_i32_e32 v1, 31, v0
	v_lshl_add_u64 v[0:1], v[0:1], 1, v[4:5]
	global_load_dwordx4 v[8:11], v[0:1], off
	v_add_u32_e32 v47, s56, v44
	v_mul_hi_i32 v0, v47, s58
	v_add_u32_e32 v0, v0, v47
	v_lshrrev_b32_e32 v1, 31, v0
	v_ashrrev_i32_e32 v0, 7, v0
	v_add_u32_e32 v22, v0, v1
	v_mul_lo_u32 v0, v22, s59
	v_add_u32_e32 v21, v47, v0
	v_add3_u32 v1, v2, s38, v0
	v_cmp_lt_i32_e64 s[4:5], 3, v21
	s_and_saveexec_b64 s[10:11], s[4:5]
	s_xor_b64 s[10:11], exec, s[10:11]
	s_cbranch_execz .LBB0_2329
	v_cmp_lt_u32_e32 vcc, 51, v21
	s_and_saveexec_b64 s[12:13], vcc
	s_xor_b64 s[12:13], exec, s[12:13]
	s_cbranch_execz .LBB0_2326
	v_cmp_lt_u32_e32 vcc, s60, v21
	s_and_saveexec_b64 s[42:43], vcc
	s_xor_b64 s[42:43], exec, s[42:43]
	s_cbranch_execz .LBB0_2323
	v_cmp_lt_u32_e32 vcc, s61, v21
	s_and_saveexec_b64 s[44:45], vcc
	s_xor_b64 s[44:45], exec, s[44:45]
	s_cbranch_execz .LBB0_2320
	v_cmp_lt_u32_e32 vcc, s62, v21
	s_and_saveexec_b64 s[46:47], vcc
	s_xor_b64 s[46:47], exec, s[46:47]
	v_lshl_add_u32 v0, v1, 3, v38
	s_andn2_saveexec_b64 s[46:47], s[46:47]
	v_mul_lo_u32 v0, v22, s63
	v_add_u32_e32 v1, s57, v42
	v_add3_u32 v0, v1, v0, s64
	s_or_b64 exec, exec, s[46:47]
	s_load_dwordx2 s[86:87], s[90:91], 0x140

.LBB0_2329:
	s_andn2_saveexec_b64 s[10:11], s[10:11]
	v_lshl_add_u32 v0, v1, 3, v41
	s_or_b64 exec, exec, s[10:11]
	v_mad_i64_i32 v[2:3], s[10:11], v22, s66, v[16:17]
	v_ashrrev_i32_e32 v1, 31, v0
	v_lshl_add_u64 v[0:1], v[0:1], 1, v[2:3]
	global_load_dwordx4 v[4:7], v[0:1], off
	v_add_u32_e32 v46, s49, v44
	v_mul_hi_i32 v0, v46, s58
	v_add_u32_e32 v0, v0, v46
	v_lshrrev_b32_e32 v1, 31, v0
	v_ashrrev_i32_e32 v0, 7, v0
	v_add_u32_e32 v20, v0, v1
	v_mul_lo_u32 v0, v20, s59
	s_lshl_b32 s10, s84, 9
	v_add_u32_e32 v45, v46, v0
	v_add3_u32 v1, s10, v50, v0
	v_cmp_lt_i32_e32 vcc, 3, v45
	s_and_saveexec_b64 s[10:11], vcc
	s_xor_b64 s[12:13], exec, s[10:11]
	s_cbranch_execz .LBB0_2349
	v_cmp_lt_u32_e64 s[10:11], 51, v45
	s_and_saveexec_b64 s[42:43], s[10:11]
	s_xor_b64 s[42:43], exec, s[42:43]
	s_cbranch_execz .LBB0_2346
	v_cmp_lt_u32_e64 s[10:11], s60, v45
	s_and_saveexec_b64 s[44:45], s[10:11]
	s_xor_b64 s[44:45], exec, s[44:45]
	s_cbranch_execz .LBB0_2343
	v_cmp_lt_u32_e64 s[10:11], s61, v45
	s_and_saveexec_b64 s[46:47], s[10:11]
	s_xor_b64 s[46:47], exec, s[46:47]
	s_cbranch_execz .LBB0_2340
	v_cmp_lt_u32_e64 s[10:11], s62, v45
	s_and_saveexec_b64 s[84:85], s[10:11]
	s_xor_b64 s[10:11], exec, s[84:85]
	v_lshl_add_u32 v0, v1, 3, v38
	s_andn2_saveexec_b64 s[10:11], s[10:11]
	v_mul_lo_u32 v0, v20, s63
	v_add_u32_e32 v1, s52, v42
	v_add3_u32 v0, v1, v0, s64
	s_or_b64 exec, exec, s[10:11]
	s_waitcnt lgkmcnt(0)
	s_load_dwordx2 s[86:87], s[90:91], 0x140

.LBB0_2349:
	s_andn2_saveexec_b64 s[10:11], s[12:13]
	v_lshl_add_u32 v0, v1, 3, v41
	s_or_b64 exec, exec, s[10:11]
	v_mad_i64_i32 v[2:3], s[10:11], v20, s66, v[16:17]
	v_ashrrev_i32_e32 v1, 31, v0
	v_lshl_add_u64 v[0:1], v[0:1], 1, v[2:3]
	global_load_dwordx4 v[0:3], v[0:1], off
	v_add_u32_e32 v28, 0xfffff000, v26
	v_lshrrev_b32_e32 v28, 11, v28
	v_ashrrev_i32_e32 v29, 8, v26
	v_cmp_lt_i32_e64 s[12:13], s72, v18
	v_cmp_gt_i32_e64 s[10:11], s67, v18
	v_ashrrev_i32_e32 v27, 31, v26
	v_cndmask_b32_e64 v28, v29, v28, s[12:13]
	v_lshl_or_b32 v28, v28, 1, 1
	v_cndmask_b32_e64 v18, v36, v37, s[12:13]
	v_ashrrev_i32_e32 v29, 31, v28
	v_and_b32_e32 v18, v18, v26
	v_lshlrev_b64 v[28:29], 8, v[28:29]
	v_lshl_add_u64 v[34:35], v[28:29], 0, v[18:19]
	s_and_saveexec_b64 s[12:13], s[8:9]
	s_xor_b64 s[12:13], exec, s[12:13]
	s_cbranch_execnz .LBB0_2355
	s_andn2_saveexec_b64 s[8:9], s[12:13]
	s_cbranch_execnz .LBB0_2372

.LBB0_2376:
	v_cmp_ne_u64_e64 s[8:9], 0, v[32:33]
	s_and_saveexec_b64 s[12:13], s[8:9]
	s_cbranch_execz .LBB0_2378
	global_load_dwordx4 v[52:55], v[32:33], off
	s_nop 0
	global_load_dwordx4 v[30:33], v[32:33], off offset:16
	s_waitcnt vmcnt(0) lgkmcnt(0)
	v_lshlrev_b32_e32 v18, 16, v12
	v_and_b32_e32 v12, 0xffff0000, v12
	v_and_b32_e32 v34, 0xffff0000, v13
	v_lshlrev_b32_e32 v56, 16, v14
	v_and_b32_e32 v14, 0xffff0000, v14
	v_and_b32_e32 v60, 0xffff0000, v15
	v_lshlrev_b32_e32 v26, 16, v13
	v_lshlrev_b32_e32 v58, 16, v15
	v_pk_mul_f32 v[12:13], v[52:53], v[12:13] op_sel:[1,0] op_sel_hi:[0,0]
	v_pk_mul_f32 v[34:35], v[54:55], v[34:35] op_sel:[1,0] op_sel_hi:[0,0]
	v_pk_mul_f32 v[14:15], v[30:31], v[14:15] op_sel:[1,0] op_sel_hi:[0,0]
	v_pk_mul_f32 v[60:61], v[32:33], v[60:61] op_sel:[1,0] op_sel_hi:[0,0]
	v_pk_fma_f32 v[62:63], v[52:53], v[18:19], v[12:13] neg_lo:[0,0,1] neg_hi:[0,0,1]
	v_pk_fma_f32 v[12:13], v[52:53], v[18:19], v[12:13] op_sel_hi:[1,0,1]
	v_pk_fma_f32 v[52:53], v[54:55], v[26:27], v[34:35] neg_lo:[0,0,1] neg_hi:[0,0,1]
	v_pk_fma_f32 v[26:27], v[54:55], v[26:27], v[34:35] op_sel_hi:[1,0,1]
	v_pk_fma_f32 v[34:35], v[30:31], v[56:57], v[14:15] neg_lo:[0,0,1] neg_hi:[0,0,1]
	v_pk_fma_f32 v[14:15], v[30:31], v[56:57], v[14:15] op_sel_hi:[1,0,1]
	v_pk_fma_f32 v[30:31], v[32:33], v[58:59], v[60:61] neg_lo:[0,0,1] neg_hi:[0,0,1]
	v_pk_fma_f32 v[32:33], v[32:33], v[58:59], v[60:61] op_sel_hi:[1,0,1]
	v_cvt_pk_bf16_f32 v12, v62, v13
	v_cvt_pk_bf16_f32 v13, v52, v27
	v_cvt_pk_bf16_f32 v14, v34, v15
	v_cvt_pk_bf16_f32 v15, v30, v33

.LBB0_2432:
	v_cmp_ne_u64_e64 s[4:5], 0, v[12:13]
	s_and_saveexec_b64 s[8:9], s[4:5]
	s_cbranch_execz .LBB0_2434
	global_load_dwordx4 v[22:25], v[12:13], off
	s_nop 0
	global_load_dwordx4 v[10:13], v[12:13], off offset:16
	v_lshlrev_b32_e32 v14, 16, v4
	v_and_b32_e32 v4, 0xffff0000, v4
	v_and_b32_e32 v26, 0xffff0000, v5
	v_lshlrev_b32_e32 v28, 16, v6
	v_and_b32_e32 v6, 0xffff0000, v6
	v_and_b32_e32 v32, 0xffff0000, v7
	v_lshlrev_b32_e32 v18, 16, v5
	v_lshlrev_b32_e32 v30, 16, v7
	s_waitcnt vmcnt(0) lgkmcnt(0)
	v_pk_mul_f32 v[4:5], v[22:23], v[4:5] op_sel:[1,0] op_sel_hi:[0,0]
	v_pk_mul_f32 v[26:27], v[24:25], v[26:27] op_sel:[1,0] op_sel_hi:[0,0]
	v_pk_mul_f32 v[6:7], v[10:11], v[6:7] op_sel:[1,0] op_sel_hi:[0,0]
	v_pk_mul_f32 v[32:33], v[12:13], v[32:33] op_sel:[1,0] op_sel_hi:[0,0]
	v_pk_fma_f32 v[34:35], v[22:23], v[14:15], v[4:5] neg_lo:[0,0,1] neg_hi:[0,0,1]
	v_pk_fma_f32 v[4:5], v[22:23], v[14:15], v[4:5] op_sel_hi:[1,0,1]
	v_pk_fma_f32 v[14:15], v[24:25], v[18:19], v[26:27] neg_lo:[0,0,1] neg_hi:[0,0,1]
	v_pk_fma_f32 v[22:23], v[24:25], v[18:19], v[26:27] op_sel_hi:[1,0,1]
	v_pk_fma_f32 v[24:25], v[10:11], v[28:29], v[6:7] neg_lo:[0,0,1] neg_hi:[0,0,1]
	v_pk_fma_f32 v[6:7], v[10:11], v[28:29], v[6:7] op_sel_hi:[1,0,1]
	v_pk_fma_f32 v[10:11], v[12:13], v[30:31], v[32:33] neg_lo:[0,0,1] neg_hi:[0,0,1]
	v_pk_fma_f32 v[12:13], v[12:13], v[30:31], v[32:33] op_sel_hi:[1,0,1]
	v_cvt_pk_bf16_f32 v4, v34, v5
	v_cvt_pk_bf16_f32 v5, v14, v23
	v_cvt_pk_bf16_f32 v6, v24, v7
	v_cvt_pk_bf16_f32 v7, v10, v13

.LBB0_2505:
	s_andn2_saveexec_b64 s[4:5], s[8:9]
	v_lshl_add_u32 v0, v16, 3, v35
	s_or_b64 exec, exec, s[4:5]
	v_mad_i64_i32 v[2:3], s[4:5], v14, s54, v[10:11]
	v_ashrrev_i32_e32 v1, 31, v0
	v_lshl_add_u64 v[0:1], v[0:1], 1, v[2:3]
	global_load_dwordx4 v[0:3], v[0:1], off
	v_add_u32_e32 v12, 0xfffff000, v20
	v_lshrrev_b32_e32 v12, 11, v12
	v_ashrrev_i32_e32 v17, 8, v20
	v_cmp_lt_i32_e64 s[8:9], s56, v9
	v_ashrrev_i32_e32 v21, 31, v20
	v_cmp_gt_i32_e64 s[4:5], s55, v9
	v_cndmask_b32_e64 v17, v17, v12, s[8:9]
	v_lshl_or_b32 v22, v17, 1, 1
	v_cndmask_b32_e64 v19, v30, v31, s[8:9]
	v_ashrrev_i32_e32 v23, 31, v22
	v_and_b32_e32 v12, v19, v20
	v_lshlrev_b64 v[22:23], 8, v[22:23]
	v_lshl_add_u64 v[28:29], v[22:23], 0, v[12:13]
	s_and_saveexec_b64 s[8:9], s[6:7]
	s_xor_b64 s[8:9], exec, s[8:9]
	s_cbranch_execnz .LBB0_2511
	s_andn2_saveexec_b64 s[6:7], s[8:9]
	s_cbranch_execnz .LBB0_2528

.LBB0_2584:
	s_andn2_saveexec_b64 s[6:7], s[6:7]
	v_lshl_add_u32 v0, v1, 3, v25
	s_or_b64 exec, exec, s[6:7]
	v_mad_i64_i32 v[2:3], s[6:7], v12, s51, v[6:7]
	v_ashrrev_i32_e32 v1, 31, v0
	v_lshl_add_u64 v[0:1], v[0:1], 1, v[2:3]
	global_load_dwordx4 v[0:3], v[0:1], off
	v_add_u32_e32 v8, 0xfffff000, v12
	v_lshrrev_b32_e32 v8, 11, v8
	v_ashrrev_i32_e32 v10, 8, v12
	v_cmp_lt_i32_e64 s[6:7], s53, v5
	v_ashrrev_i32_e32 v13, 31, v12
	v_cmp_gt_i32_e32 vcc, s52, v5
	v_cndmask_b32_e64 v10, v10, v8, s[6:7]
	v_cndmask_b32_e64 v11, v20, v21, s[6:7]
	v_lshl_or_b32 v10, v10, 1, 1
	v_and_b32_e32 v8, v11, v12
	v_ashrrev_i32_e32 v11, 31, v10
	v_lshlrev_b64 v[10:11], 8, v[10:11]
	v_lshl_add_u64 v[18:19], v[10:11], 0, v[8:9]
	s_and_saveexec_b64 s[6:7], s[4:5]
	s_xor_b64 s[6:7], exec, s[6:7]
	s_cbranch_execnz .LBB0_2590
	s_andn2_saveexec_b64 s[4:5], s[6:7]
	s_cbranch_execnz .LBB0_2607

.LBB0_2615:
	v_add_u32_e32 v18, s39, v53
	v_mad_i64_i32 v[22:23], s[4:5], v18, s54, v[16:17]
	s_waitcnt lgkmcnt(0)
	global_load_dwordx4 v[8:11], v51, s[56:57] offset:48
	global_load_dwordx4 v[0:3], v51, s[58:59] offset:48
	global_load_dwordx4 v[12:15], v51, s[56:57] offset:32
	global_load_dwordx4 v[4:7], v51, s[58:59] offset:32
	v_add_co_u32_e32 v36, vcc, 0x1000, v22
	v_add_u32_e32 v20, s2, v53
	s_nop 0
	v_addc_co_u32_e32 v37, vcc, 0, v23, vcc
	v_mad_i64_i32 v[34:35], s[4:5], v20, s54, v[16:17]
	global_load_dwordx4 v[26:29], v[36:37], off offset:64
	global_load_dwordx4 v[30:33], v[36:37], off offset:80
	v_add_co_u32_e32 v42, vcc, s55, v34
	s_add_i32 s3, s3, s33
	s_nop 0
	v_addc_co_u32_e32 v43, vcc, 0, v35, vcc
	global_load_dwordx4 v[34:37], v[42:43], off offset:64
	global_load_dwordx4 v[38:41], v[42:43], off offset:80
	s_add_i32 s4, s79, s3
	s_cmp_gt_i32 s4, 23
	v_ashrrev_i32_e32 v19, 31, v18
	v_lshlrev_b64 v[18:19], 5, v[18:19]
	v_lshl_add_u64 v[24:25], s[72:73], 0, v[18:19]
	v_lshl_add_u64 v[22:23], s[74:75], 0, v[18:19]
	v_ashrrev_i32_e32 v21, 31, v20
	v_lshlrev_b64 v[20:21], 5, v[20:21]
	v_lshl_add_u64 v[18:19], s[72:73], 0, v[20:21]
	v_lshl_add_u64 v[20:21], s[74:75], 0, v[20:21]
	v_add_u32_e32 v53, s38, v53
	s_waitcnt vmcnt(0)
	v_mul_f32_e32 v8, 0x3fb8aa3b, v8
	v_mul_f32_e32 v9, 0x3fb8aa3b, v9
	v_mul_f32_e32 v12, 0x3fb8aa3b, v12
	v_mul_f32_e32 v14, 0x3fb8aa3b, v14
	v_mul_f32_e32 v13, 0x3fb8aa3b, v13
	v_mul_f32_e32 v15, 0x3fb8aa3b, v15
	v_mul_f32_e32 v10, 0x3fb8aa3b, v10
	v_mul_f32_e32 v11, 0x3fb8aa3b, v11
	v_exp_f32_e32 v42, v12
	v_exp_f32_e32 v44, v14
	v_exp_f32_e32 v43, v13
	v_exp_f32_e32 v45, v15
	v_exp_f32_e32 v46, v8
	v_exp_f32_e32 v47, v9
	v_exp_f32_e32 v48, v10
	v_exp_f32_e32 v49, v11
	s_waitcnt lgkmcnt(0)
	v_lshlrev_b32_e32 v8, 16, v26
	v_and_b32_e32 v9, 0xffff0000, v26
	v_lshlrev_b32_e32 v10, 16, v27
	v_and_b32_e32 v11, 0xffff0000, v27
	v_lshlrev_b32_e32 v14, 16, v30
	v_and_b32_e32 v26, 0xffff0000, v30
	v_lshlrev_b32_e32 v27, 16, v31
	v_lshlrev_b32_e32 v12, 16, v28
	v_and_b32_e32 v13, 0xffff0000, v28
	v_lshlrev_b32_e32 v28, 16, v29
	v_and_b32_e32 v29, 0xffff0000, v29
	v_and_b32_e32 v30, 0xffff0000, v31
	v_lshlrev_b32_e32 v31, 16, v32
	v_and_b32_e32 v32, 0xffff0000, v32
	v_mul_f32_e32 v56, 0xbfb8aa3b, v14
	v_pk_add_f32 v[14:15], v[4:5], v[8:9]
	v_mul_f32_e32 v57, 0xbfb8aa3b, v26
	v_mul_f32_e32 v58, 0xbfb8aa3b, v27
	v_pk_add_f32 v[26:27], v[6:7], v[10:11]
	v_lshlrev_b32_e32 v54, 16, v33
	v_and_b32_e32 v55, 0xffff0000, v33
	v_xor_b32_e32 v8, 0x80000000, v42
	v_xor_b32_e32 v10, 0x80000000, v44
	v_mul_f32_e32 v42, 0xbfb8aa3b, v30
	v_mul_f32_e32 v44, 0xbfb8aa3b, v32
	v_pk_add_f32 v[32:33], v[2:3], v[28:29]
	v_lshlrev_b32_e32 v2, 16, v36
	v_and_b32_e32 v3, 0xffff0000, v36
	v_mul_f32_e32 v62, 0x3fb8aa3b, v15
	v_exp_f32_e32 v36, v58
	v_mul_f32_e32 v58, 0x3fb8aa3b, v27
	v_xor_b32_e32 v9, 0x80000000, v43
	v_xor_b32_e32 v11, 0x80000000, v45
	v_mul_f32_e32 v43, 0xbfb8aa3b, v31
	v_pk_add_f32 v[30:31], v[0:1], v[12:13]
	v_mul_f32_e32 v45, 0xbfb8aa3b, v54
	v_xor_b32_e32 v13, 0x80000000, v47
	v_xor_b32_e32 v12, 0x80000000, v46
	v_xor_b32_e32 v29, 0x80000000, v49
	v_xor_b32_e32 v28, 0x80000000, v48
	v_mul_f32_e32 v46, 0xbfb8aa3b, v55
	v_lshlrev_b32_e32 v6, 16, v34
	v_and_b32_e32 v7, 0xffff0000, v34
	v_lshlrev_b32_e32 v4, 16, v35
	v_and_b32_e32 v5, 0xffff0000, v35
	v_lshlrev_b32_e32 v0, 16, v37
	v_and_b32_e32 v1, 0xffff0000, v37
	v_lshlrev_b32_e32 v47, 16, v38
	v_and_b32_e32 v48, 0xffff0000, v38
	v_lshlrev_b32_e32 v49, 16, v39
	v_and_b32_e32 v54, 0xffff0000, v39
	v_lshlrev_b32_e32 v55, 16, v40
	v_and_b32_e32 v59, 0xffff0000, v40
	v_lshlrev_b32_e32 v60, 16, v41
	v_and_b32_e32 v61, 0xffff0000, v41
	v_exp_f32_e32 v34, v56
	v_mul_f32_e32 v56, 0x3fb8aa3b, v14
	v_exp_f32_e32 v35, v57
	v_mul_f32_e32 v57, 0x3fb8aa3b, v26
	v_exp_f32_e32 v37, v42
	v_exp_f32_e32 v62, v62
	v_exp_f32_e32 v58, v58
	v_exp_f32_e32 v38, v43
	v_mul_f32_e32 v42, 0x3fb8aa3b, v30
	v_mul_f32_e32 v43, 0x3fb8aa3b, v31
	v_exp_f32_e32 v40, v45
	v_exp_f32_e32 v41, v46
	v_mul_f32_e32 v46, 0xbfb8aa3b, v47
	v_mul_f32_e32 v47, 0xbfb8aa3b, v48
	v_mul_f32_e32 v48, 0xbfb8aa3b, v49
	v_mul_f32_e32 v49, 0xbfb8aa3b, v54
	v_mul_f32_e32 v54, 0xbfb8aa3b, v55
	v_mul_f32_e32 v55, 0xbfb8aa3b, v59
	v_mul_f32_e32 v59, 0xbfb8aa3b, v60
	v_mul_f32_e32 v60, 0xbfb8aa3b, v61
	v_exp_f32_e32 v61, v56
	v_exp_f32_e32 v63, v57
	v_exp_f32_e32 v39, v44
	v_mul_f32_e32 v44, 0x3fb8aa3b, v32
	v_mul_f32_e32 v45, 0x3fb8aa3b, v33
	v_exp_f32_e32 v64, v42
	v_exp_f32_e32 v65, v43
	v_exp_f32_e32 v42, v46
	v_exp_f32_e32 v43, v47
	v_exp_f32_e32 v46, v48
	v_exp_f32_e32 v47, v49
	v_exp_f32_e32 v54, v54
	v_exp_f32_e32 v55, v55
	v_exp_f32_e32 v56, v59
	v_exp_f32_e32 v57, v60
	v_exp_f32_e32 v66, v44
	v_exp_f32_e32 v67, v45
	v_pk_add_f32 v[48:49], v[36:37], 1.0 op_sel_hi:[1,0]
	v_add_f32_e32 v60, 1.0, v62
	v_add_f32_e32 v58, 1.0, v58
	v_pk_add_f32 v[44:45], v[34:35], 1.0 op_sel_hi:[1,0]
	v_pk_add_f32 v[40:41], v[40:41], 1.0 op_sel_hi:[1,0]
	v_add_f32_e32 v59, 1.0, v61
	v_add_f32_e32 v61, 1.0, v63
	v_div_scale_f32 v62, s[4:5], v49, v49, 1.0
	v_cmp_gt_f32_e64 s[40:41], s60, v60
	v_cmp_gt_f32_e64 s[44:45], s60, v58
	v_pk_add_f32 v[36:37], v[38:39], 1.0 op_sel_hi:[1,0]
	v_div_scale_f32 v68, s[4:5], v48, v48, 1.0
	v_div_scale_f32 v72, s[4:5], v44, v44, 1.0
	v_div_scale_f32 v74, s[4:5], v41, v41, 1.0
	v_pk_add_f32 v[42:43], v[42:43], 1.0 op_sel_hi:[1,0]
	v_pk_add_f32 v[46:47], v[46:47], 1.0 op_sel_hi:[1,0]
	v_pk_add_f32 v[34:35], v[54:55], 1.0 op_sel_hi:[1,0]
	v_pk_add_f32 v[38:39], v[56:57], 1.0 op_sel_hi:[1,0]
	v_cndmask_b32_e64 v55, 0, 32, s[40:41]
	v_cmp_gt_f32_e64 s[42:43], s60, v61
	v_cndmask_b32_e64 v57, 0, 32, s[44:45]
	v_rcp_f32_e32 v82, v62
	v_div_scale_f32 v70, s[4:5], v45, v45, 1.0
	v_add_f32_e32 v64, 1.0, v64
	v_add_f32_e32 v65, 1.0, v65
	v_add_f32_e32 v66, 1.0, v66
	v_add_f32_e32 v67, 1.0, v67
	v_div_scale_f32 v76, s[4:5], v40, v40, 1.0
	v_cmp_gt_f32_e64 s[36:37], s60, v59
	v_cndmask_b32_e64 v56, 0, 32, s[42:43]
	v_rcp_f32_e32 v83, v68
	v_rcp_f32_e32 v85, v72
	v_rcp_f32_e32 v90, v74
	v_div_scale_f32 v96, s[16:17], v46, v46, 1.0
	v_div_scale_f32 v100, s[16:17], v42, v42, 1.0
	v_div_scale_f32 v102, s[16:17], v39, v39, 1.0
	v_ldexp_f32 v55, v60, v55
	v_ldexp_f32 v57, v58, v57
	v_cndmask_b32_e64 v54, 0, 32, s[36:37]
	v_rcp_f32_e32 v84, v70
	v_cmp_gt_f32_e64 s[46:47], s60, v64
	v_cmp_gt_f32_e64 s[48:49], s60, v65
	v_cmp_gt_f32_e64 s[50:51], s60, v66
	v_cmp_gt_f32_e64 s[52:53], s60, v67
	v_rcp_f32_e32 v91, v76
	v_div_scale_f32 v98, s[16:17], v43, v43, 1.0
	v_div_scale_f32 v104, s[16:17], v38, v38, 1.0
	v_ldexp_f32 v56, v61, v56
	v_rcp_f32_e32 v111, v96
	v_rcp_f32_e32 v113, v100
	v_rcp_f32_e32 v114, v102
	v_log_f32_e32 v55, v55
	v_log_f32_e32 v57, v57
	v_div_scale_f32 v78, s[4:5], v37, v37, 1.0
	v_cndmask_b32_e64 v86, 0, 32, s[46:47]
	v_cndmask_b32_e64 v87, 0, 32, s[48:49]
	v_cndmask_b32_e64 v88, 0, 32, s[50:51]
	v_cndmask_b32_e64 v89, 0, 32, s[52:53]
	v_div_scale_f32 v94, s[16:17], v47, v47, 1.0
	v_ldexp_f32 v54, v59, v54
	v_rcp_f32_e32 v112, v98
	v_rcp_f32_e32 v115, v104
	v_log_f32_e32 v56, v56
	v_div_scale_f32 v80, s[4:5], v36, v36, 1.0
	v_rcp_f32_e32 v92, v78
	v_div_scale_f32 v106, s[16:17], v35, v35, 1.0
	v_ldexp_f32 v64, v64, v86
	v_ldexp_f32 v65, v65, v87
	v_ldexp_f32 v66, v66, v88
	v_ldexp_f32 v67, v67, v89
	v_rcp_f32_e32 v110, v94
	v_log_f32_e32 v54, v54
	v_fma_f32 v118, -v62, v82, 1.0
	v_div_scale_f32 v63, vcc, 1.0, v49, 1.0
	v_rcp_f32_e32 v93, v80
	v_div_scale_f32 v108, s[16:17], v34, v34, 1.0
	v_rcp_f32_e32 v116, v106
	v_log_f32_e32 v64, v64
	v_log_f32_e32 v65, v65
	v_log_f32_e32 v66, v66
	v_log_f32_e32 v67, v67
	v_fma_f32 v119, -v68, v83, 1.0
	v_fma_f32 v121, -v72, v85, 1.0
	v_fma_f32 v122, -v74, v90, 1.0
	v_fmac_f32_e32 v82, v118, v82
	v_div_scale_f32 v69, s[30:31], 1.0, v48, 1.0
	v_rcp_f32_e32 v117, v108
	v_fma_f32 v120, -v70, v84, 1.0
	v_fma_f32 v123, -v76, v91, 1.0
	v_fmac_f32_e32 v83, v119, v83
	v_fmac_f32_e32 v85, v121, v85
	v_fmac_f32_e32 v90, v122, v90
	v_fma_f32 v119, -v96, v111, 1.0
	v_fma_f32 v121, -v100, v113, 1.0
	v_fma_f32 v122, -v102, v114, 1.0
	v_mul_f32_e32 v127, 0x3f317217, v55
	v_mul_f32_e32 v129, 0x3f317217, v57
	v_mul_f32_e32 v130, v63, v82
	v_fmac_f32_e32 v84, v120, v84
	v_fmac_f32_e32 v91, v123, v91
	v_fma_f32 v120, -v98, v112, 1.0
	v_fma_f32 v123, -v104, v115, 1.0
	v_mul_f32_e32 v128, 0x3f317217, v56
	v_mul_f32_e32 v131, v69, v83
	v_fmac_f32_e32 v111, v119, v111
	v_fmac_f32_e32 v113, v121, v113
	v_fmac_f32_e32 v114, v122, v114
	v_fma_f32 v119, v55, s61, -v127
	v_fma_f32 v121, v57, s61, -v129
	v_fma_f32 v122, -v62, v130, v63
	v_div_scale_f32 v71, s[14:15], 1.0, v45, 1.0
	v_fma_f32 v124, -v78, v92, 1.0
	v_fma_f32 v118, -v94, v110, 1.0
	v_mul_f32_e32 v126, 0x3f317217, v54
	v_fmac_f32_e32 v112, v120, v112
	v_fmac_f32_e32 v115, v123, v115
	v_fma_f32 v120, v56, s61, -v128
	v_fma_f32 v123, -v68, v131, v69
	v_fmac_f32_e32 v119, 0x3377d1cf, v55
	v_fmac_f32_e32 v121, 0x3377d1cf, v57
	v_fmac_f32_e32 v130, v122, v82
	v_div_scale_f32 v73, s[10:11], 1.0, v44, 1.0
	v_cndmask_b32_e64 v59, 0, v52, s[36:37]
	v_cndmask_b32_e64 v61, 0, v52, s[42:43]
	v_fma_f32 v125, -v80, v93, 1.0
	v_fmac_f32_e32 v92, v124, v92
	v_fma_f32 v124, -v106, v116, 1.0
	v_mul_f32_e32 v132, v71, v84
	v_mul_f32_e32 v134, 0x3f317217, v64
	v_mul_f32_e32 v135, 0x3f317217, v65
	v_mul_f32_e32 v136, 0x3f317217, v66
	v_mul_f32_e32 v137, 0x3f317217, v67
	v_fmac_f32_e32 v110, v118, v110
	v_fma_f32 v118, v54, s61, -v126
	v_fmac_f32_e32 v120, 0x3377d1cf, v56
	v_fmac_f32_e32 v131, v123, v83
	v_fmac_f32_e32 v119, 0x3f317217, v55
	v_cmp_lt_f32_e64 s[36:37], |v55|, s62
	v_fmac_f32_e32 v121, 0x3f317217, v57
	v_cmp_lt_f32_e64 s[42:43], |v57|, s62
	v_fma_f32 v62, -v62, v130, v63
	v_div_scale_f32 v75, s[12:13], 1.0, v41, 1.0
	v_cndmask_b32_e64 v60, 0, v52, s[40:41]
	v_cndmask_b32_e64 v58, 0, v52, s[44:45]
	v_fmac_f32_e32 v93, v125, v93
	v_fma_f32 v125, -v108, v117, 1.0
	v_mul_f32_e32 v133, v73, v85
	v_fmac_f32_e32 v116, v124, v116
	v_fma_f32 v124, -v70, v132, v71
	v_fma_f32 v126, v64, s61, -v134
	v_fma_f32 v127, v65, s61, -v135
	v_fma_f32 v128, v66, s61, -v136
	v_fma_f32 v129, v67, s61, -v137
	v_fmac_f32_e32 v118, 0x3377d1cf, v54
	v_fmac_f32_e32 v120, 0x3f317217, v56
	v_cmp_lt_f32_e64 s[40:41], |v56|, s62
	v_fma_f32 v63, -v68, v131, v69
	v_cndmask_b32_e64 v55, v55, v119, s[36:37]
	v_cndmask_b32_e64 v57, v57, v121, s[42:43]
	v_div_fmas_f32 v62, v62, v82, v130
	s_mov_b64 vcc, s[30:31]
	v_div_scale_f32 v77, s[8:9], 1.0, v40, 1.0
	v_cndmask_b32_e64 v89, 0, v52, s[52:53]
	v_mul_f32_e32 v138, v75, v90
	v_fmac_f32_e32 v117, v125, v117
	v_fma_f32 v125, -v72, v133, v73
	v_fmac_f32_e32 v132, v124, v84
	v_fmac_f32_e32 v126, 0x3377d1cf, v64
	v_fmac_f32_e32 v127, 0x3377d1cf, v65
	v_fmac_f32_e32 v128, 0x3377d1cf, v66
	v_fmac_f32_e32 v129, 0x3377d1cf, v67
	v_fmac_f32_e32 v118, 0x3f317217, v54
	v_cmp_lt_f32_e64 s[52:53], |v54|, s62
	v_cndmask_b32_e64 v56, v56, v120, s[40:41]
	v_sub_f32_e32 v55, v55, v60
	v_sub_f32_e32 v58, v57, v58
	v_div_fixup_f32 v57, v62, v49, 1.0
	v_div_fmas_f32 v49, v63, v83, v131
	v_cmp_lt_f32_e32 vcc, s63, v15
	v_div_scale_f32 v79, s[6:7], 1.0, v37, 1.0
	v_cndmask_b32_e64 v86, 0, v52, s[46:47]
	v_cndmask_b32_e64 v87, 0, v52, s[48:49]
	v_cndmask_b32_e64 v88, 0, v52, s[50:51]
	v_mul_f32_e32 v139, v77, v91
	v_fma_f32 v134, -v74, v138, v75
	v_fmac_f32_e32 v133, v125, v85
	v_fma_f32 v68, -v70, v132, v71
	v_fmac_f32_e32 v126, 0x3f317217, v64
	v_cmp_lt_f32_e64 s[44:45], |v64|, s62
	v_fmac_f32_e32 v127, 0x3f317217, v65
	v_cmp_lt_f32_e64 s[46:47], |v65|, s62
	v_fmac_f32_e32 v128, 0x3f317217, v66
	v_cmp_lt_f32_e64 s[48:49], |v66|, s62
	v_fmac_f32_e32 v129, 0x3f317217, v67
	v_cmp_lt_f32_e64 s[50:51], |v67|, s62
	v_cndmask_b32_e64 v54, v54, v118, s[52:53]
	v_sub_f32_e32 v56, v56, v61
	v_cmp_lt_f32_e64 s[36:37], s63, v26
	v_cmp_lt_f32_e64 s[40:41], s63, v27
	v_cndmask_b32_e32 v15, v55, v15, vcc
	s_mov_b64 vcc, s[14:15]
	v_div_scale_f32 v81, s[4:5], 1.0, v36, 1.0
	v_mul_f32_e32 v140, v79, v92
	v_fma_f32 v135, -v76, v139, v77
	v_fmac_f32_e32 v138, v134, v90
	v_fma_f32 v69, -v72, v133, v73
	v_cndmask_b32_e64 v64, v64, v126, s[44:45]
	v_cndmask_b32_e64 v65, v65, v127, s[46:47]
	v_cndmask_b32_e64 v66, v66, v128, s[48:49]
	v_cndmask_b32_e64 v67, v67, v129, s[50:51]
	v_sub_f32_e32 v54, v54, v59
	v_cmp_lt_f32_e64 s[42:43], s63, v14
	v_cndmask_b32_e64 v27, v58, v27, s[40:41]
	v_cndmask_b32_e64 v26, v56, v26, s[36:37]
	v_div_fixup_f32 v56, v49, v48, 1.0
	v_div_fmas_f32 v48, v68, v84, v132
	s_mov_b64 vcc, s[10:11]
	v_mul_f32_e32 v141, v81, v93
	v_fma_f32 v136, -v78, v140, v79
	v_fmac_f32_e32 v139, v135, v91
	v_fma_f32 v70, -v74, v138, v75
	v_sub_f32_e32 v59, v64, v86
	v_sub_f32_e32 v60, v65, v87
	v_sub_f32_e32 v61, v66, v88
	v_sub_f32_e32 v62, v67, v89
	v_cmp_lt_f32_e64 s[30:31], s63, v32
	v_cmp_lt_f32_e64 s[44:45], s63, v33
	v_cmp_lt_f32_e64 s[46:47], s63, v30
	v_cmp_lt_f32_e64 s[48:49], s63, v31
	v_cndmask_b32_e64 v14, v54, v14, s[42:43]
	v_pk_mul_f32 v[10:11], v[26:27], v[10:11]
	v_div_fmas_f32 v26, v69, v85, v133
	s_mov_b64 vcc, s[12:13]
	v_div_scale_f32 v95, s[34:35], 1.0, v47, 1.0
	v_fma_f32 v137, -v80, v141, v81
	v_fmac_f32_e32 v140, v136, v92
	v_fma_f32 v71, -v76, v139, v77
	v_cndmask_b32_e64 v31, v60, v31, s[48:49]
	v_cndmask_b32_e64 v30, v59, v30, s[46:47]
	v_cndmask_b32_e64 v33, v62, v33, s[44:45]
	v_cndmask_b32_e64 v32, v61, v32, s[30:31]
	v_pk_mul_f32 v[8:9], v[14:15], v[8:9]
	v_div_fixup_f32 v54, v26, v44, 1.0
	v_div_fmas_f32 v26, v70, v90, v138
	s_mov_b64 vcc, s[8:9]
	v_mul_f32_e32 v142, v95, v110
	v_fmac_f32_e32 v141, v137, v93
	v_fma_f32 v72, -v78, v140, v79
	v_pk_mul_f32 v[14:15], v[32:33], v[28:29]
	v_pk_mul_f32 v[12:13], v[30:31], v[12:13]
	flat_store_dwordx4 v[24:25], v[8:11]
	flat_store_dwordx4 v[24:25], v[12:15] offset:16
	v_fma_f32 v122, -v94, v142, v95
	v_div_fmas_f32 v8, v71, v91, v139
	s_mov_b64 vcc, s[6:7]
	v_fma_f32 v73, -v80, v141, v81
	v_div_fixup_f32 v10, v8, v40, 1.0
	v_div_fmas_f32 v8, v72, v92, v140
	s_mov_b64 vcc, s[4:5]
	v_fmac_f32_e32 v142, v122, v110
	v_div_fixup_f32 v9, v8, v37, 1.0
	v_div_fmas_f32 v8, v73, v93, v141
	v_fma_f32 v74, -v94, v142, v95
	v_div_fixup_f32 v55, v48, v45, 1.0
	v_div_fixup_f32 v11, v26, v41, 1.0
	v_div_fixup_f32 v8, v8, v36, 1.0
	s_mov_b64 vcc, s[34:35]
	flat_store_dwordx4 v[22:23], v[54:57]
	v_div_fmas_f32 v12, v74, v110, v142
	flat_store_dwordx4 v[22:23], v[8:11] offset:16
	v_div_scale_f32 v97, s[28:29], 1.0, v46, 1.0
	s_nop 0
	v_div_fixup_f32 v11, v12, v47, 1.0
	global_load_dwordx4 v[12:15], v51, s[56:57] offset:32
	global_load_dwordx4 v[22:25], v51, s[58:59] offset:32
	global_load_dwordx4 v[26:29], v51, s[56:57] offset:48
	global_load_dwordx4 v[30:33], v51, s[58:59] offset:48
	v_div_scale_f32 v99, s[26:27], 1.0, v43, 1.0
	v_mul_f32_e32 v143, v97, v111
	v_div_scale_f32 v101, s[24:25], 1.0, v42, 1.0
	v_mul_f32_e32 v144, v99, v112
	v_fma_f32 v123, -v96, v143, v97
	v_div_scale_f32 v103, s[22:23], 1.0, v39, 1.0
	v_mul_f32_e32 v145, v101, v113
	v_fma_f32 v124, -v98, v144, v99
	v_fmac_f32_e32 v143, v123, v111
	v_div_scale_f32 v105, s[20:21], 1.0, v38, 1.0
	v_mul_f32_e32 v146, v103, v114
	v_fma_f32 v125, -v100, v145, v101
	v_fmac_f32_e32 v144, v124, v112
	v_fma_f32 v75, -v96, v143, v97
	s_mov_b64 vcc, s[28:29]
	v_div_scale_f32 v107, s[18:19], 1.0, v35, 1.0
	v_mul_f32_e32 v147, v105, v115
	v_fma_f32 v134, -v102, v146, v103
	v_fmac_f32_e32 v145, v125, v113
	v_fma_f32 v76, -v98, v144, v99
	v_div_fmas_f32 v8, v75, v111, v143
	s_mov_b64 vcc, s[26:27]
	v_div_scale_f32 v109, s[16:17], 1.0, v34, 1.0
	v_mul_f32_e32 v148, v107, v116
	v_fma_f32 v135, -v104, v147, v105
	v_fmac_f32_e32 v146, v134, v114
	v_fma_f32 v77, -v100, v145, v101
	v_div_fixup_f32 v10, v8, v46, 1.0
	v_div_fmas_f32 v8, v76, v112, v144
	s_mov_b64 vcc, s[24:25]
	v_mul_f32_e32 v149, v109, v117
	v_fma_f32 v136, -v106, v148, v107
	v_fmac_f32_e32 v147, v135, v115
	v_fma_f32 v78, -v102, v146, v103
	v_div_fixup_f32 v9, v8, v43, 1.0
	v_div_fmas_f32 v8, v77, v113, v145
	s_mov_b64 vcc, s[22:23]
	v_fma_f32 v137, -v108, v149, v109
	v_fmac_f32_e32 v148, v136, v116
	v_fma_f32 v79, -v104, v147, v105
	v_div_fmas_f32 v36, v78, v114, v146
	s_mov_b64 vcc, s[20:21]
	v_fmac_f32_e32 v149, v137, v117
	v_fma_f32 v80, -v106, v148, v107
	v_div_fixup_f32 v8, v8, v42, 1.0
	v_div_fixup_f32 v37, v36, v39, 1.0
	v_div_fmas_f32 v36, v79, v115, v147
	s_mov_b64 vcc, s[18:19]
	v_fma_f32 v81, -v108, v149, v109
	flat_store_dwordx4 v[20:21], v[8:11]
	v_div_fixup_f32 v36, v36, v38, 1.0
	s_waitcnt vmcnt(0)
	v_pk_add_f32 v[6:7], v[22:23], v[6:7]
	v_div_fmas_f32 v8, v80, v116, v148
	s_mov_b64 vcc, s[16:17]
	v_div_fixup_f32 v35, v8, v35, 1.0
	v_div_fmas_f32 v8, v81, v117, v149
	v_div_fixup_f32 v34, v8, v34, 1.0
	v_mul_f32_e32 v8, 0x3fb8aa3b, v12
	v_mul_f32_e32 v9, 0x3fb8aa3b, v13
	v_pk_add_f32 v[4:5], v[24:25], v[4:5]
	flat_store_dwordx4 v[20:21], v[34:37] offset:16
	v_mul_f32_e32 v10, 0x3fb8aa3b, v14
	v_mul_f32_e32 v11, 0x3fb8aa3b, v15
	v_mul_f32_e32 v12, 0x3fb8aa3b, v26
	v_mul_f32_e32 v13, 0x3fb8aa3b, v27
	v_pk_add_f32 v[2:3], v[30:31], v[2:3]
	v_pk_add_f32 v[0:1], v[32:33], v[0:1]
	v_exp_f32_e32 v20, v8
	v_exp_f32_e32 v21, v9
	v_mul_f32_e32 v8, 0x3fb8aa3b, v6
	v_mul_f32_e32 v9, 0x3fb8aa3b, v7
	v_mul_f32_e32 v22, 0x3fb8aa3b, v4
	v_mul_f32_e32 v23, 0x3fb8aa3b, v5
	v_mul_f32_e32 v14, 0x3fb8aa3b, v28
	v_mul_f32_e32 v15, 0x3fb8aa3b, v29
	v_exp_f32_e32 v10, v10
	v_exp_f32_e32 v11, v11
	v_exp_f32_e32 v24, v12
	v_exp_f32_e32 v25, v13
	v_mul_f32_e32 v12, 0x3fb8aa3b, v2
	v_mul_f32_e32 v13, 0x3fb8aa3b, v3
	v_mul_f32_e32 v26, 0x3fb8aa3b, v0
	v_mul_f32_e32 v27, 0x3fb8aa3b, v1
	v_exp_f32_e32 v28, v8
	v_exp_f32_e32 v29, v9
	v_exp_f32_e32 v22, v22
	v_exp_f32_e32 v23, v23
	v_exp_f32_e32 v14, v14
	v_exp_f32_e32 v15, v15
	v_exp_f32_e32 v30, v12
	v_exp_f32_e32 v31, v13
	v_exp_f32_e32 v26, v26
	v_exp_f32_e32 v27, v27
	v_xor_b32_e32 v9, 0x80000000, v11
	v_xor_b32_e32 v8, 0x80000000, v10
	v_xor_b32_e32 v11, 0x80000000, v21
	v_xor_b32_e32 v10, 0x80000000, v20
	v_add_f32_e32 v20, 1.0, v28
	v_add_f32_e32 v21, 1.0, v29
	v_add_f32_e32 v22, 1.0, v22
	v_add_f32_e32 v23, 1.0, v23
	v_xor_b32_e32 v13, 0x80000000, v15
	v_xor_b32_e32 v12, 0x80000000, v14
	v_xor_b32_e32 v15, 0x80000000, v25
	v_xor_b32_e32 v14, 0x80000000, v24
	v_add_f32_e32 v24, 1.0, v30
	v_add_f32_e32 v25, 1.0, v31
	v_add_f32_e32 v26, 1.0, v26
	v_add_f32_e32 v27, 1.0, v27
	v_cmp_gt_f32_e32 vcc, s60, v20
	v_cmp_gt_f32_e64 s[4:5], s60, v21
	v_cmp_gt_f32_e64 s[6:7], s60, v22
	v_cmp_gt_f32_e64 s[8:9], s60, v23
	v_cndmask_b32_e64 v28, 0, 32, vcc
	v_cndmask_b32_e64 v29, 0, 32, s[4:5]
	v_cndmask_b32_e64 v30, 0, 32, s[6:7]
	v_cndmask_b32_e64 v31, 0, 32, s[8:9]
	v_cmp_gt_f32_e64 s[10:11], s60, v24
	v_cmp_gt_f32_e64 s[12:13], s60, v25
	v_cmp_gt_f32_e64 s[14:15], s60, v26
	v_cmp_gt_f32_e64 s[16:17], s60, v27
	v_cndmask_b32_e64 v32, 0, 32, s[10:11]
	v_cndmask_b32_e64 v33, 0, 32, s[12:13]
	v_cndmask_b32_e64 v34, 0, 32, s[14:15]
	v_cndmask_b32_e64 v35, 0, 32, s[16:17]
	v_ldexp_f32 v20, v20, v28
	v_ldexp_f32 v21, v21, v29
	v_ldexp_f32 v22, v22, v30
	v_ldexp_f32 v23, v23, v31
	v_ldexp_f32 v24, v24, v32
	v_ldexp_f32 v25, v25, v33
	v_ldexp_f32 v26, v26, v34
	v_ldexp_f32 v27, v27, v35
	v_log_f32_e32 v20, v20
	v_log_f32_e32 v21, v21
	v_log_f32_e32 v22, v22
	v_log_f32_e32 v23, v23
	v_log_f32_e32 v24, v24
	v_log_f32_e32 v25, v25
	v_log_f32_e32 v26, v26
	v_log_f32_e32 v27, v27
	v_mul_f32_e32 v36, 0x3f317217, v20
	v_mul_f32_e32 v37, 0x3f317217, v21
	v_mul_f32_e32 v38, 0x3f317217, v22
	v_mul_f32_e32 v39, 0x3f317217, v23
	v_mul_f32_e32 v40, 0x3f317217, v24
	v_mul_f32_e32 v41, 0x3f317217, v25
	v_mul_f32_e32 v42, 0x3f317217, v26
	v_mul_f32_e32 v43, 0x3f317217, v27
	v_fma_f32 v36, v20, s61, -v36
	v_fma_f32 v37, v21, s61, -v37
	v_fma_f32 v38, v22, s61, -v38
	v_fma_f32 v39, v23, s61, -v39
	v_fma_f32 v40, v24, s61, -v40
	v_fma_f32 v41, v25, s61, -v41
	v_fma_f32 v42, v26, s61, -v42
	v_fma_f32 v43, v27, s61, -v43
	v_fmac_f32_e32 v36, 0x3377d1cf, v20
	v_fmac_f32_e32 v37, 0x3377d1cf, v21
	v_fmac_f32_e32 v38, 0x3377d1cf, v22
	v_fmac_f32_e32 v39, 0x3377d1cf, v23
	v_cndmask_b32_e32 v28, 0, v52, vcc
	v_cndmask_b32_e64 v29, 0, v52, s[4:5]
	v_cndmask_b32_e64 v30, 0, v52, s[6:7]
	v_cndmask_b32_e64 v35, 0, v52, s[16:17]
	v_fmac_f32_e32 v40, 0x3377d1cf, v24
	v_fmac_f32_e32 v41, 0x3377d1cf, v25
	v_fmac_f32_e32 v42, 0x3377d1cf, v26
	v_fmac_f32_e32 v43, 0x3377d1cf, v27
	v_fmac_f32_e32 v36, 0x3f317217, v20
	v_fmac_f32_e32 v37, 0x3f317217, v21
	v_cmp_lt_f32_e64 vcc, |v21|, s62
	v_fmac_f32_e32 v38, 0x3f317217, v22
	v_cmp_lt_f32_e64 s[4:5], |v22|, s62
	v_fmac_f32_e32 v39, 0x3f317217, v23
	v_cmp_lt_f32_e64 s[6:7], |v23|, s62
	v_cmp_lt_f32_e64 s[16:17], |v20|, s62
	v_cndmask_b32_e64 v31, 0, v52, s[8:9]
	v_cndmask_b32_e64 v32, 0, v52, s[10:11]
	v_cndmask_b32_e64 v33, 0, v52, s[12:13]
	v_cndmask_b32_e64 v34, 0, v52, s[14:15]
	v_fmac_f32_e32 v40, 0x3f317217, v24
	v_cmp_lt_f32_e64 s[8:9], |v24|, s62
	v_fmac_f32_e32 v41, 0x3f317217, v25
	v_cmp_lt_f32_e64 s[10:11], |v25|, s62
	v_fmac_f32_e32 v42, 0x3f317217, v26
	v_cmp_lt_f32_e64 s[12:13], |v26|, s62
	v_fmac_f32_e32 v43, 0x3f317217, v27
	v_cmp_lt_f32_e64 s[14:15], |v27|, s62
	v_cndmask_b32_e64 v20, v20, v36, s[16:17]
	v_cndmask_b32_e32 v21, v21, v37, vcc
	v_cndmask_b32_e64 v22, v22, v38, s[4:5]
	v_cndmask_b32_e64 v23, v23, v39, s[6:7]
	v_cndmask_b32_e64 v24, v24, v40, s[8:9]
	v_cndmask_b32_e64 v25, v25, v41, s[10:11]
	v_cndmask_b32_e64 v26, v26, v42, s[12:13]
	v_cndmask_b32_e64 v27, v27, v43, s[14:15]
	v_sub_f32_e32 v20, v20, v28
	v_sub_f32_e32 v21, v21, v29
	v_sub_f32_e32 v22, v22, v30
	v_sub_f32_e32 v23, v23, v31
	v_cmp_lt_f32_e32 vcc, s63, v6
	v_cmp_lt_f32_e64 s[4:5], s63, v7
	v_cmp_lt_f32_e64 s[6:7], s63, v4
	v_cmp_lt_f32_e64 s[16:17], s63, v5
	v_sub_f32_e32 v24, v24, v32
	v_sub_f32_e32 v25, v25, v33
	v_sub_f32_e32 v26, v26, v34
	v_sub_f32_e32 v27, v27, v35
	v_cmp_lt_f32_e64 s[8:9], s63, v2
	v_cmp_lt_f32_e64 s[10:11], s63, v3
	v_cmp_lt_f32_e64 s[12:13], s63, v0
	v_cmp_lt_f32_e64 s[14:15], s63, v1
	v_cndmask_b32_e64 v5, v23, v5, s[16:17]
	v_cndmask_b32_e64 v4, v22, v4, s[6:7]
	v_cndmask_b32_e64 v7, v21, v7, s[4:5]
	v_cndmask_b32_e32 v6, v20, v6, vcc
	v_cndmask_b32_e64 v21, v27, v1, s[14:15]
	v_cndmask_b32_e64 v20, v26, v0, s[12:13]
	v_cndmask_b32_e64 v23, v25, v3, s[10:11]
	v_cndmask_b32_e64 v22, v24, v2, s[8:9]
	v_pk_mul_f32 v[0:1], v[6:7], v[10:11]
	v_pk_mul_f32 v[2:3], v[4:5], v[8:9]
	v_pk_mul_f32 v[4:5], v[22:23], v[14:15]
	v_pk_mul_f32 v[6:7], v[20:21], v[12:13]
	flat_store_dwordx4 v[18:19], v[0:3]
	flat_store_dwordx4 v[18:19], v[4:7] offset:16
	s_cbranch_scc0 .LBB0_2615

.LBB0_2618:
	v_mad_i64_i32 v[0:1], s[4:5], v16, s10, v[18:19]
	s_waitcnt lgkmcnt(0)
	global_load_dwordx4 v[8:11], v22, s[12:13] offset:32
	v_add_co_u32_e32 v0, vcc, 0x1000, v0
	v_ashrrev_i32_e32 v17, 31, v16
	s_nop 0
	v_addc_co_u32_e32 v1, vcc, 0, v1, vcc
	global_load_dwordx4 v[12:15], v[0:1], off offset:64
	global_load_dwordx4 v[24:27], v[0:1], off offset:80
	global_load_dwordx4 v[28:31], v22, s[14:15] offset:32
	s_nop 0
	global_load_dwordx4 v[0:3], v22, s[12:13] offset:48
	global_load_dwordx4 v[4:7], v22, s[14:15] offset:48
	s_add_i32 s3, s3, s79
	s_cmp_lt_i32 s3, 24
	s_waitcnt vmcnt(0)
	v_mul_f32_e32 v8, 0x3fb8aa3b, v8
	v_mul_f32_e32 v9, 0x3fb8aa3b, v9
	v_exp_f32_e32 v34, v8
	v_exp_f32_e32 v35, v9
	s_waitcnt lgkmcnt(0)
	v_lshlrev_b32_e32 v8, 16, v12
	v_and_b32_e32 v9, 0xffff0000, v12
	v_mul_f32_e32 v10, 0x3fb8aa3b, v10
	v_mul_f32_e32 v11, 0x3fb8aa3b, v11
	v_pk_add_f32 v[8:9], v[28:29], v[8:9]
	v_exp_f32_e32 v36, v10
	v_exp_f32_e32 v37, v11
	v_lshlrev_b32_e32 v10, 16, v13
	v_and_b32_e32 v11, 0xffff0000, v13
	v_lshlrev_b32_e32 v12, 16, v24
	v_and_b32_e32 v13, 0xffff0000, v24
	v_mul_f32_e32 v24, 0x3fb8aa3b, v8
	v_lshlrev_b32_e32 v32, 16, v14
	v_and_b32_e32 v33, 0xffff0000, v14
	v_lshlrev_b32_e32 v20, 16, v15
	v_and_b32_e32 v21, 0xffff0000, v15
	v_lshlrev_b32_e32 v14, 16, v25
	v_and_b32_e32 v15, 0xffff0000, v25
	v_pk_add_f32 v[10:11], v[30:31], v[10:11]
	v_mul_f32_e32 v25, 0x3fb8aa3b, v9
	v_exp_f32_e32 v24, v24
	v_lshlrev_b32_e32 v38, 16, v26
	v_and_b32_e32 v39, 0xffff0000, v26
	v_mul_f32_e32 v26, 0x3fb8aa3b, v10
	v_exp_f32_e32 v25, v25
	v_lshlrev_b32_e32 v40, 16, v27
	v_and_b32_e32 v41, 0xffff0000, v27
	v_mul_f32_e32 v27, 0x3fb8aa3b, v11
	v_exp_f32_e32 v26, v26
	v_exp_f32_e32 v27, v27
	v_add_f32_e32 v24, 1.0, v24
	v_add_f32_e32 v25, 1.0, v25
	v_cmp_gt_f32_e32 vcc, s11, v24
	v_add_f32_e32 v26, 1.0, v26
	v_cmp_gt_f32_e64 s[4:5], s11, v25
	v_cndmask_b32_e64 v28, 0, 32, vcc
	v_add_f32_e32 v27, 1.0, v27
	v_cndmask_b32_e64 v29, 0, 32, s[4:5]
	v_cmp_gt_f32_e64 s[6:7], s11, v26
	v_ldexp_f32 v24, v24, v28
	v_cmp_gt_f32_e64 s[8:9], s11, v27
	v_cndmask_b32_e64 v30, 0, 32, s[6:7]
	v_ldexp_f32 v25, v25, v29
	v_log_f32_e32 v24, v24
	v_cndmask_b32_e64 v31, 0, 32, s[8:9]
	v_ldexp_f32 v26, v26, v30
	v_log_f32_e32 v25, v25
	v_ldexp_f32 v27, v27, v31
	v_log_f32_e32 v26, v26
	v_log_f32_e32 v27, v27
	v_mul_f32_e32 v31, 0x3f317217, v24
	v_mul_f32_e32 v42, 0x3f317217, v25
	v_fma_f32 v31, v24, s16, -v31
	v_mul_f32_e32 v14, 0xbfb8aa3b, v14
	v_mul_f32_e32 v43, 0x3f317217, v26
	v_fma_f32 v42, v25, s16, -v42
	v_fmac_f32_e32 v31, 0x3377d1cf, v24
	v_mul_f32_e32 v15, 0xbfb8aa3b, v15
	v_exp_f32_e32 v14, v14
	v_cndmask_b32_e32 v28, 0, v23, vcc
	v_mul_f32_e32 v44, 0x3f317217, v27
	v_fma_f32 v43, v26, s16, -v43
	v_fmac_f32_e32 v42, 0x3377d1cf, v25
	v_fmac_f32_e32 v31, 0x3f317217, v24
	v_cmp_lt_f32_e64 vcc, |v24|, s17
	v_exp_f32_e32 v15, v15
	v_fma_f32 v44, v27, s16, -v44
	v_fmac_f32_e32 v43, 0x3377d1cf, v26
	v_fmac_f32_e32 v42, 0x3f317217, v25
	v_cndmask_b32_e32 v24, v24, v31, vcc
	v_cmp_lt_f32_e64 vcc, |v25|, s17
	v_fmac_f32_e32 v44, 0x3377d1cf, v27
	v_fmac_f32_e32 v43, 0x3f317217, v26
	v_cndmask_b32_e32 v25, v25, v42, vcc
	v_cmp_lt_f32_e64 vcc, |v26|, s17
	v_fmac_f32_e32 v44, 0x3f317217, v27
	v_sub_f32_e32 v24, v24, v28
	v_cndmask_b32_e32 v26, v26, v43, vcc
	v_cmp_lt_f32_e64 vcc, |v27|, s17
	v_cndmask_b32_e64 v28, 0, v23, s[8:9]
	v_pk_add_f32 v[14:15], v[14:15], 1.0 op_sel_hi:[1,0]
	v_cndmask_b32_e32 v27, v27, v44, vcc
	v_cndmask_b32_e64 v29, 0, v23, s[4:5]
	v_sub_f32_e32 v27, v27, v28
	v_div_scale_f32 v28, s[4:5], v15, v15, 1.0
	v_sub_f32_e32 v25, v25, v29
	v_rcp_f32_e32 v29, v28
	v_cmp_lt_f32_e32 vcc, s18, v9
	v_cndmask_b32_e64 v30, 0, v23, s[6:7]
	v_sub_f32_e32 v26, v26, v30
	v_cndmask_b32_e32 v9, v25, v9, vcc
	v_cmp_lt_f32_e32 vcc, s18, v8
	v_xor_b32_e32 v25, 0x80000000, v35
	v_mul_f32_e32 v12, 0xbfb8aa3b, v12
	v_cndmask_b32_e32 v8, v24, v8, vcc
	v_cmp_lt_f32_e32 vcc, s18, v11
	v_xor_b32_e32 v24, 0x80000000, v34
	v_pk_mul_f32 v[8:9], v[8:9], v[24:25]
	v_cndmask_b32_e32 v11, v27, v11, vcc
	v_cmp_lt_f32_e32 vcc, s18, v10
	v_fma_f32 v24, -v28, v29, 1.0
	v_fmac_f32_e32 v29, v24, v29
	v_cndmask_b32_e32 v10, v26, v10, vcc
	v_div_scale_f32 v24, vcc, 1.0, v15, 1.0
	v_xor_b32_e32 v27, 0x80000000, v37
	v_xor_b32_e32 v26, 0x80000000, v36
	v_mul_f32_e32 v25, v24, v29
	v_pk_mul_f32 v[10:11], v[10:11], v[26:27]
	v_fma_f32 v26, -v28, v25, v24
	v_fmac_f32_e32 v25, v26, v29
	v_div_scale_f32 v26, s[4:5], v14, v14, 1.0
	v_rcp_f32_e32 v27, v26
	v_fma_f32 v24, -v28, v25, v24
	v_mul_f32_e32 v13, 0xbfb8aa3b, v13
	v_div_fmas_f32 v24, v24, v29, v25
	v_exp_f32_e32 v12, v12
	v_exp_f32_e32 v13, v13
	v_div_fixup_f32 v15, v24, v15, 1.0
	v_fma_f32 v24, -v26, v27, 1.0
	v_fmac_f32_e32 v27, v24, v27
	v_div_scale_f32 v24, vcc, 1.0, v14, 1.0
	v_mul_f32_e32 v25, v24, v27
	v_fma_f32 v28, -v26, v25, v24
	v_pk_add_f32 v[12:13], v[12:13], 1.0 op_sel_hi:[1,0]
	v_fmac_f32_e32 v25, v28, v27
	v_fma_f32 v24, -v26, v25, v24
	v_div_scale_f32 v26, s[4:5], v13, v13, 1.0
	v_rcp_f32_e32 v28, v26
	v_div_fmas_f32 v24, v24, v27, v25
	v_div_fixup_f32 v14, v24, v14, 1.0
	v_pk_add_f32 v[4:5], v[4:5], v[32:33]
	v_fma_f32 v24, -v26, v28, 1.0
	v_fmac_f32_e32 v28, v24, v28
	v_div_scale_f32 v24, vcc, 1.0, v13, 1.0
	v_mul_f32_e32 v25, v24, v28
	v_fma_f32 v27, -v26, v25, v24
	v_fmac_f32_e32 v25, v27, v28
	v_fma_f32 v24, -v26, v25, v24
	v_div_scale_f32 v26, s[4:5], v12, v12, 1.0
	v_rcp_f32_e32 v27, v26
	v_div_fmas_f32 v24, v24, v28, v25
	v_div_fixup_f32 v13, v24, v13, 1.0
	v_mul_f32_e32 v0, 0x3fb8aa3b, v0
	v_fma_f32 v24, -v26, v27, 1.0
	v_fmac_f32_e32 v27, v24, v27
	v_div_scale_f32 v24, vcc, 1.0, v12, 1.0
	v_mul_f32_e32 v25, v24, v27
	v_fma_f32 v28, -v26, v25, v24
	v_fmac_f32_e32 v25, v28, v27
	v_fma_f32 v24, -v26, v25, v24
	v_div_fmas_f32 v24, v24, v27, v25
	v_div_fixup_f32 v12, v24, v12, 1.0
	v_mul_f32_e32 v24, 0x3fb8aa3b, v4
	v_exp_f32_e32 v24, v24
	v_exp_f32_e32 v26, v0
	v_mul_f32_e32 v0, 0xbfb8aa3b, v38
	v_mul_f32_e32 v3, 0x3fb8aa3b, v3
	v_add_f32_e32 v24, 1.0, v24
	v_cmp_gt_f32_e32 vcc, s11, v24
	v_mul_f32_e32 v2, 0x3fb8aa3b, v2
	s_nop 0
	v_cndmask_b32_e64 v25, 0, 32, vcc
	v_ldexp_f32 v24, v24, v25
	v_log_f32_e32 v25, v24
	v_exp_f32_e32 v24, v0
	v_mul_f32_e32 v0, 0x3fb8aa3b, v1
	v_mul_f32_e32 v1, 0x3fb8aa3b, v5
	v_exp_f32_e32 v1, v1
	v_exp_f32_e32 v27, v0
	v_mul_f32_e32 v0, 0x3f317217, v25
	v_fma_f32 v0, v25, s16, -v0
	v_add_f32_e32 v1, 1.0, v1
	v_cmp_gt_f32_e64 s[4:5], s11, v1
	v_fmac_f32_e32 v0, 0x3377d1cf, v25
	v_fmac_f32_e32 v0, 0x3f317217, v25
	v_cndmask_b32_e64 v28, 0, 32, s[4:5]
	v_ldexp_f32 v1, v1, v28
	v_log_f32_e32 v1, v1
	v_cmp_lt_f32_e64 s[6:7], |v25|, s17
	s_nop 1
	v_cndmask_b32_e64 v0, v25, v0, s[6:7]
	v_cndmask_b32_e32 v25, 0, v23, vcc
	v_sub_f32_e32 v28, v0, v25
	v_mul_f32_e32 v0, 0x3f317217, v1
	v_fma_f32 v0, v1, s16, -v0
	v_fmac_f32_e32 v0, 0x3377d1cf, v1
	v_fmac_f32_e32 v0, 0x3f317217, v1
	v_cmp_lt_f32_e64 vcc, |v1|, s17
	s_nop 1
	v_cndmask_b32_e32 v0, v1, v0, vcc
	v_cndmask_b32_e64 v1, 0, v23, s[4:5]
	v_sub_f32_e32 v29, v0, v1
	v_mul_f32_e32 v0, 0xbfb8aa3b, v39
	v_exp_f32_e32 v25, v0
	v_pk_add_f32 v[0:1], v[6:7], v[20:21]
	v_exp_f32_e32 v21, v3
	v_mul_f32_e32 v6, 0x3fb8aa3b, v0
	v_exp_f32_e32 v6, v6
	v_exp_f32_e32 v20, v2
	v_mul_f32_e32 v2, 0xbfb8aa3b, v40
	v_exp_f32_e32 v2, v2
	v_add_f32_e32 v6, 1.0, v6
	v_cmp_gt_f32_e32 vcc, s11, v6
	v_xor_b32_e32 v21, 0x80000000, v21
	v_xor_b32_e32 v20, 0x80000000, v20
	v_cndmask_b32_e64 v7, 0, 32, vcc
	v_ldexp_f32 v6, v6, v7
	v_mul_f32_e32 v7, 0x3fb8aa3b, v1
	v_exp_f32_e32 v7, v7
	v_log_f32_e32 v6, v6
	v_add_f32_e32 v7, 1.0, v7
	v_cmp_gt_f32_e64 s[4:5], s11, v7
	v_mul_f32_e32 v3, 0x3f317217, v6
	v_fma_f32 v3, v6, s16, -v3
	v_cndmask_b32_e64 v30, 0, 32, s[4:5]
	v_ldexp_f32 v7, v7, v30
	v_log_f32_e32 v7, v7
	v_fmac_f32_e32 v3, 0x3377d1cf, v6
	v_fmac_f32_e32 v3, 0x3f317217, v6
	v_cmp_lt_f32_e64 s[6:7], |v6|, s17
	s_nop 1
	v_cndmask_b32_e64 v3, v6, v3, s[6:7]
	v_cndmask_b32_e32 v6, 0, v23, vcc
	v_sub_f32_e32 v3, v3, v6
	v_mul_f32_e32 v6, 0x3f317217, v7
	v_fma_f32 v6, v7, s16, -v6
	v_fmac_f32_e32 v6, 0x3377d1cf, v7
	v_fmac_f32_e32 v6, 0x3f317217, v7
	v_cmp_lt_f32_e64 vcc, |v7|, s17
	s_nop 1
	v_cndmask_b32_e32 v6, v7, v6, vcc
	v_cmp_lt_f32_e32 vcc, s18, v5
	v_cndmask_b32_e64 v7, 0, v23, s[4:5]
	v_sub_f32_e32 v6, v6, v7
	v_cndmask_b32_e32 v5, v29, v5, vcc
	v_cmp_lt_f32_e32 vcc, s18, v4
	v_xor_b32_e32 v7, 0x80000000, v27
	s_nop 0
	v_cndmask_b32_e32 v4, v28, v4, vcc
	v_cmp_lt_f32_e32 vcc, s18, v1
	s_nop 1
	v_cndmask_b32_e32 v1, v6, v1, vcc
	v_cmp_lt_f32_e32 vcc, s18, v0
	v_xor_b32_e32 v6, 0x80000000, v26
	s_nop 0
	v_cndmask_b32_e32 v0, v3, v0, vcc
	v_mul_f32_e32 v3, 0xbfb8aa3b, v41
	v_exp_f32_e32 v3, v3
	s_nop 0
	v_pk_add_f32 v[26:27], v[2:3], 1.0 op_sel_hi:[1,0]
	s_nop 0
	v_div_scale_f32 v28, s[4:5], v27, v27, 1.0
	v_rcp_f32_e32 v29, v28
	v_pk_mul_f32 v[2:3], v[0:1], v[20:21]
	v_pk_mul_f32 v[0:1], v[4:5], v[6:7]
	v_pk_add_f32 v[4:5], v[24:25], 1.0 op_sel_hi:[1,0]
	v_fma_f32 v6, -v28, v29, 1.0
	v_fmac_f32_e32 v29, v6, v29
	v_div_scale_f32 v6, vcc, 1.0, v27, 1.0
	v_mul_f32_e32 v7, v6, v29
	v_fma_f32 v20, -v28, v7, v6
	v_fmac_f32_e32 v7, v20, v29
	v_div_scale_f32 v20, s[4:5], v26, v26, 1.0
	v_rcp_f32_e32 v21, v20
	v_fma_f32 v6, -v28, v7, v6
	v_div_fmas_f32 v6, v6, v29, v7
	v_div_fixup_f32 v7, v6, v27, 1.0
	v_fma_f32 v6, -v20, v21, 1.0
	v_fmac_f32_e32 v21, v6, v21
	v_div_scale_f32 v6, vcc, 1.0, v26, 1.0
	v_mul_f32_e32 v24, v6, v21
	v_fma_f32 v25, -v20, v24, v6
	v_fmac_f32_e32 v24, v25, v21
	v_fma_f32 v6, -v20, v24, v6
	v_div_scale_f32 v20, s[4:5], v5, v5, 1.0
	v_rcp_f32_e32 v25, v20
	v_div_fmas_f32 v6, v6, v21, v24
	v_div_fixup_f32 v6, v6, v26, 1.0
	v_fma_f32 v21, -v20, v25, 1.0
	v_fmac_f32_e32 v25, v21, v25
	v_div_scale_f32 v21, vcc, 1.0, v5, 1.0
	v_mul_f32_e32 v24, v21, v25
	v_fma_f32 v26, -v20, v24, v21
	v_fmac_f32_e32 v24, v26, v25
	v_fma_f32 v20, -v20, v24, v21
	v_div_scale_f32 v21, s[4:5], v4, v4, 1.0
	v_rcp_f32_e32 v26, v21
	v_div_fmas_f32 v20, v20, v25, v24
	v_div_fixup_f32 v5, v20, v5, 1.0
	v_fma_f32 v20, -v21, v26, 1.0
	v_fmac_f32_e32 v26, v20, v26
	v_div_scale_f32 v20, vcc, 1.0, v4, 1.0
	v_mul_f32_e32 v24, v20, v26
	v_fma_f32 v25, -v21, v24, v20
	v_fmac_f32_e32 v24, v25, v26
	v_fma_f32 v20, -v21, v24, v20
	v_div_fmas_f32 v20, v20, v26, v24
	v_div_fixup_f32 v4, v20, v4, 1.0
	v_lshlrev_b64 v[20:21], 5, v[16:17]
	v_lshl_add_u64 v[24:25], s[72:73], 0, v[20:21]
	flat_store_dwordx4 v[24:25], v[8:11]
	flat_store_dwordx4 v[24:25], v[0:3] offset:16
	v_add_u32_e32 v16, s2, v16
	s_nop 0
	v_lshl_add_u64 v[0:1], s[74:75], 0, v[20:21]
	flat_store_dwordx4 v[0:1], v[12:15]
	flat_store_dwordx4 v[0:1], v[4:7] offset:16
	s_cbranch_scc1 .LBB0_2618

.LBB0_2623:
	s_and_saveexec_b64 s[18:19], s[4:5]
	s_cbranch_execz .LBB0_2622
	s_cmpk_gt_i32 s77, 0x7f
	s_cselect_b32 s6, s23, 0xe0
	s_cselect_b32 s13, s22, 0x100
	s_and_b32 s10, s6, s12
	v_add_u32_e32 v0, s12, v52
	v_mad_i64_i32 v[24:25], s[6:7], v0, s24, v[56:57]
	v_add_u32_e32 v9, s10, v52
	s_add_u32 s8, s90, s76
	v_cmp_lt_i32_e32 vcc, 0, v9
	v_cmp_ge_i32_e64 s[6:7], s13, v9
	s_addc_u32 s9, s91, s80
	v_mov_b32_e32 v0, 0
	s_and_b64 s[10:11], vcc, s[6:7]
	v_mov_b32_e32 v4, 0
	v_mov_b32_e32 v5, 0
	v_mov_b32_e32 v6, 0
	v_mov_b32_e32 v7, 0
	s_and_saveexec_b64 s[6:7], s[10:11]
	s_cbranch_execz .LBB0_2626
	v_add_co_u32_e32 v2, vcc, 0xfffffa00, v24
	s_nop 1
	v_addc_co_u32_e32 v3, vcc, -1, v25, vcc
	global_load_dwordx4 v[4:7], v[2:3], off
.LBB0_2626:
	s_or_b64 exec, exec, s[6:7]
	s_load_dwordx2 s[20:21], s[8:9], 0xc0
	v_cmp_gt_u32_e64 s[6:7], s13, v9
	v_mov_b32_e32 v1, 0
	v_mov_b32_e32 v2, 0
	v_mov_b32_e32 v3, 0
	s_and_saveexec_b64 s[8:9], s[6:7]
	s_cbranch_execz .LBB0_2628
	v_add_co_u32_e32 v0, vcc, 0x1000, v24
	s_nop 1
	v_addc_co_u32_e32 v1, vcc, 0, v25, vcc
	global_load_dwordx4 v[0:3], v[0:1], off offset:96

.LBB0_2630:
	s_or_b64 exec, exec, s[8:9]
	v_or_b32_e32 v8, 3, v9
	v_cmp_lt_i32_e32 vcc, -1, v9
	v_cmp_ge_i32_e64 s[10:11], s13, v8
	v_cmp_gt_i32_e64 s[8:9], 0, v9
	s_and_b64 s[26:27], vcc, s[10:11]
	v_mov_b32_e32 v21, 0
	v_mov_b32_e32 v22, 0
	v_mov_b32_e32 v23, 0
	s_and_saveexec_b64 s[10:11], s[26:27]
	s_cbranch_execz .LBB0_2632
	v_add_co_u32_e32 v10, vcc, 0x3000, v24
	s_nop 1
	v_addc_co_u32_e32 v11, vcc, 0, v25, vcc
	global_load_dwordx4 v[20:23], v[10:11], off offset:3360
.LBB0_2632:
	s_or_b64 exec, exec, s[10:11]
	v_mov_b32_e32 v32, 0
	v_mov_b32_e32 v28, 0
	v_mov_b32_e32 v29, 0
	v_mov_b32_e32 v30, 0
	v_mov_b32_e32 v31, 0
	s_and_saveexec_b64 s[10:11], s[6:7]
	s_cbranch_execz .LBB0_2634
	v_add_co_u32_e32 v10, vcc, 0x5000, v24
	s_nop 1
	v_addc_co_u32_e32 v11, vcc, 0, v25, vcc
	global_load_dwordx4 v[28:31], v[10:11], off offset:896
.LBB0_2634:
	s_or_b64 exec, exec, s[10:11]
	v_or_b32_e32 v8, 5, v9
	v_cmp_ge_i32_e32 vcc, s13, v8
	s_xor_b64 s[6:7], s[8:9], -1
	s_and_b64 s[10:11], s[6:7], vcc
	v_mov_b32_e32 v33, 0
	v_mov_b32_e32 v34, 0
	v_mov_b32_e32 v35, 0
	s_and_saveexec_b64 s[8:9], s[10:11]
	s_cbranch_execz .LBB0_2636
	v_add_co_u32_e32 v10, vcc, 0x6000, v24
	s_nop 1
	v_addc_co_u32_e32 v11, vcc, 0, v25, vcc
	global_load_dwordx4 v[32:35], v[10:11], off offset:2528

.LBB0_2718:
	s_or_b64 exec, exec, s[34:35]
	v_lshrrev_b32_e32 v101, 4, v98
	v_lshl_add_u64 v[70:71], s[8:9], 0, v[74:75]
	v_lshlrev_b32_e32 v100, 2, v101
	s_lshl_b32 s10, s10, 1
	v_or_b32_e32 v90, v151, v100
	v_lshl_add_u64 v[70:71], v[70:71], 0, s[10:11]
	v_lshlrev_b32_e32 v72, 1, v126
	v_lshl_add_u64 v[70:71], v[70:71], 0, v[72:73]
	v_xad_u32 v72, v90, -1, s75
	v_cndmask_b32_e32 v74, v72, v90, vcc
	v_or_b32_e32 v72, 1, v90
	v_xad_u32 v78, v90, -2, s75
	v_ashrrev_i32_e32 v75, 31, v74
	v_cndmask_b32_e32 v78, v78, v72, vcc
	v_lshl_add_u64 v[74:75], v[68:69], 0, v[74:75]
	v_ashrrev_i32_e32 v79, 31, v78
	v_lshlrev_b64 v[74:75], 9, v[74:75]
	v_lshl_add_u64 v[78:79], v[68:69], 0, v[78:79]
	v_lshl_add_u64 v[74:75], v[70:71], 0, v[74:75]
	v_lshlrev_b64 v[78:79], 9, v[78:79]
	v_lshl_add_u64 v[80:81], v[70:71], 0, v[78:79]
	global_load_ushort v86, v[74:75], off
	global_load_ushort v87, v[74:75], off offset:32
	global_load_ushort v94, v[74:75], off offset:64
	global_load_ushort v95, v[74:75], off offset:96
	global_load_ushort v84, v[80:81], off
	global_load_ushort v85, v[80:81], off offset:32
	global_load_ushort v78, v[80:81], off offset:64
	global_load_ushort v79, v[80:81], off offset:96
	v_or_b32_e32 v72, 2, v90
	v_xad_u32 v74, v90, -3, s75
	v_cndmask_b32_e32 v74, v74, v72, vcc
	v_or_b32_e32 v72, 3, v90
	v_xad_u32 v80, v90, -4, s75
	v_ashrrev_i32_e32 v75, 31, v74
	v_cndmask_b32_e32 v80, v80, v72, vcc
	v_lshl_add_u64 v[74:75], v[68:69], 0, v[74:75]
	v_ashrrev_i32_e32 v81, 31, v80
	v_lshlrev_b64 v[74:75], 9, v[74:75]
	v_lshl_add_u64 v[80:81], v[68:69], 0, v[80:81]
	v_lshl_add_u64 v[74:75], v[70:71], 0, v[74:75]
	v_lshlrev_b64 v[80:81], 9, v[80:81]
	v_lshl_add_u64 v[80:81], v[70:71], 0, v[80:81]
	global_load_ushort v106, v[74:75], off
	global_load_ushort v107, v[74:75], off offset:32
	global_load_ushort v108, v[74:75], off offset:64
	global_load_ushort v109, v[74:75], off offset:96
	global_load_ushort v102, v[80:81], off
	global_load_ushort v103, v[80:81], off offset:32
	global_load_ushort v104, v[80:81], off offset:64
	global_load_ushort v105, v[80:81], off offset:96
	v_bitop3_b32 v74, v151, s43, v100 bitop3:0x36
	v_or_b32_e32 v72, 16, v90
	v_add_u32_e32 v74, s75, v74
	v_bitop3_b32 v80, v151, s47, v100 bitop3:0x36
	v_cndmask_b32_e32 v74, v74, v72, vcc
	v_or_b32_e32 v72, 17, v90
	v_add_u32_e32 v80, s75, v80
	v_ashrrev_i32_e32 v75, 31, v74
	v_cndmask_b32_e32 v80, v80, v72, vcc
	v_lshl_add_u64 v[74:75], v[68:69], 0, v[74:75]
	v_ashrrev_i32_e32 v81, 31, v80
	v_lshlrev_b64 v[74:75], 9, v[74:75]
	v_lshl_add_u64 v[80:81], v[68:69], 0, v[80:81]
	v_lshl_add_u64 v[74:75], v[70:71], 0, v[74:75]
	v_lshlrev_b64 v[80:81], 9, v[80:81]
	v_lshl_add_u64 v[80:81], v[70:71], 0, v[80:81]
	global_load_ushort v114, v[74:75], off
	global_load_ushort v115, v[74:75], off offset:32
	global_load_ushort v116, v[74:75], off offset:64
	global_load_ushort v117, v[74:75], off offset:96
	global_load_ushort v110, v[80:81], off
	global_load_ushort v111, v[80:81], off offset:32
	global_load_ushort v112, v[80:81], off offset:64
	global_load_ushort v113, v[80:81], off offset:96
	v_bitop3_b32 v74, v151, s48, v100 bitop3:0x36
	v_or_b32_e32 v72, 18, v90
	v_add_u32_e32 v74, s75, v74
	v_bitop3_b32 v80, v151, s49, v100 bitop3:0x36
	v_cndmask_b32_e32 v74, v74, v72, vcc
	v_or_b32_e32 v72, 19, v90
	v_add_u32_e32 v80, s75, v80
	v_ashrrev_i32_e32 v75, 31, v74
	v_cndmask_b32_e32 v80, v80, v72, vcc
	v_lshl_add_u64 v[74:75], v[68:69], 0, v[74:75]
	v_ashrrev_i32_e32 v81, 31, v80
	v_lshlrev_b64 v[74:75], 9, v[74:75]
	v_lshl_add_u64 v[80:81], v[68:69], 0, v[80:81]
	v_lshl_add_u64 v[74:75], v[70:71], 0, v[74:75]
	v_lshlrev_b64 v[80:81], 9, v[80:81]
	v_lshl_add_u64 v[80:81], v[70:71], 0, v[80:81]
	global_load_ushort v122, v[74:75], off
	global_load_ushort v123, v[74:75], off offset:32
	global_load_ushort v124, v[74:75], off offset:64
	global_load_ushort v125, v[74:75], off offset:96
	global_load_ushort v118, v[80:81], off
	global_load_ushort v119, v[80:81], off offset:32
	global_load_ushort v120, v[80:81], off offset:64
	global_load_ushort v121, v[80:81], off offset:96
	v_bitop3_b32 v74, v151, s44, v100 bitop3:0x36
	v_or_b32_e32 v72, 32, v90
	v_add_u32_e32 v74, s75, v74
	v_bitop3_b32 v80, v151, s50, v100 bitop3:0x36
	v_cndmask_b32_e32 v74, v74, v72, vcc
	v_or_b32_e32 v72, 33, v90
	v_add_u32_e32 v80, s75, v80
	v_ashrrev_i32_e32 v75, 31, v74
	v_cndmask_b32_e32 v80, v80, v72, vcc
	v_lshl_add_u64 v[74:75], v[68:69], 0, v[74:75]
	v_ashrrev_i32_e32 v81, 31, v80
	v_lshlrev_b64 v[74:75], 9, v[74:75]
	v_lshl_add_u64 v[80:81], v[68:69], 0, v[80:81]
	v_lshl_add_u64 v[74:75], v[70:71], 0, v[74:75]
	v_lshlrev_b64 v[80:81], 9, v[80:81]
	v_lshl_add_u64 v[80:81], v[70:71], 0, v[80:81]
	global_load_ushort v132, v[74:75], off
	global_load_ushort v133, v[74:75], off offset:32
	global_load_ushort v134, v[74:75], off offset:64
	global_load_ushort v135, v[74:75], off offset:96
	global_load_ushort v128, v[80:81], off
	global_load_ushort v129, v[80:81], off offset:32
	global_load_ushort v130, v[80:81], off offset:64
	global_load_ushort v131, v[80:81], off offset:96
	v_bitop3_b32 v74, v151, s51, v100 bitop3:0x36
	v_or_b32_e32 v72, 34, v90
	v_add_u32_e32 v74, s75, v74
	v_bitop3_b32 v80, v151, s52, v100 bitop3:0x36
	v_cndmask_b32_e32 v74, v74, v72, vcc
	v_or_b32_e32 v72, 35, v90
	v_add_u32_e32 v80, s75, v80
	v_ashrrev_i32_e32 v75, 31, v74
	v_cndmask_b32_e32 v80, v80, v72, vcc
	v_lshl_add_u64 v[74:75], v[68:69], 0, v[74:75]
	v_ashrrev_i32_e32 v81, 31, v80
	v_lshlrev_b64 v[74:75], 9, v[74:75]
	v_lshl_add_u64 v[80:81], v[68:69], 0, v[80:81]
	v_lshl_add_u64 v[74:75], v[70:71], 0, v[74:75]
	v_lshlrev_b64 v[80:81], 9, v[80:81]
	v_lshl_add_u64 v[88:89], v[70:71], 0, v[80:81]
	global_load_ushort v136, v[74:75], off
	global_load_ushort v137, v[74:75], off offset:32
	global_load_ushort v138, v[74:75], off offset:64
	global_load_ushort v139, v[74:75], off offset:96
	global_load_ushort v82, v[88:89], off
	global_load_ushort v83, v[88:89], off offset:32
	global_load_ushort v80, v[88:89], off offset:64
	global_load_ushort v81, v[88:89], off offset:96
	v_bitop3_b32 v74, v151, s45, v100 bitop3:0x36
	v_or_b32_e32 v72, 48, v90
	v_add_u32_e32 v74, s75, v74
	v_bitop3_b32 v88, v151, s53, v100 bitop3:0x36
	v_cndmask_b32_e32 v74, v74, v72, vcc
	v_or_b32_e32 v72, 49, v90
	v_add_u32_e32 v88, s75, v88
	v_ashrrev_i32_e32 v75, 31, v74
	v_cndmask_b32_e32 v88, v88, v72, vcc
	v_lshl_add_u64 v[74:75], v[68:69], 0, v[74:75]
	v_ashrrev_i32_e32 v89, 31, v88
	v_lshlrev_b64 v[74:75], 9, v[74:75]
	v_lshl_add_u64 v[88:89], v[68:69], 0, v[88:89]
	v_lshl_add_u64 v[74:75], v[70:71], 0, v[74:75]
	v_lshlrev_b64 v[88:89], 9, v[88:89]
	v_lshl_add_u64 v[88:89], v[70:71], 0, v[88:89]
	global_load_ushort v145, v[74:75], off
	global_load_ushort v146, v[74:75], off offset:32
	global_load_ushort v147, v[74:75], off offset:64
	global_load_ushort v148, v[74:75], off offset:96
	global_load_ushort v141, v[88:89], off
	global_load_ushort v142, v[88:89], off offset:32
	global_load_ushort v143, v[88:89], off offset:64
	global_load_ushort v144, v[88:89], off offset:96
	v_bitop3_b32 v74, v151, s54, v100 bitop3:0x36
	v_or_b32_e32 v72, 50, v90
	v_add_u32_e32 v74, s75, v74
	v_bitop3_b32 v88, v151, s55, v100 bitop3:0x36
	v_cndmask_b32_e32 v74, v74, v72, vcc
	v_or_b32_e32 v72, 51, v90
	v_add_u32_e32 v88, s75, v88
	v_cndmask_b32_e32 v88, v88, v72, vcc
	v_ashrrev_i32_e32 v75, 31, v74
	v_ashrrev_i32_e32 v89, 31, v88
	v_lshl_add_u64 v[74:75], v[68:69], 0, v[74:75]
	v_lshl_add_u64 v[88:89], v[68:69], 0, v[88:89]
	v_lshlrev_b64 v[74:75], 9, v[74:75]
	v_lshlrev_b64 v[88:89], 9, v[88:89]
	v_lshl_add_u64 v[74:75], v[70:71], 0, v[74:75]
	v_lshl_add_u64 v[70:71], v[70:71], 0, v[88:89]
	global_load_ushort v149, v[74:75], off
	global_load_ushort v150, v[74:75], off offset:32
	global_load_ushort v93, v[74:75], off offset:64
	global_load_ushort v92, v[74:75], off offset:96
	global_load_ushort v91, v[70:71], off
	global_load_ushort v90, v[70:71], off offset:32
	global_load_ushort v89, v[70:71], off offset:64
	global_load_ushort v88, v[70:71], off offset:96
	v_lshrrev_b32_e32 v70, 1, v99
	v_and_b32_e32 v162, 32, v70
	v_or_b32_e32 v153, v151, v162
	v_lshlrev_b32_e32 v72, 1, v98
	v_lshl_add_u64 v[70:71], s[30:31], 0, v[72:73]
	v_xad_u32 v72, v153, -1, s75
	v_cndmask_b32_e32 v74, v72, v153, vcc
	v_or_b32_e32 v72, 1, v153
	v_xad_u32 v154, v153, -2, s75
	v_cndmask_b32_e32 v154, v154, v72, vcc
	v_or_b32_e32 v72, 2, v153
	v_xad_u32 v156, v153, -3, s75
	v_cndmask_b32_e32 v156, v156, v72, vcc
	v_or_b32_e32 v72, 3, v153
	v_xad_u32 v158, v153, -4, s75
	v_cndmask_b32_e32 v158, v158, v72, vcc
	v_or_b32_e32 v72, 4, v153
	v_xad_u32 v160, v153, -5, s75
	v_cndmask_b32_e32 v160, v160, v72, vcc
	v_or_b32_e32 v72, 5, v153
	v_xad_u32 v163, v153, -6, s75
	v_cndmask_b32_e32 v164, v163, v72, vcc
	v_ashrrev_i32_e32 v165, 31, v164
	v_lshl_add_u64 v[164:165], v[68:69], 0, v[164:165]
	v_lshlrev_b64 v[164:165], 9, v[164:165]
	v_or_b32_e32 v72, 6, v153
	v_xad_u32 v163, v153, -7, s75
	v_lshl_add_u64 v[166:167], v[70:71], 0, v[164:165]
	v_cndmask_b32_e32 v164, v163, v72, vcc
	v_ashrrev_i32_e32 v165, 31, v164
	v_lshl_add_u64 v[164:165], v[68:69], 0, v[164:165]
	v_lshlrev_b64 v[164:165], 9, v[164:165]
	v_or_b32_e32 v72, 7, v153
	v_xad_u32 v163, v153, -8, s75
	v_ashrrev_i32_e32 v75, 31, v74
	v_lshl_add_u64 v[176:177], v[70:71], 0, v[164:165]
	v_cndmask_b32_e32 v164, v163, v72, vcc
	v_lshl_add_u64 v[74:75], v[68:69], 0, v[74:75]
	v_ashrrev_i32_e32 v155, 31, v154
	v_ashrrev_i32_e32 v157, 31, v156
	v_ashrrev_i32_e32 v159, 31, v158
	v_ashrrev_i32_e32 v161, 31, v160
	v_ashrrev_i32_e32 v165, 31, v164
	v_lshlrev_b64 v[74:75], 9, v[74:75]
	v_lshl_add_u64 v[154:155], v[68:69], 0, v[154:155]
	v_lshl_add_u64 v[156:157], v[68:69], 0, v[156:157]
	v_lshl_add_u64 v[158:159], v[68:69], 0, v[158:159]
	v_lshl_add_u64 v[160:161], v[68:69], 0, v[160:161]
	v_lshl_add_u64 v[164:165], v[68:69], 0, v[164:165]
	v_lshl_add_u64 v[74:75], v[70:71], 0, v[74:75]
	v_lshlrev_b64 v[154:155], 9, v[154:155]
	v_lshlrev_b64 v[156:157], 9, v[156:157]
	v_lshlrev_b64 v[158:159], 9, v[158:159]
	v_lshlrev_b64 v[160:161], 9, v[160:161]
	v_lshlrev_b64 v[164:165], 9, v[164:165]
	v_lshl_add_u64 v[154:155], v[70:71], 0, v[154:155]
	v_lshl_add_u64 v[156:157], v[70:71], 0, v[156:157]
	v_lshl_add_u64 v[158:159], v[70:71], 0, v[158:159]
	v_lshl_add_u64 v[160:161], v[70:71], 0, v[160:161]
	v_lshl_add_u64 v[178:179], v[70:71], 0, v[164:165]
	global_load_ushort v173, v[74:75], off
	global_load_ushort v175, v[154:155], off
	global_load_ushort v169, v[156:157], off
	global_load_ushort v170, v[158:159], off
	global_load_ushort v165, v[160:161], off
	s_nop 0
	global_load_ushort v166, v[166:167], off
	s_nop 0
	global_load_ushort v163, v[176:177], off
	global_load_ushort v164, v[178:179], off
	v_or_b32_e32 v72, 8, v153
	v_xad_u32 v74, v153, -9, s75
	v_cndmask_b32_e32 v74, v74, v72, vcc
	v_or_b32_e32 v72, 9, v153
	v_xad_u32 v154, v153, -10, s75
	v_cndmask_b32_e32 v154, v154, v72, vcc
	v_or_b32_e32 v72, 10, v153
	v_xad_u32 v156, v153, -11, s75
	v_cndmask_b32_e32 v156, v156, v72, vcc
	v_or_b32_e32 v72, 11, v153
	v_xad_u32 v158, v153, -12, s75
	v_cndmask_b32_e32 v158, v158, v72, vcc
	v_or_b32_e32 v72, 12, v153
	v_xad_u32 v160, v153, -13, s75
	v_cndmask_b32_e32 v160, v160, v72, vcc
	v_or_b32_e32 v72, 13, v153
	v_xad_u32 v167, v153, -14, s75
	v_cndmask_b32_e32 v176, v167, v72, vcc
	v_ashrrev_i32_e32 v177, 31, v176
	v_lshl_add_u64 v[176:177], v[68:69], 0, v[176:177]
	v_lshlrev_b64 v[176:177], 9, v[176:177]
	v_or_b32_e32 v72, 14, v153
	v_xad_u32 v167, v153, -15, s75
	v_lshl_add_u64 v[178:179], v[70:71], 0, v[176:177]
	v_cndmask_b32_e32 v176, v167, v72, vcc
	v_ashrrev_i32_e32 v177, 31, v176
	v_lshl_add_u64 v[176:177], v[68:69], 0, v[176:177]
	v_lshlrev_b64 v[176:177], 9, v[176:177]
	v_or_b32_e32 v72, 15, v153
	v_xad_u32 v167, v153, -16, s75
	v_ashrrev_i32_e32 v75, 31, v74
	v_lshl_add_u64 v[182:183], v[70:71], 0, v[176:177]
	v_cndmask_b32_e32 v176, v167, v72, vcc
	v_lshl_add_u64 v[74:75], v[68:69], 0, v[74:75]
	v_ashrrev_i32_e32 v155, 31, v154
	v_ashrrev_i32_e32 v157, 31, v156
	v_ashrrev_i32_e32 v159, 31, v158
	v_ashrrev_i32_e32 v161, 31, v160
	v_ashrrev_i32_e32 v177, 31, v176
	v_lshlrev_b64 v[74:75], 9, v[74:75]
	v_lshl_add_u64 v[154:155], v[68:69], 0, v[154:155]
	v_lshl_add_u64 v[156:157], v[68:69], 0, v[156:157]
	v_lshl_add_u64 v[158:159], v[68:69], 0, v[158:159]
	v_lshl_add_u64 v[160:161], v[68:69], 0, v[160:161]
	v_lshl_add_u64 v[176:177], v[68:69], 0, v[176:177]
	v_lshl_add_u64 v[74:75], v[70:71], 0, v[74:75]
	v_lshlrev_b64 v[154:155], 9, v[154:155]
	v_lshlrev_b64 v[156:157], 9, v[156:157]
	v_lshlrev_b64 v[158:159], 9, v[158:159]
	v_lshlrev_b64 v[160:161], 9, v[160:161]
	v_lshlrev_b64 v[176:177], 9, v[176:177]
	v_lshl_add_u64 v[154:155], v[70:71], 0, v[154:155]
	v_lshl_add_u64 v[156:157], v[70:71], 0, v[156:157]
	v_lshl_add_u64 v[158:159], v[70:71], 0, v[158:159]
	v_lshl_add_u64 v[160:161], v[70:71], 0, v[160:161]
	v_lshl_add_u64 v[184:185], v[70:71], 0, v[176:177]
	global_load_ushort v180, v[74:75], off
	global_load_ushort v181, v[154:155], off
	global_load_ushort v176, v[156:157], off
	global_load_ushort v177, v[158:159], off
	global_load_ushort v171, v[160:161], off
	global_load_ushort v172, v[178:179], off
	global_load_ushort v167, v[182:183], off
	global_load_ushort v168, v[184:185], off
	v_bitop3_b32 v74, v151, s43, v162 bitop3:0x36
	v_or_b32_e32 v72, 16, v153
	v_add_u32_e32 v74, s75, v74
	v_bitop3_b32 v154, v151, s47, v162 bitop3:0x36
	v_cndmask_b32_e32 v74, v74, v72, vcc
	v_or_b32_e32 v72, 17, v153
	v_add_u32_e32 v154, s75, v154
	v_bitop3_b32 v156, v151, s48, v162 bitop3:0x36
	v_cndmask_b32_e32 v154, v154, v72, vcc
	v_or_b32_e32 v72, 18, v153
	v_add_u32_e32 v156, s75, v156
	v_bitop3_b32 v158, v151, s49, v162 bitop3:0x36
	v_cndmask_b32_e32 v156, v156, v72, vcc
	v_or_b32_e32 v72, 19, v153
	v_add_u32_e32 v158, s75, v158
	v_bitop3_b32 v160, v151, s56, v162 bitop3:0x36
	v_cndmask_b32_e32 v158, v158, v72, vcc
	v_or_b32_e32 v72, 20, v153
	v_add_u32_e32 v160, s75, v160
	v_bitop3_b32 v178, v151, s57, v162 bitop3:0x36
	v_cndmask_b32_e32 v160, v160, v72, vcc
	v_or_b32_e32 v72, 21, v153
	v_add_u32_e32 v178, s75, v178
	v_bitop3_b32 v182, v151, s58, v162 bitop3:0x36
	v_cndmask_b32_e32 v178, v178, v72, vcc
	v_or_b32_e32 v72, 22, v153
	v_add_u32_e32 v182, s75, v182
	v_cndmask_b32_e32 v182, v182, v72, vcc
	v_ashrrev_i32_e32 v183, 31, v182
	v_lshl_add_u64 v[182:183], v[68:69], 0, v[182:183]
	v_lshlrev_b64 v[182:183], 9, v[182:183]
	v_lshl_add_u64 v[192:193], v[70:71], 0, v[182:183]
	v_bitop3_b32 v182, v151, s59, v162 bitop3:0x36
	v_or_b32_e32 v72, 23, v153
	v_add_u32_e32 v182, s75, v182
	v_ashrrev_i32_e32 v75, 31, v74
	v_ashrrev_i32_e32 v179, 31, v178
	v_cndmask_b32_e32 v182, v182, v72, vcc
	v_lshl_add_u64 v[74:75], v[68:69], 0, v[74:75]
	v_ashrrev_i32_e32 v155, 31, v154
	v_ashrrev_i32_e32 v157, 31, v156
	v_ashrrev_i32_e32 v159, 31, v158
	v_ashrrev_i32_e32 v161, 31, v160
	v_lshl_add_u64 v[178:179], v[68:69], 0, v[178:179]
	v_ashrrev_i32_e32 v183, 31, v182
	v_lshlrev_b64 v[74:75], 9, v[74:75]
	v_lshl_add_u64 v[154:155], v[68:69], 0, v[154:155]
	v_lshl_add_u64 v[156:157], v[68:69], 0, v[156:157]
	v_lshl_add_u64 v[158:159], v[68:69], 0, v[158:159]
	v_lshl_add_u64 v[160:161], v[68:69], 0, v[160:161]
	v_lshlrev_b64 v[178:179], 9, v[178:179]
	v_lshl_add_u64 v[182:183], v[68:69], 0, v[182:183]
	v_lshl_add_u64 v[74:75], v[70:71], 0, v[74:75]
	v_lshlrev_b64 v[154:155], 9, v[154:155]
	v_lshlrev_b64 v[156:157], 9, v[156:157]
	v_lshlrev_b64 v[158:159], 9, v[158:159]
	v_lshlrev_b64 v[160:161], 9, v[160:161]
	v_lshl_add_u64 v[178:179], v[70:71], 0, v[178:179]
	v_lshlrev_b64 v[182:183], 9, v[182:183]
	v_lshl_add_u64 v[154:155], v[70:71], 0, v[154:155]
	v_lshl_add_u64 v[156:157], v[70:71], 0, v[156:157]
	v_lshl_add_u64 v[158:159], v[70:71], 0, v[158:159]
	v_lshl_add_u64 v[160:161], v[70:71], 0, v[160:161]
	v_lshl_add_u64 v[194:195], v[70:71], 0, v[182:183]
	global_load_ushort v188, v[74:75], off
	global_load_ushort v190, v[154:155], off
	global_load_ushort v184, v[156:157], off
	global_load_ushort v186, v[158:159], off
	global_load_ushort v182, v[160:161], off
	global_load_ushort v183, v[178:179], off
	s_nop 0
	global_load_ushort v178, v[192:193], off
	global_load_ushort v179, v[194:195], off
	v_bitop3_b32 v74, v151, s60, v162 bitop3:0x36
	v_or_b32_e32 v72, 24, v153
	v_add_u32_e32 v74, s75, v74
	v_bitop3_b32 v154, v151, s61, v162 bitop3:0x36
	v_cndmask_b32_e32 v74, v74, v72, vcc
	v_or_b32_e32 v72, 25, v153
	v_add_u32_e32 v154, s75, v154
	v_bitop3_b32 v156, v151, s62, v162 bitop3:0x36
	v_cndmask_b32_e32 v154, v154, v72, vcc
	v_or_b32_e32 v72, 26, v153
	v_add_u32_e32 v156, s75, v156
	v_bitop3_b32 v158, v151, s63, v162 bitop3:0x36
	v_cndmask_b32_e32 v156, v156, v72, vcc
	v_or_b32_e32 v72, 27, v153
	v_add_u32_e32 v158, s75, v158
	v_bitop3_b32 v160, v151, s64, v162 bitop3:0x36
	v_cndmask_b32_e32 v158, v158, v72, vcc
	v_or_b32_e32 v72, 28, v153
	v_add_u32_e32 v160, s75, v160
	v_bitop3_b32 v185, v151, s65, v162 bitop3:0x36
	v_cndmask_b32_e32 v160, v160, v72, vcc
	v_or_b32_e32 v72, 29, v153
	v_add_u32_e32 v185, s75, v185
	v_cndmask_b32_e32 v192, v185, v72, vcc
	v_ashrrev_i32_e32 v193, 31, v192
	v_lshl_add_u64 v[192:193], v[68:69], 0, v[192:193]
	v_bitop3_b32 v185, v151, s66, v162 bitop3:0x36
	v_lshlrev_b64 v[192:193], 9, v[192:193]
	v_or_b32_e32 v72, 30, v153
	v_add_u32_e32 v185, s75, v185
	v_lshl_add_u64 v[198:199], v[70:71], 0, v[192:193]
	v_cndmask_b32_e32 v192, v185, v72, vcc
	v_ashrrev_i32_e32 v193, 31, v192
	v_lshl_add_u64 v[192:193], v[68:69], 0, v[192:193]
	v_bitop3_b32 v151, v151, s67, v162 bitop3:0x36
	v_lshlrev_b64 v[192:193], 9, v[192:193]
	v_or_b32_e32 v72, 31, v153
	v_add_u32_e32 v151, s75, v151
	v_ashrrev_i32_e32 v75, 31, v74
	v_lshl_add_u64 v[206:207], v[70:71], 0, v[192:193]
	v_cndmask_b32_e32 v192, v151, v72, vcc
	v_lshl_add_u64 v[74:75], v[68:69], 0, v[74:75]
	v_ashrrev_i32_e32 v155, 31, v154
	v_ashrrev_i32_e32 v157, 31, v156
	v_ashrrev_i32_e32 v159, 31, v158
	v_ashrrev_i32_e32 v161, 31, v160
	v_ashrrev_i32_e32 v193, 31, v192
	v_lshlrev_b64 v[74:75], 9, v[74:75]
	v_lshl_add_u64 v[154:155], v[68:69], 0, v[154:155]
	v_lshl_add_u64 v[156:157], v[68:69], 0, v[156:157]
	v_lshl_add_u64 v[158:159], v[68:69], 0, v[158:159]
	v_lshl_add_u64 v[160:161], v[68:69], 0, v[160:161]
	v_lshl_add_u64 v[68:69], v[68:69], 0, v[192:193]
	v_lshl_add_u64 v[74:75], v[70:71], 0, v[74:75]
	v_lshlrev_b64 v[154:155], 9, v[154:155]
	v_lshlrev_b64 v[156:157], 9, v[156:157]
	v_lshlrev_b64 v[158:159], 9, v[158:159]
	v_lshlrev_b64 v[160:161], 9, v[160:161]
	v_lshlrev_b64 v[68:69], 9, v[68:69]
	v_lshl_add_u64 v[154:155], v[70:71], 0, v[154:155]
	v_lshl_add_u64 v[156:157], v[70:71], 0, v[156:157]
	v_lshl_add_u64 v[158:159], v[70:71], 0, v[158:159]
	v_lshl_add_u64 v[160:161], v[70:71], 0, v[160:161]
	v_lshl_add_u64 v[68:69], v[70:71], 0, v[68:69]
	global_load_ushort v195, v[74:75], off
	global_load_ushort v196, v[154:155], off
	global_load_ushort v193, v[156:157], off
	global_load_ushort v194, v[158:159], off
	global_load_ushort v189, v[160:161], off
	global_load_ushort v191, v[198:199], off
	global_load_ushort v185, v[206:207], off
	global_load_ushort v187, v[68:69], off
	v_mul_lo_u32 v151, v140, s46
	s_waitcnt lgkmcnt(0)
	s_barrier
	s_and_saveexec_b64 s[30:31], s[6:7]
	s_cbranch_execz .LBB0_2720
	v_and_b32_e32 v68, 64, v97
	v_add_u32_e32 v69, -1, v97
	v_cmp_lt_i32_e32 vcc, v69, v68
	v_add_u32_e32 v70, -2, v97
	s_nop 0
	v_cndmask_b32_e32 v69, v69, v97, vcc
	v_lshlrev_b32_e32 v69, 2, v69
	ds_bpermute_b32 v69, v69, v152
	v_cmp_eq_u32_e32 vcc, 0, v98
	s_waitcnt lgkmcnt(0)
	v_add_f32_e32 v69, v152, v69
	v_cndmask_b32_e32 v69, v69, v152, vcc
	v_cmp_lt_i32_e32 vcc, v70, v68
	s_nop 1
	v_cndmask_b32_e32 v70, v70, v97, vcc
	v_lshlrev_b32_e32 v70, 2, v70
	ds_bpermute_b32 v70, v70, v69
	v_cmp_gt_u32_e32 vcc, 2, v98
	s_waitcnt lgkmcnt(0)
	v_add_f32_e32 v70, v69, v70
	v_cndmask_b32_e32 v69, v70, v69, vcc
	v_add_u32_e32 v70, -4, v97
	v_cmp_lt_i32_e32 vcc, v70, v68
	s_nop 1
	v_cndmask_b32_e32 v70, v70, v97, vcc
	v_lshlrev_b32_e32 v70, 2, v70
	ds_bpermute_b32 v70, v70, v69
	v_cmp_gt_u32_e32 vcc, 4, v98
	s_waitcnt lgkmcnt(0)
	v_add_f32_e32 v70, v69, v70
	v_cndmask_b32_e32 v69, v70, v69, vcc
	v_add_u32_e32 v70, -8, v97
	v_cmp_lt_i32_e32 vcc, v70, v68
	s_nop 1
	v_cndmask_b32_e32 v70, v70, v97, vcc
	v_lshlrev_b32_e32 v70, 2, v70
	ds_bpermute_b32 v70, v70, v69
	v_cmp_gt_u32_e32 vcc, 8, v98
	s_waitcnt lgkmcnt(0)
	v_add_f32_e32 v70, v69, v70
	v_cndmask_b32_e32 v69, v70, v69, vcc
	v_add_u32_e32 v70, -16, v97
	v_cmp_lt_i32_e32 vcc, v70, v68
	s_nop 1
	v_cndmask_b32_e32 v70, v70, v97, vcc
	v_lshlrev_b32_e32 v70, 2, v70
	ds_bpermute_b32 v70, v70, v69
	v_cmp_gt_u32_e32 vcc, 16, v98
	s_waitcnt lgkmcnt(0)
	v_add_f32_e32 v70, v69, v70
	v_cndmask_b32_e32 v69, v70, v69, vcc
	v_subrev_u32_e32 v70, 32, v97
	v_cmp_lt_i32_e32 vcc, v70, v68
	s_nop 1
	v_cndmask_b32_e32 v68, v70, v97, vcc
	v_lshlrev_b32_e32 v68, 2, v68
	ds_bpermute_b32 v68, v68, v69
	v_cmp_gt_u32_e32 vcc, 32, v98
	s_waitcnt lgkmcnt(0)
	v_add_f32_e32 v68, v69, v68
	v_cndmask_b32_e32 v68, v68, v69, vcc
	v_lshl_add_u32 v69, v98, 2, v151
	ds_write2st64_b32 v69, v68, v127 offset0:68 offset1:69

.LBB0_2888:
	s_and_b64 s[10:11], s[10:11], exec
	v_ashrrev_i32_e32 v29, 3, v3
	s_cselect_b32 s10, s18, 0x30c0000
	v_add_u32_e32 v4, s24, v29
	s_add_u32 s10, s8, s10
	v_ashrrev_i32_e32 v5, 31, v4
	s_addc_u32 s11, s9, 0
	v_lshlrev_b64 v[4:5], 8, v[4:5]
	v_lshlrev_b32_e32 v0, 4, v3
	v_lshl_add_u64 v[4:5], s[10:11], 0, v[4:5]
	v_and_b32_e32 v0, 0x70, v0
	v_lshl_add_u64 v[106:107], v[4:5], 0, v[0:1]
	v_add_co_u32_e32 v110, vcc, s19, v106
	v_add_u32_e32 v4, s25, v29
	s_nop 0
	v_addc_co_u32_e32 v111, vcc, 0, v107, vcc
	v_ashrrev_i32_e32 v5, 31, v4
	v_add_co_u32_e32 v112, vcc, s20, v106
	v_lshlrev_b64 v[4:5], 8, v[4:5]
	s_nop 0
	v_addc_co_u32_e32 v113, vcc, 0, v107, vcc
	v_lshl_add_u64 v[4:5], s[4:5], 0, v[4:5]
	v_add_co_u32_e32 v114, vcc, s21, v106
	v_lshl_add_u64 v[108:109], v[4:5], 0, v[0:1]
	s_nop 0
	v_addc_co_u32_e32 v115, vcc, 0, v107, vcc
	v_add_co_u32_e32 v116, vcc, s19, v108
	global_load_dwordx4 v[4:7], v[110:111], off
	global_load_dwordx4 v[8:11], v[112:113], off
	global_load_dwordx4 v[12:15], v[106:107], off
	global_load_dwordx4 v[16:19], v[108:109], off
	v_addc_co_u32_e32 v117, vcc, 0, v109, vcc
	global_load_dwordx4 v[20:23], v[114:115], off
	global_load_dwordx4 v[24:27], v[116:117], off
	v_bfe_u32 v122, v3, 4, 2
	v_ashrrev_i32_e32 v28, 1, v3
	v_and_b32_e32 v30, 0x4f, v3
	v_and_b32_e32 v123, 0xffffffc0, v28
	v_lshlrev_b32_e32 v28, 4, v122
	v_mad_u64_u32 v[118:119], s[10:11], v29, s22, v[0:1]
	v_mad_u32_u24 v0, v30, s22, v28
	s_waitcnt lgkmcnt(0)
	s_barrier
	v_and_b32_e32 v97, 15, v3
	s_add_u32 s6, s8, s6
	s_addc_u32 s7, s9, s7
	s_add_i32 s15, s15, s14
	s_add_i32 s2, s2, s3
	s_add_i32 s16, s16, s17
	s_cmpk_lt_u32 s15, 0xe0
	s_waitcnt vmcnt(0)
	ds_write_b128 v118, v[12:15]
	ds_write_b128 v118, v[16:19] offset:36864
	ds_write_b128 v118, v[4:7] offset:9216
	ds_write_b128 v118, v[8:11] offset:18432
	ds_write_b128 v118, v[20:23] offset:27648
	ds_write_b128 v118, v[24:27] offset:46080
	s_waitcnt lgkmcnt(0)
	s_barrier
	ds_read_b128 v[4:7], v0 offset:36864
	v_or_b32_e32 v8, v123, v97
	v_mad_u64_u32 v[120:121], s[10:11], v8, s22, v[28:29]
	ds_read_b128 v[8:11], v120
	ds_read_b128 v[12:15], v120 offset:64
	ds_read_b128 v[16:19], v0 offset:36928
	ds_read_b128 v[24:27], v0 offset:39168
	ds_read_b128 v[28:31], v0 offset:39232
	ds_read_b128 v[36:39], v0 offset:41472
	ds_read_b128 v[40:43], v0 offset:41536
	ds_read_b128 v[48:51], v0 offset:43776
	ds_read_b128 v[52:55], v0 offset:43840
	ds_read_b128 v[56:59], v120 offset:2304
	ds_read_b128 v[60:63], v120 offset:2368
	ds_read_b128 v[76:79], v120 offset:4608
	ds_read_b128 v[80:83], v120 offset:4672
	s_waitcnt lgkmcnt(12)
	v_mfma_f32_16x16x32_bf16 v[20:23], v[4:7], v[8:11], 0
	ds_read_b128 v[98:101], v120 offset:6912
	ds_read_b128 v[102:105], v120 offset:6976
	s_waitcnt lgkmcnt(11)
	v_mfma_f32_16x16x32_bf16 v[32:35], v[24:27], v[8:11], 0
	s_waitcnt lgkmcnt(9)
	v_mfma_f32_16x16x32_bf16 v[44:47], v[36:39], v[8:11], 0
	s_waitcnt lgkmcnt(7)
	v_mfma_f32_16x16x32_bf16 v[8:11], v[48:51], v[8:11], 0
	s_waitcnt lgkmcnt(5)
	v_mfma_f32_16x16x32_bf16 v[64:67], v[4:7], v[56:59], 0
	v_mfma_f32_16x16x32_bf16 v[68:71], v[24:27], v[56:59], 0
	v_mfma_f32_16x16x32_bf16 v[72:75], v[36:39], v[56:59], 0
	v_mfma_f32_16x16x32_bf16 v[56:59], v[48:51], v[56:59], 0
	s_waitcnt lgkmcnt(3)
	v_mfma_f32_16x16x32_bf16 v[84:87], v[4:7], v[76:79], 0
	v_mfma_f32_16x16x32_bf16 v[88:91], v[24:27], v[76:79], 0
	v_mfma_f32_16x16x32_bf16 v[92:95], v[36:39], v[76:79], 0
	v_mfma_f32_16x16x32_bf16 v[76:79], v[48:51], v[76:79], 0
	s_waitcnt lgkmcnt(1)
	v_mfma_f32_16x16x32_bf16 v[4:7], v[4:7], v[98:101], 0
	v_mfma_f32_16x16x32_bf16 v[24:27], v[24:27], v[98:101], 0
	v_mfma_f32_16x16x32_bf16 v[36:39], v[36:39], v[98:101], 0
	v_mfma_f32_16x16x32_bf16 v[48:51], v[48:51], v[98:101], 0
	v_mfma_f32_16x16x32_bf16 v[20:23], v[16:19], v[12:15], v[20:23]
	v_mfma_f32_16x16x32_bf16 v[32:35], v[28:31], v[12:15], v[32:35]
	v_mfma_f32_16x16x32_bf16 v[44:47], v[40:43], v[12:15], v[44:47]
	v_mfma_f32_16x16x32_bf16 v[8:11], v[52:55], v[12:15], v[8:11]
	v_mfma_f32_16x16x32_bf16 v[12:15], v[16:19], v[60:63], v[64:67]
	v_mfma_f32_16x16x32_bf16 v[64:67], v[28:31], v[60:63], v[68:71]
	v_mfma_f32_16x16x32_bf16 v[68:71], v[40:43], v[60:63], v[72:75]
	v_mfma_f32_16x16x32_bf16 v[56:59], v[52:55], v[60:63], v[56:59]
	v_mfma_f32_16x16x32_bf16 v[60:63], v[16:19], v[80:83], v[84:87]
	v_mfma_f32_16x16x32_bf16 v[72:75], v[28:31], v[80:83], v[88:91]
	v_mfma_f32_16x16x32_bf16 v[84:87], v[40:43], v[80:83], v[92:95]
	s_nop 1
	global_load_dwordx4 v[88:91], v[108:109], off offset:128
	global_load_dwordx4 v[92:95], v[106:107], off offset:128
	v_mfma_f32_16x16x32_bf16 v[76:79], v[52:55], v[80:83], v[76:79]
	global_load_dwordx4 v[80:83], v[110:111], off offset:128
	global_load_dwordx4 v[98:101], v[112:113], off offset:128
	global_load_dwordx4 v[106:109], v[114:115], off offset:128
	s_waitcnt lgkmcnt(0)
	v_mfma_f32_16x16x32_bf16 v[4:7], v[16:19], v[102:105], v[4:7]
	global_load_dwordx4 v[16:19], v[116:117], off offset:128
	s_waitcnt lgkmcnt(0)
	s_barrier
	s_waitcnt vmcnt(0)
	ds_write_b128 v118, v[92:95]
	ds_write_b128 v118, v[80:83] offset:9216
	ds_write_b128 v118, v[98:101] offset:18432
	ds_write_b128 v118, v[106:109] offset:27648
	ds_write_b128 v118, v[88:91] offset:36864
	ds_write_b128 v118, v[16:19] offset:46080
	s_waitcnt lgkmcnt(0)
	s_barrier
	ds_read_b128 v[16:19], v0 offset:36864
	v_mfma_f32_16x16x32_bf16 v[24:27], v[28:31], v[102:105], v[24:27]
	v_mfma_f32_16x16x32_bf16 v[28:31], v[40:43], v[102:105], v[36:39]
	v_mfma_f32_16x16x32_bf16 v[36:39], v[52:55], v[102:105], v[48:51]
	ds_read_b128 v[40:43], v120
	s_nop 1
	ds_read_b128 v[48:51], v120 offset:64
	ds_read_b128 v[52:55], v0 offset:36928
	ds_read_b128 v[80:83], v0 offset:39168
	ds_read_b128 v[88:91], v0 offset:39232
	ds_read_b128 v[92:95], v0 offset:41472
	ds_read_b128 v[98:101], v0 offset:41536
	ds_read_b128 v[102:105], v0 offset:43776
	ds_read_b128 v[106:109], v0 offset:43840
	s_waitcnt lgkmcnt(8)
	v_mfma_f32_16x16x32_bf16 v[20:23], v[16:19], v[40:43], v[20:23]
	v_and_b32_e32 v0, 64, v3
	v_or_b32_e32 v3, s24, v97
	v_lshlrev_b32_e32 v97, 2, v122
	s_waitcnt lgkmcnt(5)
	v_mfma_f32_16x16x32_bf16 v[32:35], v[80:83], v[40:43], v[32:35]
	v_add_u32_e32 v122, v3, v123
	v_ashrrev_i32_e32 v123, 31, v122
	v_lshlrev_b64 v[118:119], 10, v[122:123]
	s_waitcnt lgkmcnt(3)
	v_mfma_f32_16x16x32_bf16 v[44:47], v[92:95], v[40:43], v[44:47]
	v_or3_b32 v0, v97, v0, s25
	v_lshlrev_b64 v[124:125], 1, v[0:1]
	s_waitcnt lgkmcnt(1)
	v_mfma_f32_16x16x32_bf16 v[8:11], v[102:105], v[40:43], v[8:11]
	ds_read_b128 v[40:43], v120 offset:2304
	ds_read_b128 v[110:113], v120 offset:2368
	s_waitcnt lgkmcnt(1)
	v_mfma_f32_16x16x32_bf16 v[12:15], v[16:19], v[40:43], v[12:15]
	v_mfma_f32_16x16x32_bf16 v[64:67], v[80:83], v[40:43], v[64:67]
	v_mfma_f32_16x16x32_bf16 v[68:71], v[92:95], v[40:43], v[68:71]
	v_mfma_f32_16x16x32_bf16 v[40:43], v[102:105], v[40:43], v[56:59]
	s_nop 2
	ds_read_b128 v[56:59], v120 offset:4608
	ds_read_b128 v[114:117], v120 offset:4672
	v_mfma_f32_16x16x32_bf16 v[20:23], v[52:55], v[48:51], v[20:23]
	s_waitcnt lgkmcnt(1)
	v_mfma_f32_16x16x32_bf16 v[60:63], v[16:19], v[56:59], v[60:63]
	v_mfma_f32_16x16x32_bf16 v[72:75], v[80:83], v[56:59], v[72:75]
	s_nop 4
	v_and_b32_sdwa v3, v20, v2 dst_sel:DWORD dst_unused:UNUSED_PAD src0_sel:WORD_1 src1_sel:DWORD
	v_and_b32_sdwa v97, v23, v2 dst_sel:DWORD dst_unused:UNUSED_PAD src0_sel:WORD_1 src1_sel:DWORD
	v_and_b32_sdwa v123, v21, v2 dst_sel:DWORD dst_unused:UNUSED_PAD src0_sel:WORD_1 src1_sel:DWORD
	v_mfma_f32_16x16x32_bf16 v[84:87], v[92:95], v[56:59], v[84:87]
	v_and_b32_sdwa v0, v22, v2 dst_sel:DWORD dst_unused:UNUSED_PAD src0_sel:WORD_1 src1_sel:DWORD
	v_add3_u32 v3, v20, v3, s23
	v_add3_u32 v20, v23, v97, s23
	v_mfma_f32_16x16x32_bf16 v[56:59], v[102:105], v[56:59], v[76:79]
	v_add3_u32 v21, v21, v123, s23
	v_add3_u32 v0, v22, v0, s23
	v_and_b32_e32 v20, 0xffff0000, v20
	v_lshl_add_u64 v[76:77], s[6:7], 0, v[118:119]
	v_lshl_add_u64 v[126:127], v[76:77], 0, v[124:125]
	ds_read_b128 v[76:79], v120 offset:6912
	ds_read_b128 v[118:121], v120 offset:6976
	v_mfma_f32_16x16x32_bf16 v[32:35], v[88:91], v[48:51], v[32:35]
	v_and_b32_e32 v21, 0xffff0000, v21
	s_waitcnt lgkmcnt(1)
	v_mfma_f32_16x16x32_bf16 v[4:7], v[16:19], v[76:79], v[4:7]
	v_or_b32_sdwa v17, v20, v0 dst_sel:DWORD dst_unused:UNUSED_PAD src0_sel:DWORD src1_sel:WORD_1
	v_or_b32_sdwa v16, v21, v3 dst_sel:DWORD dst_unused:UNUSED_PAD src0_sel:DWORD src1_sel:WORD_1
	flat_store_dwordx2 v[126:127], v[16:17]
	v_mfma_f32_16x16x32_bf16 v[16:19], v[80:83], v[76:79], v[24:27]
	s_nop 0
	v_and_b32_sdwa v0, v35, v2 dst_sel:DWORD dst_unused:UNUSED_PAD src0_sel:WORD_1 src1_sel:DWORD
	v_and_b32_sdwa v3, v33, v2 dst_sel:DWORD dst_unused:UNUSED_PAD src0_sel:WORD_1 src1_sel:DWORD
	v_and_b32_sdwa v128, v34, v2 dst_sel:DWORD dst_unused:UNUSED_PAD src0_sel:WORD_1 src1_sel:DWORD
	v_mfma_f32_16x16x32_bf16 v[24:27], v[98:101], v[48:51], v[44:47]
	v_and_b32_sdwa v129, v32, v2 dst_sel:DWORD dst_unused:UNUSED_PAD src0_sel:WORD_1 src1_sel:DWORD
	v_add3_u32 v0, v35, v0, s23
	v_add3_u32 v3, v33, v3, s23
	v_add3_u32 v32, v32, v129, s23
	v_add3_u32 v34, v34, v128, s23
	v_and_b32_e32 v0, 0xffff0000, v0
	v_and_b32_e32 v3, 0xffff0000, v3
	v_mfma_f32_16x16x32_bf16 v[20:23], v[92:95], v[76:79], v[28:31]
	s_nop 2
	v_or_b32_sdwa v29, v0, v34 dst_sel:DWORD dst_unused:UNUSED_PAD src0_sel:DWORD src1_sel:WORD_1
	v_or_b32_sdwa v28, v3, v32 dst_sel:DWORD dst_unused:UNUSED_PAD src0_sel:DWORD src1_sel:WORD_1
	v_and_b32_sdwa v0, v26, v2 dst_sel:DWORD dst_unused:UNUSED_PAD src0_sel:WORD_1 src1_sel:DWORD
	v_and_b32_sdwa v3, v24, v2 dst_sel:DWORD dst_unused:UNUSED_PAD src0_sel:WORD_1 src1_sel:DWORD
	v_mfma_f32_16x16x32_bf16 v[8:11], v[106:109], v[48:51], v[8:11]
	v_add3_u32 v3, v24, v3, s23
	v_add3_u32 v0, v26, v0, s23
	v_and_b32_sdwa v24, v27, v2 dst_sel:DWORD dst_unused:UNUSED_PAD src0_sel:WORD_1 src1_sel:DWORD
	v_and_b32_sdwa v26, v25, v2 dst_sel:DWORD dst_unused:UNUSED_PAD src0_sel:WORD_1 src1_sel:DWORD
	v_add3_u32 v24, v27, v24, s23
	v_add3_u32 v25, v25, v26, s23
	v_and_b32_e32 v32, 0xffff0000, v24
	v_and_b32_e32 v34, 0xffff0000, v25
	v_mfma_f32_16x16x32_bf16 v[12:15], v[52:55], v[110:113], v[12:15]
	v_or_b32_sdwa v33, v32, v0 dst_sel:DWORD dst_unused:UNUSED_PAD src0_sel:DWORD src1_sel:WORD_1
	v_or_b32_sdwa v32, v34, v3 dst_sel:DWORD dst_unused:UNUSED_PAD src0_sel:DWORD src1_sel:WORD_1
	v_and_b32_sdwa v0, v10, v2 dst_sel:DWORD dst_unused:UNUSED_PAD src0_sel:WORD_1 src1_sel:DWORD
	v_and_b32_sdwa v3, v8, v2 dst_sel:DWORD dst_unused:UNUSED_PAD src0_sel:WORD_1 src1_sel:DWORD
	v_add3_u32 v3, v8, v3, s23
	v_add3_u32 v0, v10, v0, s23
	v_and_b32_sdwa v8, v11, v2 dst_sel:DWORD dst_unused:UNUSED_PAD src0_sel:WORD_1 src1_sel:DWORD
	v_and_b32_sdwa v10, v9, v2 dst_sel:DWORD dst_unused:UNUSED_PAD src0_sel:WORD_1 src1_sel:DWORD
	v_add3_u32 v8, v11, v8, s23
	v_add3_u32 v44, v9, v10, s23
	flat_store_dwordx2 v[126:127], v[28:29] offset:32
	v_mfma_f32_16x16x32_bf16 v[28:31], v[102:105], v[76:79], v[36:39]
	v_and_b32_e32 v45, 0xffff0000, v8
	v_and_b32_e32 v44, 0xffff0000, v44
	v_or_b32_sdwa v49, v45, v0 dst_sel:DWORD dst_unused:UNUSED_PAD src0_sel:DWORD src1_sel:WORD_1
	v_mfma_f32_16x16x32_bf16 v[24:27], v[88:91], v[110:113], v[64:67]
	v_or_b32_sdwa v48, v44, v3 dst_sel:DWORD dst_unused:UNUSED_PAD src0_sel:DWORD src1_sel:WORD_1
	v_and_b32_sdwa v0, v14, v2 dst_sel:DWORD dst_unused:UNUSED_PAD src0_sel:WORD_1 src1_sel:DWORD
	v_and_b32_sdwa v3, v12, v2 dst_sel:DWORD dst_unused:UNUSED_PAD src0_sel:WORD_1 src1_sel:DWORD
	v_add3_u32 v3, v12, v3, s23
	v_add3_u32 v0, v14, v0, s23
	v_and_b32_sdwa v12, v15, v2 dst_sel:DWORD dst_unused:UNUSED_PAD src0_sel:WORD_1 src1_sel:DWORD
	v_and_b32_sdwa v14, v13, v2 dst_sel:DWORD dst_unused:UNUSED_PAD src0_sel:WORD_1 src1_sel:DWORD
	v_mfma_f32_16x16x32_bf16 v[36:39], v[106:109], v[110:113], v[40:43]
	v_add3_u32 v12, v15, v12, s23
	flat_store_dwordx2 v[126:127], v[32:33] offset:64
	flat_store_dwordx2 v[126:127], v[48:49] offset:96
	v_mfma_f32_16x16x32_bf16 v[40:43], v[52:55], v[114:117], v[60:63]
	s_waitcnt lgkmcnt(0)
	v_mfma_f32_16x16x32_bf16 v[4:7], v[52:55], v[118:121], v[4:7]
	v_add3_u32 v52, v13, v14, s23
	v_and_b32_e32 v53, 0xffff0000, v12
	v_or_b32_e32 v60, 16, v122
	v_mfma_f32_16x16x32_bf16 v[12:15], v[106:109], v[118:121], v[28:31]
	v_ashrrev_i32_e32 v61, 31, v60
	s_nop 1
	v_and_b32_e32 v28, 0xffff0000, v52
	v_or_b32_sdwa v29, v53, v0 dst_sel:DWORD dst_unused:UNUSED_PAD src0_sel:DWORD src1_sel:WORD_1
	v_or_b32_sdwa v28, v28, v3 dst_sel:DWORD dst_unused:UNUSED_PAD src0_sel:DWORD src1_sel:WORD_1
	v_and_b32_sdwa v0, v26, v2 dst_sel:DWORD dst_unused:UNUSED_PAD src0_sel:WORD_1 src1_sel:DWORD
	v_and_b32_sdwa v3, v24, v2 dst_sel:DWORD dst_unused:UNUSED_PAD src0_sel:WORD_1 src1_sel:DWORD
	v_mfma_f32_16x16x32_bf16 v[32:35], v[98:101], v[110:113], v[68:71]
	v_add3_u32 v3, v24, v3, s23
	v_add3_u32 v0, v26, v0, s23
	v_and_b32_sdwa v24, v27, v2 dst_sel:DWORD dst_unused:UNUSED_PAD src0_sel:WORD_1 src1_sel:DWORD
	v_and_b32_sdwa v26, v25, v2 dst_sel:DWORD dst_unused:UNUSED_PAD src0_sel:WORD_1 src1_sel:DWORD
	v_mfma_f32_16x16x32_bf16 v[48:51], v[106:109], v[114:117], v[56:59]
	v_add3_u32 v24, v27, v24, s23
	v_add3_u32 v25, v25, v26, s23
	v_and_b32_e32 v24, 0xffff0000, v24
	v_lshlrev_b64 v[56:57], 10, v[60:61]
	v_lshl_add_u64 v[56:57], s[6:7], 0, v[56:57]
	v_and_b32_e32 v26, 0xffff0000, v25
	v_lshl_add_u64 v[56:57], v[56:57], 0, v[124:125]
	v_or_b32_sdwa v25, v24, v0 dst_sel:DWORD dst_unused:UNUSED_PAD src0_sel:DWORD src1_sel:WORD_1
	v_or_b32_sdwa v24, v26, v3 dst_sel:DWORD dst_unused:UNUSED_PAD src0_sel:DWORD src1_sel:WORD_1
	flat_store_dwordx2 v[56:57], v[24:25] offset:32
	v_and_b32_sdwa v24, v35, v2 dst_sel:DWORD dst_unused:UNUSED_PAD src0_sel:WORD_1 src1_sel:DWORD
	v_and_b32_sdwa v25, v33, v2 dst_sel:DWORD dst_unused:UNUSED_PAD src0_sel:WORD_1 src1_sel:DWORD
	v_and_b32_sdwa v0, v34, v2 dst_sel:DWORD dst_unused:UNUSED_PAD src0_sel:WORD_1 src1_sel:DWORD
	v_and_b32_sdwa v3, v32, v2 dst_sel:DWORD dst_unused:UNUSED_PAD src0_sel:WORD_1 src1_sel:DWORD
	v_add3_u32 v24, v35, v24, s23
	v_add3_u32 v25, v33, v25, s23
	v_add3_u32 v3, v32, v3, s23
	v_add3_u32 v0, v34, v0, s23
	v_and_b32_e32 v24, 0xffff0000, v24
	v_and_b32_e32 v26, 0xffff0000, v25
	v_or_b32_sdwa v25, v24, v0 dst_sel:DWORD dst_unused:UNUSED_PAD src0_sel:DWORD src1_sel:WORD_1
	v_or_b32_sdwa v24, v26, v3 dst_sel:DWORD dst_unused:UNUSED_PAD src0_sel:DWORD src1_sel:WORD_1
	flat_store_dwordx2 v[56:57], v[24:25] offset:64
	v_and_b32_sdwa v24, v39, v2 dst_sel:DWORD dst_unused:UNUSED_PAD src0_sel:WORD_1 src1_sel:DWORD
	v_and_b32_sdwa v25, v37, v2 dst_sel:DWORD dst_unused:UNUSED_PAD src0_sel:WORD_1 src1_sel:DWORD
	v_and_b32_sdwa v0, v38, v2 dst_sel:DWORD dst_unused:UNUSED_PAD src0_sel:WORD_1 src1_sel:DWORD
	v_and_b32_sdwa v3, v36, v2 dst_sel:DWORD dst_unused:UNUSED_PAD src0_sel:WORD_1 src1_sel:DWORD
	v_add3_u32 v24, v39, v24, s23
	v_add3_u32 v25, v37, v25, s23
	v_mfma_f32_16x16x32_bf16 v[8:11], v[88:91], v[114:117], v[72:75]
	v_add3_u32 v3, v36, v3, s23
	v_add3_u32 v0, v38, v0, s23
	v_and_b32_e32 v24, 0xffff0000, v24
	v_and_b32_e32 v26, 0xffff0000, v25
	v_or_b32_sdwa v25, v24, v0 dst_sel:DWORD dst_unused:UNUSED_PAD src0_sel:DWORD src1_sel:WORD_1
	v_or_b32_sdwa v24, v26, v3 dst_sel:DWORD dst_unused:UNUSED_PAD src0_sel:DWORD src1_sel:WORD_1
	v_and_b32_sdwa v26, v43, v2 dst_sel:DWORD dst_unused:UNUSED_PAD src0_sel:WORD_1 src1_sel:DWORD
	v_and_b32_sdwa v27, v41, v2 dst_sel:DWORD dst_unused:UNUSED_PAD src0_sel:WORD_1 src1_sel:DWORD
	v_and_b32_sdwa v0, v42, v2 dst_sel:DWORD dst_unused:UNUSED_PAD src0_sel:WORD_1 src1_sel:DWORD
	v_and_b32_sdwa v3, v40, v2 dst_sel:DWORD dst_unused:UNUSED_PAD src0_sel:WORD_1 src1_sel:DWORD
	v_add3_u32 v26, v43, v26, s23
	v_add3_u32 v27, v41, v27, s23
	flat_store_dwordx2 v[56:57], v[28:29]
	v_add3_u32 v3, v40, v3, s23
	v_add3_u32 v0, v42, v0, s23
	v_and_b32_e32 v26, 0xffff0000, v26
	v_and_b32_e32 v28, 0xffff0000, v27
	flat_store_dwordx2 v[56:57], v[24:25] offset:96
	v_or_b32_e32 v24, 32, v122
	v_or_b32_sdwa v27, v26, v0 dst_sel:DWORD dst_unused:UNUSED_PAD src0_sel:DWORD src1_sel:WORD_1
	v_or_b32_sdwa v26, v28, v3 dst_sel:DWORD dst_unused:UNUSED_PAD src0_sel:DWORD src1_sel:WORD_1
	v_and_b32_sdwa v0, v10, v2 dst_sel:DWORD dst_unused:UNUSED_PAD src0_sel:WORD_1 src1_sel:DWORD
	v_and_b32_sdwa v3, v8, v2 dst_sel:DWORD dst_unused:UNUSED_PAD src0_sel:WORD_1 src1_sel:DWORD
	v_mfma_f32_16x16x32_bf16 v[44:47], v[98:101], v[114:117], v[84:87]
	v_ashrrev_i32_e32 v25, 31, v24
	v_add3_u32 v3, v8, v3, s23
	v_add3_u32 v0, v10, v0, s23
	v_and_b32_sdwa v8, v11, v2 dst_sel:DWORD dst_unused:UNUSED_PAD src0_sel:WORD_1 src1_sel:DWORD
	v_and_b32_sdwa v10, v9, v2 dst_sel:DWORD dst_unused:UNUSED_PAD src0_sel:WORD_1 src1_sel:DWORD
	v_lshlrev_b64 v[24:25], 10, v[24:25]
	v_add3_u32 v8, v11, v8, s23
	v_add3_u32 v9, v9, v10, s23
	v_lshl_add_u64 v[24:25], s[6:7], 0, v[24:25]
	v_and_b32_e32 v8, 0xffff0000, v8
	v_and_b32_e32 v10, 0xffff0000, v9
	v_lshl_add_u64 v[24:25], v[24:25], 0, v[124:125]
	v_or_b32_sdwa v9, v8, v0 dst_sel:DWORD dst_unused:UNUSED_PAD src0_sel:DWORD src1_sel:WORD_1
	v_or_b32_sdwa v8, v10, v3 dst_sel:DWORD dst_unused:UNUSED_PAD src0_sel:DWORD src1_sel:WORD_1
	flat_store_dwordx2 v[24:25], v[8:9] offset:32
	v_and_b32_sdwa v8, v47, v2 dst_sel:DWORD dst_unused:UNUSED_PAD src0_sel:WORD_1 src1_sel:DWORD
	v_and_b32_sdwa v9, v45, v2 dst_sel:DWORD dst_unused:UNUSED_PAD src0_sel:WORD_1 src1_sel:DWORD
	v_and_b32_sdwa v0, v46, v2 dst_sel:DWORD dst_unused:UNUSED_PAD src0_sel:WORD_1 src1_sel:DWORD
	v_and_b32_sdwa v3, v44, v2 dst_sel:DWORD dst_unused:UNUSED_PAD src0_sel:WORD_1 src1_sel:DWORD
	v_add3_u32 v8, v47, v8, s23
	v_add3_u32 v9, v45, v9, s23
	v_add3_u32 v3, v44, v3, s23
	v_add3_u32 v0, v46, v0, s23
	v_and_b32_e32 v8, 0xffff0000, v8
	v_and_b32_e32 v10, 0xffff0000, v9
	v_or_b32_sdwa v9, v8, v0 dst_sel:DWORD dst_unused:UNUSED_PAD src0_sel:DWORD src1_sel:WORD_1
	v_or_b32_sdwa v8, v10, v3 dst_sel:DWORD dst_unused:UNUSED_PAD src0_sel:DWORD src1_sel:WORD_1
	flat_store_dwordx2 v[24:25], v[8:9] offset:64
	v_and_b32_sdwa v8, v51, v2 dst_sel:DWORD dst_unused:UNUSED_PAD src0_sel:WORD_1 src1_sel:DWORD
	v_and_b32_sdwa v9, v49, v2 dst_sel:DWORD dst_unused:UNUSED_PAD src0_sel:WORD_1 src1_sel:DWORD
	v_and_b32_sdwa v0, v50, v2 dst_sel:DWORD dst_unused:UNUSED_PAD src0_sel:WORD_1 src1_sel:DWORD
	v_and_b32_sdwa v3, v48, v2 dst_sel:DWORD dst_unused:UNUSED_PAD src0_sel:WORD_1 src1_sel:DWORD
	v_add3_u32 v8, v51, v8, s23
	v_add3_u32 v9, v49, v9, s23
	v_add3_u32 v3, v48, v3, s23
	v_add3_u32 v0, v50, v0, s23
	v_and_b32_e32 v8, 0xffff0000, v8
	v_and_b32_e32 v10, 0xffff0000, v9
	v_or_b32_sdwa v9, v8, v0 dst_sel:DWORD dst_unused:UNUSED_PAD src0_sel:DWORD src1_sel:WORD_1
	v_or_b32_sdwa v8, v10, v3 dst_sel:DWORD dst_unused:UNUSED_PAD src0_sel:DWORD src1_sel:WORD_1
	flat_store_dwordx2 v[24:25], v[8:9] offset:96
	v_or_b32_e32 v8, 48, v122
	v_and_b32_sdwa v0, v6, v2 dst_sel:DWORD dst_unused:UNUSED_PAD src0_sel:WORD_1 src1_sel:DWORD
	v_and_b32_sdwa v3, v4, v2 dst_sel:DWORD dst_unused:UNUSED_PAD src0_sel:WORD_1 src1_sel:DWORD
	v_mfma_f32_16x16x32_bf16 v[16:19], v[88:91], v[118:121], v[16:19]
	v_ashrrev_i32_e32 v9, 31, v8
	v_add3_u32 v3, v4, v3, s23
	v_add3_u32 v0, v6, v0, s23
	v_and_b32_sdwa v4, v7, v2 dst_sel:DWORD dst_unused:UNUSED_PAD src0_sel:WORD_1 src1_sel:DWORD
	v_and_b32_sdwa v6, v5, v2 dst_sel:DWORD dst_unused:UNUSED_PAD src0_sel:WORD_1 src1_sel:DWORD
	v_lshlrev_b64 v[8:9], 10, v[8:9]
	v_add3_u32 v4, v7, v4, s23
	v_add3_u32 v5, v5, v6, s23
	v_lshl_add_u64 v[8:9], s[6:7], 0, v[8:9]
	v_and_b32_e32 v4, 0xffff0000, v4
	v_and_b32_e32 v6, 0xffff0000, v5
	v_lshl_add_u64 v[8:9], v[8:9], 0, v[124:125]
	v_or_b32_sdwa v5, v4, v0 dst_sel:DWORD dst_unused:UNUSED_PAD src0_sel:DWORD src1_sel:WORD_1
	v_or_b32_sdwa v4, v6, v3 dst_sel:DWORD dst_unused:UNUSED_PAD src0_sel:DWORD src1_sel:WORD_1
	v_mfma_f32_16x16x32_bf16 v[20:23], v[98:101], v[118:121], v[20:23]
	flat_store_dwordx2 v[8:9], v[4:5]
	v_and_b32_sdwa v4, v19, v2 dst_sel:DWORD dst_unused:UNUSED_PAD src0_sel:WORD_1 src1_sel:DWORD
	v_and_b32_sdwa v5, v17, v2 dst_sel:DWORD dst_unused:UNUSED_PAD src0_sel:WORD_1 src1_sel:DWORD
	v_and_b32_sdwa v0, v18, v2 dst_sel:DWORD dst_unused:UNUSED_PAD src0_sel:WORD_1 src1_sel:DWORD
	v_and_b32_sdwa v3, v16, v2 dst_sel:DWORD dst_unused:UNUSED_PAD src0_sel:WORD_1 src1_sel:DWORD
	v_add3_u32 v4, v19, v4, s23
	v_add3_u32 v5, v17, v5, s23
	v_add3_u32 v3, v16, v3, s23
	v_add3_u32 v0, v18, v0, s23
	v_and_b32_e32 v4, 0xffff0000, v4
	v_and_b32_e32 v6, 0xffff0000, v5
	v_or_b32_sdwa v5, v4, v0 dst_sel:DWORD dst_unused:UNUSED_PAD src0_sel:DWORD src1_sel:WORD_1
	v_or_b32_sdwa v4, v6, v3 dst_sel:DWORD dst_unused:UNUSED_PAD src0_sel:DWORD src1_sel:WORD_1
	flat_store_dwordx2 v[8:9], v[4:5] offset:32
	v_and_b32_sdwa v4, v23, v2 dst_sel:DWORD dst_unused:UNUSED_PAD src0_sel:WORD_1 src1_sel:DWORD
	v_and_b32_sdwa v5, v21, v2 dst_sel:DWORD dst_unused:UNUSED_PAD src0_sel:WORD_1 src1_sel:DWORD
	v_and_b32_sdwa v0, v22, v2 dst_sel:DWORD dst_unused:UNUSED_PAD src0_sel:WORD_1 src1_sel:DWORD
	v_and_b32_sdwa v3, v20, v2 dst_sel:DWORD dst_unused:UNUSED_PAD src0_sel:WORD_1 src1_sel:DWORD
	v_add3_u32 v4, v23, v4, s23
	v_add3_u32 v5, v21, v5, s23
	v_add3_u32 v3, v20, v3, s23
	v_add3_u32 v0, v22, v0, s23
	v_and_b32_e32 v4, 0xffff0000, v4
	v_and_b32_e32 v6, 0xffff0000, v5
	v_or_b32_sdwa v5, v4, v0 dst_sel:DWORD dst_unused:UNUSED_PAD src0_sel:DWORD src1_sel:WORD_1
	v_or_b32_sdwa v4, v6, v3 dst_sel:DWORD dst_unused:UNUSED_PAD src0_sel:DWORD src1_sel:WORD_1
	flat_store_dwordx2 v[8:9], v[4:5] offset:64
	v_and_b32_sdwa v4, v15, v2 dst_sel:DWORD dst_unused:UNUSED_PAD src0_sel:WORD_1 src1_sel:DWORD
	v_and_b32_sdwa v5, v13, v2 dst_sel:DWORD dst_unused:UNUSED_PAD src0_sel:WORD_1 src1_sel:DWORD
	v_and_b32_sdwa v0, v14, v2 dst_sel:DWORD dst_unused:UNUSED_PAD src0_sel:WORD_1 src1_sel:DWORD
	v_and_b32_sdwa v3, v12, v2 dst_sel:DWORD dst_unused:UNUSED_PAD src0_sel:WORD_1 src1_sel:DWORD
	v_add3_u32 v4, v15, v4, s23
	v_add3_u32 v5, v13, v5, s23
	v_add3_u32 v3, v12, v3, s23
	v_add3_u32 v0, v14, v0, s23
	v_and_b32_e32 v4, 0xffff0000, v4
	v_and_b32_e32 v6, 0xffff0000, v5
	v_or_b32_sdwa v5, v4, v0 dst_sel:DWORD dst_unused:UNUSED_PAD src0_sel:DWORD src1_sel:WORD_1
	v_or_b32_sdwa v4, v6, v3 dst_sel:DWORD dst_unused:UNUSED_PAD src0_sel:DWORD src1_sel:WORD_1
	flat_store_dwordx2 v[24:25], v[26:27]
	flat_store_dwordx2 v[8:9], v[4:5] offset:96
	s_waitcnt lgkmcnt(0)
	s_barrier
	s_cbranch_scc0 .LBB0_2897

.LBB0_3159:
	s_cmpk_gt_i32 s33, 0xbf
	s_cbranch_scc0 .LBB0_3163
	v_lshl_add_u64 v[20:21], s[20:21], 0, v[0:1]
	v_lshlrev_b64 v[22:23], 9, v[20:21]
	v_lshl_add_u64 v[40:41], v[4:5], 0, v[22:23]
	v_lshl_add_u64 v[42:43], v[6:7], 0, v[22:23]
	v_lshl_add_u64 v[22:23], v[8:9], 0, v[22:23]
	global_load_dwordx2 v[44:45], v[40:41], off
	global_load_dwordx2 v[46:47], v[42:43], off
	s_add_u32 s6, s0, s24
	global_load_dwordx2 v[22:23], v[22:23], off
	s_addc_u32 s7, s1, s25
	s_load_dwordx2 s[6:7], s[6:7], 0xb8
	v_lshlrev_b64 v[40:41], 11, v[20:21]
	v_lshl_add_u64 v[48:49], s[18:19], 0, v[40:41]
	s_waitcnt lgkmcnt(0)
	global_load_dwordx4 v[40:43], v29, s[6:7] offset:256
	s_waitcnt vmcnt(0)
	v_lshlrev_b32_e32 v50, 16, v44
	v_lshlrev_b32_e32 v52, 16, v46
	v_and_b32_e32 v51, 0xffff0000, v44
	v_and_b32_e32 v53, 0xffff0000, v46
	v_lshlrev_b32_e32 v44, 16, v45
	v_lshlrev_b32_e32 v46, 16, v47
	v_and_b32_e32 v45, 0xffff0000, v45
	v_and_b32_e32 v47, 0xffff0000, v47
	v_lshlrev_b32_e32 v56, 16, v22
	v_and_b32_e32 v57, 0xffff0000, v22
	v_lshlrev_b32_e32 v58, 16, v23
	v_and_b32_e32 v59, 0xffff0000, v23
	v_pk_add_f32 v[22:23], v[44:45], v[46:47]
	v_pk_add_f32 v[44:45], v[50:51], v[52:53]
	v_mul_f32_e32 v52, 0xbfb8aa3b, v56
	v_mul_f32_e32 v53, 0xbfb8aa3b, v57
	v_mul_f32_e32 v54, 0xbfb8aa3b, v58
	v_mul_f32_e32 v55, 0xbfb8aa3b, v59
	v_exp_f32_e32 v52, v52
	v_exp_f32_e32 v53, v53
	v_pk_mul_f32 v[50:51], v[44:45], v[44:45]
	v_exp_f32_e32 v54, v54
	v_exp_f32_e32 v55, v55
	v_pk_mul_f32 v[46:47], v[22:23], v[22:23]
	v_add_f32_e32 v50, v50, v51
	v_add_f32_e32 v46, v46, v50
	v_add_f32_e32 v50, v47, v46
	v_pk_add_f32 v[46:47], v[52:53], 1.0 op_sel_hi:[1,0]
	s_nop 0
	v_add_f32_dpp v52, v50, v50 quad_perm:[1,0,3,2] row_mask:0xf bank_mask:0xf bound_ctrl:1
	v_pk_add_f32 v[50:51], v[54:55], 1.0 op_sel_hi:[1,0]
	v_div_scale_f32 v53, s[6:7], v47, v47, v57
	v_div_scale_f32 v55, s[6:7], v46, v46, v56
	v_add_f32_dpp v52, v52, v52 quad_perm:[2,3,0,1] row_mask:0xf bank_mask:0xf bound_ctrl:1
	v_div_scale_f32 v61, s[8:9], v51, v51, v59
	v_rcp_f32_e32 v64, v53
	v_rcp_f32_e32 v65, v55
	v_add_f32_dpp v52, v52, v52 row_half_mirror row_mask:0xf bank_mask:0xf bound_ctrl:1
	v_rcp_f32_e32 v66, v61
	v_div_scale_f32 v63, s[10:11], v50, v50, v58
	v_add_f32_dpp v52, v52, v52 row_mirror row_mask:0xf bank_mask:0xf bound_ctrl:1
	v_fmamk_f32 v52, v52, 0x3c800000, v30
	v_mul_f32_e32 v68, 0x4b800000, v52
	v_fma_f32 v69, -v53, v64, 1.0
	v_cmp_gt_f32_e64 s[10:11], s31, v52
	v_div_scale_f32 v54, vcc, v57, v47, v57
	v_fma_f32 v70, -v55, v65, 1.0
	v_cndmask_b32_e64 v52, v52, v68, s[10:11]
	v_fma_f32 v68, -v61, v66, 1.0
	v_fmac_f32_e32 v64, v69, v64
	v_div_scale_f32 v60, s[6:7], v56, v46, v56
	v_fmac_f32_e32 v65, v70, v65
	v_rsq_f32_e32 v52, v52
	v_fmac_f32_e32 v66, v68, v66
	v_mul_f32_e32 v68, v54, v64
	v_mul_f32_e32 v69, v60, v65
	v_fma_f32 v72, -v53, v68, v54
	v_div_scale_f32 v62, s[8:9], v59, v51, v59
	v_fma_f32 v73, -v55, v69, v60
	v_fmac_f32_e32 v68, v72, v64
	v_rcp_f32_e32 v67, v63
	v_mul_f32_e32 v70, v62, v66
	v_fmac_f32_e32 v69, v73, v65
	v_fma_f32 v53, -v53, v68, v54
	v_fma_f32 v75, -v61, v70, v62
	v_fma_f32 v54, -v55, v69, v60
	v_mul_f32_e32 v55, 0x45800000, v52
	v_div_fmas_f32 v53, v53, v64, v68
	s_mov_b64 vcc, s[6:7]
	v_fmac_f32_e32 v70, v75, v66
	v_cndmask_b32_e64 v52, v52, v55, s[10:11]
	v_div_fixup_f32 v47, v53, v47, v57
	v_div_fmas_f32 v53, v54, v65, v69
	v_fma_f32 v60, -v61, v70, v62
	v_pk_mul_f32 v[22:23], v[22:23], v[52:53] op_sel_hi:[1,0]
	s_mov_b64 vcc, s[8:9]
	v_fma_f32 v71, -v63, v67, 1.0
	v_pk_mul_f32 v[22:23], v[42:43], v[22:23]
	v_div_fmas_f32 v42, v60, v66, v70
	v_pk_mul_f32 v[44:45], v[44:45], v[52:53] op_sel_hi:[1,0]
	v_div_fixup_f32 v43, v42, v51, v59
	v_fmac_f32_e32 v67, v71, v67
	v_div_scale_f32 v42, vcc, v58, v50, v58
	v_pk_mul_f32 v[40:41], v[40:41], v[44:45]
	v_mul_f32_e32 v44, v42, v67
	v_fma_f32 v45, -v63, v44, v42
	v_fmac_f32_e32 v44, v45, v67
	v_fma_f32 v42, -v63, v44, v42
	v_div_fmas_f32 v42, v42, v67, v44
	v_div_fixup_f32 v46, v53, v46, v56
	v_div_fixup_f32 v42, v42, v50, v58
	v_pk_mul_f32 v[40:41], v[46:47], v[40:41]
	v_pk_mul_f32 v[22:23], v[42:43], v[22:23]
	v_lshl_add_u64 v[42:43], v[48:49], 0, v[2:3]
	v_cvt_pk_bf16_f32 v40, v40, v41
	v_cvt_pk_bf16_f32 v41, v22, v23
	v_add_co_u32_e32 v22, vcc, 0x4552000, v42
	s_mov_b64 s[8:9], 0
	s_nop 0
	v_addc_co_u32_e32 v23, vcc, 0, v43, vcc
	flat_store_dwordx2 v[22:23], v[40:41] offset:1024 sc1
	s_waitcnt vmcnt(0)
	s_mov_b64 s[6:7], 0
	s_and_saveexec_b64 s[10:11], s[4:5]
	s_xor_b64 s[10:11], exec, s[10:11]
	v_ashrrev_i64 v[22:23], 2, v[20:21]
	s_mov_b64 s[6:7], exec
	v_and_b32_e32 v22, 0xffffffc0, v22
	s_or_b64 exec, exec, s[10:11]
	s_and_b64 vcc, exec, s[8:9]
	s_cbranch_vccnz .LBB0_3164
	s_branch .LBB0_3167

.LBB0_3164:
	s_ashr_i32 s23, s22, 31
	v_lshl_add_u64 v[40:41], s[22:23], 1, v[10:11]
	v_lshl_add_u64 v[20:21], v[40:41], 0, v[12:13]
	s_waitcnt lgkmcnt(0)
	s_barrier
	global_load_dwordx4 v[20:23], v[20:21], off
	v_lshl_add_u64 v[42:43], v[40:41], 0, v[14:15]
	v_add_u32_e32 v52, v28, v25
	v_add_u32_e32 v53, v27, v25
	v_add_u32_e32 v54, v26, v25
	v_add_u32_e32 v55, v24, v25
	s_waitcnt vmcnt(0) lgkmcnt(0)
	ds_write_b16 v31, v20
	ds_write_b16_d16_hi v31, v20 offset:528
	ds_write_b16 v31, v21 offset:1056
	ds_write_b16_d16_hi v31, v21 offset:1584
	ds_write_b16 v31, v22 offset:2112
	ds_write_b16_d16_hi v31, v22 offset:2640
	ds_write_b16 v31, v23 offset:3168
	ds_write_b16_d16_hi v31, v23 offset:3696
	global_load_dwordx4 v[20:23], v[42:43], off
	v_lshl_add_u64 v[42:43], v[40:41], 0, v[16:17]
	v_lshl_add_u64 v[40:41], v[40:41], 0, v[18:19]
	s_waitcnt vmcnt(0) lgkmcnt(0)
	ds_write_b16 v32, v20
	ds_write_b16_d16_hi v32, v20 offset:528
	ds_write_b16 v32, v21 offset:1056
	ds_write_b16_d16_hi v32, v21 offset:1584
	ds_write_b16 v32, v22 offset:2112
	ds_write_b16_d16_hi v32, v22 offset:2640
	ds_write_b16 v32, v23 offset:3168
	ds_write_b16_d16_hi v32, v23 offset:3696
	global_load_dwordx4 v[20:23], v[42:43], off
	s_waitcnt vmcnt(0) lgkmcnt(0)
	ds_write_b16 v33, v20
	ds_write_b16_d16_hi v33, v20 offset:528
	ds_write_b16 v33, v21 offset:1056
	ds_write_b16_d16_hi v33, v21 offset:1584
	ds_write_b16 v33, v22 offset:2112
	ds_write_b16_d16_hi v33, v22 offset:2640
	ds_write_b16 v33, v23 offset:3168
	ds_write_b16_d16_hi v33, v23 offset:3696
	global_load_dwordx4 v[20:23], v[40:41], off
	s_waitcnt vmcnt(0) lgkmcnt(0)
	ds_write_b16 v34, v20
	ds_write_b16_d16_hi v34, v20 offset:528
	ds_write_b16 v34, v21 offset:1056
	ds_write_b16_d16_hi v34, v21 offset:1584
	ds_write_b16 v34, v22 offset:2112
	ds_write_b16_d16_hi v34, v22 offset:2640
	ds_write_b16 v34, v23 offset:3168
	ds_write_b16_d16_hi v34, v23 offset:3696
	s_waitcnt lgkmcnt(0)
	s_barrier
	ds_read_b128 v[20:23], v35
	ds_read_b128 v[40:43], v36
	ds_read_b128 v[44:47], v37
	ds_read_b128 v[48:51], v38
	s_waitcnt lgkmcnt(3)
	buffer_store_dwordx4 v[20:23], v52, s[12:15], 0 offen sc1
	s_waitcnt lgkmcnt(2)
	buffer_store_dwordx4 v[40:43], v53, s[12:15], 0 offen sc1
	s_waitcnt lgkmcnt(1)
	buffer_store_dwordx4 v[44:47], v54, s[12:15], 0 offen sc1
	s_waitcnt lgkmcnt(0)
	buffer_store_dwordx4 v[48:51], v55, s[12:15], 0 offen sc1
	s_waitcnt vmcnt(0)
	s_and_saveexec_b64 s[10:11], s[4:5]
	s_and_b32 s8, s29, 0xffffffc0
	s_ashr_i32 s9, s8, 31
	s_or_b64 s[6:7], s[6:7], exec
	s_or_b64 exec, exec, s[10:11]
	v_mov_b64_e32 v[22:23], s[8:9]

.LBB0_3170:
	s_andn2_b64 vcc, exec, s[4:5]
	s_cbranch_vccnz .LBB0_3188
	s_cmpk_gt_i32 s2, 0xbf
	v_ashrrev_i32_e32 v4, 6, v74
	v_and_b32_e32 v75, 63, v74
	s_cbranch_scc0 .LBB0_3177
	s_mul_i32 s4, s2, 0x48
	s_addk_i32 s4, 0xe800
	s_mov_b32 s5, 0
	v_ashrrev_i32_e32 v5, 31, v4
	v_lshlrev_b32_e32 v8, 3, v75
	v_mov_b32_e32 v9, 0
	v_lshl_add_u64 v[6:7], s[4:5], 0, v[4:5]
	v_lshl_add_u64 v[0:1], s[18:19], 0, v[8:9]
	s_mov_b64 s[4:5], 0x6952000
	s_waitcnt vmcnt(0)
	v_lshl_add_u64 v[26:27], v[0:1], 0, s[4:5]
	s_mov_b64 s[4:5], 0x6f52000
	v_lshl_add_u64 v[28:29], v[0:1], 0, s[4:5]
	s_mov_b64 s[4:5], 0xcb32000
	v_lshlrev_b64 v[2:3], 9, v[6:7]
	v_lshl_add_u64 v[30:31], v[0:1], 0, s[4:5]
	v_lshl_add_u64 v[10:11], v[26:27], 0, v[2:3]
	v_lshl_add_u64 v[0:1], v[30:31], 0, v[2:3]
	v_lshl_add_u64 v[12:13], v[28:29], 0, v[2:3]
	global_load_dwordx2 v[76:77], v[10:11], off
	global_load_dwordx2 v[78:79], v[12:13], off
	global_load_dwordx2 v[80:81], v[0:1], off
	v_lshl_add_u64 v[10:11], v[6:7], 0, 8
	v_lshlrev_b64 v[0:1], 9, v[10:11]
	v_lshl_add_u64 v[2:3], v[26:27], 0, v[0:1]
	v_lshl_add_u64 v[12:13], v[6:7], 0, 16
	global_load_dwordx2 v[70:71], v[2:3], off
	v_lshl_add_u64 v[2:3], v[28:29], 0, v[0:1]
	v_lshl_add_u64 v[0:1], v[30:31], 0, v[0:1]
	v_lshlrev_b64 v[14:15], 9, v[12:13]
	v_lshl_add_u64 v[16:17], v[26:27], 0, v[14:15]
	v_lshl_add_u64 v[18:19], v[28:29], 0, v[14:15]
	global_load_dwordx2 v[72:73], v[2:3], off
	global_load_dwordx2 v[68:69], v[0:1], off
	global_load_dwordx2 v[64:65], v[16:17], off
	global_load_dwordx2 v[66:67], v[18:19], off
	v_lshl_add_u64 v[0:1], v[30:31], 0, v[14:15]
	v_lshl_add_u64 v[14:15], v[6:7], 0, 24
	v_lshlrev_b64 v[2:3], 9, v[14:15]
	v_lshl_add_u64 v[16:17], v[26:27], 0, v[2:3]
	v_lshl_add_u64 v[18:19], v[28:29], 0, v[2:3]
	v_lshl_add_u64 v[2:3], v[30:31], 0, v[2:3]
	global_load_dwordx2 v[44:45], v[0:1], off
	global_load_dwordx2 v[60:61], v[16:17], off
	global_load_dwordx2 v[62:63], v[18:19], off
	global_load_dwordx2 v[58:59], v[2:3], off
	v_lshl_add_u64 v[16:17], v[6:7], 0, 32
	v_lshlrev_b64 v[0:1], 9, v[16:17]
	v_lshl_add_u64 v[18:19], v[6:7], 0, 40
	v_lshl_add_u64 v[2:3], v[26:27], 0, v[0:1]
	v_lshl_add_u64 v[20:21], v[28:29], 0, v[0:1]
	v_lshlrev_b64 v[22:23], 9, v[18:19]
	s_ashr_i32 s5, s24, 31
	v_lshl_add_u64 v[0:1], v[30:31], 0, v[0:1]
	v_lshl_add_u64 v[24:25], v[26:27], 0, v[22:23]
	global_load_dwordx2 v[54:55], v[2:3], off
	global_load_dwordx2 v[56:57], v[20:21], off
	global_load_dwordx2 v[52:53], v[0:1], off
	global_load_dwordx2 v[48:49], v[24:25], off
	v_lshl_add_u64 v[20:21], v[6:7], 0, 48
	s_add_u32 s4, s0, s24
	v_lshl_add_u64 v[0:1], v[28:29], 0, v[22:23]
	v_lshl_add_u64 v[2:3], v[30:31], 0, v[22:23]
	v_lshlrev_b64 v[22:23], 9, v[20:21]
	s_addc_u32 s5, s1, s5
	v_lshl_add_u64 v[24:25], v[26:27], 0, v[22:23]
	v_lshl_add_u64 v[32:33], v[28:29], 0, v[22:23]
	global_load_dwordx2 v[50:51], v[0:1], off
	global_load_dwordx2 v[46:47], v[2:3], off
	global_load_dwordx2 v[38:39], v[24:25], off
	global_load_dwordx2 v[40:41], v[32:33], off
	s_load_dwordx2 s[4:5], s[4:5], 0xb8
	v_lshl_add_u64 v[0:1], v[30:31], 0, v[22:23]
	v_lshl_add_u64 v[22:23], v[6:7], 0, 56
	v_lshlrev_b64 v[2:3], 9, v[22:23]
	v_lshl_add_u64 v[24:25], v[26:27], 0, v[2:3]
	v_lshl_add_u64 v[82:83], v[28:29], 0, v[2:3]
	v_lshl_add_u64 v[2:3], v[30:31], 0, v[2:3]
	global_load_dwordx2 v[42:43], v[0:1], off
	global_load_dwordx2 v[34:35], v[24:25], off
	global_load_dwordx2 v[36:37], v[82:83], off
	global_load_dwordx2 v[32:33], v[2:3], off
	v_lshlrev_b32_e32 v0, 4, v74
	v_and_b32_e32 v0, 0xf0, v0
	s_waitcnt lgkmcnt(0)
	global_load_dwordx4 v[0:3], v0, s[4:5] offset:256
	v_lshl_add_u64 v[24:25], v[6:7], 0, 64
	v_lshlrev_b64 v[82:83], 9, v[24:25]
	v_lshl_add_u64 v[84:85], v[26:27], 0, v[82:83]
	v_lshl_add_u64 v[86:87], v[28:29], 0, v[82:83]
	v_lshl_add_u64 v[82:83], v[30:31], 0, v[82:83]
	global_load_dwordx2 v[28:29], v[84:85], off
	global_load_dwordx2 v[30:31], v[86:87], off
	global_load_dwordx2 v[26:27], v[82:83], off
	s_mov_b32 s7, 0x800000
	s_mov_b32 s8, 0x4552000
	s_mov_b32 s6, 0x3c800000
	s_mov_b64 s[10:11], 0
	s_waitcnt vmcnt(0)
	v_lshlrev_b32_e32 v82, 16, v76
	v_lshlrev_b32_e32 v84, 16, v78
	v_lshlrev_b32_e32 v5, 16, v80
	v_and_b32_e32 v88, 0xffff0000, v80
	v_mul_f32_e32 v80, 0xbfb8aa3b, v5
	v_exp_f32_e32 v86, v80
	v_mul_f32_e32 v80, 0xbfb8aa3b, v88
	v_exp_f32_e32 v87, v80
	v_and_b32_e32 v83, 0xffff0000, v76
	v_and_b32_e32 v85, 0xffff0000, v78
	v_lshlrev_b32_e32 v76, 16, v77
	v_lshlrev_b32_e32 v78, 16, v79
	v_and_b32_e32 v77, 0xffff0000, v77
	v_and_b32_e32 v79, 0xffff0000, v79
	v_pk_add_f32 v[76:77], v[76:77], v[78:79]
	v_pk_add_f32 v[78:79], v[86:87], 1.0 op_sel_hi:[1,0]
	v_pk_add_f32 v[82:83], v[82:83], v[84:85]
	v_div_scale_f32 v86, s[4:5], v79, v79, v88
	v_rcp_f32_e32 v87, v86
	v_pk_mul_f32 v[84:85], v[82:83], v[82:83]
	v_lshlrev_b32_e32 v89, 16, v81
	v_and_b32_e32 v90, 0xffff0000, v81
	v_fma_f32 v91, -v86, v87, 1.0
	v_fmac_f32_e32 v87, v91, v87
	v_div_scale_f32 v91, vcc, v88, v79, v88
	v_mul_f32_e32 v92, v91, v87
	v_fma_f32 v93, -v86, v92, v91
	v_fmac_f32_e32 v92, v93, v87
	v_fma_f32 v86, -v86, v92, v91
	v_div_scale_f32 v91, s[4:5], v78, v78, v5
	v_pk_mul_f32 v[80:81], v[76:77], v[76:77]
	v_rcp_f32_e32 v93, v91
	v_add_f32_e32 v84, v84, v85
	v_add_f32_e32 v80, v84, v80
	v_add_f32_e32 v80, v81, v80
	v_div_fmas_f32 v86, v86, v87, v92
	v_div_fixup_f32 v79, v86, v79, v88
	v_add_f32_dpp v80, v80, v80 quad_perm:[1,0,3,2] row_mask:0xf bank_mask:0xf bound_ctrl:1
	v_fma_f32 v86, -v91, v93, 1.0
	v_fmac_f32_e32 v93, v86, v93
	v_add_f32_dpp v80, v80, v80 quad_perm:[2,3,0,1] row_mask:0xf bank_mask:0xf bound_ctrl:1
	v_div_scale_f32 v86, vcc, v5, v78, v5
	s_nop 0
	v_add_f32_dpp v80, v80, v80 row_half_mirror row_mask:0xf bank_mask:0xf bound_ctrl:1
	v_mul_f32_e32 v87, v86, v93
	v_mov_b32_e32 v81, 0x358637bd
	v_add_f32_dpp v80, v80, v80 row_mirror row_mask:0xf bank_mask:0xf bound_ctrl:1
	v_fma_f32 v88, -v91, v87, v86
	v_fmac_f32_e32 v81, 0x3c800000, v80
	v_fmac_f32_e32 v87, v88, v93
	v_mul_f32_e32 v80, 0x4b800000, v81
	v_cmp_gt_f32_e64 s[4:5], s7, v81
	v_fma_f32 v86, -v91, v87, v86
	v_lshlrev_b32_e32 v91, 16, v45
	v_cndmask_b32_e64 v80, v81, v80, s[4:5]
	v_rsq_f32_e32 v84, v80
	v_div_fmas_f32 v80, v86, v93, v87
	v_div_fixup_f32 v78, v80, v78, v5
	v_mul_f32_e32 v80, 0xbfb8aa3b, v89
	v_mul_f32_e32 v81, 0xbfb8aa3b, v90
	v_exp_f32_e32 v80, v80
	v_exp_f32_e32 v81, v81
	v_mul_f32_e32 v5, 0x45800000, v84
	v_cndmask_b32_e64 v84, v84, v5, s[4:5]
	v_pk_mul_f32 v[82:83], v[82:83], v[84:85] op_sel_hi:[1,0]
	v_pk_add_f32 v[80:81], v[80:81], 1.0 op_sel_hi:[1,0]
	v_pk_mul_f32 v[82:83], v[0:1], v[82:83]
	v_div_scale_f32 v5, s[4:5], v81, v81, v90
	v_rcp_f32_e32 v85, v5
	v_pk_mul_f32 v[78:79], v[78:79], v[82:83]
	v_and_b32_e32 v92, 0xffff0000, v45
	v_cvt_pk_bf16_f32 v78, v78, v79
	v_fma_f32 v82, -v5, v85, 1.0
	v_pk_mul_f32 v[76:77], v[76:77], v[84:85] op_sel_hi:[1,0]
	v_fmac_f32_e32 v85, v82, v85
	v_div_scale_f32 v82, vcc, v90, v81, v90
	v_mul_f32_e32 v83, v82, v85
	v_fma_f32 v84, -v5, v83, v82
	v_fmac_f32_e32 v83, v84, v85
	v_fma_f32 v5, -v5, v83, v82
	v_div_scale_f32 v82, s[4:5], v80, v80, v89
	v_rcp_f32_e32 v84, v82
	v_div_fmas_f32 v5, v5, v85, v83
	v_div_fixup_f32 v81, v5, v81, v90
	v_pk_mul_f32 v[76:77], v[2:3], v[76:77]
	v_fma_f32 v5, -v82, v84, 1.0
	v_fmac_f32_e32 v84, v5, v84
	v_div_scale_f32 v5, vcc, v89, v80, v89
	v_mul_f32_e32 v83, v5, v84
	v_fma_f32 v85, -v82, v83, v5
	v_fmac_f32_e32 v83, v85, v84
	v_fma_f32 v5, -v82, v83, v5
	v_div_fmas_f32 v5, v5, v84, v83
	v_div_fixup_f32 v80, v5, v80, v89
	v_pk_mul_f32 v[76:77], v[80:81], v[76:77]
	v_lshlrev_b32_e32 v5, 16, v68
	v_cvt_pk_bf16_f32 v79, v76, v77
	v_lshlrev_b64 v[76:77], 11, v[6:7]
	v_and_b32_e32 v82, 0xffff0000, v68
	v_mul_f32_e32 v68, 0xbfb8aa3b, v5
	v_lshl_add_u64 v[76:77], s[18:19], 0, v[76:77]
	v_exp_f32_e32 v80, v68
	v_mul_f32_e32 v68, 0xbfb8aa3b, v82
	v_lshl_add_u64 v[76:77], v[76:77], 0, v[8:9]
	v_exp_f32_e32 v81, v68
	v_add_co_u32_e32 v76, vcc, s8, v76
	v_lshlrev_b32_e32 v83, 16, v69
	s_nop 0
	v_addc_co_u32_e32 v77, vcc, 0, v77, vcc
	flat_store_dwordx2 v[76:77], v[78:79] offset:1024 sc1
	v_lshlrev_b32_e32 v76, 16, v70
	v_lshlrev_b32_e32 v78, 16, v72
	v_and_b32_e32 v77, 0xffff0000, v70
	v_and_b32_e32 v79, 0xffff0000, v72
	v_lshlrev_b32_e32 v70, 16, v71
	v_lshlrev_b32_e32 v72, 16, v73
	v_and_b32_e32 v71, 0xffff0000, v71
	v_and_b32_e32 v73, 0xffff0000, v73
	v_and_b32_e32 v84, 0xffff0000, v69
	v_pk_add_f32 v[68:69], v[70:71], v[72:73]
	v_pk_add_f32 v[70:71], v[80:81], 1.0 op_sel_hi:[1,0]
	v_and_b32_e32 v90, 0xffff0000, v44
	v_div_scale_f32 v80, s[4:5], v71, v71, v82
	v_rcp_f32_e32 v81, v80
	v_pk_add_f32 v[76:77], v[76:77], v[78:79]
	v_pk_mul_f32 v[72:73], v[68:69], v[68:69]
	v_pk_mul_f32 v[78:79], v[76:77], v[76:77]
	v_fma_f32 v85, -v80, v81, 1.0
	v_fmac_f32_e32 v81, v85, v81
	v_div_scale_f32 v85, vcc, v82, v71, v82
	v_mul_f32_e32 v86, v85, v81
	v_fma_f32 v87, -v80, v86, v85
	v_fmac_f32_e32 v86, v87, v81
	v_fma_f32 v80, -v80, v86, v85
	v_div_scale_f32 v85, s[4:5], v70, v70, v5
	v_rcp_f32_e32 v87, v85
	v_div_fmas_f32 v80, v80, v81, v86
	v_div_fixup_f32 v71, v80, v71, v82
	v_mul_f32_e32 v81, 0xbfb8aa3b, v84
	v_fma_f32 v80, -v85, v87, 1.0
	v_fmac_f32_e32 v87, v80, v87
	v_mul_f32_e32 v80, 0xbfb8aa3b, v83
	v_exp_f32_e32 v80, v80
	v_exp_f32_e32 v81, v81
	v_div_scale_f32 v82, vcc, v5, v70, v5
	v_mul_f32_e32 v86, v82, v87
	v_fma_f32 v88, -v85, v86, v82
	v_fmac_f32_e32 v86, v88, v87
	v_pk_add_f32 v[80:81], v[80:81], 1.0 op_sel_hi:[1,0]
	v_fma_f32 v82, -v85, v86, v82
	v_div_scale_f32 v85, s[4:5], v81, v81, v84
	v_rcp_f32_e32 v88, v85
	v_div_fmas_f32 v82, v82, v87, v86
	v_div_fixup_f32 v70, v82, v70, v5
	v_and_b32_e32 v87, 0xffff0000, v66
	v_fma_f32 v5, -v85, v88, 1.0
	v_fmac_f32_e32 v88, v5, v88
	v_div_scale_f32 v5, vcc, v84, v81, v84
	v_mul_f32_e32 v82, v5, v88
	v_fma_f32 v86, -v85, v82, v5
	v_fmac_f32_e32 v82, v86, v88
	v_fma_f32 v5, -v85, v82, v5
	v_div_scale_f32 v85, s[4:5], v80, v80, v83
	v_rcp_f32_e32 v86, v85
	v_div_fmas_f32 v5, v5, v88, v82
	v_div_fixup_f32 v81, v5, v81, v84
	v_fma_f32 v5, -v85, v86, 1.0
	v_fmac_f32_e32 v86, v5, v86
	v_div_scale_f32 v5, vcc, v83, v80, v83
	v_mul_f32_e32 v82, v5, v86
	v_fma_f32 v84, -v85, v82, v5
	v_fmac_f32_e32 v82, v84, v86
	v_fma_f32 v5, -v85, v82, v5
	v_div_fmas_f32 v5, v5, v86, v82
	v_div_fixup_f32 v80, v5, v80, v83
	v_lshlrev_b32_e32 v5, 16, v44
	v_mul_f32_e32 v44, 0xbfb8aa3b, v5
	v_exp_f32_e32 v88, v44
	v_mul_f32_e32 v44, 0xbfb8aa3b, v90
	v_exp_f32_e32 v89, v44
	v_lshlrev_b32_e32 v84, 16, v64
	v_lshlrev_b32_e32 v86, 16, v66
	v_and_b32_e32 v85, 0xffff0000, v64
	v_lshlrev_b32_e32 v64, 16, v65
	v_lshlrev_b32_e32 v66, 16, v67
	v_and_b32_e32 v65, 0xffff0000, v65
	v_and_b32_e32 v67, 0xffff0000, v67
	v_pk_add_f32 v[64:65], v[64:65], v[66:67]
	v_pk_add_f32 v[66:67], v[88:89], 1.0 op_sel_hi:[1,0]
	v_pk_add_f32 v[84:85], v[84:85], v[86:87]
	v_div_scale_f32 v88, s[4:5], v67, v67, v90
	v_rcp_f32_e32 v89, v88
	v_pk_mul_f32 v[86:87], v[84:85], v[84:85]
	v_pk_mul_f32 v[44:45], v[64:65], v[64:65]
	v_lshlrev_b64 v[82:83], 11, v[10:11]
	v_fma_f32 v93, -v88, v89, 1.0
	v_fmac_f32_e32 v89, v93, v89
	v_div_scale_f32 v93, vcc, v90, v67, v90
	v_mul_f32_e32 v94, v93, v89
	v_fma_f32 v95, -v88, v94, v93
	v_fmac_f32_e32 v94, v95, v89
	v_fma_f32 v88, -v88, v94, v93
	v_div_scale_f32 v93, s[4:5], v66, v66, v5
	v_rcp_f32_e32 v95, v93
	v_div_fmas_f32 v88, v88, v89, v94
	v_div_fixup_f32 v67, v88, v67, v90
	s_mov_b32 s4, 0x358637bd
	v_fma_f32 v88, -v93, v95, 1.0
	v_fmac_f32_e32 v95, v88, v95
	v_div_scale_f32 v88, vcc, v5, v66, v5
	v_mul_f32_e32 v90, v88, v95
	v_fma_f32 v89, -v93, v90, v88
	v_fmac_f32_e32 v90, v89, v95
	v_fma_f32 v93, -v93, v90, v88
	v_mov_b32_e32 v88, v86
	v_mov_b32_e32 v89, v78
	v_mov_b32_e32 v78, v87
	v_pk_add_f32 v[78:79], v[88:89], v[78:79]
	v_mov_b32_e32 v86, v44
	v_mov_b32_e32 v87, v72
	v_pk_add_f32 v[78:79], v[78:79], v[86:87]
	v_mov_b32_e32 v72, v45
	v_pk_add_f32 v[44:45], v[72:73], v[78:79]
	v_lshl_add_u64 v[82:83], s[18:19], 0, v[82:83]
	v_lshl_add_u64 v[82:83], v[82:83], 0, v[8:9]
	v_mov_b32_dpp v73, v45 quad_perm:[1,0,3,2] row_mask:0xf bank_mask:0xf bound_ctrl:1
	v_mov_b32_dpp v72, v44 quad_perm:[1,0,3,2] row_mask:0xf bank_mask:0xf bound_ctrl:1
	v_pk_add_f32 v[44:45], v[44:45], v[72:73]
	s_nop 1
	v_mov_b32_dpp v73, v45 quad_perm:[2,3,0,1] row_mask:0xf bank_mask:0xf bound_ctrl:1
	v_mov_b32_dpp v72, v44 quad_perm:[2,3,0,1] row_mask:0xf bank_mask:0xf bound_ctrl:1
	v_pk_add_f32 v[44:45], v[44:45], v[72:73]
	s_nop 1
	v_mov_b32_dpp v73, v45 row_half_mirror row_mask:0xf bank_mask:0xf bound_ctrl:1
	v_mov_b32_dpp v72, v44 row_half_mirror row_mask:0xf bank_mask:0xf bound_ctrl:1
	v_pk_add_f32 v[44:45], v[44:45], v[72:73]
	s_nop 1
	v_mov_b32_dpp v73, v45 row_mirror row_mask:0xf bank_mask:0xf bound_ctrl:1
	v_mov_b32_dpp v72, v44 row_mirror row_mask:0xf bank_mask:0xf bound_ctrl:1
	v_pk_add_f32 v[72:73], v[44:45], v[72:73]
	v_mov_b64_e32 v[44:45], s[4:5]
	v_pk_fma_f32 v[72:73], v[72:73], s[6:7], v[44:45] op_sel_hi:[1,0,0]
	s_nop 0
	v_mul_f32_e32 v78, 0x4b800000, v73
	v_cmp_gt_f32_e64 s[4:5], s7, v73
	s_nop 1
	v_cndmask_b32_e64 v73, v73, v78, s[4:5]
	v_rsq_f32_e32 v73, v73
	v_div_fmas_f32 v78, v93, v95, v90
	v_div_fixup_f32 v66, v78, v66, v5
	v_cmp_gt_f32_e32 vcc, s7, v72
	v_mul_f32_e32 v5, 0x45800000, v73
	v_cndmask_b32_e64 v78, v73, v5, s[4:5]
	v_pk_mul_f32 v[76:77], v[76:77], v[78:79] op_sel_hi:[1,0]
	v_pk_mul_f32 v[68:69], v[68:69], v[78:79] op_sel_hi:[1,0]
	v_pk_mul_f32 v[76:77], v[0:1], v[76:77]
	v_pk_mul_f32 v[68:69], v[2:3], v[68:69]
	v_pk_mul_f32 v[70:71], v[70:71], v[76:77]
	v_pk_mul_f32 v[68:69], v[80:81], v[68:69]
	v_cvt_pk_bf16_f32 v70, v70, v71
	v_cvt_pk_bf16_f32 v71, v68, v69
	v_add_co_u32_e64 v68, s[4:5], s8, v82
	v_mul_f32_e32 v5, 0x4b800000, v72
	s_nop 0
	v_addc_co_u32_e64 v69, s[4:5], 0, v83, s[4:5]
	v_cndmask_b32_e32 v5, v72, v5, vcc
	flat_store_dwordx2 v[68:69], v[70:71] offset:1024 sc1
	v_mul_f32_e32 v68, 0xbfb8aa3b, v91
	v_mul_f32_e32 v69, 0xbfb8aa3b, v92
	v_rsq_f32_e32 v5, v5
	v_exp_f32_e32 v68, v68
	v_exp_f32_e32 v69, v69
	v_and_b32_e32 v80, 0xffff0000, v52
	v_mul_f32_e32 v70, 0x45800000, v5
	v_cndmask_b32_e32 v70, v5, v70, vcc
	v_pk_add_f32 v[68:69], v[68:69], 1.0 op_sel_hi:[1,0]
	v_pk_mul_f32 v[72:73], v[84:85], v[70:71] op_sel_hi:[1,0]
	v_div_scale_f32 v5, s[4:5], v69, v69, v92
	v_rcp_f32_e32 v71, v5
	v_pk_mul_f32 v[72:73], v[0:1], v[72:73]
	v_lshlrev_b32_e32 v81, 16, v53
	v_pk_mul_f32 v[66:67], v[66:67], v[72:73]
	v_pk_mul_f32 v[64:65], v[64:65], v[70:71] op_sel_hi:[1,0]
	v_fma_f32 v70, -v5, v71, 1.0
	v_fmac_f32_e32 v71, v70, v71
	v_div_scale_f32 v70, vcc, v92, v69, v92
	v_mul_f32_e32 v72, v70, v71
	v_fma_f32 v73, -v5, v72, v70
	v_fmac_f32_e32 v72, v73, v71
	v_fma_f32 v5, -v5, v72, v70
	v_div_scale_f32 v70, s[4:5], v68, v68, v91
	v_rcp_f32_e32 v73, v70
	v_div_fmas_f32 v5, v5, v71, v72
	v_div_fixup_f32 v69, v5, v69, v92
	v_pk_mul_f32 v[64:65], v[2:3], v[64:65]
	v_fma_f32 v5, -v70, v73, 1.0
	v_fmac_f32_e32 v73, v5, v73
	v_div_scale_f32 v5, vcc, v91, v68, v91
	v_mul_f32_e32 v71, v5, v73
	v_fma_f32 v72, -v70, v71, v5
	v_fmac_f32_e32 v71, v72, v73
	v_fma_f32 v5, -v70, v71, v5
	v_div_fmas_f32 v5, v5, v73, v71
	v_div_fixup_f32 v68, v5, v68, v91
	v_pk_mul_f32 v[64:65], v[68:69], v[64:65]
	v_lshlrev_b32_e32 v5, 16, v58
	v_cvt_pk_bf16_f32 v66, v66, v67
	v_cvt_pk_bf16_f32 v67, v64, v65
	v_lshlrev_b64 v[64:65], 11, v[12:13]
	v_and_b32_e32 v70, 0xffff0000, v58
	v_mul_f32_e32 v58, 0xbfb8aa3b, v5
	v_lshl_add_u64 v[64:65], s[18:19], 0, v[64:65]
	v_exp_f32_e32 v68, v58
	v_mul_f32_e32 v58, 0xbfb8aa3b, v70
	v_lshl_add_u64 v[64:65], v[64:65], 0, v[8:9]
	v_exp_f32_e32 v69, v58
	v_add_co_u32_e32 v64, vcc, s8, v64
	v_lshlrev_b32_e32 v71, 16, v59
	s_nop 0
	v_addc_co_u32_e32 v65, vcc, 0, v65, vcc
	flat_store_dwordx2 v[64:65], v[66:67] offset:1024 sc1
	v_lshlrev_b32_e32 v64, 16, v60
	v_lshlrev_b32_e32 v66, 16, v62
	v_and_b32_e32 v65, 0xffff0000, v60
	v_and_b32_e32 v67, 0xffff0000, v62
	v_lshlrev_b32_e32 v60, 16, v61
	v_lshlrev_b32_e32 v62, 16, v63
	v_and_b32_e32 v61, 0xffff0000, v61
	v_and_b32_e32 v63, 0xffff0000, v63
	v_and_b32_e32 v72, 0xffff0000, v59
	v_pk_add_f32 v[58:59], v[60:61], v[62:63]
	v_pk_add_f32 v[60:61], v[68:69], 1.0 op_sel_hi:[1,0]
	v_and_b32_e32 v82, 0xffff0000, v53
	v_div_scale_f32 v68, s[4:5], v61, v61, v70
	v_rcp_f32_e32 v69, v68
	v_pk_add_f32 v[64:65], v[64:65], v[66:67]
	v_pk_mul_f32 v[62:63], v[58:59], v[58:59]
	v_pk_mul_f32 v[66:67], v[64:65], v[64:65]
	v_fma_f32 v73, -v68, v69, 1.0
	v_fmac_f32_e32 v69, v73, v69
	v_div_scale_f32 v73, vcc, v70, v61, v70
	v_mul_f32_e32 v76, v73, v69
	v_fma_f32 v77, -v68, v76, v73
	v_fmac_f32_e32 v76, v77, v69
	v_fma_f32 v68, -v68, v76, v73
	v_div_scale_f32 v73, s[4:5], v60, v60, v5
	v_rcp_f32_e32 v77, v73
	v_div_fmas_f32 v68, v68, v69, v76
	v_div_fixup_f32 v61, v68, v61, v70
	v_mul_f32_e32 v69, 0xbfb8aa3b, v72
	v_fma_f32 v68, -v73, v77, 1.0
	v_fmac_f32_e32 v77, v68, v77
	v_mul_f32_e32 v68, 0xbfb8aa3b, v71
	v_exp_f32_e32 v68, v68
	v_exp_f32_e32 v69, v69
	v_div_scale_f32 v70, vcc, v5, v60, v5
	v_mul_f32_e32 v76, v70, v77
	v_fma_f32 v78, -v73, v76, v70
	v_fmac_f32_e32 v76, v78, v77
	v_pk_add_f32 v[68:69], v[68:69], 1.0 op_sel_hi:[1,0]
	v_fma_f32 v70, -v73, v76, v70
	v_div_scale_f32 v73, s[4:5], v69, v69, v72
	v_rcp_f32_e32 v78, v73
	v_div_fmas_f32 v70, v70, v77, v76
	v_div_fixup_f32 v60, v70, v60, v5
	v_and_b32_e32 v77, 0xffff0000, v56
	v_fma_f32 v5, -v73, v78, 1.0
	v_fmac_f32_e32 v78, v5, v78
	v_div_scale_f32 v5, vcc, v72, v69, v72
	v_mul_f32_e32 v70, v5, v78
	v_fma_f32 v76, -v73, v70, v5
	v_fmac_f32_e32 v70, v76, v78
	v_fma_f32 v5, -v73, v70, v5
	v_div_scale_f32 v73, s[4:5], v68, v68, v71
	v_rcp_f32_e32 v76, v73
	v_div_fmas_f32 v5, v5, v78, v70
	v_div_fixup_f32 v69, v5, v69, v72
	v_fma_f32 v5, -v73, v76, 1.0
	v_fmac_f32_e32 v76, v5, v76
	v_div_scale_f32 v5, vcc, v71, v68, v71
	v_mul_f32_e32 v70, v5, v76
	v_fma_f32 v72, -v73, v70, v5
	v_fmac_f32_e32 v70, v72, v76
	v_fma_f32 v5, -v73, v70, v5
	v_div_fmas_f32 v5, v5, v76, v70
	v_div_fixup_f32 v68, v5, v68, v71
	v_lshlrev_b32_e32 v5, 16, v52
	v_mul_f32_e32 v52, 0xbfb8aa3b, v5
	v_exp_f32_e32 v78, v52
	v_mul_f32_e32 v52, 0xbfb8aa3b, v80
	v_exp_f32_e32 v79, v52
	v_lshlrev_b32_e32 v72, 16, v54
	v_lshlrev_b32_e32 v76, 16, v56
	v_and_b32_e32 v73, 0xffff0000, v54
	v_lshlrev_b32_e32 v54, 16, v55
	v_lshlrev_b32_e32 v56, 16, v57
	v_and_b32_e32 v55, 0xffff0000, v55
	v_and_b32_e32 v57, 0xffff0000, v57
	v_pk_add_f32 v[52:53], v[54:55], v[56:57]
	v_pk_add_f32 v[54:55], v[78:79], 1.0 op_sel_hi:[1,0]
	v_pk_add_f32 v[72:73], v[72:73], v[76:77]
	v_div_scale_f32 v78, s[4:5], v55, v55, v80
	v_rcp_f32_e32 v79, v78
	v_pk_mul_f32 v[76:77], v[72:73], v[72:73]
	v_pk_mul_f32 v[56:57], v[52:53], v[52:53]
	v_lshlrev_b64 v[70:71], 11, v[14:15]
	v_fma_f32 v83, -v78, v79, 1.0
	v_fmac_f32_e32 v79, v83, v79
	v_div_scale_f32 v83, vcc, v80, v55, v80
	v_mul_f32_e32 v84, v83, v79
	v_fma_f32 v85, -v78, v84, v83
	v_fmac_f32_e32 v84, v85, v79
	v_fma_f32 v78, -v78, v84, v83
	v_div_scale_f32 v83, s[4:5], v54, v54, v5
	v_rcp_f32_e32 v85, v83
	v_div_fmas_f32 v78, v78, v79, v84
	v_div_fixup_f32 v55, v78, v55, v80
	v_lshl_add_u64 v[70:71], s[18:19], 0, v[70:71]
	v_fma_f32 v78, -v83, v85, 1.0
	v_fmac_f32_e32 v85, v78, v85
	v_div_scale_f32 v78, vcc, v5, v54, v5
	v_mul_f32_e32 v80, v78, v85
	v_fma_f32 v79, -v83, v80, v78
	v_fmac_f32_e32 v80, v79, v85
	v_fma_f32 v83, -v83, v80, v78
	v_mov_b32_e32 v78, v76
	v_mov_b32_e32 v79, v66
	v_mov_b32_e32 v66, v77
	v_pk_add_f32 v[66:67], v[78:79], v[66:67]
	v_mov_b32_e32 v76, v56
	v_mov_b32_e32 v77, v62
	v_pk_add_f32 v[66:67], v[66:67], v[76:77]
	v_mov_b32_e32 v62, v57
	v_pk_add_f32 v[56:57], v[62:63], v[66:67]
	v_lshl_add_u64 v[70:71], v[70:71], 0, v[8:9]
	v_and_b32_e32 v66, 0xffff0000, v42
	v_mov_b32_dpp v63, v57 quad_perm:[1,0,3,2] row_mask:0xf bank_mask:0xf bound_ctrl:1
	v_mov_b32_dpp v62, v56 quad_perm:[1,0,3,2] row_mask:0xf bank_mask:0xf bound_ctrl:1
	v_pk_add_f32 v[56:57], v[56:57], v[62:63]
	v_lshlrev_b32_e32 v67, 16, v43
	s_nop 0
	v_mov_b32_dpp v63, v57 quad_perm:[2,3,0,1] row_mask:0xf bank_mask:0xf bound_ctrl:1
	v_mov_b32_dpp v62, v56 quad_perm:[2,3,0,1] row_mask:0xf bank_mask:0xf bound_ctrl:1
	v_pk_add_f32 v[56:57], v[56:57], v[62:63]
	s_nop 1
	v_mov_b32_dpp v63, v57 row_half_mirror row_mask:0xf bank_mask:0xf bound_ctrl:1
	v_mov_b32_dpp v62, v56 row_half_mirror row_mask:0xf bank_mask:0xf bound_ctrl:1
	v_pk_add_f32 v[56:57], v[56:57], v[62:63]
	s_nop 1
	v_mov_b32_dpp v63, v57 row_mirror row_mask:0xf bank_mask:0xf bound_ctrl:1
	v_mov_b32_dpp v62, v56 row_mirror row_mask:0xf bank_mask:0xf bound_ctrl:1
	v_pk_add_f32 v[56:57], v[56:57], v[62:63]
	s_nop 0
	v_pk_fma_f32 v[56:57], v[56:57], s[6:7], v[44:45] op_sel_hi:[1,0,0]
	s_nop 0
	v_mul_f32_e32 v62, 0x4b800000, v57
	v_cmp_gt_f32_e64 s[4:5], s7, v57
	s_nop 1
	v_cndmask_b32_e64 v57, v57, v62, s[4:5]
	v_rsq_f32_e32 v57, v57
	v_div_fmas_f32 v62, v83, v85, v80
	v_div_fixup_f32 v54, v62, v54, v5
	v_cmp_gt_f32_e32 vcc, s7, v56
	v_mul_f32_e32 v5, 0x45800000, v57
	v_cndmask_b32_e64 v62, v57, v5, s[4:5]
	v_pk_mul_f32 v[64:65], v[64:65], v[62:63] op_sel_hi:[1,0]
	v_pk_mul_f32 v[58:59], v[58:59], v[62:63] op_sel_hi:[1,0]
	v_pk_mul_f32 v[64:65], v[0:1], v[64:65]
	v_pk_mul_f32 v[58:59], v[2:3], v[58:59]
	v_mul_f32_e32 v5, 0x4b800000, v56
	v_pk_mul_f32 v[60:61], v[60:61], v[64:65]
	v_pk_mul_f32 v[58:59], v[68:69], v[58:59]
	v_cndmask_b32_e32 v5, v56, v5, vcc
	v_add_co_u32_e64 v56, s[4:5], s8, v70
	v_cvt_pk_bf16_f32 v60, v60, v61
	v_cvt_pk_bf16_f32 v61, v58, v59
	v_addc_co_u32_e64 v57, s[4:5], 0, v71, s[4:5]
	flat_store_dwordx2 v[56:57], v[60:61] offset:1024 sc1
	v_mul_f32_e32 v56, 0xbfb8aa3b, v81
	v_mul_f32_e32 v57, 0xbfb8aa3b, v82
	v_rsq_f32_e32 v5, v5
	v_exp_f32_e32 v56, v56
	v_exp_f32_e32 v57, v57
	v_and_b32_e32 v68, 0xffff0000, v43
	v_mul_f32_e32 v58, 0x45800000, v5
	v_cndmask_b32_e32 v58, v5, v58, vcc
	v_pk_add_f32 v[56:57], v[56:57], 1.0 op_sel_hi:[1,0]
	v_pk_mul_f32 v[60:61], v[72:73], v[58:59] op_sel_hi:[1,0]
	v_div_scale_f32 v5, s[4:5], v57, v57, v82
	v_rcp_f32_e32 v59, v5
	v_pk_mul_f32 v[60:61], v[0:1], v[60:61]
	v_pk_mul_f32 v[52:53], v[52:53], v[58:59] op_sel_hi:[1,0]
	v_fma_f32 v58, -v5, v59, 1.0
	v_fmac_f32_e32 v59, v58, v59
	v_div_scale_f32 v58, vcc, v82, v57, v82
	v_pk_mul_f32 v[54:55], v[54:55], v[60:61]
	v_mul_f32_e32 v60, v58, v59
	v_fma_f32 v61, -v5, v60, v58
	v_fmac_f32_e32 v60, v61, v59
	v_fma_f32 v5, -v5, v60, v58
	v_div_scale_f32 v58, s[4:5], v56, v56, v81
	v_rcp_f32_e32 v61, v58
	v_div_fmas_f32 v5, v5, v59, v60
	v_div_fixup_f32 v57, v5, v57, v82
	v_pk_mul_f32 v[52:53], v[2:3], v[52:53]
	v_fma_f32 v5, -v58, v61, 1.0
	v_fmac_f32_e32 v61, v5, v61
	v_div_scale_f32 v5, vcc, v81, v56, v81
	v_mul_f32_e32 v59, v5, v61
	v_fma_f32 v60, -v58, v59, v5
	v_fmac_f32_e32 v59, v60, v61
	v_fma_f32 v5, -v58, v59, v5
	v_div_fmas_f32 v5, v5, v61, v59
	v_div_fixup_f32 v56, v5, v56, v81
	v_pk_mul_f32 v[52:53], v[56:57], v[52:53]
	v_lshlrev_b32_e32 v5, 16, v46
	v_cvt_pk_bf16_f32 v54, v54, v55
	v_cvt_pk_bf16_f32 v55, v52, v53
	v_lshlrev_b64 v[52:53], 11, v[16:17]
	v_and_b32_e32 v58, 0xffff0000, v46
	v_mul_f32_e32 v46, 0xbfb8aa3b, v5
	v_lshl_add_u64 v[52:53], s[18:19], 0, v[52:53]
	v_exp_f32_e32 v56, v46
	v_mul_f32_e32 v46, 0xbfb8aa3b, v58
	v_lshl_add_u64 v[52:53], v[52:53], 0, v[8:9]
	v_exp_f32_e32 v57, v46
	v_add_co_u32_e32 v52, vcc, s8, v52
	v_lshlrev_b32_e32 v59, 16, v47
	s_nop 0
	v_addc_co_u32_e32 v53, vcc, 0, v53, vcc
	flat_store_dwordx2 v[52:53], v[54:55] offset:1024 sc1
	v_lshlrev_b32_e32 v52, 16, v48
	v_lshlrev_b32_e32 v54, 16, v50
	v_and_b32_e32 v53, 0xffff0000, v48
	v_and_b32_e32 v55, 0xffff0000, v50
	v_lshlrev_b32_e32 v48, 16, v49
	v_lshlrev_b32_e32 v50, 16, v51
	v_and_b32_e32 v49, 0xffff0000, v49
	v_and_b32_e32 v51, 0xffff0000, v51
	v_and_b32_e32 v60, 0xffff0000, v47
	v_pk_add_f32 v[46:47], v[48:49], v[50:51]
	v_pk_add_f32 v[48:49], v[56:57], 1.0 op_sel_hi:[1,0]
	v_pk_add_f32 v[52:53], v[52:53], v[54:55]
	v_div_scale_f32 v56, s[4:5], v49, v49, v58
	v_rcp_f32_e32 v57, v56
	v_pk_mul_f32 v[54:55], v[52:53], v[52:53]
	v_pk_mul_f32 v[50:51], v[46:47], v[46:47]
	v_fma_f32 v61, -v56, v57, 1.0
	v_fmac_f32_e32 v57, v61, v57
	v_div_scale_f32 v61, vcc, v58, v49, v58
	v_mul_f32_e32 v62, v61, v57
	v_fma_f32 v63, -v56, v62, v61
	v_fmac_f32_e32 v62, v63, v57
	v_fma_f32 v56, -v56, v62, v61
	v_div_scale_f32 v61, s[4:5], v48, v48, v5
	v_rcp_f32_e32 v63, v61
	v_div_fmas_f32 v56, v56, v57, v62
	v_div_fixup_f32 v49, v56, v49, v58
	v_mul_f32_e32 v57, 0xbfb8aa3b, v60
	v_fma_f32 v56, -v61, v63, 1.0
	v_fmac_f32_e32 v63, v56, v63
	v_mul_f32_e32 v56, 0xbfb8aa3b, v59
	v_exp_f32_e32 v56, v56
	v_exp_f32_e32 v57, v57
	v_div_scale_f32 v58, vcc, v5, v48, v5
	v_mul_f32_e32 v62, v58, v63
	v_fma_f32 v64, -v61, v62, v58
	v_fmac_f32_e32 v62, v64, v63
	v_pk_add_f32 v[56:57], v[56:57], 1.0 op_sel_hi:[1,0]
	v_fma_f32 v58, -v61, v62, v58
	v_div_scale_f32 v61, s[4:5], v57, v57, v60
	v_rcp_f32_e32 v64, v61
	v_div_fmas_f32 v58, v58, v63, v62
	v_div_fixup_f32 v48, v58, v48, v5
	v_and_b32_e32 v63, 0xffff0000, v40
	v_fma_f32 v5, -v61, v64, 1.0
	v_fmac_f32_e32 v64, v5, v64
	v_div_scale_f32 v5, vcc, v60, v57, v60
	v_mul_f32_e32 v58, v5, v64
	v_fma_f32 v62, -v61, v58, v5
	v_fmac_f32_e32 v58, v62, v64
	v_fma_f32 v5, -v61, v58, v5
	v_div_scale_f32 v61, s[4:5], v56, v56, v59
	v_rcp_f32_e32 v62, v61
	v_div_fmas_f32 v5, v5, v64, v58
	v_div_fixup_f32 v57, v5, v57, v60
	v_fma_f32 v5, -v61, v62, 1.0
	v_fmac_f32_e32 v62, v5, v62
	v_div_scale_f32 v5, vcc, v59, v56, v59
	v_mul_f32_e32 v58, v5, v62
	v_fma_f32 v60, -v61, v58, v5
	v_fmac_f32_e32 v58, v60, v62
	v_fma_f32 v5, -v61, v58, v5
	v_div_fmas_f32 v5, v5, v62, v58
	v_div_fixup_f32 v56, v5, v56, v59
	v_lshlrev_b32_e32 v5, 16, v42
	v_mul_f32_e32 v42, 0xbfb8aa3b, v5
	v_exp_f32_e32 v64, v42
	v_mul_f32_e32 v42, 0xbfb8aa3b, v66
	v_exp_f32_e32 v65, v42
	v_lshlrev_b32_e32 v60, 16, v38
	v_lshlrev_b32_e32 v62, 16, v40
	v_and_b32_e32 v61, 0xffff0000, v38
	v_lshlrev_b32_e32 v38, 16, v39
	v_lshlrev_b32_e32 v40, 16, v41
	v_and_b32_e32 v39, 0xffff0000, v39
	v_and_b32_e32 v41, 0xffff0000, v41
	v_pk_add_f32 v[38:39], v[38:39], v[40:41]
	v_pk_add_f32 v[40:41], v[64:65], 1.0 op_sel_hi:[1,0]
	v_pk_add_f32 v[60:61], v[60:61], v[62:63]
	v_div_scale_f32 v64, s[4:5], v41, v41, v66
	v_rcp_f32_e32 v65, v64
	v_pk_mul_f32 v[62:63], v[60:61], v[60:61]
	v_pk_mul_f32 v[42:43], v[38:39], v[38:39]
	v_lshlrev_b64 v[58:59], 11, v[18:19]
	v_fma_f32 v69, -v64, v65, 1.0
	v_fmac_f32_e32 v65, v69, v65
	v_div_scale_f32 v69, vcc, v66, v41, v66
	v_mul_f32_e32 v70, v69, v65
	v_fma_f32 v71, -v64, v70, v69
	v_fmac_f32_e32 v70, v71, v65
	v_fma_f32 v64, -v64, v70, v69
	v_div_scale_f32 v69, s[4:5], v40, v40, v5
	v_rcp_f32_e32 v71, v69
	v_div_fmas_f32 v64, v64, v65, v70
	v_div_fixup_f32 v41, v64, v41, v66
	v_lshl_add_u64 v[58:59], s[18:19], 0, v[58:59]
	v_fma_f32 v64, -v69, v71, 1.0
	v_fmac_f32_e32 v71, v64, v71
	v_div_scale_f32 v64, vcc, v5, v40, v5
	v_mul_f32_e32 v66, v64, v71
	v_fma_f32 v65, -v69, v66, v64
	v_fmac_f32_e32 v66, v65, v71
	v_fma_f32 v69, -v69, v66, v64
	v_mov_b32_e32 v64, v62
	v_mov_b32_e32 v65, v54
	v_mov_b32_e32 v54, v63
	v_pk_add_f32 v[54:55], v[64:65], v[54:55]
	v_mov_b32_e32 v62, v42
	v_mov_b32_e32 v63, v50
	v_pk_add_f32 v[54:55], v[54:55], v[62:63]
	v_mov_b32_e32 v50, v43
	v_pk_add_f32 v[42:43], v[50:51], v[54:55]
	v_lshl_add_u64 v[58:59], v[58:59], 0, v[8:9]
	s_waitcnt lgkmcnt(0)
	v_and_b32_e32 v54, 0xffff0000, v26
	v_mov_b32_dpp v51, v43 quad_perm:[1,0,3,2] row_mask:0xf bank_mask:0xf bound_ctrl:1
	v_mov_b32_dpp v50, v42 quad_perm:[1,0,3,2] row_mask:0xf bank_mask:0xf bound_ctrl:1
	v_pk_add_f32 v[42:43], v[42:43], v[50:51]
	v_lshlrev_b32_e32 v55, 16, v27
	s_nop 0
	v_mov_b32_dpp v51, v43 quad_perm:[2,3,0,1] row_mask:0xf bank_mask:0xf bound_ctrl:1
	v_mov_b32_dpp v50, v42 quad_perm:[2,3,0,1] row_mask:0xf bank_mask:0xf bound_ctrl:1
	v_pk_add_f32 v[42:43], v[42:43], v[50:51]
	s_nop 1
	v_mov_b32_dpp v51, v43 row_half_mirror row_mask:0xf bank_mask:0xf bound_ctrl:1
	v_mov_b32_dpp v50, v42 row_half_mirror row_mask:0xf bank_mask:0xf bound_ctrl:1
	v_pk_add_f32 v[42:43], v[42:43], v[50:51]
	s_nop 1
	v_mov_b32_dpp v51, v43 row_mirror row_mask:0xf bank_mask:0xf bound_ctrl:1
	v_mov_b32_dpp v50, v42 row_mirror row_mask:0xf bank_mask:0xf bound_ctrl:1
	v_pk_add_f32 v[42:43], v[42:43], v[50:51]
	s_nop 0
	v_pk_fma_f32 v[42:43], v[42:43], s[6:7], v[44:45] op_sel_hi:[1,0,0]
	s_nop 0
	v_mul_f32_e32 v50, 0x4b800000, v43
	v_cmp_gt_f32_e64 s[4:5], s7, v43
	s_nop 1
	v_cndmask_b32_e64 v43, v43, v50, s[4:5]
	v_rsq_f32_e32 v43, v43
	v_div_fmas_f32 v50, v69, v71, v66
	v_div_fixup_f32 v40, v50, v40, v5
	v_cmp_gt_f32_e32 vcc, s7, v42
	v_mul_f32_e32 v5, 0x45800000, v43
	v_cndmask_b32_e64 v50, v43, v5, s[4:5]
	v_pk_mul_f32 v[52:53], v[52:53], v[50:51] op_sel_hi:[1,0]
	v_pk_mul_f32 v[46:47], v[46:47], v[50:51] op_sel_hi:[1,0]
	v_pk_mul_f32 v[52:53], v[0:1], v[52:53]
	v_pk_mul_f32 v[46:47], v[2:3], v[46:47]
	v_mul_f32_e32 v5, 0x4b800000, v42
	v_pk_mul_f32 v[48:49], v[48:49], v[52:53]
	v_pk_mul_f32 v[46:47], v[56:57], v[46:47]
	v_cndmask_b32_e32 v5, v42, v5, vcc
	v_add_co_u32_e64 v42, s[4:5], s8, v58
	v_cvt_pk_bf16_f32 v48, v48, v49
	v_cvt_pk_bf16_f32 v49, v46, v47
	v_addc_co_u32_e64 v43, s[4:5], 0, v59, s[4:5]
	flat_store_dwordx2 v[42:43], v[48:49] offset:1024 sc1
	v_mul_f32_e32 v42, 0xbfb8aa3b, v67
	v_mul_f32_e32 v43, 0xbfb8aa3b, v68
	v_rsq_f32_e32 v5, v5
	v_exp_f32_e32 v42, v42
	v_exp_f32_e32 v43, v43
	v_and_b32_e32 v56, 0xffff0000, v27
	v_mul_f32_e32 v46, 0x45800000, v5
	v_cndmask_b32_e32 v46, v5, v46, vcc
	v_pk_add_f32 v[42:43], v[42:43], 1.0 op_sel_hi:[1,0]
	v_pk_mul_f32 v[48:49], v[60:61], v[46:47] op_sel_hi:[1,0]
	v_div_scale_f32 v5, s[4:5], v43, v43, v68
	v_rcp_f32_e32 v47, v5
	v_pk_mul_f32 v[48:49], v[0:1], v[48:49]
	v_pk_mul_f32 v[38:39], v[38:39], v[46:47] op_sel_hi:[1,0]
	v_fma_f32 v46, -v5, v47, 1.0
	v_fmac_f32_e32 v47, v46, v47
	v_div_scale_f32 v46, vcc, v68, v43, v68
	v_pk_mul_f32 v[40:41], v[40:41], v[48:49]
	v_mul_f32_e32 v48, v46, v47
	v_fma_f32 v49, -v5, v48, v46
	v_fmac_f32_e32 v48, v49, v47
	v_fma_f32 v5, -v5, v48, v46
	v_div_scale_f32 v46, s[4:5], v42, v42, v67
	v_rcp_f32_e32 v49, v46
	v_div_fmas_f32 v5, v5, v47, v48
	v_div_fixup_f32 v43, v5, v43, v68
	v_pk_mul_f32 v[38:39], v[2:3], v[38:39]
	v_fma_f32 v5, -v46, v49, 1.0
	v_fmac_f32_e32 v49, v5, v49
	v_div_scale_f32 v5, vcc, v67, v42, v67
	v_mul_f32_e32 v47, v5, v49
	v_fma_f32 v48, -v46, v47, v5
	v_fmac_f32_e32 v47, v48, v49
	v_fma_f32 v5, -v46, v47, v5
	v_div_fmas_f32 v5, v5, v49, v47
	v_div_fixup_f32 v42, v5, v42, v67
	v_pk_mul_f32 v[38:39], v[42:43], v[38:39]
	v_lshlrev_b32_e32 v5, 16, v32
	v_cvt_pk_bf16_f32 v40, v40, v41
	v_cvt_pk_bf16_f32 v41, v38, v39
	v_lshlrev_b64 v[38:39], 11, v[20:21]
	v_and_b32_e32 v46, 0xffff0000, v32
	v_mul_f32_e32 v32, 0xbfb8aa3b, v5
	v_lshl_add_u64 v[38:39], s[18:19], 0, v[38:39]
	v_exp_f32_e32 v42, v32
	v_mul_f32_e32 v32, 0xbfb8aa3b, v46
	v_lshl_add_u64 v[38:39], v[38:39], 0, v[8:9]
	v_exp_f32_e32 v43, v32
	v_add_co_u32_e32 v38, vcc, s8, v38
	v_lshlrev_b32_e32 v47, 16, v33
	s_nop 0
	v_addc_co_u32_e32 v39, vcc, 0, v39, vcc
	flat_store_dwordx2 v[38:39], v[40:41] offset:1024 sc1
	v_lshlrev_b32_e32 v38, 16, v34
	v_lshlrev_b32_e32 v40, 16, v36
	v_and_b32_e32 v39, 0xffff0000, v34
	v_and_b32_e32 v41, 0xffff0000, v36
	v_lshlrev_b32_e32 v34, 16, v35
	v_lshlrev_b32_e32 v36, 16, v37
	v_and_b32_e32 v35, 0xffff0000, v35
	v_and_b32_e32 v37, 0xffff0000, v37
	v_and_b32_e32 v48, 0xffff0000, v33
	v_pk_add_f32 v[32:33], v[34:35], v[36:37]
	v_pk_add_f32 v[34:35], v[42:43], 1.0 op_sel_hi:[1,0]
	v_pk_add_f32 v[38:39], v[38:39], v[40:41]
	v_div_scale_f32 v42, s[4:5], v35, v35, v46
	v_rcp_f32_e32 v43, v42
	v_pk_mul_f32 v[40:41], v[38:39], v[38:39]
	v_pk_mul_f32 v[36:37], v[32:33], v[32:33]
	v_fma_f32 v49, -v42, v43, 1.0
	v_fmac_f32_e32 v43, v49, v43
	v_div_scale_f32 v49, vcc, v46, v35, v46
	v_mul_f32_e32 v50, v49, v43
	v_fma_f32 v51, -v42, v50, v49
	v_fmac_f32_e32 v50, v51, v43
	v_fma_f32 v42, -v42, v50, v49
	v_div_scale_f32 v49, s[4:5], v34, v34, v5
	v_rcp_f32_e32 v51, v49
	v_div_fmas_f32 v42, v42, v43, v50
	v_div_fixup_f32 v35, v42, v35, v46
	v_mul_f32_e32 v43, 0xbfb8aa3b, v48
	v_fma_f32 v42, -v49, v51, 1.0
	v_fmac_f32_e32 v51, v42, v51
	v_mul_f32_e32 v42, 0xbfb8aa3b, v47
	v_exp_f32_e32 v42, v42
	v_exp_f32_e32 v43, v43
	v_div_scale_f32 v46, vcc, v5, v34, v5
	v_mul_f32_e32 v50, v46, v51
	v_fma_f32 v52, -v49, v50, v46
	v_fmac_f32_e32 v50, v52, v51
	v_pk_add_f32 v[42:43], v[42:43], 1.0 op_sel_hi:[1,0]
	v_fma_f32 v46, -v49, v50, v46
	v_div_scale_f32 v49, s[4:5], v43, v43, v48
	v_rcp_f32_e32 v52, v49
	v_div_fmas_f32 v46, v46, v51, v50
	v_div_fixup_f32 v34, v46, v34, v5
	v_and_b32_e32 v51, 0xffff0000, v30
	v_fma_f32 v5, -v49, v52, 1.0
	v_fmac_f32_e32 v52, v5, v52
	v_div_scale_f32 v5, vcc, v48, v43, v48
	v_mul_f32_e32 v46, v5, v52
	v_fma_f32 v50, -v49, v46, v5
	v_fmac_f32_e32 v46, v50, v52
	v_fma_f32 v5, -v49, v46, v5
	v_div_scale_f32 v49, s[4:5], v42, v42, v47
	v_rcp_f32_e32 v50, v49
	v_div_fmas_f32 v5, v5, v52, v46
	v_div_fixup_f32 v43, v5, v43, v48
	v_fma_f32 v5, -v49, v50, 1.0
	v_fmac_f32_e32 v50, v5, v50
	v_div_scale_f32 v5, vcc, v47, v42, v47
	v_mul_f32_e32 v46, v5, v50
	v_fma_f32 v48, -v49, v46, v5
	v_fmac_f32_e32 v46, v48, v50
	v_fma_f32 v5, -v49, v46, v5
	v_div_fmas_f32 v5, v5, v50, v46
	v_div_fixup_f32 v42, v5, v42, v47
	v_lshlrev_b32_e32 v5, 16, v26
	v_mul_f32_e32 v26, 0xbfb8aa3b, v5
	v_exp_f32_e32 v52, v26
	v_mul_f32_e32 v26, 0xbfb8aa3b, v54
	v_exp_f32_e32 v53, v26
	v_lshlrev_b32_e32 v48, 16, v28
	v_lshlrev_b32_e32 v50, 16, v30
	v_and_b32_e32 v49, 0xffff0000, v28
	v_lshlrev_b32_e32 v28, 16, v29
	v_lshlrev_b32_e32 v30, 16, v31
	v_and_b32_e32 v29, 0xffff0000, v29
	v_and_b32_e32 v31, 0xffff0000, v31
	v_pk_add_f32 v[26:27], v[28:29], v[30:31]
	v_pk_add_f32 v[28:29], v[52:53], 1.0 op_sel_hi:[1,0]
	v_pk_add_f32 v[48:49], v[48:49], v[50:51]
	v_div_scale_f32 v52, s[4:5], v29, v29, v54
	v_rcp_f32_e32 v53, v52
	v_pk_mul_f32 v[50:51], v[48:49], v[48:49]
	v_pk_mul_f32 v[30:31], v[26:27], v[26:27]
	v_lshlrev_b64 v[46:47], 11, v[22:23]
	v_fma_f32 v57, -v52, v53, 1.0
	v_fmac_f32_e32 v53, v57, v53
	v_div_scale_f32 v57, vcc, v54, v29, v54
	v_mul_f32_e32 v58, v57, v53
	v_fma_f32 v59, -v52, v58, v57
	v_fmac_f32_e32 v58, v59, v53
	v_fma_f32 v52, -v52, v58, v57
	v_div_scale_f32 v57, s[4:5], v28, v28, v5
	v_rcp_f32_e32 v59, v57
	v_div_fmas_f32 v52, v52, v53, v58
	v_div_fixup_f32 v29, v52, v29, v54
	v_lshl_add_u64 v[46:47], s[18:19], 0, v[46:47]
	v_fma_f32 v52, -v57, v59, 1.0
	v_fmac_f32_e32 v59, v52, v59
	v_div_scale_f32 v52, vcc, v5, v28, v5
	v_mul_f32_e32 v54, v52, v59
	v_fma_f32 v53, -v57, v54, v52
	v_fmac_f32_e32 v54, v53, v59
	v_fma_f32 v57, -v57, v54, v52
	v_mov_b32_e32 v52, v50
	v_mov_b32_e32 v53, v40
	v_mov_b32_e32 v40, v51
	v_pk_add_f32 v[40:41], v[52:53], v[40:41]
	v_mov_b32_e32 v50, v30
	v_mov_b32_e32 v51, v36
	v_pk_add_f32 v[40:41], v[40:41], v[50:51]
	v_mov_b32_e32 v36, v31
	v_pk_add_f32 v[30:31], v[36:37], v[40:41]
	v_lshl_add_u64 v[46:47], v[46:47], 0, v[8:9]
	s_nop 0
	v_mov_b32_dpp v37, v31 quad_perm:[1,0,3,2] row_mask:0xf bank_mask:0xf bound_ctrl:1
	v_mov_b32_dpp v36, v30 quad_perm:[1,0,3,2] row_mask:0xf bank_mask:0xf bound_ctrl:1
	v_pk_add_f32 v[30:31], v[30:31], v[36:37]
	s_nop 1
	v_mov_b32_dpp v37, v31 quad_perm:[2,3,0,1] row_mask:0xf bank_mask:0xf bound_ctrl:1
	v_mov_b32_dpp v36, v30 quad_perm:[2,3,0,1] row_mask:0xf bank_mask:0xf bound_ctrl:1
	v_pk_add_f32 v[30:31], v[30:31], v[36:37]
	s_nop 1
	v_mov_b32_dpp v37, v31 row_half_mirror row_mask:0xf bank_mask:0xf bound_ctrl:1
	v_mov_b32_dpp v36, v30 row_half_mirror row_mask:0xf bank_mask:0xf bound_ctrl:1
	v_pk_add_f32 v[30:31], v[30:31], v[36:37]
	s_nop 1
	v_mov_b32_dpp v37, v31 row_mirror row_mask:0xf bank_mask:0xf bound_ctrl:1
	v_mov_b32_dpp v36, v30 row_mirror row_mask:0xf bank_mask:0xf bound_ctrl:1
	v_pk_add_f32 v[30:31], v[30:31], v[36:37]
	s_nop 0
	v_pk_fma_f32 v[30:31], v[30:31], s[6:7], v[44:45] op_sel_hi:[1,0,0]
	s_nop 0
	v_mul_f32_e32 v36, 0x4b800000, v31
	v_cmp_gt_f32_e64 s[4:5], s7, v31
	s_nop 1
	v_cndmask_b32_e64 v31, v31, v36, s[4:5]
	v_rsq_f32_e32 v31, v31
	v_div_fmas_f32 v36, v57, v59, v54
	v_div_fixup_f32 v28, v36, v28, v5
	v_cmp_gt_f32_e32 vcc, s7, v30
	v_mul_f32_e32 v5, 0x45800000, v31
	v_cndmask_b32_e64 v36, v31, v5, s[4:5]
	v_pk_mul_f32 v[38:39], v[38:39], v[36:37] op_sel_hi:[1,0]
	v_pk_mul_f32 v[32:33], v[32:33], v[36:37] op_sel_hi:[1,0]
	v_pk_mul_f32 v[38:39], v[0:1], v[38:39]
	v_pk_mul_f32 v[32:33], v[2:3], v[32:33]
	v_mul_f32_e32 v5, 0x4b800000, v30
	v_pk_mul_f32 v[34:35], v[34:35], v[38:39]
	v_pk_mul_f32 v[32:33], v[42:43], v[32:33]
	v_cndmask_b32_e32 v5, v30, v5, vcc
	v_add_co_u32_e64 v30, s[4:5], s8, v46
	v_cvt_pk_bf16_f32 v34, v34, v35
	v_cvt_pk_bf16_f32 v35, v32, v33
	v_addc_co_u32_e64 v31, s[4:5], 0, v47, s[4:5]
	flat_store_dwordx2 v[30:31], v[34:35] offset:1024 sc1
	v_mul_f32_e32 v30, 0xbfb8aa3b, v55
	v_mul_f32_e32 v31, 0xbfb8aa3b, v56
	v_rsq_f32_e32 v5, v5
	v_exp_f32_e32 v30, v30
	v_exp_f32_e32 v31, v31
	v_mul_f32_e32 v32, 0x45800000, v5
	v_cndmask_b32_e32 v32, v5, v32, vcc
	v_pk_add_f32 v[30:31], v[30:31], 1.0 op_sel_hi:[1,0]
	v_pk_mul_f32 v[34:35], v[48:49], v[32:33] op_sel_hi:[1,0]
	v_div_scale_f32 v5, s[4:5], v31, v31, v56
	v_rcp_f32_e32 v33, v5
	v_pk_mul_f32 v[0:1], v[0:1], v[34:35]
	v_pk_mul_f32 v[26:27], v[26:27], v[32:33] op_sel_hi:[1,0]
	s_nop 0
	v_pk_mul_f32 v[2:3], v[2:3], v[26:27]
	v_fma_f32 v26, -v5, v33, 1.0
	v_fmac_f32_e32 v33, v26, v33
	v_div_scale_f32 v26, vcc, v56, v31, v56
	v_mul_f32_e32 v27, v26, v33
	v_pk_mul_f32 v[0:1], v[28:29], v[0:1]
	v_fma_f32 v28, -v5, v27, v26
	v_fmac_f32_e32 v27, v28, v33
	v_fma_f32 v5, -v5, v27, v26
	v_div_scale_f32 v26, s[4:5], v30, v30, v55
	v_rcp_f32_e32 v28, v26
	v_div_fmas_f32 v5, v5, v33, v27
	v_div_fixup_f32 v27, v5, v31, v56
	v_cvt_pk_bf16_f32 v0, v0, v1
	v_fma_f32 v5, -v26, v28, 1.0
	v_fmac_f32_e32 v28, v5, v28
	v_div_scale_f32 v5, vcc, v55, v30, v55
	v_mul_f32_e32 v29, v5, v28
	v_fma_f32 v31, -v26, v29, v5
	v_fmac_f32_e32 v29, v31, v28
	v_fma_f32 v5, -v26, v29, v5
	v_div_fmas_f32 v5, v5, v28, v29
	v_div_fixup_f32 v26, v5, v30, v55
	v_pk_mul_f32 v[2:3], v[26:27], v[2:3]
	s_mov_b64 s[4:5], 0
	v_cvt_pk_bf16_f32 v1, v2, v3
	v_lshlrev_b64 v[2:3], 11, v[24:25]
	v_lshl_add_u64 v[2:3], s[18:19], 0, v[2:3]
	v_lshl_add_u64 v[2:3], v[2:3], 0, v[8:9]
	v_add_co_u32_e32 v2, vcc, 0x4552000, v2
	s_nop 1
	v_addc_co_u32_e32 v3, vcc, 0, v3, vcc
	flat_store_dwordx2 v[2:3], v[0:1] offset:1024 sc1
	s_waitcnt vmcnt(0)
	v_cmp_eq_u32_e32 vcc, 0, v75
	s_and_saveexec_b64 s[6:7], vcc
	s_cbranch_execz .LBB0_3176
	v_alignbit_b32 v0, v11, v10, 8
	v_alignbit_b32 v1, v7, v6, 8
	v_cmp_eq_u32_e32 vcc, v0, v1
	v_alignbit_b32 v2, v13, v12, 8
	v_alignbit_b32 v3, v17, v16, 8
	v_cndmask_b32_e64 v0, 1, 2, vcc
	v_cmp_eq_u32_e32 vcc, v2, v1
	v_alignbit_b32 v2, v15, v14, 8
	s_mov_b64 s[8:9], 0
	v_addc_co_u32_e32 v0, vcc, 0, v0, vcc
	v_cmp_eq_u32_e32 vcc, v2, v1
	s_nop 1
	v_cndmask_b32_e64 v2, 0, 1, vcc
	v_cmp_eq_u32_e32 vcc, v3, v1
	v_alignbit_b32 v3, v21, v20, 8
	s_nop 0
	v_addc_co_u32_e32 v0, vcc, v0, v2, vcc
	v_alignbit_b32 v2, v19, v18, 8
	v_cmp_eq_u32_e32 vcc, v2, v1
	s_nop 1
	v_cndmask_b32_e64 v2, 0, 1, vcc
	v_cmp_eq_u32_e32 vcc, v3, v1
	v_alignbit_b32 v3, v25, v24, 8
	s_nop 0
	v_addc_co_u32_e32 v0, vcc, v0, v2, vcc
	v_alignbit_b32 v2, v23, v22, 8
	v_cmp_eq_u32_e32 vcc, v2, v1
	s_nop 1
	v_cndmask_b32_e64 v2, 0, 1, vcc
	v_cmp_eq_u32_e32 vcc, v3, v1
	s_nop 1
	v_addc_co_u32_e32 v2, vcc, v0, v2, vcc
	v_lshlrev_b32_e32 v0, 6, v1
	v_ashrrev_i32_e32 v1, 31, v0
	v_lshl_add_u64 v[6:7], v[0:1], 2, s[16:17]
	flat_atomic_add v[6:7], v2
	v_cmp_gt_u32_e32 vcc, 9, v2
	s_and_saveexec_b64 s[10:11], vcc
	s_xor_b64 s[10:11], exec, s[10:11]
	s_mov_b64 s[8:9], exec
	v_sub_u32_e32 v1, 9, v2
	s_or_b64 exec, exec, s[10:11]
	s_and_b64 s[10:11], s[8:9], exec

.LBB0_3178:
	s_lshl_b32 s4, s2, 6
	s_ashr_i32 s5, s4, 31
	s_lshl_b64 s[6:7], s[4:5], 1
	v_lshlrev_b32_e32 v0, 3, v74
	s_add_u32 s6, s18, s6
	v_and_b32_e32 v5, 56, v0
	s_addc_u32 s7, s19, s7
	v_lshlrev_b32_e32 v6, 1, v5
	v_mov_b32_e32 v7, 0
	v_lshl_add_u64 v[0:1], s[6:7], 0, v[6:7]
	s_mov_b64 s[6:7], 0x7552000
	v_lshl_add_u64 v[8:9], v[0:1], 0, s[6:7]
	v_ashrrev_i32_e32 v6, 3, v74
	s_movk_i32 s5, 0x6000
	v_mad_i64_i32 v[0:1], s[6:7], v6, s5, v[8:9]
	s_waitcnt lgkmcnt(0)
	s_barrier
	global_load_dwordx4 v[0:3], v[0:1], off
	v_add_u32_e32 v12, 0x200, v74
	v_mul_u32_u24_e32 v5, 0x210, v5
	v_ashrrev_i32_e32 v13, 3, v12
	v_lshl_add_u32 v6, v6, 1, v5
	v_mad_i64_i32 v[10:11], s[6:7], v13, s5, v[8:9]
	v_lshl_add_u32 v13, v13, 1, v5
	s_waitcnt vmcnt(0) lgkmcnt(0)
	ds_write_b16 v6, v0
	ds_write_b16_d16_hi v6, v0 offset:528
	ds_write_b16 v6, v1 offset:1056
	ds_write_b16_d16_hi v6, v1 offset:1584
	ds_write_b16 v6, v2 offset:2112
	ds_write_b16_d16_hi v6, v2 offset:2640
	ds_write_b16 v6, v3 offset:3168
	ds_write_b16_d16_hi v6, v3 offset:3696
	global_load_dwordx4 v[0:3], v[10:11], off
	v_add_u32_e32 v6, 0x400, v74
	v_ashrrev_i32_e32 v14, 3, v6
	v_mad_i64_i32 v[10:11], s[6:7], v14, s5, v[8:9]
	v_ashrrev_i32_e32 v6, 5, v6
	s_waitcnt vmcnt(0) lgkmcnt(0)
	ds_write_b16 v13, v0
	ds_write_b16_d16_hi v13, v0 offset:528
	ds_write_b16 v13, v1 offset:1056
	ds_write_b16_d16_hi v13, v1 offset:1584
	ds_write_b16 v13, v2 offset:2112
	ds_write_b16_d16_hi v13, v2 offset:2640
	ds_write_b16 v13, v3 offset:3168
	ds_write_b16_d16_hi v13, v3 offset:3696
	global_load_dwordx4 v[0:3], v[10:11], off
	v_add_u32_e32 v13, 0x600, v74
	v_ashrrev_i32_e32 v18, 3, v13
	v_lshl_add_u32 v10, v14, 1, v5
	v_mad_i64_i32 v[8:9], s[6:7], v18, s5, v[8:9]
	s_movk_i32 s5, 0x210
	v_ashrrev_i32_e32 v20, 5, v13
	s_mov_b32 s7, 0x20000
	s_brev_b32 s6, -2
	s_waitcnt vmcnt(0) lgkmcnt(0)
	ds_write_b16 v10, v0
	ds_write_b16_d16_hi v10, v0 offset:528
	ds_write_b16 v10, v1 offset:1056
	ds_write_b16_d16_hi v10, v1 offset:1584
	ds_write_b16 v10, v2 offset:2112
	ds_write_b16_d16_hi v10, v2 offset:2640
	ds_write_b16 v10, v3 offset:3168
	ds_write_b16_d16_hi v10, v3 offset:3696
	global_load_dwordx4 v[8:11], v[8:9], off
	v_lshlrev_b32_e32 v0, 4, v74
	v_ashrrev_i32_e32 v1, 5, v74
	v_and_b32_e32 v2, 0x1f0, v0
	v_ashrrev_i32_e32 v3, 5, v12
	v_mad_u64_u32 v[12:13], s[8:9], v1, s5, v[2:3]
	v_add_u32_e32 v19, s4, v1
	v_or_b32_e32 v21, 0x600, v2
	v_add_u32_e32 v1, s4, v3
	v_mad_u64_u32 v[14:15], s[8:9], v3, s5, v[2:3]
	v_add_u32_e32 v13, s4, v6
	v_mad_u64_u32 v[16:17], s[8:9], v6, s5, v[2:3]
	v_add_u32_e32 v6, s4, v20
	v_mad_u64_u32 v[2:3], s[4:5], v20, s5, v[2:3]
	v_lshl_add_u32 v3, v18, 1, v5
	v_lshl_or_b32 v5, v19, 11, v21
	v_lshl_or_b32 v1, v1, 11, v21
	v_lshl_or_b32 v24, v13, 11, v21
	v_lshl_or_b32 v6, v6, 11, v21
	s_add_u32 s4, s18, 0x4552000
	s_addc_u32 s5, s19, 0
	s_and_b32 s5, s5, 0xffff
	s_waitcnt vmcnt(0) lgkmcnt(0)
	ds_write_b16 v3, v8
	ds_write_b16_d16_hi v3, v8 offset:528
	ds_write_b16 v3, v9 offset:1056
	ds_write_b16_d16_hi v3, v9 offset:1584
	ds_write_b16 v3, v10 offset:2112
	ds_write_b16_d16_hi v3, v10 offset:2640
	ds_write_b16 v3, v11 offset:3168
	ds_write_b16_d16_hi v3, v11 offset:3696
	s_waitcnt lgkmcnt(0)
	s_barrier
	ds_read_b128 v[8:11], v12
	ds_read_b128 v[12:15], v14
	ds_read_b128 v[16:19], v16
	ds_read_b128 v[20:23], v2
	s_waitcnt lgkmcnt(3)
	buffer_store_dwordx4 v[8:11], v5, s[4:7], 0 offen sc1
	s_waitcnt lgkmcnt(2)
	buffer_store_dwordx4 v[12:15], v1, s[4:7], 0 offen sc1
	s_waitcnt lgkmcnt(1)
	buffer_store_dwordx4 v[16:19], v24, s[4:7], 0 offen sc1
	s_waitcnt lgkmcnt(0)
	buffer_store_dwordx4 v[20:23], v6, s[4:7], 0 offen sc1
	s_waitcnt vmcnt(0)
	v_cmp_eq_u32_e64 s[4:5], 0, v75
	s_and_saveexec_b64 s[6:7], s[4:5]
	s_cbranch_execz .LBB0_3180
	s_lshl_b32 s8, s2, 4
	s_andn2_b32 s8, s8, 63
	s_ashr_i32 s9, s8, 31
	s_lshl_b64 s[8:9], s[8:9], 2
	s_add_u32 s8, s16, s8
	s_addc_u32 s9, s17, s9
	v_mov_b32_e32 v1, 1
	v_mov_b64_e32 v[2:3], s[8:9]
	flat_atomic_add v[2:3], v1
.LBB0_3180:
	s_or_b64 exec, exec, s[6:7]
	s_mul_i32 s6, s2, 40
	s_ashr_i32 s7, s6, 31
	v_ashrrev_i32_e32 v5, 31, v4
	v_lshlrev_b32_e32 v6, 3, v75
	v_lshl_add_u64 v[4:5], s[6:7], 0, v[4:5]
	v_lshl_add_u64 v[2:3], s[18:19], 0, v[6:7]
	s_mov_b64 s[6:7], 0x6952000
	v_lshl_add_u64 v[16:17], v[2:3], 0, s[6:7]
	s_mov_b64 s[6:7], 0x6f52000
	v_lshl_add_u64 v[18:19], v[2:3], 0, s[6:7]
	s_mov_b64 s[6:7], 0xcb32000
	v_lshlrev_b64 v[8:9], 9, v[4:5]
	v_lshl_add_u64 v[2:3], v[2:3], 0, s[6:7]
	v_lshl_add_u64 v[10:11], v[16:17], 0, v[8:9]
	v_lshl_add_u64 v[12:13], v[18:19], 0, v[8:9]
	v_lshl_add_u64 v[8:9], v[2:3], 0, v[8:9]
	global_load_dwordx2 v[34:35], v[10:11], off
	global_load_dwordx2 v[36:37], v[12:13], off
	global_load_dwordx2 v[38:39], v[8:9], off
	s_ashr_i32 s7, s24, 31
	s_add_u32 s6, s0, s24
	s_addc_u32 s7, s1, s7
	s_load_dwordx2 s[6:7], s[6:7], 0xb8
	v_lshl_add_u64 v[14:15], v[4:5], 0, 8
	v_and_b32_e32 v70, 0xf0, v0
	v_lshl_add_u64 v[12:13], v[4:5], 0, 16
	v_lshl_add_u64 v[10:11], v[4:5], 0, 24
	v_lshl_add_u64 v[8:9], v[4:5], 0, 32
	v_lshlrev_b64 v[0:1], 9, v[14:15]
	v_lshlrev_b64 v[20:21], 9, v[12:13]
	v_lshlrev_b64 v[22:23], 9, v[10:11]
	v_lshlrev_b64 v[24:25], 9, v[8:9]
	v_lshl_add_u64 v[40:41], v[16:17], 0, v[0:1]
	v_lshl_add_u64 v[42:43], v[18:19], 0, v[0:1]
	v_lshl_add_u64 v[44:45], v[2:3], 0, v[0:1]
	v_lshl_add_u64 v[46:47], v[16:17], 0, v[20:21]
	v_lshl_add_u64 v[48:49], v[18:19], 0, v[20:21]
	v_lshl_add_u64 v[50:51], v[2:3], 0, v[20:21]
	v_lshl_add_u64 v[52:53], v[16:17], 0, v[22:23]
	v_lshl_add_u64 v[54:55], v[18:19], 0, v[22:23]
	v_lshl_add_u64 v[56:57], v[2:3], 0, v[22:23]
	v_lshl_add_u64 v[58:59], v[16:17], 0, v[24:25]
	v_lshl_add_u64 v[60:61], v[18:19], 0, v[24:25]
	v_lshl_add_u64 v[62:63], v[2:3], 0, v[24:25]
	global_load_dwordx2 v[64:65], v[40:41], off
	s_waitcnt lgkmcnt(0)
	global_load_dwordx4 v[0:3], v70, s[6:7] offset:256
	global_load_dwordx2 v[66:67], v[42:43], off
	global_load_dwordx2 v[68:69], v[44:45], off
	global_load_dwordx2 v[30:31], v[46:47], off
	global_load_dwordx2 v[32:33], v[48:49], off
	global_load_dwordx2 v[28:29], v[50:51], off
	global_load_dwordx2 v[24:25], v[52:53], off
	global_load_dwordx2 v[26:27], v[54:55], off
	global_load_dwordx2 v[22:23], v[56:57], off
	global_load_dwordx2 v[18:19], v[58:59], off
	global_load_dwordx2 v[20:21], v[60:61], off
	global_load_dwordx2 v[16:17], v[62:63], off
	s_mov_b32 s13, 0x800000
	s_mov_b32 s12, 0x3c800000
	s_waitcnt vmcnt(0)
	v_lshlrev_b32_e32 v40, 16, v34
	v_lshlrev_b32_e32 v42, 16, v36
	v_and_b32_e32 v41, 0xffff0000, v34
	v_and_b32_e32 v43, 0xffff0000, v36
	v_lshlrev_b32_e32 v34, 16, v35
	v_lshlrev_b32_e32 v36, 16, v37
	v_and_b32_e32 v35, 0xffff0000, v35
	v_and_b32_e32 v37, 0xffff0000, v37
	v_lshlrev_b32_e32 v44, 16, v38
	v_and_b32_e32 v45, 0xffff0000, v38
	v_pk_add_f32 v[34:35], v[34:35], v[36:37]
	v_mul_f32_e32 v36, 0xbfb8aa3b, v44
	v_mul_f32_e32 v37, 0xbfb8aa3b, v45
	v_exp_f32_e32 v36, v36
	v_exp_f32_e32 v37, v37
	v_lshlrev_b32_e32 v46, 16, v39
	v_and_b32_e32 v47, 0xffff0000, v39
	v_pk_add_f32 v[38:39], v[40:41], v[42:43]
	v_pk_add_f32 v[36:37], v[36:37], 1.0 op_sel_hi:[1,0]
	v_pk_mul_f32 v[42:43], v[38:39], v[38:39]
	v_div_scale_f32 v48, s[6:7], v37, v37, v45
	v_rcp_f32_e32 v51, v48
	v_div_scale_f32 v50, s[6:7], v36, v36, v44
	v_pk_mul_f32 v[40:41], v[34:35], v[34:35]
	v_rcp_f32_e32 v52, v50
	v_add_f32_e32 v42, v42, v43
	v_add_f32_e32 v40, v42, v40
	v_fma_f32 v54, -v48, v51, 1.0
	v_add_f32_e32 v40, v41, v40
	v_div_scale_f32 v49, vcc, v45, v37, v45
	v_fmac_f32_e32 v51, v54, v51
	v_add_f32_dpp v40, v40, v40 quad_perm:[1,0,3,2] row_mask:0xf bank_mask:0xf bound_ctrl:1
	v_fma_f32 v55, -v50, v52, 1.0
	v_mul_f32_e32 v54, v49, v51
	v_add_f32_dpp v40, v40, v40 quad_perm:[2,3,0,1] row_mask:0xf bank_mask:0xf bound_ctrl:1
	v_div_scale_f32 v53, s[6:7], v44, v36, v44
	v_fmac_f32_e32 v52, v55, v52
	v_fma_f32 v56, -v48, v54, v49
	v_add_f32_dpp v40, v40, v40 row_half_mirror row_mask:0xf bank_mask:0xf bound_ctrl:1
	v_mul_f32_e32 v55, v53, v52
	v_fmac_f32_e32 v54, v56, v51
	v_add_f32_dpp v40, v40, v40 row_mirror row_mask:0xf bank_mask:0xf bound_ctrl:1
	v_mov_b32_e32 v41, 0x358637bd
	v_fma_f32 v57, -v50, v55, v53
	v_fma_f32 v48, -v48, v54, v49
	v_fmac_f32_e32 v41, 0x3c800000, v40
	v_fmac_f32_e32 v55, v57, v52
	v_div_fmas_f32 v48, v48, v51, v54
	v_mul_f32_e32 v40, 0x4b800000, v41
	v_cmp_gt_f32_e64 s[8:9], s13, v41
	v_div_fixup_f32 v37, v48, v37, v45
	v_fma_f32 v45, -v50, v55, v53
	v_cndmask_b32_e64 v40, v41, v40, s[8:9]
	s_mov_b64 vcc, s[6:7]
	v_rsq_f32_e32 v42, v40
	v_div_fmas_f32 v40, v45, v52, v55
	v_div_fixup_f32 v36, v40, v36, v44
	v_mul_f32_e32 v40, 0xbfb8aa3b, v46
	v_mul_f32_e32 v41, 0xbfb8aa3b, v47
	v_exp_f32_e32 v40, v40
	v_exp_f32_e32 v41, v41
	v_mul_f32_e32 v43, 0x45800000, v42
	v_cndmask_b32_e64 v42, v42, v43, s[8:9]
	v_pk_mul_f32 v[38:39], v[38:39], v[42:43] op_sel_hi:[1,0]
	v_pk_add_f32 v[40:41], v[40:41], 1.0 op_sel_hi:[1,0]
	v_pk_mul_f32 v[38:39], v[0:1], v[38:39]
	v_div_scale_f32 v43, s[6:7], v41, v41, v47
	v_rcp_f32_e32 v44, v43
	v_pk_mul_f32 v[36:37], v[36:37], v[38:39]
	v_pk_mul_f32 v[34:35], v[34:35], v[42:43] op_sel_hi:[1,0]
	v_cvt_pk_bf16_f32 v36, v36, v37
	v_fma_f32 v38, -v43, v44, 1.0
	v_fmac_f32_e32 v44, v38, v44
	v_div_scale_f32 v38, vcc, v47, v41, v47
	v_mul_f32_e32 v39, v38, v44
	v_fma_f32 v42, -v43, v39, v38
	v_fmac_f32_e32 v39, v42, v44
	v_div_scale_f32 v42, s[6:7], v40, v40, v46
	v_fma_f32 v38, -v43, v39, v38
	v_rcp_f32_e32 v43, v42
	v_div_fmas_f32 v38, v38, v44, v39
	v_div_fixup_f32 v39, v38, v41, v47
	v_pk_mul_f32 v[34:35], v[2:3], v[34:35]
	v_fma_f32 v38, -v42, v43, 1.0
	v_fmac_f32_e32 v43, v38, v43
	v_div_scale_f32 v38, vcc, v46, v40, v46
	v_mul_f32_e32 v41, v38, v43
	v_fma_f32 v44, -v42, v41, v38
	v_fmac_f32_e32 v41, v44, v43
	v_fma_f32 v38, -v42, v41, v38
	v_div_fmas_f32 v38, v38, v43, v41
	v_div_fixup_f32 v38, v38, v40, v46
	s_waitcnt lgkmcnt(0)
	v_lshlrev_b32_e32 v46, 16, v68
	v_and_b32_e32 v44, 0xffff0000, v68
	v_mul_f32_e32 v42, 0xbfb8aa3b, v46
	v_mul_f32_e32 v43, 0xbfb8aa3b, v44
	v_exp_f32_e32 v42, v42
	v_exp_f32_e32 v43, v43
	v_pk_mul_f32 v[34:35], v[38:39], v[34:35]
	v_lshlrev_b32_e32 v38, 16, v65
	v_lshlrev_b32_e32 v40, 16, v67
	v_and_b32_e32 v39, 0xffff0000, v65
	v_and_b32_e32 v41, 0xffff0000, v67
	v_pk_add_f32 v[38:39], v[38:39], v[40:41]
	v_pk_add_f32 v[40:41], v[42:43], 1.0 op_sel_hi:[1,0]
	v_cvt_pk_bf16_f32 v37, v34, v35
	v_div_scale_f32 v45, s[6:7], v41, v41, v44
	v_lshlrev_b64 v[34:35], 11, v[4:5]
	v_rcp_f32_e32 v49, v45
	v_lshl_add_u64 v[34:35], s[18:19], 0, v[34:35]
	v_lshl_add_u64 v[34:35], v[34:35], 0, v[6:7]
	s_mov_b32 s8, 0x4552000
	v_add_co_u32_e32 v34, vcc, s8, v34
	v_fma_f32 v50, -v45, v49, 1.0
	s_nop 0
	v_addc_co_u32_e32 v35, vcc, 0, v35, vcc
	v_fmac_f32_e32 v49, v50, v49
	v_div_scale_f32 v50, vcc, v44, v41, v44
	v_mul_f32_e32 v51, v50, v49
	v_fma_f32 v52, -v45, v51, v50
	v_fmac_f32_e32 v51, v52, v49
	v_fma_f32 v45, -v45, v51, v50
	v_div_scale_f32 v50, s[6:7], v40, v40, v46
	v_rcp_f32_e32 v52, v50
	v_div_fmas_f32 v45, v45, v49, v51
	v_lshlrev_b32_e32 v47, 16, v69
	v_and_b32_e32 v48, 0xffff0000, v69
	v_div_fixup_f32 v41, v45, v41, v44
	v_fma_f32 v44, -v50, v52, 1.0
	v_fmac_f32_e32 v52, v44, v52
	v_mul_f32_e32 v44, 0xbfb8aa3b, v47
	v_mul_f32_e32 v45, 0xbfb8aa3b, v48
	v_exp_f32_e32 v44, v44
	v_exp_f32_e32 v45, v45
	v_div_scale_f32 v49, vcc, v46, v40, v46
	v_mul_f32_e32 v51, v49, v52
	v_fma_f32 v53, -v50, v51, v49
	v_fmac_f32_e32 v51, v53, v52
	v_pk_add_f32 v[44:45], v[44:45], 1.0 op_sel_hi:[1,0]
	v_fma_f32 v49, -v50, v51, v49
	v_div_scale_f32 v50, s[6:7], v45, v45, v48
	v_rcp_f32_e32 v53, v50
	v_div_fmas_f32 v49, v49, v52, v51
	v_div_fixup_f32 v40, v49, v40, v46
	v_lshlrev_b32_e32 v54, 16, v28
	v_fma_f32 v46, -v50, v53, 1.0
	v_fmac_f32_e32 v53, v46, v53
	v_div_scale_f32 v46, vcc, v48, v45, v48
	v_mul_f32_e32 v49, v46, v53
	v_fma_f32 v51, -v50, v49, v46
	v_fmac_f32_e32 v49, v51, v53
	v_fma_f32 v46, -v50, v49, v46
	v_div_scale_f32 v50, s[6:7], v44, v44, v47
	v_rcp_f32_e32 v51, v50
	v_div_fmas_f32 v46, v46, v53, v49
	v_div_fixup_f32 v45, v46, v45, v48
	v_and_b32_e32 v55, 0xffff0000, v28
	v_fma_f32 v46, -v50, v51, 1.0
	v_fmac_f32_e32 v51, v46, v51
	v_div_scale_f32 v46, vcc, v47, v44, v47
	v_mul_f32_e32 v28, 0xbfb8aa3b, v54
	v_mul_f32_e32 v48, v46, v51
	v_exp_f32_e32 v52, v28
	v_mul_f32_e32 v28, 0xbfb8aa3b, v55
	v_fma_f32 v49, -v50, v48, v46
	v_exp_f32_e32 v53, v28
	v_fmac_f32_e32 v48, v49, v51
	v_fma_f32 v46, -v50, v48, v46
	v_div_fmas_f32 v46, v46, v51, v48
	v_lshlrev_b32_e32 v48, 16, v30
	v_lshlrev_b32_e32 v50, 16, v32
	v_and_b32_e32 v49, 0xffff0000, v30
	v_and_b32_e32 v51, 0xffff0000, v32
	v_lshlrev_b32_e32 v30, 16, v31
	v_lshlrev_b32_e32 v32, 16, v33
	v_and_b32_e32 v31, 0xffff0000, v31
	v_and_b32_e32 v33, 0xffff0000, v33
	v_pk_add_f32 v[30:31], v[30:31], v[32:33]
	v_pk_add_f32 v[32:33], v[52:53], 1.0 op_sel_hi:[1,0]
	flat_store_dwordx2 v[34:35], v[36:37] offset:1024 sc1
	v_div_scale_f32 v52, s[6:7], v33, v33, v55
	v_rcp_f32_e32 v53, v52
	v_lshlrev_b32_e32 v34, 16, v64
	v_lshlrev_b32_e32 v36, 16, v66
	v_and_b32_e32 v35, 0xffff0000, v64
	v_fma_f32 v58, -v52, v53, 1.0
	v_fmac_f32_e32 v53, v58, v53
	v_div_scale_f32 v58, vcc, v55, v33, v55
	v_mul_f32_e32 v59, v58, v53
	v_fma_f32 v60, -v52, v59, v58
	v_fmac_f32_e32 v59, v60, v53
	v_fma_f32 v52, -v52, v59, v58
	v_div_scale_f32 v58, s[6:7], v32, v32, v54
	v_rcp_f32_e32 v60, v58
	v_div_fmas_f32 v52, v52, v53, v59
	v_div_fixup_f32 v33, v52, v33, v55
	v_and_b32_e32 v37, 0xffff0000, v66
	v_fma_f32 v52, -v58, v60, 1.0
	v_fmac_f32_e32 v60, v52, v60
	v_div_scale_f32 v52, vcc, v54, v32, v54
	v_mul_f32_e32 v55, v52, v60
	v_pk_add_f32 v[34:35], v[34:35], v[36:37]
	v_pk_add_f32 v[48:49], v[48:49], v[50:51]
	v_fma_f32 v53, -v58, v55, v52
	v_pk_mul_f32 v[36:37], v[34:35], v[34:35]
	v_pk_mul_f32 v[50:51], v[48:49], v[48:49]
	v_fmac_f32_e32 v55, v53, v60
	v_pk_mul_f32 v[42:43], v[38:39], v[38:39]
	v_lshlrev_b32_e32 v56, 16, v29
	v_and_b32_e32 v57, 0xffff0000, v29
	v_pk_mul_f32 v[28:29], v[30:31], v[30:31]
	v_fma_f32 v58, -v58, v55, v52
	v_mov_b32_e32 v52, v50
	v_mov_b32_e32 v53, v36
	v_mov_b32_e32 v36, v51
	v_pk_add_f32 v[36:37], v[52:53], v[36:37]
	v_mov_b32_e32 v50, v28
	v_mov_b32_e32 v51, v42
	v_pk_add_f32 v[36:37], v[36:37], v[50:51]
	v_mov_b32_e32 v42, v29
	v_pk_add_f32 v[28:29], v[42:43], v[36:37]
	s_mov_b32 s6, 0x358637bd
	v_div_fixup_f32 v44, v46, v44, v47
	v_mov_b32_dpp v37, v29 quad_perm:[1,0,3,2] row_mask:0xf bank_mask:0xf bound_ctrl:1
	v_mov_b32_dpp v36, v28 quad_perm:[1,0,3,2] row_mask:0xf bank_mask:0xf bound_ctrl:1
	v_pk_add_f32 v[28:29], v[28:29], v[36:37]
	v_lshlrev_b64 v[46:47], 11, v[14:15]
	v_lshl_add_u64 v[46:47], s[18:19], 0, v[46:47]
	v_mov_b32_dpp v37, v29 quad_perm:[2,3,0,1] row_mask:0xf bank_mask:0xf bound_ctrl:1
	v_mov_b32_dpp v36, v28 quad_perm:[2,3,0,1] row_mask:0xf bank_mask:0xf bound_ctrl:1
	v_pk_add_f32 v[28:29], v[28:29], v[36:37]
	v_lshl_add_u64 v[46:47], v[46:47], 0, v[6:7]
	s_nop 0
	v_mov_b32_dpp v37, v29 row_half_mirror row_mask:0xf bank_mask:0xf bound_ctrl:1
	v_mov_b32_dpp v36, v28 row_half_mirror row_mask:0xf bank_mask:0xf bound_ctrl:1
	v_pk_add_f32 v[28:29], v[28:29], v[36:37]
	s_nop 1
	v_mov_b32_dpp v37, v29 row_mirror row_mask:0xf bank_mask:0xf bound_ctrl:1
	v_mov_b32_dpp v36, v28 row_mirror row_mask:0xf bank_mask:0xf bound_ctrl:1
	v_pk_add_f32 v[36:37], v[28:29], v[36:37]
	v_mov_b64_e32 v[28:29], s[6:7]
	v_pk_fma_f32 v[36:37], v[36:37], s[12:13], v[28:29] op_sel_hi:[1,0,0]
	s_nop 0
	v_mul_f32_e32 v42, 0x4b800000, v37
	v_cmp_gt_f32_e64 s[6:7], s13, v37
	s_nop 1
	v_cndmask_b32_e64 v37, v37, v42, s[6:7]
	v_rsq_f32_e32 v37, v37
	v_div_fmas_f32 v42, v58, v60, v55
	v_div_fixup_f32 v32, v42, v32, v54
	v_cmp_gt_f32_e32 vcc, s13, v36
	v_mul_f32_e32 v42, 0x45800000, v37
	v_cndmask_b32_e64 v42, v37, v42, s[6:7]
	v_pk_mul_f32 v[34:35], v[34:35], v[42:43] op_sel_hi:[1,0]
	v_pk_mul_f32 v[38:39], v[38:39], v[42:43] op_sel_hi:[1,0]
	v_pk_mul_f32 v[34:35], v[0:1], v[34:35]
	v_pk_mul_f32 v[38:39], v[2:3], v[38:39]
	v_mul_f32_e32 v37, 0x4b800000, v36
	v_pk_mul_f32 v[34:35], v[40:41], v[34:35]
	v_pk_mul_f32 v[38:39], v[44:45], v[38:39]
	v_cndmask_b32_e32 v36, v36, v37, vcc
	v_cvt_pk_bf16_f32 v34, v34, v35
	v_cvt_pk_bf16_f32 v35, v38, v39
	v_rsq_f32_e32 v38, v36
	v_add_co_u32_e64 v36, s[6:7], s8, v46
	v_lshlrev_b32_e32 v44, 16, v16
	s_nop 0
	v_addc_co_u32_e64 v37, s[6:7], 0, v47, s[6:7]
	flat_store_dwordx2 v[36:37], v[34:35] offset:1024 sc1
	v_mul_f32_e32 v34, 0xbfb8aa3b, v56
	v_mul_f32_e32 v35, 0xbfb8aa3b, v57
	v_exp_f32_e32 v34, v34
	v_exp_f32_e32 v35, v35
	v_mul_f32_e32 v36, 0x45800000, v38
	v_cndmask_b32_e32 v36, v38, v36, vcc
	v_pk_mul_f32 v[38:39], v[48:49], v[36:37] op_sel_hi:[1,0]
	v_pk_add_f32 v[34:35], v[34:35], 1.0 op_sel_hi:[1,0]
	v_pk_mul_f32 v[38:39], v[0:1], v[38:39]
	v_div_scale_f32 v37, s[6:7], v35, v35, v57
	v_rcp_f32_e32 v40, v37
	v_pk_mul_f32 v[30:31], v[30:31], v[36:37] op_sel_hi:[1,0]
	v_pk_mul_f32 v[32:33], v[32:33], v[38:39]
	v_pk_mul_f32 v[30:31], v[2:3], v[30:31]
	v_fma_f32 v36, -v37, v40, 1.0
	v_fmac_f32_e32 v40, v36, v40
	v_div_scale_f32 v36, vcc, v57, v35, v57
	v_mul_f32_e32 v38, v36, v40
	v_fma_f32 v39, -v37, v38, v36
	v_fmac_f32_e32 v38, v39, v40
	v_fma_f32 v36, -v37, v38, v36
	v_div_scale_f32 v37, s[6:7], v34, v34, v56
	v_rcp_f32_e32 v39, v37
	v_div_fmas_f32 v36, v36, v40, v38
	v_div_fixup_f32 v35, v36, v35, v57
	v_cvt_pk_bf16_f32 v32, v32, v33
	v_fma_f32 v36, -v37, v39, 1.0
	v_fmac_f32_e32 v39, v36, v39
	v_div_scale_f32 v36, vcc, v56, v34, v56
	v_mul_f32_e32 v38, v36, v39
	v_fma_f32 v40, -v37, v38, v36
	v_fmac_f32_e32 v38, v40, v39
	v_fma_f32 v36, -v37, v38, v36
	v_div_fmas_f32 v36, v36, v39, v38
	v_div_fixup_f32 v34, v36, v34, v56
	v_pk_mul_f32 v[30:31], v[34:35], v[30:31]
	v_lshlrev_b32_e32 v36, 16, v22
	v_cvt_pk_bf16_f32 v33, v30, v31
	v_lshlrev_b64 v[30:31], 11, v[12:13]
	v_and_b32_e32 v37, 0xffff0000, v22
	v_mul_f32_e32 v22, 0xbfb8aa3b, v36
	v_lshl_add_u64 v[30:31], s[18:19], 0, v[30:31]
	v_exp_f32_e32 v34, v22
	v_mul_f32_e32 v22, 0xbfb8aa3b, v37
	v_lshl_add_u64 v[30:31], v[30:31], 0, v[6:7]
	v_exp_f32_e32 v35, v22
	v_add_co_u32_e32 v30, vcc, s8, v30
	v_lshlrev_b32_e32 v38, 16, v23
	s_nop 0
	v_addc_co_u32_e32 v31, vcc, 0, v31, vcc
	flat_store_dwordx2 v[30:31], v[32:33] offset:1024 sc1
	v_lshlrev_b32_e32 v30, 16, v24
	v_lshlrev_b32_e32 v32, 16, v26
	v_and_b32_e32 v31, 0xffff0000, v24
	v_and_b32_e32 v33, 0xffff0000, v26
	v_lshlrev_b32_e32 v24, 16, v25
	v_lshlrev_b32_e32 v26, 16, v27
	v_and_b32_e32 v25, 0xffff0000, v25
	v_and_b32_e32 v27, 0xffff0000, v27
	v_and_b32_e32 v39, 0xffff0000, v23
	v_pk_add_f32 v[22:23], v[24:25], v[26:27]
	v_pk_add_f32 v[24:25], v[34:35], 1.0 op_sel_hi:[1,0]
	v_and_b32_e32 v45, 0xffff0000, v16
	v_div_scale_f32 v34, s[6:7], v25, v25, v37
	v_rcp_f32_e32 v35, v34
	v_mul_f32_e32 v16, 0xbfb8aa3b, v44
	v_lshlrev_b32_e32 v46, 16, v17
	v_and_b32_e32 v47, 0xffff0000, v17
	v_fma_f32 v40, -v34, v35, 1.0
	v_fmac_f32_e32 v35, v40, v35
	v_div_scale_f32 v40, vcc, v37, v25, v37
	v_mul_f32_e32 v41, v40, v35
	v_fma_f32 v42, -v34, v41, v40
	v_fmac_f32_e32 v41, v42, v35
	v_fma_f32 v34, -v34, v41, v40
	v_div_scale_f32 v40, s[6:7], v24, v24, v36
	v_rcp_f32_e32 v42, v40
	v_div_fmas_f32 v34, v34, v35, v41
	v_div_fixup_f32 v25, v34, v25, v37
	v_mul_f32_e32 v35, 0xbfb8aa3b, v39
	v_fma_f32 v34, -v40, v42, 1.0
	v_fmac_f32_e32 v42, v34, v42
	v_mul_f32_e32 v34, 0xbfb8aa3b, v38
	v_exp_f32_e32 v34, v34
	v_exp_f32_e32 v35, v35
	v_div_scale_f32 v37, vcc, v36, v24, v36
	v_mul_f32_e32 v41, v37, v42
	v_fma_f32 v43, -v40, v41, v37
	v_fmac_f32_e32 v41, v43, v42
	v_pk_add_f32 v[34:35], v[34:35], 1.0 op_sel_hi:[1,0]
	v_fma_f32 v37, -v40, v41, v37
	v_div_scale_f32 v40, s[6:7], v35, v35, v39
	v_rcp_f32_e32 v43, v40
	v_div_fmas_f32 v37, v37, v42, v41
	v_div_fixup_f32 v24, v37, v24, v36
	v_exp_f32_e32 v42, v16
	v_fma_f32 v36, -v40, v43, 1.0
	v_fmac_f32_e32 v43, v36, v43
	v_div_scale_f32 v36, vcc, v39, v35, v39
	v_mul_f32_e32 v37, v36, v43
	v_fma_f32 v41, -v40, v37, v36
	v_fmac_f32_e32 v37, v41, v43
	v_fma_f32 v36, -v40, v37, v36
	v_div_scale_f32 v40, s[6:7], v34, v34, v38
	v_rcp_f32_e32 v41, v40
	v_div_fmas_f32 v36, v36, v43, v37
	v_div_fixup_f32 v35, v36, v35, v39
	v_mul_f32_e32 v16, 0xbfb8aa3b, v45
	v_fma_f32 v36, -v40, v41, 1.0
	v_fmac_f32_e32 v41, v36, v41
	v_div_scale_f32 v36, vcc, v38, v34, v38
	v_mul_f32_e32 v37, v36, v41
	v_fma_f32 v39, -v40, v37, v36
	v_fmac_f32_e32 v37, v39, v41
	v_exp_f32_e32 v43, v16
	v_fma_f32 v36, -v40, v37, v36
	v_div_fmas_f32 v36, v36, v41, v37
	v_div_fixup_f32 v34, v36, v34, v38
	v_lshlrev_b32_e32 v38, 16, v18
	v_lshlrev_b32_e32 v40, 16, v20
	v_and_b32_e32 v39, 0xffff0000, v18
	v_and_b32_e32 v41, 0xffff0000, v20
	v_lshlrev_b32_e32 v18, 16, v19
	v_lshlrev_b32_e32 v20, 16, v21
	v_and_b32_e32 v19, 0xffff0000, v19
	v_and_b32_e32 v21, 0xffff0000, v21
	v_pk_add_f32 v[16:17], v[18:19], v[20:21]
	v_pk_add_f32 v[18:19], v[42:43], 1.0 op_sel_hi:[1,0]
	v_pk_add_f32 v[30:31], v[30:31], v[32:33]
	v_div_scale_f32 v42, s[6:7], v19, v19, v45
	v_rcp_f32_e32 v43, v42
	v_pk_add_f32 v[38:39], v[38:39], v[40:41]
	v_pk_mul_f32 v[32:33], v[30:31], v[30:31]
	v_pk_mul_f32 v[40:41], v[38:39], v[38:39]
	v_fma_f32 v48, -v42, v43, 1.0
	v_fmac_f32_e32 v43, v48, v43
	v_div_scale_f32 v48, vcc, v45, v19, v45
	v_mul_f32_e32 v49, v48, v43
	v_fma_f32 v50, -v42, v49, v48
	v_fmac_f32_e32 v49, v50, v43
	v_fma_f32 v42, -v42, v49, v48
	v_div_scale_f32 v48, s[6:7], v18, v18, v44
	v_rcp_f32_e32 v50, v48
	v_div_fmas_f32 v42, v42, v43, v49
	v_div_fixup_f32 v19, v42, v19, v45
	v_pk_mul_f32 v[26:27], v[22:23], v[22:23]
	v_fma_f32 v42, -v48, v50, 1.0
	v_fmac_f32_e32 v50, v42, v50
	v_div_scale_f32 v42, vcc, v44, v18, v44
	v_mul_f32_e32 v45, v42, v50
	v_fma_f32 v43, -v48, v45, v42
	v_fmac_f32_e32 v45, v43, v50
	v_pk_mul_f32 v[20:21], v[16:17], v[16:17]
	v_fma_f32 v48, -v48, v45, v42
	v_mov_b32_e32 v42, v40
	v_mov_b32_e32 v43, v32
	v_mov_b32_e32 v32, v41
	v_pk_add_f32 v[32:33], v[42:43], v[32:33]
	v_mov_b32_e32 v40, v20
	v_mov_b32_e32 v41, v26
	v_pk_add_f32 v[32:33], v[32:33], v[40:41]
	v_mov_b32_e32 v26, v21
	v_pk_add_f32 v[20:21], v[26:27], v[32:33]
	v_lshlrev_b64 v[36:37], 11, v[10:11]
	v_lshl_add_u64 v[36:37], s[18:19], 0, v[36:37]
	v_mov_b32_dpp v27, v21 quad_perm:[1,0,3,2] row_mask:0xf bank_mask:0xf bound_ctrl:1
	v_mov_b32_dpp v26, v20 quad_perm:[1,0,3,2] row_mask:0xf bank_mask:0xf bound_ctrl:1
	v_pk_add_f32 v[20:21], v[20:21], v[26:27]
	v_lshl_add_u64 v[36:37], v[36:37], 0, v[6:7]
	s_nop 0
	v_mov_b32_dpp v27, v21 quad_perm:[2,3,0,1] row_mask:0xf bank_mask:0xf bound_ctrl:1
	v_mov_b32_dpp v26, v20 quad_perm:[2,3,0,1] row_mask:0xf bank_mask:0xf bound_ctrl:1
	v_pk_add_f32 v[20:21], v[20:21], v[26:27]
	s_nop 1
	v_mov_b32_dpp v27, v21 row_half_mirror row_mask:0xf bank_mask:0xf bound_ctrl:1
	v_mov_b32_dpp v26, v20 row_half_mirror row_mask:0xf bank_mask:0xf bound_ctrl:1
	v_pk_add_f32 v[20:21], v[20:21], v[26:27]
	s_nop 1
	v_mov_b32_dpp v27, v21 row_mirror row_mask:0xf bank_mask:0xf bound_ctrl:1
	v_mov_b32_dpp v26, v20 row_mirror row_mask:0xf bank_mask:0xf bound_ctrl:1
	v_pk_add_f32 v[20:21], v[20:21], v[26:27]
	s_nop 0
	v_pk_fma_f32 v[20:21], v[20:21], s[12:13], v[28:29] op_sel_hi:[1,0,0]
	s_nop 0
	v_mul_f32_e32 v26, 0x4b800000, v21
	v_cmp_gt_f32_e64 s[6:7], s13, v21
	s_nop 1
	v_cndmask_b32_e64 v21, v21, v26, s[6:7]
	v_rsq_f32_e32 v21, v21
	v_div_fmas_f32 v26, v48, v50, v45
	v_div_fixup_f32 v18, v26, v18, v44
	v_cmp_gt_f32_e32 vcc, s13, v20
	v_mul_f32_e32 v26, 0x45800000, v21
	v_cndmask_b32_e64 v26, v21, v26, s[6:7]
	v_pk_mul_f32 v[28:29], v[30:31], v[26:27] op_sel_hi:[1,0]
	v_pk_mul_f32 v[22:23], v[22:23], v[26:27] op_sel_hi:[1,0]
	v_pk_mul_f32 v[28:29], v[0:1], v[28:29]
	v_pk_mul_f32 v[22:23], v[2:3], v[22:23]
	v_mul_f32_e32 v21, 0x4b800000, v20
	v_pk_mul_f32 v[24:25], v[24:25], v[28:29]
	v_pk_mul_f32 v[22:23], v[34:35], v[22:23]
	v_cndmask_b32_e32 v20, v20, v21, vcc
	v_cvt_pk_bf16_f32 v24, v24, v25
	v_cvt_pk_bf16_f32 v25, v22, v23
	v_rsq_f32_e32 v22, v20
	v_add_co_u32_e64 v20, s[6:7], s8, v36
	v_mul_f32_e32 v23, 0x45800000, v22
	s_nop 0
	v_addc_co_u32_e64 v21, s[6:7], 0, v37, s[6:7]
	flat_store_dwordx2 v[20:21], v[24:25] offset:1024 sc1
	v_mul_f32_e32 v20, 0xbfb8aa3b, v46
	v_mul_f32_e32 v21, 0xbfb8aa3b, v47
	v_exp_f32_e32 v20, v20
	v_exp_f32_e32 v21, v21
	v_cndmask_b32_e32 v22, v22, v23, vcc
	v_pk_mul_f32 v[24:25], v[38:39], v[22:23] op_sel_hi:[1,0]
	v_pk_add_f32 v[20:21], v[20:21], 1.0 op_sel_hi:[1,0]
	s_nop 0
	v_div_scale_f32 v23, s[6:7], v21, v21, v47
	v_pk_mul_f32 v[0:1], v[0:1], v[24:25]
	v_rcp_f32_e32 v24, v23
	v_pk_mul_f32 v[16:17], v[16:17], v[22:23] op_sel_hi:[1,0]
	v_pk_mul_f32 v[0:1], v[18:19], v[0:1]
	v_pk_mul_f32 v[2:3], v[2:3], v[16:17]
	v_fma_f32 v16, -v23, v24, 1.0
	v_fmac_f32_e32 v24, v16, v24
	v_div_scale_f32 v16, vcc, v47, v21, v47
	v_mul_f32_e32 v17, v16, v24
	v_fma_f32 v18, -v23, v17, v16
	v_fmac_f32_e32 v17, v18, v24
	v_div_scale_f32 v18, s[6:7], v20, v20, v46
	v_rcp_f32_e32 v19, v18
	v_fma_f32 v16, -v23, v17, v16
	v_div_fmas_f32 v16, v16, v24, v17
	v_div_fixup_f32 v17, v16, v21, v47
	v_fma_f32 v16, -v18, v19, 1.0
	v_fmac_f32_e32 v19, v16, v19
	v_div_scale_f32 v16, vcc, v46, v20, v46
	v_mul_f32_e32 v21, v16, v19
	v_fma_f32 v22, -v18, v21, v16
	v_fmac_f32_e32 v21, v22, v19
	v_fma_f32 v16, -v18, v21, v16
	v_div_fmas_f32 v16, v16, v19, v21
	v_div_fixup_f32 v16, v16, v20, v46
	v_pk_mul_f32 v[2:3], v[16:17], v[2:3]
	v_cvt_pk_bf16_f32 v0, v0, v1
	v_cvt_pk_bf16_f32 v1, v2, v3
	v_lshlrev_b64 v[2:3], 11, v[8:9]
	v_lshl_add_u64 v[2:3], s[18:19], 0, v[2:3]
	v_lshl_add_u64 v[2:3], v[2:3], 0, v[6:7]
	v_add_co_u32_e32 v2, vcc, 0x4552000, v2
	s_nop 1
	v_addc_co_u32_e32 v3, vcc, 0, v3, vcc
	flat_store_dwordx2 v[2:3], v[0:1] offset:1024 sc1
	s_waitcnt vmcnt(0)
	s_and_saveexec_b64 s[6:7], s[4:5]
	s_cbranch_execz .LBB0_3184
	v_alignbit_b32 v0, v15, v14, 8
	v_alignbit_b32 v1, v5, v4, 8
	v_cmp_eq_u32_e32 vcc, v0, v1
	v_alignbit_b32 v2, v13, v12, 8
	v_alignbit_b32 v3, v9, v8, 8
	v_cndmask_b32_e64 v0, 1, 2, vcc
	v_cmp_eq_u32_e32 vcc, v2, v1
	v_alignbit_b32 v2, v11, v10, 8
	s_mov_b64 s[4:5], s[10:11]
	v_addc_co_u32_e32 v0, vcc, 0, v0, vcc
	v_cmp_eq_u32_e32 vcc, v2, v1
	s_nop 1
	v_cndmask_b32_e64 v2, 0, 1, vcc
	v_cmp_eq_u32_e32 vcc, v3, v1
	s_nop 1
	v_addc_co_u32_e32 v2, vcc, v0, v2, vcc
	v_lshlrev_b32_e32 v0, 6, v1
	v_ashrrev_i32_e32 v1, 31, v0
	v_lshl_add_u64 v[4:5], v[0:1], 2, s[16:17]
	flat_atomic_add v[4:5], v2
	v_cmp_gt_u32_e32 vcc, 5, v2
	s_and_saveexec_b64 s[8:9], vcc
	v_sub_u32_e32 v1, 5, v2
	s_or_b64 s[4:5], s[10:11], exec
	s_or_b64 exec, exec, s[8:9]
	s_andn2_b64 s[8:9], s[10:11], exec
	s_and_b64 s[4:5], s[4:5], exec
	s_or_b64 s[10:11], s[8:9], s[4:5]

.LBB0_3319:
	v_ashrrev_i32_e32 v77, 31, v76
	v_lshlrev_b64 v[0:1], 12, v[76:77]
	v_lshl_add_u64 v[104:105], s[18:19], 0, v[0:1]
	v_add_u32_e32 v0, 0xfffff000, v76
	v_lshrrev_b32_e32 v0, 11, v0
	v_add_u32_e32 v0, 6, v0
	v_cmp_lt_i32_e32 vcc, s33, v76
	v_lshl_add_u64 v[8:9], v[104:105], 0, v[78:79]
	global_load_dwordx4 v[10:13], v[8:9], off offset:2048
	global_load_dwordx4 v[40:43], v[8:9], off offset:3072
	v_cndmask_b32_e32 v85, 5, v0, vcc
	v_mad_u64_u32 v[0:1], s[6:7], v85, s36, v[66:67]
	global_load_dwordx4 v[44:47], v[0:1], off
	global_load_dwordx4 v[48:51], v[64:65], off
	global_load_dwordx4 v[52:55], v[64:65], off offset:16
	global_load_dwordx4 v[92:95], v[0:1], off offset:16
	global_load_dwordx4 v[96:99], v[0:1], off offset:2048
	global_load_dwordx4 v[100:103], v[64:65], off offset:2048
	global_load_dwordx4 v[106:109], v[64:65], off offset:2064
	global_load_dwordx4 v[120:123], v[0:1], off offset:2064
	v_lshlrev_b64 v[0:1], 11, v[76:77]
	v_lshl_add_u64 v[0:1], v[62:63], 0, v[0:1]
	global_load_dwordx4 v[124:127], v[0:1], off
	global_load_dwordx4 v[128:131], v[0:1], off offset:1024
	v_add_u32_e32 v0, 1, v76
	v_ashrrev_i32_e32 v1, 31, v0
	v_lshlrev_b64 v[6:7], 12, v[0:1]
	v_lshlrev_b64 v[0:1], 11, v[0:1]
	v_lshl_add_u64 v[0:1], v[62:63], 0, v[0:1]
	global_load_dwordx4 v[132:135], v[0:1], off
	global_load_dwordx4 v[136:139], v[0:1], off offset:1024
	v_add_u32_e32 v2, 2, v76
	v_add_u32_e32 v4, 3, v76
	v_ashrrev_i32_e32 v3, 31, v2
	v_ashrrev_i32_e32 v5, 31, v4
	v_lshlrev_b64 v[14:15], 12, v[2:3]
	v_lshlrev_b64 v[2:3], 11, v[2:3]
	v_lshlrev_b64 v[16:17], 12, v[4:5]
	v_lshlrev_b64 v[4:5], 11, v[4:5]
	v_lshl_add_u64 v[114:115], s[18:19], 0, v[6:7]
	v_lshl_add_u64 v[112:113], s[18:19], 0, v[14:15]
	v_lshl_add_u64 v[2:3], v[62:63], 0, v[2:3]
	v_lshl_add_u64 v[90:91], v[74:75], 0, v[16:17]
	v_lshl_add_u64 v[14:15], v[62:63], 0, v[4:5]
	v_lshl_add_u64 v[116:117], v[114:115], 0, v[78:79]
	v_lshl_add_u64 v[118:119], v[112:113], 0, v[78:79]
	global_load_dwordx4 v[144:147], v[2:3], off
	global_load_dwordx4 v[152:155], v[2:3], off offset:1024
	global_load_dwordx4 v[20:23], v[90:91], off offset:2048
	global_load_dwordx4 v[16:19], v[90:91], off offset:3072
	global_load_dwordx4 v[4:7], v[14:15], off
	s_nop 0
	global_load_dwordx4 v[0:3], v[14:15], off offset:1024
	global_load_dwordx4 v[36:39], v[116:117], off offset:2048
	global_load_dwordx4 v[32:35], v[116:117], off offset:3072
	global_load_dwordx4 v[28:31], v[118:119], off offset:2048
	global_load_dwordx4 v[24:27], v[118:119], off offset:3072
	s_waitcnt vmcnt(0) lgkmcnt(0)
	v_lshlrev_b32_e32 v14, 16, v10
	v_lshlrev_b32_e32 v142, 16, v40
	v_and_b32_e32 v143, 0xffff0000, v40
	v_lshlrev_b32_e32 v148, 16, v41
	v_and_b32_e32 v149, 0xffff0000, v41
	v_pk_mul_f32 v[40:41], v[50:51], v[46:47]
	v_lshlrev_b32_e32 v150, 16, v42
	v_and_b32_e32 v151, 0xffff0000, v42
	v_lshlrev_b32_e32 v156, 16, v43
	v_and_b32_e32 v157, 0xffff0000, v43
	v_pk_mul_f32 v[42:43], v[48:49], v[44:45]
	v_pk_mul_f32 v[48:49], v[102:103], v[98:99]
	v_pk_mul_f32 v[98:99], v[80:81], v[40:41]
	v_lshlrev_b32_e32 v40, 16, v124
	v_and_b32_e32 v41, 0xffff0000, v124
	v_pk_mul_f32 v[44:45], v[54:55], v[94:95]
	v_pk_mul_f32 v[46:47], v[52:53], v[92:93]
	v_pk_mul_f32 v[102:103], v[72:73], v[42:43]
	v_lshlrev_b32_e32 v42, 16, v125
	v_and_b32_e32 v43, 0xffff0000, v125
	v_pk_mul_f32 v[158:159], v[40:41], v[40:41]
	v_pk_mul_f32 v[50:51], v[100:101], v[96:97]
	v_pk_mul_f32 v[54:55], v[106:107], v[120:121]
	v_pk_mul_f32 v[94:95], v[80:81], v[44:45]
	v_pk_mul_f32 v[100:101], v[72:73], v[46:47]
	v_lshlrev_b32_e32 v44, 16, v126
	v_and_b32_e32 v45, 0xffff0000, v126
	v_lshlrev_b32_e32 v46, 16, v127
	v_and_b32_e32 v47, 0xffff0000, v127
	v_lshlrev_b32_e32 v120, 16, v130
	v_and_b32_e32 v121, 0xffff0000, v130
	v_lshlrev_b32_e32 v126, 16, v131
	v_and_b32_e32 v127, 0xffff0000, v131
	v_pk_mul_f32 v[130:131], v[42:43], v[42:43]
	v_add_f32_e32 v56, v158, v159
	v_add_f32_e32 v56, v130, v56
	v_pk_mul_f32 v[92:93], v[80:81], v[48:49]
	v_pk_mul_f32 v[96:97], v[72:73], v[50:51]
	v_lshlrev_b32_e32 v48, 16, v128
	v_and_b32_e32 v49, 0xffff0000, v128
	v_lshlrev_b32_e32 v50, 16, v129
	v_and_b32_e32 v51, 0xffff0000, v129
	v_pk_mul_f32 v[128:129], v[44:45], v[44:45]
	v_add_f32_e32 v56, v131, v56
	v_add_f32_e32 v56, v128, v56
	v_pk_mul_f32 v[124:125], v[46:47], v[46:47]
	v_add_f32_e32 v56, v129, v56
	v_add_f32_e32 v56, v124, v56
	v_pk_mul_f32 v[52:53], v[108:109], v[122:123]
	v_pk_mul_f32 v[122:123], v[48:49], v[48:49]
	v_add_f32_e32 v56, v125, v56
	v_add_f32_e32 v56, v122, v56
	v_pk_mul_f32 v[110:111], v[50:51], v[50:51]
	v_add_f32_e32 v56, v123, v56
	v_add_f32_e32 v56, v110, v56
	v_pk_mul_f32 v[108:109], v[120:121], v[120:121]
	v_add_f32_e32 v56, v111, v56
	v_add_f32_e32 v56, v108, v56
	v_pk_mul_f32 v[106:107], v[126:127], v[126:127]
	v_add_f32_e32 v56, v109, v56
	v_add_f32_e32 v56, v106, v56
	v_add_f32_e32 v56, v107, v56
	v_lshlrev_b32_e32 v106, 16, v132
	v_and_b32_e32 v107, 0xffff0000, v132
	v_add_f32_dpp v56, v56, v56 quad_perm:[1,0,3,2] row_mask:0xf bank_mask:0xf bound_ctrl:1
	v_lshlrev_b32_e32 v108, 16, v133
	v_and_b32_e32 v109, 0xffff0000, v133
	v_add_f32_dpp v56, v56, v56 quad_perm:[2,3,0,1] row_mask:0xf bank_mask:0xf bound_ctrl:1
	v_pk_mul_f32 v[170:171], v[106:107], v[106:107]
	v_pk_mul_f32 v[158:159], v[108:109], v[108:109]
	v_add_f32_dpp v56, v56, v56 row_half_mirror row_mask:0xf bank_mask:0xf bound_ctrl:1
	v_lshlrev_b32_e32 v110, 16, v134
	v_and_b32_e32 v111, 0xffff0000, v134
	v_add_f32_dpp v56, v56, v56 row_mirror row_mask:0xf bank_mask:0xf bound_ctrl:1
	v_mov_b32_e32 v77, v56
	s_nop 1
	v_permlane16_swap_b32_e32 v56, v77
	v_add_f32_e32 v123, v56, v77
	v_add_f32_e32 v56, v170, v171
	v_add_f32_e32 v56, v158, v56
	v_lshlrev_b32_e32 v166, 16, v138
	v_and_b32_e32 v167, 0xffff0000, v138
	v_lshlrev_b32_e32 v168, 16, v139
	v_and_b32_e32 v169, 0xffff0000, v139
	v_pk_mul_f32 v[138:139], v[110:111], v[110:111]
	v_add_f32_e32 v56, v159, v56
	v_lshlrev_b32_e32 v160, 16, v135
	v_and_b32_e32 v161, 0xffff0000, v135
	v_add_f32_e32 v56, v138, v56
	v_lshlrev_b32_e32 v162, 16, v136
	v_and_b32_e32 v163, 0xffff0000, v136
	v_lshlrev_b32_e32 v164, 16, v137
	v_and_b32_e32 v165, 0xffff0000, v137
	v_pk_mul_f32 v[136:137], v[160:161], v[160:161]
	v_add_f32_e32 v56, v139, v56
	v_add_f32_e32 v56, v136, v56
	v_pk_mul_f32 v[134:135], v[162:163], v[162:163]
	v_add_f32_e32 v56, v137, v56
	v_add_f32_e32 v56, v134, v56
	v_pk_mul_f32 v[132:133], v[164:165], v[164:165]
	v_add_f32_e32 v56, v135, v56
	v_add_f32_e32 v56, v132, v56
	v_pk_mul_f32 v[130:131], v[166:167], v[166:167]
	v_add_f32_e32 v56, v133, v56
	v_add_f32_e32 v56, v130, v56
	v_pk_mul_f32 v[128:129], v[168:169], v[168:169]
	v_add_f32_e32 v56, v131, v56
	v_add_f32_e32 v56, v128, v56
	v_add_f32_e32 v56, v129, v56
	v_mov_b32_e32 v125, v123
	s_nop 1
	v_permlane32_swap_b32_e32 v123, v125
	v_add_f32_dpp v56, v56, v56 quad_perm:[1,0,3,2] row_mask:0xf bank_mask:0xf bound_ctrl:1
	v_and_b32_e32 v15, 0xffff0000, v10
	v_lshlrev_b32_e32 v10, 16, v11
	v_add_f32_dpp v56, v56, v56 quad_perm:[2,3,0,1] row_mask:0xf bank_mask:0xf bound_ctrl:1
	v_and_b32_e32 v11, 0xffff0000, v11
	v_lshlrev_b32_e32 v140, 16, v12
	v_add_f32_dpp v56, v56, v56 row_half_mirror row_mask:0xf bank_mask:0xf bound_ctrl:1
	v_and_b32_e32 v141, 0xffff0000, v12
	v_lshlrev_b32_e32 v12, 16, v13
	v_add_f32_dpp v56, v56, v56 row_mirror row_mask:0xf bank_mask:0xf bound_ctrl:1
	v_mov_b32_e32 v77, v56
	s_nop 1
	v_permlane16_swap_b32_e32 v56, v77
	v_add_f32_e32 v122, v56, v77
	v_mov_b32_e32 v124, v122
	s_nop 1
	v_permlane32_swap_b32_e32 v122, v124
	v_pk_add_f32 v[122:123], v[122:123], v[124:125]
	v_pk_mul_f32 v[124:125], v[72:73], v[54:55]
	v_pk_fma_f32 v[170:171], v[122:123], s[24:25], v[82:83] op_sel_hi:[1,0,0]
	v_pk_mul_f32 v[122:123], v[80:81], v[52:53]
	v_mul_f32_e32 v56, 0x4b800000, v171
	v_cmp_gt_f32_e32 vcc, s37, v171
	v_and_b32_e32 v13, 0xffff0000, v13
	v_lshlrev_b32_e32 v136, 16, v1
	v_cndmask_b32_e32 v56, v171, v56, vcc
	v_rsq_f32_e32 v56, v56
	v_and_b32_e32 v137, 0xffff0000, v1
	v_lshlrev_b32_e32 v138, 16, v2
	v_and_b32_e32 v139, 0xffff0000, v2
	v_mul_f32_e32 v52, 0x45800000, v56
	v_cndmask_b32_e32 v54, v56, v52, vcc
	v_pk_mul_f32 v[40:41], v[54:55], v[40:41] op_sel_hi:[0,1]
	v_pk_fma_f32 v[40:41], v[102:103], v[40:41], v[14:15]
	v_pk_mul_f32 v[14:15], v[54:55], v[42:43] op_sel_hi:[0,1]
	v_pk_fma_f32 v[42:43], v[98:99], v[14:15], v[10:11]
	v_pk_mul_f32 v[10:11], v[54:55], v[44:45] op_sel_hi:[0,1]
	v_pk_fma_f32 v[44:45], v[100:101], v[10:11], v[140:141]
	v_pk_mul_f32 v[10:11], v[54:55], v[46:47] op_sel_hi:[0,1]
	v_pk_fma_f32 v[46:47], v[94:95], v[10:11], v[12:13]
	v_pk_mul_f32 v[10:11], v[54:55], v[48:49] op_sel_hi:[0,1]
	v_pk_fma_f32 v[48:49], v[96:97], v[10:11], v[142:143]
	v_pk_mul_f32 v[10:11], v[54:55], v[50:51] op_sel_hi:[0,1]
	v_pk_fma_f32 v[50:51], v[92:93], v[10:11], v[148:149]
	v_pk_mul_f32 v[10:11], v[54:55], v[120:121] op_sel_hi:[0,1]
	v_lshlrev_b32_e32 v120, 16, v144
	v_and_b32_e32 v121, 0xffff0000, v144
	v_lshlrev_b32_e32 v142, 16, v145
	v_and_b32_e32 v143, 0xffff0000, v145
	v_pk_mul_f32 v[134:135], v[120:121], v[120:121]
	v_pk_mul_f32 v[132:133], v[142:143], v[142:143]
	v_add_f32_e32 v56, v134, v135
	v_lshlrev_b32_e32 v144, 16, v146
	v_and_b32_e32 v145, 0xffff0000, v146
	v_add_f32_e32 v56, v132, v56
	v_pk_mul_f32 v[130:131], v[144:145], v[144:145]
	v_add_f32_e32 v56, v133, v56
	v_lshlrev_b32_e32 v146, 16, v147
	v_and_b32_e32 v147, 0xffff0000, v147
	v_add_f32_e32 v56, v130, v56
	v_pk_mul_f32 v[128:129], v[146:147], v[146:147]
	v_add_f32_e32 v56, v131, v56
	v_lshlrev_b32_e32 v148, 16, v152
	v_and_b32_e32 v149, 0xffff0000, v152
	v_add_f32_e32 v56, v128, v56
	v_pk_fma_f32 v[52:53], v[124:125], v[10:11], v[150:151]
	v_pk_mul_f32 v[10:11], v[54:55], v[126:127] op_sel_hi:[0,1]
	v_pk_mul_f32 v[126:127], v[148:149], v[148:149]
	v_add_f32_e32 v56, v129, v56
	v_lshlrev_b32_e32 v150, 16, v153
	v_and_b32_e32 v151, 0xffff0000, v153
	v_add_f32_e32 v56, v126, v56
	v_pk_mul_f32 v[14:15], v[150:151], v[150:151]
	v_add_f32_e32 v56, v127, v56
	v_lshlrev_b32_e32 v152, 16, v154
	v_and_b32_e32 v153, 0xffff0000, v154
	v_add_f32_e32 v14, v14, v56
	v_pk_mul_f32 v[12:13], v[152:153], v[152:153]
	v_add_f32_e32 v14, v15, v14
	v_lshlrev_b32_e32 v154, 16, v155
	v_and_b32_e32 v155, 0xffff0000, v155
	v_add_f32_e32 v12, v12, v14
	v_pk_fma_f32 v[54:55], v[122:123], v[10:11], v[156:157]
	v_pk_mul_f32 v[10:11], v[154:155], v[154:155]
	v_add_f32_e32 v12, v13, v12
	v_add_f32_e32 v10, v10, v12
	v_add_f32_e32 v10, v11, v10
	v_lshlrev_b32_e32 v126, 16, v4
	v_and_b32_e32 v127, 0xffff0000, v4
	v_add_f32_dpp v10, v10, v10 quad_perm:[1,0,3,2] row_mask:0xf bank_mask:0xf bound_ctrl:1
	v_lshlrev_b32_e32 v128, 16, v5
	v_and_b32_e32 v129, 0xffff0000, v5
	v_add_f32_dpp v10, v10, v10 quad_perm:[2,3,0,1] row_mask:0xf bank_mask:0xf bound_ctrl:1
	v_pk_mul_f32 v[176:177], v[126:127], v[126:127]
	v_pk_mul_f32 v[14:15], v[128:129], v[128:129]
	v_add_f32_dpp v10, v10, v10 row_half_mirror row_mask:0xf bank_mask:0xf bound_ctrl:1
	v_add_f32_e32 v56, v176, v177
	v_lshlrev_b32_e32 v130, 16, v6
	v_add_f32_dpp v10, v10, v10 row_mirror row_mask:0xf bank_mask:0xf bound_ctrl:1
	v_and_b32_e32 v131, 0xffff0000, v6
	v_add_f32_e32 v14, v14, v56
	v_mov_b32_e32 v11, v10
	v_pk_mul_f32 v[12:13], v[130:131], v[130:131]
	v_add_f32_e32 v14, v15, v14
	v_permlane16_swap_b32_e32 v10, v11
	v_lshlrev_b32_e32 v132, 16, v7
	v_and_b32_e32 v133, 0xffff0000, v7
	v_add_f32_e32 v12, v12, v14
	v_add_f32_e32 v157, v10, v11
	v_pk_mul_f32 v[10:11], v[132:133], v[132:133]
	v_add_f32_e32 v12, v13, v12
	v_lshlrev_b32_e32 v134, 16, v0
	v_and_b32_e32 v135, 0xffff0000, v0
	v_add_f32_e32 v10, v10, v12
	v_pk_mul_f32 v[6:7], v[134:135], v[134:135]
	v_add_f32_e32 v10, v11, v10
	v_add_f32_e32 v6, v6, v10
	v_pk_mul_f32 v[4:5], v[136:137], v[136:137]
	v_add_f32_e32 v6, v7, v6
	v_add_f32_e32 v4, v4, v6
	v_lshlrev_b32_e32 v140, 16, v3
	v_and_b32_e32 v141, 0xffff0000, v3
	v_pk_mul_f32 v[2:3], v[138:139], v[138:139]
	v_add_f32_e32 v4, v5, v4
	v_add_f32_e32 v2, v2, v4
	v_pk_mul_f32 v[0:1], v[140:141], v[140:141]
	v_add_f32_e32 v2, v3, v2
	v_add_f32_e32 v0, v0, v2
	v_add_f32_e32 v0, v1, v0
	v_mov_b32_e32 v159, v157
	v_cmp_gt_f32_e64 s[6:7], s37, v170
	v_add_f32_dpp v0, v0, v0 quad_perm:[1,0,3,2] row_mask:0xf bank_mask:0xf bound_ctrl:1
	v_permlane32_swap_b32_e32 v157, v159
	s_nop 0
	v_add_f32_dpp v0, v0, v0 quad_perm:[2,3,0,1] row_mask:0xf bank_mask:0xf bound_ctrl:1
	s_and_b64 vcc, exec, s[22:23]
	s_nop 0
	v_add_f32_dpp v0, v0, v0 row_half_mirror row_mask:0xf bank_mask:0xf bound_ctrl:1
	s_nop 1
	v_add_f32_dpp v0, v0, v0 row_mirror row_mask:0xf bank_mask:0xf bound_ctrl:1
	v_mov_b32_e32 v1, v0
	s_nop 1
	v_permlane16_swap_b32_e32 v0, v1
	v_add_f32_e32 v156, v0, v1
	v_mov_b32_e32 v158, v156
	s_nop 1
	v_permlane32_swap_b32_e32 v156, v158
	s_cbranch_vccz .LBB0_3334
	v_cvt_pk_bf16_f32 v0, v40, v41
	v_cvt_pk_bf16_f32 v1, v42, v43
	v_cvt_pk_bf16_f32 v2, v44, v45
	v_cvt_pk_bf16_f32 v3, v46, v47
	v_cvt_pk_bf16_f32 v176, v48, v49
	v_cvt_pk_bf16_f32 v177, v50, v51
	v_cvt_pk_bf16_f32 v178, v52, v53
	v_cvt_pk_bf16_f32 v179, v54, v55
	flat_store_dwordx4 v[8:9], v[0:3] offset:2048
	v_lshlrev_b32_e32 v4, 16, v0
	v_and_b32_e32 v5, 0xffff0000, v0
	v_lshlrev_b32_e32 v6, 16, v1
	v_and_b32_e32 v7, 0xffff0000, v1
	v_lshlrev_b32_e32 v12, 16, v2
	v_and_b32_e32 v13, 0xffff0000, v2
	v_lshlrev_b32_e32 v14, 16, v3
	v_and_b32_e32 v15, 0xffff0000, v3
	flat_store_dwordx4 v[8:9], v[176:179] offset:3072
	v_lshlrev_b32_e32 v0, 16, v176
	v_and_b32_e32 v1, 0xffff0000, v176
	v_lshlrev_b32_e32 v2, 16, v177
	v_and_b32_e32 v3, 0xffff0000, v177
	v_lshlrev_b32_e32 v8, 16, v178
	v_and_b32_e32 v9, 0xffff0000, v178
	v_lshlrev_b32_e32 v10, 16, v179
	v_and_b32_e32 v11, 0xffff0000, v179
	v_lshlrev_b32_e32 v56, 2, v58
	s_cbranch_execnz .LBB0_3322

.LBB0_3331:
	s_and_b64 vcc, exec, s[6:7]
	s_cbranch_vccnz .LBB0_3318
	v_mul_hi_u32_u24_e32 v17, 0x6000, v85
	v_mul_u32_u24_e32 v16, 0x6000, v85
	v_lshl_add_u64 v[16:17], s[20:21], 0, v[16:17]
	v_lshl_add_u64 v[18:19], v[16:17], 0, s[28:29]
	v_lshl_add_u64 v[20:21], v[18:19], 0, v[56:57]
	v_mov_b32_e32 v85, v57
	global_load_dwordx4 v[100:103], v[20:21], off
	v_lshl_add_u64 v[20:21], v[18:19], 0, v[84:85]
	v_mov_b32_e32 v87, v57
	global_load_dwordx4 v[122:125], v[20:21], off
	v_lshl_add_u64 v[20:21], v[18:19], 0, v[86:87]
	v_mov_b32_e32 v89, v57
	global_load_dwordx4 v[126:129], v[20:21], off
	v_lshl_add_u64 v[18:19], v[18:19], 0, v[88:89]
	global_load_dwordx4 v[130:133], v[18:19], off
	global_load_dwordx4 v[134:137], v[68:69], off
	global_load_dwordx4 v[138:141], v[68:69], off offset:16
	global_load_dwordx4 v[142:145], v[70:71], off
	global_load_dwordx4 v[146:149], v[70:71], off offset:16
	v_lshl_add_u64 v[16:17], v[16:17], 0, s[30:31]
	v_lshl_add_u64 v[18:19], v[16:17], 0, v[56:57]
	global_load_dwordx4 v[28:31], v[18:19], off
	v_lshl_add_u64 v[18:19], v[16:17], 0, v[84:85]
	global_load_dwordx4 v[24:27], v[18:19], off
	v_lshl_add_u64 v[18:19], v[16:17], 0, v[86:87]
	global_load_dwordx4 v[20:23], v[18:19], off
	v_lshl_add_u64 v[16:17], v[16:17], 0, v[88:89]
	global_load_dwordx4 v[16:19], v[16:17], off
	v_mul_f32_e32 v77, v5, v5
	v_mul_f32_e32 v90, v13, v13
	v_mul_f32_e32 v91, v1, v1
	v_fmac_f32_e32 v77, v4, v4
	v_fmac_f32_e32 v90, v12, v12
	v_mul_f32_e32 v112, v9, v9
	v_fmac_f32_e32 v91, v0, v0
	v_fmac_f32_e32 v77, v6, v6
	v_fmac_f32_e32 v90, v14, v14
	v_fmac_f32_e32 v112, v8, v8
	v_fmac_f32_e32 v91, v2, v2
	v_fmac_f32_e32 v77, v7, v7
	v_fmac_f32_e32 v90, v15, v15
	v_fmac_f32_e32 v112, v10, v10
	v_fmac_f32_e32 v91, v3, v3
	v_add_f32_e32 v56, v90, v77
	v_fmac_f32_e32 v112, v11, v11
	v_add_f32_e32 v56, v91, v56
	v_add_f32_e32 v56, v112, v56
	v_mul_f32_e32 v113, v111, v111
	v_mul_f32_e32 v150, v109, v109
	v_add_f32_dpp v56, v56, v56 quad_perm:[1,0,3,2] row_mask:0xf bank_mask:0xf bound_ctrl:1
	v_mul_f32_e32 v152, v55, v55
	v_fmac_f32_e32 v113, v110, v110
	v_add_f32_dpp v56, v56, v56 quad_perm:[2,3,0,1] row_mask:0xf bank_mask:0xf bound_ctrl:1
	v_fmac_f32_e32 v150, v108, v108
	v_fmac_f32_e32 v152, v54, v54
	v_add_f32_dpp v56, v56, v56 row_half_mirror row_mask:0xf bank_mask:0xf bound_ctrl:1
	v_fmac_f32_e32 v113, v106, v106
	v_fmac_f32_e32 v150, v104, v104
	v_add_f32_dpp v56, v56, v56 row_mirror row_mask:0xf bank_mask:0xf bound_ctrl:1
	v_fmac_f32_e32 v152, v50, v50
	v_fmac_f32_e32 v113, v107, v107
	v_fmac_f32_e32 v150, v105, v105
	v_mov_b32_e32 v85, v56
	v_fmac_f32_e32 v152, v51, v51
	v_add_f32_e32 v77, v113, v150
	v_permlane16_swap_b32_e32 v56, v85
	v_add_f32_e32 v151, v56, v85
	v_add_f32_e32 v56, v77, v152
	v_mul_f32_e32 v77, v53, v53
	v_fmac_f32_e32 v77, v52, v52
	v_fmac_f32_e32 v77, v48, v48
	v_fmac_f32_e32 v77, v49, v49
	v_add_f32_e32 v56, v56, v77
	v_mov_b32_e32 v153, v151
	s_nop 1
	v_permlane32_swap_b32_e32 v151, v153
	v_add_f32_dpp v56, v56, v56 quad_perm:[1,0,3,2] row_mask:0xf bank_mask:0xf bound_ctrl:1
	v_add_u32_e32 v85, 0xffffe800, v83
	s_waitcnt vmcnt(0) lgkmcnt(0)
	v_pk_add_f32 v[90:91], v[102:103], 1.0 op_sel_hi:[1,0]
	v_add_f32_dpp v56, v56, v56 quad_perm:[2,3,0,1] row_mask:0xf bank_mask:0xf bound_ctrl:1
	v_pk_add_f32 v[100:101], v[100:101], 1.0 op_sel_hi:[1,0]
	v_pk_add_f32 v[132:133], v[132:133], 1.0 op_sel_hi:[1,0]
	v_add_f32_dpp v56, v56, v56 row_half_mirror row_mask:0xf bank_mask:0xf bound_ctrl:1
	v_pk_add_f32 v[102:103], v[124:125], 1.0 op_sel_hi:[1,0]
	v_pk_add_f32 v[128:129], v[128:129], 1.0 op_sel_hi:[1,0]
	v_add_f32_dpp v56, v56, v56 row_mirror row_mask:0xf bank_mask:0xf bound_ctrl:1
	v_mov_b32_e32 v77, v56
	s_nop 1
	v_permlane16_swap_b32_e32 v56, v77
	v_add_f32_e32 v150, v56, v77
	v_mov_b32_e32 v152, v150
	s_nop 1
	v_permlane32_swap_b32_e32 v150, v152
	v_pk_add_f32 v[124:125], v[122:123], 1.0 op_sel_hi:[1,0]
	v_pk_add_f32 v[154:155], v[126:127], 1.0 op_sel_hi:[1,0]
	v_pk_mul_f32 v[122:123], v[136:137], v[90:91]
	v_pk_mul_f32 v[126:127], v[134:135], v[100:101]
	v_pk_mul_f32 v[100:101], v[144:145], v[128:129]
	v_pk_mul_f32 v[90:91], v[148:149], v[132:133]
	v_pk_add_f32 v[128:129], v[150:151], v[152:153]
	v_mov_b64_e32 v[132:133], s[26:27]
	v_pk_fma_f32 v[134:135], v[128:129], s[24:25], v[132:133] op_sel_hi:[1,0,0]
	v_pk_mul_f32 v[112:113], v[140:141], v[102:103]
	v_mul_f32_e32 v56, 0x4b800000, v135
	v_cmp_gt_f32_e32 vcc, s37, v135
	v_pk_mul_f32 v[102:103], v[142:143], v[154:155]
	v_pk_mul_f32 v[124:125], v[138:139], v[124:125]
	v_cndmask_b32_e32 v56, v135, v56, vcc
	v_rsq_f32_e32 v56, v56
	v_add_u32_e32 v77, 0xffffe400, v83
	v_pk_add_f32 v[130:131], v[130:131], 1.0 op_sel_hi:[1,0]
	v_mul_f32_e32 v87, 0x45800000, v56
	v_cndmask_b32_e32 v56, v56, v87, vcc
	v_pk_mul_f32 v[0:1], v[0:1], v[56:57] op_sel_hi:[1,0]
	v_pk_mul_f32 v[2:3], v[2:3], v[56:57] op_sel_hi:[1,0]
	v_pk_mul_f32 v[4:5], v[4:5], v[56:57] op_sel_hi:[1,0]
	v_pk_mul_f32 v[12:13], v[12:13], v[56:57] op_sel_hi:[1,0]
	v_pk_mul_f32 v[6:7], v[6:7], v[56:57] op_sel_hi:[1,0]
	v_pk_mul_f32 v[14:15], v[14:15], v[56:57] op_sel_hi:[1,0]
	v_pk_fma_f32 v[0:1], v[102:103], v[0:1], v[20:21]
	v_pk_fma_f32 v[2:3], v[100:101], v[2:3], v[22:23]
	v_pk_fma_f32 v[4:5], v[126:127], v[4:5], v[28:29]
	v_pk_fma_f32 v[12:13], v[124:125], v[12:13], v[24:25]
	v_pk_fma_f32 v[6:7], v[122:123], v[6:7], v[30:31]
	v_pk_fma_f32 v[14:15], v[112:113], v[14:15], v[26:27]
	v_cvt_pk_bf16_f32 v0, v0, v1
	v_cvt_pk_bf16_f32 v1, v2, v3
	v_mul_f32_e32 v2, 0x4b800000, v134
	v_cmp_gt_f32_e32 vcc, s37, v134
	v_cvt_pk_bf16_f32 v4, v4, v5
	v_cvt_pk_bf16_f32 v5, v6, v7
	v_cvt_pk_bf16_f32 v6, v12, v13
	v_cvt_pk_bf16_f32 v7, v14, v15
	v_cndmask_b32_e32 v2, v134, v2, vcc
	buffer_store_dwordx4 v[4:7], v77, s[12:15], 0 offen sc1
	v_pk_mul_f32 v[128:129], v[146:147], v[130:131]
	v_add_u32_e32 v12, 0xfffff800, v83
	v_pk_mul_f32 v[4:5], v[8:9], v[56:57] op_sel_hi:[1,0]
	v_rsq_f32_e32 v8, v2
	v_pk_mul_f32 v[6:7], v[10:11], v[56:57] op_sel_hi:[1,0]
	v_pk_fma_f32 v[4:5], v[128:129], v[4:5], v[16:17]
	v_pk_fma_f32 v[6:7], v[90:91], v[6:7], v[18:19]
	v_cvt_pk_bf16_f32 v2, v4, v5
	v_cvt_pk_bf16_f32 v3, v6, v7
	buffer_store_dwordx4 v[0:3], v85, s[12:15], 0 offen sc1
	s_nop 1
	v_mul_f32_e32 v0, 0x45800000, v8
	v_cndmask_b32_e32 v4, v8, v0, vcc
	v_pk_mul_f32 v[0:1], v[110:111], v[4:5] op_sel_hi:[1,0]
	v_pk_mul_f32 v[2:3], v[108:109], v[4:5] op_sel_hi:[1,0]
	v_pk_mul_f32 v[6:7], v[106:107], v[4:5] op_sel_hi:[1,0]
	v_pk_mul_f32 v[8:9], v[104:105], v[4:5] op_sel_hi:[1,0]
	v_pk_fma_f32 v[0:1], v[126:127], v[0:1], v[28:29]
	v_pk_fma_f32 v[2:3], v[124:125], v[2:3], v[24:25]
	v_pk_fma_f32 v[6:7], v[122:123], v[6:7], v[30:31]
	v_pk_fma_f32 v[8:9], v[112:113], v[8:9], v[26:27]
	v_cvt_pk_bf16_f32 v0, v0, v1
	v_cvt_pk_bf16_f32 v1, v6, v7
	v_cvt_pk_bf16_f32 v2, v2, v3
	v_cvt_pk_bf16_f32 v3, v8, v9
	v_add_u32_e32 v5, 0xffffec00, v83
	buffer_store_dwordx4 v[0:3], v5, s[12:15], 0 offen sc1
	v_pk_mul_f32 v[6:7], v[50:51], v[4:5] op_sel_hi:[1,0]
	v_add_u32_e32 v8, 0xfffff000, v83
	v_pk_mul_f32 v[0:1], v[54:55], v[4:5] op_sel_hi:[1,0]
	v_pk_mul_f32 v[2:3], v[52:53], v[4:5] op_sel_hi:[1,0]
	v_pk_mul_f32 v[4:5], v[48:49], v[4:5] op_sel_hi:[1,0]
	v_pk_fma_f32 v[2:3], v[128:129], v[2:3], v[16:17]
	v_pk_fma_f32 v[4:5], v[90:91], v[4:5], v[18:19]
	v_cvt_pk_bf16_f32 v2, v2, v3
	v_cvt_pk_bf16_f32 v3, v4, v5
	v_mul_f32_e32 v4, v117, v117
	v_mul_f32_e32 v5, v121, v121
	v_fmac_f32_e32 v4, v116, v116
	v_fmac_f32_e32 v5, v120, v120
	v_fmac_f32_e32 v4, v42, v42
	v_fmac_f32_e32 v5, v114, v114
	v_fmac_f32_e32 v4, v43, v43
	v_fmac_f32_e32 v5, v115, v115
	v_add_f32_e32 v4, v4, v5
	v_mul_f32_e32 v5, v47, v47
	v_fmac_f32_e32 v5, v46, v46
	v_fmac_f32_e32 v5, v40, v40
	v_fmac_f32_e32 v5, v41, v41
	v_add_f32_e32 v4, v4, v5
	v_mul_f32_e32 v5, v119, v119
	v_fmac_f32_e32 v5, v118, v118
	v_fmac_f32_e32 v5, v44, v44
	v_fmac_f32_e32 v5, v45, v45
	v_add_f32_e32 v4, v4, v5
	v_pk_fma_f32 v[0:1], v[102:103], v[0:1], v[20:21]
	v_pk_fma_f32 v[6:7], v[100:101], v[6:7], v[22:23]
	v_add_f32_dpp v4, v4, v4 quad_perm:[1,0,3,2] row_mask:0xf bank_mask:0xf bound_ctrl:1
	v_cvt_pk_bf16_f32 v0, v0, v1
	v_cvt_pk_bf16_f32 v1, v6, v7
	v_add_f32_dpp v4, v4, v4 quad_perm:[2,3,0,1] row_mask:0xf bank_mask:0xf bound_ctrl:1
	v_mul_f32_e32 v6, v97, v97
	v_fmac_f32_e32 v6, v96, v96
	v_add_f32_dpp v4, v4, v4 row_half_mirror row_mask:0xf bank_mask:0xf bound_ctrl:1
	v_fmac_f32_e32 v6, v92, v92
	v_fmac_f32_e32 v6, v93, v93
	v_add_f32_dpp v4, v4, v4 row_mirror row_mask:0xf bank_mask:0xf bound_ctrl:1
	v_mov_b32_e32 v5, v4
	s_nop 1
	v_permlane16_swap_b32_e32 v4, v5
	v_add_f32_e32 v5, v4, v5
	v_mul_f32_e32 v4, v99, v99
	v_fmac_f32_e32 v4, v98, v98
	v_fmac_f32_e32 v4, v94, v94
	v_fmac_f32_e32 v4, v95, v95
	v_add_f32_e32 v4, v4, v6
	v_mul_f32_e32 v6, v39, v39
	v_fmac_f32_e32 v6, v38, v38
	v_fmac_f32_e32 v6, v34, v34
	v_fmac_f32_e32 v6, v35, v35
	v_add_f32_e32 v4, v4, v6
	v_mul_f32_e32 v6, v37, v37
	v_fmac_f32_e32 v6, v36, v36
	v_fmac_f32_e32 v6, v32, v32
	v_fmac_f32_e32 v6, v33, v33
	v_add_f32_e32 v4, v4, v6
	v_mov_b32_e32 v7, v5
	s_nop 1
	v_permlane32_swap_b32_e32 v5, v7
	v_add_f32_dpp v4, v4, v4 quad_perm:[1,0,3,2] row_mask:0xf bank_mask:0xf bound_ctrl:1
	buffer_store_dwordx4 v[0:3], v8, s[12:15], 0 offen sc1
	s_nop 0
	v_add_f32_dpp v4, v4, v4 quad_perm:[2,3,0,1] row_mask:0xf bank_mask:0xf bound_ctrl:1
	s_nop 1
	v_add_f32_dpp v4, v4, v4 row_half_mirror row_mask:0xf bank_mask:0xf bound_ctrl:1
	s_nop 1
	v_add_f32_dpp v4, v4, v4 row_mirror row_mask:0xf bank_mask:0xf bound_ctrl:1
	v_mov_b32_e32 v6, v4
	s_nop 1
	v_permlane16_swap_b32_e32 v4, v6
	v_add_f32_e32 v4, v4, v6
	v_mov_b32_e32 v6, v4
	s_nop 1
	v_permlane32_swap_b32_e32 v4, v6
	v_pk_add_f32 v[4:5], v[4:5], v[6:7]
	v_add_u32_e32 v7, 0xfffff400, v83
	v_pk_fma_f32 v[4:5], v[4:5], s[24:25], v[132:133] op_sel_hi:[1,0,0]
	s_nop 0
	v_mul_f32_e32 v6, 0x4b800000, v5
	v_cmp_gt_f32_e32 vcc, s37, v5
	s_nop 1
	v_cndmask_b32_e32 v5, v5, v6, vcc
	v_rsq_f32_e32 v5, v5
	s_nop 0
	v_mul_f32_e32 v0, 0x45800000, v5
	v_cndmask_b32_e32 v6, v5, v0, vcc
	v_pk_mul_f32 v[0:1], v[116:117], v[6:7] op_sel_hi:[1,0]
	v_pk_mul_f32 v[2:3], v[120:121], v[6:7] op_sel_hi:[1,0]
	v_pk_mul_f32 v[8:9], v[42:43], v[6:7] op_sel_hi:[1,0]
	v_pk_mul_f32 v[10:11], v[114:115], v[6:7] op_sel_hi:[1,0]
	v_mul_f32_e32 v5, 0x4b800000, v4
	v_cmp_gt_f32_e32 vcc, s37, v4
	v_pk_fma_f32 v[0:1], v[126:127], v[0:1], v[28:29]
	v_pk_fma_f32 v[2:3], v[124:125], v[2:3], v[24:25]
	v_pk_fma_f32 v[8:9], v[122:123], v[8:9], v[30:31]
	v_pk_fma_f32 v[10:11], v[112:113], v[10:11], v[26:27]
	v_cndmask_b32_e32 v4, v4, v5, vcc
	v_cvt_pk_bf16_f32 v0, v0, v1
	v_cvt_pk_bf16_f32 v1, v8, v9
	v_cvt_pk_bf16_f32 v2, v2, v3
	v_cvt_pk_bf16_f32 v3, v10, v11
	v_rsq_f32_e32 v4, v4
	buffer_store_dwordx4 v[0:3], v7, s[12:15], 0 offen sc1
	v_pk_mul_f32 v[8:9], v[40:41], v[6:7] op_sel_hi:[1,0]
	s_nop 0
	v_pk_mul_f32 v[0:1], v[46:47], v[6:7] op_sel_hi:[1,0]
	v_pk_mul_f32 v[2:3], v[118:119], v[6:7] op_sel_hi:[1,0]
	v_pk_mul_f32 v[6:7], v[44:45], v[6:7] op_sel_hi:[1,0]
	v_pk_fma_f32 v[0:1], v[102:103], v[0:1], v[20:21]
	v_pk_fma_f32 v[2:3], v[128:129], v[2:3], v[16:17]
	v_pk_fma_f32 v[8:9], v[100:101], v[8:9], v[22:23]
	v_pk_fma_f32 v[6:7], v[90:91], v[6:7], v[18:19]
	v_cvt_pk_bf16_f32 v0, v0, v1
	v_cvt_pk_bf16_f32 v1, v8, v9
	v_cvt_pk_bf16_f32 v2, v2, v3
	v_cvt_pk_bf16_f32 v3, v6, v7
	buffer_store_dwordx4 v[0:3], v12, s[12:15], 0 offen sc1
	s_nop 1
	v_mul_f32_e32 v0, 0x45800000, v4
	v_cndmask_b32_e32 v4, v4, v0, vcc
	v_pk_mul_f32 v[0:1], v[98:99], v[4:5] op_sel_hi:[1,0]
	v_pk_mul_f32 v[2:3], v[96:97], v[4:5] op_sel_hi:[1,0]
	v_pk_mul_f32 v[6:7], v[94:95], v[4:5] op_sel_hi:[1,0]
	v_pk_mul_f32 v[8:9], v[92:93], v[4:5] op_sel_hi:[1,0]
	v_pk_fma_f32 v[0:1], v[126:127], v[0:1], v[28:29]
	v_pk_fma_f32 v[2:3], v[124:125], v[2:3], v[24:25]
	v_pk_fma_f32 v[6:7], v[122:123], v[6:7], v[30:31]
	v_pk_fma_f32 v[8:9], v[112:113], v[8:9], v[26:27]
	v_cvt_pk_bf16_f32 v0, v0, v1
	v_cvt_pk_bf16_f32 v1, v6, v7
	v_cvt_pk_bf16_f32 v2, v2, v3
	v_cvt_pk_bf16_f32 v3, v8, v9
	v_add_u32_e32 v5, 0xfffffc00, v83
	buffer_store_dwordx4 v[0:3], v5, s[12:15], 0 offen sc1
	v_pk_mul_f32 v[6:7], v[34:35], v[4:5] op_sel_hi:[1,0]
	s_nop 0
	v_pk_mul_f32 v[0:1], v[38:39], v[4:5] op_sel_hi:[1,0]
	v_pk_mul_f32 v[2:3], v[36:37], v[4:5] op_sel_hi:[1,0]
	v_pk_mul_f32 v[4:5], v[32:33], v[4:5] op_sel_hi:[1,0]
	v_pk_fma_f32 v[0:1], v[102:103], v[0:1], v[20:21]
	v_pk_fma_f32 v[2:3], v[128:129], v[2:3], v[16:17]
	v_pk_fma_f32 v[6:7], v[100:101], v[6:7], v[22:23]
	v_pk_fma_f32 v[4:5], v[90:91], v[4:5], v[18:19]
	v_cvt_pk_bf16_f32 v0, v0, v1
	v_cvt_pk_bf16_f32 v1, v6, v7
	v_cvt_pk_bf16_f32 v2, v2, v3
	v_cvt_pk_bf16_f32 v3, v4, v5
	buffer_store_dwordx4 v[0:3], v83, s[12:15], 0 offen sc1
	s_waitcnt vmcnt(0)
	s_and_saveexec_b64 s[6:7], s[4:5]
	s_cbranch_execz .LBB0_3317
	v_ashrrev_i32_e32 v0, 2, v76
	v_and_b32_e32 v0, 0xffffffc0, v0
	v_ashrrev_i32_e32 v1, 31, v0
	v_lshl_add_u64 v[0:1], v[0:1], 2, s[16:17]
	flat_atomic_add v[0:1], v172
	s_branch .LBB0_3317

.LBB0_3564:
	v_add_u32_e32 v39, 0xfffff000, v28
	v_ashrrev_i32_e32 v29, 31, v28
	v_add_u32_e32 v38, 1, v28
	v_add_u32_e32 v40, 2, v28
	v_add_u32_e32 v42, 3, v28
	v_lshrrev_b32_e32 v48, 11, v39
	v_lshlrev_b64 v[44:45], 12, v[28:29]
	v_ashrrev_i32_e32 v39, 31, v38
	v_lshlrev_b64 v[46:47], 11, v[28:29]
	v_ashrrev_i32_e32 v41, 31, v40
	v_ashrrev_i32_e32 v43, 31, v42
	v_lshl_add_u64 v[44:45], s[88:89], 0, v[44:45]
	v_lshlrev_b64 v[54:55], 12, v[38:39]
	v_lshl_add_u64 v[50:51], v[18:19], 0, v[46:47]
	v_lshlrev_b64 v[38:39], 11, v[38:39]
	v_lshlrev_b64 v[56:57], 12, v[40:41]
	v_lshlrev_b64 v[40:41], 11, v[40:41]
	v_lshlrev_b64 v[58:59], 12, v[42:43]
	v_add_u32_e32 v29, 6, v48
	v_cmp_lt_i32_e32 vcc, s3, v28
	v_lshl_add_u64 v[60:61], v[44:45], 0, v[30:31]
	v_lshl_add_u64 v[62:63], s[88:89], 0, v[54:55]
	global_load_dwordx4 v[0:3], v[20:21], off offset:16
	global_load_dwordx4 v[4:7], v[20:21], off
	global_load_dwordx4 v[8:11], v[20:21], off offset:2064
	global_load_dwordx4 v[12:15], v[20:21], off offset:2048
	v_lshlrev_b64 v[42:43], 11, v[42:43]
	global_load_dwordx4 v[46:49], v[50:51], off
	v_lshl_add_u64 v[64:65], v[18:19], 0, v[38:39]
	global_load_dwordx4 v[50:53], v[50:51], off offset:1024
	v_lshl_add_u64 v[66:67], s[88:89], 0, v[56:57]
	v_lshl_add_u64 v[40:41], v[18:19], 0, v[40:41]
	v_lshl_add_u64 v[58:59], v[26:27], 0, v[58:59]
	v_cndmask_b32_e32 v29, 5, v29, vcc
	global_load_dwordx4 v[54:57], v[60:61], off offset:2048
	global_load_dwordx4 v[74:77], v[60:61], off offset:3072
	global_load_dwordx4 v[94:97], v[58:59], off offset:2048
	global_load_dwordx4 v[98:101], v[58:59], off offset:3072
	global_load_dwordx4 v[102:105], v[64:65], off
	v_lshl_add_u64 v[60:61], v[62:63], 0, v[30:31]
	v_lshl_add_u64 v[42:43], v[18:19], 0, v[42:43]
	global_load_dwordx4 v[106:109], v[64:65], off offset:1024
	v_lshl_add_u64 v[64:65], v[66:67], 0, v[30:31]
	global_load_dwordx4 v[110:113], v[40:41], off
	global_load_dwordx4 v[114:117], v[40:41], off offset:1024
	global_load_dwordx4 v[118:121], v[42:43], off
	global_load_dwordx4 v[122:125], v[42:43], off offset:1024
	v_mad_u64_u32 v[68:69], s[0:1], v29, s9, v[22:23]
	global_load_dwordx4 v[126:129], v[60:61], off offset:2048
	global_load_dwordx4 v[130:133], v[60:61], off offset:3072
	global_load_dwordx4 v[134:137], v[64:65], off offset:2048
	global_load_dwordx4 v[138:141], v[64:65], off offset:3072
	global_load_dwordx4 v[142:145], v[68:69], off
	global_load_dwordx4 v[146:149], v[68:69], off offset:16
	global_load_dwordx4 v[150:153], v[68:69], off offset:2048
	global_load_dwordx4 v[154:157], v[68:69], off offset:2064
	v_lshl_add_u64 v[40:41], v[58:59], 0, v[16:17]
	v_lshl_add_u64 v[38:39], v[44:45], 0, v[36:37]
	v_lshl_add_u64 v[44:45], v[62:63], 0, v[36:37]
	v_lshl_add_u64 v[42:43], v[66:67], 0, v[36:37]
	s_add_i32 s85, s85, s86
	s_cmpk_lt_i32 s85, 0x180
	v_add_u32_e32 v28, s2, v28
	s_waitcnt vmcnt(0) lgkmcnt(0)
	v_lshlrev_b32_e32 v78, 16, v46
	v_and_b32_e32 v79, 0xffff0000, v46
	v_lshlrev_b32_e32 v80, 16, v47
	v_and_b32_e32 v81, 0xffff0000, v47
	v_pk_mul_f32 v[162:163], v[78:79], v[78:79]
	v_pk_mul_f32 v[164:165], v[80:81], v[80:81]
	v_add_f32_e32 v29, v162, v163
	v_lshlrev_b32_e32 v166, 16, v102
	v_and_b32_e32 v167, 0xffff0000, v102
	v_lshlrev_b32_e32 v102, 16, v103
	v_and_b32_e32 v103, 0xffff0000, v103
	v_lshlrev_b32_e32 v174, 16, v110
	v_and_b32_e32 v175, 0xffff0000, v110
	v_lshlrev_b32_e32 v182, 16, v118
	v_and_b32_e32 v183, 0xffff0000, v118
	v_pk_mul_f32 v[0:1], v[0:1], v[146:147]
	v_pk_mul_f32 v[8:9], v[8:9], v[154:155]
	v_pk_mul_f32 v[154:155], v[166:167], v[166:167]
	v_lshlrev_b32_e32 v110, 16, v111
	v_and_b32_e32 v111, 0xffff0000, v111
	v_lshlrev_b32_e32 v118, 16, v119
	v_and_b32_e32 v119, 0xffff0000, v119
	v_pk_mul_f32 v[2:3], v[2:3], v[148:149]
	v_pk_mul_f32 v[10:11], v[10:11], v[156:157]
	v_pk_mul_f32 v[156:157], v[102:103], v[102:103]
	v_pk_mul_f32 v[216:217], v[174:175], v[174:175]
	v_pk_mul_f32 v[232:233], v[182:183], v[182:183]
	v_pk_mul_f32 v[242:243], v[24:25], v[0:1]
	v_add_f32_e32 v1, v154, v155
	v_lshlrev_b32_e32 v82, 16, v48
	v_and_b32_e32 v83, 0xffff0000, v48
	v_lshlrev_b32_e32 v168, 16, v104
	v_and_b32_e32 v169, 0xffff0000, v104
	v_pk_mul_f32 v[218:219], v[110:111], v[110:111]
	v_pk_mul_f32 v[234:235], v[118:119], v[118:119]
	v_pk_mul_f32 v[240:241], v[32:33], v[2:3]
	v_add_f32_e32 v0, v164, v29
	v_add_f32_e32 v2, v216, v217
	v_add_f32_e32 v3, v232, v233
	v_add_f32_e32 v1, v156, v1
	v_pk_mul_f32 v[158:159], v[82:83], v[82:83]
	v_lshlrev_b32_e32 v176, 16, v112
	v_and_b32_e32 v177, 0xffff0000, v112
	v_lshlrev_b32_e32 v184, 16, v120
	v_and_b32_e32 v185, 0xffff0000, v120
	v_pk_mul_f32 v[12:13], v[12:13], v[150:151]
	v_pk_mul_f32 v[150:151], v[168:169], v[168:169]
	v_add_f32_e32 v0, v165, v0
	v_add_f32_e32 v2, v218, v2
	v_add_f32_e32 v3, v234, v3
	v_add_f32_e32 v1, v157, v1
	v_lshlrev_b32_e32 v84, 16, v49
	v_and_b32_e32 v85, 0xffff0000, v49
	v_lshlrev_b32_e32 v104, 16, v105
	v_and_b32_e32 v105, 0xffff0000, v105
	v_pk_mul_f32 v[212:213], v[176:177], v[176:177]
	v_pk_mul_f32 v[228:229], v[184:185], v[184:185]
	v_add_f32_e32 v0, v158, v0
	v_add_f32_e32 v2, v219, v2
	v_add_f32_e32 v3, v235, v3
	v_add_f32_e32 v1, v150, v1
	v_pk_mul_f32 v[160:161], v[84:85], v[84:85]
	v_lshlrev_b32_e32 v112, 16, v113
	v_and_b32_e32 v113, 0xffff0000, v113
	v_lshlrev_b32_e32 v120, 16, v121
	v_and_b32_e32 v121, 0xffff0000, v121
	v_pk_mul_f32 v[14:15], v[14:15], v[152:153]
	v_pk_mul_f32 v[152:153], v[104:105], v[104:105]
	v_add_f32_e32 v0, v159, v0
	v_add_f32_e32 v2, v212, v2
	v_add_f32_e32 v3, v228, v3
	v_add_f32_e32 v1, v151, v1
	v_lshlrev_b32_e32 v86, 16, v50
	v_and_b32_e32 v87, 0xffff0000, v50
	v_lshlrev_b32_e32 v170, 16, v106
	v_and_b32_e32 v171, 0xffff0000, v106
	v_pk_mul_f32 v[214:215], v[112:113], v[112:113]
	v_pk_mul_f32 v[230:231], v[120:121], v[120:121]
	v_add_f32_e32 v0, v160, v0
	v_add_f32_e32 v2, v213, v2
	v_add_f32_e32 v3, v229, v3
	v_add_f32_e32 v1, v152, v1
	v_lshlrev_b32_e32 v90, 16, v52
	v_and_b32_e32 v91, 0xffff0000, v52
	v_lshlrev_b32_e32 v92, 16, v53
	v_and_b32_e32 v93, 0xffff0000, v53
	v_lshlrev_b32_e32 v52, 16, v98
	v_and_b32_e32 v53, 0xffff0000, v98
	v_lshlrev_b32_e32 v58, 16, v99
	v_and_b32_e32 v59, 0xffff0000, v99
	v_pk_mul_f32 v[98:99], v[86:87], v[86:87]
	v_lshlrev_b32_e32 v178, 16, v114
	v_and_b32_e32 v179, 0xffff0000, v114
	v_lshlrev_b32_e32 v186, 16, v122
	v_and_b32_e32 v187, 0xffff0000, v122
	v_pk_mul_f32 v[146:147], v[170:171], v[170:171]
	v_add_f32_e32 v0, v161, v0
	v_add_f32_e32 v2, v214, v2
	v_add_f32_e32 v3, v230, v3
	v_add_f32_e32 v1, v153, v1
	v_lshlrev_b32_e32 v88, 16, v51
	v_and_b32_e32 v89, 0xffff0000, v51
	v_lshlrev_b32_e32 v106, 16, v107
	v_and_b32_e32 v107, 0xffff0000, v107
	v_pk_mul_f32 v[208:209], v[178:179], v[178:179]
	v_pk_mul_f32 v[224:225], v[186:187], v[186:187]
	v_add_f32_e32 v0, v98, v0
	v_add_f32_e32 v2, v215, v2
	v_add_f32_e32 v3, v231, v3
	v_add_f32_e32 v1, v146, v1
	v_lshlrev_b32_e32 v64, 16, v56
	v_and_b32_e32 v65, 0xffff0000, v56
	v_lshlrev_b32_e32 v70, 16, v57
	v_and_b32_e32 v71, 0xffff0000, v57
	v_lshlrev_b32_e32 v56, 16, v100
	v_and_b32_e32 v57, 0xffff0000, v100
	v_lshlrev_b32_e32 v62, 16, v101
	v_and_b32_e32 v63, 0xffff0000, v101
	v_pk_mul_f32 v[100:101], v[88:89], v[88:89]
	v_lshlrev_b32_e32 v114, 16, v115
	v_and_b32_e32 v115, 0xffff0000, v115
	v_lshlrev_b32_e32 v122, 16, v123
	v_and_b32_e32 v123, 0xffff0000, v123
	v_pk_mul_f32 v[148:149], v[106:107], v[106:107]
	v_add_f32_e32 v0, v99, v0
	v_add_f32_e32 v2, v208, v2
	v_add_f32_e32 v3, v224, v3
	v_add_f32_e32 v1, v147, v1
	v_lshlrev_b32_e32 v172, 16, v108
	v_and_b32_e32 v173, 0xffff0000, v108
	v_pk_mul_f32 v[210:211], v[114:115], v[114:115]
	v_pk_mul_f32 v[226:227], v[122:123], v[122:123]
	v_add_f32_e32 v0, v100, v0
	v_add_f32_e32 v2, v209, v2
	v_add_f32_e32 v3, v225, v3
	v_add_f32_e32 v1, v148, v1
	v_lshlrev_b32_e32 v46, 16, v94
	v_and_b32_e32 v47, 0xffff0000, v94
	v_lshlrev_b32_e32 v50, 16, v95
	v_and_b32_e32 v51, 0xffff0000, v95
	v_pk_mul_f32 v[94:95], v[90:91], v[90:91]
	v_lshlrev_b32_e32 v180, 16, v116
	v_and_b32_e32 v181, 0xffff0000, v116
	v_lshlrev_b32_e32 v188, 16, v124
	v_and_b32_e32 v189, 0xffff0000, v124
	v_pk_mul_f32 v[4:5], v[4:5], v[142:143]
	v_pk_mul_f32 v[142:143], v[172:173], v[172:173]
	v_add_f32_e32 v0, v101, v0
	v_add_f32_e32 v2, v210, v2
	v_add_f32_e32 v3, v226, v3
	v_add_f32_e32 v1, v149, v1
	v_lshlrev_b32_e32 v108, 16, v109
	v_and_b32_e32 v109, 0xffff0000, v109
	v_pk_mul_f32 v[162:163], v[180:181], v[180:181]
	v_pk_mul_f32 v[220:221], v[188:189], v[188:189]
	v_add_f32_e32 v0, v94, v0
	v_add_f32_e32 v2, v211, v2
	v_add_f32_e32 v3, v227, v3
	v_add_f32_e32 v1, v142, v1
	v_lshlrev_b32_e32 v60, 16, v54
	v_and_b32_e32 v61, 0xffff0000, v54
	v_lshlrev_b32_e32 v66, 16, v55
	v_and_b32_e32 v67, 0xffff0000, v55
	v_lshlrev_b32_e32 v48, 16, v96
	v_and_b32_e32 v49, 0xffff0000, v96
	v_lshlrev_b32_e32 v54, 16, v97
	v_and_b32_e32 v55, 0xffff0000, v97
	v_pk_mul_f32 v[96:97], v[92:93], v[92:93]
	v_lshlrev_b32_e32 v116, 16, v117
	v_and_b32_e32 v117, 0xffff0000, v117
	v_lshlrev_b32_e32 v124, 16, v125
	v_and_b32_e32 v125, 0xffff0000, v125
	v_pk_mul_f32 v[6:7], v[6:7], v[144:145]
	v_pk_mul_f32 v[144:145], v[108:109], v[108:109]
	v_add_f32_e32 v0, v95, v0
	v_add_f32_e32 v2, v162, v2
	v_add_f32_e32 v3, v220, v3
	v_add_f32_e32 v1, v143, v1
	v_pk_mul_f32 v[206:207], v[116:117], v[116:117]
	v_pk_mul_f32 v[222:223], v[124:125], v[124:125]
	v_add_f32_e32 v0, v96, v0
	v_add_f32_e32 v2, v163, v2
	v_add_f32_e32 v3, v221, v3
	v_add_f32_e32 v1, v144, v1
	v_add_f32_e32 v0, v97, v0
	v_add_f32_e32 v2, v206, v2
	v_add_f32_e32 v3, v222, v3
	v_add_f32_e32 v1, v145, v1
	v_add_f32_dpp v0, v0, v0 quad_perm:[1,0,3,2] row_mask:0xf bank_mask:0xf bound_ctrl:1
	v_add_f32_e32 v2, v207, v2
	v_add_f32_e32 v3, v223, v3
	v_add_f32_dpp v1, v1, v1 quad_perm:[1,0,3,2] row_mask:0xf bank_mask:0xf bound_ctrl:1
	v_add_f32_dpp v0, v0, v0 quad_perm:[2,3,0,1] row_mask:0xf bank_mask:0xf bound_ctrl:1
	v_add_f32_dpp v2, v2, v2 quad_perm:[1,0,3,2] row_mask:0xf bank_mask:0xf bound_ctrl:1
	v_add_f32_dpp v3, v3, v3 quad_perm:[1,0,3,2] row_mask:0xf bank_mask:0xf bound_ctrl:1
	v_add_f32_dpp v1, v1, v1 quad_perm:[2,3,0,1] row_mask:0xf bank_mask:0xf bound_ctrl:1
	v_add_f32_dpp v0, v0, v0 row_half_mirror row_mask:0xf bank_mask:0xf bound_ctrl:1
	v_add_f32_dpp v2, v2, v2 quad_perm:[2,3,0,1] row_mask:0xf bank_mask:0xf bound_ctrl:1
	v_add_f32_dpp v3, v3, v3 quad_perm:[2,3,0,1] row_mask:0xf bank_mask:0xf bound_ctrl:1
	v_add_f32_dpp v1, v1, v1 row_half_mirror row_mask:0xf bank_mask:0xf bound_ctrl:1
	v_pk_mul_f32 v[238:239], v[24:25], v[4:5]
	v_add_f32_dpp v0, v0, v0 row_mirror row_mask:0xf bank_mask:0xf bound_ctrl:1
	v_add_f32_dpp v2, v2, v2 row_half_mirror row_mask:0xf bank_mask:0xf bound_ctrl:1
	v_add_f32_dpp v3, v3, v3 row_half_mirror row_mask:0xf bank_mask:0xf bound_ctrl:1
	v_add_f32_dpp v5, v1, v1 row_mirror row_mask:0xf bank_mask:0xf bound_ctrl:1
	v_pk_mul_f32 v[236:237], v[32:33], v[6:7]
	v_mov_b32_e32 v4, v0
	v_add_f32_dpp v2, v2, v2 row_mirror row_mask:0xf bank_mask:0xf bound_ctrl:1
	v_add_f32_dpp v6, v3, v3 row_mirror row_mask:0xf bank_mask:0xf bound_ctrl:1
	v_mov_b32_e32 v7, v5
	v_pk_mul_f32 v[250:251], v[24:25], v[8:9]
	v_permlane16_swap_b32_e32 v0, v4
	v_mov_b32_e32 v8, v2
	v_mov_b32_e32 v9, v6
	v_permlane16_swap_b32_e32 v5, v7
	v_add_f32_e32 v1, v0, v4
	v_permlane16_swap_b32_e32 v2, v8
	v_permlane16_swap_b32_e32 v6, v9
	v_add_f32_e32 v0, v5, v7
	v_mov_b32_e32 v3, v1
	v_add_f32_e32 v5, v2, v8
	v_add_f32_e32 v4, v6, v9
	v_mov_b32_e32 v2, v0
	v_permlane32_swap_b32_e32 v1, v3
	v_mov_b32_e32 v7, v5
	v_mov_b32_e32 v6, v4
	v_permlane32_swap_b32_e32 v0, v2
	v_permlane32_swap_b32_e32 v5, v7
	v_permlane32_swap_b32_e32 v4, v6
	v_pk_add_f32 v[0:1], v[0:1], v[2:3]
	v_pk_add_f32 v[2:3], v[4:5], v[6:7]
	v_pk_fma_f32 v[0:1], v[0:1], s[8:9], v[34:35] op_sel_hi:[1,0,0]
	v_pk_fma_f32 v[2:3], v[2:3], s[8:9], v[34:35] op_sel_hi:[1,0,0]
	v_mul_f32_e32 v4, 0x4b800000, v1
	v_cmp_gt_f32_e64 s[6:7], s10, v1
	v_mul_f32_e32 v5, 0x4b800000, v0
	v_cmp_gt_f32_e32 vcc, s10, v0
	v_mul_f32_e32 v6, 0x4b800000, v3
	v_mul_f32_e32 v7, 0x4b800000, v2
	v_cmp_gt_f32_e64 s[0:1], s10, v2
	v_cmp_gt_f32_e64 s[4:5], s10, v3
	v_cndmask_b32_e64 v1, v1, v4, s[6:7]
	v_cndmask_b32_e32 v0, v0, v5, vcc
	v_cndmask_b32_e64 v3, v3, v6, s[4:5]
	v_cndmask_b32_e64 v2, v2, v7, s[0:1]
	v_rsq_f32_e32 v1, v1
	v_rsq_f32_e32 v4, v0
	v_rsq_f32_e32 v3, v3
	v_rsq_f32_e32 v5, v2
	v_mul_f32_e32 v0, 0x45800000, v1
	v_mul_f32_e32 v2, 0x45800000, v4
	v_mul_f32_e32 v6, 0x45800000, v3
	v_mul_f32_e32 v7, 0x45800000, v5
	v_cndmask_b32_e64 v0, v1, v0, s[6:7]
	v_pk_mul_f32 v[248:249], v[32:33], v[10:11]
	v_cndmask_b32_e32 v2, v4, v2, vcc
	v_cndmask_b32_e64 v4, v3, v6, s[4:5]
	v_cndmask_b32_e64 v6, v5, v7, s[0:1]
	v_pk_mul_f32 v[8:9], v[0:1], v[78:79] op_sel_hi:[0,1]
	v_pk_mul_f32 v[10:11], v[0:1], v[80:81] op_sel_hi:[0,1]
	v_lshlrev_b32_e32 v68, 16, v74
	v_and_b32_e32 v69, 0xffff0000, v74
	v_lshlrev_b32_e32 v74, 16, v75
	v_and_b32_e32 v75, 0xffff0000, v75
	v_lshlrev_b32_e32 v72, 16, v76
	v_and_b32_e32 v73, 0xffff0000, v76
	v_lshlrev_b32_e32 v76, 16, v77
	v_and_b32_e32 v77, 0xffff0000, v77
	v_lshlrev_b32_e32 v190, 16, v126
	v_and_b32_e32 v191, 0xffff0000, v126
	v_lshlrev_b32_e32 v126, 16, v127
	v_and_b32_e32 v127, 0xffff0000, v127
	v_lshlrev_b32_e32 v192, 16, v128
	v_and_b32_e32 v193, 0xffff0000, v128
	v_lshlrev_b32_e32 v128, 16, v129
	v_and_b32_e32 v129, 0xffff0000, v129
	v_lshlrev_b32_e32 v194, 16, v130
	v_and_b32_e32 v195, 0xffff0000, v130
	v_lshlrev_b32_e32 v130, 16, v131
	v_and_b32_e32 v131, 0xffff0000, v131
	v_lshlrev_b32_e32 v196, 16, v132
	v_and_b32_e32 v197, 0xffff0000, v132
	v_lshlrev_b32_e32 v132, 16, v133
	v_and_b32_e32 v133, 0xffff0000, v133
	v_lshlrev_b32_e32 v198, 16, v134
	v_and_b32_e32 v199, 0xffff0000, v134
	v_lshlrev_b32_e32 v134, 16, v135
	v_and_b32_e32 v135, 0xffff0000, v135
	v_lshlrev_b32_e32 v200, 16, v136
	v_and_b32_e32 v201, 0xffff0000, v136
	v_lshlrev_b32_e32 v136, 16, v137
	v_and_b32_e32 v137, 0xffff0000, v137
	v_lshlrev_b32_e32 v202, 16, v138
	v_and_b32_e32 v203, 0xffff0000, v138
	v_lshlrev_b32_e32 v138, 16, v139
	v_and_b32_e32 v139, 0xffff0000, v139
	v_lshlrev_b32_e32 v204, 16, v140
	v_and_b32_e32 v205, 0xffff0000, v140
	v_lshlrev_b32_e32 v140, 16, v141
	v_and_b32_e32 v141, 0xffff0000, v141
	v_pk_mul_f32 v[244:245], v[32:33], v[14:15]
	v_pk_mul_f32 v[246:247], v[24:25], v[12:13]
	v_pk_mul_f32 v[12:13], v[0:1], v[82:83] op_sel_hi:[0,1]
	v_pk_mul_f32 v[14:15], v[0:1], v[84:85] op_sel_hi:[0,1]
	v_pk_mul_f32 v[78:79], v[0:1], v[86:87] op_sel_hi:[0,1]
	v_pk_mul_f32 v[80:81], v[0:1], v[88:89] op_sel_hi:[0,1]
	v_pk_mul_f32 v[82:83], v[0:1], v[90:91] op_sel_hi:[0,1]
	v_pk_mul_f32 v[84:85], v[0:1], v[92:93] op_sel_hi:[0,1]
	v_pk_mul_f32 v[86:87], v[2:3], v[166:167] op_sel_hi:[0,1]
	v_pk_mul_f32 v[88:89], v[2:3], v[102:103] op_sel_hi:[0,1]
	v_pk_mul_f32 v[90:91], v[2:3], v[168:169] op_sel_hi:[0,1]
	v_pk_mul_f32 v[92:93], v[2:3], v[104:105] op_sel_hi:[0,1]
	v_pk_mul_f32 v[94:95], v[2:3], v[170:171] op_sel_hi:[0,1]
	v_pk_mul_f32 v[96:97], v[2:3], v[106:107] op_sel_hi:[0,1]
	v_pk_mul_f32 v[98:99], v[2:3], v[172:173] op_sel_hi:[0,1]
	v_pk_mul_f32 v[100:101], v[2:3], v[108:109] op_sel_hi:[0,1]
	v_pk_mul_f32 v[102:103], v[4:5], v[174:175] op_sel_hi:[0,1]
	v_pk_mul_f32 v[104:105], v[4:5], v[110:111] op_sel_hi:[0,1]
	v_pk_mul_f32 v[106:107], v[4:5], v[176:177] op_sel_hi:[0,1]
	v_pk_mul_f32 v[108:109], v[4:5], v[112:113] op_sel_hi:[0,1]
	v_pk_mul_f32 v[110:111], v[4:5], v[178:179] op_sel_hi:[0,1]
	v_pk_mul_f32 v[112:113], v[4:5], v[114:115] op_sel_hi:[0,1]
	v_pk_mul_f32 v[114:115], v[4:5], v[180:181] op_sel_hi:[0,1]
	v_pk_mul_f32 v[116:117], v[4:5], v[116:117] op_sel_hi:[0,1]
	v_pk_mul_f32 v[142:143], v[6:7], v[182:183] op_sel_hi:[0,1]
	v_pk_mul_f32 v[118:119], v[6:7], v[118:119] op_sel_hi:[0,1]
	v_pk_mul_f32 v[144:145], v[6:7], v[184:185] op_sel_hi:[0,1]
	v_pk_mul_f32 v[120:121], v[6:7], v[120:121] op_sel_hi:[0,1]
	v_pk_mul_f32 v[146:147], v[6:7], v[186:187] op_sel_hi:[0,1]
	v_pk_mul_f32 v[122:123], v[6:7], v[122:123] op_sel_hi:[0,1]
	v_pk_mul_f32 v[148:149], v[6:7], v[188:189] op_sel_hi:[0,1]
	v_pk_mul_f32 v[124:125], v[6:7], v[124:125] op_sel_hi:[0,1]
	v_pk_fma_f32 v[2:3], v[236:237], v[10:11], v[66:67]
	v_pk_fma_f32 v[0:1], v[238:239], v[8:9], v[60:61]
	v_pk_fma_f32 v[6:7], v[240:241], v[14:15], v[70:71]
	v_pk_fma_f32 v[4:5], v[242:243], v[12:13], v[64:65]
	v_pk_fma_f32 v[10:11], v[244:245], v[80:81], v[74:75]
	v_pk_fma_f32 v[8:9], v[246:247], v[78:79], v[68:69]
	v_pk_fma_f32 v[14:15], v[248:249], v[84:85], v[76:77]
	v_pk_fma_f32 v[12:13], v[250:251], v[82:83], v[72:73]
	v_pk_fma_f32 v[66:67], v[236:237], v[88:89], v[126:127]
	v_pk_fma_f32 v[64:65], v[238:239], v[86:87], v[190:191]
	v_pk_fma_f32 v[70:71], v[240:241], v[92:93], v[128:129]
	v_pk_fma_f32 v[68:69], v[242:243], v[90:91], v[192:193]
	v_pk_fma_f32 v[74:75], v[244:245], v[96:97], v[130:131]
	v_pk_fma_f32 v[72:73], v[246:247], v[94:95], v[194:195]
	v_pk_fma_f32 v[78:79], v[248:249], v[100:101], v[132:133]
	v_pk_fma_f32 v[76:77], v[250:251], v[98:99], v[196:197]
	v_pk_fma_f32 v[82:83], v[236:237], v[104:105], v[134:135]
	v_pk_fma_f32 v[80:81], v[238:239], v[102:103], v[198:199]
	v_pk_fma_f32 v[86:87], v[240:241], v[108:109], v[136:137]
	v_pk_fma_f32 v[84:85], v[242:243], v[106:107], v[200:201]
	v_pk_fma_f32 v[90:91], v[244:245], v[112:113], v[138:139]
	v_pk_fma_f32 v[88:89], v[246:247], v[110:111], v[202:203]
	v_pk_fma_f32 v[94:95], v[248:249], v[116:117], v[140:141]
	v_pk_fma_f32 v[92:93], v[250:251], v[114:115], v[204:205]
	v_pk_fma_f32 v[98:99], v[236:237], v[118:119], v[50:51]
	v_pk_fma_f32 v[96:97], v[238:239], v[142:143], v[46:47]
	v_pk_fma_f32 v[50:51], v[240:241], v[120:121], v[54:55]
	v_pk_fma_f32 v[48:49], v[242:243], v[144:145], v[48:49]
	v_pk_fma_f32 v[54:55], v[244:245], v[122:123], v[58:59]
	v_pk_fma_f32 v[52:53], v[246:247], v[146:147], v[52:53]
	v_pk_fma_f32 v[58:59], v[248:249], v[124:125], v[62:63]
	v_pk_fma_f32 v[56:57], v[250:251], v[148:149], v[56:57]
	flat_store_dwordx4 v[38:39], v[0:3]
	flat_store_dwordx4 v[38:39], v[4:7] offset:16
	flat_store_dwordx4 v[38:39], v[8:11] offset:2048
	flat_store_dwordx4 v[38:39], v[12:15] offset:2064
	flat_store_dwordx4 v[44:45], v[64:67]
	flat_store_dwordx4 v[44:45], v[68:71] offset:16
	flat_store_dwordx4 v[44:45], v[72:75] offset:2048
	flat_store_dwordx4 v[44:45], v[76:79] offset:2064
	flat_store_dwordx4 v[42:43], v[80:83]
	flat_store_dwordx4 v[42:43], v[84:87] offset:16
	flat_store_dwordx4 v[42:43], v[88:91] offset:2048
	flat_store_dwordx4 v[42:43], v[92:95] offset:2064
	flat_store_dwordx4 v[40:41], v[96:99]
	flat_store_dwordx4 v[40:41], v[48:51] offset:16
	flat_store_dwordx4 v[40:41], v[52:55] offset:2048
	flat_store_dwordx4 v[40:41], v[56:59] offset:2064
	s_cbranch_scc1 .LBB0_3564
